# flat->global memory ops; hand-pipelined sample-row GEMM K loop; prologue transpose scale loads batched
# speedup vs baseline: 1.0116x; 1.0116x over previous
.LBB0_18:
	v_ashrrev_i32_e32 v51, 31, v50
	v_mov_b32_e32 v21, 0
	v_mov_b32_e32 v66, 0
	s_and_saveexec_b64 s[0:1], vcc
	s_cbranch_execz .LBB0_20
	v_lshlrev_b64 v[22:23], 6, v[50:51]
	v_lshl_add_u64 v[22:23], v[18:19], 0, v[22:23]
	global_load_dword v66, v[22:23], off
.LBB0_20:
	s_or_b64 exec, exec, s[0:1]
	v_lshlrev_b64 v[22:23], 11, v[50:51]
	v_lshl_add_u64 v[22:23], v[16:17], 0, v[22:23]
	global_load_dwordx2 v[58:59], v[22:23], off
	global_load_dwordx2 v[56:57], v[22:23], off offset:512
	global_load_dwordx2 v[54:55], v[22:23], off offset:1024
	global_load_dwordx2 v[52:53], v[22:23], off offset:1536
	v_add_u32_e32 v20, s80, v50
	v_cmp_gt_i32_e64 s[4:5], s25, v20
	s_nop 1
	v_cndmask_b32_e64 v22, v50, v20, s[4:5]
	v_ashrrev_i32_e32 v23, 31, v22
	s_and_saveexec_b64 s[0:1], vcc
	s_cbranch_execz .LBB0_22
	v_lshlrev_b64 v[24:25], 6, v[22:23]
	v_lshl_add_u64 v[24:25], v[18:19], 0, v[24:25]
	global_load_dword v21, v[24:25], off
.LBB0_22:
	s_or_b64 exec, exec, s[0:1]
	v_lshlrev_b64 v[22:23], 11, v[22:23]
	v_lshl_add_u64 v[22:23], v[16:17], 0, v[22:23]
	global_load_dwordx2 v[48:49], v[22:23], off
	global_load_dwordx2 v[46:47], v[22:23], off offset:512
	global_load_dwordx2 v[44:45], v[22:23], off offset:1024
	global_load_dwordx2 v[42:43], v[22:23], off offset:1536
	v_add_u32_e32 v34, s20, v50
	v_cmp_gt_i32_e64 s[6:7], s25, v34
	v_mov_b32_e32 v25, 0
	v_mov_b32_e32 v35, 0
	v_cndmask_b32_e64 v22, v50, v34, s[6:7]
	v_ashrrev_i32_e32 v23, 31, v22
	s_and_saveexec_b64 s[0:1], vcc
	s_cbranch_execz .LBB0_24
	v_lshlrev_b64 v[26:27], 6, v[22:23]
	v_lshl_add_u64 v[26:27], v[18:19], 0, v[26:27]
	global_load_dword v35, v[26:27], off
.LBB0_24:
	s_or_b64 exec, exec, s[0:1]
	v_lshlrev_b64 v[22:23], 11, v[22:23]
	v_lshl_add_u64 v[22:23], v[16:17], 0, v[22:23]
	global_load_dwordx2 v[40:41], v[22:23], off
	global_load_dwordx2 v[38:39], v[22:23], off offset:512
	global_load_dwordx2 v[36:37], v[22:23], off offset:1024
	global_load_dwordx2 v[32:33], v[22:23], off offset:1536
	v_add_u32_e32 v24, s23, v50
	v_cmp_gt_i32_e64 s[0:1], s25, v24
	s_nop 1
	v_cndmask_b32_e64 v22, v50, v24, s[0:1]
	v_ashrrev_i32_e32 v23, 31, v22
	s_and_saveexec_b64 s[12:13], vcc
	s_cbranch_execz .LBB0_26
	v_lshlrev_b64 v[26:27], 6, v[22:23]
	v_lshl_add_u64 v[26:27], v[18:19], 0, v[26:27]
	global_load_dword v25, v[26:27], off
.LBB0_26:
	s_or_b64 exec, exec, s[12:13]
	v_lshlrev_b64 v[22:23], 11, v[22:23]
	v_lshl_add_u64 v[22:23], v[16:17], 0, v[22:23]
	global_load_dwordx2 v[30:31], v[22:23], off
	global_load_dwordx2 v[28:29], v[22:23], off offset:512
	global_load_dwordx2 v[26:27], v[22:23], off offset:1024
	s_nop 0
	global_load_dwordx2 v[22:23], v[22:23], off offset:1536
	s_waitcnt vmcnt(0) lgkmcnt(0)
	ds_bpermute_b32 v67, v60, v66
	s_mov_b64 s[12:13], s[40:41]
	v_lshlrev_b64 v[50:51], 12, v[50:51]
	s_waitcnt lgkmcnt(0)
	v_add_f32_e32 v66, v66, v67
	ds_bpermute_b32 v67, v61, v66
	v_lshl_add_u64 v[50:51], s[12:13], 0, v[50:51]
	v_lshl_add_u64 v[72:73], v[50:51], 0, v[192:193]
	v_lshlrev_b32_e32 v50, 16, v58
	v_and_b32_e32 v51, 0xffff0000, v58
	s_waitcnt lgkmcnt(0)
	v_add_f32_e32 v66, v66, v67
	ds_bpermute_b32 v67, v62, v66
	v_lshlrev_b32_e32 v58, 16, v59
	v_and_b32_e32 v59, 0xffff0000, v59
	s_waitcnt lgkmcnt(0)
	v_add_f32_e32 v66, v66, v67
	ds_bpermute_b32 v67, v63, v66
	s_waitcnt lgkmcnt(0)
	v_add_f32_e32 v66, v66, v67
	ds_bpermute_b32 v67, v64, v66
	s_waitcnt lgkmcnt(0)
	v_add_f32_e32 v66, v66, v67
	ds_bpermute_b32 v67, v65, v66
	s_waitcnt lgkmcnt(0)
	v_add_f32_e32 v66, v66, v67
	v_fmamk_f32 v66, v66, 0x3a800000, v215
	v_rsq_f32_e32 v70, v66
	s_nop 0
	v_pk_mul_f32 v[50:51], v[70:71], v[50:51] op_sel_hi:[0,1]
	v_pk_mul_f32 v[66:67], v[0:1], v[50:51]
	v_lshlrev_b32_e32 v50, 16, v56
	v_and_b32_e32 v51, 0xffff0000, v56
	v_lshlrev_b32_e32 v56, 16, v57
	v_and_b32_e32 v57, 0xffff0000, v57
	v_pk_mul_f32 v[58:59], v[70:71], v[58:59] op_sel_hi:[0,1]
	v_pk_mul_f32 v[50:51], v[70:71], v[50:51] op_sel_hi:[0,1]
	v_pk_mul_f32 v[56:57], v[70:71], v[56:57] op_sel_hi:[0,1]
	v_pk_mul_f32 v[68:69], v[2:3], v[58:59]
	v_pk_mul_f32 v[58:59], v[6:7], v[56:57]
	v_pk_mul_f32 v[56:57], v[4:5], v[50:51]
	v_lshlrev_b32_e32 v50, 16, v54
	v_and_b32_e32 v51, 0xffff0000, v54
	v_lshlrev_b32_e32 v54, 16, v55
	v_and_b32_e32 v55, 0xffff0000, v55
	v_pk_mul_f32 v[50:51], v[70:71], v[50:51] op_sel_hi:[0,1]
	v_pk_mul_f32 v[54:55], v[70:71], v[54:55] op_sel_hi:[0,1]
	global_store_dwordx4 v[72:73], v[56:59], off offset:1024
	global_store_dwordx4 v[72:73], v[66:69], off
	s_nop 0
	v_pk_mul_f32 v[56:57], v[10:11], v[54:55]
	v_pk_mul_f32 v[54:55], v[8:9], v[50:51]
	v_lshlrev_b32_e32 v50, 16, v52
	v_and_b32_e32 v51, 0xffff0000, v52
	v_lshlrev_b32_e32 v52, 16, v53
	v_and_b32_e32 v53, 0xffff0000, v53
	v_pk_mul_f32 v[50:51], v[70:71], v[50:51] op_sel_hi:[0,1]
	v_pk_mul_f32 v[52:53], v[70:71], v[52:53] op_sel_hi:[0,1]
	v_pk_mul_f32 v[52:53], v[14:15], v[52:53]
	v_pk_mul_f32 v[50:51], v[12:13], v[50:51]
	global_store_dwordx4 v[72:73], v[54:57], off offset:2048
	global_store_dwordx4 v[72:73], v[50:53], off offset:3072
	s_and_saveexec_b64 s[12:13], s[4:5]
	s_cbranch_execz .LBB0_17
	ds_bpermute_b32 v50, v60, v21
	s_mov_b64 s[4:5], s[40:41]
	s_waitcnt lgkmcnt(0)
	v_add_f32_e32 v21, v21, v50
	ds_bpermute_b32 v50, v61, v21
	s_waitcnt lgkmcnt(0)
	v_add_f32_e32 v51, v21, v50
	ds_bpermute_b32 v52, v62, v51
	v_ashrrev_i32_e32 v21, 31, v20
	v_lshlrev_b32_e32 v50, 16, v48
	v_lshlrev_b64 v[58:59], 12, v[20:21]
	v_lshl_add_u64 v[58:59], s[4:5], 0, v[58:59]
	s_waitcnt lgkmcnt(0)
	v_add_f32_e32 v53, v51, v52
	ds_bpermute_b32 v54, v63, v53
	v_and_b32_e32 v51, 0xffff0000, v48
	v_lshlrev_b32_e32 v48, 16, v49
	v_and_b32_e32 v49, 0xffff0000, v49
	v_lshlrev_b32_e32 v52, 16, v46
	s_waitcnt lgkmcnt(0)
	v_add_f32_e32 v55, v53, v54
	ds_bpermute_b32 v56, v64, v55
	v_and_b32_e32 v53, 0xffff0000, v46
	v_lshlrev_b32_e32 v46, 16, v47
	v_and_b32_e32 v47, 0xffff0000, v47
	v_lshlrev_b32_e32 v54, 16, v44
	s_waitcnt lgkmcnt(0)
	v_add_f32_e32 v56, v55, v56
	ds_bpermute_b32 v57, v65, v56
	v_and_b32_e32 v55, 0xffff0000, v44
	v_lshlrev_b32_e32 v44, 16, v45
	v_and_b32_e32 v45, 0xffff0000, v45
	v_lshl_add_u64 v[58:59], v[58:59], 0, v[192:193]
	s_waitcnt lgkmcnt(0)
	v_add_f32_e32 v56, v56, v57
	v_fmamk_f32 v56, v56, 0x3a800000, v215
	v_rsq_f32_e32 v56, v56
	s_nop 0
	v_pk_mul_f32 v[50:51], v[56:57], v[50:51] op_sel_hi:[0,1]
	v_pk_mul_f32 v[48:49], v[56:57], v[48:49] op_sel_hi:[0,1]
	v_pk_mul_f32 v[52:53], v[56:57], v[52:53] op_sel_hi:[0,1]
	v_pk_mul_f32 v[66:67], v[56:57], v[46:47] op_sel_hi:[0,1]
	v_pk_mul_f32 v[54:55], v[56:57], v[54:55] op_sel_hi:[0,1]
	v_pk_mul_f32 v[68:69], v[56:57], v[44:45] op_sel_hi:[0,1]
	v_pk_mul_f32 v[46:47], v[2:3], v[48:49]
	v_pk_mul_f32 v[44:45], v[0:1], v[50:51]
	v_pk_mul_f32 v[50:51], v[6:7], v[66:67]
	v_pk_mul_f32 v[48:49], v[4:5], v[52:53]
	global_store_dwordx4 v[58:59], v[44:47], off
	global_store_dwordx4 v[58:59], v[48:51], off offset:1024
	s_nop 0
	v_pk_mul_f32 v[46:47], v[10:11], v[68:69]
	v_pk_mul_f32 v[44:45], v[8:9], v[54:55]
	global_store_dwordx4 v[58:59], v[44:47], off offset:2048
	s_nop 1
	v_lshlrev_b32_e32 v44, 16, v42
	v_and_b32_e32 v45, 0xffff0000, v42
	v_lshlrev_b32_e32 v42, 16, v43
	v_and_b32_e32 v43, 0xffff0000, v43
	v_pk_mul_f32 v[46:47], v[56:57], v[44:45] op_sel_hi:[0,1]
	v_pk_mul_f32 v[42:43], v[56:57], v[42:43] op_sel_hi:[0,1]
	v_pk_mul_f32 v[44:45], v[14:15], v[42:43]
	v_pk_mul_f32 v[42:43], v[12:13], v[46:47]
	global_store_dwordx4 v[58:59], v[42:45], off offset:3072
	s_and_b64 exec, exec, s[6:7]
	s_cbranch_execz .LBB0_17
	ds_bpermute_b32 v21, v60, v35
	s_mov_b64 s[4:5], s[40:41]
	v_lshlrev_b32_e32 v42, 16, v40
	v_lshlrev_b32_e32 v44, 16, v38
	s_waitcnt lgkmcnt(0)
	v_add_f32_e32 v21, v35, v21
	ds_bpermute_b32 v35, v61, v21
	v_lshlrev_b32_e32 v46, 16, v36
	s_waitcnt lgkmcnt(0)
	v_add_f32_e32 v21, v21, v35
	ds_bpermute_b32 v43, v62, v21
	v_ashrrev_i32_e32 v35, 31, v34
	v_lshlrev_b64 v[34:35], 12, v[34:35]
	v_lshl_add_u64 v[34:35], s[4:5], 0, v[34:35]
	v_lshl_add_u64 v[50:51], v[34:35], 0, v[192:193]
	s_waitcnt lgkmcnt(0)
	v_add_f32_e32 v21, v21, v43
	ds_bpermute_b32 v45, v63, v21
	v_and_b32_e32 v43, 0xffff0000, v40
	v_lshlrev_b32_e32 v40, 16, v41
	v_and_b32_e32 v41, 0xffff0000, v41
	s_waitcnt lgkmcnt(0)
	v_add_f32_e32 v21, v21, v45
	ds_bpermute_b32 v47, v64, v21
	v_and_b32_e32 v45, 0xffff0000, v38
	v_lshlrev_b32_e32 v38, 16, v39
	v_and_b32_e32 v39, 0xffff0000, v39
	s_waitcnt lgkmcnt(0)
	v_add_f32_e32 v21, v21, v47
	ds_bpermute_b32 v48, v65, v21
	v_and_b32_e32 v47, 0xffff0000, v36
	v_lshlrev_b32_e32 v36, 16, v37
	v_and_b32_e32 v37, 0xffff0000, v37
	s_waitcnt lgkmcnt(0)
	v_add_f32_e32 v21, v21, v48
	v_fmamk_f32 v21, v21, 0x3a800000, v215
	v_rsq_f32_e32 v48, v21
	s_nop 0
	v_pk_mul_f32 v[34:35], v[48:49], v[42:43] op_sel_hi:[0,1]
	v_pk_mul_f32 v[40:41], v[48:49], v[40:41] op_sel_hi:[0,1]
	v_pk_mul_f32 v[42:43], v[48:49], v[44:45] op_sel_hi:[0,1]
	v_pk_mul_f32 v[38:39], v[48:49], v[38:39] op_sel_hi:[0,1]
	v_pk_mul_f32 v[44:45], v[48:49], v[46:47] op_sel_hi:[0,1]
	v_pk_mul_f32 v[46:47], v[48:49], v[36:37] op_sel_hi:[0,1]
	v_pk_mul_f32 v[36:37], v[2:3], v[40:41]
	v_pk_mul_f32 v[34:35], v[0:1], v[34:35]
	v_pk_mul_f32 v[40:41], v[6:7], v[38:39]
	v_pk_mul_f32 v[38:39], v[4:5], v[42:43]
	global_store_dwordx4 v[50:51], v[34:37], off
	global_store_dwordx4 v[50:51], v[38:41], off offset:1024
	s_nop 0
	v_pk_mul_f32 v[36:37], v[10:11], v[46:47]
	v_pk_mul_f32 v[34:35], v[8:9], v[44:45]
	global_store_dwordx4 v[50:51], v[34:37], off offset:2048
	s_nop 1
	v_lshlrev_b32_e32 v34, 16, v32
	v_and_b32_e32 v35, 0xffff0000, v32
	v_lshlrev_b32_e32 v32, 16, v33
	v_and_b32_e32 v33, 0xffff0000, v33
	v_pk_mul_f32 v[36:37], v[48:49], v[34:35] op_sel_hi:[0,1]
	v_pk_mul_f32 v[32:33], v[48:49], v[32:33] op_sel_hi:[0,1]
	v_pk_mul_f32 v[34:35], v[14:15], v[32:33]
	v_pk_mul_f32 v[32:33], v[12:13], v[36:37]
	global_store_dwordx4 v[50:51], v[32:35], off offset:3072
	s_and_b64 exec, exec, s[0:1]
	s_cbranch_execz .LBB0_17
	ds_bpermute_b32 v21, v60, v25
	s_mov_b64 s[0:1], s[40:41]
	v_lshlrev_b32_e32 v32, 16, v30
	v_lshlrev_b32_e32 v34, 16, v28
	s_waitcnt lgkmcnt(0)
	v_add_f32_e32 v21, v25, v21
	ds_bpermute_b32 v25, v61, v21
	v_lshlrev_b32_e32 v36, 16, v26
	s_waitcnt lgkmcnt(0)
	v_add_f32_e32 v21, v21, v25
	ds_bpermute_b32 v33, v62, v21
	v_ashrrev_i32_e32 v25, 31, v24
	v_lshlrev_b64 v[24:25], 12, v[24:25]
	v_lshl_add_u64 v[24:25], s[0:1], 0, v[24:25]
	v_lshl_add_u64 v[40:41], v[24:25], 0, v[192:193]
	s_waitcnt lgkmcnt(0)
	v_add_f32_e32 v21, v21, v33
	ds_bpermute_b32 v35, v63, v21
	v_and_b32_e32 v33, 0xffff0000, v30
	v_lshlrev_b32_e32 v30, 16, v31
	v_and_b32_e32 v31, 0xffff0000, v31
	s_waitcnt lgkmcnt(0)
	v_add_f32_e32 v21, v21, v35
	ds_bpermute_b32 v37, v64, v21
	v_and_b32_e32 v35, 0xffff0000, v28
	v_lshlrev_b32_e32 v28, 16, v29
	v_and_b32_e32 v29, 0xffff0000, v29
	s_waitcnt lgkmcnt(0)
	v_add_f32_e32 v21, v21, v37
	ds_bpermute_b32 v38, v65, v21
	v_and_b32_e32 v37, 0xffff0000, v26
	v_lshlrev_b32_e32 v26, 16, v27
	v_and_b32_e32 v27, 0xffff0000, v27
	s_waitcnt lgkmcnt(0)
	v_add_f32_e32 v21, v21, v38
	v_fmamk_f32 v21, v21, 0x3a800000, v215
	v_rsq_f32_e32 v38, v21
	s_nop 0
	v_pk_mul_f32 v[24:25], v[38:39], v[32:33] op_sel_hi:[0,1]
	v_pk_mul_f32 v[30:31], v[38:39], v[30:31] op_sel_hi:[0,1]
	v_pk_mul_f32 v[32:33], v[38:39], v[34:35] op_sel_hi:[0,1]
	v_pk_mul_f32 v[28:29], v[38:39], v[28:29] op_sel_hi:[0,1]
	v_pk_mul_f32 v[34:35], v[38:39], v[36:37] op_sel_hi:[0,1]
	v_pk_mul_f32 v[36:37], v[38:39], v[26:27] op_sel_hi:[0,1]
	v_pk_mul_f32 v[26:27], v[2:3], v[30:31]
	v_pk_mul_f32 v[24:25], v[0:1], v[24:25]
	v_pk_mul_f32 v[30:31], v[6:7], v[28:29]
	v_pk_mul_f32 v[28:29], v[4:5], v[32:33]
	global_store_dwordx4 v[40:41], v[24:27], off
	global_store_dwordx4 v[40:41], v[28:31], off offset:1024
	s_nop 0
	v_pk_mul_f32 v[26:27], v[10:11], v[36:37]
	v_pk_mul_f32 v[24:25], v[8:9], v[34:35]
	global_store_dwordx4 v[40:41], v[24:27], off offset:2048
	s_nop 1
	v_lshlrev_b32_e32 v24, 16, v22
	v_and_b32_e32 v25, 0xffff0000, v22
	v_lshlrev_b32_e32 v22, 16, v23
	v_and_b32_e32 v23, 0xffff0000, v23
	v_pk_mul_f32 v[26:27], v[38:39], v[24:25] op_sel_hi:[0,1]
	v_pk_mul_f32 v[22:23], v[38:39], v[22:23] op_sel_hi:[0,1]
	v_pk_mul_f32 v[24:25], v[14:15], v[22:23]
	v_pk_mul_f32 v[22:23], v[12:13], v[26:27]
	global_store_dwordx4 v[40:41], v[22:25], off offset:3072
	s_branch .LBB0_17

.LBB0_46:
	s_lshl_b32 s1, s16, 5
	s_and_b32 s0, s16, 0x100
	s_and_b32 s1, s1, 0xe0
	s_or_b32 s0, s1, s0
	s_bfe_u32 s1, s16, 0x50003
	s_or_b32 s4, s0, s1
	s_and_b64 s[0:1], s[84:85], exec
	s_cselect_b32 s17, s4, s16
	s_waitcnt lgkmcnt(0)
	v_mov_b32_e32 v129, v214
	s_ashr_i32 s23, s17, 6
	s_bfe_u32 s25, s17, 0x20004
	s_lshl_b32 s17, s17, 7
	s_add_i32 s4, s23, s19
	s_lshl_b32 s23, s23, 11
	s_and_b32 s17, s17, 0x780
	v_ashrrev_i32_e32 v0, 2, v129
	v_bfi_b32 v0, -16, v0, v129
	s_or_b32 s17, s23, s17
	s_ashr_i32 s5, s4, 31
	v_add_u32_e32 v0, s17, v0
	s_mov_b64 s[26:27], s[42:43]
	v_ashrrev_i32_e32 v1, 31, v0
	s_lshl_b64 s[4:5], s[4:5], 19
	s_lshl_b32 s17, s25, 17
	s_mov_b64 s[0:1], s[42:43]
	s_mov_b64 s[28:29], s[42:43]
	v_lshlrev_b64 v[140:141], 11, v[0:1]
	s_lshl_b32 s82, s25, 9
	s_or_b32 s4, s4, s17
	v_bfe_u32 v174, v129, 4, 2
	s_add_u32 s26, s26, s4
	v_lshl_add_u64 v[0:1], s[28:29], 0, v[140:141]
	v_lshlrev_b32_e32 v34, 3, v129
	v_lshlrev_b32_e32 v32, 4, v129
	v_lshl_add_u64 v[0:1], v[0:1], 0, s[82:83]
	v_lshlrev_b32_e32 v102, 4, v174
	v_mov_b32_e32 v103, v193
	s_addc_u32 s27, s27, s5
	v_and_b32_e32 v80, 0x1f0, v32
	v_mov_b32_e32 v81, v193
	v_and_b32_e32 v122, 0xffffff00, v34
	v_lshl_add_u64 v[0:1], v[0:1], 0, v[102:103]
	s_mov_b64 s[28:29], 0xfc00000
	v_lshl_add_u64 v[32:33], s[26:27], 0, v[80:81]
	s_mov_b64 s[26:27], 0x6400000
	v_ashrrev_i32_e32 v123, 31, v122
	v_lshl_add_u64 v[2:3], v[0:1], 0, s[28:29]
	v_add_co_u32_e32 v0, vcc, s31, v0
	v_lshl_add_u64 v[120:121], v[32:33], 0, s[26:27]
	v_lshlrev_b64 v[82:83], 1, v[122:123]
	v_addc_co_u32_e32 v1, vcc, 0, v1, vcc
	v_lshl_add_u64 v[32:33], v[120:121], 0, v[82:83]
	global_load_dwordx4 v[24:27], v[2:3], off offset:64
	global_load_dwordx4 v[20:23], v[2:3], off offset:128
	global_load_dwordx4 v[16:19], v[2:3], off offset:192
	global_load_dwordx4 v[12:15], v[2:3], off offset:256
	global_load_dwordx4 v[8:11], v[2:3], off offset:320
	global_load_dwordx4 v[4:7], v[2:3], off offset:384
	global_load_dwordx4 v[28:31], v[0:1], off
	s_nop 0
	global_load_dwordx4 v[0:3], v[2:3], off offset:448
	v_add_u32_e32 v36, 0x1000, v122
	global_load_dwordx4 v[32:35], v[32:33], off
	v_add_u32_e32 v40, 0x2000, v122
	v_add_u32_e32 v44, 0x3000, v122
	v_add_u32_e32 v48, 0x4000, v122
	v_add_u32_e32 v52, 0x5000, v122
	v_add_u32_e32 v56, 0x6000, v122
	v_add_u32_e32 v60, 0x7000, v122
	v_add_u32_e32 v64, 0x8000, v122
	v_add_u32_e32 v68, 0x9000, v122
	v_add_u32_e32 v72, 0xa000, v122
	v_add_u32_e32 v76, 0xb000, v122
	v_add_u32_e32 v98, 0xc000, v122
	v_ashrrev_i32_e32 v37, 31, v36
	v_ashrrev_i32_e32 v41, 31, v40
	v_ashrrev_i32_e32 v45, 31, v44
	v_ashrrev_i32_e32 v49, 31, v48
	v_ashrrev_i32_e32 v53, 31, v52
	v_ashrrev_i32_e32 v57, 31, v56
	v_ashrrev_i32_e32 v61, 31, v60
	v_ashrrev_i32_e32 v65, 31, v64
	v_ashrrev_i32_e32 v69, 31, v68
	v_ashrrev_i32_e32 v73, 31, v72
	v_ashrrev_i32_e32 v77, 31, v76
	v_ashrrev_i32_e32 v99, 31, v98
	v_add_u32_e32 v108, 0xd000, v122
	v_add_u32_e32 v116, 0xe000, v122
	v_add_u32_e32 v122, 0xf000, v122
	v_lshlrev_b64 v[84:85], 1, v[36:37]
	v_lshlrev_b64 v[86:87], 1, v[40:41]
	v_lshlrev_b64 v[88:89], 1, v[44:45]
	v_lshlrev_b64 v[90:91], 1, v[48:49]
	v_lshlrev_b64 v[92:93], 1, v[52:53]
	v_lshlrev_b64 v[94:95], 1, v[56:57]
	v_lshlrev_b64 v[96:97], 1, v[60:61]
	v_lshlrev_b64 v[104:105], 1, v[64:65]
	v_lshlrev_b64 v[106:107], 1, v[68:69]
	v_lshlrev_b64 v[112:113], 1, v[72:73]
	v_lshlrev_b64 v[114:115], 1, v[76:77]
	v_lshlrev_b64 v[124:125], 1, v[98:99]
	v_ashrrev_i32_e32 v109, 31, v108
	v_ashrrev_i32_e32 v117, 31, v116
	v_ashrrev_i32_e32 v123, 31, v122
	v_lshl_add_u64 v[36:37], v[120:121], 0, v[84:85]
	v_lshl_add_u64 v[40:41], v[120:121], 0, v[86:87]
	v_lshl_add_u64 v[44:45], v[120:121], 0, v[88:89]
	v_lshl_add_u64 v[48:49], v[120:121], 0, v[90:91]
	v_lshl_add_u64 v[52:53], v[120:121], 0, v[92:93]
	v_lshl_add_u64 v[56:57], v[120:121], 0, v[94:95]
	v_lshl_add_u64 v[60:61], v[120:121], 0, v[96:97]
	v_lshl_add_u64 v[64:65], v[120:121], 0, v[104:105]
	v_lshl_add_u64 v[68:69], v[120:121], 0, v[106:107]
	v_lshl_add_u64 v[72:73], v[120:121], 0, v[112:113]
	v_lshl_add_u64 v[76:77], v[120:121], 0, v[114:115]
	v_lshl_add_u64 v[98:99], v[120:121], 0, v[124:125]
	v_lshlrev_b64 v[126:127], 1, v[108:109]
	v_lshlrev_b64 v[132:133], 1, v[116:117]
	v_lshlrev_b64 v[134:135], 1, v[122:123]
	global_load_dwordx4 v[36:39], v[36:37], off
	v_lshl_add_u64 v[108:109], v[120:121], 0, v[126:127]
	global_load_dwordx4 v[40:43], v[40:41], off
	v_lshl_add_u64 v[116:117], v[120:121], 0, v[132:133]
	global_load_dwordx4 v[44:47], v[44:45], off
	v_lshl_add_u64 v[120:121], v[120:121], 0, v[134:135]
	global_load_dwordx4 v[48:51], v[48:49], off
	v_add_u32_e32 v128, 0, v80
	global_load_dwordx4 v[52:55], v[52:53], off
	v_ashrrev_i32_e32 v103, 5, v129
	global_load_dwordx4 v[56:59], v[56:57], off
	v_mad_u64_u32 v[142:143], s[26:27], v103, s34, v[128:129]
	global_load_dwordx4 v[60:63], v[60:61], off
	v_and_b32_e32 v130, 15, v129
	global_load_dwordx4 v[64:67], v[64:65], off
	v_mul_u32_u24_e32 v143, 0x210, v130
	global_load_dwordx4 v[68:71], v[68:69], off
	s_add_u32 s0, s0, s4
	global_load_dwordx4 v[72:75], v[72:73], off
	s_addc_u32 s1, s1, s5
	global_load_dwordx4 v[76:79], v[76:77], off
	v_cmp_lt_i32_e32 vcc, v223, v218
	global_load_dwordx4 v[98:101], v[98:99], off
	v_lshlrev_b32_e32 v192, 3, v174
	global_load_dwordx4 v[108:111], v[108:109], off
	s_nop 0
	global_load_dwordx4 v[116:119], v[116:117], off
	s_nop 0
	global_load_dwordx4 v[120:123], v[120:121], off
	s_waitcnt vmcnt(0) lgkmcnt(0)
	ds_write_b128 v142, v[32:35]
	v_add_u32_e32 v32, 0x200, v129
	v_ashrrev_i32_e32 v32, 5, v32
	v_mad_u64_u32 v[144:145], s[26:27], v32, s34, v[128:129]
	v_add_u32_e32 v32, 0x400, v129
	v_ashrrev_i32_e32 v32, 5, v32
	v_mad_u64_u32 v[146:147], s[26:27], v32, s34, v[128:129]
	v_add_u32_e32 v32, 0x600, v129
	v_ashrrev_i32_e32 v32, 5, v32
	v_mad_u64_u32 v[148:149], s[26:27], v32, s34, v[128:129]
	v_add_u32_e32 v32, 0x800, v129
	v_ashrrev_i32_e32 v32, 5, v32
	v_mad_u64_u32 v[150:151], s[26:27], v32, s34, v[128:129]
	v_add_u32_e32 v32, 0xa00, v129
	v_ashrrev_i32_e32 v32, 5, v32
	v_mad_u64_u32 v[152:153], s[26:27], v32, s34, v[128:129]
	v_add_u32_e32 v32, 0xc00, v129
	v_ashrrev_i32_e32 v32, 5, v32
	v_mad_u64_u32 v[154:155], s[26:27], v32, s34, v[128:129]
	v_add_u32_e32 v32, 0xe00, v129
	v_ashrrev_i32_e32 v32, 5, v32
	v_mad_u64_u32 v[156:157], s[26:27], v32, s34, v[128:129]
	v_add_u32_e32 v32, 0x1000, v129
	v_ashrrev_i32_e32 v32, 5, v32
	v_mad_u64_u32 v[158:159], s[26:27], v32, s34, v[128:129]
	v_add_u32_e32 v32, 0x1200, v129
	v_ashrrev_i32_e32 v32, 5, v32
	v_mad_u64_u32 v[160:161], s[26:27], v32, s34, v[128:129]
	v_add_u32_e32 v32, 0x1400, v129
	v_ashrrev_i32_e32 v32, 5, v32
	v_mad_u64_u32 v[162:163], s[26:27], v32, s34, v[128:129]
	v_add_u32_e32 v32, 0x1600, v129
	v_ashrrev_i32_e32 v32, 5, v32
	v_mad_u64_u32 v[164:165], s[26:27], v32, s34, v[128:129]
	v_add_u32_e32 v32, 0x1800, v129
	v_ashrrev_i32_e32 v32, 5, v32
	v_mad_u64_u32 v[166:167], s[26:27], v32, s34, v[128:129]
	v_add_u32_e32 v32, 0x1a00, v129
	v_ashrrev_i32_e32 v32, 5, v32
	v_mad_u64_u32 v[168:169], s[26:27], v32, s34, v[128:129]
	v_add_u32_e32 v32, 0x1c00, v129
	v_ashrrev_i32_e32 v32, 5, v32
	v_mad_u64_u32 v[170:171], s[26:27], v32, s34, v[128:129]
	v_add_u32_e32 v32, 0x1e00, v129
	v_ashrrev_i32_e32 v32, 5, v32
	ds_write_b128 v144, v[36:39]
	ds_write_b128 v146, v[40:43]
	ds_write_b128 v148, v[44:47]
	ds_write_b128 v150, v[48:51]
	ds_write_b128 v152, v[52:55]
	ds_write_b128 v154, v[56:59]
	ds_write_b128 v156, v[60:63]
	ds_write_b128 v158, v[64:67]
	ds_write_b128 v160, v[68:71]
	v_mad_u64_u32 v[172:173], s[26:27], v32, s34, v[128:129]
	ds_write_b128 v162, v[72:75]
	ds_write_b128 v164, v[76:79]
	ds_write_b128 v166, v[98:101]
	v_add3_u32 v98, 0, v143, v102
	ds_write_b128 v168, v[108:111]
	v_add_u32_e32 v99, 0x10800, v98
	ds_write_b128 v170, v[116:119]
	v_add_u32_e32 v108, 0x12900, v98
	ds_write_b128 v172, v[120:123]
	s_waitcnt lgkmcnt(0)
	s_barrier
	ds_read_b128 v[32:35], v98
	ds_read_b128 v[36:39], v98 offset:64
	ds_read_b128 v[40:43], v98 offset:8448
	ds_read_b128 v[44:47], v98 offset:8512
	s_waitcnt lgkmcnt(3)
	v_mfma_f32_16x16x32_bf16 v[32:35], v[32:35], v[28:31], 0
	v_add_u32_e32 v120, 0x16b00, v98
	v_add_u32_e32 v136, 0x1ad00, v98
	s_waitcnt lgkmcnt(1)
	v_mfma_f32_16x16x32_bf16 v[40:43], v[40:43], v[28:31], 0
	v_mfma_f32_16x16x32_bf16 v[32:35], v[36:39], v[24:27], v[32:35]
	s_waitcnt lgkmcnt(0)
	v_mfma_f32_16x16x32_bf16 v[36:39], v[44:47], v[24:27], v[40:43]
	s_nop 4
	ds_read_b128 v[40:43], v98 offset:128
	ds_read_b128 v[44:47], v98 offset:192
	s_waitcnt lgkmcnt(1)
	v_mfma_f32_16x16x32_bf16 v[32:35], v[40:43], v[20:23], v[32:35]
	ds_read_b128 v[40:43], v98 offset:8576
	ds_read_b128 v[48:51], v98 offset:8640
	s_waitcnt lgkmcnt(1)
	v_mfma_f32_16x16x32_bf16 v[36:39], v[40:43], v[20:23], v[36:39]
	v_mfma_f32_16x16x32_bf16 v[32:35], v[44:47], v[16:19], v[32:35]
	ds_read_b128 v[40:43], v98 offset:256
	ds_read_b128 v[44:47], v98 offset:320
	s_waitcnt lgkmcnt(2)
	v_mfma_f32_16x16x32_bf16 v[36:39], v[48:51], v[16:19], v[36:39]
	s_waitcnt lgkmcnt(1)
	v_mfma_f32_16x16x32_bf16 v[32:35], v[40:43], v[12:15], v[32:35]
	ds_read_b128 v[40:43], v98 offset:8704
	ds_read_b128 v[48:51], v98 offset:8768
	s_waitcnt lgkmcnt(1)
	v_mfma_f32_16x16x32_bf16 v[36:39], v[40:43], v[12:15], v[36:39]
	v_mfma_f32_16x16x32_bf16 v[32:35], v[44:47], v[8:11], v[32:35]
	ds_read_b128 v[40:43], v98 offset:384
	ds_read_b128 v[44:47], v98 offset:448
	s_waitcnt lgkmcnt(2)
	v_mfma_f32_16x16x32_bf16 v[36:39], v[48:51], v[8:11], v[36:39]
	s_waitcnt lgkmcnt(1)
	v_mfma_f32_16x16x32_bf16 v[32:35], v[40:43], v[4:7], v[32:35]
	ds_read_b128 v[40:43], v98 offset:8832
	ds_read_b128 v[48:51], v98 offset:8896
	s_waitcnt lgkmcnt(1)
	v_mfma_f32_16x16x32_bf16 v[40:43], v[40:43], v[4:7], v[36:39]
	v_mfma_f32_16x16x32_bf16 v[36:39], v[44:47], v[0:3], v[32:35]
	s_waitcnt lgkmcnt(0)
	v_mfma_f32_16x16x32_bf16 v[32:35], v[48:51], v[0:3], v[40:43]
	s_nop 4
	ds_read_b128 v[40:43], v98 offset:16896
	ds_read_b128 v[44:47], v98 offset:16960
	ds_read_b128 v[48:51], v98 offset:25344
	ds_read_b128 v[52:55], v98 offset:25408
	s_waitcnt lgkmcnt(3)
	v_mfma_f32_16x16x32_bf16 v[40:43], v[40:43], v[28:31], 0
	s_waitcnt lgkmcnt(1)
	v_mfma_f32_16x16x32_bf16 v[48:51], v[48:51], v[28:31], 0
	v_mfma_f32_16x16x32_bf16 v[40:43], v[44:47], v[24:27], v[40:43]
	s_waitcnt lgkmcnt(0)
	v_mfma_f32_16x16x32_bf16 v[44:47], v[52:55], v[24:27], v[48:51]
	s_nop 4
	ds_read_b128 v[48:51], v98 offset:17024
	ds_read_b128 v[52:55], v98 offset:17088
	s_waitcnt lgkmcnt(1)
	v_mfma_f32_16x16x32_bf16 v[40:43], v[48:51], v[20:23], v[40:43]
	ds_read_b128 v[48:51], v98 offset:25472
	ds_read_b128 v[56:59], v98 offset:25536
	s_waitcnt lgkmcnt(1)
	v_mfma_f32_16x16x32_bf16 v[44:47], v[48:51], v[20:23], v[44:47]
	v_mfma_f32_16x16x32_bf16 v[40:43], v[52:55], v[16:19], v[40:43]
	ds_read_b128 v[48:51], v98 offset:17152
	ds_read_b128 v[52:55], v98 offset:17216
	s_waitcnt lgkmcnt(2)
	v_mfma_f32_16x16x32_bf16 v[44:47], v[56:59], v[16:19], v[44:47]
	s_waitcnt lgkmcnt(1)
	v_mfma_f32_16x16x32_bf16 v[40:43], v[48:51], v[12:15], v[40:43]
	ds_read_b128 v[48:51], v98 offset:25600
	ds_read_b128 v[56:59], v98 offset:25664
	s_waitcnt lgkmcnt(1)
	v_mfma_f32_16x16x32_bf16 v[44:47], v[48:51], v[12:15], v[44:47]
	v_mfma_f32_16x16x32_bf16 v[40:43], v[52:55], v[8:11], v[40:43]
	ds_read_b128 v[48:51], v98 offset:17280
	ds_read_b128 v[52:55], v98 offset:17344
	s_waitcnt lgkmcnt(2)
	v_mfma_f32_16x16x32_bf16 v[44:47], v[56:59], v[8:11], v[44:47]
	s_waitcnt lgkmcnt(1)
	v_mfma_f32_16x16x32_bf16 v[40:43], v[48:51], v[4:7], v[40:43]
	ds_read_b128 v[48:51], v98 offset:25728
	ds_read_b128 v[56:59], v98 offset:25792
	s_waitcnt lgkmcnt(1)
	v_mfma_f32_16x16x32_bf16 v[48:51], v[48:51], v[4:7], v[44:47]
	v_mfma_f32_16x16x32_bf16 v[44:47], v[52:55], v[0:3], v[40:43]
	s_waitcnt lgkmcnt(0)
	v_mfma_f32_16x16x32_bf16 v[40:43], v[56:59], v[0:3], v[48:51]
	s_nop 4
	ds_read_b128 v[48:51], v98 offset:33792
	ds_read_b128 v[52:55], v98 offset:33856
	ds_read_b128 v[56:59], v98 offset:42240
	ds_read_b128 v[60:63], v98 offset:42304
	s_waitcnt lgkmcnt(3)
	v_mfma_f32_16x16x32_bf16 v[48:51], v[48:51], v[28:31], 0
	s_waitcnt lgkmcnt(1)
	v_mfma_f32_16x16x32_bf16 v[56:59], v[56:59], v[28:31], 0
	v_mfma_f32_16x16x32_bf16 v[48:51], v[52:55], v[24:27], v[48:51]
	s_waitcnt lgkmcnt(0)
	v_mfma_f32_16x16x32_bf16 v[52:55], v[60:63], v[24:27], v[56:59]
	s_nop 4
	ds_read_b128 v[56:59], v98 offset:33920
	ds_read_b128 v[60:63], v98 offset:33984
	s_waitcnt lgkmcnt(1)
	v_mfma_f32_16x16x32_bf16 v[48:51], v[56:59], v[20:23], v[48:51]
	ds_read_b128 v[56:59], v98 offset:42368
	ds_read_b128 v[64:67], v98 offset:42432
	s_waitcnt lgkmcnt(1)
	v_mfma_f32_16x16x32_bf16 v[52:55], v[56:59], v[20:23], v[52:55]
	v_mfma_f32_16x16x32_bf16 v[48:51], v[60:63], v[16:19], v[48:51]
	ds_read_b128 v[56:59], v98 offset:34048
	ds_read_b128 v[60:63], v98 offset:34112
	s_waitcnt lgkmcnt(2)
	v_mfma_f32_16x16x32_bf16 v[52:55], v[64:67], v[16:19], v[52:55]
	s_waitcnt lgkmcnt(1)
	v_mfma_f32_16x16x32_bf16 v[48:51], v[56:59], v[12:15], v[48:51]
	ds_read_b128 v[56:59], v98 offset:42496
	ds_read_b128 v[64:67], v98 offset:42560
	s_waitcnt lgkmcnt(1)
	v_mfma_f32_16x16x32_bf16 v[52:55], v[56:59], v[12:15], v[52:55]
	v_mfma_f32_16x16x32_bf16 v[48:51], v[60:63], v[8:11], v[48:51]
	ds_read_b128 v[56:59], v98 offset:34176
	ds_read_b128 v[60:63], v98 offset:34240
	s_waitcnt lgkmcnt(2)
	v_mfma_f32_16x16x32_bf16 v[52:55], v[64:67], v[8:11], v[52:55]
	s_waitcnt lgkmcnt(1)
	v_mfma_f32_16x16x32_bf16 v[48:51], v[56:59], v[4:7], v[48:51]
	ds_read_b128 v[56:59], v98 offset:42624
	ds_read_b128 v[64:67], v98 offset:42688
	s_waitcnt lgkmcnt(1)
	v_mfma_f32_16x16x32_bf16 v[56:59], v[56:59], v[4:7], v[52:55]
	v_mfma_f32_16x16x32_bf16 v[52:55], v[60:63], v[0:3], v[48:51]
	s_waitcnt lgkmcnt(0)
	v_mfma_f32_16x16x32_bf16 v[48:51], v[64:67], v[0:3], v[56:59]
	s_nop 4
	ds_read_b128 v[56:59], v98 offset:50688
	ds_read_b128 v[60:63], v98 offset:50752
	ds_read_b128 v[64:67], v98 offset:59136
	ds_read_b128 v[68:71], v98 offset:59200
	s_waitcnt lgkmcnt(3)
	v_mfma_f32_16x16x32_bf16 v[56:59], v[56:59], v[28:31], 0
	s_waitcnt lgkmcnt(1)
	v_mfma_f32_16x16x32_bf16 v[64:67], v[64:67], v[28:31], 0
	v_mfma_f32_16x16x32_bf16 v[56:59], v[60:63], v[24:27], v[56:59]
	s_waitcnt lgkmcnt(0)
	v_mfma_f32_16x16x32_bf16 v[60:63], v[68:71], v[24:27], v[64:67]
	s_nop 4
	ds_read_b128 v[64:67], v98 offset:50816
	ds_read_b128 v[68:71], v98 offset:50880
	s_waitcnt lgkmcnt(1)
	v_mfma_f32_16x16x32_bf16 v[56:59], v[64:67], v[20:23], v[56:59]
	ds_read_b128 v[64:67], v98 offset:59264
	ds_read_b128 v[72:75], v98 offset:59328
	s_waitcnt lgkmcnt(1)
	v_mfma_f32_16x16x32_bf16 v[60:63], v[64:67], v[20:23], v[60:63]
	v_mfma_f32_16x16x32_bf16 v[56:59], v[68:71], v[16:19], v[56:59]
	ds_read_b128 v[64:67], v98 offset:50944
	ds_read_b128 v[68:71], v98 offset:51008
	s_waitcnt lgkmcnt(2)
	v_mfma_f32_16x16x32_bf16 v[60:63], v[72:75], v[16:19], v[60:63]
	s_waitcnt lgkmcnt(1)
	v_mfma_f32_16x16x32_bf16 v[56:59], v[64:67], v[12:15], v[56:59]
	ds_read_b128 v[64:67], v98 offset:59392
	ds_read_b128 v[72:75], v98 offset:59456
	s_waitcnt lgkmcnt(1)
	v_mfma_f32_16x16x32_bf16 v[60:63], v[64:67], v[12:15], v[60:63]
	v_mfma_f32_16x16x32_bf16 v[56:59], v[68:71], v[8:11], v[56:59]
	ds_read_b128 v[64:67], v98 offset:51072
	ds_read_b128 v[68:71], v98 offset:51136
	s_waitcnt lgkmcnt(2)
	v_mfma_f32_16x16x32_bf16 v[60:63], v[72:75], v[8:11], v[60:63]
	s_waitcnt lgkmcnt(1)
	v_mfma_f32_16x16x32_bf16 v[56:59], v[64:67], v[4:7], v[56:59]
	ds_read_b128 v[64:67], v98 offset:59520
	ds_read_b128 v[72:75], v98 offset:59584
	s_waitcnt lgkmcnt(1)
	v_mfma_f32_16x16x32_bf16 v[64:67], v[64:67], v[4:7], v[60:63]
	v_mfma_f32_16x16x32_bf16 v[60:63], v[68:71], v[0:3], v[56:59]
	ds_read_b128 v[68:71], v99 offset:64
	s_waitcnt lgkmcnt(1)
	v_mfma_f32_16x16x32_bf16 v[56:59], v[72:75], v[0:3], v[64:67]
	s_nop 3
	ds_read_b128 v[64:67], v99
	ds_read_b128 v[72:75], v108
	ds_read_b128 v[76:79], v108 offset:64
	s_waitcnt lgkmcnt(2)
	v_mfma_f32_16x16x32_bf16 v[64:67], v[64:67], v[28:31], 0
	s_waitcnt lgkmcnt(1)
	v_mfma_f32_16x16x32_bf16 v[72:75], v[72:75], v[28:31], 0
	v_mfma_f32_16x16x32_bf16 v[64:67], v[68:71], v[24:27], v[64:67]
	s_waitcnt lgkmcnt(0)
	v_mfma_f32_16x16x32_bf16 v[68:71], v[76:79], v[24:27], v[72:75]
	s_nop 4
	ds_read_b128 v[72:75], v99 offset:128
	ds_read_b128 v[76:79], v99 offset:192
	s_waitcnt lgkmcnt(1)
	v_mfma_f32_16x16x32_bf16 v[64:67], v[72:75], v[20:23], v[64:67]
	ds_read_b128 v[72:75], v108 offset:128
	ds_read_b128 v[100:103], v108 offset:192
	s_waitcnt lgkmcnt(1)
	v_mfma_f32_16x16x32_bf16 v[68:71], v[72:75], v[20:23], v[68:71]
	v_mfma_f32_16x16x32_bf16 v[64:67], v[76:79], v[16:19], v[64:67]
	ds_read_b128 v[72:75], v99 offset:256
	ds_read_b128 v[76:79], v99 offset:320
	s_waitcnt lgkmcnt(2)
	v_mfma_f32_16x16x32_bf16 v[68:71], v[100:103], v[16:19], v[68:71]
	s_waitcnt lgkmcnt(1)
	v_mfma_f32_16x16x32_bf16 v[64:67], v[72:75], v[12:15], v[64:67]
	ds_read_b128 v[72:75], v108 offset:256
	ds_read_b128 v[100:103], v108 offset:320
	s_waitcnt lgkmcnt(1)
	v_mfma_f32_16x16x32_bf16 v[68:71], v[72:75], v[12:15], v[68:71]
	v_mfma_f32_16x16x32_bf16 v[64:67], v[76:79], v[8:11], v[64:67]
	ds_read_b128 v[72:75], v99 offset:384
	ds_read_b128 v[76:79], v99 offset:448
	v_add_u32_e32 v99, 0x14a00, v98
	s_waitcnt lgkmcnt(2)
	v_mfma_f32_16x16x32_bf16 v[68:71], v[100:103], v[8:11], v[68:71]
	s_waitcnt lgkmcnt(1)
	v_mfma_f32_16x16x32_bf16 v[64:67], v[72:75], v[4:7], v[64:67]
	ds_read_b128 v[72:75], v108 offset:384
	ds_read_b128 v[100:103], v108 offset:448
	s_waitcnt lgkmcnt(1)
	v_mfma_f32_16x16x32_bf16 v[72:75], v[72:75], v[4:7], v[68:71]
	v_mfma_f32_16x16x32_bf16 v[68:71], v[76:79], v[0:3], v[64:67]
	ds_read_b128 v[76:79], v99 offset:64
	s_waitcnt lgkmcnt(1)
	v_mfma_f32_16x16x32_bf16 v[64:67], v[100:103], v[0:3], v[72:75]
	s_nop 3
	ds_read_b128 v[72:75], v99
	ds_read_b128 v[100:103], v120
	ds_read_b128 v[108:111], v120 offset:64
	s_waitcnt lgkmcnt(2)
	v_mfma_f32_16x16x32_bf16 v[72:75], v[72:75], v[28:31], 0
	s_waitcnt lgkmcnt(1)
	v_mfma_f32_16x16x32_bf16 v[100:103], v[100:103], v[28:31], 0
	v_mfma_f32_16x16x32_bf16 v[72:75], v[76:79], v[24:27], v[72:75]
	s_waitcnt lgkmcnt(0)
	v_mfma_f32_16x16x32_bf16 v[76:79], v[108:111], v[24:27], v[100:103]
	s_nop 4
	ds_read_b128 v[100:103], v99 offset:128
	ds_read_b128 v[108:111], v99 offset:192
	s_waitcnt lgkmcnt(1)
	v_mfma_f32_16x16x32_bf16 v[72:75], v[100:103], v[20:23], v[72:75]
	ds_read_b128 v[100:103], v120 offset:128
	ds_read_b128 v[116:119], v120 offset:192
	s_waitcnt lgkmcnt(1)
	v_mfma_f32_16x16x32_bf16 v[76:79], v[100:103], v[20:23], v[76:79]
	v_mfma_f32_16x16x32_bf16 v[72:75], v[108:111], v[16:19], v[72:75]
	ds_read_b128 v[100:103], v99 offset:256
	ds_read_b128 v[108:111], v99 offset:320
	s_waitcnt lgkmcnt(2)
	v_mfma_f32_16x16x32_bf16 v[76:79], v[116:119], v[16:19], v[76:79]
	s_waitcnt lgkmcnt(1)
	v_mfma_f32_16x16x32_bf16 v[72:75], v[100:103], v[12:15], v[72:75]
	ds_read_b128 v[100:103], v120 offset:256
	ds_read_b128 v[116:119], v120 offset:320
	s_waitcnt lgkmcnt(1)
	v_mfma_f32_16x16x32_bf16 v[76:79], v[100:103], v[12:15], v[76:79]
	v_mfma_f32_16x16x32_bf16 v[72:75], v[108:111], v[8:11], v[72:75]
	ds_read_b128 v[100:103], v99 offset:384
	ds_read_b128 v[108:111], v99 offset:448
	v_add_u32_e32 v99, 0x18c00, v98
	s_waitcnt lgkmcnt(2)
	v_mfma_f32_16x16x32_bf16 v[76:79], v[116:119], v[8:11], v[76:79]
	s_waitcnt lgkmcnt(1)
	v_mfma_f32_16x16x32_bf16 v[72:75], v[100:103], v[4:7], v[72:75]
	ds_read_b128 v[100:103], v120 offset:384
	ds_read_b128 v[116:119], v120 offset:448
	s_waitcnt lgkmcnt(1)
	v_mfma_f32_16x16x32_bf16 v[100:103], v[100:103], v[4:7], v[76:79]
	v_mfma_f32_16x16x32_bf16 v[76:79], v[108:111], v[0:3], v[72:75]
	ds_read_b128 v[108:111], v99 offset:64
	s_waitcnt lgkmcnt(1)
	v_mfma_f32_16x16x32_bf16 v[72:75], v[116:119], v[0:3], v[100:103]
	s_nop 3
	ds_read_b128 v[100:103], v99
	ds_read_b128 v[116:119], v136
	ds_read_b128 v[120:123], v136 offset:64
	s_waitcnt lgkmcnt(2)
	v_mfma_f32_16x16x32_bf16 v[100:103], v[100:103], v[28:31], 0
	s_waitcnt lgkmcnt(1)
	v_mfma_f32_16x16x32_bf16 v[116:119], v[116:119], v[28:31], 0
	v_mfma_f32_16x16x32_bf16 v[100:103], v[108:111], v[24:27], v[100:103]
	s_waitcnt lgkmcnt(0)
	v_mfma_f32_16x16x32_bf16 v[108:111], v[120:123], v[24:27], v[116:119]
	s_nop 4
	ds_read_b128 v[116:119], v99 offset:128
	ds_read_b128 v[120:123], v99 offset:192
	s_waitcnt lgkmcnt(1)
	v_mfma_f32_16x16x32_bf16 v[100:103], v[116:119], v[20:23], v[100:103]
	ds_read_b128 v[116:119], v136 offset:128
	ds_read_b128 v[128:131], v136 offset:192
	s_waitcnt lgkmcnt(1)
	v_mfma_f32_16x16x32_bf16 v[108:111], v[116:119], v[20:23], v[108:111]
	v_mfma_f32_16x16x32_bf16 v[100:103], v[120:123], v[16:19], v[100:103]
	ds_read_b128 v[116:119], v99 offset:256
	ds_read_b128 v[120:123], v99 offset:320
	s_waitcnt lgkmcnt(2)
	v_mfma_f32_16x16x32_bf16 v[108:111], v[128:131], v[16:19], v[108:111]
	s_waitcnt lgkmcnt(1)
	v_mfma_f32_16x16x32_bf16 v[100:103], v[116:119], v[12:15], v[100:103]
	ds_read_b128 v[116:119], v136 offset:256
	ds_read_b128 v[128:131], v136 offset:320
	s_waitcnt lgkmcnt(1)
	v_mfma_f32_16x16x32_bf16 v[108:111], v[116:119], v[12:15], v[108:111]
	v_mfma_f32_16x16x32_bf16 v[100:103], v[120:123], v[8:11], v[100:103]
	ds_read_b128 v[116:119], v99 offset:384
	ds_read_b128 v[120:123], v99 offset:448
	v_add_u32_e32 v99, 0x1ce00, v98
	v_add_u32_e32 v98, 0x1ef00, v98
	s_waitcnt lgkmcnt(2)
	v_mfma_f32_16x16x32_bf16 v[108:111], v[128:131], v[8:11], v[108:111]
	s_waitcnt lgkmcnt(1)
	v_mfma_f32_16x16x32_bf16 v[100:103], v[116:119], v[4:7], v[100:103]
	ds_read_b128 v[116:119], v136 offset:384
	ds_read_b128 v[128:131], v136 offset:448
	s_waitcnt lgkmcnt(1)
	v_mfma_f32_16x16x32_bf16 v[108:111], v[116:119], v[4:7], v[108:111]
	ds_read_b128 v[116:119], v99 offset:64
	v_mfma_f32_16x16x32_bf16 v[120:123], v[120:123], v[0:3], v[100:103]
	s_waitcnt lgkmcnt(1)
	v_mfma_f32_16x16x32_bf16 v[100:103], v[128:131], v[0:3], v[108:111]
	s_nop 3
	ds_read_b128 v[108:111], v99
	ds_read_b128 v[128:131], v98
	ds_read_b128 v[136:139], v98 offset:64
	s_waitcnt lgkmcnt(2)
	v_mfma_f32_16x16x32_bf16 v[108:111], v[108:111], v[28:31], 0
	s_waitcnt lgkmcnt(1)
	v_mfma_f32_16x16x32_bf16 v[28:31], v[128:131], v[28:31], 0
	v_mfma_f32_16x16x32_bf16 v[108:111], v[116:119], v[24:27], v[108:111]
	s_waitcnt lgkmcnt(0)
	v_mfma_f32_16x16x32_bf16 v[24:27], v[136:139], v[24:27], v[28:31]
	s_nop 4
	ds_read_b128 v[28:31], v99 offset:128
	ds_read_b128 v[116:119], v99 offset:192
	s_waitcnt lgkmcnt(1)
	v_mfma_f32_16x16x32_bf16 v[28:31], v[28:31], v[20:23], v[108:111]
	s_nop 2
	ds_read_b128 v[108:111], v98 offset:128
	ds_read_b128 v[128:131], v98 offset:192
	s_waitcnt lgkmcnt(1)
	v_mfma_f32_16x16x32_bf16 v[20:23], v[108:111], v[20:23], v[24:27]
	v_mfma_f32_16x16x32_bf16 v[24:27], v[116:119], v[16:19], v[28:31]
	s_nop 2
	ds_read_b128 v[28:31], v99 offset:256
	s_waitcnt lgkmcnt(1)
	v_mfma_f32_16x16x32_bf16 v[16:19], v[128:131], v[16:19], v[20:23]
	s_nop 2
	ds_read_b128 v[20:23], v98 offset:256
	ds_read_b128 v[108:111], v99 offset:320
	ds_read_b128 v[116:119], v98 offset:320
	s_waitcnt lgkmcnt(3)
	v_mfma_f32_16x16x32_bf16 v[24:27], v[28:31], v[12:15], v[24:27]
	ds_read_b128 v[28:31], v99 offset:384
	ds_read_b128 v[128:131], v99 offset:448
	ds_read_b128 v[136:139], v98 offset:384
	ds_read_b128 v[176:179], v98 offset:448
	s_waitcnt lgkmcnt(6)
	v_mfma_f32_16x16x32_bf16 v[12:15], v[20:23], v[12:15], v[16:19]
	s_waitcnt lgkmcnt(5)
	v_mfma_f32_16x16x32_bf16 v[24:27], v[108:111], v[8:11], v[24:27]
	s_nop 0
	v_lshl_add_u64 v[16:17], s[0:1], 0, v[80:81]
	s_mov_b64 s[0:1], 0x6c00000
	v_lshl_add_u64 v[180:181], v[16:17], 0, s[0:1]
	s_waitcnt lgkmcnt(4)
	v_mfma_f32_16x16x32_bf16 v[8:11], v[116:119], v[8:11], v[12:15]
	v_lshl_add_u64 v[16:17], v[180:181], 0, v[82:83]
	v_lshl_add_u64 v[20:21], v[180:181], 0, v[84:85]
	v_lshl_add_u64 v[80:81], v[180:181], 0, v[86:87]
	s_waitcnt lgkmcnt(3)
	v_mfma_f32_16x16x32_bf16 v[12:15], v[28:31], v[4:7], v[24:27]
	v_lshl_add_u64 v[82:83], v[180:181], 0, v[88:89]
	global_load_dwordx4 v[16:19], v[16:17], off
	s_nop 0
	global_load_dwordx4 v[20:23], v[20:21], off
	v_lshl_add_u64 v[24:25], v[180:181], 0, v[90:91]
	s_waitcnt lgkmcnt(0)
	v_mfma_f32_16x16x32_bf16 v[8:11], v[136:139], v[4:7], v[8:11]
	global_load_dwordx4 v[28:31], v[80:81], off
	s_nop 0
	global_load_dwordx4 v[80:83], v[82:83], off
	v_lshl_add_u64 v[26:27], v[180:181], 0, v[92:93]
	global_load_dwordx4 v[84:87], v[24:25], off
	global_load_dwordx4 v[88:91], v[26:27], off
	v_lshl_add_u64 v[24:25], v[180:181], 0, v[94:95]
	v_mfma_f32_16x16x32_bf16 v[4:7], v[128:131], v[0:3], v[12:15]
	v_lshl_add_u64 v[26:27], v[180:181], 0, v[96:97]
	global_load_dwordx4 v[92:95], v[24:25], off
	global_load_dwordx4 v[96:99], v[26:27], off
	v_lshl_add_u64 v[12:13], v[180:181], 0, v[104:105]
	v_mfma_f32_16x16x32_bf16 v[0:3], v[176:179], v[0:3], v[8:11]
	s_mov_b64 s[0:1], s[42:43]
	s_nop 1
	v_lshl_add_u64 v[8:9], v[180:181], 0, v[106:107]
	global_load_dwordx4 v[104:107], v[12:13], off
	global_load_dwordx4 v[108:111], v[8:9], off
	v_lshl_add_u64 v[8:9], v[180:181], 0, v[112:113]
	v_lshl_add_u64 v[10:11], v[180:181], 0, v[114:115]
	global_load_dwordx4 v[112:115], v[8:9], off
	global_load_dwordx4 v[116:119], v[10:11], off
	v_max_f32_e32 v8, v38, v38
	v_max_f32_e32 v9, v37, v37
	v_max_f32_e32 v8, v9, v8
	v_max3_f32 v8, v36, s33, v8
	v_max_f32_e32 v9, v34, v34
	v_max_f32_e32 v10, v33, v33
	v_max3_f32 v8, v8, v39, v32
	v_max_f32_e32 v9, v10, v9
	v_max3_f32 v8, v8, v9, v35
	v_max_f32_e32 v9, v46, v46
	v_max_f32_e32 v10, v45, v45
	v_max_f32_e32 v9, v10, v9
	v_max3_f32 v8, v8, v44, v9
	v_max_f32_e32 v9, v42, v42
	v_max_f32_e32 v10, v41, v41
	v_max3_f32 v8, v8, v47, v40
	v_max_f32_e32 v9, v10, v9
	v_max3_f32 v8, v8, v9, v43
	v_max_f32_e32 v9, v54, v54
	v_max_f32_e32 v10, v53, v53
	v_max_f32_e32 v9, v10, v9
	v_max3_f32 v8, v8, v52, v9
	v_max_f32_e32 v9, v50, v50
	v_max_f32_e32 v10, v49, v49
	v_max3_f32 v8, v8, v55, v48
	v_max_f32_e32 v9, v10, v9
	v_max3_f32 v8, v8, v9, v51
	v_max_f32_e32 v9, v62, v62
	v_max_f32_e32 v10, v61, v61
	v_max_f32_e32 v9, v10, v9
	v_max3_f32 v8, v8, v60, v9
	v_max_f32_e32 v9, v58, v58
	v_max_f32_e32 v10, v57, v57
	v_max3_f32 v8, v8, v63, v56
	v_max_f32_e32 v9, v10, v9
	v_max3_f32 v8, v8, v9, v59
	v_max_f32_e32 v9, v70, v70
	v_max_f32_e32 v10, v69, v69
	v_max_f32_e32 v9, v10, v9
	v_max3_f32 v8, v8, v68, v9
	v_max_f32_e32 v9, v66, v66
	v_max_f32_e32 v10, v65, v65
	v_max3_f32 v8, v8, v71, v64
	v_max_f32_e32 v9, v10, v9
	v_max3_f32 v8, v8, v9, v67
	v_max_f32_e32 v9, v78, v78
	v_max_f32_e32 v10, v77, v77
	v_max_f32_e32 v9, v10, v9
	v_max3_f32 v8, v8, v76, v9
	v_max_f32_e32 v9, v74, v74
	v_max_f32_e32 v10, v73, v73
	v_max3_f32 v8, v8, v79, v72
	v_max_f32_e32 v9, v10, v9
	v_max3_f32 v8, v8, v9, v75
	v_max_f32_e32 v9, v122, v122
	v_max_f32_e32 v10, v121, v121
	v_max_f32_e32 v9, v10, v9
	v_max3_f32 v8, v8, v120, v9
	v_max_f32_e32 v9, v102, v102
	v_max_f32_e32 v10, v101, v101
	v_max3_f32 v8, v8, v123, v100
	v_max_f32_e32 v9, v10, v9
	v_max3_f32 v8, v8, v9, v103
	v_max_f32_e32 v9, v6, v6
	v_max_f32_e32 v10, v5, v5
	v_max_f32_e32 v9, v10, v9
	v_max3_f32 v8, v8, v4, v9
	v_max_f32_e32 v9, v2, v2
	v_max_f32_e32 v10, v1, v1
	v_max3_f32 v8, v8, v7, v0
	v_max_f32_e32 v9, v10, v9
	v_max3_f32 v12, v8, v9, v3
	v_cndmask_b32_e32 v8, v217, v223, vcc
	v_lshlrev_b32_e32 v13, 2, v8
	ds_bpermute_b32 v14, v13, v12
	v_lshl_add_u64 v[8:9], v[180:181], 0, v[124:125]
	v_lshl_add_u64 v[10:11], v[180:181], 0, v[126:127]
	global_load_dwordx4 v[124:127], v[8:9], off
	global_load_dwordx4 v[128:131], v[10:11], off
	v_cmp_lt_i32_e32 vcc, v224, v218
	s_waitcnt lgkmcnt(0)
	v_max_f32_e32 v8, v14, v14
	v_max_f32_e32 v12, v12, v8
	v_cndmask_b32_e32 v8, v217, v224, vcc
	v_lshlrev_b32_e32 v14, 2, v8
	ds_bpermute_b32 v15, v14, v12
	v_lshl_add_u64 v[8:9], v[180:181], 0, v[132:133]
	v_lshl_add_u64 v[10:11], v[180:181], 0, v[134:135]
	global_load_dwordx4 v[132:135], v[8:9], off
	global_load_dwordx4 v[136:139], v[10:11], off
	s_waitcnt lgkmcnt(0)
	v_max_f32_e32 v8, v15, v15
	v_max_f32_e32 v8, v12, v8
	v_sub_f32_e32 v9, v36, v8
	v_exp_f32_e32 v9, v9
	v_sub_f32_e32 v10, v37, v8
	v_exp_f32_e32 v10, v10
	v_sub_f32_e32 v11, v38, v8
	v_exp_f32_e32 v11, v11
	v_sub_f32_e32 v12, v39, v8
	v_exp_f32_e32 v12, v12
	v_sub_f32_e32 v24, v32, v8
	v_add_f32_e32 v15, 0, v9
	v_exp_f32_e32 v24, v24
	v_sub_f32_e32 v25, v33, v8
	v_add_f32_e32 v15, v10, v15
	v_exp_f32_e32 v25, v25
	v_sub_f32_e32 v26, v34, v8
	v_add_f32_e32 v15, v11, v15
	v_exp_f32_e32 v26, v26
	v_sub_f32_e32 v27, v35, v8
	v_add_f32_e32 v15, v12, v15
	v_exp_f32_e32 v27, v27
	v_sub_f32_e32 v32, v44, v8
	v_add_f32_e32 v15, v24, v15
	v_exp_f32_e32 v32, v32
	v_sub_f32_e32 v33, v45, v8
	v_add_f32_e32 v15, v25, v15
	v_exp_f32_e32 v33, v33
	v_sub_f32_e32 v34, v46, v8
	v_add_f32_e32 v15, v26, v15
	v_exp_f32_e32 v34, v34
	v_sub_f32_e32 v35, v47, v8
	v_add_f32_e32 v15, v27, v15
	v_exp_f32_e32 v35, v35
	v_sub_f32_e32 v36, v40, v8
	v_add_f32_e32 v15, v32, v15
	v_exp_f32_e32 v36, v36
	v_sub_f32_e32 v37, v41, v8
	v_add_f32_e32 v15, v33, v15
	v_exp_f32_e32 v37, v37
	v_sub_f32_e32 v38, v42, v8
	v_add_f32_e32 v15, v34, v15
	v_exp_f32_e32 v38, v38
	v_sub_f32_e32 v39, v43, v8
	v_add_f32_e32 v15, v35, v15
	v_exp_f32_e32 v39, v39
	v_sub_f32_e32 v40, v52, v8
	v_add_f32_e32 v15, v36, v15
	v_exp_f32_e32 v40, v40
	v_sub_f32_e32 v41, v53, v8
	v_add_f32_e32 v15, v37, v15
	v_exp_f32_e32 v41, v41
	v_sub_f32_e32 v42, v54, v8
	v_add_f32_e32 v15, v38, v15
	v_exp_f32_e32 v42, v42
	v_sub_f32_e32 v43, v55, v8
	v_add_f32_e32 v15, v39, v15
	v_exp_f32_e32 v43, v43
	v_sub_f32_e32 v44, v48, v8
	v_add_f32_e32 v15, v40, v15
	v_exp_f32_e32 v44, v44
	v_sub_f32_e32 v45, v49, v8
	v_add_f32_e32 v15, v41, v15
	v_exp_f32_e32 v45, v45
	v_sub_f32_e32 v46, v50, v8
	v_add_f32_e32 v15, v42, v15
	v_exp_f32_e32 v46, v46
	v_sub_f32_e32 v47, v51, v8
	v_add_f32_e32 v15, v43, v15
	v_exp_f32_e32 v47, v47
	v_sub_f32_e32 v48, v60, v8
	v_add_f32_e32 v15, v44, v15
	v_exp_f32_e32 v48, v48
	v_sub_f32_e32 v49, v61, v8
	v_add_f32_e32 v15, v45, v15
	v_exp_f32_e32 v49, v49
	v_sub_f32_e32 v50, v62, v8
	v_add_f32_e32 v15, v46, v15
	v_exp_f32_e32 v50, v50
	v_sub_f32_e32 v51, v63, v8
	v_add_f32_e32 v15, v47, v15
	v_exp_f32_e32 v51, v51
	v_sub_f32_e32 v52, v56, v8
	v_add_f32_e32 v15, v48, v15
	v_exp_f32_e32 v52, v52
	v_sub_f32_e32 v53, v57, v8
	v_add_f32_e32 v15, v49, v15
	v_exp_f32_e32 v53, v53
	v_sub_f32_e32 v54, v58, v8
	v_add_f32_e32 v15, v50, v15
	v_exp_f32_e32 v54, v54
	v_sub_f32_e32 v55, v59, v8
	v_add_f32_e32 v15, v51, v15
	v_exp_f32_e32 v55, v55
	v_sub_f32_e32 v56, v68, v8
	v_add_f32_e32 v15, v52, v15
	v_exp_f32_e32 v56, v56
	v_sub_f32_e32 v57, v69, v8
	v_add_f32_e32 v15, v53, v15
	v_exp_f32_e32 v57, v57
	v_sub_f32_e32 v58, v70, v8
	v_add_f32_e32 v15, v54, v15
	v_exp_f32_e32 v58, v58
	v_sub_f32_e32 v59, v71, v8
	v_add_f32_e32 v15, v55, v15
	v_exp_f32_e32 v59, v59
	v_sub_f32_e32 v60, v64, v8
	v_add_f32_e32 v15, v56, v15
	v_exp_f32_e32 v60, v60
	v_sub_f32_e32 v61, v65, v8
	v_add_f32_e32 v15, v57, v15
	v_exp_f32_e32 v61, v61
	v_sub_f32_e32 v62, v66, v8
	v_add_f32_e32 v15, v58, v15
	v_exp_f32_e32 v62, v62
	v_sub_f32_e32 v63, v67, v8
	v_add_f32_e32 v15, v59, v15
	v_exp_f32_e32 v63, v63
	v_sub_f32_e32 v64, v76, v8
	v_add_f32_e32 v15, v60, v15
	v_exp_f32_e32 v64, v64
	v_sub_f32_e32 v65, v77, v8
	v_add_f32_e32 v15, v61, v15
	v_exp_f32_e32 v65, v65
	v_sub_f32_e32 v66, v78, v8
	v_add_f32_e32 v15, v62, v15
	v_exp_f32_e32 v66, v66
	v_sub_f32_e32 v67, v79, v8
	v_add_f32_e32 v15, v63, v15
	v_exp_f32_e32 v67, v67
	v_sub_f32_e32 v68, v72, v8
	v_add_f32_e32 v15, v64, v15
	v_exp_f32_e32 v68, v68
	v_sub_f32_e32 v69, v73, v8
	v_add_f32_e32 v15, v65, v15
	v_exp_f32_e32 v69, v69
	v_sub_f32_e32 v70, v74, v8
	v_add_f32_e32 v15, v66, v15
	v_exp_f32_e32 v70, v70
	v_sub_f32_e32 v71, v75, v8
	v_add_f32_e32 v15, v67, v15
	v_exp_f32_e32 v71, v71
	v_sub_f32_e32 v72, v120, v8
	v_add_f32_e32 v15, v68, v15
	v_exp_f32_e32 v72, v72
	v_sub_f32_e32 v73, v121, v8
	v_add_f32_e32 v15, v69, v15
	v_exp_f32_e32 v73, v73
	v_sub_f32_e32 v74, v122, v8
	v_add_f32_e32 v15, v70, v15
	v_exp_f32_e32 v74, v74
	v_sub_f32_e32 v75, v123, v8
	v_add_f32_e32 v15, v71, v15
	v_exp_f32_e32 v75, v75
	v_sub_f32_e32 v76, v100, v8
	v_add_f32_e32 v15, v72, v15
	v_exp_f32_e32 v76, v76
	v_sub_f32_e32 v77, v101, v8
	v_add_f32_e32 v15, v73, v15
	v_exp_f32_e32 v77, v77
	v_sub_f32_e32 v78, v102, v8
	v_add_f32_e32 v15, v74, v15
	v_exp_f32_e32 v78, v78
	v_sub_f32_e32 v79, v103, v8
	v_add_f32_e32 v15, v75, v15
	v_exp_f32_e32 v79, v79
	v_sub_f32_e32 v4, v4, v8
	v_add_f32_e32 v15, v76, v15
	v_exp_f32_e32 v100, v4
	v_sub_f32_e32 v4, v5, v8
	v_add_f32_e32 v15, v77, v15
	v_exp_f32_e32 v101, v4
	v_sub_f32_e32 v4, v6, v8
	v_add_f32_e32 v15, v78, v15
	v_exp_f32_e32 v102, v4
	v_sub_f32_e32 v4, v7, v8
	v_add_f32_e32 v15, v79, v15
	v_exp_f32_e32 v103, v4
	v_sub_f32_e32 v0, v0, v8
	v_add_f32_e32 v4, v100, v15
	v_exp_f32_e32 v120, v0
	v_sub_f32_e32 v0, v1, v8
	v_add_f32_e32 v4, v101, v4
	v_exp_f32_e32 v121, v0
	v_sub_f32_e32 v0, v2, v8
	v_add_f32_e32 v4, v102, v4
	v_exp_f32_e32 v122, v0
	v_sub_f32_e32 v0, v3, v8
	v_add_f32_e32 v4, v103, v4
	v_exp_f32_e32 v123, v0
	v_add_f32_e32 v0, v120, v4
	v_add_f32_e32 v0, v121, v0
	v_add_f32_e32 v0, v122, v0
	v_add_f32_e32 v0, v123, v0
	ds_bpermute_b32 v1, v13, v0
	s_barrier
	s_waitcnt vmcnt(0) lgkmcnt(0)
	ds_write_b128 v142, v[16:19]
	ds_write_b128 v144, v[20:23]
	ds_write_b128 v146, v[28:31]
	ds_write_b128 v148, v[80:83]
	ds_write_b128 v150, v[84:87]
	ds_write_b128 v152, v[88:91]
	ds_write_b128 v154, v[92:95]
	ds_write_b128 v156, v[96:99]
	ds_write_b128 v158, v[104:107]
	ds_write_b128 v160, v[108:111]
	ds_write_b128 v162, v[112:115]
	ds_write_b128 v164, v[116:119]
	ds_write_b128 v166, v[124:127]
	ds_write_b128 v168, v[128:131]
	ds_write_b128 v170, v[132:135]
	ds_write_b128 v172, v[136:139]
	s_waitcnt lgkmcnt(0)
	v_add_f32_e32 v0, v0, v1
	ds_bpermute_b32 v1, v14, v0
	s_barrier
	s_waitcnt lgkmcnt(0)
	v_cvt_pk_bf16_f32 v2, v24, v25
	v_add_f32_e32 v145, v0, v1
	v_rcp_f32_e32 v16, v145
	v_lshl_add_u64 v[18:19], s[0:1], 0, v[140:141]
	v_lshl_add_u64 v[18:19], v[18:19], 0, s[82:83]
	v_lshl_add_u64 v[18:19], v[18:19], 0, v[192:193]
	s_mov_b64 s[0:1], 0x11e00000
	v_cvt_pk_bf16_f32 v0, v9, v10
	v_cvt_pk_bf16_f32 v1, v11, v12
	v_cvt_pk_bf16_f32 v3, v26, v27
	v_cvt_pk_bf16_f32 v4, v32, v33
	v_cvt_pk_bf16_f32 v5, v34, v35
	v_cvt_pk_bf16_f32 v6, v36, v37
	v_cvt_pk_bf16_f32 v7, v38, v39
	v_cvt_pk_bf16_f32 v8, v40, v41
	v_cvt_pk_bf16_f32 v9, v42, v43
	v_cvt_pk_bf16_f32 v10, v44, v45
	v_cvt_pk_bf16_f32 v11, v46, v47
	v_cvt_pk_bf16_f32 v12, v48, v49
	v_cvt_pk_bf16_f32 v13, v50, v51
	v_cvt_pk_bf16_f32 v14, v52, v53
	v_cvt_pk_bf16_f32 v15, v54, v55
	v_cvt_pk_bf16_f32 v24, v56, v57
	v_cvt_pk_bf16_f32 v25, v58, v59
	v_cvt_pk_bf16_f32 v26, v60, v61
	v_cvt_pk_bf16_f32 v27, v62, v63
	v_cvt_pk_bf16_f32 v32, v64, v65
	v_cvt_pk_bf16_f32 v33, v66, v67
	v_cvt_pk_bf16_f32 v34, v68, v69
	v_cvt_pk_bf16_f32 v35, v70, v71
	v_cvt_pk_bf16_f32 v36, v72, v73
	v_cvt_pk_bf16_f32 v37, v74, v75
	v_cvt_pk_bf16_f32 v38, v76, v77
	v_cvt_pk_bf16_f32 v39, v78, v79
	v_cvt_pk_bf16_f32 v40, v100, v101
	v_cvt_pk_bf16_f32 v41, v102, v103
	v_cvt_pk_bf16_f32 v42, v120, v121
	v_cvt_pk_bf16_f32 v43, v122, v123
	v_lshl_add_u64 v[18:19], v[18:19], 0, s[0:1]
	v_mov_b32_e32 v17, v16
	v_add3_u32 v20, v143, v192, 0
	s_mov_b32 s0, -2
.LBB0_47:
	ds_read2_b64 v[28:31], v20 offset1:4
	ds_read2_b64 v[48:51], v20 offset0:8 offset1:12
	v_add_u32_e32 v21, 0x2000, v20
	ds_read2_b64 v[44:47], v21 offset0:32 offset1:36
	v_add_u32_e32 v56, 0x4000, v20
	v_add_u32_e32 v57, 0x6000, v20
	s_add_i32 s0, s0, 4
	s_cmp_lt_u32 s0, 14
	s_waitcnt lgkmcnt(0)
	v_mfma_f32_16x16x32_bf16 v[28:31], v[28:31], v[0:3], 0
	s_waitcnt lgkmcnt(1)
	v_mfma_f32_16x16x32_bf16 v[28:31], v[48:51], v[4:7], v[28:31]
	ds_read2_b64 v[48:51], v21 offset0:40 offset1:44
	s_waitcnt lgkmcnt(1)
	v_mfma_f32_16x16x32_bf16 v[44:47], v[44:47], v[0:3], 0
	s_waitcnt lgkmcnt(0)
	v_mfma_f32_16x16x32_bf16 v[44:47], v[48:51], v[4:7], v[44:47]
	ds_read2_b64 v[48:51], v20 offset0:16 offset1:20
	s_waitcnt lgkmcnt(0)
	v_mfma_f32_16x16x32_bf16 v[28:31], v[48:51], v[8:11], v[28:31]
	ds_read2_b64 v[48:51], v21 offset0:48 offset1:52
	s_waitcnt lgkmcnt(0)
	v_mfma_f32_16x16x32_bf16 v[44:47], v[48:51], v[8:11], v[44:47]
	ds_read2_b64 v[48:51], v20 offset0:24 offset1:28
	s_waitcnt lgkmcnt(0)
	v_mfma_f32_16x16x32_bf16 v[28:31], v[48:51], v[12:15], v[28:31]
	ds_read2_b64 v[48:51], v21 offset0:56 offset1:60
	s_waitcnt lgkmcnt(0)
	v_mfma_f32_16x16x32_bf16 v[44:47], v[48:51], v[12:15], v[44:47]
	ds_read2_b64 v[48:51], v20 offset0:32 offset1:36
	s_waitcnt lgkmcnt(0)
	v_mfma_f32_16x16x32_bf16 v[28:31], v[48:51], v[24:27], v[28:31]
	ds_read2_b64 v[48:51], v21 offset0:64 offset1:68
	s_waitcnt lgkmcnt(0)
	v_mfma_f32_16x16x32_bf16 v[44:47], v[48:51], v[24:27], v[44:47]
	ds_read2_b64 v[48:51], v20 offset0:40 offset1:44
	s_waitcnt lgkmcnt(0)
	v_mfma_f32_16x16x32_bf16 v[28:31], v[48:51], v[32:35], v[28:31]
	ds_read2_b64 v[48:51], v21 offset0:72 offset1:76
	s_waitcnt lgkmcnt(0)
	v_mfma_f32_16x16x32_bf16 v[44:47], v[48:51], v[32:35], v[44:47]
	ds_read2_b64 v[48:51], v20 offset0:48 offset1:52
	ds_read2_b64 v[52:55], v20 offset0:56 offset1:60
	v_add_u32_e32 v20, 0x8400, v20
	s_waitcnt lgkmcnt(0)
	v_mfma_f32_16x16x32_bf16 v[28:31], v[48:51], v[36:39], v[28:31]
	ds_read2_b64 v[48:51], v21 offset0:80 offset1:84
	s_waitcnt lgkmcnt(0)
	v_mfma_f32_16x16x32_bf16 v[44:47], v[48:51], v[36:39], v[44:47]
	ds_read2_b64 v[48:51], v21 offset0:88 offset1:92
	v_mfma_f32_16x16x32_bf16 v[28:31], v[52:55], v[40:43], v[28:31]
	s_waitcnt lgkmcnt(0)
	v_mfma_f32_16x16x32_bf16 v[44:47], v[48:51], v[40:43], v[44:47]
	s_nop 5
	v_mul_f32_e64 v22, v16, v28
	v_mul_f32_e64 v23, v17, v29
	v_pk_mul_f32 v[28:29], v[16:17], v[30:31]
	v_cvt_pk_bf16_f32 v22, v22, v23
	v_cvt_pk_bf16_f32 v23, v28, v29
	v_pk_mul_f32 v[28:29], v[16:17], v[44:45]
	v_pk_mul_f32 v[30:31], v[16:17], v[46:47]
	global_store_dwordx2 v[18:19], v[22:23], off
	v_cvt_pk_bf16_f32 v22, v28, v29
	v_cvt_pk_bf16_f32 v23, v30, v31
	global_store_dwordx2 v[18:19], v[22:23], off offset:32
	ds_read2_b64 v[28:31], v56 offset0:64 offset1:68
	ds_read2_b64 v[48:51], v56 offset0:72 offset1:76
	s_waitcnt lgkmcnt(0)
	v_mfma_f32_16x16x32_bf16 v[28:31], v[28:31], v[0:3], 0
	ds_read2_b64 v[44:47], v57 offset0:96 offset1:100
	v_mfma_f32_16x16x32_bf16 v[28:31], v[48:51], v[4:7], v[28:31]
	ds_read2_b64 v[48:51], v57 offset0:104 offset1:108
	s_waitcnt lgkmcnt(0)
	v_mfma_f32_16x16x32_bf16 v[44:47], v[44:47], v[0:3], 0
	v_mfma_f32_16x16x32_bf16 v[44:47], v[48:51], v[4:7], v[44:47]
	ds_read2_b64 v[48:51], v56 offset0:80 offset1:84
	s_waitcnt lgkmcnt(0)
	v_mfma_f32_16x16x32_bf16 v[28:31], v[48:51], v[8:11], v[28:31]
	ds_read2_b64 v[48:51], v57 offset0:112 offset1:116
	s_waitcnt lgkmcnt(0)
	v_mfma_f32_16x16x32_bf16 v[44:47], v[48:51], v[8:11], v[44:47]
	ds_read2_b64 v[48:51], v56 offset0:88 offset1:92
	s_waitcnt lgkmcnt(0)
	v_mfma_f32_16x16x32_bf16 v[28:31], v[48:51], v[12:15], v[28:31]
	ds_read2_b64 v[48:51], v57 offset0:120 offset1:124
	s_waitcnt lgkmcnt(0)
	v_mfma_f32_16x16x32_bf16 v[44:47], v[48:51], v[12:15], v[44:47]
	ds_read2_b64 v[48:51], v56 offset0:96 offset1:100
	s_waitcnt lgkmcnt(0)
	v_mfma_f32_16x16x32_bf16 v[28:31], v[48:51], v[24:27], v[28:31]
	ds_read2_b64 v[48:51], v57 offset0:128 offset1:132
	s_waitcnt lgkmcnt(0)
	v_mfma_f32_16x16x32_bf16 v[44:47], v[48:51], v[24:27], v[44:47]
	ds_read2_b64 v[48:51], v56 offset0:104 offset1:108
	s_waitcnt lgkmcnt(0)
	v_mfma_f32_16x16x32_bf16 v[28:31], v[48:51], v[32:35], v[28:31]
	ds_read2_b64 v[48:51], v57 offset0:136 offset1:140
	s_waitcnt lgkmcnt(0)
	v_mfma_f32_16x16x32_bf16 v[44:47], v[48:51], v[32:35], v[44:47]
	ds_read2_b64 v[48:51], v56 offset0:112 offset1:116
	s_waitcnt lgkmcnt(0)
	v_mfma_f32_16x16x32_bf16 v[28:31], v[48:51], v[36:39], v[28:31]
	ds_read2_b64 v[48:51], v57 offset0:144 offset1:148
	s_waitcnt lgkmcnt(0)
	v_mfma_f32_16x16x32_bf16 v[44:47], v[48:51], v[36:39], v[44:47]
	ds_read2_b64 v[48:51], v56 offset0:120 offset1:124
	s_waitcnt lgkmcnt(0)
	v_mfma_f32_16x16x32_bf16 v[28:31], v[48:51], v[40:43], v[28:31]
	ds_read2_b64 v[48:51], v57 offset0:152 offset1:156
	s_nop 6
	v_pk_mul_f32 v[22:23], v[16:17], v[28:29]
	s_waitcnt lgkmcnt(0)
	v_mfma_f32_16x16x32_bf16 v[44:47], v[48:51], v[40:43], v[44:47]
	v_mul_f32_e64 v28, v16, v30
	v_mul_f32_e64 v29, v17, v31
	v_cvt_pk_bf16_f32 v22, v22, v23
	v_cvt_pk_bf16_f32 v23, v28, v29
	s_nop 3
	v_pk_mul_f32 v[30:31], v[16:17], v[44:45]
	v_pk_mul_f32 v[44:45], v[16:17], v[46:47]
	v_cvt_pk_bf16_f32 v28, v30, v31
	v_cvt_pk_bf16_f32 v29, v44, v45
	global_store_dwordx2 v[18:19], v[22:23], off offset:64
	global_store_dwordx2 v[18:19], v[28:29], off offset:96
	v_lshl_add_u64 v[18:19], v[18:19], 0, s[46:47]
	s_cbranch_scc1 .LBB0_47
	s_add_i32 s16, s16, s70
	s_cmpk_gt_i32 s16, 0x1ff
	s_waitcnt lgkmcnt(0)
	s_barrier
	s_cbranch_scc0 .LBB0_46
	s_branch .LBB0_40
.LBB0_49:
	s_or_b64 exec, exec, s[4:5]
	v_readlane_b32 s48, v250, 31
	v_readlane_b32 s60, v250, 43
	v_readlane_b32 s61, v250, 44
	s_add_u32 s4, s60, s16
	s_addc_u32 s5, s61, s17
	v_and_b32_e32 v125, 63, v101
	s_add_u32 s4, s4, s27
	v_ashrrev_i32_e32 v101, 31, v100
	s_addc_u32 s5, s5, 0
	v_lshlrev_b64 v[0:1], 12, v[100:101]
	v_lshl_add_u64 v[0:1], s[4:5], 0, v[0:1]
	v_lshlrev_b32_e32 v192, 4, v125
	v_lshl_add_u64 v[0:1], v[0:1], 0, v[192:193]
	v_add_co_u32_e32 v2, vcc, s73, v0
	s_mov_b32 s4, 0xe000
	s_nop 0
	v_addc_co_u32_e32 v3, vcc, 0, v1, vcc
	global_load_dwordx4 v[120:123], v[2:3], off offset:-4096
	global_load_dwordx4 v[116:119], v[2:3], off
	v_add_co_u32_e32 v2, vcc, s72, v0
	v_lshlrev_b32_e32 v126, 5, v125
	s_nop 0
	v_addc_co_u32_e32 v3, vcc, 0, v1, vcc
	global_load_dwordx4 v[112:115], v[2:3], off offset:-4096
	global_load_dwordx4 v[108:111], v[2:3], off
	v_add_co_u32_e32 v2, vcc, s74, v0
	v_lshlrev_b32_e32 v127, 2, v124
	s_nop 0
	v_addc_co_u32_e32 v3, vcc, 0, v1, vcc
	global_load_dwordx4 v[104:107], v[2:3], off offset:-4096
	global_load_dwordx4 v[100:103], v[2:3], off
	v_add_co_u32_e32 v2, vcc, s77, v0
	v_add3_u32 v134, 0, v126, v127
	s_nop 0
	v_addc_co_u32_e32 v3, vcc, 0, v1, vcc
	global_load_dwordx4 v[96:99], v[2:3], off offset:-4096
	global_load_dwordx4 v[92:95], v[2:3], off
	v_add_co_u32_e32 v2, vcc, s79, v0
	s_add_i32 s25, s25, s70
	s_nop 0
	v_addc_co_u32_e32 v3, vcc, 0, v1, vcc
	global_load_dwordx4 v[88:91], v[2:3], off offset:-4096
	global_load_dwordx4 v[84:87], v[2:3], off
	v_add_co_u32_e32 v2, vcc, s81, v0
	s_add_i32 s23, s23, s30
	s_nop 0
	v_addc_co_u32_e32 v3, vcc, 0, v1, vcc
	global_load_dwordx4 v[80:83], v[2:3], off offset:-4096
	global_load_dwordx4 v[76:79], v[2:3], off
	v_add_co_u32_e32 v2, vcc, s4, v0
	s_mov_b32 s4, 0x10000
	s_nop 0
	v_addc_co_u32_e32 v3, vcc, 0, v1, vcc
	global_load_dwordx4 v[72:75], v[2:3], off offset:-4096
	global_load_dwordx4 v[68:71], v[2:3], off
	v_add_co_u32_e32 v2, vcc, s4, v0
	s_mov_b32 s4, 0x12000
	s_nop 0
	v_addc_co_u32_e32 v3, vcc, 0, v1, vcc
	global_load_dwordx4 v[64:67], v[2:3], off offset:-4096
	global_load_dwordx4 v[60:63], v[2:3], off
	v_add_co_u32_e32 v2, vcc, s4, v0
	s_mov_b32 s4, 0x14000
	s_nop 0
	v_addc_co_u32_e32 v3, vcc, 0, v1, vcc
	global_load_dwordx4 v[56:59], v[2:3], off offset:-4096
	global_load_dwordx4 v[52:55], v[2:3], off
	v_add_co_u32_e32 v2, vcc, s4, v0
	s_mov_b32 s4, 0x16000
	s_nop 0
	v_addc_co_u32_e32 v3, vcc, 0, v1, vcc
	global_load_dwordx4 v[48:51], v[2:3], off offset:-4096
	global_load_dwordx4 v[44:47], v[2:3], off
	v_add_co_u32_e32 v2, vcc, s4, v0
	s_mov_b32 s4, 0x18000
	s_nop 0
	v_addc_co_u32_e32 v3, vcc, 0, v1, vcc
	global_load_dwordx4 v[40:43], v[2:3], off offset:-4096
	global_load_dwordx4 v[36:39], v[2:3], off
	v_add_co_u32_e32 v2, vcc, s4, v0
	s_mov_b32 s4, 0x1a000
	s_nop 0
	v_addc_co_u32_e32 v3, vcc, 0, v1, vcc
	global_load_dwordx4 v[32:35], v[2:3], off offset:-4096
	global_load_dwordx4 v[28:31], v[2:3], off
	v_add_co_u32_e32 v2, vcc, s4, v0
	s_mov_b32 s4, 0x1c000
	s_nop 0
	v_addc_co_u32_e32 v3, vcc, 0, v1, vcc
	global_load_dwordx4 v[24:27], v[2:3], off offset:-4096
	global_load_dwordx4 v[20:23], v[2:3], off
	v_add_co_u32_e32 v2, vcc, s4, v0
	s_mov_b32 s4, 0x1e000
	s_nop 0
	v_addc_co_u32_e32 v3, vcc, 0, v1, vcc
	global_load_dwordx4 v[16:19], v[2:3], off offset:-4096
	global_load_dwordx4 v[12:15], v[2:3], off
	v_add_co_u32_e32 v2, vcc, s4, v0
	s_mov_b32 s4, 0x1f000
	s_nop 0
	v_addc_co_u32_e32 v3, vcc, 0, v1, vcc
	global_load_dwordx4 v[8:11], v[2:3], off offset:-4096
	global_load_dwordx4 v[4:7], v[2:3], off
	v_add_co_u32_e32 v2, vcc, s4, v0
	v_readlane_b32 s58, v250, 41
	s_nop 0
	v_addc_co_u32_e32 v3, vcc, 0, v1, vcc
	global_load_dwordx4 v[128:131], v[0:1], off
	s_nop 0
	global_load_dwordx4 v[0:3], v[2:3], off
	s_waitcnt lgkmcnt(0)
	s_barrier
	ds_read2st64_b32 v[126:127], v134 offset1:8
	ds_read2st64_b32 v[132:133], v134 offset0:16 offset1:24
	v_cmp_lt_i32_e32 vcc, v219, v218
	v_readlane_b32 s59, v250, 42
	s_cmpk_gt_i32 s25, 0x1ff
	s_waitcnt lgkmcnt(1)
	v_max3_f32 v135, v126, s33, v127
	v_cndmask_b32_e32 v136, v217, v219, vcc
	s_waitcnt lgkmcnt(0)
	v_max3_f32 v135, v135, v132, v133
	v_lshlrev_b32_e32 v136, 2, v136
	ds_bpermute_b32 v137, v136, v135
	v_cmp_lt_i32_e32 vcc, v220, v218
	v_readlane_b32 s49, v250, 32
	v_readlane_b32 s50, v250, 33
	v_readlane_b32 s51, v250, 34
	s_waitcnt lgkmcnt(0)
	v_max_f32_e32 v137, v137, v137
	v_max_f32_e32 v135, v135, v137
	v_cndmask_b32_e32 v137, v217, v220, vcc
	v_lshlrev_b32_e32 v137, 2, v137
	ds_bpermute_b32 v138, v137, v135
	v_cmp_lt_i32_e32 vcc, v221, v218
	v_readlane_b32 s52, v250, 35
	v_readlane_b32 s53, v250, 36
	v_readlane_b32 s54, v250, 37
	s_waitcnt lgkmcnt(0)
	v_max_f32_e32 v138, v138, v138
	v_max_f32_e32 v135, v135, v138
	v_cndmask_b32_e32 v138, v217, v221, vcc
	v_lshlrev_b32_e32 v138, 2, v138
	ds_bpermute_b32 v139, v138, v135
	v_cmp_lt_i32_e32 vcc, v222, v218
	v_readlane_b32 s55, v250, 38
	v_readlane_b32 s56, v250, 39
	v_readlane_b32 s57, v250, 40
	s_waitcnt lgkmcnt(0)
	v_max_f32_e32 v139, v139, v139
	v_max_f32_e32 v135, v135, v139
	v_cndmask_b32_e32 v139, v217, v222, vcc
	v_lshlrev_b32_e32 v139, 2, v139
	ds_bpermute_b32 v140, v139, v135
	v_cmp_lt_i32_e32 vcc, v223, v218
	v_readlane_b32 s62, v250, 45
	v_readlane_b32 s63, v250, 46
	s_waitcnt lgkmcnt(0)
	v_max_f32_e32 v140, v140, v140
	v_max_f32_e32 v135, v135, v140
	v_cndmask_b32_e32 v140, v217, v223, vcc
	v_lshlrev_b32_e32 v140, 2, v140
	ds_bpermute_b32 v141, v140, v135
	v_cmp_lt_i32_e32 vcc, v224, v218
	s_waitcnt lgkmcnt(0)
	v_max_f32_e32 v141, v141, v141
	v_max_f32_e32 v135, v135, v141
	v_cndmask_b32_e32 v141, v217, v224, vcc
	v_lshlrev_b32_e32 v141, 2, v141
	ds_bpermute_b32 v142, v141, v135
	s_waitcnt lgkmcnt(0)
	v_max_f32_e32 v142, v142, v142
	v_max_f32_e32 v135, v135, v142
	v_sub_f32_e32 v126, v126, v135
	v_exp_f32_e32 v126, v126
	v_sub_f32_e32 v127, v127, v135
	v_exp_f32_e32 v127, v127
	v_sub_f32_e32 v132, v132, v135
	v_exp_f32_e32 v132, v132
	v_sub_f32_e32 v133, v133, v135
	v_exp_f32_e32 v133, v133
	v_add_f32_e32 v135, 0, v126
	v_add_f32_e32 v135, v127, v135
	v_add_f32_e32 v135, v132, v135
	v_add_f32_e32 v135, v133, v135
	ds_bpermute_b32 v136, v136, v135
	s_waitcnt lgkmcnt(0)
	v_add_f32_e32 v135, v135, v136
	ds_bpermute_b32 v136, v137, v135
	s_waitcnt lgkmcnt(0)
	v_add_f32_e32 v135, v135, v136
	ds_bpermute_b32 v136, v138, v135
	s_waitcnt lgkmcnt(0)
	v_add_f32_e32 v135, v135, v136
	ds_bpermute_b32 v136, v139, v135
	s_waitcnt lgkmcnt(0)
	v_add_f32_e32 v135, v135, v136
	ds_bpermute_b32 v136, v140, v135
	s_waitcnt lgkmcnt(0)
	v_add_f32_e32 v135, v135, v136
	ds_bpermute_b32 v136, v141, v135
	s_waitcnt lgkmcnt(0)
	v_add_f32_e32 v135, v135, v136
	v_div_scale_f32 v136, s[4:5], v135, v135, 1.0
	v_rcp_f32_e32 v137, v136
	s_mov_b64 s[4:5], s[42:43]
	v_fma_f32 v138, -v136, v137, 1.0
	v_fmac_f32_e32 v137, v138, v137
	v_div_scale_f32 v138, vcc, 1.0, v135, 1.0
	v_mul_f32_e32 v139, v138, v137
	v_fma_f32 v140, -v136, v139, v138
	v_fmac_f32_e32 v139, v140, v137
	v_fma_f32 v136, -v136, v139, v138
	v_div_fmas_f32 v136, v136, v137, v139
	v_div_fixup_f32 v135, v136, v135, 1.0
	v_mul_f32_e32 v126, v126, v135
	v_mul_f32_e32 v127, v127, v135
	ds_write2st64_b32 v134, v126, v127 offset1:8
	v_mul_f32_e32 v126, v132, v135
	v_mul_f32_e32 v127, v133, v135
	ds_write2st64_b32 v134, v126, v127 offset0:16 offset1:24
	v_lshl_add_u32 v126, v124, 10, 0
	s_waitcnt lgkmcnt(0)
	s_barrier
	ds_read_b128 v[132:135], v126
	ds_read_b128 v[136:139], v126 offset:16
	ds_read_b128 v[140:143], v126 offset:32
	ds_read_b128 v[144:147], v126 offset:48
	s_waitcnt vmcnt(1) lgkmcnt(3)
	v_pk_fma_f32 v[154:155], v[130:131], v[134:135], 0 op_sel_hi:[1,0,0]
	v_pk_fma_f32 v[156:157], v[128:129], v[134:135], 0 op_sel_hi:[1,0,0]
	v_mov_b32_e32 v134, v135
	s_waitcnt lgkmcnt(2)
	v_pk_fma_f32 v[166:167], v[130:131], v[138:139], 0 op_sel_hi:[1,0,0]
	v_pk_fma_f32 v[168:169], v[128:129], v[138:139], 0 op_sel_hi:[1,0,0]
	v_mov_b32_e32 v138, v139
	v_pk_fma_f32 v[148:149], v[130:131], v[132:133], 0 op_sel_hi:[1,0,0]
	v_pk_fma_f32 v[150:151], v[128:129], v[132:133], 0 op_sel_hi:[1,0,0]
	v_pk_fma_f32 v[152:153], v[130:131], v[132:133], 0 op_sel:[0,1,0] op_sel_hi:[1,1,0]
	v_pk_fma_f32 v[132:133], v[128:129], v[132:133], 0 op_sel:[0,1,0] op_sel_hi:[1,1,0]
	v_pk_fma_f32 v[158:159], v[130:131], v[134:135], 0 op_sel_hi:[1,0,0]
	v_pk_fma_f32 v[134:135], v[128:129], v[134:135], 0 op_sel_hi:[1,0,0]
	v_pk_fma_f32 v[160:161], v[130:131], v[136:137], 0 op_sel_hi:[1,0,0]
	v_pk_fma_f32 v[162:163], v[128:129], v[136:137], 0 op_sel_hi:[1,0,0]
	v_pk_fma_f32 v[164:165], v[130:131], v[136:137], 0 op_sel:[0,1,0] op_sel_hi:[1,1,0]
	v_pk_fma_f32 v[136:137], v[128:129], v[136:137], 0 op_sel:[0,1,0] op_sel_hi:[1,1,0]
	v_pk_fma_f32 v[170:171], v[130:131], v[138:139], 0 op_sel_hi:[1,0,0]
	v_pk_fma_f32 v[138:139], v[128:129], v[138:139], 0 op_sel_hi:[1,0,0]
	s_waitcnt lgkmcnt(1)
	v_mov_b32_e32 v128, v143
	v_pk_fma_f32 v[150:151], v[120:121], v[140:141], v[150:151] op_sel_hi:[1,0,1]
	v_pk_fma_f32 v[148:149], v[122:123], v[140:141], v[148:149] op_sel_hi:[1,0,1]
	v_pk_fma_f32 v[132:133], v[120:121], v[140:141], v[132:133] op_sel:[0,1,0]
	v_pk_fma_f32 v[140:141], v[122:123], v[140:141], v[152:153] op_sel:[0,1,0]
	v_pk_fma_f32 v[152:153], v[120:121], v[142:143], v[156:157] op_sel_hi:[1,0,1]
	v_pk_fma_f32 v[154:155], v[122:123], v[142:143], v[154:155] op_sel_hi:[1,0,1]
	v_pk_fma_f32 v[134:135], v[120:121], v[128:129], v[134:135] op_sel_hi:[1,0,1]
	v_pk_fma_f32 v[142:143], v[122:123], v[128:129], v[158:159] op_sel_hi:[1,0,1]
	s_waitcnt lgkmcnt(0)
	v_pk_fma_f32 v[156:157], v[120:121], v[144:145], v[162:163] op_sel_hi:[1,0,1]
	v_pk_fma_f32 v[158:159], v[122:123], v[144:145], v[160:161] op_sel_hi:[1,0,1]
	v_pk_fma_f32 v[160:161], v[120:121], v[146:147], v[168:169] op_sel_hi:[1,0,1]
	v_pk_fma_f32 v[162:163], v[122:123], v[146:147], v[166:167] op_sel_hi:[1,0,1]
	ds_read_b128 v[128:131], v126 offset:64
	v_mov_b32_e32 v146, v147
	v_pk_fma_f32 v[136:137], v[120:121], v[144:145], v[136:137] op_sel:[0,1,0]
	v_pk_fma_f32 v[144:145], v[122:123], v[144:145], v[164:165] op_sel:[0,1,0]
	v_pk_fma_f32 v[138:139], v[120:121], v[146:147], v[138:139] op_sel_hi:[1,0,1]
	v_pk_fma_f32 v[146:147], v[122:123], v[146:147], v[170:171] op_sel_hi:[1,0,1]
	ds_read_b128 v[120:123], v126 offset:80
	s_waitcnt lgkmcnt(1)
	v_pk_fma_f32 v[148:149], v[118:119], v[128:129], v[148:149] op_sel_hi:[1,0,1]
	v_pk_fma_f32 v[150:151], v[116:117], v[128:129], v[150:151] op_sel_hi:[1,0,1]
	v_pk_fma_f32 v[140:141], v[118:119], v[128:129], v[140:141] op_sel:[0,1,0]
	v_pk_fma_f32 v[132:133], v[116:117], v[128:129], v[132:133] op_sel:[0,1,0]
	v_mov_b32_e32 v128, v131
	v_pk_fma_f32 v[154:155], v[118:119], v[130:131], v[154:155] op_sel_hi:[1,0,1]
	v_pk_fma_f32 v[152:153], v[116:117], v[130:131], v[152:153] op_sel_hi:[1,0,1]
	v_pk_fma_f32 v[142:143], v[118:119], v[128:129], v[142:143] op_sel_hi:[1,0,1]
	v_pk_fma_f32 v[134:135], v[116:117], v[128:129], v[134:135] op_sel_hi:[1,0,1]
	s_waitcnt lgkmcnt(0)
	v_pk_fma_f32 v[158:159], v[118:119], v[120:121], v[158:159] op_sel_hi:[1,0,1]
	v_pk_fma_f32 v[156:157], v[116:117], v[120:121], v[156:157] op_sel_hi:[1,0,1]
	v_pk_fma_f32 v[144:145], v[118:119], v[120:121], v[144:145] op_sel:[0,1,0]
	v_pk_fma_f32 v[120:121], v[116:117], v[120:121], v[136:137] op_sel:[0,1,0]
	v_pk_fma_f32 v[136:137], v[118:119], v[122:123], v[162:163] op_sel_hi:[1,0,1]
	v_pk_fma_f32 v[160:161], v[116:117], v[122:123], v[160:161] op_sel_hi:[1,0,1]
	ds_read_b128 v[128:131], v126 offset:96
	v_mov_b32_e32 v122, v123
	v_pk_fma_f32 v[146:147], v[118:119], v[122:123], v[146:147] op_sel_hi:[1,0,1]
	v_pk_fma_f32 v[138:139], v[116:117], v[122:123], v[138:139] op_sel_hi:[1,0,1]
	ds_read_b128 v[116:119], v126 offset:112
	s_waitcnt lgkmcnt(1)
	v_mov_b32_e32 v122, v131
	v_pk_fma_f32 v[148:149], v[114:115], v[128:129], v[148:149] op_sel_hi:[1,0,1]
	v_pk_fma_f32 v[150:151], v[112:113], v[128:129], v[150:151] op_sel_hi:[1,0,1]
	v_pk_fma_f32 v[140:141], v[114:115], v[128:129], v[140:141] op_sel:[0,1,0]
	v_pk_fma_f32 v[128:129], v[112:113], v[128:129], v[132:133] op_sel:[0,1,0]
	v_pk_fma_f32 v[132:133], v[114:115], v[130:131], v[154:155] op_sel_hi:[1,0,1]
	v_pk_fma_f32 v[152:153], v[112:113], v[130:131], v[152:153] op_sel_hi:[1,0,1]
	v_pk_fma_f32 v[130:131], v[114:115], v[122:123], v[142:143] op_sel_hi:[1,0,1]
	v_pk_fma_f32 v[134:135], v[112:113], v[122:123], v[134:135] op_sel_hi:[1,0,1]
	s_waitcnt lgkmcnt(0)
	v_pk_fma_f32 v[142:143], v[114:115], v[116:117], v[158:159] op_sel_hi:[1,0,1]
	v_pk_fma_f32 v[154:155], v[112:113], v[116:117], v[156:157] op_sel_hi:[1,0,1]
	v_pk_fma_f32 v[144:145], v[114:115], v[116:117], v[144:145] op_sel:[0,1,0]
	v_pk_fma_f32 v[116:117], v[112:113], v[116:117], v[120:121] op_sel:[0,1,0]
	v_pk_fma_f32 v[136:137], v[114:115], v[118:119], v[136:137] op_sel_hi:[1,0,1]
	v_pk_fma_f32 v[156:157], v[112:113], v[118:119], v[160:161] op_sel_hi:[1,0,1]
	ds_read_b128 v[120:123], v126 offset:128
	v_mov_b32_e32 v118, v119
	v_pk_fma_f32 v[146:147], v[114:115], v[118:119], v[146:147] op_sel_hi:[1,0,1]
	v_pk_fma_f32 v[138:139], v[112:113], v[118:119], v[138:139] op_sel_hi:[1,0,1]
	ds_read_b128 v[112:115], v126 offset:144
	s_waitcnt lgkmcnt(1)
	v_mov_b32_e32 v118, v123
	v_pk_fma_f32 v[148:149], v[110:111], v[120:121], v[148:149] op_sel_hi:[1,0,1]
	v_pk_fma_f32 v[150:151], v[108:109], v[120:121], v[150:151] op_sel_hi:[1,0,1]
	v_pk_fma_f32 v[140:141], v[110:111], v[120:121], v[140:141] op_sel:[0,1,0]
	v_pk_fma_f32 v[120:121], v[108:109], v[120:121], v[128:129] op_sel:[0,1,0]
	v_pk_fma_f32 v[128:129], v[110:111], v[122:123], v[132:133] op_sel_hi:[1,0,1]
	v_pk_fma_f32 v[132:133], v[108:109], v[122:123], v[152:153] op_sel_hi:[1,0,1]
	v_pk_fma_f32 v[122:123], v[110:111], v[118:119], v[130:131] op_sel_hi:[1,0,1]
	v_pk_fma_f32 v[130:131], v[108:109], v[118:119], v[134:135] op_sel_hi:[1,0,1]
	s_waitcnt lgkmcnt(0)
	v_pk_fma_f32 v[134:135], v[110:111], v[112:113], v[142:143] op_sel_hi:[1,0,1]
	v_pk_fma_f32 v[142:143], v[108:109], v[112:113], v[154:155] op_sel_hi:[1,0,1]
	v_pk_fma_f32 v[144:145], v[110:111], v[112:113], v[144:145] op_sel:[0,1,0]
	v_pk_fma_f32 v[112:113], v[108:109], v[112:113], v[116:117] op_sel:[0,1,0]
	v_pk_fma_f32 v[136:137], v[110:111], v[114:115], v[136:137] op_sel_hi:[1,0,1]
	v_pk_fma_f32 v[152:153], v[108:109], v[114:115], v[156:157] op_sel_hi:[1,0,1]
	ds_read_b128 v[116:119], v126 offset:160
	v_mov_b32_e32 v114, v115
	v_pk_fma_f32 v[146:147], v[110:111], v[114:115], v[146:147] op_sel_hi:[1,0,1]
	v_pk_fma_f32 v[138:139], v[108:109], v[114:115], v[138:139] op_sel_hi:[1,0,1]
	ds_read_b128 v[108:111], v126 offset:176
	s_waitcnt lgkmcnt(1)
	v_mov_b32_e32 v114, v119
	v_pk_fma_f32 v[148:149], v[106:107], v[116:117], v[148:149] op_sel_hi:[1,0,1]
	v_pk_fma_f32 v[150:151], v[104:105], v[116:117], v[150:151] op_sel_hi:[1,0,1]
	v_pk_fma_f32 v[140:141], v[106:107], v[116:117], v[140:141] op_sel:[0,1,0]
	v_pk_fma_f32 v[116:117], v[104:105], v[116:117], v[120:121] op_sel:[0,1,0]
	v_pk_fma_f32 v[120:121], v[106:107], v[118:119], v[128:129] op_sel_hi:[1,0,1]
	v_pk_fma_f32 v[128:129], v[104:105], v[118:119], v[132:133] op_sel_hi:[1,0,1]
	v_pk_fma_f32 v[118:119], v[106:107], v[114:115], v[122:123] op_sel_hi:[1,0,1]
	v_pk_fma_f32 v[122:123], v[104:105], v[114:115], v[130:131] op_sel_hi:[1,0,1]
	s_waitcnt lgkmcnt(0)
	v_pk_fma_f32 v[130:131], v[106:107], v[108:109], v[134:135] op_sel_hi:[1,0,1]
	v_pk_fma_f32 v[132:133], v[104:105], v[108:109], v[142:143] op_sel_hi:[1,0,1]
	v_pk_fma_f32 v[134:135], v[106:107], v[108:109], v[144:145] op_sel:[0,1,0]
	v_pk_fma_f32 v[108:109], v[104:105], v[108:109], v[112:113] op_sel:[0,1,0]
	v_pk_fma_f32 v[136:137], v[106:107], v[110:111], v[136:137] op_sel_hi:[1,0,1]
	v_pk_fma_f32 v[142:143], v[104:105], v[110:111], v[152:153] op_sel_hi:[1,0,1]
	ds_read_b128 v[112:115], v126 offset:192
	v_mov_b32_e32 v110, v111
	v_pk_fma_f32 v[144:145], v[106:107], v[110:111], v[146:147] op_sel_hi:[1,0,1]
	v_pk_fma_f32 v[138:139], v[104:105], v[110:111], v[138:139] op_sel_hi:[1,0,1]
	ds_read_b128 v[104:107], v126 offset:208
	s_waitcnt lgkmcnt(1)
	v_mov_b32_e32 v110, v115
	v_pk_fma_f32 v[146:147], v[102:103], v[112:113], v[148:149] op_sel_hi:[1,0,1]
	v_pk_fma_f32 v[148:149], v[100:101], v[112:113], v[150:151] op_sel_hi:[1,0,1]
	v_pk_fma_f32 v[140:141], v[102:103], v[112:113], v[140:141] op_sel:[0,1,0]
	v_pk_fma_f32 v[112:113], v[100:101], v[112:113], v[116:117] op_sel:[0,1,0]
	v_pk_fma_f32 v[116:117], v[102:103], v[114:115], v[120:121] op_sel_hi:[1,0,1]
	v_pk_fma_f32 v[120:121], v[100:101], v[114:115], v[128:129] op_sel_hi:[1,0,1]
	v_pk_fma_f32 v[114:115], v[102:103], v[110:111], v[118:119] op_sel_hi:[1,0,1]
	v_pk_fma_f32 v[118:119], v[100:101], v[110:111], v[122:123] op_sel_hi:[1,0,1]
	s_waitcnt lgkmcnt(0)
	v_pk_fma_f32 v[122:123], v[102:103], v[104:105], v[130:131] op_sel_hi:[1,0,1]
	v_pk_fma_f32 v[128:129], v[100:101], v[104:105], v[132:133] op_sel_hi:[1,0,1]
	v_pk_fma_f32 v[130:131], v[102:103], v[104:105], v[134:135] op_sel:[0,1,0]
	v_pk_fma_f32 v[104:105], v[100:101], v[104:105], v[108:109] op_sel:[0,1,0]
	v_pk_fma_f32 v[132:133], v[102:103], v[106:107], v[136:137] op_sel_hi:[1,0,1]
	v_pk_fma_f32 v[134:135], v[100:101], v[106:107], v[142:143] op_sel_hi:[1,0,1]
	ds_read_b128 v[108:111], v126 offset:224
	v_mov_b32_e32 v106, v107
	v_pk_fma_f32 v[136:137], v[102:103], v[106:107], v[144:145] op_sel_hi:[1,0,1]
	v_pk_fma_f32 v[138:139], v[100:101], v[106:107], v[138:139] op_sel_hi:[1,0,1]
	ds_read_b128 v[100:103], v126 offset:240
	s_waitcnt lgkmcnt(1)
	v_mov_b32_e32 v106, v111
	v_pk_fma_f32 v[142:143], v[98:99], v[108:109], v[146:147] op_sel_hi:[1,0,1]
	v_pk_fma_f32 v[144:145], v[96:97], v[108:109], v[148:149] op_sel_hi:[1,0,1]
	v_pk_fma_f32 v[140:141], v[98:99], v[108:109], v[140:141] op_sel:[0,1,0]
	v_pk_fma_f32 v[108:109], v[96:97], v[108:109], v[112:113] op_sel:[0,1,0]
	v_pk_fma_f32 v[112:113], v[98:99], v[110:111], v[116:117] op_sel_hi:[1,0,1]
	v_pk_fma_f32 v[116:117], v[96:97], v[110:111], v[120:121] op_sel_hi:[1,0,1]
	v_pk_fma_f32 v[110:111], v[98:99], v[106:107], v[114:115] op_sel_hi:[1,0,1]
	v_pk_fma_f32 v[114:115], v[96:97], v[106:107], v[118:119] op_sel_hi:[1,0,1]
	s_waitcnt lgkmcnt(0)
	v_pk_fma_f32 v[118:119], v[98:99], v[100:101], v[122:123] op_sel_hi:[1,0,1]
	v_pk_fma_f32 v[120:121], v[96:97], v[100:101], v[128:129] op_sel_hi:[1,0,1]
	v_pk_fma_f32 v[122:123], v[98:99], v[100:101], v[130:131] op_sel:[0,1,0]
	v_pk_fma_f32 v[100:101], v[96:97], v[100:101], v[104:105] op_sel:[0,1,0]
	v_pk_fma_f32 v[128:129], v[98:99], v[102:103], v[132:133] op_sel_hi:[1,0,1]
	v_pk_fma_f32 v[130:131], v[96:97], v[102:103], v[134:135] op_sel_hi:[1,0,1]
	ds_read_b128 v[104:107], v126 offset:256
	v_mov_b32_e32 v102, v103
	v_pk_fma_f32 v[132:133], v[98:99], v[102:103], v[136:137] op_sel_hi:[1,0,1]
	v_pk_fma_f32 v[134:135], v[96:97], v[102:103], v[138:139] op_sel_hi:[1,0,1]
	ds_read_b128 v[96:99], v126 offset:272
	s_waitcnt lgkmcnt(1)
	v_mov_b32_e32 v102, v107
	v_pk_fma_f32 v[136:137], v[94:95], v[104:105], v[142:143] op_sel_hi:[1,0,1]
	v_pk_fma_f32 v[138:139], v[92:93], v[104:105], v[144:145] op_sel_hi:[1,0,1]
	v_pk_fma_f32 v[140:141], v[94:95], v[104:105], v[140:141] op_sel:[0,1,0]
	v_pk_fma_f32 v[104:105], v[92:93], v[104:105], v[108:109] op_sel:[0,1,0]
	v_pk_fma_f32 v[108:109], v[94:95], v[106:107], v[112:113] op_sel_hi:[1,0,1]
	v_pk_fma_f32 v[112:113], v[92:93], v[106:107], v[116:117] op_sel_hi:[1,0,1]
	v_pk_fma_f32 v[106:107], v[94:95], v[102:103], v[110:111] op_sel_hi:[1,0,1]
	v_pk_fma_f32 v[110:111], v[92:93], v[102:103], v[114:115] op_sel_hi:[1,0,1]
	s_waitcnt lgkmcnt(0)
	v_pk_fma_f32 v[114:115], v[94:95], v[96:97], v[118:119] op_sel_hi:[1,0,1]
	v_pk_fma_f32 v[116:117], v[92:93], v[96:97], v[120:121] op_sel_hi:[1,0,1]
	v_pk_fma_f32 v[118:119], v[94:95], v[96:97], v[122:123] op_sel:[0,1,0]
	v_pk_fma_f32 v[96:97], v[92:93], v[96:97], v[100:101] op_sel:[0,1,0]
	v_pk_fma_f32 v[120:121], v[94:95], v[98:99], v[128:129] op_sel_hi:[1,0,1]
	v_pk_fma_f32 v[122:123], v[92:93], v[98:99], v[130:131] op_sel_hi:[1,0,1]
	ds_read_b128 v[100:103], v126 offset:288
	v_mov_b32_e32 v98, v99
	v_pk_fma_f32 v[128:129], v[94:95], v[98:99], v[132:133] op_sel_hi:[1,0,1]
	v_pk_fma_f32 v[130:131], v[92:93], v[98:99], v[134:135] op_sel_hi:[1,0,1]
	ds_read_b128 v[92:95], v126 offset:304
	s_waitcnt lgkmcnt(1)
	v_mov_b32_e32 v98, v103
	v_pk_fma_f32 v[132:133], v[90:91], v[100:101], v[136:137] op_sel_hi:[1,0,1]
	v_pk_fma_f32 v[134:135], v[88:89], v[100:101], v[138:139] op_sel_hi:[1,0,1]
	v_pk_fma_f32 v[136:137], v[90:91], v[100:101], v[140:141] op_sel:[0,1,0]
	v_pk_fma_f32 v[100:101], v[88:89], v[100:101], v[104:105] op_sel:[0,1,0]
	v_pk_fma_f32 v[104:105], v[90:91], v[102:103], v[108:109] op_sel_hi:[1,0,1]
	v_pk_fma_f32 v[108:109], v[88:89], v[102:103], v[112:113] op_sel_hi:[1,0,1]
	v_pk_fma_f32 v[102:103], v[90:91], v[98:99], v[106:107] op_sel_hi:[1,0,1]
	v_pk_fma_f32 v[106:107], v[88:89], v[98:99], v[110:111] op_sel_hi:[1,0,1]
	s_waitcnt lgkmcnt(0)
	v_pk_fma_f32 v[110:111], v[90:91], v[92:93], v[114:115] op_sel_hi:[1,0,1]
	v_pk_fma_f32 v[112:113], v[88:89], v[92:93], v[116:117] op_sel_hi:[1,0,1]
	v_pk_fma_f32 v[114:115], v[90:91], v[92:93], v[118:119] op_sel:[0,1,0]
	v_pk_fma_f32 v[92:93], v[88:89], v[92:93], v[96:97] op_sel:[0,1,0]
	v_pk_fma_f32 v[116:117], v[90:91], v[94:95], v[120:121] op_sel_hi:[1,0,1]
	v_pk_fma_f32 v[118:119], v[88:89], v[94:95], v[122:123] op_sel_hi:[1,0,1]
	ds_read_b128 v[96:99], v126 offset:320
	v_mov_b32_e32 v94, v95
	v_pk_fma_f32 v[120:121], v[90:91], v[94:95], v[128:129] op_sel_hi:[1,0,1]
	v_pk_fma_f32 v[122:123], v[88:89], v[94:95], v[130:131] op_sel_hi:[1,0,1]
	ds_read_b128 v[88:91], v126 offset:336
	s_waitcnt lgkmcnt(1)
	v_mov_b32_e32 v94, v99
	v_pk_fma_f32 v[128:129], v[86:87], v[96:97], v[132:133] op_sel_hi:[1,0,1]
	v_pk_fma_f32 v[130:131], v[84:85], v[96:97], v[134:135] op_sel_hi:[1,0,1]
	v_pk_fma_f32 v[132:133], v[86:87], v[96:97], v[136:137] op_sel:[0,1,0]
	v_pk_fma_f32 v[96:97], v[84:85], v[96:97], v[100:101] op_sel:[0,1,0]
	v_pk_fma_f32 v[100:101], v[86:87], v[98:99], v[104:105] op_sel_hi:[1,0,1]
	v_pk_fma_f32 v[104:105], v[84:85], v[98:99], v[108:109] op_sel_hi:[1,0,1]
	v_pk_fma_f32 v[98:99], v[86:87], v[94:95], v[102:103] op_sel_hi:[1,0,1]
	v_pk_fma_f32 v[102:103], v[84:85], v[94:95], v[106:107] op_sel_hi:[1,0,1]
	s_waitcnt lgkmcnt(0)
	v_pk_fma_f32 v[106:107], v[86:87], v[88:89], v[110:111] op_sel_hi:[1,0,1]
	v_pk_fma_f32 v[108:109], v[84:85], v[88:89], v[112:113] op_sel_hi:[1,0,1]
	v_pk_fma_f32 v[110:111], v[86:87], v[88:89], v[114:115] op_sel:[0,1,0]
	v_pk_fma_f32 v[88:89], v[84:85], v[88:89], v[92:93] op_sel:[0,1,0]
	v_pk_fma_f32 v[112:113], v[86:87], v[90:91], v[116:117] op_sel_hi:[1,0,1]
	v_pk_fma_f32 v[114:115], v[84:85], v[90:91], v[118:119] op_sel_hi:[1,0,1]
	ds_read_b128 v[92:95], v126 offset:352
	v_mov_b32_e32 v90, v91
	v_pk_fma_f32 v[116:117], v[86:87], v[90:91], v[120:121] op_sel_hi:[1,0,1]
	v_pk_fma_f32 v[118:119], v[84:85], v[90:91], v[122:123] op_sel_hi:[1,0,1]
	ds_read_b128 v[84:87], v126 offset:368
	s_waitcnt lgkmcnt(1)
	v_mov_b32_e32 v90, v95
	v_pk_fma_f32 v[120:121], v[82:83], v[92:93], v[128:129] op_sel_hi:[1,0,1]
	v_pk_fma_f32 v[122:123], v[80:81], v[92:93], v[130:131] op_sel_hi:[1,0,1]
	v_pk_fma_f32 v[128:129], v[82:83], v[92:93], v[132:133] op_sel:[0,1,0]
	v_pk_fma_f32 v[92:93], v[80:81], v[92:93], v[96:97] op_sel:[0,1,0]
	v_pk_fma_f32 v[96:97], v[82:83], v[94:95], v[100:101] op_sel_hi:[1,0,1]
	v_pk_fma_f32 v[100:101], v[80:81], v[94:95], v[104:105] op_sel_hi:[1,0,1]
	v_pk_fma_f32 v[94:95], v[82:83], v[90:91], v[98:99] op_sel_hi:[1,0,1]
	v_pk_fma_f32 v[98:99], v[80:81], v[90:91], v[102:103] op_sel_hi:[1,0,1]
	s_waitcnt lgkmcnt(0)
	v_pk_fma_f32 v[102:103], v[82:83], v[84:85], v[106:107] op_sel_hi:[1,0,1]
	v_pk_fma_f32 v[104:105], v[80:81], v[84:85], v[108:109] op_sel_hi:[1,0,1]
	v_pk_fma_f32 v[106:107], v[82:83], v[84:85], v[110:111] op_sel:[0,1,0]
	v_pk_fma_f32 v[84:85], v[80:81], v[84:85], v[88:89] op_sel:[0,1,0]
	v_pk_fma_f32 v[108:109], v[82:83], v[86:87], v[112:113] op_sel_hi:[1,0,1]
	v_pk_fma_f32 v[110:111], v[80:81], v[86:87], v[114:115] op_sel_hi:[1,0,1]
	ds_read_b128 v[88:91], v126 offset:384
	v_mov_b32_e32 v86, v87
	v_pk_fma_f32 v[112:113], v[82:83], v[86:87], v[116:117] op_sel_hi:[1,0,1]
	v_pk_fma_f32 v[114:115], v[80:81], v[86:87], v[118:119] op_sel_hi:[1,0,1]
	ds_read_b128 v[80:83], v126 offset:400
	s_waitcnt lgkmcnt(1)
	v_mov_b32_e32 v86, v91
	v_pk_fma_f32 v[116:117], v[78:79], v[88:89], v[120:121] op_sel_hi:[1,0,1]
	v_pk_fma_f32 v[118:119], v[76:77], v[88:89], v[122:123] op_sel_hi:[1,0,1]
	v_pk_fma_f32 v[120:121], v[78:79], v[88:89], v[128:129] op_sel:[0,1,0]
	v_pk_fma_f32 v[88:89], v[76:77], v[88:89], v[92:93] op_sel:[0,1,0]
	v_pk_fma_f32 v[92:93], v[78:79], v[90:91], v[96:97] op_sel_hi:[1,0,1]
	v_pk_fma_f32 v[96:97], v[76:77], v[90:91], v[100:101] op_sel_hi:[1,0,1]
	v_pk_fma_f32 v[90:91], v[78:79], v[86:87], v[94:95] op_sel_hi:[1,0,1]
	v_pk_fma_f32 v[94:95], v[76:77], v[86:87], v[98:99] op_sel_hi:[1,0,1]
	s_waitcnt lgkmcnt(0)
	v_pk_fma_f32 v[98:99], v[78:79], v[80:81], v[102:103] op_sel_hi:[1,0,1]
	v_pk_fma_f32 v[100:101], v[76:77], v[80:81], v[104:105] op_sel_hi:[1,0,1]
	v_pk_fma_f32 v[102:103], v[78:79], v[80:81], v[106:107] op_sel:[0,1,0]
	v_pk_fma_f32 v[80:81], v[76:77], v[80:81], v[84:85] op_sel:[0,1,0]
	v_pk_fma_f32 v[104:105], v[78:79], v[82:83], v[108:109] op_sel_hi:[1,0,1]
	v_pk_fma_f32 v[106:107], v[76:77], v[82:83], v[110:111] op_sel_hi:[1,0,1]
	ds_read_b128 v[84:87], v126 offset:416
	v_mov_b32_e32 v82, v83
	v_pk_fma_f32 v[108:109], v[78:79], v[82:83], v[112:113] op_sel_hi:[1,0,1]
	v_pk_fma_f32 v[110:111], v[76:77], v[82:83], v[114:115] op_sel_hi:[1,0,1]
	ds_read_b128 v[76:79], v126 offset:432
	s_waitcnt lgkmcnt(1)
	v_mov_b32_e32 v82, v87
	v_pk_fma_f32 v[112:113], v[74:75], v[84:85], v[116:117] op_sel_hi:[1,0,1]
	v_pk_fma_f32 v[114:115], v[72:73], v[84:85], v[118:119] op_sel_hi:[1,0,1]
	v_pk_fma_f32 v[116:117], v[74:75], v[84:85], v[120:121] op_sel:[0,1,0]
	v_pk_fma_f32 v[84:85], v[72:73], v[84:85], v[88:89] op_sel:[0,1,0]
	v_pk_fma_f32 v[88:89], v[74:75], v[86:87], v[92:93] op_sel_hi:[1,0,1]
	v_pk_fma_f32 v[92:93], v[72:73], v[86:87], v[96:97] op_sel_hi:[1,0,1]
	v_pk_fma_f32 v[86:87], v[74:75], v[82:83], v[90:91] op_sel_hi:[1,0,1]
	v_pk_fma_f32 v[90:91], v[72:73], v[82:83], v[94:95] op_sel_hi:[1,0,1]
	s_waitcnt lgkmcnt(0)
	v_pk_fma_f32 v[94:95], v[74:75], v[76:77], v[98:99] op_sel_hi:[1,0,1]
	v_pk_fma_f32 v[96:97], v[72:73], v[76:77], v[100:101] op_sel_hi:[1,0,1]
	v_pk_fma_f32 v[98:99], v[74:75], v[76:77], v[102:103] op_sel:[0,1,0]
	v_pk_fma_f32 v[76:77], v[72:73], v[76:77], v[80:81] op_sel:[0,1,0]
	v_pk_fma_f32 v[100:101], v[74:75], v[78:79], v[104:105] op_sel_hi:[1,0,1]
	v_pk_fma_f32 v[102:103], v[72:73], v[78:79], v[106:107] op_sel_hi:[1,0,1]
	ds_read_b128 v[80:83], v126 offset:448
	v_mov_b32_e32 v78, v79
	v_pk_fma_f32 v[104:105], v[74:75], v[78:79], v[108:109] op_sel_hi:[1,0,1]
	v_pk_fma_f32 v[106:107], v[72:73], v[78:79], v[110:111] op_sel_hi:[1,0,1]
	ds_read_b128 v[72:75], v126 offset:464
	s_waitcnt lgkmcnt(1)
	v_mov_b32_e32 v78, v83
	v_pk_fma_f32 v[108:109], v[70:71], v[80:81], v[112:113] op_sel_hi:[1,0,1]
	v_pk_fma_f32 v[110:111], v[68:69], v[80:81], v[114:115] op_sel_hi:[1,0,1]
	v_pk_fma_f32 v[112:113], v[70:71], v[80:81], v[116:117] op_sel:[0,1,0]
	v_pk_fma_f32 v[80:81], v[68:69], v[80:81], v[84:85] op_sel:[0,1,0]
	v_pk_fma_f32 v[84:85], v[70:71], v[82:83], v[88:89] op_sel_hi:[1,0,1]
	v_pk_fma_f32 v[88:89], v[68:69], v[82:83], v[92:93] op_sel_hi:[1,0,1]
	v_pk_fma_f32 v[82:83], v[70:71], v[78:79], v[86:87] op_sel_hi:[1,0,1]
	v_pk_fma_f32 v[86:87], v[68:69], v[78:79], v[90:91] op_sel_hi:[1,0,1]
	s_waitcnt lgkmcnt(0)
	v_pk_fma_f32 v[90:91], v[70:71], v[72:73], v[94:95] op_sel_hi:[1,0,1]
	v_pk_fma_f32 v[92:93], v[68:69], v[72:73], v[96:97] op_sel_hi:[1,0,1]
	v_pk_fma_f32 v[94:95], v[70:71], v[72:73], v[98:99] op_sel:[0,1,0]
	v_pk_fma_f32 v[72:73], v[68:69], v[72:73], v[76:77] op_sel:[0,1,0]
	v_pk_fma_f32 v[96:97], v[70:71], v[74:75], v[100:101] op_sel_hi:[1,0,1]
	v_pk_fma_f32 v[98:99], v[68:69], v[74:75], v[102:103] op_sel_hi:[1,0,1]
	ds_read_b128 v[76:79], v126 offset:480
	v_mov_b32_e32 v74, v75
	v_pk_fma_f32 v[100:101], v[70:71], v[74:75], v[104:105] op_sel_hi:[1,0,1]
	v_pk_fma_f32 v[102:103], v[68:69], v[74:75], v[106:107] op_sel_hi:[1,0,1]
	ds_read_b128 v[68:71], v126 offset:496
	s_waitcnt lgkmcnt(1)
	v_mov_b32_e32 v74, v79
	v_pk_fma_f32 v[104:105], v[66:67], v[76:77], v[108:109] op_sel_hi:[1,0,1]
	v_pk_fma_f32 v[106:107], v[64:65], v[76:77], v[110:111] op_sel_hi:[1,0,1]
	v_pk_fma_f32 v[108:109], v[66:67], v[76:77], v[112:113] op_sel:[0,1,0]
	v_pk_fma_f32 v[76:77], v[64:65], v[76:77], v[80:81] op_sel:[0,1,0]
	v_pk_fma_f32 v[80:81], v[66:67], v[78:79], v[84:85] op_sel_hi:[1,0,1]
	v_pk_fma_f32 v[84:85], v[64:65], v[78:79], v[88:89] op_sel_hi:[1,0,1]
	v_pk_fma_f32 v[78:79], v[66:67], v[74:75], v[82:83] op_sel_hi:[1,0,1]
	v_pk_fma_f32 v[82:83], v[64:65], v[74:75], v[86:87] op_sel_hi:[1,0,1]
	s_waitcnt lgkmcnt(0)
	v_pk_fma_f32 v[86:87], v[66:67], v[68:69], v[90:91] op_sel_hi:[1,0,1]
	v_pk_fma_f32 v[88:89], v[64:65], v[68:69], v[92:93] op_sel_hi:[1,0,1]
	v_pk_fma_f32 v[90:91], v[66:67], v[68:69], v[94:95] op_sel:[0,1,0]
	v_pk_fma_f32 v[68:69], v[64:65], v[68:69], v[72:73] op_sel:[0,1,0]
	v_pk_fma_f32 v[92:93], v[66:67], v[70:71], v[96:97] op_sel_hi:[1,0,1]
	v_pk_fma_f32 v[94:95], v[64:65], v[70:71], v[98:99] op_sel_hi:[1,0,1]
	ds_read_b128 v[72:75], v126 offset:512
	v_mov_b32_e32 v70, v71
	v_pk_fma_f32 v[96:97], v[66:67], v[70:71], v[100:101] op_sel_hi:[1,0,1]
	v_pk_fma_f32 v[98:99], v[64:65], v[70:71], v[102:103] op_sel_hi:[1,0,1]
	ds_read_b128 v[64:67], v126 offset:528
	s_waitcnt lgkmcnt(1)
	v_mov_b32_e32 v70, v75
	v_pk_fma_f32 v[100:101], v[62:63], v[72:73], v[104:105] op_sel_hi:[1,0,1]
	v_pk_fma_f32 v[102:103], v[60:61], v[72:73], v[106:107] op_sel_hi:[1,0,1]
	v_pk_fma_f32 v[104:105], v[62:63], v[72:73], v[108:109] op_sel:[0,1,0]
	v_pk_fma_f32 v[72:73], v[60:61], v[72:73], v[76:77] op_sel:[0,1,0]
	v_pk_fma_f32 v[76:77], v[62:63], v[74:75], v[80:81] op_sel_hi:[1,0,1]
	v_pk_fma_f32 v[80:81], v[60:61], v[74:75], v[84:85] op_sel_hi:[1,0,1]
	v_pk_fma_f32 v[74:75], v[62:63], v[70:71], v[78:79] op_sel_hi:[1,0,1]
	v_pk_fma_f32 v[78:79], v[60:61], v[70:71], v[82:83] op_sel_hi:[1,0,1]
	s_waitcnt lgkmcnt(0)
	v_pk_fma_f32 v[82:83], v[62:63], v[64:65], v[86:87] op_sel_hi:[1,0,1]
	v_pk_fma_f32 v[84:85], v[60:61], v[64:65], v[88:89] op_sel_hi:[1,0,1]
	v_pk_fma_f32 v[86:87], v[62:63], v[64:65], v[90:91] op_sel:[0,1,0]
	v_pk_fma_f32 v[64:65], v[60:61], v[64:65], v[68:69] op_sel:[0,1,0]
	v_pk_fma_f32 v[88:89], v[62:63], v[66:67], v[92:93] op_sel_hi:[1,0,1]
	v_pk_fma_f32 v[90:91], v[60:61], v[66:67], v[94:95] op_sel_hi:[1,0,1]
	ds_read_b128 v[68:71], v126 offset:544
	v_mov_b32_e32 v66, v67
	v_pk_fma_f32 v[92:93], v[62:63], v[66:67], v[96:97] op_sel_hi:[1,0,1]
	v_pk_fma_f32 v[94:95], v[60:61], v[66:67], v[98:99] op_sel_hi:[1,0,1]
	ds_read_b128 v[60:63], v126 offset:560
	s_waitcnt lgkmcnt(1)
	v_mov_b32_e32 v66, v71
	v_pk_fma_f32 v[96:97], v[58:59], v[68:69], v[100:101] op_sel_hi:[1,0,1]
	v_pk_fma_f32 v[98:99], v[56:57], v[68:69], v[102:103] op_sel_hi:[1,0,1]
	v_pk_fma_f32 v[100:101], v[58:59], v[68:69], v[104:105] op_sel:[0,1,0]
	v_pk_fma_f32 v[68:69], v[56:57], v[68:69], v[72:73] op_sel:[0,1,0]
	v_pk_fma_f32 v[72:73], v[58:59], v[70:71], v[76:77] op_sel_hi:[1,0,1]
	v_pk_fma_f32 v[76:77], v[56:57], v[70:71], v[80:81] op_sel_hi:[1,0,1]
	v_pk_fma_f32 v[70:71], v[58:59], v[66:67], v[74:75] op_sel_hi:[1,0,1]
	v_pk_fma_f32 v[74:75], v[56:57], v[66:67], v[78:79] op_sel_hi:[1,0,1]
	s_waitcnt lgkmcnt(0)
	v_pk_fma_f32 v[78:79], v[58:59], v[60:61], v[82:83] op_sel_hi:[1,0,1]
	v_pk_fma_f32 v[80:81], v[56:57], v[60:61], v[84:85] op_sel_hi:[1,0,1]
	v_pk_fma_f32 v[82:83], v[58:59], v[60:61], v[86:87] op_sel:[0,1,0]
	v_pk_fma_f32 v[60:61], v[56:57], v[60:61], v[64:65] op_sel:[0,1,0]
	v_pk_fma_f32 v[84:85], v[58:59], v[62:63], v[88:89] op_sel_hi:[1,0,1]
	v_pk_fma_f32 v[86:87], v[56:57], v[62:63], v[90:91] op_sel_hi:[1,0,1]
	ds_read_b128 v[64:67], v126 offset:576
	v_mov_b32_e32 v62, v63
	v_pk_fma_f32 v[88:89], v[58:59], v[62:63], v[92:93] op_sel_hi:[1,0,1]
	v_pk_fma_f32 v[90:91], v[56:57], v[62:63], v[94:95] op_sel_hi:[1,0,1]
	ds_read_b128 v[56:59], v126 offset:592
	s_waitcnt lgkmcnt(1)
	v_mov_b32_e32 v62, v67
	v_pk_fma_f32 v[92:93], v[54:55], v[64:65], v[96:97] op_sel_hi:[1,0,1]
	v_pk_fma_f32 v[94:95], v[52:53], v[64:65], v[98:99] op_sel_hi:[1,0,1]
	v_pk_fma_f32 v[96:97], v[54:55], v[64:65], v[100:101] op_sel:[0,1,0]
	v_pk_fma_f32 v[64:65], v[52:53], v[64:65], v[68:69] op_sel:[0,1,0]
	v_pk_fma_f32 v[68:69], v[54:55], v[66:67], v[72:73] op_sel_hi:[1,0,1]
	v_pk_fma_f32 v[72:73], v[52:53], v[66:67], v[76:77] op_sel_hi:[1,0,1]
	v_pk_fma_f32 v[66:67], v[54:55], v[62:63], v[70:71] op_sel_hi:[1,0,1]
	v_pk_fma_f32 v[70:71], v[52:53], v[62:63], v[74:75] op_sel_hi:[1,0,1]
	s_waitcnt lgkmcnt(0)
	v_pk_fma_f32 v[74:75], v[54:55], v[56:57], v[78:79] op_sel_hi:[1,0,1]
	v_pk_fma_f32 v[76:77], v[52:53], v[56:57], v[80:81] op_sel_hi:[1,0,1]
	v_pk_fma_f32 v[78:79], v[54:55], v[56:57], v[82:83] op_sel:[0,1,0]
	v_pk_fma_f32 v[56:57], v[52:53], v[56:57], v[60:61] op_sel:[0,1,0]
	v_pk_fma_f32 v[80:81], v[54:55], v[58:59], v[84:85] op_sel_hi:[1,0,1]
	v_pk_fma_f32 v[82:83], v[52:53], v[58:59], v[86:87] op_sel_hi:[1,0,1]
	ds_read_b128 v[60:63], v126 offset:608
	v_mov_b32_e32 v58, v59
	v_pk_fma_f32 v[84:85], v[54:55], v[58:59], v[88:89] op_sel_hi:[1,0,1]
	v_pk_fma_f32 v[86:87], v[52:53], v[58:59], v[90:91] op_sel_hi:[1,0,1]
	ds_read_b128 v[52:55], v126 offset:624
	s_waitcnt lgkmcnt(1)
	v_mov_b32_e32 v58, v63
	v_pk_fma_f32 v[88:89], v[50:51], v[60:61], v[92:93] op_sel_hi:[1,0,1]
	v_pk_fma_f32 v[90:91], v[48:49], v[60:61], v[94:95] op_sel_hi:[1,0,1]
	v_pk_fma_f32 v[92:93], v[50:51], v[60:61], v[96:97] op_sel:[0,1,0]
	v_pk_fma_f32 v[60:61], v[48:49], v[60:61], v[64:65] op_sel:[0,1,0]
	v_pk_fma_f32 v[64:65], v[50:51], v[62:63], v[68:69] op_sel_hi:[1,0,1]
	v_pk_fma_f32 v[68:69], v[48:49], v[62:63], v[72:73] op_sel_hi:[1,0,1]
	v_pk_fma_f32 v[62:63], v[50:51], v[58:59], v[66:67] op_sel_hi:[1,0,1]
	v_pk_fma_f32 v[66:67], v[48:49], v[58:59], v[70:71] op_sel_hi:[1,0,1]
	s_waitcnt lgkmcnt(0)
	v_pk_fma_f32 v[70:71], v[50:51], v[52:53], v[74:75] op_sel_hi:[1,0,1]
	v_pk_fma_f32 v[72:73], v[48:49], v[52:53], v[76:77] op_sel_hi:[1,0,1]
	v_pk_fma_f32 v[74:75], v[50:51], v[52:53], v[78:79] op_sel:[0,1,0]
	v_pk_fma_f32 v[52:53], v[48:49], v[52:53], v[56:57] op_sel:[0,1,0]
	v_pk_fma_f32 v[76:77], v[50:51], v[54:55], v[80:81] op_sel_hi:[1,0,1]
	v_pk_fma_f32 v[78:79], v[48:49], v[54:55], v[82:83] op_sel_hi:[1,0,1]
	ds_read_b128 v[56:59], v126 offset:640
	v_mov_b32_e32 v54, v55
	v_pk_fma_f32 v[80:81], v[50:51], v[54:55], v[84:85] op_sel_hi:[1,0,1]
	v_pk_fma_f32 v[82:83], v[48:49], v[54:55], v[86:87] op_sel_hi:[1,0,1]
	ds_read_b128 v[48:51], v126 offset:656
	s_waitcnt lgkmcnt(1)
	v_mov_b32_e32 v54, v59
	v_pk_fma_f32 v[84:85], v[46:47], v[56:57], v[88:89] op_sel_hi:[1,0,1]
	v_pk_fma_f32 v[86:87], v[44:45], v[56:57], v[90:91] op_sel_hi:[1,0,1]
	v_pk_fma_f32 v[88:89], v[46:47], v[56:57], v[92:93] op_sel:[0,1,0]
	v_pk_fma_f32 v[56:57], v[44:45], v[56:57], v[60:61] op_sel:[0,1,0]
	v_pk_fma_f32 v[60:61], v[46:47], v[58:59], v[64:65] op_sel_hi:[1,0,1]
	v_pk_fma_f32 v[64:65], v[44:45], v[58:59], v[68:69] op_sel_hi:[1,0,1]
	v_pk_fma_f32 v[58:59], v[46:47], v[54:55], v[62:63] op_sel_hi:[1,0,1]
	v_pk_fma_f32 v[62:63], v[44:45], v[54:55], v[66:67] op_sel_hi:[1,0,1]
	s_waitcnt lgkmcnt(0)
	v_pk_fma_f32 v[66:67], v[46:47], v[48:49], v[70:71] op_sel_hi:[1,0,1]
	v_pk_fma_f32 v[68:69], v[44:45], v[48:49], v[72:73] op_sel_hi:[1,0,1]
	v_pk_fma_f32 v[70:71], v[46:47], v[48:49], v[74:75] op_sel:[0,1,0]
	v_pk_fma_f32 v[48:49], v[44:45], v[48:49], v[52:53] op_sel:[0,1,0]
	v_pk_fma_f32 v[72:73], v[46:47], v[50:51], v[76:77] op_sel_hi:[1,0,1]
	v_pk_fma_f32 v[74:75], v[44:45], v[50:51], v[78:79] op_sel_hi:[1,0,1]
	ds_read_b128 v[52:55], v126 offset:672
	v_mov_b32_e32 v50, v51
	v_pk_fma_f32 v[76:77], v[46:47], v[50:51], v[80:81] op_sel_hi:[1,0,1]
	v_pk_fma_f32 v[78:79], v[44:45], v[50:51], v[82:83] op_sel_hi:[1,0,1]
	ds_read_b128 v[44:47], v126 offset:688
	s_waitcnt lgkmcnt(1)
	v_mov_b32_e32 v50, v55
	v_pk_fma_f32 v[80:81], v[42:43], v[52:53], v[84:85] op_sel_hi:[1,0,1]
	v_pk_fma_f32 v[82:83], v[40:41], v[52:53], v[86:87] op_sel_hi:[1,0,1]
	v_pk_fma_f32 v[84:85], v[42:43], v[52:53], v[88:89] op_sel:[0,1,0]
	v_pk_fma_f32 v[52:53], v[40:41], v[52:53], v[56:57] op_sel:[0,1,0]
	v_pk_fma_f32 v[56:57], v[42:43], v[54:55], v[60:61] op_sel_hi:[1,0,1]
	v_pk_fma_f32 v[60:61], v[40:41], v[54:55], v[64:65] op_sel_hi:[1,0,1]
	v_pk_fma_f32 v[54:55], v[42:43], v[50:51], v[58:59] op_sel_hi:[1,0,1]
	v_pk_fma_f32 v[58:59], v[40:41], v[50:51], v[62:63] op_sel_hi:[1,0,1]
	s_waitcnt lgkmcnt(0)
	v_pk_fma_f32 v[62:63], v[42:43], v[44:45], v[66:67] op_sel_hi:[1,0,1]
	v_pk_fma_f32 v[64:65], v[40:41], v[44:45], v[68:69] op_sel_hi:[1,0,1]
	v_pk_fma_f32 v[66:67], v[42:43], v[44:45], v[70:71] op_sel:[0,1,0]
	v_pk_fma_f32 v[44:45], v[40:41], v[44:45], v[48:49] op_sel:[0,1,0]
	v_pk_fma_f32 v[68:69], v[42:43], v[46:47], v[72:73] op_sel_hi:[1,0,1]
	v_pk_fma_f32 v[70:71], v[40:41], v[46:47], v[74:75] op_sel_hi:[1,0,1]
	ds_read_b128 v[48:51], v126 offset:704
	v_mov_b32_e32 v46, v47
	v_pk_fma_f32 v[72:73], v[42:43], v[46:47], v[76:77] op_sel_hi:[1,0,1]
	v_pk_fma_f32 v[74:75], v[40:41], v[46:47], v[78:79] op_sel_hi:[1,0,1]
	ds_read_b128 v[40:43], v126 offset:720
	s_waitcnt lgkmcnt(1)
	v_mov_b32_e32 v46, v51
	v_pk_fma_f32 v[76:77], v[38:39], v[48:49], v[80:81] op_sel_hi:[1,0,1]
	v_pk_fma_f32 v[78:79], v[36:37], v[48:49], v[82:83] op_sel_hi:[1,0,1]
	v_pk_fma_f32 v[80:81], v[38:39], v[48:49], v[84:85] op_sel:[0,1,0]
	v_pk_fma_f32 v[48:49], v[36:37], v[48:49], v[52:53] op_sel:[0,1,0]
	v_pk_fma_f32 v[52:53], v[38:39], v[50:51], v[56:57] op_sel_hi:[1,0,1]
	v_pk_fma_f32 v[56:57], v[36:37], v[50:51], v[60:61] op_sel_hi:[1,0,1]
	v_pk_fma_f32 v[50:51], v[38:39], v[46:47], v[54:55] op_sel_hi:[1,0,1]
	v_pk_fma_f32 v[54:55], v[36:37], v[46:47], v[58:59] op_sel_hi:[1,0,1]
	s_waitcnt lgkmcnt(0)
	v_pk_fma_f32 v[58:59], v[38:39], v[40:41], v[62:63] op_sel_hi:[1,0,1]
	v_pk_fma_f32 v[60:61], v[36:37], v[40:41], v[64:65] op_sel_hi:[1,0,1]
	v_pk_fma_f32 v[62:63], v[38:39], v[40:41], v[66:67] op_sel:[0,1,0]
	v_pk_fma_f32 v[40:41], v[36:37], v[40:41], v[44:45] op_sel:[0,1,0]
	v_pk_fma_f32 v[64:65], v[38:39], v[42:43], v[68:69] op_sel_hi:[1,0,1]
	v_pk_fma_f32 v[66:67], v[36:37], v[42:43], v[70:71] op_sel_hi:[1,0,1]
	ds_read_b128 v[44:47], v126 offset:736
	v_mov_b32_e32 v42, v43
	v_pk_fma_f32 v[68:69], v[38:39], v[42:43], v[72:73] op_sel_hi:[1,0,1]
	v_pk_fma_f32 v[70:71], v[36:37], v[42:43], v[74:75] op_sel_hi:[1,0,1]
	ds_read_b128 v[36:39], v126 offset:752
	s_waitcnt lgkmcnt(1)
	v_mov_b32_e32 v42, v47
	v_pk_fma_f32 v[72:73], v[34:35], v[44:45], v[76:77] op_sel_hi:[1,0,1]
	v_pk_fma_f32 v[74:75], v[32:33], v[44:45], v[78:79] op_sel_hi:[1,0,1]
	v_pk_fma_f32 v[76:77], v[34:35], v[44:45], v[80:81] op_sel:[0,1,0]
	v_pk_fma_f32 v[44:45], v[32:33], v[44:45], v[48:49] op_sel:[0,1,0]
	v_pk_fma_f32 v[48:49], v[34:35], v[46:47], v[52:53] op_sel_hi:[1,0,1]
	v_pk_fma_f32 v[52:53], v[32:33], v[46:47], v[56:57] op_sel_hi:[1,0,1]
	v_pk_fma_f32 v[46:47], v[34:35], v[42:43], v[50:51] op_sel_hi:[1,0,1]
	v_pk_fma_f32 v[50:51], v[32:33], v[42:43], v[54:55] op_sel_hi:[1,0,1]
	s_waitcnt lgkmcnt(0)
	v_pk_fma_f32 v[54:55], v[34:35], v[36:37], v[58:59] op_sel_hi:[1,0,1]
	v_pk_fma_f32 v[56:57], v[32:33], v[36:37], v[60:61] op_sel_hi:[1,0,1]
	v_pk_fma_f32 v[58:59], v[34:35], v[36:37], v[62:63] op_sel:[0,1,0]
	v_pk_fma_f32 v[36:37], v[32:33], v[36:37], v[40:41] op_sel:[0,1,0]
	v_pk_fma_f32 v[60:61], v[34:35], v[38:39], v[64:65] op_sel_hi:[1,0,1]
	v_pk_fma_f32 v[62:63], v[32:33], v[38:39], v[66:67] op_sel_hi:[1,0,1]
	ds_read_b128 v[40:43], v126 offset:768
	v_mov_b32_e32 v38, v39
	v_pk_fma_f32 v[64:65], v[34:35], v[38:39], v[68:69] op_sel_hi:[1,0,1]
	v_pk_fma_f32 v[66:67], v[32:33], v[38:39], v[70:71] op_sel_hi:[1,0,1]
	ds_read_b128 v[32:35], v126 offset:784
	s_waitcnt lgkmcnt(1)
	v_mov_b32_e32 v38, v43
	v_pk_fma_f32 v[68:69], v[30:31], v[40:41], v[72:73] op_sel_hi:[1,0,1]
	v_pk_fma_f32 v[70:71], v[28:29], v[40:41], v[74:75] op_sel_hi:[1,0,1]
	v_pk_fma_f32 v[72:73], v[30:31], v[40:41], v[76:77] op_sel:[0,1,0]
	v_pk_fma_f32 v[40:41], v[28:29], v[40:41], v[44:45] op_sel:[0,1,0]
	v_pk_fma_f32 v[44:45], v[30:31], v[42:43], v[48:49] op_sel_hi:[1,0,1]
	v_pk_fma_f32 v[48:49], v[28:29], v[42:43], v[52:53] op_sel_hi:[1,0,1]
	v_pk_fma_f32 v[42:43], v[30:31], v[38:39], v[46:47] op_sel_hi:[1,0,1]
	v_pk_fma_f32 v[46:47], v[28:29], v[38:39], v[50:51] op_sel_hi:[1,0,1]
	s_waitcnt lgkmcnt(0)
	v_pk_fma_f32 v[50:51], v[30:31], v[32:33], v[54:55] op_sel_hi:[1,0,1]
	v_pk_fma_f32 v[52:53], v[28:29], v[32:33], v[56:57] op_sel_hi:[1,0,1]
	v_pk_fma_f32 v[54:55], v[30:31], v[32:33], v[58:59] op_sel:[0,1,0]
	v_pk_fma_f32 v[32:33], v[28:29], v[32:33], v[36:37] op_sel:[0,1,0]
	v_pk_fma_f32 v[56:57], v[30:31], v[34:35], v[60:61] op_sel_hi:[1,0,1]
	v_pk_fma_f32 v[58:59], v[28:29], v[34:35], v[62:63] op_sel_hi:[1,0,1]
	ds_read_b128 v[36:39], v126 offset:800
	v_mov_b32_e32 v34, v35
	v_pk_fma_f32 v[60:61], v[30:31], v[34:35], v[64:65] op_sel_hi:[1,0,1]
	v_pk_fma_f32 v[62:63], v[28:29], v[34:35], v[66:67] op_sel_hi:[1,0,1]
	ds_read_b128 v[28:31], v126 offset:816
	s_waitcnt lgkmcnt(1)
	v_mov_b32_e32 v34, v39
	v_pk_fma_f32 v[64:65], v[26:27], v[36:37], v[68:69] op_sel_hi:[1,0,1]
	v_pk_fma_f32 v[66:67], v[24:25], v[36:37], v[70:71] op_sel_hi:[1,0,1]
	v_pk_fma_f32 v[68:69], v[26:27], v[36:37], v[72:73] op_sel:[0,1,0]
	v_pk_fma_f32 v[36:37], v[24:25], v[36:37], v[40:41] op_sel:[0,1,0]
	v_pk_fma_f32 v[40:41], v[26:27], v[38:39], v[44:45] op_sel_hi:[1,0,1]
	v_pk_fma_f32 v[44:45], v[24:25], v[38:39], v[48:49] op_sel_hi:[1,0,1]
	v_pk_fma_f32 v[38:39], v[26:27], v[34:35], v[42:43] op_sel_hi:[1,0,1]
	v_pk_fma_f32 v[42:43], v[24:25], v[34:35], v[46:47] op_sel_hi:[1,0,1]
	s_waitcnt lgkmcnt(0)
	v_pk_fma_f32 v[46:47], v[26:27], v[28:29], v[50:51] op_sel_hi:[1,0,1]
	v_pk_fma_f32 v[48:49], v[24:25], v[28:29], v[52:53] op_sel_hi:[1,0,1]
	v_pk_fma_f32 v[50:51], v[26:27], v[28:29], v[54:55] op_sel:[0,1,0]
	v_pk_fma_f32 v[28:29], v[24:25], v[28:29], v[32:33] op_sel:[0,1,0]
	v_pk_fma_f32 v[52:53], v[26:27], v[30:31], v[56:57] op_sel_hi:[1,0,1]
	v_pk_fma_f32 v[54:55], v[24:25], v[30:31], v[58:59] op_sel_hi:[1,0,1]
	ds_read_b128 v[32:35], v126 offset:832
	v_mov_b32_e32 v30, v31
	v_pk_fma_f32 v[56:57], v[26:27], v[30:31], v[60:61] op_sel_hi:[1,0,1]
	v_pk_fma_f32 v[58:59], v[24:25], v[30:31], v[62:63] op_sel_hi:[1,0,1]
	ds_read_b128 v[24:27], v126 offset:848
	s_waitcnt lgkmcnt(1)
	v_mov_b32_e32 v30, v35
	v_pk_fma_f32 v[60:61], v[22:23], v[32:33], v[64:65] op_sel_hi:[1,0,1]
	v_pk_fma_f32 v[62:63], v[20:21], v[32:33], v[66:67] op_sel_hi:[1,0,1]
	v_pk_fma_f32 v[64:65], v[22:23], v[32:33], v[68:69] op_sel:[0,1,0]
	v_pk_fma_f32 v[32:33], v[20:21], v[32:33], v[36:37] op_sel:[0,1,0]
	v_pk_fma_f32 v[36:37], v[22:23], v[34:35], v[40:41] op_sel_hi:[1,0,1]
	v_pk_fma_f32 v[40:41], v[20:21], v[34:35], v[44:45] op_sel_hi:[1,0,1]
	v_pk_fma_f32 v[34:35], v[22:23], v[30:31], v[38:39] op_sel_hi:[1,0,1]
	v_pk_fma_f32 v[38:39], v[20:21], v[30:31], v[42:43] op_sel_hi:[1,0,1]
	s_waitcnt lgkmcnt(0)
	v_pk_fma_f32 v[42:43], v[22:23], v[24:25], v[46:47] op_sel_hi:[1,0,1]
	v_pk_fma_f32 v[44:45], v[20:21], v[24:25], v[48:49] op_sel_hi:[1,0,1]
	v_pk_fma_f32 v[46:47], v[22:23], v[24:25], v[50:51] op_sel:[0,1,0]
	v_pk_fma_f32 v[24:25], v[20:21], v[24:25], v[28:29] op_sel:[0,1,0]
	v_pk_fma_f32 v[48:49], v[22:23], v[26:27], v[52:53] op_sel_hi:[1,0,1]
	v_pk_fma_f32 v[50:51], v[20:21], v[26:27], v[54:55] op_sel_hi:[1,0,1]
	ds_read_b128 v[28:31], v126 offset:864
	v_mov_b32_e32 v26, v27
	v_pk_fma_f32 v[52:53], v[22:23], v[26:27], v[56:57] op_sel_hi:[1,0,1]
	v_pk_fma_f32 v[54:55], v[20:21], v[26:27], v[58:59] op_sel_hi:[1,0,1]
	ds_read_b128 v[20:23], v126 offset:880
	s_waitcnt lgkmcnt(1)
	v_mov_b32_e32 v26, v31
	v_pk_fma_f32 v[56:57], v[18:19], v[28:29], v[60:61] op_sel_hi:[1,0,1]
	v_pk_fma_f32 v[58:59], v[16:17], v[28:29], v[62:63] op_sel_hi:[1,0,1]
	v_pk_fma_f32 v[60:61], v[18:19], v[28:29], v[64:65] op_sel:[0,1,0]
	v_pk_fma_f32 v[28:29], v[16:17], v[28:29], v[32:33] op_sel:[0,1,0]
	v_pk_fma_f32 v[32:33], v[18:19], v[30:31], v[36:37] op_sel_hi:[1,0,1]
	v_pk_fma_f32 v[36:37], v[16:17], v[30:31], v[40:41] op_sel_hi:[1,0,1]
	v_pk_fma_f32 v[30:31], v[18:19], v[26:27], v[34:35] op_sel_hi:[1,0,1]
	v_pk_fma_f32 v[34:35], v[16:17], v[26:27], v[38:39] op_sel_hi:[1,0,1]
	s_waitcnt lgkmcnt(0)
	v_pk_fma_f32 v[38:39], v[18:19], v[20:21], v[42:43] op_sel_hi:[1,0,1]
	v_pk_fma_f32 v[40:41], v[16:17], v[20:21], v[44:45] op_sel_hi:[1,0,1]
	v_pk_fma_f32 v[42:43], v[18:19], v[20:21], v[46:47] op_sel:[0,1,0]
	v_pk_fma_f32 v[20:21], v[16:17], v[20:21], v[24:25] op_sel:[0,1,0]
	v_pk_fma_f32 v[44:45], v[18:19], v[22:23], v[48:49] op_sel_hi:[1,0,1]
	v_pk_fma_f32 v[46:47], v[16:17], v[22:23], v[50:51] op_sel_hi:[1,0,1]
	ds_read_b128 v[24:27], v126 offset:896
	v_mov_b32_e32 v22, v23
	v_pk_fma_f32 v[48:49], v[18:19], v[22:23], v[52:53] op_sel_hi:[1,0,1]
	v_pk_fma_f32 v[50:51], v[16:17], v[22:23], v[54:55] op_sel_hi:[1,0,1]
	ds_read_b128 v[16:19], v126 offset:912
	s_waitcnt lgkmcnt(1)
	v_mov_b32_e32 v22, v27
	v_pk_fma_f32 v[52:53], v[14:15], v[24:25], v[56:57] op_sel_hi:[1,0,1]
	v_pk_fma_f32 v[54:55], v[12:13], v[24:25], v[58:59] op_sel_hi:[1,0,1]
	v_pk_fma_f32 v[56:57], v[14:15], v[24:25], v[60:61] op_sel:[0,1,0]
	v_pk_fma_f32 v[24:25], v[12:13], v[24:25], v[28:29] op_sel:[0,1,0]
	v_pk_fma_f32 v[28:29], v[14:15], v[26:27], v[32:33] op_sel_hi:[1,0,1]
	v_pk_fma_f32 v[32:33], v[12:13], v[26:27], v[36:37] op_sel_hi:[1,0,1]
	v_pk_fma_f32 v[26:27], v[14:15], v[22:23], v[30:31] op_sel_hi:[1,0,1]
	v_pk_fma_f32 v[30:31], v[12:13], v[22:23], v[34:35] op_sel_hi:[1,0,1]
	s_waitcnt lgkmcnt(0)
	v_pk_fma_f32 v[34:35], v[14:15], v[16:17], v[38:39] op_sel_hi:[1,0,1]
	v_pk_fma_f32 v[36:37], v[12:13], v[16:17], v[40:41] op_sel_hi:[1,0,1]
	v_pk_fma_f32 v[38:39], v[14:15], v[16:17], v[42:43] op_sel:[0,1,0]
	v_pk_fma_f32 v[16:17], v[12:13], v[16:17], v[20:21] op_sel:[0,1,0]
	v_pk_fma_f32 v[40:41], v[14:15], v[18:19], v[44:45] op_sel_hi:[1,0,1]
	v_pk_fma_f32 v[42:43], v[12:13], v[18:19], v[46:47] op_sel_hi:[1,0,1]
	ds_read_b128 v[20:23], v126 offset:928
	v_mov_b32_e32 v18, v19
	v_pk_fma_f32 v[44:45], v[14:15], v[18:19], v[48:49] op_sel_hi:[1,0,1]
	v_pk_fma_f32 v[46:47], v[12:13], v[18:19], v[50:51] op_sel_hi:[1,0,1]
	ds_read_b128 v[12:15], v126 offset:944
	s_waitcnt lgkmcnt(1)
	v_mov_b32_e32 v18, v23
	v_pk_fma_f32 v[48:49], v[10:11], v[20:21], v[52:53] op_sel_hi:[1,0,1]
	v_pk_fma_f32 v[50:51], v[8:9], v[20:21], v[54:55] op_sel_hi:[1,0,1]
	v_pk_fma_f32 v[52:53], v[10:11], v[20:21], v[56:57] op_sel:[0,1,0]
	v_pk_fma_f32 v[20:21], v[8:9], v[20:21], v[24:25] op_sel:[0,1,0]
	v_pk_fma_f32 v[24:25], v[10:11], v[22:23], v[28:29] op_sel_hi:[1,0,1]
	v_pk_fma_f32 v[28:29], v[8:9], v[22:23], v[32:33] op_sel_hi:[1,0,1]
	v_pk_fma_f32 v[22:23], v[10:11], v[18:19], v[26:27] op_sel_hi:[1,0,1]
	v_pk_fma_f32 v[26:27], v[8:9], v[18:19], v[30:31] op_sel_hi:[1,0,1]
	s_waitcnt lgkmcnt(0)
	v_pk_fma_f32 v[30:31], v[10:11], v[12:13], v[34:35] op_sel_hi:[1,0,1]
	v_pk_fma_f32 v[32:33], v[8:9], v[12:13], v[36:37] op_sel_hi:[1,0,1]
	v_pk_fma_f32 v[34:35], v[10:11], v[12:13], v[38:39] op_sel:[0,1,0]
	v_pk_fma_f32 v[12:13], v[8:9], v[12:13], v[16:17] op_sel:[0,1,0]
	v_pk_fma_f32 v[36:37], v[10:11], v[14:15], v[40:41] op_sel_hi:[1,0,1]
	v_pk_fma_f32 v[38:39], v[8:9], v[14:15], v[42:43] op_sel_hi:[1,0,1]
	ds_read_b128 v[16:19], v126 offset:960
	v_mov_b32_e32 v14, v15
	v_pk_fma_f32 v[40:41], v[10:11], v[14:15], v[44:45] op_sel_hi:[1,0,1]
	v_pk_fma_f32 v[42:43], v[8:9], v[14:15], v[46:47] op_sel_hi:[1,0,1]
	ds_read_b128 v[8:11], v126 offset:976
	s_waitcnt lgkmcnt(1)
	v_mov_b32_e32 v14, v19
	v_pk_fma_f32 v[44:45], v[6:7], v[16:17], v[48:49] op_sel_hi:[1,0,1]
	v_pk_fma_f32 v[46:47], v[4:5], v[16:17], v[50:51] op_sel_hi:[1,0,1]
	v_pk_fma_f32 v[48:49], v[6:7], v[16:17], v[52:53] op_sel:[0,1,0]
	v_pk_fma_f32 v[16:17], v[4:5], v[16:17], v[20:21] op_sel:[0,1,0]
	v_pk_fma_f32 v[20:21], v[6:7], v[18:19], v[24:25] op_sel_hi:[1,0,1]
	v_pk_fma_f32 v[24:25], v[4:5], v[18:19], v[28:29] op_sel_hi:[1,0,1]
	v_pk_fma_f32 v[28:29], v[6:7], v[14:15], v[22:23] op_sel_hi:[1,0,1]
	v_pk_fma_f32 v[26:27], v[4:5], v[14:15], v[26:27] op_sel_hi:[1,0,1]
	s_waitcnt lgkmcnt(0)
	v_pk_fma_f32 v[30:31], v[6:7], v[8:9], v[30:31] op_sel_hi:[1,0,1]
	v_pk_fma_f32 v[32:33], v[4:5], v[8:9], v[32:33] op_sel_hi:[1,0,1]
	v_pk_fma_f32 v[34:35], v[6:7], v[8:9], v[34:35] op_sel:[0,1,0]
	v_pk_fma_f32 v[50:51], v[4:5], v[8:9], v[12:13] op_sel:[0,1,0]
	ds_read_b128 v[12:15], v126 offset:992
	v_mov_b32_e32 v8, v11
	v_pk_fma_f32 v[36:37], v[6:7], v[10:11], v[36:37] op_sel_hi:[1,0,1]
	v_pk_fma_f32 v[38:39], v[4:5], v[10:11], v[38:39] op_sel_hi:[1,0,1]
	v_pk_fma_f32 v[40:41], v[6:7], v[8:9], v[40:41] op_sel_hi:[1,0,1]
	v_pk_fma_f32 v[42:43], v[4:5], v[8:9], v[42:43] op_sel_hi:[1,0,1]
	ds_read_b128 v[4:7], v126 offset:1008
	s_waitcnt vmcnt(0) lgkmcnt(1)
	v_pk_fma_f32 v[10:11], v[2:3], v[12:13], v[44:45] op_sel_hi:[1,0,1]
	v_pk_fma_f32 v[8:9], v[0:1], v[12:13], v[46:47] op_sel_hi:[1,0,1]
	v_pk_fma_f32 v[18:19], v[2:3], v[12:13], v[48:49] op_sel:[0,1,0]
	v_pk_fma_f32 v[16:17], v[0:1], v[12:13], v[16:17] op_sel:[0,1,0]
	v_mov_b32_e32 v12, v15
	v_pk_fma_f32 v[22:23], v[2:3], v[14:15], v[20:21] op_sel_hi:[1,0,1]
	v_pk_fma_f32 v[20:21], v[0:1], v[14:15], v[24:25] op_sel_hi:[1,0,1]
	v_pk_fma_f32 v[14:15], v[2:3], v[12:13], v[28:29] op_sel_hi:[1,0,1]
	v_pk_fma_f32 v[12:13], v[0:1], v[12:13], v[26:27] op_sel_hi:[1,0,1]
	s_waitcnt lgkmcnt(0)
	v_pk_fma_f32 v[26:27], v[2:3], v[4:5], v[30:31] op_sel_hi:[1,0,1]
	v_pk_fma_f32 v[24:25], v[0:1], v[4:5], v[32:33] op_sel_hi:[1,0,1]
	v_pk_fma_f32 v[30:31], v[2:3], v[4:5], v[34:35] op_sel:[0,1,0]
	v_pk_fma_f32 v[28:29], v[0:1], v[4:5], v[50:51] op_sel:[0,1,0]
	v_mov_b32_e32 v4, v7
	v_pk_fma_f32 v[34:35], v[2:3], v[6:7], v[36:37] op_sel_hi:[1,0,1]
	v_pk_fma_f32 v[32:33], v[0:1], v[6:7], v[38:39] op_sel_hi:[1,0,1]
	v_pk_fma_f32 v[2:3], v[2:3], v[4:5], v[40:41] op_sel_hi:[1,0,1]
	v_pk_fma_f32 v[0:1], v[0:1], v[4:5], v[42:43] op_sel_hi:[1,0,1]
	v_lshlrev_b32_e32 v4, 13, v124
	v_add3_u32 v4, 0, v4, v192
	ds_write_b128 v4, v[8:11] offset:8192
	ds_write_b128 v4, v[16:19] offset:9216
	ds_write_b128 v4, v[20:23] offset:10240
	ds_write_b128 v4, v[12:15] offset:11264
	ds_write_b128 v4, v[24:27] offset:12288
	ds_write_b128 v4, v[28:31] offset:13312
	ds_write_b128 v4, v[32:35] offset:14336
	ds_write_b128 v4, v[0:3] offset:15360
	v_add_u32_e32 v20, v126, v192
	s_waitcnt lgkmcnt(0)
	s_barrier
	ds_read_b128 v[0:3], v20 offset:8192
	ds_read_b128 v[4:7], v20 offset:16384
	v_add_u32_e32 v16, 0x2000, v20
	v_lshlrev_b32_e32 v192, 3, v125
	s_waitcnt lgkmcnt(1)
	v_pk_add_f32 v[8:9], v[2:3], 0 op_sel_hi:[1,0]
	v_pk_add_f32 v[10:11], v[0:1], 0 op_sel_hi:[1,0]
	ds_read_b128 v[0:3], v20 offset:24576
	s_waitcnt lgkmcnt(1)
	v_pk_add_f32 v[12:13], v[8:9], v[6:7]
	v_pk_add_f32 v[14:15], v[10:11], v[4:5]
	ds_read_b128 v[4:7], v20 offset:32768
	ds_read_b128 v[8:11], v16 offset:57344
	s_waitcnt lgkmcnt(2)
	v_pk_add_f32 v[12:13], v[12:13], v[2:3]
	v_pk_add_f32 v[16:17], v[14:15], v[0:1]
	ds_read_b128 v[0:3], v20 offset:40960
	s_waitcnt lgkmcnt(2)
	v_pk_add_f32 v[18:19], v[12:13], v[6:7]
	ds_read_b128 v[12:15], v20 offset:49152
	v_pk_add_f32 v[16:17], v[16:17], v[4:5]
	ds_read_b128 v[4:7], v20 offset:57344
	s_waitcnt lgkmcnt(2)
	v_pk_add_f32 v[0:1], v[16:17], v[0:1]
	v_pk_add_f32 v[2:3], v[18:19], v[2:3]
	s_waitcnt lgkmcnt(1)
	v_pk_add_f32 v[0:1], v[0:1], v[12:13]
	v_pk_add_f32 v[2:3], v[2:3], v[14:15]
	s_waitcnt lgkmcnt(0)
	v_pk_add_f32 v[0:1], v[0:1], v[4:5]
	v_add_u32_e32 v4, s26, v124
	v_ashrrev_i32_e32 v5, 31, v4
	v_lshlrev_b64 v[4:5], 11, v[4:5]
	v_pk_add_f32 v[2:3], v[2:3], v[6:7]
	v_lshl_add_u64 v[4:5], s[4:5], 0, v[4:5]
	v_lshl_add_u64 v[4:5], v[4:5], 0, s[82:83]
	v_pk_add_f32 v[2:3], v[2:3], v[10:11]
	v_pk_add_f32 v[0:1], v[0:1], v[8:9]
	v_lshl_add_u64 v[4:5], v[4:5], 0, v[192:193]
	v_cvt_pk_bf16_f32 v0, v0, v1
	v_cvt_pk_bf16_f32 v1, v2, v3
	v_add_co_u32_e32 v2, vcc, 0x11e00000, v4
	s_nop 1
	v_addc_co_u32_e32 v3, vcc, 0, v5, vcc
	global_store_dwordx2 v[2:3], v[0:1], off
	s_waitcnt lgkmcnt(0)
	s_barrier
	s_cbranch_scc1 .LBB0_43
.LBB0_50:
	s_ashr_i32 s4, s25, 2
	s_ashr_i32 s5, s4, 31
	s_lshl_b64 s[16:17], s[4:5], 18
	s_add_u32 s16, s16, s10
	s_addc_u32 s17, s17, s11
	s_lshl_b32 s26, s4, 3
	v_mov_b32_e32 v101, v214
	s_addk_i32 s26, 0x4000
	s_and_b32 s27, s23, 0x300
	v_and_or_b32 v0, v101, 7, s26
	v_ashrrev_i32_e32 v1, 31, v0
	s_mov_b64 s[4:5], s[42:43]
	v_lshlrev_b64 v[0:1], 11, v[0:1]
	s_lshl_b32 s82, s27, 1
	v_lshl_add_u64 v[0:1], s[4:5], 0, v[0:1]
	v_lshl_add_u64 v[0:1], v[0:1], 0, s[82:83]
	v_and_b32_e32 v192, 48, v101
	v_lshl_add_u64 v[0:1], v[0:1], 0, v[192:193]
	s_lshl_b64 s[16:17], s[16:17], 2
	v_add_co_u32_e32 v2, vcc, s31, v0
	v_ashrrev_i32_e32 v124, 6, v101
	s_add_u32 s4, s58, s16
	v_and_b32_e32 v122, 15, v101
	v_addc_co_u32_e32 v3, vcc, 0, v1, vcc
	s_addc_u32 s5, s59, s17
	s_lshl_b32 s27, s27, 2
	v_lshlrev_b32_e32 v100, 5, v124
	v_bfe_u32 v123, v101, 4, 2
	global_load_dwordx4 v[64:67], v[2:3], off
	s_add_u32 s4, s4, s27
	v_or_b32_e32 v2, v100, v122
	s_addc_u32 s5, s5, 0
	v_lshlrev_b32_e32 v192, 5, v123
	v_ashrrev_i32_e32 v3, 31, v2
	v_lshl_add_u64 v[4:5], s[4:5], 0, v[192:193]
	v_lshlrev_b64 v[6:7], 12, v[2:3]
	v_lshl_add_u64 v[6:7], v[4:5], 0, v[6:7]
	global_load_dwordx4 v[68:71], v[6:7], off
	global_load_dwordx4 v[72:75], v[6:7], off offset:16
	global_load_dwordx4 v[76:79], v[6:7], off offset:128
	global_load_dwordx4 v[80:83], v[6:7], off offset:144
	s_mov_b64 s[4:5], 0xfc00000
	v_lshl_add_u64 v[0:1], v[0:1], 0, s[4:5]
	global_load_dwordx4 v[84:87], v[0:1], off offset:64
	global_load_dwordx4 v[88:91], v[6:7], off offset:256
	global_load_dwordx4 v[92:95], v[6:7], off offset:272
	global_load_dwordx4 v[96:99], v[0:1], off offset:128
	global_load_dwordx4 v[102:105], v[6:7], off offset:384
	global_load_dwordx4 v[106:109], v[6:7], off offset:400
	global_load_dwordx4 v[110:113], v[0:1], off offset:192
	global_load_dwordx4 v[114:117], v[6:7], off offset:512
	global_load_dwordx4 v[118:121], v[6:7], off offset:528
	s_waitcnt lgkmcnt(0)
	global_load_dwordx4 v[126:129], v[0:1], off offset:256
	global_load_dwordx4 v[130:133], v[6:7], off offset:640
	global_load_dwordx4 v[134:137], v[6:7], off offset:656
	global_load_dwordx4 v[138:141], v[0:1], off offset:320
	global_load_dwordx4 v[142:145], v[6:7], off offset:784
	global_load_dwordx4 v[146:149], v[6:7], off offset:768
	global_load_dwordx4 v[150:153], v[0:1], off offset:384
	global_load_dwordx4 v[154:157], v[0:1], off offset:448
	v_or_b32_e32 v2, 16, v2
	v_ashrrev_i32_e32 v3, 31, v2
	v_lshlrev_b64 v[2:3], 12, v[2:3]
	v_lshl_add_u64 v[4:5], v[4:5], 0, v[2:3]
	global_load_dwordx4 v[158:161], v[6:7], off offset:912
	global_load_dwordx4 v[162:165], v[6:7], off offset:896
	global_load_dwordx4 v[56:59], v[4:5], off offset:16
	global_load_dwordx4 v[60:63], v[4:5], off
	global_load_dwordx4 v[48:51], v[4:5], off offset:144
	global_load_dwordx4 v[52:55], v[4:5], off offset:128
	global_load_dwordx4 v[40:43], v[4:5], off offset:272
	global_load_dwordx4 v[44:47], v[4:5], off offset:256
	global_load_dwordx4 v[32:35], v[4:5], off offset:400
	global_load_dwordx4 v[36:39], v[4:5], off offset:384
	global_load_dwordx4 v[24:27], v[4:5], off offset:528
	global_load_dwordx4 v[28:31], v[4:5], off offset:512
	global_load_dwordx4 v[16:19], v[4:5], off offset:656
	global_load_dwordx4 v[20:23], v[4:5], off offset:640
	global_load_dwordx4 v[8:11], v[4:5], off offset:784
	global_load_dwordx4 v[12:15], v[4:5], off offset:768
	global_load_dwordx4 v[0:3], v[4:5], off offset:912
	s_nop 0
	global_load_dwordx4 v[4:7], v[4:5], off offset:896
	v_cmp_lt_u32_e64 s[4:5], 7, v122
	v_lshl_add_u32 v125, v122, 2, 0
	v_lshl_or_b32 v123, v123, 2, v100
	v_cmp_gt_u32_e32 vcc, 8, v122
	s_waitcnt vmcnt(0) lgkmcnt(0)
	v_cndmask_b32_e64 v67, v67, 0, s[4:5]
	v_cndmask_b32_e64 v66, v66, 0, s[4:5]
	v_cndmask_b32_e64 v65, v65, 0, s[4:5]
	v_cndmask_b32_e64 v64, v64, 0, s[4:5]
	v_cvt_pk_bf16_f32 v68, v68, v69
	v_cvt_pk_bf16_f32 v69, v70, v71
	v_cvt_pk_bf16_f32 v70, v72, v73
	v_cvt_pk_bf16_f32 v71, v74, v75
	v_cvt_pk_bf16_f32 v72, v76, v77
	v_cvt_pk_bf16_f32 v73, v78, v79
	v_cvt_pk_bf16_f32 v74, v80, v81
	v_cvt_pk_bf16_f32 v75, v82, v83
	v_mfma_f32_16x16x32_bf16 v[76:79], v[68:71], v[64:67], 0
	v_cndmask_b32_e64 v71, v87, 0, s[4:5]
	v_cndmask_b32_e64 v70, v86, 0, s[4:5]
	v_cndmask_b32_e64 v69, v85, 0, s[4:5]
	v_cndmask_b32_e64 v68, v84, 0, s[4:5]
	v_cvt_pk_bf16_f32 v80, v88, v89
	v_cvt_pk_bf16_f32 v81, v90, v91
	v_cvt_pk_bf16_f32 v82, v92, v93
	v_cvt_pk_bf16_f32 v83, v94, v95
	v_mfma_f32_16x16x32_bf16 v[76:79], v[72:75], v[68:71], v[76:79]
	v_cndmask_b32_e64 v75, v99, 0, s[4:5]
	v_cndmask_b32_e64 v74, v98, 0, s[4:5]
	v_cndmask_b32_e64 v73, v97, 0, s[4:5]
	v_cndmask_b32_e64 v72, v96, 0, s[4:5]
	v_cvt_pk_bf16_f32 v84, v102, v103
	v_cvt_pk_bf16_f32 v85, v104, v105
	v_cvt_pk_bf16_f32 v86, v106, v107
	v_cvt_pk_bf16_f32 v87, v108, v109
	v_mfma_f32_16x16x32_bf16 v[80:83], v[80:83], v[72:75], v[76:79]
	v_cvt_pk_bf16_f32 v88, v114, v115
	v_cvt_pk_bf16_f32 v89, v116, v117
	v_cvt_pk_bf16_f32 v90, v118, v119
	v_cndmask_b32_e64 v79, v113, 0, s[4:5]
	v_cndmask_b32_e64 v78, v112, 0, s[4:5]
	v_cndmask_b32_e64 v77, v111, 0, s[4:5]
	v_cndmask_b32_e64 v76, v110, 0, s[4:5]
	v_cvt_pk_bf16_f32 v91, v120, v121
	v_cvt_pk_bf16_f32 v92, v130, v131
	v_mfma_f32_16x16x32_bf16 v[84:87], v[84:87], v[76:79], v[80:83]
	v_cvt_pk_bf16_f32 v93, v132, v133
	v_cvt_pk_bf16_f32 v94, v134, v135
	v_cvt_pk_bf16_f32 v95, v136, v137
	v_cndmask_b32_e64 v83, v129, 0, s[4:5]
	v_cndmask_b32_e64 v82, v128, 0, s[4:5]
	v_cndmask_b32_e64 v81, v127, 0, s[4:5]
	v_cndmask_b32_e64 v80, v126, 0, s[4:5]
	v_cvt_pk_bf16_f32 v96, v146, v147
	v_cvt_pk_bf16_f32 v97, v148, v149
	v_mfma_f32_16x16x32_bf16 v[88:91], v[88:91], v[80:83], v[84:87]
	v_cvt_pk_bf16_f32 v98, v142, v143
	v_cvt_pk_bf16_f32 v99, v144, v145
	v_cvt_pk_bf16_f32 v102, v162, v163
	v_cndmask_b32_e64 v87, v141, 0, s[4:5]
	v_cndmask_b32_e64 v86, v140, 0, s[4:5]
	v_cndmask_b32_e64 v85, v139, 0, s[4:5]
	v_cndmask_b32_e64 v84, v138, 0, s[4:5]
	v_cvt_pk_bf16_f32 v103, v164, v165
	v_cvt_pk_bf16_f32 v104, v158, v159
	v_mfma_f32_16x16x32_bf16 v[92:95], v[92:95], v[84:87], v[88:91]
	v_cvt_pk_bf16_f32 v105, v160, v161
	s_nop 1
	v_cndmask_b32_e64 v91, v153, 0, s[4:5]
	v_cndmask_b32_e64 v90, v152, 0, s[4:5]
	v_cndmask_b32_e64 v89, v151, 0, s[4:5]
	v_cndmask_b32_e64 v88, v150, 0, s[4:5]
	s_nop 1
	v_mfma_f32_16x16x32_bf16 v[96:99], v[96:99], v[88:91], v[92:95]
	s_nop 2
	v_cndmask_b32_e64 v95, v157, 0, s[4:5]
	v_cndmask_b32_e64 v94, v156, 0, s[4:5]
	v_cndmask_b32_e64 v93, v155, 0, s[4:5]
	v_cndmask_b32_e64 v92, v154, 0, s[4:5]
	s_nop 1
	v_mfma_f32_16x16x32_bf16 v[96:99], v[102:105], v[92:95], v[96:99]
	v_lshl_add_u32 v102, v123, 5, v125
	s_and_saveexec_b64 s[4:5], vcc
	s_cbranch_execz .LBB0_52
	s_nop 4
	ds_write2_b32 v102, v96, v97 offset1:8
	ds_write2_b32 v102, v98, v99 offset0:16 offset1:24

.LBB0_103:
	s_or_b64 exec, exec, s[0:1]
	s_mov_b64 s[0:1], s[40:41]
	s_waitcnt lgkmcnt(0)
	s_barrier
	s_lshl_b64 s[4:5], s[16:17], 14
	s_add_u32 s0, s0, s4
	s_addc_u32 s1, s1, s5
	v_lshl_add_u64 v[2:3], v[64:65], 2, s[0:1]
	s_mov_b64 s[0:1], 0x7cf8000
	v_lshl_add_u64 v[18:19], v[2:3], 0, s[0:1]
	v_readlane_b32 s0, v251, 9
	s_mov_b32 s4, 0x3b000000
	s_ashr_i32 s3, s2, 31
	v_mov_b32_e32 v1, s0
	ds_read_b64 v[20:21], v1
	v_readlane_b32 s0, v251, 10
	s_waitcnt lgkmcnt(0)
	v_add_f32_e32 v1, 0, v20
	v_mov_b32_e32 v7, s0
	v_add_f32_e32 v5, 0, v21
	ds_read_b64 v[20:21], v7
	v_readlane_b32 s0, v251, 11
	s_waitcnt lgkmcnt(0)
	v_add_f32_e32 v1, v1, v20
	v_mov_b32_e32 v7, s0
	v_add_f32_e32 v5, v5, v21
	ds_read_b64 v[20:21], v7
	v_readlane_b32 s0, v251, 12
	s_waitcnt lgkmcnt(0)
	v_add_f32_e32 v1, v1, v20
	v_mov_b32_e32 v7, s0
	v_add_f32_e32 v5, v5, v21
	ds_read_b64 v[20:21], v7
	v_readlane_b32 s0, v251, 13
	s_waitcnt lgkmcnt(0)
	v_add_f32_e32 v1, v1, v20
	v_mov_b32_e32 v7, s0
	v_add_f32_e32 v5, v5, v21
	ds_read_b64 v[20:21], v7
	v_readlane_b32 s0, v251, 14
	s_waitcnt lgkmcnt(0)
	v_add_f32_e32 v1, v1, v20
	v_mov_b32_e32 v7, s0
	v_add_f32_e32 v5, v5, v21
	ds_read_b64 v[20:21], v7
	v_readlane_b32 s0, v251, 15
	s_waitcnt lgkmcnt(0)
	v_add_f32_e32 v1, v1, v20
	v_mov_b32_e32 v7, s0
	v_add_f32_e32 v5, v5, v21
	ds_read_b64 v[20:21], v7
	v_readlane_b32 s0, v251, 16
	s_waitcnt lgkmcnt(0)
	v_add_f32_e32 v1, v1, v20
	v_mov_b32_e32 v7, s0
	v_add_f32_e32 v5, v5, v21
	ds_read_b64 v[20:21], v7
	s_mov_b32 s0, 0x7cf8000
	s_waitcnt lgkmcnt(0)
	v_add_f32_e32 v1, v1, v20
	v_mul_f32_e32 v7, 0x3b000000, v1
	v_add_f32_e32 v5, v5, v21
	v_mul_f32_e32 v7, v7, v7
	v_fma_f32 v5, v5, s4, -v7
	v_max_f32_e32 v5, 0, v5
	v_add_f32_e32 v5, 0x358637bd, v5
	v_rsq_f32_e32 v5, v5
	v_fmac_f32_e32 v16, 0xbb000000, v1
	v_mul_f32_e32 v1, v16, v5
	v_add_co_u32_e32 v16, vcc, s0, v2
	v_fma_f32 v9, v141, v1, v140
	s_nop 0
	v_addc_co_u32_e32 v17, vcc, 0, v3, vcc
	s_add_i32 s0, 0, 0x22008
	global_store_dword v[16:17], v9, off
	v_mov_b32_e32 v1, s0
	ds_read_b64 v[16:17], v1
	v_readlane_b32 s0, v251, 38
	s_waitcnt lgkmcnt(0)
	v_add_f32_e32 v1, 0, v16
	v_mov_b32_e32 v7, s0
	v_add_f32_e32 v5, 0, v17
	ds_read_b64 v[16:17], v7
	v_readlane_b32 s0, v251, 39
	s_waitcnt lgkmcnt(0)
	v_add_f32_e32 v1, v1, v16
	v_mov_b32_e32 v7, s0
	v_add_f32_e32 v5, v5, v17
	ds_read_b64 v[16:17], v7
	v_readlane_b32 s0, v251, 40
	s_waitcnt lgkmcnt(0)
	v_add_f32_e32 v1, v1, v16
	v_mov_b32_e32 v7, s0
	v_add_f32_e32 v5, v5, v17
	ds_read_b64 v[16:17], v7
	v_readlane_b32 s0, v251, 41
	s_waitcnt lgkmcnt(0)
	v_add_f32_e32 v1, v1, v16
	v_mov_b32_e32 v7, s0
	v_add_f32_e32 v5, v5, v17
	ds_read_b64 v[16:17], v7
	v_readlane_b32 s0, v251, 42
	s_waitcnt lgkmcnt(0)
	v_add_f32_e32 v1, v1, v16
	v_mov_b32_e32 v7, s0
	v_add_f32_e32 v5, v5, v17
	ds_read_b64 v[16:17], v7
	v_readlane_b32 s0, v251, 43
	s_waitcnt lgkmcnt(0)
	v_add_f32_e32 v1, v1, v16
	v_mov_b32_e32 v7, s0
	v_add_f32_e32 v5, v5, v17
	ds_read_b64 v[16:17], v7
	v_readlane_b32 s0, v251, 44
	s_waitcnt lgkmcnt(0)
	v_add_f32_e32 v1, v1, v16
	v_mov_b32_e32 v7, s0
	v_add_f32_e32 v5, v5, v17
	ds_read_b64 v[16:17], v7
	v_readlane_b32 s0, v251, 17
	s_waitcnt lgkmcnt(0)
	v_add_f32_e32 v1, v1, v16
	v_mul_f32_e32 v7, 0x3b000000, v1
	v_add_f32_e32 v5, v5, v17
	v_mul_f32_e32 v7, v7, v7
	v_fma_f32 v5, v5, s4, -v7
	v_max_f32_e32 v5, 0, v5
	v_add_f32_e32 v5, 0x358637bd, v5
	v_rsq_f32_e32 v5, v5
	v_fmac_f32_e32 v14, 0xbb000000, v1
	v_mov_b32_e32 v7, s0
	v_readlane_b32 s0, v251, 18
	v_mul_f32_e32 v1, v14, v5
	v_fma_f32 v11, v141, v1, v140
	global_store_dword v[18:19], v11, off offset:2048
	v_mov_b32_e32 v1, s30
	ds_read_b64 v[14:15], v1
	s_waitcnt lgkmcnt(0)
	v_add_f32_e32 v1, 0, v14
	v_add_f32_e32 v5, 0, v15
	ds_read_b64 v[14:15], v7
	v_mov_b32_e32 v7, s0
	v_readlane_b32 s0, v251, 19
	s_waitcnt lgkmcnt(0)
	v_add_f32_e32 v1, v1, v14
	v_add_f32_e32 v5, v5, v15
	ds_read_b64 v[14:15], v7
	v_mov_b32_e32 v7, s0
	v_readlane_b32 s0, v251, 20
	s_waitcnt lgkmcnt(0)
	v_add_f32_e32 v1, v1, v14
	v_add_f32_e32 v5, v5, v15
	ds_read_b64 v[14:15], v7
	v_mov_b32_e32 v7, s0
	v_readlane_b32 s0, v251, 21
	s_waitcnt lgkmcnt(0)
	v_add_f32_e32 v1, v1, v14
	v_add_f32_e32 v5, v5, v15
	ds_read_b64 v[14:15], v7
	v_mov_b32_e32 v7, s0
	v_readlane_b32 s0, v251, 22
	s_waitcnt lgkmcnt(0)
	v_add_f32_e32 v1, v1, v14
	v_add_f32_e32 v5, v5, v15
	ds_read_b64 v[14:15], v7
	v_mov_b32_e32 v7, s0
	v_readlane_b32 s0, v251, 23
	s_waitcnt lgkmcnt(0)
	v_add_f32_e32 v1, v1, v14
	v_add_f32_e32 v5, v5, v15
	ds_read_b64 v[14:15], v7
	v_mov_b32_e32 v7, s0
	s_mov_b32 s0, 0x7cf9000
	s_waitcnt lgkmcnt(0)
	v_add_f32_e32 v1, v1, v14
	v_add_f32_e32 v5, v5, v15
	ds_read_b64 v[14:15], v7
	s_waitcnt lgkmcnt(0)
	v_add_f32_e32 v1, v1, v14
	v_mul_f32_e32 v7, 0x3b000000, v1
	v_add_f32_e32 v5, v5, v15
	v_mul_f32_e32 v7, v7, v7
	v_fma_f32 v5, v5, s4, -v7
	v_max_f32_e32 v5, 0, v5
	v_add_f32_e32 v5, 0x358637bd, v5
	v_rsq_f32_e32 v5, v5
	v_fmac_f32_e32 v12, 0xbb000000, v1
	v_add_co_u32_e32 v14, vcc, s0, v2
	v_mul_f32_e32 v1, v12, v5
	v_fma_f32 v12, v141, v1, v140
	v_addc_co_u32_e32 v15, vcc, 0, v3, vcc
	s_add_i32 s0, 0, 0x22018
	global_store_dword v[14:15], v12, off
	v_mov_b32_e32 v1, s0
	ds_read_b64 v[16:17], v1
	v_readlane_b32 s0, v251, 45
	s_waitcnt lgkmcnt(0)
	v_add_f32_e32 v1, 0, v16
	v_mov_b32_e32 v7, s0
	v_add_f32_e32 v5, 0, v17
	ds_read_b64 v[16:17], v7
	v_readlane_b32 s0, v251, 46
	s_waitcnt lgkmcnt(0)
	v_add_f32_e32 v1, v1, v16
	v_mov_b32_e32 v7, s0
	v_add_f32_e32 v5, v5, v17
	ds_read_b64 v[16:17], v7
	v_readlane_b32 s0, v251, 47
	s_waitcnt lgkmcnt(0)
	v_add_f32_e32 v1, v1, v16
	v_mov_b32_e32 v7, s0
	v_add_f32_e32 v5, v5, v17
	ds_read_b64 v[16:17], v7
	v_readlane_b32 s0, v251, 48
	s_waitcnt lgkmcnt(0)
	v_add_f32_e32 v1, v1, v16
	v_mov_b32_e32 v7, s0
	v_add_f32_e32 v5, v5, v17
	ds_read_b64 v[16:17], v7
	v_readlane_b32 s0, v251, 49
	s_waitcnt lgkmcnt(0)
	v_add_f32_e32 v1, v1, v16
	v_mov_b32_e32 v7, s0
	v_add_f32_e32 v5, v5, v17
	ds_read_b64 v[16:17], v7
	v_readlane_b32 s0, v251, 50
	s_waitcnt lgkmcnt(0)
	v_add_f32_e32 v1, v1, v16
	v_mov_b32_e32 v7, s0
	v_add_f32_e32 v5, v5, v17
	ds_read_b64 v[16:17], v7
	v_readlane_b32 s0, v251, 51
	s_waitcnt lgkmcnt(0)
	v_add_f32_e32 v1, v1, v16
	v_mov_b32_e32 v7, s0
	v_add_f32_e32 v5, v5, v17
	ds_read_b64 v[16:17], v7
	v_readlane_b32 s0, v251, 24
	s_waitcnt lgkmcnt(0)
	v_add_f32_e32 v1, v1, v16
	v_mul_f32_e32 v7, 0x3b000000, v1
	v_add_f32_e32 v5, v5, v17
	v_mul_f32_e32 v7, v7, v7
	v_fma_f32 v5, v5, s4, -v7
	v_max_f32_e32 v5, 0, v5
	v_add_f32_e32 v5, 0x358637bd, v5
	v_rsq_f32_e32 v5, v5
	v_fmac_f32_e32 v10, 0xbb000000, v1
	v_mov_b32_e32 v7, s0
	v_readlane_b32 s0, v251, 25
	v_mul_f32_e32 v1, v10, v5
	v_fma_f32 v10, v141, v1, v140
	global_store_dword v[14:15], v10, off offset:2048
	v_mov_b32_e32 v1, s29
	ds_read_b64 v[14:15], v1
	s_waitcnt lgkmcnt(0)
	v_add_f32_e32 v1, 0, v14
	v_add_f32_e32 v5, 0, v15
	ds_read_b64 v[14:15], v7
	v_mov_b32_e32 v7, s0
	v_readlane_b32 s0, v251, 26
	s_waitcnt lgkmcnt(0)
	v_add_f32_e32 v1, v1, v14
	v_add_f32_e32 v5, v5, v15
	ds_read_b64 v[14:15], v7
	v_mov_b32_e32 v7, s0
	v_readlane_b32 s0, v251, 27
	s_waitcnt lgkmcnt(0)
	v_add_f32_e32 v1, v1, v14
	v_add_f32_e32 v5, v5, v15
	ds_read_b64 v[14:15], v7
	v_mov_b32_e32 v7, s0
	v_readlane_b32 s0, v251, 28
	s_waitcnt lgkmcnt(0)
	v_add_f32_e32 v1, v1, v14
	v_add_f32_e32 v5, v5, v15
	ds_read_b64 v[14:15], v7
	v_mov_b32_e32 v7, s0
	v_readlane_b32 s0, v251, 29
	s_waitcnt lgkmcnt(0)
	v_add_f32_e32 v1, v1, v14
	v_add_f32_e32 v5, v5, v15
	ds_read_b64 v[14:15], v7
	v_mov_b32_e32 v7, s0
	v_readlane_b32 s0, v251, 30
	s_waitcnt lgkmcnt(0)
	v_add_f32_e32 v1, v1, v14
	v_add_f32_e32 v5, v5, v15
	ds_read_b64 v[14:15], v7
	v_mov_b32_e32 v7, s0
	s_mov_b32 s0, 0x7cfa000
	s_waitcnt lgkmcnt(0)
	v_add_f32_e32 v1, v1, v14
	v_add_f32_e32 v5, v5, v15
	ds_read_b64 v[14:15], v7
	s_waitcnt lgkmcnt(0)
	v_add_f32_e32 v1, v1, v14
	v_mul_f32_e32 v7, 0x3b000000, v1
	v_add_f32_e32 v5, v5, v15
	v_mul_f32_e32 v7, v7, v7
	v_fma_f32 v5, v5, s4, -v7
	v_max_f32_e32 v5, 0, v5
	v_add_f32_e32 v5, 0x358637bd, v5
	v_rsq_f32_e32 v5, v5
	v_fmac_f32_e32 v8, 0xbb000000, v1
	v_add_co_u32_e32 v14, vcc, s0, v2
	v_mul_f32_e32 v1, v8, v5
	v_fma_f32 v8, v141, v1, v140
	v_addc_co_u32_e32 v15, vcc, 0, v3, vcc
	s_add_i32 s0, 0, 0x22028
	global_store_dword v[14:15], v8, off
	v_mov_b32_e32 v1, s0
	ds_read_b64 v[16:17], v1
	v_readlane_b32 s0, v251, 52
	s_waitcnt lgkmcnt(0)
	v_add_f32_e32 v1, 0, v16
	v_mov_b32_e32 v7, s0
	v_add_f32_e32 v5, 0, v17
	ds_read_b64 v[16:17], v7
	v_readlane_b32 s0, v251, 53
	s_waitcnt lgkmcnt(0)
	v_add_f32_e32 v1, v1, v16
	v_mov_b32_e32 v7, s0
	v_add_f32_e32 v5, v5, v17
	ds_read_b64 v[16:17], v7
	v_readlane_b32 s0, v251, 54
	s_waitcnt lgkmcnt(0)
	v_add_f32_e32 v1, v1, v16
	v_mov_b32_e32 v7, s0
	v_add_f32_e32 v5, v5, v17
	ds_read_b64 v[16:17], v7
	v_readlane_b32 s0, v251, 55
	s_waitcnt lgkmcnt(0)
	v_add_f32_e32 v1, v1, v16
	v_mov_b32_e32 v7, s0
	v_add_f32_e32 v5, v5, v17
	ds_read_b64 v[16:17], v7
	v_readlane_b32 s0, v251, 56
	s_waitcnt lgkmcnt(0)
	v_add_f32_e32 v1, v1, v16
	v_mov_b32_e32 v7, s0
	v_add_f32_e32 v5, v5, v17
	ds_read_b64 v[16:17], v7
	v_readlane_b32 s0, v251, 57
	s_waitcnt lgkmcnt(0)
	v_add_f32_e32 v1, v1, v16
	v_mov_b32_e32 v7, s0
	v_add_f32_e32 v5, v5, v17
	ds_read_b64 v[16:17], v7
	v_readlane_b32 s0, v251, 58
	s_waitcnt lgkmcnt(0)
	v_add_f32_e32 v1, v1, v16
	v_mov_b32_e32 v7, s0
	v_add_f32_e32 v5, v5, v17
	ds_read_b64 v[16:17], v7
	v_readlane_b32 s0, v251, 31
	s_waitcnt lgkmcnt(0)
	v_add_f32_e32 v1, v1, v16
	v_mul_f32_e32 v7, 0x3b000000, v1
	v_add_f32_e32 v5, v5, v17
	v_mul_f32_e32 v7, v7, v7
	v_fma_f32 v5, v5, s4, -v7
	v_max_f32_e32 v5, 0, v5
	v_add_f32_e32 v5, 0x358637bd, v5
	v_rsq_f32_e32 v5, v5
	v_fmac_f32_e32 v6, 0xbb000000, v1
	v_mul_f32_e32 v1, v6, v5
	v_fma_f32 v13, v141, v1, v140
	global_store_dword v[14:15], v13, off offset:2048
	v_mov_b32_e32 v1, s28
	ds_read_b64 v[6:7], v1
	v_readlane_b32 s16, v250, 5
	v_readlane_b32 s30, v250, 19
	v_readlane_b32 s31, v250, 20
	v_readlane_b32 s17, v250, 6
	s_waitcnt lgkmcnt(0)
	v_add_f32_e32 v1, 0, v6
	v_mov_b32_e32 v6, s0
	v_add_f32_e32 v5, 0, v7
	ds_read_b64 v[6:7], v6
	v_readlane_b32 s0, v251, 32
	v_readlane_b32 s18, v250, 7
	v_readlane_b32 s19, v250, 8
	v_readlane_b32 s20, v250, 9
	s_waitcnt lgkmcnt(0)
	v_add_f32_e32 v1, v1, v6
	v_mov_b32_e32 v6, s0
	v_add_f32_e32 v5, v5, v7
	ds_read_b64 v[6:7], v6
	v_readlane_b32 s0, v251, 33
	v_readlane_b32 s21, v250, 10
	v_readlane_b32 s22, v250, 11
	v_readlane_b32 s23, v250, 12
	s_waitcnt lgkmcnt(0)
	v_add_f32_e32 v1, v1, v6
	v_mov_b32_e32 v6, s0
	v_add_f32_e32 v5, v5, v7
	ds_read_b64 v[6:7], v6
	v_readlane_b32 s0, v251, 34
	v_readlane_b32 s24, v250, 13
	v_readlane_b32 s25, v250, 14
	v_readlane_b32 s26, v250, 15
	s_waitcnt lgkmcnt(0)
	v_add_f32_e32 v1, v1, v6
	v_mov_b32_e32 v6, s0
	v_add_f32_e32 v5, v5, v7
	ds_read_b64 v[6:7], v6
	v_readlane_b32 s0, v251, 35
	v_readlane_b32 s27, v250, 16
	v_readlane_b32 s28, v250, 17
	v_readlane_b32 s29, v250, 18
	s_waitcnt lgkmcnt(0)
	v_add_f32_e32 v1, v1, v6
	v_mov_b32_e32 v6, s0
	v_add_f32_e32 v5, v5, v7
	ds_read_b64 v[6:7], v6
	v_readlane_b32 s0, v251, 36
	s_waitcnt lgkmcnt(0)
	v_add_f32_e32 v1, v1, v6
	v_mov_b32_e32 v6, s0
	v_add_f32_e32 v5, v5, v7
	ds_read_b64 v[6:7], v6
	v_readlane_b32 s0, v251, 37
	s_waitcnt lgkmcnt(0)
	v_add_f32_e32 v1, v1, v6
	v_mov_b32_e32 v6, s0
	v_add_f32_e32 v5, v5, v7
	ds_read_b64 v[6:7], v6
	s_mov_b32 s0, 0x7cfb000
	v_add_co_u32_e32 v2, vcc, s0, v2
	s_add_i32 s0, 0, 0x22038
	s_waitcnt lgkmcnt(0)
	v_add_f32_e32 v1, v1, v6
	v_mul_f32_e32 v6, 0x3b000000, v1
	v_add_f32_e32 v5, v5, v7
	v_mul_f32_e32 v6, v6, v6
	v_fma_f32 v5, v5, s4, -v6
	v_max_f32_e32 v5, 0, v5
	v_add_f32_e32 v5, 0x358637bd, v5
	v_rsq_f32_e32 v5, v5
	v_fmac_f32_e32 v4, 0xbb000000, v1
	v_addc_co_u32_e32 v3, vcc, 0, v3, vcc
	v_mul_f32_e32 v1, v4, v5
	v_fma_f32 v14, v141, v1, v140
	global_store_dword v[2:3], v14, off
	v_mov_b32_e32 v1, s0
	ds_read_b64 v[4:5], v1
	v_readlane_b32 s0, v251, 59
	s_waitcnt lgkmcnt(0)
	v_add_f32_e32 v1, 0, v4
	v_mov_b32_e32 v4, s0
	v_add_f32_e32 v6, 0, v5
	ds_read_b64 v[4:5], v4
	v_readlane_b32 s0, v251, 60
	s_waitcnt lgkmcnt(0)
	v_add_f32_e32 v1, v1, v4
	v_mov_b32_e32 v4, s0
	v_add_f32_e32 v6, v6, v5
	ds_read_b64 v[4:5], v4
	v_readlane_b32 s0, v251, 61
	s_waitcnt lgkmcnt(0)
	v_add_f32_e32 v1, v1, v4
	v_mov_b32_e32 v4, s0
	v_add_f32_e32 v6, v6, v5
	ds_read_b64 v[4:5], v4
	v_readlane_b32 s0, v251, 62
	s_waitcnt lgkmcnt(0)
	v_add_f32_e32 v1, v1, v4
	v_mov_b32_e32 v4, s0
	v_add_f32_e32 v6, v6, v5
	ds_read_b64 v[4:5], v4
	v_readlane_b32 s0, v251, 63
	s_waitcnt lgkmcnt(0)
	v_add_f32_e32 v1, v1, v4
	v_mov_b32_e32 v4, s0
	v_add_f32_e32 v6, v6, v5
	ds_read_b64 v[4:5], v4
	v_readlane_b32 s0, v252, 0
	s_waitcnt lgkmcnt(0)
	v_add_f32_e32 v1, v1, v4
	v_mov_b32_e32 v4, s0
	v_add_f32_e32 v6, v6, v5
	ds_read_b64 v[4:5], v4
	v_readlane_b32 s0, v252, 1
	s_waitcnt lgkmcnt(0)
	v_add_f32_e32 v1, v1, v4
	v_mov_b32_e32 v4, s0
	v_add_f32_e32 v6, v6, v5
	ds_read_b64 v[4:5], v4
	s_lshl_b64 s[0:1], s[2:3], 7
	s_waitcnt lgkmcnt(0)
	v_add_f32_e32 v1, v1, v4
	v_add_f32_e32 v4, v6, v5
	v_mul_f32_e32 v5, 0x3b000000, v1
	v_mul_f32_e32 v5, v5, v5
	v_fma_f32 v4, v4, s4, -v5
	v_max_f32_e32 v4, 0, v4
	v_readlane_b32 s4, v253, 61
	v_add_f32_e32 v4, 0x358637bd, v4
	v_readlane_b32 s5, v253, 62
	s_add_u32 s0, s0, s4
	v_rsq_f32_e32 v4, v4
	s_addc_u32 s1, s1, s5
	s_lshl_b64 s[0:1], s[0:1], 9
	s_add_u32 s0, s30, s0
	v_fmac_f32_e32 v0, 0xbb000000, v1
	s_addc_u32 s1, s31, s1
	s_lshl_b64 s[2:3], s[2:3], 9
	v_readlane_b32 s4, v253, 51
	v_mul_f32_e32 v0, v0, v4
	v_readlane_b32 s5, v253, 52
	s_add_u32 s2, s4, s2
	v_fmac_f32_e32 v140, v141, v0
	s_addc_u32 s3, s5, s3
	s_mov_b64 s[4:5], s[42:43]
	global_store_dword v[2:3], v140, off offset:2048
	global_load_dwordx4 v[0:3], v193, s[2:3] offset:16
	global_load_dwordx4 v[16:19], v193, s[2:3]
	global_load_dword v6, v193, s[0:1]
	s_add_u32 s4, s4, s14
	s_addc_u32 s5, s5, s15
	v_lshl_add_u64 v[4:5], v[64:65], 1, s[4:5]
	s_brev_b32 s2, 40
	v_add_co_u32_e32 v20, vcc, s2, v4
	s_mov_b32 s2, 0x14001000
	s_nop 0
	v_addc_co_u32_e32 v21, vcc, 0, v5, vcc
	s_waitcnt vmcnt(0)
	v_fma_f32 v15, v9, v6, v16
	ds_read2st64_b32 v[6:7], v92 offset0:64 offset1:72
	s_waitcnt lgkmcnt(0)
	v_mul_f32_e32 v6, v6, v15
	v_cvt_pk_bf16_f32 v6, v6, s0
	global_store_short v[20:21], v6, off offset:2048
	global_load_dwordx2 v[20:21], v193, s[0:1] offset:512
	s_waitcnt vmcnt(0)
	v_fma_f32 v6, v9, v20, v17
	v_fmac_f32_e32 v6, v11, v21
	global_load_dwordx3 v[20:22], v193, s[0:1] offset:1024
	v_mul_f32_e32 v6, v7, v6
	v_cvt_pk_bf16_f32 v15, v6, s0
	v_add_co_u32_e32 v6, vcc, s2, v4
	s_mov_b32 s2, 0x14002000
	s_nop 0
	v_addc_co_u32_e32 v7, vcc, 0, v5, vcc
	global_store_short v[6:7], v15, off offset:2048
	ds_read2st64_b32 v[6:7], v92 offset0:80 offset1:88
	v_add_co_u32_e32 v16, vcc, s2, v4
	s_mov_b32 s2, 0x14003000
	s_nop 0
	v_addc_co_u32_e32 v17, vcc, 0, v5, vcc
	s_waitcnt vmcnt(0)
	v_fma_f32 v15, v9, v20, v18
	v_fmac_f32_e32 v15, v11, v21
	v_fmac_f32_e32 v15, v12, v22
	global_load_dwordx4 v[20:23], v193, s[0:1] offset:1536
	s_waitcnt lgkmcnt(0)
	v_mul_f32_e32 v6, v6, v15
	v_cvt_pk_bf16_f32 v6, v6, s0
	global_store_short v[16:17], v6, off offset:2048
	s_waitcnt vmcnt(0)
	v_fmac_f32_e32 v19, v9, v20
	v_fmac_f32_e32 v19, v11, v21
	v_fmac_f32_e32 v19, v12, v22
	v_fmac_f32_e32 v19, v10, v23
	v_mul_f32_e32 v6, v7, v19
	v_cvt_pk_bf16_f32 v15, v6, s0
	v_add_co_u32_e32 v6, vcc, s2, v4
	s_mov_b32 s2, 0x14004000
	s_nop 0
	v_addc_co_u32_e32 v7, vcc, 0, v5, vcc
	global_store_short v[6:7], v15, off offset:2048
	global_load_dword v6, v193, s[0:1] offset:2064
	s_nop 0
	global_load_dwordx4 v[16:19], v193, s[0:1] offset:2048
	s_waitcnt vmcnt(0)
	v_fma_f32 v0, v9, v16, v0
	v_fmac_f32_e32 v0, v11, v17
	v_fmac_f32_e32 v0, v12, v18
	v_fmac_f32_e32 v0, v10, v19
	v_fmac_f32_e32 v0, v8, v6
	ds_read2st64_b32 v[6:7], v92 offset0:96 offset1:104
	v_add_co_u32_e32 v16, vcc, s2, v4
	s_mov_b32 s2, 0x14005000
	s_nop 0
	v_addc_co_u32_e32 v17, vcc, 0, v5, vcc
	s_waitcnt lgkmcnt(0)
	v_mul_f32_e32 v0, v6, v0
	v_cvt_pk_bf16_f32 v0, v0, s0
	global_store_short v[16:17], v0, off offset:2048
	global_load_dwordx2 v[20:21], v193, s[0:1] offset:2576
	s_nop 0
	global_load_dwordx4 v[16:19], v193, s[0:1] offset:2560
	s_waitcnt vmcnt(0)
	v_fma_f32 v0, v9, v16, v1
	v_fmac_f32_e32 v0, v11, v17
	v_fmac_f32_e32 v0, v12, v18
	v_fmac_f32_e32 v0, v10, v19
	v_fmac_f32_e32 v0, v8, v20
	v_fmac_f32_e32 v0, v13, v21
	v_mul_f32_e32 v0, v7, v0
	v_cvt_pk_bf16_f32 v6, v0, s0
	v_add_co_u32_e32 v0, vcc, s2, v4
	s_mov_b32 s2, 0x14006000
	s_nop 0
	v_addc_co_u32_e32 v1, vcc, 0, v5, vcc
	global_store_short v[0:1], v6, off offset:2048
	global_load_dwordx3 v[20:22], v193, s[0:1] offset:3088
	global_load_dwordx4 v[16:19], v193, s[0:1] offset:3072
	ds_read2st64_b32 v[0:1], v92 offset0:112 offset1:120
	v_add_co_u32_e32 v6, vcc, s2, v4
	s_waitcnt vmcnt(0)
	v_fma_f32 v2, v9, v16, v2
	v_fmac_f32_e32 v2, v11, v17
	v_fmac_f32_e32 v2, v12, v18
	v_fmac_f32_e32 v2, v10, v19
	v_fmac_f32_e32 v2, v8, v20
	v_fmac_f32_e32 v2, v13, v21
	v_fmac_f32_e32 v2, v14, v22
	s_waitcnt lgkmcnt(0)
	v_mul_f32_e32 v0, v0, v2
	v_cvt_pk_bf16_f32 v0, v0, s0
	v_addc_co_u32_e32 v7, vcc, 0, v5, vcc
	global_store_short v[6:7], v0, off offset:2048
	global_load_dwordx4 v[16:19], v193, s[0:1] offset:3600
	global_load_dwordx4 v[20:23], v193, s[0:1] offset:3584
	s_waitcnt vmcnt(0)
	v_fmac_f32_e32 v3, v9, v20
	v_fmac_f32_e32 v3, v11, v21
	v_fmac_f32_e32 v3, v12, v22
	v_fmac_f32_e32 v3, v10, v23
	v_fmac_f32_e32 v3, v8, v16
	v_fmac_f32_e32 v3, v13, v17
	v_fmac_f32_e32 v3, v14, v18
	v_fmac_f32_e32 v3, v140, v19
	v_mul_f32_e32 v0, v1, v3
	v_cvt_pk_bf16_f32 v2, v0, s0
	v_add_co_u32_e32 v0, vcc, 0x14007000, v4
	s_nop 1
	v_addc_co_u32_e32 v1, vcc, 0, v5, vcc
	global_store_short v[0:1], v2, off offset:2048
	s_waitcnt lgkmcnt(0)
	s_barrier

.LBB0_109:
	v_readlane_b32 s0, v253, 43
	v_readlane_b32 s1, v253, 44
	s_or_b32 s0, s0, s10
	s_lshl_b64 s[0:1], s[0:1], 9
	v_readlane_b32 s12, v252, 40
	v_readlane_b32 s13, v252, 41
	s_add_u32 s0, s12, s0
	v_lshl_or_b32 v36, v183, 2, s8
	s_addc_u32 s1, s13, s1
	v_ashrrev_i32_e32 v37, 31, v36
	v_lshl_add_u64 v[32:33], v[36:37], 2, s[0:1]
	v_lshlrev_b32_e32 v38, 2, v34
	global_load_dwordx4 v[32:35], v[32:33], off
	v_mul_lo_u32 v36, v36, s66
	v_add3_u32 v36, 0, v38, v36
	v_add_u32_e32 v37, 0x9000, v36
	s_lshl_b32 s82, s10, 8
	v_lshlrev_b32_e32 v192, 1, v182
	s_mov_b64 s[0:1], s[42:43]
	v_readlane_b32 s14, v252, 42
	v_readlane_b32 s15, v252, 43
	v_readlane_b32 s16, v252, 44
	v_readlane_b32 s17, v252, 45
	v_readlane_b32 s18, v252, 46
	v_readlane_b32 s19, v252, 47
	v_readlane_b32 s20, v252, 48
	v_readlane_b32 s21, v252, 49
	v_readlane_b32 s22, v252, 50
	v_readlane_b32 s23, v252, 51
	v_readlane_b32 s24, v252, 52
	v_readlane_b32 s25, v252, 53
	v_readlane_b32 s26, v252, 54
	v_readlane_b32 s27, v252, 55
	s_waitcnt vmcnt(0)
	v_add_f32_e32 v4, v4, v32
	v_add_f32_e32 v0, v0, v32
	ds_write2_b32 v37, v4, v0 offset0:96 offset1:112
	v_add_f32_e32 v0, v25, v33
	v_add_f32_e32 v4, v29, v33
	ds_write2_b32 v37, v0, v4 offset0:132 offset1:148
	v_add_f32_e32 v0, v21, v33
	v_add_f32_e32 v4, v17, v33
	ds_write2_b32 v37, v0, v4 offset0:164 offset1:180
	v_add_f32_e32 v0, v13, v33
	v_add_f32_e32 v4, v9, v33
	ds_write2_b32 v37, v0, v4 offset0:196 offset1:212
	v_add_f32_e32 v0, v5, v33
	v_add_f32_e32 v1, v1, v33
	ds_write2_b32 v37, v0, v1 offset0:228 offset1:244
	v_add_f32_e32 v0, v26, v34
	v_add_f32_e32 v1, v30, v34
	v_add_u32_e32 v4, 0x9400, v36
	ds_write2_b32 v4, v0, v1 offset0:8 offset1:24
	v_add_f32_e32 v0, v22, v34
	v_add_f32_e32 v1, v18, v34
	ds_write2_b32 v4, v0, v1 offset0:40 offset1:56
	v_add_f32_e32 v0, v14, v34
	v_add_f32_e32 v1, v10, v34
	ds_write2_b32 v4, v0, v1 offset0:72 offset1:88
	v_add_f32_e32 v0, v6, v34
	v_add_f32_e32 v1, v2, v34
	ds_write2_b32 v4, v0, v1 offset0:104 offset1:120
	v_add_f32_e32 v0, v27, v35
	v_add_f32_e32 v1, v31, v35
	ds_write2_b32 v4, v0, v1 offset0:140 offset1:156
	v_add_f32_e32 v0, v23, v35
	v_add_f32_e32 v1, v19, v35
	ds_write2_b32 v4, v0, v1 offset0:172 offset1:188
	v_add_f32_e32 v0, v15, v35
	v_add_f32_e32 v1, v11, v35
	ds_write2_b32 v4, v0, v1 offset0:204 offset1:220
	v_add_f32_e32 v0, v7, v35
	v_add_f32_e32 v1, v3, v35
	v_ashrrev_i32_e32 v9, 4, v65
	ds_write2_b32 v4, v0, v1 offset0:236 offset1:252
	v_add_u32_e32 v10, s7, v9
	v_mov_b64_e32 v[0:1], s[2:3]
	v_mad_i64_i32 v[2:3], s[2:3], v10, s76, v[0:1]
	v_lshl_add_u64 v[2:3], v[2:3], 0, s[82:83]
	v_add_f32_e32 v24, v24, v32
	v_add_f32_e32 v28, v28, v32
	v_add_f32_e32 v20, v20, v32
	v_add_f32_e32 v16, v16, v32
	v_add_f32_e32 v12, v12, v32
	v_add_f32_e32 v8, v8, v32
	v_lshl_add_u64 v[2:3], v[2:3], 0, v[192:193]
	ds_write2_b32 v37, v24, v28 offset1:16
	ds_write2_b32 v37, v20, v16 offset0:32 offset1:48
	ds_write2_b32 v37, v12, v8 offset0:64 offset1:80
	s_waitcnt lgkmcnt(0)
	s_barrier
	global_load_dwordx4 v[18:21], v[2:3], off offset:3072
	v_add_u32_e32 v2, 0x200, v65
	v_ashrrev_i32_e32 v38, 4, v2
	v_add_u32_e32 v34, s7, v38
	v_mad_i64_i32 v[2:3], s[2:3], v34, s76, v[0:1]
	v_lshl_add_u64 v[2:3], v[2:3], 0, s[82:83]
	v_lshl_add_u64 v[2:3], v[2:3], 0, v[192:193]
	global_load_dwordx4 v[22:25], v[2:3], off offset:3072
	v_add_u32_e32 v2, 0x400, v65
	v_ashrrev_i32_e32 v39, 4, v2
	v_add_u32_e32 v16, s7, v39
	v_mad_i64_i32 v[2:3], s[2:3], v16, s76, v[0:1]
	v_lshl_add_u64 v[2:3], v[2:3], 0, s[82:83]
	v_lshl_add_u64 v[2:3], v[2:3], 0, v[192:193]
	global_load_dwordx4 v[4:7], v[2:3], off offset:3072
	v_add_u32_e32 v2, 0x600, v65
	v_ashrrev_i32_e32 v40, 4, v2
	v_add_u32_e32 v12, s7, v40
	v_mad_i64_i32 v[0:1], s[2:3], v12, s76, v[0:1]
	v_lshl_add_u64 v[0:1], v[0:1], 0, s[82:83]
	v_lshl_add_u64 v[0:1], v[0:1], 0, v[192:193]
	global_load_dwordx4 v[0:3], v[0:1], off offset:3072
	s_add_u32 s0, s0, s82
	s_addc_u32 s1, s1, 0
	v_lshl_add_u32 v8, v182, 2, 0
	v_lshl_add_u64 v[14:15], s[0:1], 0, v[192:193]
	s_mov_b64 s[0:1], 0x14000800
	v_lshl_add_u64 v[14:15], v[14:15], 0, s[0:1]
	v_mad_u64_u32 v[30:31], s[0:1], v9, s66, v[8:9]
	ds_read_b128 v[26:29], v30 offset:36864
	ds_read_b128 v[30:33], v30 offset:36880
	v_ashrrev_i32_e32 v11, 31, v10
	v_lshlrev_b64 v[10:11], 12, v[10:11]
	v_lshl_add_u64 v[10:11], v[14:15], 0, v[10:11]
	v_ashrrev_i32_e32 v35, 31, v34
	v_ashrrev_i32_e32 v17, 31, v16
	v_ashrrev_i32_e32 v13, 31, v12
	s_add_i32 s5, s5, s70
	s_add_i32 s4, s4, s70
	s_cmpk_lt_i32 s5, 0x200
	s_waitcnt vmcnt(0) lgkmcnt(0)
	v_lshlrev_b32_e32 v36, 16, v18
	v_and_b32_e32 v37, 0xffff0000, v18
	v_pk_mul_f32 v[26:27], v[26:27], v[36:37]
	s_nop 0
	v_cvt_pk_bf16_f32 v18, v26, v27
	v_lshlrev_b32_e32 v26, 16, v19
	v_and_b32_e32 v27, 0xffff0000, v19
	v_pk_mul_f32 v[26:27], v[28:29], v[26:27]
	s_nop 0
	v_cvt_pk_bf16_f32 v19, v26, v27
	v_lshlrev_b32_e32 v26, 16, v20
	v_and_b32_e32 v27, 0xffff0000, v20
	v_pk_mul_f32 v[26:27], v[30:31], v[26:27]
	s_nop 0
	v_cvt_pk_bf16_f32 v20, v26, v27
	v_lshlrev_b32_e32 v26, 16, v21
	v_and_b32_e32 v27, 0xffff0000, v21
	v_pk_mul_f32 v[26:27], v[32:33], v[26:27]
	s_nop 0
	v_cvt_pk_bf16_f32 v21, v26, v27
	global_store_dwordx4 v[10:11], v[18:21], off
	v_mad_u64_u32 v[10:11], s[0:1], v38, s66, v[8:9]
	ds_read_b128 v[18:21], v10 offset:36864
	ds_read_b128 v[26:29], v10 offset:36880
	v_lshlrev_b32_e32 v10, 16, v22
	v_and_b32_e32 v11, 0xffff0000, v22
	s_waitcnt lgkmcnt(0)
	v_pk_mul_f32 v[10:11], v[18:19], v[10:11]
	s_nop 0
	v_cvt_pk_bf16_f32 v18, v10, v11
	v_lshlrev_b32_e32 v10, 16, v23
	v_and_b32_e32 v11, 0xffff0000, v23
	v_pk_mul_f32 v[10:11], v[20:21], v[10:11]
	s_nop 0
	v_cvt_pk_bf16_f32 v19, v10, v11
	v_lshlrev_b32_e32 v10, 16, v24
	v_and_b32_e32 v11, 0xffff0000, v24
	v_pk_mul_f32 v[10:11], v[26:27], v[10:11]
	s_nop 0
	v_cvt_pk_bf16_f32 v20, v10, v11
	v_lshlrev_b32_e32 v10, 16, v25
	v_and_b32_e32 v11, 0xffff0000, v25
	v_pk_mul_f32 v[10:11], v[28:29], v[10:11]
	s_nop 0
	v_cvt_pk_bf16_f32 v21, v10, v11
	v_lshlrev_b64 v[10:11], 12, v[34:35]
	v_lshl_add_u64 v[10:11], v[14:15], 0, v[10:11]
	global_store_dwordx4 v[10:11], v[18:21], off
	v_mad_u64_u32 v[10:11], s[0:1], v39, s66, v[8:9]
	ds_read_b128 v[18:21], v10 offset:36864
	ds_read_b128 v[22:25], v10 offset:36880
	v_lshlrev_b32_e32 v10, 16, v4
	v_and_b32_e32 v11, 0xffff0000, v4
	s_waitcnt lgkmcnt(0)
	v_pk_mul_f32 v[10:11], v[18:19], v[10:11]
	s_nop 0
	v_cvt_pk_bf16_f32 v4, v10, v11
	v_lshlrev_b32_e32 v10, 16, v5
	v_and_b32_e32 v11, 0xffff0000, v5
	v_pk_mul_f32 v[10:11], v[20:21], v[10:11]
	s_nop 0
	v_cvt_pk_bf16_f32 v5, v10, v11
	v_lshlrev_b32_e32 v10, 16, v6
	v_and_b32_e32 v11, 0xffff0000, v6
	v_pk_mul_f32 v[10:11], v[22:23], v[10:11]
	s_nop 0
	v_cvt_pk_bf16_f32 v6, v10, v11
	v_lshlrev_b32_e32 v10, 16, v7
	v_and_b32_e32 v11, 0xffff0000, v7
	v_pk_mul_f32 v[10:11], v[24:25], v[10:11]
	s_nop 0
	v_cvt_pk_bf16_f32 v7, v10, v11
	v_lshlrev_b64 v[10:11], 12, v[16:17]
	v_lshl_add_u64 v[10:11], v[14:15], 0, v[10:11]
	global_store_dwordx4 v[10:11], v[4:7], off
	v_lshlrev_b32_e32 v16, 16, v0
	v_and_b32_e32 v17, 0xffff0000, v0
	v_mad_u64_u32 v[4:5], s[0:1], v40, s66, v[8:9]
	ds_read_b128 v[8:11], v4 offset:36864
	ds_read_b128 v[4:7], v4 offset:36880
	s_waitcnt lgkmcnt(0)
	v_pk_mul_f32 v[8:9], v[8:9], v[16:17]
	s_nop 0
	v_cvt_pk_bf16_f32 v0, v8, v9
	v_lshlrev_b32_e32 v8, 16, v1
	v_and_b32_e32 v9, 0xffff0000, v1
	v_pk_mul_f32 v[8:9], v[10:11], v[8:9]
	s_nop 0
	v_cvt_pk_bf16_f32 v1, v8, v9
	v_lshlrev_b32_e32 v8, 16, v2
	v_and_b32_e32 v9, 0xffff0000, v2
	v_pk_mul_f32 v[4:5], v[4:5], v[8:9]
	s_nop 0
	v_cvt_pk_bf16_f32 v2, v4, v5
	v_lshlrev_b32_e32 v4, 16, v3
	v_and_b32_e32 v5, 0xffff0000, v3
	v_pk_mul_f32 v[4:5], v[6:7], v[4:5]
	s_nop 0
	v_cvt_pk_bf16_f32 v3, v4, v5
	v_lshlrev_b64 v[4:5], 12, v[12:13]
	v_lshl_add_u64 v[4:5], v[14:15], 0, v[4:5]
	global_store_dwordx4 v[4:5], v[0:3], off
	s_waitcnt lgkmcnt(0)
	s_barrier
	s_cbranch_scc0 .LBB0_117
.LBB0_110:
	v_mov_b32_e32 v65, v214
	s_lshl_b32 s0, s5, 5
	v_readfirstlane_b32 s9, v65
	s_ashr_i32 s11, s9, 6
	s_and_b32 s7, s0, 0xffffff80
	s_mov_b64 s[0:1], s[42:43]
	s_add_u32 s2, s0, 0x18400000
	s_addc_u32 s3, s1, 0
	s_lshl_b32 s8, s11, 4
	s_add_i32 s0, s8, s7
	s_mul_i32 s10, s0, 0x3800
	s_mul_hi_i32 s1, s0, 0x3800
	s_add_u32 s12, s2, s10
	v_and_b32_e32 v178, 63, v65
	s_addc_u32 s13, s3, s1
	s_or_b32 s1, s0, 1
	v_lshlrev_b32_e32 v192, 4, v178
	s_mul_hi_i32 s10, s1, 0x3800
	s_mulk_i32 s1, 0x3800
	s_waitcnt vmcnt(0)
	v_lshl_add_u64 v[0:1], s[12:13], 0, v[192:193]
	s_add_u32 s12, s2, s1
	s_addc_u32 s13, s3, s10
	s_or_b32 s1, s0, 2
	s_mul_hi_i32 s10, s1, 0x3800
	s_mulk_i32 s1, 0x3800
	v_add_co_u32_e32 v0, vcc, s65, v0
	v_lshl_add_u64 v[2:3], s[12:13], 0, v[192:193]
	s_add_u32 s12, s2, s1
	v_addc_co_u32_e32 v1, vcc, 0, v1, vcc
	s_addc_u32 s13, s3, s10
	s_or_b32 s1, s0, 3
	v_add_co_u32_e32 v2, vcc, s65, v2
	s_mul_hi_i32 s10, s1, 0x3800
	s_mulk_i32 s1, 0x3800
	v_addc_co_u32_e32 v3, vcc, 0, v3, vcc
	global_load_dwordx4 v[48:51], v[0:1], off
	global_load_dwordx4 v[52:55], v[2:3], off
	v_lshl_add_u64 v[0:1], s[12:13], 0, v[192:193]
	s_add_u32 s12, s2, s1
	s_addc_u32 s13, s3, s10
	s_or_b32 s1, s0, 4
	s_mul_hi_i32 s10, s1, 0x3800
	s_mulk_i32 s1, 0x3800
	v_add_co_u32_e32 v0, vcc, s65, v0
	v_lshl_add_u64 v[2:3], s[12:13], 0, v[192:193]
	s_add_u32 s12, s2, s1
	v_addc_co_u32_e32 v1, vcc, 0, v1, vcc
	s_addc_u32 s13, s3, s10
	s_or_b32 s1, s0, 5
	v_add_co_u32_e32 v2, vcc, s65, v2
	s_mul_hi_i32 s10, s1, 0x3800
	s_mulk_i32 s1, 0x3800
	v_addc_co_u32_e32 v3, vcc, 0, v3, vcc
	global_load_dwordx4 v[56:59], v[0:1], off
	global_load_dwordx4 v[60:63], v[2:3], off
	v_lshl_add_u64 v[0:1], s[12:13], 0, v[192:193]
	s_add_u32 s12, s2, s1
	s_addc_u32 s13, s3, s10
	s_or_b32 s1, s0, 6
	s_mul_hi_i32 s10, s1, 0x3800
	s_mulk_i32 s1, 0x3800
	v_add_co_u32_e32 v0, vcc, s65, v0
	v_lshl_add_u64 v[2:3], s[12:13], 0, v[192:193]
	s_add_u32 s12, s2, s1
	v_addc_co_u32_e32 v1, vcc, 0, v1, vcc
	s_addc_u32 s13, s3, s10
	s_or_b32 s1, s0, 7
	v_add_co_u32_e32 v2, vcc, s65, v2
	s_mul_hi_i32 s10, s1, 0x3800
	s_mulk_i32 s1, 0x3800
	v_addc_co_u32_e32 v3, vcc, 0, v3, vcc
	global_load_dwordx4 v[32:35], v[0:1], off
	global_load_dwordx4 v[36:39], v[2:3], off
	v_lshl_add_u64 v[0:1], s[12:13], 0, v[192:193]
	s_add_u32 s12, s2, s1
	s_addc_u32 s13, s3, s10
	s_or_b32 s1, s0, 8
	s_mul_hi_i32 s10, s1, 0x3800
	s_mulk_i32 s1, 0x3800
	v_add_co_u32_e32 v0, vcc, s65, v0
	v_lshl_add_u64 v[2:3], s[12:13], 0, v[192:193]
	s_add_u32 s12, s2, s1
	v_addc_co_u32_e32 v1, vcc, 0, v1, vcc
	s_addc_u32 s13, s3, s10
	s_or_b32 s1, s0, 9
	v_add_co_u32_e32 v2, vcc, s65, v2
	s_mul_hi_i32 s10, s1, 0x3800
	s_mulk_i32 s1, 0x3800
	v_addc_co_u32_e32 v3, vcc, 0, v3, vcc
	global_load_dwordx4 v[40:43], v[0:1], off
	global_load_dwordx4 v[44:47], v[2:3], off
	v_lshl_add_u64 v[0:1], s[12:13], 0, v[192:193]
	s_add_u32 s12, s2, s1
	s_addc_u32 s13, s3, s10
	s_or_b32 s1, s0, 10
	s_mul_hi_i32 s10, s1, 0x3800
	s_mulk_i32 s1, 0x3800
	v_add_co_u32_e32 v0, vcc, s65, v0
	v_lshl_add_u64 v[2:3], s[12:13], 0, v[192:193]
	s_add_u32 s12, s2, s1
	v_addc_co_u32_e32 v1, vcc, 0, v1, vcc
	s_addc_u32 s13, s3, s10
	s_or_b32 s1, s0, 11
	v_add_co_u32_e32 v2, vcc, s65, v2
	s_mul_hi_i32 s10, s1, 0x3800
	s_mulk_i32 s1, 0x3800
	v_addc_co_u32_e32 v3, vcc, 0, v3, vcc
	global_load_dwordx4 v[16:19], v[0:1], off
	global_load_dwordx4 v[20:23], v[2:3], off
	v_lshl_add_u64 v[0:1], s[12:13], 0, v[192:193]
	s_add_u32 s12, s2, s1
	s_addc_u32 s13, s3, s10
	s_or_b32 s1, s0, 12
	s_mul_hi_i32 s10, s1, 0x3800
	s_mulk_i32 s1, 0x3800
	v_add_co_u32_e32 v0, vcc, s65, v0
	v_lshl_add_u64 v[2:3], s[12:13], 0, v[192:193]
	s_add_u32 s12, s2, s1
	v_addc_co_u32_e32 v1, vcc, 0, v1, vcc
	s_addc_u32 s13, s3, s10
	s_or_b32 s1, s0, 13
	v_add_co_u32_e32 v2, vcc, s65, v2
	s_mul_hi_i32 s10, s1, 0x3800
	s_mulk_i32 s1, 0x3800
	v_addc_co_u32_e32 v3, vcc, 0, v3, vcc
	global_load_dwordx4 v[24:27], v[0:1], off
	global_load_dwordx4 v[28:31], v[2:3], off
	v_lshl_add_u64 v[0:1], s[12:13], 0, v[192:193]
	s_add_u32 s12, s2, s1
	s_addc_u32 s13, s3, s10
	s_or_b32 s1, s0, 14
	s_mul_hi_i32 s10, s1, 0x3800
	s_mulk_i32 s1, 0x3800
	v_add_co_u32_e32 v0, vcc, s65, v0
	v_lshl_add_u64 v[2:3], s[12:13], 0, v[192:193]
	s_add_u32 s12, s2, s1
	v_addc_co_u32_e32 v1, vcc, 0, v1, vcc
	s_addc_u32 s13, s3, s10
	s_or_b32 s0, s0, 15
	v_add_co_u32_e32 v4, vcc, s65, v2
	s_mul_hi_i32 s1, s0, 0x3800
	s_mulk_i32 s0, 0x3800
	v_addc_co_u32_e32 v5, vcc, 0, v3, vcc
	v_lshl_add_u64 v[8:9], s[12:13], 0, v[192:193]
	s_add_u32 s0, s2, s0
	v_add_co_u32_e32 v8, vcc, s65, v8
	s_addc_u32 s1, s3, s1
	s_nop 0
	v_addc_co_u32_e32 v9, vcc, 0, v9, vcc
	v_lshl_add_u64 v[10:11], s[0:1], 0, v[192:193]
	v_add_co_u32_e32 v12, vcc, s65, v10
	global_load_dwordx4 v[0:3], v[0:1], off
	s_nop 0
	global_load_dwordx4 v[4:7], v[4:5], off
	v_addc_co_u32_e32 v13, vcc, 0, v11, vcc
	global_load_dwordx4 v[8:11], v[8:9], off
	s_nop 0
	global_load_dwordx4 v[12:15], v[12:13], off
	s_waitcnt vmcnt(0) lgkmcnt(0)
	v_lshlrev_b32_e32 v174, 16, v48
	v_lshlrev_b32_e32 v176, 16, v56
	v_lshlrev_b32_e32 v175, 16, v52
	v_add_f32_e32 v66, 0, v174
	v_add_f32_e32 v67, 0, v175
	v_add_f32_e32 v68, 0, v176
	v_and_b32_e32 v170, 0xffff0000, v48
	v_and_b32_e32 v172, 0xffff0000, v56
	v_and_b32_e32 v171, 0xffff0000, v52
	v_add_f32_e32 v48, v66, v170
	v_add_f32_e32 v52, v67, v171
	v_add_f32_e32 v56, v68, v172
	v_lshlrev_b32_e32 v166, 16, v49
	v_lshlrev_b32_e32 v168, 16, v57
	v_lshlrev_b32_e32 v167, 16, v53
	v_add_f32_e32 v48, v48, v166
	v_add_f32_e32 v52, v52, v167
	v_add_f32_e32 v56, v56, v168
	v_and_b32_e32 v162, 0xffff0000, v49
	v_and_b32_e32 v164, 0xffff0000, v57
	v_and_b32_e32 v163, 0xffff0000, v53
	v_add_f32_e32 v48, v48, v162
	v_add_f32_e32 v49, v52, v163
	v_add_f32_e32 v52, v56, v164
	v_lshlrev_b32_e32 v158, 16, v50
	v_lshlrev_b32_e32 v160, 16, v58
	v_lshlrev_b32_e32 v159, 16, v54
	v_add_f32_e32 v48, v48, v158
	v_add_f32_e32 v49, v49, v159
	v_add_f32_e32 v52, v52, v160
	v_and_b32_e32 v154, 0xffff0000, v50
	v_and_b32_e32 v156, 0xffff0000, v58
	v_and_b32_e32 v155, 0xffff0000, v54
	v_add_f32_e32 v48, v48, v154
	v_add_f32_e32 v49, v49, v155
	v_add_f32_e32 v50, v52, v156
	v_lshlrev_b32_e32 v146, 16, v51
	v_lshlrev_b32_e32 v148, 16, v59
	v_lshlrev_b32_e32 v147, 16, v55
	v_add_f32_e32 v48, v48, v146
	v_add_f32_e32 v49, v49, v147
	v_add_f32_e32 v50, v50, v148
	v_and_b32_e32 v150, 0xffff0000, v51
	v_and_b32_e32 v152, 0xffff0000, v59
	v_and_b32_e32 v151, 0xffff0000, v55
	v_lshlrev_b32_e32 v145, 16, v44
	v_lshlrev_b32_e32 v144, 16, v40
	v_lshlrev_b32_e32 v143, 16, v36
	v_lshlrev_b32_e32 v142, 16, v32
	v_add_f32_e32 v183, v48, v150
	v_add_f32_e32 v184, v49, v151
	v_add_f32_e32 v185, v50, v152
	v_add_f32_e32 v48, 0, v142
	v_add_f32_e32 v49, 0, v143
	v_add_f32_e32 v50, 0, v144
	v_add_f32_e32 v51, 0, v145
	v_and_b32_e32 v123, 0xffff0000, v44
	v_and_b32_e32 v122, 0xffff0000, v40
	v_and_b32_e32 v131, 0xffff0000, v36
	v_and_b32_e32 v130, 0xffff0000, v32
	v_add_f32_e32 v44, v48, v130
	v_add_f32_e32 v48, v49, v131
	v_add_f32_e32 v49, v50, v122
	v_add_f32_e32 v50, v51, v123
	v_lshlrev_b32_e32 v137, 16, v45
	v_lshlrev_b32_e32 v136, 16, v41
	v_lshlrev_b32_e32 v141, 16, v37
	v_lshlrev_b32_e32 v140, 16, v33
	v_add_f32_e32 v44, v44, v140
	v_add_f32_e32 v48, v48, v141
	v_add_f32_e32 v49, v49, v136
	v_add_f32_e32 v50, v50, v137
	v_and_b32_e32 v133, 0xffff0000, v45
	v_and_b32_e32 v132, 0xffff0000, v41
	v_and_b32_e32 v139, 0xffff0000, v37
	v_and_b32_e32 v138, 0xffff0000, v33
	v_add_f32_e32 v33, v44, v138
	v_add_f32_e32 v37, v48, v139
	v_add_f32_e32 v41, v49, v132
	v_add_f32_e32 v44, v50, v133
	v_lshlrev_b32_e32 v127, 16, v46
	v_lshlrev_b32_e32 v126, 16, v42
	v_lshlrev_b32_e32 v135, 16, v38
	v_add_f32_e32 v37, v37, v135
	v_add_f32_e32 v41, v41, v126
	v_add_f32_e32 v44, v44, v127
	v_and_b32_e32 v121, 0xffff0000, v46
	v_and_b32_e32 v120, 0xffff0000, v42
	v_and_b32_e32 v129, 0xffff0000, v38
	v_lshlrev_b32_e32 v134, 16, v34
	v_and_b32_e32 v128, 0xffff0000, v34
	v_add_f32_e32 v34, v37, v129
	v_add_f32_e32 v37, v41, v120
	v_add_f32_e32 v38, v44, v121
	v_lshlrev_b32_e32 v117, 16, v47
	v_lshlrev_b32_e32 v116, 16, v43
	v_add_f32_e32 v37, v37, v116
	v_add_f32_e32 v38, v38, v117
	v_and_b32_e32 v115, 0xffff0000, v47
	v_and_b32_e32 v114, 0xffff0000, v43
	v_lshlrev_b32_e32 v87, 16, v28
	v_lshlrev_b32_e32 v86, 16, v24
	v_lshlrev_b32_e32 v83, 16, v20
	v_lshlrev_b32_e32 v82, 16, v16
	v_lshlrev_b32_e32 v125, 16, v39
	v_lshlrev_b32_e32 v124, 16, v35
	v_and_b32_e32 v119, 0xffff0000, v39
	v_and_b32_e32 v118, 0xffff0000, v35
	v_add_f32_e32 v35, v37, v114
	v_add_f32_e32 v37, v38, v115
	v_add_f32_e32 v38, 0, v82
	v_add_f32_e32 v39, 0, v83
	v_add_f32_e32 v41, 0, v86
	v_add_f32_e32 v42, 0, v87
	v_and_b32_e32 v79, 0xffff0000, v28
	v_and_b32_e32 v78, 0xffff0000, v24
	v_and_b32_e32 v81, 0xffff0000, v20
	v_and_b32_e32 v80, 0xffff0000, v16
	v_add_f32_e32 v28, v38, v80
	v_add_f32_e32 v38, v39, v81
	v_add_f32_e32 v39, v41, v78
	v_add_f32_e32 v41, v42, v79
	v_lshlrev_b32_e32 v91, 16, v29
	v_lshlrev_b32_e32 v90, 16, v25
	v_lshlrev_b32_e32 v93, 16, v21
	v_lshlrev_b32_e32 v92, 16, v17
	v_add_f32_e32 v28, v28, v92
	v_add_f32_e32 v38, v38, v93
	v_add_f32_e32 v39, v39, v90
	v_add_f32_e32 v41, v41, v91
	v_and_b32_e32 v95, 0xffff0000, v29
	v_and_b32_e32 v94, 0xffff0000, v25
	v_and_b32_e32 v97, 0xffff0000, v21
	v_and_b32_e32 v96, 0xffff0000, v17
	v_add_f32_e32 v17, v28, v96
	v_add_f32_e32 v21, v38, v97
	v_add_f32_e32 v25, v39, v94
	v_add_f32_e32 v28, v41, v95
	v_lshlrev_b32_e32 v99, 16, v30
	v_lshlrev_b32_e32 v98, 16, v26
	v_lshlrev_b32_e32 v101, 16, v22
	v_lshlrev_b32_e32 v177, 16, v60
	v_add_f32_e32 v21, v21, v101
	v_add_f32_e32 v25, v25, v98
	v_add_f32_e32 v28, v28, v99
	v_and_b32_e32 v103, 0xffff0000, v30
	v_and_b32_e32 v102, 0xffff0000, v26
	v_and_b32_e32 v105, 0xffff0000, v22
	v_add_f32_e32 v69, 0, v177
	v_and_b32_e32 v173, 0xffff0000, v60
	v_lshlrev_b32_e32 v100, 16, v18
	v_and_b32_e32 v104, 0xffff0000, v18
	v_add_f32_e32 v18, v21, v105
	v_add_f32_e32 v21, v25, v102
	v_add_f32_e32 v22, v28, v103
	v_lshlrev_b32_e32 v107, 16, v31
	v_lshlrev_b32_e32 v106, 16, v27
	v_add_f32_e32 v60, v69, v173
	v_lshlrev_b32_e32 v169, 16, v61
	v_add_f32_e32 v21, v21, v106
	v_add_f32_e32 v22, v22, v107
	v_and_b32_e32 v111, 0xffff0000, v31
	v_and_b32_e32 v110, 0xffff0000, v27
	v_lshlrev_b32_e32 v88, 16, v8
	v_lshlrev_b32_e32 v85, 16, v4
	v_lshlrev_b32_e32 v84, 16, v0
	v_add_f32_e32 v60, v60, v169
	v_and_b32_e32 v165, 0xffff0000, v61
	v_lshlrev_b32_e32 v109, 16, v23
	v_lshlrev_b32_e32 v108, 16, v19
	v_and_b32_e32 v113, 0xffff0000, v23
	v_and_b32_e32 v112, 0xffff0000, v19
	v_add_f32_e32 v19, v21, v110
	v_add_f32_e32 v21, v22, v111
	v_add_f32_e32 v22, 0, v84
	v_add_f32_e32 v23, 0, v85
	v_add_f32_e32 v25, 0, v88
	v_and_b32_e32 v56, 0xffff0000, v8
	v_and_b32_e32 v67, 0xffff0000, v4
	v_and_b32_e32 v66, 0xffff0000, v0
	v_add_f32_e32 v53, v60, v165
	v_lshlrev_b32_e32 v161, 16, v62
	v_lshlrev_b32_e32 v89, 16, v12
	v_and_b32_e32 v57, 0xffff0000, v12
	v_add_f32_e32 v12, v22, v66
	v_add_f32_e32 v22, v23, v67
	v_add_f32_e32 v23, v25, v56
	v_lshlrev_b32_e32 v72, 16, v9
	v_lshlrev_b32_e32 v77, 16, v5
	v_add_f32_e32 v53, v53, v161
	v_and_b32_e32 v157, 0xffff0000, v62
	v_add_f32_e32 v22, v22, v77
	v_add_f32_e32 v23, v23, v72
	v_and_b32_e32 v68, 0xffff0000, v9
	v_and_b32_e32 v75, 0xffff0000, v5
	v_add_f32_e32 v52, v53, v157
	v_lshlrev_b32_e32 v149, 16, v63
	v_add_f32_e32 v5, v22, v75
	v_add_f32_e32 v9, v23, v68
	v_lshlrev_b32_e32 v60, 16, v10
	v_lshlrev_b32_e32 v71, 16, v6
	v_add_f32_e32 v52, v52, v149
	v_and_b32_e32 v153, 0xffff0000, v63
	v_add_f32_e32 v17, v17, v100
	v_add_f32_e32 v5, v5, v71
	v_add_f32_e32 v9, v9, v60
	v_and_b32_e32 v54, 0xffff0000, v10
	v_and_b32_e32 v63, 0xffff0000, v6
	v_add_f32_e32 v186, v52, v153
	v_add_f32_e32 v17, v17, v104
	v_lshlrev_b32_e32 v70, 16, v2
	v_and_b32_e32 v62, 0xffff0000, v2
	v_add_f32_e32 v2, v5, v63
	v_add_f32_e32 v5, v9, v54
	v_lshlrev_b32_e32 v52, 16, v11
	v_mul_f32_e32 v182, v170, v170
	v_mul_f32_e32 v16, v80, v80
	v_add_f32_e32 v17, v17, v108
	v_add_f32_e32 v5, v5, v52
	v_and_b32_e32 v48, 0xffff0000, v11
	v_cmp_lt_i32_e32 vcc, v224, v218
	v_fmac_f32_e32 v182, v174, v174
	v_fmac_f32_e32 v16, v82, v82
	v_add_f32_e32 v17, v17, v112
	v_lshlrev_b32_e32 v58, 16, v3
	v_and_b32_e32 v50, 0xffff0000, v3
	v_add_f32_e32 v3, v5, v48
	v_cndmask_b32_e32 v5, v217, v224, vcc
	v_cmp_gt_u32_e32 vcc, 32, v178
	v_mul_f32_e32 v181, v171, v171
	v_fmac_f32_e32 v182, v166, v166
	v_mul_f32_e32 v20, v81, v81
	v_fmac_f32_e32 v16, v92, v92
	v_lshlrev_b32_e32 v59, 16, v7
	v_and_b32_e32 v51, 0xffff0000, v7
	v_lshlrev_b32_e32 v5, 2, v5
	v_cndmask_b32_e32 v7, v183, v17, vcc
	v_fmac_f32_e32 v181, v175, v175
	v_fmac_f32_e32 v182, v162, v162
	v_fmac_f32_e32 v20, v83, v83
	v_fmac_f32_e32 v16, v96, v96
	ds_bpermute_b32 v7, v5, v7
	v_fmac_f32_e32 v181, v167, v167
	v_fmac_f32_e32 v182, v158, v158
	v_fmac_f32_e32 v20, v93, v93
	v_fmac_f32_e32 v16, v100, v100
	v_fmac_f32_e32 v181, v163, v163
	v_fmac_f32_e32 v182, v154, v154
	v_fmac_f32_e32 v20, v97, v97
	v_fmac_f32_e32 v16, v104, v104
	v_add_f32_e32 v26, 0, v89
	v_fmac_f32_e32 v181, v159, v159
	v_fmac_f32_e32 v182, v146, v146
	v_fmac_f32_e32 v20, v101, v101
	v_fmac_f32_e32 v16, v108, v108
	v_add_f32_e32 v25, v26, v57
	v_lshlrev_b32_e32 v73, 16, v13
	v_lshlrev_b32_e32 v76, 16, v1
	v_fmac_f32_e32 v181, v155, v155
	v_fmac_f32_e32 v182, v150, v150
	v_fmac_f32_e32 v20, v105, v105
	v_add_f32_e32 v18, v18, v109
	v_fmac_f32_e32 v16, v112, v112
	v_add_f32_e32 v12, v12, v76
	v_add_f32_e32 v25, v25, v73
	v_and_b32_e32 v69, 0xffff0000, v13
	v_and_b32_e32 v74, 0xffff0000, v1
	v_cndmask_b32_e32 v9, v17, v183, vcc
	v_fmac_f32_e32 v181, v147, v147
	v_fmac_f32_e32 v20, v109, v109
	v_add_f32_e32 v18, v18, v113
	v_add_f32_e32 v1, v12, v74
	v_add_f32_e32 v12, v25, v69
	v_lshlrev_b32_e32 v61, 16, v14
	s_waitcnt lgkmcnt(0)
	v_add_f32_e32 v7, v9, v7
	v_cndmask_b32_e32 v9, v182, v16, vcc
	v_mul_f32_e32 v179, v172, v172
	v_fmac_f32_e32 v181, v151, v151
	v_mul_f32_e32 v24, v78, v78
	v_fmac_f32_e32 v20, v113, v113
	v_add_f32_e32 v12, v12, v61
	v_and_b32_e32 v55, 0xffff0000, v14
	ds_bpermute_b32 v9, v5, v9
	v_cndmask_b32_e32 v11, v184, v18, vcc
	v_fmac_f32_e32 v179, v176, v176
	v_fmac_f32_e32 v24, v86, v86
	v_add_f32_e32 v6, v12, v55
	ds_bpermute_b32 v11, v5, v11
	v_cndmask_b32_e32 v12, v181, v20, vcc
	v_fmac_f32_e32 v179, v168, v168
	v_fmac_f32_e32 v24, v90, v90
	ds_bpermute_b32 v12, v5, v12
	v_fmac_f32_e32 v179, v164, v164
	v_fmac_f32_e32 v24, v94, v94
	v_fmac_f32_e32 v179, v160, v160
	v_fmac_f32_e32 v24, v98, v98
	v_cndmask_b32_e32 v10, v16, v182, vcc
	v_fmac_f32_e32 v179, v156, v156
	v_fmac_f32_e32 v24, v102, v102
	s_waitcnt lgkmcnt(2)
	v_add_f32_e32 v9, v10, v9
	v_cndmask_b32_e32 v10, v18, v184, vcc
	v_fmac_f32_e32 v179, v148, v148
	v_fmac_f32_e32 v24, v106, v106
	s_waitcnt lgkmcnt(1)
	v_add_f32_e32 v10, v10, v11
	v_cndmask_b32_e32 v11, v20, v181, vcc
	v_mul_f32_e32 v180, v173, v173
	v_fmac_f32_e32 v179, v152, v152
	v_mul_f32_e32 v42, v79, v79
	v_fmac_f32_e32 v24, v110, v110
	s_waitcnt lgkmcnt(0)
	v_add_f32_e32 v11, v11, v12
	v_cndmask_b32_e32 v12, v185, v19, vcc
	v_fmac_f32_e32 v180, v177, v177
	v_mul_f32_e32 v32, v130, v130
	v_fmac_f32_e32 v42, v87, v87
	v_mul_f32_e32 v0, v66, v66
	ds_bpermute_b32 v12, v5, v12
	v_cndmask_b32_e32 v14, v179, v24, vcc
	v_fmac_f32_e32 v180, v169, v169
	v_fmac_f32_e32 v32, v142, v142
	v_fmac_f32_e32 v42, v91, v91
	v_fmac_f32_e32 v0, v84, v84
	v_lshlrev_b32_e32 v53, 16, v15
	v_and_b32_e32 v49, 0xffff0000, v15
	ds_bpermute_b32 v14, v5, v14
	v_cndmask_b32_e32 v15, v186, v21, vcc
	v_fmac_f32_e32 v180, v165, v165
	v_fmac_f32_e32 v32, v140, v140
	v_fmac_f32_e32 v42, v95, v95
	v_fmac_f32_e32 v0, v76, v76
	ds_bpermute_b32 v15, v5, v15
	v_fmac_f32_e32 v180, v161, v161
	v_fmac_f32_e32 v32, v138, v138
	v_fmac_f32_e32 v42, v99, v99
	v_fmac_f32_e32 v0, v74, v74
	v_fmac_f32_e32 v180, v157, v157
	v_add_f32_e32 v33, v33, v134
	v_fmac_f32_e32 v32, v134, v134
	v_fmac_f32_e32 v42, v103, v103
	v_add_f32_e32 v1, v1, v70
	v_fmac_f32_e32 v0, v70, v70
	v_cndmask_b32_e32 v13, v19, v185, vcc
	v_fmac_f32_e32 v180, v149, v149
	v_add_f32_e32 v33, v33, v128
	v_fmac_f32_e32 v32, v128, v128
	v_fmac_f32_e32 v42, v107, v107
	v_add_f32_e32 v1, v1, v62
	v_fmac_f32_e32 v0, v62, v62
	s_waitcnt lgkmcnt(2)
	v_add_f32_e32 v12, v13, v12
	v_cndmask_b32_e32 v13, v24, v179, vcc
	v_fmac_f32_e32 v180, v153, v153
	v_mul_f32_e32 v36, v131, v131
	v_add_f32_e32 v33, v33, v124
	v_fmac_f32_e32 v32, v124, v124
	v_fmac_f32_e32 v42, v111, v111
	v_mul_f32_e32 v4, v67, v67
	v_add_f32_e32 v1, v1, v58
	v_fmac_f32_e32 v0, v58, v58
	s_waitcnt lgkmcnt(1)
	v_add_f32_e32 v13, v13, v14
	v_cndmask_b32_e32 v14, v21, v186, vcc
	v_fmac_f32_e32 v36, v143, v143
	v_add_f32_e32 v33, v33, v118
	v_fmac_f32_e32 v32, v118, v118
	v_fmac_f32_e32 v4, v85, v85
	v_add_f32_e32 v1, v1, v50
	v_fmac_f32_e32 v0, v50, v50
	s_waitcnt lgkmcnt(0)
	v_add_f32_e32 v14, v14, v15
	v_cndmask_b32_e32 v15, v180, v42, vcc
	v_fmac_f32_e32 v36, v141, v141
	v_fmac_f32_e32 v4, v77, v77
	ds_bpermute_b32 v15, v5, v15
	v_cndmask_b32_e32 v17, v33, v1, vcc
	v_cndmask_b32_e32 v18, v32, v0, vcc
	v_fmac_f32_e32 v36, v139, v139
	v_fmac_f32_e32 v4, v75, v75
	ds_bpermute_b32 v17, v5, v17
	ds_bpermute_b32 v18, v5, v18
	v_fmac_f32_e32 v36, v135, v135
	v_fmac_f32_e32 v4, v71, v71
	v_mul_f32_e32 v40, v122, v122
	v_fmac_f32_e32 v36, v129, v129
	v_add_f32_e32 v34, v34, v125
	v_mul_f32_e32 v8, v56, v56
	v_fmac_f32_e32 v4, v63, v63
	v_add_f32_e32 v2, v2, v59
	v_fmac_f32_e32 v40, v144, v144
	v_mul_f32_e32 v187, v123, v123
	v_fmac_f32_e32 v36, v125, v125
	v_add_f32_e32 v34, v34, v119
	v_fmac_f32_e32 v8, v88, v88
	v_mul_f32_e32 v26, v57, v57
	v_fmac_f32_e32 v4, v59, v59
	v_add_f32_e32 v2, v2, v51
	v_cndmask_b32_e32 v16, v42, v180, vcc
	v_fmac_f32_e32 v187, v145, v145
	v_fmac_f32_e32 v40, v136, v136
	v_fmac_f32_e32 v36, v119, v119
	v_fmac_f32_e32 v26, v89, v89
	v_fmac_f32_e32 v8, v72, v72
	v_fmac_f32_e32 v4, v51, v51
	s_waitcnt lgkmcnt(2)
	v_add_f32_e32 v15, v16, v15
	v_cndmask_b32_e32 v1, v1, v33, vcc
	v_cndmask_b32_e32 v0, v0, v32, vcc
	v_cndmask_b32_e32 v16, v34, v2, vcc
	v_fmac_f32_e32 v187, v137, v137
	v_fmac_f32_e32 v40, v132, v132
	v_fmac_f32_e32 v26, v73, v73
	v_fmac_f32_e32 v8, v68, v68
	s_waitcnt lgkmcnt(1)
	v_add_f32_e32 v1, v1, v17
	s_waitcnt lgkmcnt(0)
	v_add_f32_e32 v0, v0, v18
	ds_bpermute_b32 v16, v5, v16
	v_cndmask_b32_e32 v17, v36, v4, vcc
	v_cndmask_b32_e32 v18, v35, v3, vcc
	v_fmac_f32_e32 v187, v133, v133
	v_fmac_f32_e32 v40, v126, v126
	v_fmac_f32_e32 v26, v69, v69
	v_fmac_f32_e32 v8, v60, v60
	ds_bpermute_b32 v17, v5, v17
	ds_bpermute_b32 v18, v5, v18
	v_fmac_f32_e32 v187, v127, v127
	v_fmac_f32_e32 v40, v120, v120
	v_fmac_f32_e32 v26, v61, v61
	v_fmac_f32_e32 v8, v54, v54
	v_fmac_f32_e32 v187, v121, v121
	v_fmac_f32_e32 v40, v116, v116
	v_fmac_f32_e32 v26, v55, v55
	v_fmac_f32_e32 v8, v52, v52
	v_fmac_f32_e32 v187, v117, v117
	v_fmac_f32_e32 v40, v114, v114
	v_add_f32_e32 v6, v6, v53
	v_fmac_f32_e32 v26, v53, v53
	v_fmac_f32_e32 v8, v48, v48
	v_cndmask_b32_e32 v2, v2, v34, vcc
	v_fmac_f32_e32 v187, v115, v115
	v_add_f32_e32 v6, v6, v49
	v_fmac_f32_e32 v26, v49, v49
	s_waitcnt lgkmcnt(2)
	v_add_f32_e32 v2, v2, v16
	v_cndmask_b32_e32 v4, v4, v36, vcc
	v_cndmask_b32_e32 v3, v3, v35, vcc
	v_cndmask_b32_e32 v16, v40, v8, vcc
	s_waitcnt lgkmcnt(1)
	v_add_f32_e32 v4, v4, v17
	s_waitcnt lgkmcnt(0)
	v_add_f32_e32 v3, v3, v18
	ds_bpermute_b32 v16, v5, v16
	v_cndmask_b32_e32 v17, v37, v6, vcc
	v_cndmask_b32_e32 v18, v187, v26, vcc
	ds_bpermute_b32 v17, v5, v17
	ds_bpermute_b32 v5, v5, v18
	v_cndmask_b32_e32 v8, v8, v40, vcc
	s_waitcnt lgkmcnt(2)
	v_add_f32_e32 v8, v8, v16
	v_cndmask_b32_e32 v16, v26, v187, vcc
	v_cndmask_b32_e32 v6, v6, v37, vcc
	s_waitcnt lgkmcnt(0)
	v_add_f32_e32 v5, v16, v5
	v_and_b32_e32 v16, 16, v65
	v_cmp_lt_i32_e32 vcc, v223, v218
	v_add_f32_e32 v6, v6, v17
	v_cmp_lt_i32_e64 s[0:1], v222, v218
	v_cndmask_b32_e32 v17, v217, v223, vcc
	v_cmp_eq_u32_e32 vcc, 0, v16
	v_lshlrev_b32_e32 v17, 2, v17
	s_nop 0
	v_cndmask_b32_e32 v16, v7, v1, vcc
	v_cndmask_b32_e32 v1, v1, v7, vcc
	ds_bpermute_b32 v7, v17, v16
	v_cndmask_b32_e32 v16, v9, v0, vcc
	v_cndmask_b32_e32 v0, v0, v9, vcc
	v_cndmask_b32_e32 v9, v12, v3, vcc
	ds_bpermute_b32 v9, v17, v9
	s_waitcnt lgkmcnt(1)
	v_add_f32_e32 v1, v1, v7
	v_cndmask_b32_e32 v7, v11, v4, vcc
	ds_bpermute_b32 v7, v17, v7
	v_cndmask_b32_e32 v18, v10, v2, vcc
	v_cndmask_b32_e32 v2, v2, v10, vcc
	v_cndmask_b32_e32 v10, v13, v8, vcc
	v_cndmask_b32_e32 v4, v4, v11, vcc
	ds_bpermute_b32 v10, v17, v10
	v_cndmask_b32_e32 v3, v3, v12, vcc
	ds_bpermute_b32 v16, v17, v16
	s_waitcnt lgkmcnt(2)
	v_add_f32_e32 v4, v4, v7
	v_add_f32_e32 v3, v3, v9
	v_cndmask_b32_e32 v7, v8, v13, vcc
	v_cndmask_b32_e32 v8, v14, v6, vcc
	v_cndmask_b32_e32 v9, v15, v5, vcc
	ds_bpermute_b32 v18, v17, v18
	ds_bpermute_b32 v8, v17, v8
	ds_bpermute_b32 v9, v17, v9
	s_waitcnt lgkmcnt(4)
	v_add_f32_e32 v7, v7, v10
	v_and_b32_e32 v10, 8, v65
	s_waitcnt lgkmcnt(3)
	v_add_f32_e32 v0, v0, v16
	v_cndmask_b32_e32 v6, v6, v14, vcc
	v_cndmask_b32_e64 v11, v217, v222, s[0:1]
	v_cmp_eq_u32_e64 s[0:1], 0, v10
	v_cndmask_b32_e32 v5, v5, v15, vcc
	s_waitcnt lgkmcnt(2)
	v_add_f32_e32 v2, v2, v18
	v_lshlrev_b32_e32 v11, 2, v11
	v_cndmask_b32_e64 v10, v1, v3, s[0:1]
	s_waitcnt lgkmcnt(1)
	v_add_f32_e32 v6, v6, v8
	s_waitcnt lgkmcnt(0)
	v_add_f32_e32 v5, v5, v9
	v_cndmask_b32_e64 v1, v3, v1, s[0:1]
	v_cndmask_b32_e64 v3, v0, v7, s[0:1]
	v_cndmask_b32_e64 v0, v7, v0, s[0:1]
	ds_bpermute_b32 v3, v11, v3
	v_cndmask_b32_e64 v7, v2, v6, s[0:1]
	v_cndmask_b32_e64 v8, v4, v5, s[0:1]
	ds_bpermute_b32 v10, v11, v10
	ds_bpermute_b32 v7, v11, v7
	ds_bpermute_b32 v8, v11, v8
	s_waitcnt lgkmcnt(3)
	v_add_f32_e32 v0, v0, v3
	v_cndmask_b32_e64 v2, v6, v2, s[0:1]
	v_cndmask_b32_e64 v3, v5, v4, s[0:1]
	v_and_b32_e32 v4, 4, v65
	v_cmp_lt_i32_e32 vcc, v221, v218
	s_waitcnt lgkmcnt(2)
	v_add_f32_e32 v1, v1, v10
	s_waitcnt lgkmcnt(1)
	v_add_f32_e32 v2, v2, v7
	s_waitcnt lgkmcnt(0)
	v_add_f32_e32 v3, v3, v8
	v_cndmask_b32_e32 v5, v217, v221, vcc
	v_cmp_eq_u32_e32 vcc, 0, v4
	v_lshlrev_b32_e32 v5, 2, v5
	s_lshl_b32 s0, s11, 7
	v_cndmask_b32_e32 v4, v1, v2, vcc
	v_cndmask_b32_e32 v6, v0, v3, vcc
	ds_bpermute_b32 v4, v5, v4
	ds_bpermute_b32 v5, v5, v6
	v_cndmask_b32_e32 v1, v2, v1, vcc
	v_cndmask_b32_e32 v0, v3, v0, vcc
	v_and_b32_e32 v2, 2, v65
	v_cmp_lt_i32_e32 vcc, v220, v218
	s_waitcnt lgkmcnt(1)
	v_add_f32_e32 v1, v1, v4
	s_waitcnt lgkmcnt(0)
	v_add_f32_e32 v0, v0, v5
	v_cndmask_b32_e32 v3, v217, v220, vcc
	v_cmp_eq_u32_e32 vcc, 0, v2
	v_lshlrev_b32_e32 v3, 2, v3
	s_add_i32 s12, s0, 0
	v_cndmask_b32_e32 v2, v1, v0, vcc
	ds_bpermute_b32 v2, v3, v2
	v_cndmask_b32_e32 v0, v0, v1, vcc
	v_cmp_lt_i32_e32 vcc, v219, v218
	s_add_i32 s12, s12, 0x22400
	s_waitcnt lgkmcnt(0)
	v_add_f32_e32 v0, v0, v2
	v_cndmask_b32_e32 v1, v217, v219, vcc
	v_lshlrev_b32_e32 v1, 2, v1
	ds_bpermute_b32 v1, v1, v0
	v_and_b32_e32 v2, 1, v65
	v_cmp_eq_u32_e32 vcc, 0, v2
	s_and_saveexec_b64 s[0:1], vcc
	s_cbranch_execz .LBB0_112
	s_waitcnt lgkmcnt(0)
	v_add_f32_e32 v0, v0, v1
	v_lshl_add_u32 v1, v178, 1, s12
	ds_write_b32 v1, v0

.LBB0_116:
	global_load_dwordx4 v[36:39], v[32:33], off
	ds_read_b128 v[40:43], v35
	s_add_i32 s9, s9, -1
	v_lshl_add_u64 v[32:33], v[32:33], 0, 64
	s_cmp_lg_u32 s9, 0
	s_waitcnt vmcnt(0) lgkmcnt(0)
	v_mfma_f32_16x16x32_bf16 v[24:27], v[36:39], v[40:43], v[24:27]
	ds_read_b128 v[40:43], v35 offset:4352
	s_waitcnt lgkmcnt(0)
	v_mfma_f32_16x16x32_bf16 v[28:31], v[36:39], v[40:43], v[28:31]
	ds_read_b128 v[40:43], v35 offset:8704
	s_waitcnt lgkmcnt(0)
	v_mfma_f32_16x16x32_bf16 v[20:23], v[36:39], v[40:43], v[20:23]
	ds_read_b128 v[40:43], v35 offset:13056
	s_waitcnt lgkmcnt(0)
	v_mfma_f32_16x16x32_bf16 v[16:19], v[36:39], v[40:43], v[16:19]
	ds_read_b128 v[40:43], v35 offset:17408
	s_waitcnt lgkmcnt(0)
	v_mfma_f32_16x16x32_bf16 v[12:15], v[36:39], v[40:43], v[12:15]
	ds_read_b128 v[40:43], v35 offset:21760
	s_waitcnt lgkmcnt(0)
	v_mfma_f32_16x16x32_bf16 v[8:11], v[36:39], v[40:43], v[8:11]
	ds_read_b128 v[40:43], v35 offset:26112
	s_waitcnt lgkmcnt(0)
	v_mfma_f32_16x16x32_bf16 v[4:7], v[36:39], v[40:43], v[4:7]
	ds_read_b128 v[40:43], v35 offset:30464
	v_add_u32_e32 v35, 64, v35
	s_waitcnt lgkmcnt(0)
	v_mfma_f32_16x16x32_bf16 v[0:3], v[36:39], v[40:43], v[0:3]
	s_cbranch_scc1 .LBB0_116
	s_branch .LBB0_109

.LBB0_121:
	v_readlane_b32 s0, v253, 43
	v_readlane_b32 s1, v253, 44
	s_or_b32 s0, s0, s12
	s_lshl_b64 s[0:1], s[0:1], 9
	v_readlane_b32 s16, v252, 40
	v_readlane_b32 s17, v252, 41
	s_add_u32 s0, s16, s0
	v_lshl_or_b32 v36, v183, 2, s10
	s_addc_u32 s1, s17, s1
	v_ashrrev_i32_e32 v37, 31, v36
	v_lshl_add_u64 v[32:33], v[36:37], 2, s[0:1]
	v_lshlrev_b32_e32 v38, 2, v34
	global_load_dwordx4 v[32:35], v[32:33], off
	v_mul_lo_u32 v36, v36, s66
	v_add3_u32 v36, 0, v38, v36
	v_add_u32_e32 v37, 0x9000, v36
	s_lshl_b32 s82, s12, 8
	v_lshlrev_b32_e32 v192, 1, v182
	s_mov_b64 s[0:1], s[42:43]
	v_readlane_b32 s18, v252, 42
	v_readlane_b32 s19, v252, 43
	v_readlane_b32 s20, v252, 44
	v_readlane_b32 s21, v252, 45
	v_readlane_b32 s22, v252, 46
	v_readlane_b32 s23, v252, 47
	v_readlane_b32 s24, v252, 48
	v_readlane_b32 s25, v252, 49
	v_readlane_b32 s26, v252, 50
	v_readlane_b32 s27, v252, 51
	v_readlane_b32 s28, v252, 52
	v_readlane_b32 s29, v252, 53
	v_readlane_b32 s30, v252, 54
	v_readlane_b32 s31, v252, 55
	s_waitcnt vmcnt(0)
	v_add_f32_e32 v4, v4, v32
	v_add_f32_e32 v0, v0, v32
	ds_write2_b32 v37, v4, v0 offset0:96 offset1:112
	v_add_f32_e32 v0, v25, v33
	v_add_f32_e32 v4, v29, v33
	ds_write2_b32 v37, v0, v4 offset0:132 offset1:148
	v_add_f32_e32 v0, v21, v33
	v_add_f32_e32 v4, v17, v33
	ds_write2_b32 v37, v0, v4 offset0:164 offset1:180
	v_add_f32_e32 v0, v13, v33
	v_add_f32_e32 v4, v9, v33
	ds_write2_b32 v37, v0, v4 offset0:196 offset1:212
	v_add_f32_e32 v0, v5, v33
	v_add_f32_e32 v1, v1, v33
	ds_write2_b32 v37, v0, v1 offset0:228 offset1:244
	v_add_f32_e32 v0, v26, v34
	v_add_f32_e32 v1, v30, v34
	v_add_u32_e32 v4, 0x9400, v36
	ds_write2_b32 v4, v0, v1 offset0:8 offset1:24
	v_add_f32_e32 v0, v22, v34
	v_add_f32_e32 v1, v18, v34
	ds_write2_b32 v4, v0, v1 offset0:40 offset1:56
	v_add_f32_e32 v0, v14, v34
	v_add_f32_e32 v1, v10, v34
	ds_write2_b32 v4, v0, v1 offset0:72 offset1:88
	v_add_f32_e32 v0, v6, v34
	v_add_f32_e32 v1, v2, v34
	ds_write2_b32 v4, v0, v1 offset0:104 offset1:120
	v_add_f32_e32 v0, v27, v35
	v_add_f32_e32 v1, v31, v35
	ds_write2_b32 v4, v0, v1 offset0:140 offset1:156
	v_add_f32_e32 v0, v23, v35
	v_add_f32_e32 v1, v19, v35
	ds_write2_b32 v4, v0, v1 offset0:172 offset1:188
	v_add_f32_e32 v0, v15, v35
	v_add_f32_e32 v1, v11, v35
	ds_write2_b32 v4, v0, v1 offset0:204 offset1:220
	v_add_f32_e32 v0, v7, v35
	v_add_f32_e32 v1, v3, v35
	v_ashrrev_i32_e32 v9, 4, v65
	ds_write2_b32 v4, v0, v1 offset0:236 offset1:252
	v_add_u32_e32 v10, s9, v9
	v_mov_b64_e32 v[0:1], s[4:5]
	v_mad_i64_i32 v[2:3], s[4:5], v10, s76, v[0:1]
	v_lshl_add_u64 v[2:3], v[2:3], 0, s[82:83]
	v_add_f32_e32 v24, v24, v32
	v_add_f32_e32 v28, v28, v32
	v_add_f32_e32 v20, v20, v32
	v_add_f32_e32 v16, v16, v32
	v_add_f32_e32 v12, v12, v32
	v_add_f32_e32 v8, v8, v32
	v_lshl_add_u64 v[2:3], v[2:3], 0, v[192:193]
	ds_write2_b32 v37, v24, v28 offset1:16
	ds_write2_b32 v37, v20, v16 offset0:32 offset1:48
	ds_write2_b32 v37, v12, v8 offset0:64 offset1:80
	s_waitcnt lgkmcnt(0)
	s_barrier
	global_load_dwordx4 v[18:21], v[2:3], off offset:3072
	v_add_u32_e32 v2, 0x200, v65
	v_ashrrev_i32_e32 v38, 4, v2
	v_add_u32_e32 v34, s9, v38
	v_mad_i64_i32 v[2:3], s[4:5], v34, s76, v[0:1]
	v_lshl_add_u64 v[2:3], v[2:3], 0, s[82:83]
	v_lshl_add_u64 v[2:3], v[2:3], 0, v[192:193]
	global_load_dwordx4 v[22:25], v[2:3], off offset:3072
	v_add_u32_e32 v2, 0x400, v65
	v_ashrrev_i32_e32 v39, 4, v2
	v_add_u32_e32 v16, s9, v39
	v_mad_i64_i32 v[2:3], s[4:5], v16, s76, v[0:1]
	v_lshl_add_u64 v[2:3], v[2:3], 0, s[82:83]
	v_lshl_add_u64 v[2:3], v[2:3], 0, v[192:193]
	global_load_dwordx4 v[4:7], v[2:3], off offset:3072
	v_add_u32_e32 v2, 0x600, v65
	v_ashrrev_i32_e32 v40, 4, v2
	v_add_u32_e32 v12, s9, v40
	v_mad_i64_i32 v[0:1], s[4:5], v12, s76, v[0:1]
	v_lshl_add_u64 v[0:1], v[0:1], 0, s[82:83]
	v_lshl_add_u64 v[0:1], v[0:1], 0, v[192:193]
	global_load_dwordx4 v[0:3], v[0:1], off offset:3072
	s_add_u32 s0, s0, s82
	s_addc_u32 s1, s1, 0
	v_lshl_add_u32 v8, v182, 2, 0
	v_lshl_add_u64 v[14:15], s[0:1], 0, v[192:193]
	s_mov_b64 s[0:1], 0x14000800
	v_lshl_add_u64 v[14:15], v[14:15], 0, s[0:1]
	v_mad_u64_u32 v[30:31], s[0:1], v9, s66, v[8:9]
	ds_read_b128 v[26:29], v30 offset:36864
	ds_read_b128 v[30:33], v30 offset:36880
	v_ashrrev_i32_e32 v11, 31, v10
	v_lshlrev_b64 v[10:11], 12, v[10:11]
	v_lshl_add_u64 v[10:11], v[14:15], 0, v[10:11]
	v_ashrrev_i32_e32 v35, 31, v34
	v_ashrrev_i32_e32 v17, 31, v16
	s_add_i32 s8, s8, 1
	v_ashrrev_i32_e32 v13, 31, v12
	s_add_u32 s2, s2, 0x8000
	s_addc_u32 s3, s3, 0
	s_cmp_eq_u32 s8, 3
	s_waitcnt vmcnt(0) lgkmcnt(0)
	v_lshlrev_b32_e32 v36, 16, v18
	v_and_b32_e32 v37, 0xffff0000, v18
	v_pk_mul_f32 v[26:27], v[26:27], v[36:37]
	s_nop 0
	v_cvt_pk_bf16_f32 v18, v26, v27
	v_lshlrev_b32_e32 v26, 16, v19
	v_and_b32_e32 v27, 0xffff0000, v19
	v_pk_mul_f32 v[26:27], v[28:29], v[26:27]
	s_nop 0
	v_cvt_pk_bf16_f32 v19, v26, v27
	v_lshlrev_b32_e32 v26, 16, v20
	v_and_b32_e32 v27, 0xffff0000, v20
	v_pk_mul_f32 v[26:27], v[30:31], v[26:27]
	s_nop 0
	v_cvt_pk_bf16_f32 v20, v26, v27
	v_lshlrev_b32_e32 v26, 16, v21
	v_and_b32_e32 v27, 0xffff0000, v21
	v_pk_mul_f32 v[26:27], v[32:33], v[26:27]
	s_nop 0
	v_cvt_pk_bf16_f32 v21, v26, v27
	global_store_dwordx4 v[10:11], v[18:21], off
	v_mad_u64_u32 v[10:11], s[0:1], v38, s66, v[8:9]
	ds_read_b128 v[18:21], v10 offset:36864
	ds_read_b128 v[26:29], v10 offset:36880
	v_lshlrev_b32_e32 v10, 16, v22
	v_and_b32_e32 v11, 0xffff0000, v22
	s_waitcnt lgkmcnt(0)
	v_pk_mul_f32 v[10:11], v[18:19], v[10:11]
	s_nop 0
	v_cvt_pk_bf16_f32 v18, v10, v11
	v_lshlrev_b32_e32 v10, 16, v23
	v_and_b32_e32 v11, 0xffff0000, v23
	v_pk_mul_f32 v[10:11], v[20:21], v[10:11]
	s_nop 0
	v_cvt_pk_bf16_f32 v19, v10, v11
	v_lshlrev_b32_e32 v10, 16, v24
	v_and_b32_e32 v11, 0xffff0000, v24
	v_pk_mul_f32 v[10:11], v[26:27], v[10:11]
	s_nop 0
	v_cvt_pk_bf16_f32 v20, v10, v11
	v_lshlrev_b32_e32 v10, 16, v25
	v_and_b32_e32 v11, 0xffff0000, v25
	v_pk_mul_f32 v[10:11], v[28:29], v[10:11]
	s_nop 0
	v_cvt_pk_bf16_f32 v21, v10, v11
	v_lshlrev_b64 v[10:11], 12, v[34:35]
	v_lshl_add_u64 v[10:11], v[14:15], 0, v[10:11]
	global_store_dwordx4 v[10:11], v[18:21], off
	v_mad_u64_u32 v[10:11], s[0:1], v39, s66, v[8:9]
	ds_read_b128 v[18:21], v10 offset:36864
	ds_read_b128 v[22:25], v10 offset:36880
	v_lshlrev_b32_e32 v10, 16, v4
	v_and_b32_e32 v11, 0xffff0000, v4
	s_waitcnt lgkmcnt(0)
	v_pk_mul_f32 v[10:11], v[18:19], v[10:11]
	s_nop 0
	v_cvt_pk_bf16_f32 v4, v10, v11
	v_lshlrev_b32_e32 v10, 16, v5
	v_and_b32_e32 v11, 0xffff0000, v5
	v_pk_mul_f32 v[10:11], v[20:21], v[10:11]
	s_nop 0
	v_cvt_pk_bf16_f32 v5, v10, v11
	v_lshlrev_b32_e32 v10, 16, v6
	v_and_b32_e32 v11, 0xffff0000, v6
	v_pk_mul_f32 v[10:11], v[22:23], v[10:11]
	s_nop 0
	v_cvt_pk_bf16_f32 v6, v10, v11
	v_lshlrev_b32_e32 v10, 16, v7
	v_and_b32_e32 v11, 0xffff0000, v7
	v_pk_mul_f32 v[10:11], v[24:25], v[10:11]
	s_nop 0
	v_cvt_pk_bf16_f32 v7, v10, v11
	v_lshlrev_b64 v[10:11], 12, v[16:17]
	v_lshl_add_u64 v[10:11], v[14:15], 0, v[10:11]
	global_store_dwordx4 v[10:11], v[4:7], off
	v_lshlrev_b32_e32 v16, 16, v0
	v_and_b32_e32 v17, 0xffff0000, v0
	v_mad_u64_u32 v[4:5], s[0:1], v40, s66, v[8:9]
	ds_read_b128 v[8:11], v4 offset:36864
	ds_read_b128 v[4:7], v4 offset:36880
	s_waitcnt lgkmcnt(0)
	v_pk_mul_f32 v[8:9], v[8:9], v[16:17]
	s_nop 0
	v_cvt_pk_bf16_f32 v0, v8, v9
	v_lshlrev_b32_e32 v8, 16, v1
	v_and_b32_e32 v9, 0xffff0000, v1
	v_pk_mul_f32 v[8:9], v[10:11], v[8:9]
	s_nop 0
	v_cvt_pk_bf16_f32 v1, v8, v9
	v_lshlrev_b32_e32 v8, 16, v2
	v_and_b32_e32 v9, 0xffff0000, v2
	v_pk_mul_f32 v[4:5], v[4:5], v[8:9]
	s_nop 0
	v_cvt_pk_bf16_f32 v2, v4, v5
	v_lshlrev_b32_e32 v4, 16, v3
	v_and_b32_e32 v5, 0xffff0000, v3
	v_pk_mul_f32 v[4:5], v[6:7], v[4:5]
	s_nop 0
	v_cvt_pk_bf16_f32 v3, v4, v5
	v_lshlrev_b64 v[4:5], 12, v[12:13]
	v_lshl_add_u64 v[4:5], v[14:15], 0, v[4:5]
	global_store_dwordx4 v[4:5], v[0:3], off
	s_waitcnt lgkmcnt(0)
	s_barrier
	s_cbranch_scc1 .LBB0_129
.LBB0_122:
	s_add_i32 s12, s7, s8
	v_mov_b32_e32 v65, v214
	s_lshl_b32 s0, s12, 5
	v_readfirstlane_b32 s11, v65
	s_ashr_i32 s13, s11, 6
	s_and_b32 s9, s0, 0xffffff80
	s_mov_b64 s[0:1], s[42:43]
	s_add_u32 s4, s0, 0x18400000
	s_addc_u32 s5, s1, 0
	s_lshl_b32 s10, s13, 4
	s_add_i32 s0, s10, s9
	s_mul_i32 s14, s0, 0x3800
	v_and_b32_e32 v178, 63, v65
	s_mul_hi_i32 s1, s0, 0x3800
	s_add_u32 s14, s4, s14
	s_addc_u32 s15, s5, s1
	v_lshlrev_b32_e32 v192, 4, v178
	s_or_b32 s1, s0, 1
	s_waitcnt vmcnt(0)
	v_lshl_add_u64 v[0:1], s[14:15], 0, v[192:193]
	s_mul_hi_i32 s15, s1, 0x3800
	s_mulk_i32 s1, 0x3800
	s_add_u32 s14, s4, s1
	s_addc_u32 s15, s5, s15
	s_or_b32 s1, s0, 2
	v_add_co_u32_e32 v0, vcc, s65, v0
	v_lshl_add_u64 v[2:3], s[14:15], 0, v[192:193]
	s_mul_hi_i32 s15, s1, 0x3800
	s_mulk_i32 s1, 0x3800
	v_addc_co_u32_e32 v1, vcc, 0, v1, vcc
	s_add_u32 s14, s4, s1
	v_add_co_u32_e32 v2, vcc, s65, v2
	s_addc_u32 s15, s5, s15
	s_or_b32 s1, s0, 3
	v_addc_co_u32_e32 v3, vcc, 0, v3, vcc
	global_load_dwordx4 v[48:51], v[0:1], off
	global_load_dwordx4 v[52:55], v[2:3], off
	v_lshl_add_u64 v[0:1], s[14:15], 0, v[192:193]
	s_mul_hi_i32 s15, s1, 0x3800
	s_mulk_i32 s1, 0x3800
	s_add_u32 s14, s4, s1
	s_addc_u32 s15, s5, s15
	s_or_b32 s1, s0, 4
	v_add_co_u32_e32 v0, vcc, s65, v0
	v_lshl_add_u64 v[2:3], s[14:15], 0, v[192:193]
	s_mul_hi_i32 s15, s1, 0x3800
	s_mulk_i32 s1, 0x3800
	v_addc_co_u32_e32 v1, vcc, 0, v1, vcc
	s_add_u32 s14, s4, s1
	v_add_co_u32_e32 v2, vcc, s65, v2
	s_addc_u32 s15, s5, s15
	s_or_b32 s1, s0, 5
	v_addc_co_u32_e32 v3, vcc, 0, v3, vcc
	global_load_dwordx4 v[56:59], v[0:1], off
	global_load_dwordx4 v[60:63], v[2:3], off
	v_lshl_add_u64 v[0:1], s[14:15], 0, v[192:193]
	s_mul_hi_i32 s15, s1, 0x3800
	s_mulk_i32 s1, 0x3800
	s_add_u32 s14, s4, s1
	s_addc_u32 s15, s5, s15
	s_or_b32 s1, s0, 6
	v_add_co_u32_e32 v0, vcc, s65, v0
	v_lshl_add_u64 v[2:3], s[14:15], 0, v[192:193]
	s_mul_hi_i32 s15, s1, 0x3800
	s_mulk_i32 s1, 0x3800
	v_addc_co_u32_e32 v1, vcc, 0, v1, vcc
	s_add_u32 s14, s4, s1
	v_add_co_u32_e32 v2, vcc, s65, v2
	s_addc_u32 s15, s5, s15
	s_or_b32 s1, s0, 7
	v_addc_co_u32_e32 v3, vcc, 0, v3, vcc
	global_load_dwordx4 v[32:35], v[0:1], off
	global_load_dwordx4 v[36:39], v[2:3], off
	v_lshl_add_u64 v[0:1], s[14:15], 0, v[192:193]
	s_mul_hi_i32 s15, s1, 0x3800
	s_mulk_i32 s1, 0x3800
	s_add_u32 s14, s4, s1
	s_addc_u32 s15, s5, s15
	s_or_b32 s1, s0, 8
	v_add_co_u32_e32 v0, vcc, s65, v0
	v_lshl_add_u64 v[2:3], s[14:15], 0, v[192:193]
	s_mul_hi_i32 s15, s1, 0x3800
	s_mulk_i32 s1, 0x3800
	v_addc_co_u32_e32 v1, vcc, 0, v1, vcc
	s_add_u32 s14, s4, s1
	v_add_co_u32_e32 v2, vcc, s65, v2
	s_addc_u32 s15, s5, s15
	s_or_b32 s1, s0, 9
	v_addc_co_u32_e32 v3, vcc, 0, v3, vcc
	global_load_dwordx4 v[40:43], v[0:1], off
	global_load_dwordx4 v[44:47], v[2:3], off
	v_lshl_add_u64 v[0:1], s[14:15], 0, v[192:193]
	s_mul_hi_i32 s15, s1, 0x3800
	s_mulk_i32 s1, 0x3800
	s_add_u32 s14, s4, s1
	s_addc_u32 s15, s5, s15
	s_or_b32 s1, s0, 10
	v_add_co_u32_e32 v0, vcc, s65, v0
	v_lshl_add_u64 v[2:3], s[14:15], 0, v[192:193]
	s_mul_hi_i32 s15, s1, 0x3800
	s_mulk_i32 s1, 0x3800
	v_addc_co_u32_e32 v1, vcc, 0, v1, vcc
	s_add_u32 s14, s4, s1
	v_add_co_u32_e32 v2, vcc, s65, v2
	s_addc_u32 s15, s5, s15
	s_or_b32 s1, s0, 11
	v_addc_co_u32_e32 v3, vcc, 0, v3, vcc
	global_load_dwordx4 v[16:19], v[0:1], off
	global_load_dwordx4 v[20:23], v[2:3], off
	v_lshl_add_u64 v[0:1], s[14:15], 0, v[192:193]
	s_mul_hi_i32 s15, s1, 0x3800
	s_mulk_i32 s1, 0x3800
	s_add_u32 s14, s4, s1
	s_addc_u32 s15, s5, s15
	s_or_b32 s1, s0, 12
	v_add_co_u32_e32 v0, vcc, s65, v0
	v_lshl_add_u64 v[2:3], s[14:15], 0, v[192:193]
	s_mul_hi_i32 s15, s1, 0x3800
	s_mulk_i32 s1, 0x3800
	v_addc_co_u32_e32 v1, vcc, 0, v1, vcc
	s_add_u32 s14, s4, s1
	v_add_co_u32_e32 v2, vcc, s65, v2
	s_addc_u32 s15, s5, s15
	s_or_b32 s1, s0, 13
	v_addc_co_u32_e32 v3, vcc, 0, v3, vcc
	global_load_dwordx4 v[24:27], v[0:1], off
	global_load_dwordx4 v[28:31], v[2:3], off
	v_lshl_add_u64 v[0:1], s[14:15], 0, v[192:193]
	s_mul_hi_i32 s15, s1, 0x3800
	s_mulk_i32 s1, 0x3800
	s_add_u32 s14, s4, s1
	s_addc_u32 s15, s5, s15
	s_or_b32 s1, s0, 14
	v_lshl_add_u64 v[2:3], s[14:15], 0, v[192:193]
	s_mul_hi_i32 s15, s1, 0x3800
	s_mulk_i32 s1, 0x3800
	v_add_co_u32_e32 v0, vcc, s65, v0
	s_add_u32 s14, s4, s1
	s_nop 0
	v_addc_co_u32_e32 v1, vcc, 0, v1, vcc
	s_addc_u32 s15, s5, s15
	s_or_b32 s0, s0, 15
	v_add_co_u32_e32 v4, vcc, s65, v2
	s_mul_hi_i32 s1, s0, 0x3800
	s_mulk_i32 s0, 0x3800
	v_addc_co_u32_e32 v5, vcc, 0, v3, vcc
	v_lshl_add_u64 v[8:9], s[14:15], 0, v[192:193]
	s_add_u32 s0, s4, s0
	v_add_co_u32_e32 v8, vcc, s65, v8
	s_addc_u32 s1, s5, s1
	s_nop 0
	v_addc_co_u32_e32 v9, vcc, 0, v9, vcc
	v_lshl_add_u64 v[10:11], s[0:1], 0, v[192:193]
	v_add_co_u32_e32 v12, vcc, s65, v10
	global_load_dwordx4 v[0:3], v[0:1], off
	s_nop 0
	global_load_dwordx4 v[4:7], v[4:5], off
	v_addc_co_u32_e32 v13, vcc, 0, v11, vcc
	global_load_dwordx4 v[8:11], v[8:9], off
	s_nop 0
	global_load_dwordx4 v[12:15], v[12:13], off
	s_waitcnt vmcnt(0) lgkmcnt(0)
	v_lshlrev_b32_e32 v174, 16, v48
	v_lshlrev_b32_e32 v176, 16, v56
	v_lshlrev_b32_e32 v175, 16, v52
	v_add_f32_e32 v66, 0, v174
	v_add_f32_e32 v67, 0, v175
	v_add_f32_e32 v68, 0, v176
	v_and_b32_e32 v170, 0xffff0000, v48
	v_and_b32_e32 v172, 0xffff0000, v56
	v_and_b32_e32 v171, 0xffff0000, v52
	v_add_f32_e32 v48, v66, v170
	v_add_f32_e32 v52, v67, v171
	v_add_f32_e32 v56, v68, v172
	v_lshlrev_b32_e32 v166, 16, v49
	v_lshlrev_b32_e32 v168, 16, v57
	v_lshlrev_b32_e32 v167, 16, v53
	v_add_f32_e32 v48, v48, v166
	v_add_f32_e32 v52, v52, v167
	v_add_f32_e32 v56, v56, v168
	v_and_b32_e32 v162, 0xffff0000, v49
	v_and_b32_e32 v164, 0xffff0000, v57
	v_and_b32_e32 v163, 0xffff0000, v53
	v_add_f32_e32 v48, v48, v162
	v_add_f32_e32 v49, v52, v163
	v_add_f32_e32 v52, v56, v164
	v_lshlrev_b32_e32 v158, 16, v50
	v_lshlrev_b32_e32 v160, 16, v58
	v_lshlrev_b32_e32 v159, 16, v54
	v_add_f32_e32 v48, v48, v158
	v_add_f32_e32 v49, v49, v159
	v_add_f32_e32 v52, v52, v160
	v_and_b32_e32 v154, 0xffff0000, v50
	v_and_b32_e32 v156, 0xffff0000, v58
	v_and_b32_e32 v155, 0xffff0000, v54
	v_add_f32_e32 v48, v48, v154
	v_add_f32_e32 v49, v49, v155
	v_add_f32_e32 v50, v52, v156
	v_lshlrev_b32_e32 v146, 16, v51
	v_lshlrev_b32_e32 v148, 16, v59
	v_lshlrev_b32_e32 v147, 16, v55
	v_add_f32_e32 v48, v48, v146
	v_add_f32_e32 v49, v49, v147
	v_add_f32_e32 v50, v50, v148
	v_and_b32_e32 v150, 0xffff0000, v51
	v_and_b32_e32 v152, 0xffff0000, v59
	v_and_b32_e32 v151, 0xffff0000, v55
	v_lshlrev_b32_e32 v145, 16, v44
	v_lshlrev_b32_e32 v144, 16, v40
	v_lshlrev_b32_e32 v143, 16, v36
	v_lshlrev_b32_e32 v142, 16, v32
	v_add_f32_e32 v183, v48, v150
	v_add_f32_e32 v184, v49, v151
	v_add_f32_e32 v185, v50, v152
	v_add_f32_e32 v48, 0, v142
	v_add_f32_e32 v49, 0, v143
	v_add_f32_e32 v50, 0, v144
	v_add_f32_e32 v51, 0, v145
	v_and_b32_e32 v123, 0xffff0000, v44
	v_and_b32_e32 v122, 0xffff0000, v40
	v_and_b32_e32 v131, 0xffff0000, v36
	v_and_b32_e32 v130, 0xffff0000, v32
	v_add_f32_e32 v44, v48, v130
	v_add_f32_e32 v48, v49, v131
	v_add_f32_e32 v49, v50, v122
	v_add_f32_e32 v50, v51, v123
	v_lshlrev_b32_e32 v137, 16, v45
	v_lshlrev_b32_e32 v136, 16, v41
	v_lshlrev_b32_e32 v141, 16, v37
	v_lshlrev_b32_e32 v140, 16, v33
	v_add_f32_e32 v44, v44, v140
	v_add_f32_e32 v48, v48, v141
	v_add_f32_e32 v49, v49, v136
	v_add_f32_e32 v50, v50, v137
	v_and_b32_e32 v133, 0xffff0000, v45
	v_and_b32_e32 v132, 0xffff0000, v41
	v_and_b32_e32 v139, 0xffff0000, v37
	v_and_b32_e32 v138, 0xffff0000, v33
	v_add_f32_e32 v33, v44, v138
	v_add_f32_e32 v37, v48, v139
	v_add_f32_e32 v41, v49, v132
	v_add_f32_e32 v44, v50, v133
	v_lshlrev_b32_e32 v127, 16, v46
	v_lshlrev_b32_e32 v126, 16, v42
	v_lshlrev_b32_e32 v135, 16, v38
	v_add_f32_e32 v37, v37, v135
	v_add_f32_e32 v41, v41, v126
	v_add_f32_e32 v44, v44, v127
	v_and_b32_e32 v121, 0xffff0000, v46
	v_and_b32_e32 v120, 0xffff0000, v42
	v_and_b32_e32 v129, 0xffff0000, v38
	v_lshlrev_b32_e32 v134, 16, v34
	v_and_b32_e32 v128, 0xffff0000, v34
	v_add_f32_e32 v34, v37, v129
	v_add_f32_e32 v37, v41, v120
	v_add_f32_e32 v38, v44, v121
	v_lshlrev_b32_e32 v117, 16, v47
	v_lshlrev_b32_e32 v116, 16, v43
	v_add_f32_e32 v37, v37, v116
	v_add_f32_e32 v38, v38, v117
	v_and_b32_e32 v115, 0xffff0000, v47
	v_and_b32_e32 v114, 0xffff0000, v43
	v_lshlrev_b32_e32 v87, 16, v28
	v_lshlrev_b32_e32 v86, 16, v24
	v_lshlrev_b32_e32 v83, 16, v20
	v_lshlrev_b32_e32 v82, 16, v16
	v_lshlrev_b32_e32 v125, 16, v39
	v_lshlrev_b32_e32 v124, 16, v35
	v_and_b32_e32 v119, 0xffff0000, v39
	v_and_b32_e32 v118, 0xffff0000, v35
	v_add_f32_e32 v35, v37, v114
	v_add_f32_e32 v37, v38, v115
	v_add_f32_e32 v38, 0, v82
	v_add_f32_e32 v39, 0, v83
	v_add_f32_e32 v41, 0, v86
	v_add_f32_e32 v42, 0, v87
	v_and_b32_e32 v79, 0xffff0000, v28
	v_and_b32_e32 v78, 0xffff0000, v24
	v_and_b32_e32 v81, 0xffff0000, v20
	v_and_b32_e32 v80, 0xffff0000, v16
	v_add_f32_e32 v28, v38, v80
	v_add_f32_e32 v38, v39, v81
	v_add_f32_e32 v39, v41, v78
	v_add_f32_e32 v41, v42, v79
	v_lshlrev_b32_e32 v91, 16, v29
	v_lshlrev_b32_e32 v90, 16, v25
	v_lshlrev_b32_e32 v93, 16, v21
	v_lshlrev_b32_e32 v92, 16, v17
	v_add_f32_e32 v28, v28, v92
	v_add_f32_e32 v38, v38, v93
	v_add_f32_e32 v39, v39, v90
	v_add_f32_e32 v41, v41, v91
	v_and_b32_e32 v95, 0xffff0000, v29
	v_and_b32_e32 v94, 0xffff0000, v25
	v_and_b32_e32 v97, 0xffff0000, v21
	v_and_b32_e32 v96, 0xffff0000, v17
	v_add_f32_e32 v17, v28, v96
	v_add_f32_e32 v21, v38, v97
	v_add_f32_e32 v25, v39, v94
	v_add_f32_e32 v28, v41, v95
	v_lshlrev_b32_e32 v99, 16, v30
	v_lshlrev_b32_e32 v98, 16, v26
	v_lshlrev_b32_e32 v101, 16, v22
	v_lshlrev_b32_e32 v177, 16, v60
	v_add_f32_e32 v21, v21, v101
	v_add_f32_e32 v25, v25, v98
	v_add_f32_e32 v28, v28, v99
	v_and_b32_e32 v103, 0xffff0000, v30
	v_and_b32_e32 v102, 0xffff0000, v26
	v_and_b32_e32 v105, 0xffff0000, v22
	v_add_f32_e32 v69, 0, v177
	v_and_b32_e32 v173, 0xffff0000, v60
	v_lshlrev_b32_e32 v100, 16, v18
	v_and_b32_e32 v104, 0xffff0000, v18
	v_add_f32_e32 v18, v21, v105
	v_add_f32_e32 v21, v25, v102
	v_add_f32_e32 v22, v28, v103
	v_lshlrev_b32_e32 v107, 16, v31
	v_lshlrev_b32_e32 v106, 16, v27
	v_add_f32_e32 v60, v69, v173
	v_lshlrev_b32_e32 v169, 16, v61
	v_add_f32_e32 v21, v21, v106
	v_add_f32_e32 v22, v22, v107
	v_and_b32_e32 v111, 0xffff0000, v31
	v_and_b32_e32 v110, 0xffff0000, v27
	v_lshlrev_b32_e32 v88, 16, v8
	v_lshlrev_b32_e32 v85, 16, v4
	v_lshlrev_b32_e32 v84, 16, v0
	v_add_f32_e32 v60, v60, v169
	v_and_b32_e32 v165, 0xffff0000, v61
	v_lshlrev_b32_e32 v109, 16, v23
	v_lshlrev_b32_e32 v108, 16, v19
	v_and_b32_e32 v113, 0xffff0000, v23
	v_and_b32_e32 v112, 0xffff0000, v19
	v_add_f32_e32 v19, v21, v110
	v_add_f32_e32 v21, v22, v111
	v_add_f32_e32 v22, 0, v84
	v_add_f32_e32 v23, 0, v85
	v_add_f32_e32 v25, 0, v88
	v_and_b32_e32 v56, 0xffff0000, v8
	v_and_b32_e32 v67, 0xffff0000, v4
	v_and_b32_e32 v66, 0xffff0000, v0
	v_add_f32_e32 v53, v60, v165
	v_lshlrev_b32_e32 v161, 16, v62
	v_lshlrev_b32_e32 v89, 16, v12
	v_and_b32_e32 v57, 0xffff0000, v12
	v_add_f32_e32 v12, v22, v66
	v_add_f32_e32 v22, v23, v67
	v_add_f32_e32 v23, v25, v56
	v_lshlrev_b32_e32 v72, 16, v9
	v_lshlrev_b32_e32 v77, 16, v5
	v_add_f32_e32 v53, v53, v161
	v_and_b32_e32 v157, 0xffff0000, v62
	v_add_f32_e32 v22, v22, v77
	v_add_f32_e32 v23, v23, v72
	v_and_b32_e32 v68, 0xffff0000, v9
	v_and_b32_e32 v75, 0xffff0000, v5
	v_add_f32_e32 v52, v53, v157
	v_lshlrev_b32_e32 v149, 16, v63
	v_add_f32_e32 v5, v22, v75
	v_add_f32_e32 v9, v23, v68
	v_lshlrev_b32_e32 v60, 16, v10
	v_lshlrev_b32_e32 v71, 16, v6
	v_add_f32_e32 v52, v52, v149
	v_and_b32_e32 v153, 0xffff0000, v63
	v_add_f32_e32 v17, v17, v100
	v_add_f32_e32 v5, v5, v71
	v_add_f32_e32 v9, v9, v60
	v_and_b32_e32 v54, 0xffff0000, v10
	v_and_b32_e32 v63, 0xffff0000, v6
	v_add_f32_e32 v186, v52, v153
	v_add_f32_e32 v17, v17, v104
	v_lshlrev_b32_e32 v70, 16, v2
	v_and_b32_e32 v62, 0xffff0000, v2
	v_add_f32_e32 v2, v5, v63
	v_add_f32_e32 v5, v9, v54
	v_lshlrev_b32_e32 v52, 16, v11
	v_mul_f32_e32 v182, v170, v170
	v_mul_f32_e32 v16, v80, v80
	v_add_f32_e32 v17, v17, v108
	v_add_f32_e32 v5, v5, v52
	v_and_b32_e32 v48, 0xffff0000, v11
	v_cmp_lt_i32_e32 vcc, v224, v218
	v_fmac_f32_e32 v182, v174, v174
	v_fmac_f32_e32 v16, v82, v82
	v_add_f32_e32 v17, v17, v112
	v_lshlrev_b32_e32 v58, 16, v3
	v_and_b32_e32 v50, 0xffff0000, v3
	v_add_f32_e32 v3, v5, v48
	v_cndmask_b32_e32 v5, v217, v224, vcc
	v_cmp_gt_u32_e32 vcc, 32, v178
	v_mul_f32_e32 v181, v171, v171
	v_fmac_f32_e32 v182, v166, v166
	v_mul_f32_e32 v20, v81, v81
	v_fmac_f32_e32 v16, v92, v92
	v_lshlrev_b32_e32 v59, 16, v7
	v_and_b32_e32 v51, 0xffff0000, v7
	v_lshlrev_b32_e32 v5, 2, v5
	v_cndmask_b32_e32 v7, v183, v17, vcc
	v_fmac_f32_e32 v181, v175, v175
	v_fmac_f32_e32 v182, v162, v162
	v_fmac_f32_e32 v20, v83, v83
	v_fmac_f32_e32 v16, v96, v96
	ds_bpermute_b32 v7, v5, v7
	v_fmac_f32_e32 v181, v167, v167
	v_fmac_f32_e32 v182, v158, v158
	v_fmac_f32_e32 v20, v93, v93
	v_fmac_f32_e32 v16, v100, v100
	v_fmac_f32_e32 v181, v163, v163
	v_fmac_f32_e32 v182, v154, v154
	v_fmac_f32_e32 v20, v97, v97
	v_fmac_f32_e32 v16, v104, v104
	v_add_f32_e32 v26, 0, v89
	v_fmac_f32_e32 v181, v159, v159
	v_fmac_f32_e32 v182, v146, v146
	v_fmac_f32_e32 v20, v101, v101
	v_fmac_f32_e32 v16, v108, v108
	v_add_f32_e32 v25, v26, v57
	v_lshlrev_b32_e32 v73, 16, v13
	v_lshlrev_b32_e32 v76, 16, v1
	v_fmac_f32_e32 v181, v155, v155
	v_fmac_f32_e32 v182, v150, v150
	v_fmac_f32_e32 v20, v105, v105
	v_add_f32_e32 v18, v18, v109
	v_fmac_f32_e32 v16, v112, v112
	v_add_f32_e32 v12, v12, v76
	v_add_f32_e32 v25, v25, v73
	v_and_b32_e32 v69, 0xffff0000, v13
	v_and_b32_e32 v74, 0xffff0000, v1
	v_cndmask_b32_e32 v9, v17, v183, vcc
	v_fmac_f32_e32 v181, v147, v147
	v_fmac_f32_e32 v20, v109, v109
	v_add_f32_e32 v18, v18, v113
	v_add_f32_e32 v1, v12, v74
	v_add_f32_e32 v12, v25, v69
	v_lshlrev_b32_e32 v61, 16, v14
	s_waitcnt lgkmcnt(0)
	v_add_f32_e32 v7, v9, v7
	v_cndmask_b32_e32 v9, v182, v16, vcc
	v_mul_f32_e32 v179, v172, v172
	v_fmac_f32_e32 v181, v151, v151
	v_mul_f32_e32 v24, v78, v78
	v_fmac_f32_e32 v20, v113, v113
	v_add_f32_e32 v12, v12, v61
	v_and_b32_e32 v55, 0xffff0000, v14
	ds_bpermute_b32 v9, v5, v9
	v_cndmask_b32_e32 v11, v184, v18, vcc
	v_fmac_f32_e32 v179, v176, v176
	v_fmac_f32_e32 v24, v86, v86
	v_add_f32_e32 v6, v12, v55
	ds_bpermute_b32 v11, v5, v11
	v_cndmask_b32_e32 v12, v181, v20, vcc
	v_fmac_f32_e32 v179, v168, v168
	v_fmac_f32_e32 v24, v90, v90
	ds_bpermute_b32 v12, v5, v12
	v_fmac_f32_e32 v179, v164, v164
	v_fmac_f32_e32 v24, v94, v94
	v_fmac_f32_e32 v179, v160, v160
	v_fmac_f32_e32 v24, v98, v98
	v_cndmask_b32_e32 v10, v16, v182, vcc
	v_fmac_f32_e32 v179, v156, v156
	v_fmac_f32_e32 v24, v102, v102
	s_waitcnt lgkmcnt(2)
	v_add_f32_e32 v9, v10, v9
	v_cndmask_b32_e32 v10, v18, v184, vcc
	v_fmac_f32_e32 v179, v148, v148
	v_fmac_f32_e32 v24, v106, v106
	s_waitcnt lgkmcnt(1)
	v_add_f32_e32 v10, v10, v11
	v_cndmask_b32_e32 v11, v20, v181, vcc
	v_mul_f32_e32 v180, v173, v173
	v_fmac_f32_e32 v179, v152, v152
	v_mul_f32_e32 v42, v79, v79
	v_fmac_f32_e32 v24, v110, v110
	s_waitcnt lgkmcnt(0)
	v_add_f32_e32 v11, v11, v12
	v_cndmask_b32_e32 v12, v185, v19, vcc
	v_fmac_f32_e32 v180, v177, v177
	v_mul_f32_e32 v32, v130, v130
	v_fmac_f32_e32 v42, v87, v87
	v_mul_f32_e32 v0, v66, v66
	ds_bpermute_b32 v12, v5, v12
	v_cndmask_b32_e32 v14, v179, v24, vcc
	v_fmac_f32_e32 v180, v169, v169
	v_fmac_f32_e32 v32, v142, v142
	v_fmac_f32_e32 v42, v91, v91
	v_fmac_f32_e32 v0, v84, v84
	v_lshlrev_b32_e32 v53, 16, v15
	v_and_b32_e32 v49, 0xffff0000, v15
	ds_bpermute_b32 v14, v5, v14
	v_cndmask_b32_e32 v15, v186, v21, vcc
	v_fmac_f32_e32 v180, v165, v165
	v_fmac_f32_e32 v32, v140, v140
	v_fmac_f32_e32 v42, v95, v95
	v_fmac_f32_e32 v0, v76, v76
	ds_bpermute_b32 v15, v5, v15
	v_fmac_f32_e32 v180, v161, v161
	v_fmac_f32_e32 v32, v138, v138
	v_fmac_f32_e32 v42, v99, v99
	v_fmac_f32_e32 v0, v74, v74
	v_fmac_f32_e32 v180, v157, v157
	v_add_f32_e32 v33, v33, v134
	v_fmac_f32_e32 v32, v134, v134
	v_fmac_f32_e32 v42, v103, v103
	v_add_f32_e32 v1, v1, v70
	v_fmac_f32_e32 v0, v70, v70
	v_cndmask_b32_e32 v13, v19, v185, vcc
	v_fmac_f32_e32 v180, v149, v149
	v_add_f32_e32 v33, v33, v128
	v_fmac_f32_e32 v32, v128, v128
	v_fmac_f32_e32 v42, v107, v107
	v_add_f32_e32 v1, v1, v62
	v_fmac_f32_e32 v0, v62, v62
	s_waitcnt lgkmcnt(2)
	v_add_f32_e32 v12, v13, v12
	v_cndmask_b32_e32 v13, v24, v179, vcc
	v_fmac_f32_e32 v180, v153, v153
	v_mul_f32_e32 v36, v131, v131
	v_add_f32_e32 v33, v33, v124
	v_fmac_f32_e32 v32, v124, v124
	v_fmac_f32_e32 v42, v111, v111
	v_mul_f32_e32 v4, v67, v67
	v_add_f32_e32 v1, v1, v58
	v_fmac_f32_e32 v0, v58, v58
	s_waitcnt lgkmcnt(1)
	v_add_f32_e32 v13, v13, v14
	v_cndmask_b32_e32 v14, v21, v186, vcc
	v_fmac_f32_e32 v36, v143, v143
	v_add_f32_e32 v33, v33, v118
	v_fmac_f32_e32 v32, v118, v118
	v_fmac_f32_e32 v4, v85, v85
	v_add_f32_e32 v1, v1, v50
	v_fmac_f32_e32 v0, v50, v50
	s_waitcnt lgkmcnt(0)
	v_add_f32_e32 v14, v14, v15
	v_cndmask_b32_e32 v15, v180, v42, vcc
	v_fmac_f32_e32 v36, v141, v141
	v_fmac_f32_e32 v4, v77, v77
	ds_bpermute_b32 v15, v5, v15
	v_cndmask_b32_e32 v17, v33, v1, vcc
	v_cndmask_b32_e32 v18, v32, v0, vcc
	v_fmac_f32_e32 v36, v139, v139
	v_fmac_f32_e32 v4, v75, v75
	ds_bpermute_b32 v17, v5, v17
	ds_bpermute_b32 v18, v5, v18
	v_fmac_f32_e32 v36, v135, v135
	v_fmac_f32_e32 v4, v71, v71
	v_mul_f32_e32 v40, v122, v122
	v_fmac_f32_e32 v36, v129, v129
	v_add_f32_e32 v34, v34, v125
	v_mul_f32_e32 v8, v56, v56
	v_fmac_f32_e32 v4, v63, v63
	v_add_f32_e32 v2, v2, v59
	v_fmac_f32_e32 v40, v144, v144
	v_mul_f32_e32 v187, v123, v123
	v_fmac_f32_e32 v36, v125, v125
	v_add_f32_e32 v34, v34, v119
	v_fmac_f32_e32 v8, v88, v88
	v_mul_f32_e32 v26, v57, v57
	v_fmac_f32_e32 v4, v59, v59
	v_add_f32_e32 v2, v2, v51
	v_cndmask_b32_e32 v16, v42, v180, vcc
	v_fmac_f32_e32 v187, v145, v145
	v_fmac_f32_e32 v40, v136, v136
	v_fmac_f32_e32 v36, v119, v119
	v_fmac_f32_e32 v26, v89, v89
	v_fmac_f32_e32 v8, v72, v72
	v_fmac_f32_e32 v4, v51, v51
	s_waitcnt lgkmcnt(2)
	v_add_f32_e32 v15, v16, v15
	v_cndmask_b32_e32 v1, v1, v33, vcc
	v_cndmask_b32_e32 v0, v0, v32, vcc
	v_cndmask_b32_e32 v16, v34, v2, vcc
	v_fmac_f32_e32 v187, v137, v137
	v_fmac_f32_e32 v40, v132, v132
	v_fmac_f32_e32 v26, v73, v73
	v_fmac_f32_e32 v8, v68, v68
	s_waitcnt lgkmcnt(1)
	v_add_f32_e32 v1, v1, v17
	s_waitcnt lgkmcnt(0)
	v_add_f32_e32 v0, v0, v18
	ds_bpermute_b32 v16, v5, v16
	v_cndmask_b32_e32 v17, v36, v4, vcc
	v_cndmask_b32_e32 v18, v35, v3, vcc
	v_fmac_f32_e32 v187, v133, v133
	v_fmac_f32_e32 v40, v126, v126
	v_fmac_f32_e32 v26, v69, v69
	v_fmac_f32_e32 v8, v60, v60
	ds_bpermute_b32 v17, v5, v17
	ds_bpermute_b32 v18, v5, v18
	v_fmac_f32_e32 v187, v127, v127
	v_fmac_f32_e32 v40, v120, v120
	v_fmac_f32_e32 v26, v61, v61
	v_fmac_f32_e32 v8, v54, v54
	v_fmac_f32_e32 v187, v121, v121
	v_fmac_f32_e32 v40, v116, v116
	v_fmac_f32_e32 v26, v55, v55
	v_fmac_f32_e32 v8, v52, v52
	v_fmac_f32_e32 v187, v117, v117
	v_fmac_f32_e32 v40, v114, v114
	v_add_f32_e32 v6, v6, v53
	v_fmac_f32_e32 v26, v53, v53
	v_fmac_f32_e32 v8, v48, v48
	v_cndmask_b32_e32 v2, v2, v34, vcc
	v_fmac_f32_e32 v187, v115, v115
	v_add_f32_e32 v6, v6, v49
	v_fmac_f32_e32 v26, v49, v49
	s_waitcnt lgkmcnt(2)
	v_add_f32_e32 v2, v2, v16
	v_cndmask_b32_e32 v4, v4, v36, vcc
	v_cndmask_b32_e32 v3, v3, v35, vcc
	v_cndmask_b32_e32 v16, v40, v8, vcc
	s_waitcnt lgkmcnt(1)
	v_add_f32_e32 v4, v4, v17
	s_waitcnt lgkmcnt(0)
	v_add_f32_e32 v3, v3, v18
	ds_bpermute_b32 v16, v5, v16
	v_cndmask_b32_e32 v17, v37, v6, vcc
	v_cndmask_b32_e32 v18, v187, v26, vcc
	ds_bpermute_b32 v17, v5, v17
	ds_bpermute_b32 v5, v5, v18
	v_cndmask_b32_e32 v8, v8, v40, vcc
	s_waitcnt lgkmcnt(2)
	v_add_f32_e32 v8, v8, v16
	v_cndmask_b32_e32 v16, v26, v187, vcc
	v_cndmask_b32_e32 v6, v6, v37, vcc
	s_waitcnt lgkmcnt(0)
	v_add_f32_e32 v5, v16, v5
	v_and_b32_e32 v16, 16, v65
	v_cmp_lt_i32_e32 vcc, v223, v218
	v_add_f32_e32 v6, v6, v17
	v_cmp_lt_i32_e64 s[0:1], v222, v218
	v_cndmask_b32_e32 v17, v217, v223, vcc
	v_cmp_eq_u32_e32 vcc, 0, v16
	v_lshlrev_b32_e32 v17, 2, v17
	s_nop 0
	v_cndmask_b32_e32 v16, v7, v1, vcc
	v_cndmask_b32_e32 v1, v1, v7, vcc
	ds_bpermute_b32 v7, v17, v16
	v_cndmask_b32_e32 v16, v9, v0, vcc
	v_cndmask_b32_e32 v0, v0, v9, vcc
	v_cndmask_b32_e32 v9, v12, v3, vcc
	ds_bpermute_b32 v9, v17, v9
	s_waitcnt lgkmcnt(1)
	v_add_f32_e32 v1, v1, v7
	v_cndmask_b32_e32 v7, v11, v4, vcc
	ds_bpermute_b32 v7, v17, v7
	v_cndmask_b32_e32 v18, v10, v2, vcc
	v_cndmask_b32_e32 v2, v2, v10, vcc
	v_cndmask_b32_e32 v10, v13, v8, vcc
	v_cndmask_b32_e32 v4, v4, v11, vcc
	ds_bpermute_b32 v10, v17, v10
	v_cndmask_b32_e32 v3, v3, v12, vcc
	ds_bpermute_b32 v16, v17, v16
	s_waitcnt lgkmcnt(2)
	v_add_f32_e32 v4, v4, v7
	v_add_f32_e32 v3, v3, v9
	v_cndmask_b32_e32 v7, v8, v13, vcc
	v_cndmask_b32_e32 v8, v14, v6, vcc
	v_cndmask_b32_e32 v9, v15, v5, vcc
	ds_bpermute_b32 v18, v17, v18
	ds_bpermute_b32 v8, v17, v8
	ds_bpermute_b32 v9, v17, v9
	s_waitcnt lgkmcnt(4)
	v_add_f32_e32 v7, v7, v10
	v_and_b32_e32 v10, 8, v65
	s_waitcnt lgkmcnt(3)
	v_add_f32_e32 v0, v0, v16
	v_cndmask_b32_e32 v6, v6, v14, vcc
	v_cndmask_b32_e64 v11, v217, v222, s[0:1]
	v_cmp_eq_u32_e64 s[0:1], 0, v10
	v_cndmask_b32_e32 v5, v5, v15, vcc
	s_waitcnt lgkmcnt(2)
	v_add_f32_e32 v2, v2, v18
	v_lshlrev_b32_e32 v11, 2, v11
	v_cndmask_b32_e64 v10, v1, v3, s[0:1]
	s_waitcnt lgkmcnt(1)
	v_add_f32_e32 v6, v6, v8
	s_waitcnt lgkmcnt(0)
	v_add_f32_e32 v5, v5, v9
	v_cndmask_b32_e64 v1, v3, v1, s[0:1]
	v_cndmask_b32_e64 v3, v0, v7, s[0:1]
	v_cndmask_b32_e64 v0, v7, v0, s[0:1]
	ds_bpermute_b32 v3, v11, v3
	v_cndmask_b32_e64 v7, v2, v6, s[0:1]
	v_cndmask_b32_e64 v8, v4, v5, s[0:1]
	ds_bpermute_b32 v10, v11, v10
	ds_bpermute_b32 v7, v11, v7
	ds_bpermute_b32 v8, v11, v8
	s_waitcnt lgkmcnt(3)
	v_add_f32_e32 v0, v0, v3
	v_cndmask_b32_e64 v2, v6, v2, s[0:1]
	v_cndmask_b32_e64 v3, v5, v4, s[0:1]
	v_and_b32_e32 v4, 4, v65
	v_cmp_lt_i32_e32 vcc, v221, v218
	s_waitcnt lgkmcnt(2)
	v_add_f32_e32 v1, v1, v10
	s_waitcnt lgkmcnt(1)
	v_add_f32_e32 v2, v2, v7
	s_waitcnt lgkmcnt(0)
	v_add_f32_e32 v3, v3, v8
	v_cndmask_b32_e32 v5, v217, v221, vcc
	v_cmp_eq_u32_e32 vcc, 0, v4
	v_lshlrev_b32_e32 v5, 2, v5
	s_lshl_b32 s0, s13, 7
	v_cndmask_b32_e32 v4, v1, v2, vcc
	v_cndmask_b32_e32 v6, v0, v3, vcc
	ds_bpermute_b32 v4, v5, v4
	ds_bpermute_b32 v5, v5, v6
	v_cndmask_b32_e32 v1, v2, v1, vcc
	v_cndmask_b32_e32 v0, v3, v0, vcc
	v_and_b32_e32 v2, 2, v65
	v_cmp_lt_i32_e32 vcc, v220, v218
	s_waitcnt lgkmcnt(1)
	v_add_f32_e32 v1, v1, v4
	s_waitcnt lgkmcnt(0)
	v_add_f32_e32 v0, v0, v5
	v_cndmask_b32_e32 v3, v217, v220, vcc
	v_cmp_eq_u32_e32 vcc, 0, v2
	v_lshlrev_b32_e32 v3, 2, v3
	s_add_i32 s14, s0, 0
	v_cndmask_b32_e32 v2, v1, v0, vcc
	ds_bpermute_b32 v2, v3, v2
	v_cndmask_b32_e32 v0, v0, v1, vcc
	v_cmp_lt_i32_e32 vcc, v219, v218
	s_add_i32 s14, s14, 0x22400
	s_waitcnt lgkmcnt(0)
	v_add_f32_e32 v0, v0, v2
	v_cndmask_b32_e32 v1, v217, v219, vcc
	v_lshlrev_b32_e32 v1, 2, v1
	ds_bpermute_b32 v1, v1, v0
	v_and_b32_e32 v2, 1, v65
	v_cmp_eq_u32_e32 vcc, 0, v2
	s_and_saveexec_b64 s[0:1], vcc
	s_cbranch_execz .LBB0_124
	s_waitcnt lgkmcnt(0)
	v_add_f32_e32 v0, v0, v1
	v_lshl_add_u32 v1, v178, 1, s14
	ds_write_b32 v1, v0

.LBB0_128:
	global_load_dwordx4 v[36:39], v[32:33], off
	ds_read_b128 v[40:43], v35
	s_add_i32 s11, s11, -1
	v_lshl_add_u64 v[32:33], v[32:33], 0, 64
	s_cmp_lg_u32 s11, 0
	s_waitcnt vmcnt(0) lgkmcnt(0)
	v_mfma_f32_16x16x32_bf16 v[24:27], v[36:39], v[40:43], v[24:27]
	ds_read_b128 v[40:43], v35 offset:4352
	s_waitcnt lgkmcnt(0)
	v_mfma_f32_16x16x32_bf16 v[28:31], v[36:39], v[40:43], v[28:31]
	ds_read_b128 v[40:43], v35 offset:8704
	s_waitcnt lgkmcnt(0)
	v_mfma_f32_16x16x32_bf16 v[20:23], v[36:39], v[40:43], v[20:23]
	ds_read_b128 v[40:43], v35 offset:13056
	s_waitcnt lgkmcnt(0)
	v_mfma_f32_16x16x32_bf16 v[16:19], v[36:39], v[40:43], v[16:19]
	ds_read_b128 v[40:43], v35 offset:17408
	s_waitcnt lgkmcnt(0)
	v_mfma_f32_16x16x32_bf16 v[12:15], v[36:39], v[40:43], v[12:15]
	ds_read_b128 v[40:43], v35 offset:21760
	s_waitcnt lgkmcnt(0)
	v_mfma_f32_16x16x32_bf16 v[8:11], v[36:39], v[40:43], v[8:11]
	ds_read_b128 v[40:43], v35 offset:26112
	s_waitcnt lgkmcnt(0)
	v_mfma_f32_16x16x32_bf16 v[4:7], v[36:39], v[40:43], v[4:7]
	ds_read_b128 v[40:43], v35 offset:30464
	v_add_u32_e32 v35, 64, v35
	s_waitcnt lgkmcnt(0)
	v_mfma_f32_16x16x32_bf16 v[0:3], v[36:39], v[40:43], v[0:3]
	s_cbranch_scc1 .LBB0_128
	s_branch .LBB0_121

.LBB0_130:
	s_and_b64 vcc, exec, s[0:1]
	s_cbranch_vccz .LBB0_139
	v_mov_b32_e32 v65, v214
	s_lshl_b32 s4, s6, 7
	v_readfirstlane_b32 s7, v65
	s_ashr_i32 s8, s7, 6
	s_mov_b64 s[0:1], s[42:43]
	s_add_u32 s2, s0, 0x18400000
	s_addc_u32 s3, s1, 0
	s_lshl_b32 s5, s8, 4
	s_add_i32 s0, s5, s4
	s_mul_i32 s6, s0, 0x3800
	s_mul_hi_i32 s1, s0, 0x3800
	s_add_u32 s10, s2, s6
	v_and_b32_e32 v182, 63, v65
	s_addc_u32 s11, s3, s1
	s_or_b32 s1, s0, 1
	v_lshlrev_b32_e32 v192, 4, v182
	s_mul_hi_i32 s6, s1, 0x3800
	s_mulk_i32 s1, 0x3800
	s_waitcnt vmcnt(0)
	v_lshl_add_u64 v[0:1], s[10:11], 0, v[192:193]
	s_add_u32 s10, s2, s1
	s_addc_u32 s11, s3, s6
	s_or_b32 s1, s0, 2
	s_mul_hi_i32 s6, s1, 0x3800
	s_mulk_i32 s1, 0x3800
	v_add_co_u32_e32 v0, vcc, s65, v0
	v_lshl_add_u64 v[2:3], s[10:11], 0, v[192:193]
	s_add_u32 s10, s2, s1
	v_addc_co_u32_e32 v1, vcc, 0, v1, vcc
	s_addc_u32 s11, s3, s6
	s_or_b32 s1, s0, 3
	v_add_co_u32_e32 v2, vcc, s65, v2
	s_mul_hi_i32 s6, s1, 0x3800
	s_mulk_i32 s1, 0x3800
	v_addc_co_u32_e32 v3, vcc, 0, v3, vcc
	global_load_dwordx4 v[48:51], v[0:1], off
	global_load_dwordx4 v[52:55], v[2:3], off
	v_lshl_add_u64 v[0:1], s[10:11], 0, v[192:193]
	s_add_u32 s10, s2, s1
	s_addc_u32 s11, s3, s6
	s_or_b32 s1, s0, 4
	s_mul_hi_i32 s6, s1, 0x3800
	s_mulk_i32 s1, 0x3800
	v_add_co_u32_e32 v0, vcc, s65, v0
	v_lshl_add_u64 v[2:3], s[10:11], 0, v[192:193]
	s_add_u32 s10, s2, s1
	v_addc_co_u32_e32 v1, vcc, 0, v1, vcc
	s_addc_u32 s11, s3, s6
	s_or_b32 s1, s0, 5
	v_add_co_u32_e32 v2, vcc, s65, v2
	s_mul_hi_i32 s6, s1, 0x3800
	s_mulk_i32 s1, 0x3800
	v_addc_co_u32_e32 v3, vcc, 0, v3, vcc
	global_load_dwordx4 v[56:59], v[0:1], off
	global_load_dwordx4 v[60:63], v[2:3], off
	v_lshl_add_u64 v[0:1], s[10:11], 0, v[192:193]
	s_add_u32 s10, s2, s1
	s_addc_u32 s11, s3, s6
	s_or_b32 s1, s0, 6
	s_mul_hi_i32 s6, s1, 0x3800
	s_mulk_i32 s1, 0x3800
	v_add_co_u32_e32 v0, vcc, s65, v0
	v_lshl_add_u64 v[2:3], s[10:11], 0, v[192:193]
	s_add_u32 s10, s2, s1
	v_addc_co_u32_e32 v1, vcc, 0, v1, vcc
	s_addc_u32 s11, s3, s6
	s_or_b32 s1, s0, 7
	v_add_co_u32_e32 v2, vcc, s65, v2
	s_mul_hi_i32 s6, s1, 0x3800
	s_mulk_i32 s1, 0x3800
	v_addc_co_u32_e32 v3, vcc, 0, v3, vcc
	global_load_dwordx4 v[32:35], v[0:1], off
	global_load_dwordx4 v[36:39], v[2:3], off
	v_lshl_add_u64 v[0:1], s[10:11], 0, v[192:193]
	s_add_u32 s10, s2, s1
	s_addc_u32 s11, s3, s6
	s_or_b32 s1, s0, 8
	s_mul_hi_i32 s6, s1, 0x3800
	s_mulk_i32 s1, 0x3800
	v_add_co_u32_e32 v0, vcc, s65, v0
	v_lshl_add_u64 v[2:3], s[10:11], 0, v[192:193]
	s_add_u32 s10, s2, s1
	v_addc_co_u32_e32 v1, vcc, 0, v1, vcc
	s_addc_u32 s11, s3, s6
	s_or_b32 s1, s0, 9
	v_add_co_u32_e32 v2, vcc, s65, v2
	s_mul_hi_i32 s6, s1, 0x3800
	s_mulk_i32 s1, 0x3800
	v_addc_co_u32_e32 v3, vcc, 0, v3, vcc
	global_load_dwordx4 v[40:43], v[0:1], off
	global_load_dwordx4 v[44:47], v[2:3], off
	v_lshl_add_u64 v[0:1], s[10:11], 0, v[192:193]
	s_add_u32 s10, s2, s1
	s_addc_u32 s11, s3, s6
	s_or_b32 s1, s0, 10
	s_mul_hi_i32 s6, s1, 0x3800
	s_mulk_i32 s1, 0x3800
	v_add_co_u32_e32 v0, vcc, s65, v0
	v_lshl_add_u64 v[2:3], s[10:11], 0, v[192:193]
	s_add_u32 s10, s2, s1
	v_addc_co_u32_e32 v1, vcc, 0, v1, vcc
	s_addc_u32 s11, s3, s6
	s_or_b32 s1, s0, 11
	v_add_co_u32_e32 v2, vcc, s65, v2
	s_mul_hi_i32 s6, s1, 0x3800
	s_mulk_i32 s1, 0x3800
	v_addc_co_u32_e32 v3, vcc, 0, v3, vcc
	global_load_dwordx4 v[16:19], v[0:1], off
	global_load_dwordx4 v[20:23], v[2:3], off
	v_lshl_add_u64 v[0:1], s[10:11], 0, v[192:193]
	s_add_u32 s10, s2, s1
	s_addc_u32 s11, s3, s6
	s_or_b32 s1, s0, 12
	s_mul_hi_i32 s6, s1, 0x3800
	s_mulk_i32 s1, 0x3800
	v_add_co_u32_e32 v0, vcc, s65, v0
	v_lshl_add_u64 v[2:3], s[10:11], 0, v[192:193]
	s_add_u32 s10, s2, s1
	v_addc_co_u32_e32 v1, vcc, 0, v1, vcc
	s_addc_u32 s11, s3, s6
	s_or_b32 s1, s0, 13
	v_add_co_u32_e32 v2, vcc, s65, v2
	s_mul_hi_i32 s6, s1, 0x3800
	s_mulk_i32 s1, 0x3800
	v_addc_co_u32_e32 v3, vcc, 0, v3, vcc
	global_load_dwordx4 v[24:27], v[0:1], off
	global_load_dwordx4 v[28:31], v[2:3], off
	v_lshl_add_u64 v[0:1], s[10:11], 0, v[192:193]
	s_add_u32 s10, s2, s1
	s_addc_u32 s11, s3, s6
	s_or_b32 s1, s0, 14
	s_mul_hi_i32 s6, s1, 0x3800
	s_mulk_i32 s1, 0x3800
	v_add_co_u32_e32 v0, vcc, s65, v0
	v_lshl_add_u64 v[2:3], s[10:11], 0, v[192:193]
	s_add_u32 s10, s2, s1
	v_addc_co_u32_e32 v1, vcc, 0, v1, vcc
	s_addc_u32 s11, s3, s6
	s_or_b32 s0, s0, 15
	v_add_co_u32_e32 v4, vcc, s65, v2
	s_mul_hi_i32 s1, s0, 0x3800
	s_mulk_i32 s0, 0x3800
	v_addc_co_u32_e32 v5, vcc, 0, v3, vcc
	v_lshl_add_u64 v[8:9], s[10:11], 0, v[192:193]
	s_add_u32 s0, s2, s0
	v_add_co_u32_e32 v8, vcc, s65, v8
	s_addc_u32 s1, s3, s1
	s_nop 0
	v_addc_co_u32_e32 v9, vcc, 0, v9, vcc
	v_lshl_add_u64 v[10:11], s[0:1], 0, v[192:193]
	v_add_co_u32_e32 v12, vcc, s65, v10
	global_load_dwordx4 v[0:3], v[0:1], off
	s_nop 0
	global_load_dwordx4 v[4:7], v[4:5], off
	v_addc_co_u32_e32 v13, vcc, 0, v11, vcc
	global_load_dwordx4 v[8:11], v[8:9], off
	s_nop 0
	global_load_dwordx4 v[12:15], v[12:13], off
	s_waitcnt vmcnt(0) lgkmcnt(0)
	v_lshlrev_b32_e32 v165, 16, v60
	v_lshlrev_b32_e32 v164, 16, v56
	v_lshlrev_b32_e32 v155, 16, v52
	v_lshlrev_b32_e32 v154, 16, v48
	v_add_f32_e32 v67, 0, v155
	v_add_f32_e32 v68, 0, v164
	v_add_f32_e32 v69, 0, v165
	v_and_b32_e32 v139, 0xffff0000, v60
	v_and_b32_e32 v138, 0xffff0000, v56
	v_and_b32_e32 v137, 0xffff0000, v52
	v_add_f32_e32 v66, 0, v154
	v_and_b32_e32 v136, 0xffff0000, v48
	v_add_f32_e32 v52, v67, v137
	v_add_f32_e32 v56, v68, v138
	v_add_f32_e32 v60, v69, v139
	v_lshlrev_b32_e32 v153, 16, v61
	v_lshlrev_b32_e32 v152, 16, v57
	v_lshlrev_b32_e32 v151, 16, v53
	v_add_f32_e32 v48, v66, v136
	v_lshlrev_b32_e32 v150, 16, v49
	v_add_f32_e32 v52, v52, v151
	v_add_f32_e32 v56, v56, v152
	v_add_f32_e32 v60, v60, v153
	v_and_b32_e32 v149, 0xffff0000, v61
	v_and_b32_e32 v148, 0xffff0000, v57
	v_and_b32_e32 v147, 0xffff0000, v53
	v_add_f32_e32 v48, v48, v150
	v_and_b32_e32 v146, 0xffff0000, v49
	v_add_f32_e32 v49, v52, v147
	v_add_f32_e32 v52, v56, v148
	v_add_f32_e32 v53, v60, v149
	v_lshlrev_b32_e32 v133, 16, v62
	v_lshlrev_b32_e32 v132, 16, v58
	v_add_f32_e32 v48, v48, v146
	v_lshlrev_b32_e32 v128, 16, v50
	v_lshlrev_b32_e32 v129, 16, v54
	v_add_f32_e32 v52, v52, v132
	v_add_f32_e32 v53, v53, v133
	v_and_b32_e32 v131, 0xffff0000, v62
	v_and_b32_e32 v130, 0xffff0000, v58
	v_add_f32_e32 v48, v48, v128
	v_add_f32_e32 v49, v49, v129
	v_and_b32_e32 v126, 0xffff0000, v50
	v_and_b32_e32 v127, 0xffff0000, v54
	v_add_f32_e32 v50, v52, v130
	v_add_f32_e32 v52, v53, v131
	v_lshlrev_b32_e32 v67, 16, v63
	v_add_f32_e32 v48, v48, v126
	v_add_f32_e32 v49, v49, v127
	v_lshlrev_b32_e32 v60, 16, v51
	v_lshlrev_b32_e32 v66, 16, v59
	v_lshlrev_b32_e32 v61, 16, v55
	v_add_f32_e32 v52, v52, v67
	v_and_b32_e32 v73, 0xffff0000, v63
	v_add_f32_e32 v48, v48, v60
	v_add_f32_e32 v49, v49, v61
	v_add_f32_e32 v50, v50, v66
	v_and_b32_e32 v70, 0xffff0000, v51
	v_and_b32_e32 v72, 0xffff0000, v59
	v_and_b32_e32 v71, 0xffff0000, v55
	v_add_f32_e32 v183, v52, v73
	v_lshlrev_b32_e32 v55, 16, v44
	v_lshlrev_b32_e32 v54, 16, v40
	v_lshlrev_b32_e32 v53, 16, v36
	v_lshlrev_b32_e32 v52, 16, v32
	v_add_f32_e32 v186, v48, v70
	v_add_f32_e32 v185, v49, v71
	v_add_f32_e32 v184, v50, v72
	v_add_f32_e32 v56, 0, v52
	v_add_f32_e32 v57, 0, v53
	v_add_f32_e32 v58, 0, v54
	v_add_f32_e32 v59, 0, v55
	v_and_b32_e32 v49, 0xffff0000, v44
	v_and_b32_e32 v48, 0xffff0000, v40
	v_and_b32_e32 v51, 0xffff0000, v36
	v_and_b32_e32 v50, 0xffff0000, v32
	v_add_f32_e32 v62, v56, v50
	v_add_f32_e32 v63, v57, v51
	v_add_f32_e32 v68, v58, v48
	v_add_f32_e32 v69, v59, v49
	v_lshlrev_b32_e32 v57, 16, v45
	v_lshlrev_b32_e32 v56, 16, v41
	v_lshlrev_b32_e32 v59, 16, v37
	v_lshlrev_b32_e32 v58, 16, v33
	v_add_f32_e32 v74, v62, v58
	v_add_f32_e32 v75, v63, v59
	v_add_f32_e32 v76, v68, v56
	v_add_f32_e32 v77, v69, v57
	v_and_b32_e32 v63, 0xffff0000, v45
	v_and_b32_e32 v62, 0xffff0000, v41
	v_and_b32_e32 v69, 0xffff0000, v37
	v_and_b32_e32 v68, 0xffff0000, v33
	v_add_f32_e32 v33, v74, v68
	v_add_f32_e32 v37, v75, v69
	v_add_f32_e32 v41, v76, v62
	v_add_f32_e32 v45, v77, v63
	v_lshlrev_b32_e32 v75, 16, v46
	v_lshlrev_b32_e32 v76, 16, v34
	v_lshlrev_b32_e32 v74, 16, v42
	v_lshlrev_b32_e32 v77, 16, v38
	v_add_f32_e32 v33, v33, v76
	v_add_f32_e32 v45, v45, v75
	v_and_b32_e32 v87, 0xffff0000, v46
	v_and_b32_e32 v88, 0xffff0000, v34
	v_add_f32_e32 v37, v37, v77
	v_add_f32_e32 v41, v41, v74
	v_and_b32_e32 v86, 0xffff0000, v42
	v_and_b32_e32 v89, 0xffff0000, v38
	v_add_f32_e32 v33, v33, v88
	v_add_f32_e32 v38, v45, v87
	v_lshlrev_b32_e32 v91, 16, v47
	v_lshlrev_b32_e32 v92, 16, v35
	v_add_f32_e32 v34, v37, v89
	v_add_f32_e32 v37, v41, v86
	v_lshlrev_b32_e32 v90, 16, v43
	v_add_f32_e32 v33, v33, v92
	v_add_f32_e32 v38, v38, v91
	v_and_b32_e32 v95, 0xffff0000, v47
	v_and_b32_e32 v98, 0xffff0000, v35
	v_lshlrev_b32_e32 v83, 16, v28
	v_lshlrev_b32_e32 v78, 16, v16
	v_lshlrev_b32_e32 v93, 16, v39
	v_add_f32_e32 v41, v37, v90
	v_add_f32_e32 v37, v33, v98
	v_add_f32_e32 v33, v38, v95
	v_add_f32_e32 v38, 0, v78
	v_add_f32_e32 v42, 0, v83
	v_and_b32_e32 v81, 0xffff0000, v28
	v_and_b32_e32 v84, 0xffff0000, v16
	v_add_f32_e32 v34, v34, v93
	v_and_b32_e32 v94, 0xffff0000, v43
	v_and_b32_e32 v99, 0xffff0000, v39
	v_lshlrev_b32_e32 v82, 16, v24
	v_lshlrev_b32_e32 v79, 16, v20
	v_add_f32_e32 v38, v38, v84
	v_add_f32_e32 v42, v42, v81
	v_lshlrev_b32_e32 v97, 16, v29
	v_lshlrev_b32_e32 v100, 16, v17
	v_add_f32_e32 v35, v34, v99
	v_add_f32_e32 v34, v41, v94
	v_add_f32_e32 v39, 0, v79
	v_add_f32_e32 v41, 0, v82
	v_and_b32_e32 v80, 0xffff0000, v24
	v_and_b32_e32 v85, 0xffff0000, v20
	v_add_f32_e32 v38, v38, v100
	v_add_f32_e32 v42, v42, v97
	v_and_b32_e32 v103, 0xffff0000, v29
	v_and_b32_e32 v104, 0xffff0000, v17
	v_add_f32_e32 v39, v39, v85
	v_add_f32_e32 v41, v41, v80
	v_lshlrev_b32_e32 v96, 16, v25
	v_lshlrev_b32_e32 v101, 16, v21
	v_add_f32_e32 v17, v38, v104
	v_add_f32_e32 v29, v42, v103
	v_lshlrev_b32_e32 v107, 16, v30
	v_lshlrev_b32_e32 v108, 16, v18
	v_add_f32_e32 v39, v39, v101
	v_add_f32_e32 v41, v41, v96
	v_and_b32_e32 v102, 0xffff0000, v25
	v_and_b32_e32 v105, 0xffff0000, v21
	v_add_f32_e32 v17, v17, v108
	v_add_f32_e32 v29, v29, v107
	v_and_b32_e32 v111, 0xffff0000, v30
	v_and_b32_e32 v112, 0xffff0000, v18
	v_add_f32_e32 v21, v39, v105
	v_add_f32_e32 v25, v41, v102
	v_lshlrev_b32_e32 v106, 16, v26
	v_lshlrev_b32_e32 v109, 16, v22
	v_and_b32_e32 v113, 0xffff0000, v22
	v_add_f32_e32 v17, v17, v112
	v_add_f32_e32 v22, v29, v111
	v_lshlrev_b32_e32 v115, 16, v31
	v_lshlrev_b32_e32 v118, 16, v19
	v_add_f32_e32 v21, v21, v109
	v_add_f32_e32 v25, v25, v106
	v_and_b32_e32 v110, 0xffff0000, v26
	v_add_f32_e32 v17, v17, v118
	v_add_f32_e32 v22, v22, v115
	v_and_b32_e32 v135, 0xffff0000, v31
	v_and_b32_e32 v144, 0xffff0000, v19
	v_lshlrev_b32_e32 v124, 16, v8
	v_lshlrev_b32_e32 v123, 16, v4
	v_add_f32_e32 v18, v21, v113
	v_add_f32_e32 v21, v25, v110
	v_lshlrev_b32_e32 v119, 16, v23
	v_and_b32_e32 v145, 0xffff0000, v23
	v_add_f32_e32 v23, v17, v144
	v_add_f32_e32 v17, v22, v135
	v_add_f32_e32 v22, 0, v123
	v_add_f32_e32 v25, 0, v124
	v_and_b32_e32 v116, 0xffff0000, v8
	v_and_b32_e32 v121, 0xffff0000, v4
	v_add_f32_e32 v22, v22, v121
	v_add_f32_e32 v25, v25, v116
	v_lshlrev_b32_e32 v140, 16, v9
	v_lshlrev_b32_e32 v143, 16, v5
	v_add_f32_e32 v22, v22, v143
	v_add_f32_e32 v25, v25, v140
	v_and_b32_e32 v156, 0xffff0000, v9
	v_and_b32_e32 v159, 0xffff0000, v5
	v_add_f32_e32 v5, v22, v159
	v_add_f32_e32 v9, v25, v156
	v_lshlrev_b32_e32 v160, 16, v10
	v_lshlrev_b32_e32 v163, 16, v6
	v_add_f32_e32 v5, v5, v163
	v_add_f32_e32 v9, v9, v160
	v_and_b32_e32 v166, 0xffff0000, v10
	v_and_b32_e32 v169, 0xffff0000, v6
	v_lshlrev_b32_e32 v162, 16, v2
	v_and_b32_e32 v168, 0xffff0000, v2
	v_add_f32_e32 v2, v5, v169
	v_add_f32_e32 v5, v9, v166
	v_lshlrev_b32_e32 v170, 16, v11
	v_mul_f32_e32 v181, v136, v136
	v_mul_f32_e32 v28, v84, v84
	v_add_f32_e32 v5, v5, v170
	v_and_b32_e32 v174, 0xffff0000, v11
	v_cmp_lt_i32_e32 vcc, v224, v218
	v_fmac_f32_e32 v181, v154, v154
	v_fmac_f32_e32 v28, v78, v78
	v_lshlrev_b32_e32 v172, 16, v3
	v_and_b32_e32 v176, 0xffff0000, v3
	v_add_f32_e32 v3, v5, v174
	v_cndmask_b32_e32 v5, v217, v224, vcc
	v_cmp_gt_u32_e32 vcc, 32, v182
	v_mul_f32_e32 v180, v137, v137
	v_fmac_f32_e32 v181, v150, v150
	v_mul_f32_e32 v24, v85, v85
	v_fmac_f32_e32 v28, v100, v100
	v_lshlrev_b32_e32 v173, 16, v7
	v_and_b32_e32 v177, 0xffff0000, v7
	v_lshlrev_b32_e32 v5, 2, v5
	v_cndmask_b32_e32 v7, v186, v23, vcc
	v_fmac_f32_e32 v180, v155, v155
	v_fmac_f32_e32 v181, v146, v146
	v_fmac_f32_e32 v24, v79, v79
	v_fmac_f32_e32 v28, v104, v104
	ds_bpermute_b32 v7, v5, v7
	v_fmac_f32_e32 v180, v151, v151
	v_fmac_f32_e32 v181, v128, v128
	v_fmac_f32_e32 v24, v101, v101
	v_fmac_f32_e32 v28, v108, v108
	v_lshlrev_b32_e32 v125, 16, v12
	v_fmac_f32_e32 v180, v147, v147
	v_fmac_f32_e32 v181, v126, v126
	v_fmac_f32_e32 v24, v105, v105
	v_fmac_f32_e32 v28, v112, v112
	v_add_f32_e32 v26, 0, v125
	v_and_b32_e32 v117, 0xffff0000, v12
	v_fmac_f32_e32 v180, v129, v129
	v_fmac_f32_e32 v181, v60, v60
	v_fmac_f32_e32 v24, v109, v109
	v_fmac_f32_e32 v28, v118, v118
	v_add_f32_e32 v26, v26, v117
	v_lshlrev_b32_e32 v141, 16, v13
	v_fmac_f32_e32 v180, v127, v127
	v_fmac_f32_e32 v181, v70, v70
	v_fmac_f32_e32 v24, v113, v113
	v_add_f32_e32 v18, v18, v119
	v_fmac_f32_e32 v28, v144, v144
	v_add_f32_e32 v26, v26, v141
	v_and_b32_e32 v157, 0xffff0000, v13
	v_cndmask_b32_e32 v9, v23, v186, vcc
	v_fmac_f32_e32 v180, v61, v61
	v_fmac_f32_e32 v24, v119, v119
	v_add_f32_e32 v19, v18, v145
	v_add_f32_e32 v13, v26, v157
	v_lshlrev_b32_e32 v161, 16, v14
	s_waitcnt lgkmcnt(0)
	v_add_f32_e32 v7, v9, v7
	v_cndmask_b32_e32 v9, v181, v28, vcc
	v_mul_f32_e32 v179, v138, v138
	v_fmac_f32_e32 v180, v71, v71
	v_mul_f32_e32 v20, v80, v80
	v_fmac_f32_e32 v24, v145, v145
	v_add_f32_e32 v13, v13, v161
	v_and_b32_e32 v167, 0xffff0000, v14
	ds_bpermute_b32 v9, v5, v9
	v_cndmask_b32_e32 v11, v185, v19, vcc
	v_fmac_f32_e32 v179, v164, v164
	v_fmac_f32_e32 v20, v82, v82
	v_add_f32_e32 v6, v13, v167
	ds_bpermute_b32 v11, v5, v11
	v_cndmask_b32_e32 v13, v180, v24, vcc
	v_fmac_f32_e32 v179, v152, v152
	v_fmac_f32_e32 v20, v96, v96
	ds_bpermute_b32 v13, v5, v13
	v_fmac_f32_e32 v179, v148, v148
	v_fmac_f32_e32 v20, v102, v102
	v_fmac_f32_e32 v179, v132, v132
	v_fmac_f32_e32 v20, v106, v106
	v_lshlrev_b32_e32 v114, 16, v27
	v_cndmask_b32_e32 v10, v28, v181, vcc
	v_fmac_f32_e32 v179, v130, v130
	v_fmac_f32_e32 v20, v110, v110
	v_add_f32_e32 v21, v21, v114
	v_and_b32_e32 v134, 0xffff0000, v27
	s_waitcnt lgkmcnt(2)
	v_add_f32_e32 v9, v10, v9
	v_cndmask_b32_e32 v10, v19, v185, vcc
	v_fmac_f32_e32 v179, v66, v66
	v_fmac_f32_e32 v20, v114, v114
	v_add_f32_e32 v18, v21, v134
	v_lshlrev_b32_e32 v122, 16, v0
	v_and_b32_e32 v120, 0xffff0000, v0
	s_waitcnt lgkmcnt(1)
	v_add_f32_e32 v10, v10, v11
	v_cndmask_b32_e32 v11, v24, v180, vcc
	v_mul_f32_e32 v178, v139, v139
	v_fmac_f32_e32 v179, v72, v72
	v_mul_f32_e32 v44, v50, v50
	v_mul_f32_e32 v16, v81, v81
	v_fmac_f32_e32 v20, v134, v134
	v_add_f32_e32 v21, 0, v122
	v_mul_f32_e32 v12, v120, v120
	s_waitcnt lgkmcnt(0)
	v_add_f32_e32 v11, v11, v13
	v_cndmask_b32_e32 v13, v184, v18, vcc
	v_fmac_f32_e32 v178, v165, v165
	v_fmac_f32_e32 v44, v52, v52
	v_fmac_f32_e32 v16, v83, v83
	v_add_f32_e32 v21, v21, v120
	v_fmac_f32_e32 v12, v122, v122
	v_lshlrev_b32_e32 v142, 16, v1
	v_lshlrev_b32_e32 v171, 16, v15
	v_and_b32_e32 v175, 0xffff0000, v15
	ds_bpermute_b32 v13, v5, v13
	v_cndmask_b32_e32 v15, v179, v20, vcc
	v_fmac_f32_e32 v178, v153, v153
	v_fmac_f32_e32 v44, v58, v58
	v_fmac_f32_e32 v16, v97, v97
	v_add_f32_e32 v21, v21, v142
	v_fmac_f32_e32 v12, v142, v142
	v_and_b32_e32 v158, 0xffff0000, v1
	v_cndmask_b32_e32 v14, v18, v184, vcc
	ds_bpermute_b32 v15, v5, v15
	v_cndmask_b32_e32 v18, v183, v17, vcc
	v_fmac_f32_e32 v178, v149, v149
	v_fmac_f32_e32 v44, v68, v68
	v_fmac_f32_e32 v16, v103, v103
	v_add_f32_e32 v1, v21, v158
	v_fmac_f32_e32 v12, v158, v158
	ds_bpermute_b32 v18, v5, v18
	v_fmac_f32_e32 v178, v133, v133
	v_fmac_f32_e32 v44, v76, v76
	v_fmac_f32_e32 v16, v107, v107
	v_add_f32_e32 v1, v1, v162
	v_fmac_f32_e32 v12, v162, v162
	v_fmac_f32_e32 v178, v131, v131
	v_fmac_f32_e32 v44, v88, v88
	v_fmac_f32_e32 v16, v111, v111
	v_add_f32_e32 v1, v1, v168
	v_fmac_f32_e32 v12, v168, v168
	v_fmac_f32_e32 v178, v67, v67
	v_mul_f32_e32 v40, v51, v51
	v_fmac_f32_e32 v44, v92, v92
	v_fmac_f32_e32 v16, v115, v115
	v_mul_f32_e32 v8, v121, v121
	v_add_f32_e32 v1, v1, v172
	v_fmac_f32_e32 v12, v172, v172
	s_waitcnt lgkmcnt(2)
	v_add_f32_e32 v13, v14, v13
	v_cndmask_b32_e32 v14, v20, v179, vcc
	v_fmac_f32_e32 v178, v73, v73
	v_fmac_f32_e32 v40, v53, v53
	v_fmac_f32_e32 v44, v98, v98
	v_fmac_f32_e32 v16, v135, v135
	v_fmac_f32_e32 v8, v123, v123
	v_add_f32_e32 v1, v1, v176
	v_fmac_f32_e32 v12, v176, v176
	s_waitcnt lgkmcnt(1)
	v_add_f32_e32 v14, v14, v15
	v_cndmask_b32_e32 v15, v17, v183, vcc
	v_fmac_f32_e32 v40, v59, v59
	v_fmac_f32_e32 v8, v143, v143
	s_waitcnt lgkmcnt(0)
	v_add_f32_e32 v15, v15, v18
	v_cndmask_b32_e32 v17, v178, v16, vcc
	v_cndmask_b32_e32 v18, v37, v1, vcc
	v_cndmask_b32_e32 v19, v44, v12, vcc
	v_fmac_f32_e32 v40, v69, v69
	v_fmac_f32_e32 v8, v159, v159
	ds_bpermute_b32 v17, v5, v17
	ds_bpermute_b32 v18, v5, v18
	ds_bpermute_b32 v19, v5, v19
	v_fmac_f32_e32 v40, v77, v77
	v_fmac_f32_e32 v8, v163, v163
	v_fmac_f32_e32 v40, v89, v89
	v_fmac_f32_e32 v8, v169, v169
	v_mul_f32_e32 v36, v48, v48
	v_mul_f32_e32 v32, v49, v49
	v_fmac_f32_e32 v40, v93, v93
	v_mul_f32_e32 v4, v116, v116
	v_mul_f32_e32 v0, v117, v117
	v_add_f32_e32 v2, v2, v173
	v_fmac_f32_e32 v8, v173, v173
	v_fmac_f32_e32 v36, v54, v54
	v_fmac_f32_e32 v32, v55, v55
	v_fmac_f32_e32 v40, v99, v99
	v_fmac_f32_e32 v4, v124, v124
	v_fmac_f32_e32 v0, v125, v125
	v_add_f32_e32 v2, v2, v177
	v_fmac_f32_e32 v8, v177, v177
	v_cndmask_b32_e32 v16, v16, v178, vcc
	v_cndmask_b32_e32 v1, v1, v37, vcc
	v_cndmask_b32_e32 v12, v12, v44, vcc
	v_fmac_f32_e32 v36, v56, v56
	v_fmac_f32_e32 v32, v57, v57
	v_fmac_f32_e32 v4, v140, v140
	v_fmac_f32_e32 v0, v141, v141
	s_waitcnt lgkmcnt(2)
	v_add_f32_e32 v16, v16, v17
	s_waitcnt lgkmcnt(1)
	v_add_f32_e32 v1, v1, v18
	s_waitcnt lgkmcnt(0)
	v_add_f32_e32 v12, v12, v19
	v_cndmask_b32_e32 v17, v35, v2, vcc
	v_cndmask_b32_e32 v18, v40, v8, vcc
	v_cndmask_b32_e32 v19, v34, v3, vcc
	v_fmac_f32_e32 v36, v62, v62
	v_fmac_f32_e32 v32, v63, v63
	v_fmac_f32_e32 v4, v156, v156
	v_fmac_f32_e32 v0, v157, v157
	ds_bpermute_b32 v17, v5, v17
	ds_bpermute_b32 v18, v5, v18
	ds_bpermute_b32 v19, v5, v19
	v_fmac_f32_e32 v36, v74, v74
	v_fmac_f32_e32 v32, v75, v75
	v_fmac_f32_e32 v4, v160, v160
	v_fmac_f32_e32 v0, v161, v161
	v_fmac_f32_e32 v36, v86, v86
	v_fmac_f32_e32 v32, v87, v87
	v_fmac_f32_e32 v4, v166, v166
	v_fmac_f32_e32 v0, v167, v167
	v_fmac_f32_e32 v36, v90, v90
	v_fmac_f32_e32 v32, v91, v91
	v_fmac_f32_e32 v4, v170, v170
	v_add_f32_e32 v6, v6, v171
	v_fmac_f32_e32 v0, v171, v171
	v_fmac_f32_e32 v36, v94, v94
	v_fmac_f32_e32 v32, v95, v95
	v_fmac_f32_e32 v4, v174, v174
	v_add_f32_e32 v6, v6, v175
	v_fmac_f32_e32 v0, v175, v175
	v_cndmask_b32_e32 v2, v2, v35, vcc
	v_cndmask_b32_e32 v8, v8, v40, vcc
	v_cndmask_b32_e32 v3, v3, v34, vcc
	s_waitcnt lgkmcnt(2)
	v_add_f32_e32 v2, v2, v17
	s_waitcnt lgkmcnt(1)
	v_add_f32_e32 v8, v8, v18
	s_waitcnt lgkmcnt(0)
	v_add_f32_e32 v3, v3, v19
	v_cndmask_b32_e32 v17, v36, v4, vcc
	v_cndmask_b32_e32 v18, v33, v6, vcc
	v_cndmask_b32_e32 v19, v32, v0, vcc
	ds_bpermute_b32 v17, v5, v17
	ds_bpermute_b32 v18, v5, v18
	ds_bpermute_b32 v5, v5, v19
	v_cndmask_b32_e32 v0, v0, v32, vcc
	v_cndmask_b32_e32 v4, v4, v36, vcc
	v_cndmask_b32_e32 v6, v6, v33, vcc
	v_cmp_lt_i32_e32 vcc, v223, v218
	s_waitcnt lgkmcnt(0)
	v_add_f32_e32 v0, v0, v5
	v_and_b32_e32 v5, 16, v65
	v_add_f32_e32 v4, v4, v17
	v_cndmask_b32_e32 v17, v217, v223, vcc
	v_cmp_eq_u32_e32 vcc, 0, v5
	v_lshlrev_b32_e32 v17, 2, v17
	v_add_f32_e32 v6, v6, v18
	v_cndmask_b32_e32 v5, v7, v1, vcc
	v_cndmask_b32_e32 v1, v1, v7, vcc
	ds_bpermute_b32 v5, v17, v5
	v_cndmask_b32_e32 v7, v9, v12, vcc
	ds_bpermute_b32 v7, v17, v7
	v_cndmask_b32_e32 v18, v10, v2, vcc
	v_cndmask_b32_e32 v2, v2, v10, vcc
	s_waitcnt lgkmcnt(1)
	v_add_f32_e32 v1, v1, v5
	v_cndmask_b32_e32 v5, v12, v9, vcc
	s_waitcnt lgkmcnt(0)
	v_add_f32_e32 v5, v5, v7
	v_cndmask_b32_e32 v7, v11, v8, vcc
	v_cndmask_b32_e32 v9, v13, v3, vcc
	ds_bpermute_b32 v7, v17, v7
	ds_bpermute_b32 v9, v17, v9
	v_cndmask_b32_e32 v10, v14, v4, vcc
	v_cndmask_b32_e32 v8, v8, v11, vcc
	ds_bpermute_b32 v10, v17, v10
	v_cndmask_b32_e32 v3, v3, v13, vcc
	s_waitcnt lgkmcnt(2)
	v_add_f32_e32 v7, v8, v7
	s_waitcnt lgkmcnt(1)
	v_add_f32_e32 v3, v3, v9
	v_cndmask_b32_e32 v8, v15, v6, vcc
	v_cndmask_b32_e32 v9, v16, v0, vcc
	ds_bpermute_b32 v18, v17, v18
	ds_bpermute_b32 v8, v17, v8
	ds_bpermute_b32 v9, v17, v9
	v_cndmask_b32_e32 v4, v4, v14, vcc
	s_waitcnt lgkmcnt(3)
	v_add_f32_e32 v4, v4, v10
	v_and_b32_e32 v10, 8, v65
	v_cmp_lt_i32_e64 s[0:1], v222, v218
	v_cndmask_b32_e32 v6, v6, v15, vcc
	v_cndmask_b32_e32 v0, v0, v16, vcc
	v_cndmask_b32_e64 v11, v217, v222, s[0:1]
	v_cmp_eq_u32_e64 s[0:1], 0, v10
	s_waitcnt lgkmcnt(2)
	v_add_f32_e32 v2, v2, v18
	v_lshlrev_b32_e32 v11, 2, v11
	v_cndmask_b32_e64 v10, v1, v3, s[0:1]
	s_waitcnt lgkmcnt(1)
	v_add_f32_e32 v6, v6, v8
	s_waitcnt lgkmcnt(0)
	v_add_f32_e32 v0, v0, v9
	v_cndmask_b32_e64 v1, v3, v1, s[0:1]
	v_cndmask_b32_e64 v3, v5, v4, s[0:1]
	v_cndmask_b32_e64 v4, v4, v5, s[0:1]
	ds_bpermute_b32 v3, v11, v3
	v_cndmask_b32_e64 v5, v2, v6, s[0:1]
	v_cndmask_b32_e64 v8, v7, v0, s[0:1]
	ds_bpermute_b32 v10, v11, v10
	ds_bpermute_b32 v5, v11, v5
	ds_bpermute_b32 v8, v11, v8
	s_waitcnt lgkmcnt(3)
	v_add_f32_e32 v3, v4, v3
	v_cndmask_b32_e64 v2, v6, v2, s[0:1]
	v_cndmask_b32_e64 v0, v0, v7, s[0:1]
	v_and_b32_e32 v4, 4, v65
	v_cmp_lt_i32_e32 vcc, v221, v218
	s_waitcnt lgkmcnt(2)
	v_add_f32_e32 v1, v1, v10
	s_waitcnt lgkmcnt(1)
	v_add_f32_e32 v2, v2, v5
	s_waitcnt lgkmcnt(0)
	v_add_f32_e32 v0, v0, v8
	v_cndmask_b32_e32 v5, v217, v221, vcc
	v_cmp_eq_u32_e32 vcc, 0, v4
	v_lshlrev_b32_e32 v5, 2, v5
	s_lshl_b32 s0, s8, 7
	v_cndmask_b32_e32 v4, v1, v2, vcc
	v_cndmask_b32_e32 v6, v3, v0, vcc
	ds_bpermute_b32 v4, v5, v4
	ds_bpermute_b32 v5, v5, v6
	v_cndmask_b32_e32 v1, v2, v1, vcc
	v_cndmask_b32_e32 v0, v0, v3, vcc
	v_and_b32_e32 v2, 2, v65
	v_cmp_lt_i32_e32 vcc, v220, v218
	s_waitcnt lgkmcnt(1)
	v_add_f32_e32 v1, v1, v4
	s_waitcnt lgkmcnt(0)
	v_add_f32_e32 v0, v0, v5
	v_cndmask_b32_e32 v3, v217, v220, vcc
	v_cmp_eq_u32_e32 vcc, 0, v2
	v_lshlrev_b32_e32 v3, 2, v3
	s_add_i32 s6, s0, 0
	v_cndmask_b32_e32 v2, v1, v0, vcc
	ds_bpermute_b32 v2, v3, v2
	v_cndmask_b32_e32 v0, v0, v1, vcc
	v_cmp_lt_i32_e32 vcc, v219, v218
	s_add_i32 s6, s6, 0x22400
	s_waitcnt lgkmcnt(0)
	v_add_f32_e32 v0, v0, v2
	v_cndmask_b32_e32 v1, v217, v219, vcc
	v_lshlrev_b32_e32 v1, 2, v1
	ds_bpermute_b32 v1, v1, v0
	v_and_b32_e32 v2, 1, v65
	v_cmp_eq_u32_e32 vcc, 0, v2
	s_and_saveexec_b64 s[0:1], vcc
	s_cbranch_execz .LBB0_133
	s_waitcnt lgkmcnt(0)
	v_add_f32_e32 v0, v0, v1
	v_lshl_add_u32 v1, v182, 1, s6
	ds_write_b32 v1, v0

.LBB0_137:
	global_load_dwordx4 v[38:41], v[32:33], off
	ds_read_b128 v[42:45], v36
	s_add_i32 s6, s6, -1
	v_lshl_add_u64 v[32:33], v[32:33], 0, 64
	s_cmp_lg_u32 s6, 0
	s_waitcnt vmcnt(0) lgkmcnt(0)
	v_mfma_f32_16x16x32_bf16 v[24:27], v[38:41], v[42:45], v[24:27]
	ds_read_b128 v[42:45], v36 offset:4352
	s_waitcnt lgkmcnt(0)
	v_mfma_f32_16x16x32_bf16 v[28:31], v[38:41], v[42:45], v[28:31]
	ds_read_b128 v[42:45], v36 offset:8704
	s_waitcnt lgkmcnt(0)
	v_mfma_f32_16x16x32_bf16 v[20:23], v[38:41], v[42:45], v[20:23]
	ds_read_b128 v[42:45], v36 offset:13056
	s_waitcnt lgkmcnt(0)
	v_mfma_f32_16x16x32_bf16 v[16:19], v[38:41], v[42:45], v[16:19]
	ds_read_b128 v[42:45], v36 offset:17408
	s_waitcnt lgkmcnt(0)
	v_mfma_f32_16x16x32_bf16 v[12:15], v[38:41], v[42:45], v[12:15]
	ds_read_b128 v[42:45], v36 offset:21760
	s_waitcnt lgkmcnt(0)
	v_mfma_f32_16x16x32_bf16 v[8:11], v[38:41], v[42:45], v[8:11]
	ds_read_b128 v[42:45], v36 offset:26112
	s_waitcnt lgkmcnt(0)
	v_mfma_f32_16x16x32_bf16 v[4:7], v[38:41], v[42:45], v[4:7]
	ds_read_b128 v[42:45], v36 offset:30464
	v_add_u32_e32 v36, 64, v36
	s_waitcnt lgkmcnt(0)
	v_mfma_f32_16x16x32_bf16 v[0:3], v[38:41], v[42:45], v[0:3]
	s_cbranch_scc1 .LBB0_137
.LBB0_138:
	v_lshl_or_b32 v36, v34, 2, s5
	v_readlane_b32 s0, v253, 51
	v_ashrrev_i32_e32 v37, 31, v36
	v_readlane_b32 s1, v253, 52
	v_lshlrev_b32_e32 v38, 2, v35
	v_lshlrev_b32_e32 v192, 1, v183
	v_lshl_add_u64 v[32:33], v[36:37], 2, s[0:1]
	global_load_dwordx4 v[32:35], v[32:33], off
	v_mul_lo_u32 v36, v36, s66
	v_add3_u32 v36, 0, v38, v36
	v_add_u32_e32 v37, 0x9000, v36
	s_mov_b64 s[0:1], s[42:43]
	s_waitcnt vmcnt(0)
	v_add_f32_e32 v4, v4, v32
	v_add_f32_e32 v0, v0, v32
	ds_write2_b32 v37, v4, v0 offset0:96 offset1:112
	v_add_f32_e32 v0, v25, v33
	v_add_f32_e32 v4, v29, v33
	ds_write2_b32 v37, v0, v4 offset0:132 offset1:148
	v_add_f32_e32 v0, v21, v33
	v_add_f32_e32 v4, v17, v33
	ds_write2_b32 v37, v0, v4 offset0:164 offset1:180
	v_add_f32_e32 v0, v13, v33
	v_add_f32_e32 v4, v9, v33
	ds_write2_b32 v37, v0, v4 offset0:196 offset1:212
	v_add_f32_e32 v0, v5, v33
	v_add_f32_e32 v1, v1, v33
	ds_write2_b32 v37, v0, v1 offset0:228 offset1:244
	v_add_f32_e32 v0, v26, v34
	v_add_f32_e32 v1, v30, v34
	v_add_u32_e32 v4, 0x9400, v36
	ds_write2_b32 v4, v0, v1 offset0:8 offset1:24
	v_add_f32_e32 v0, v22, v34
	v_add_f32_e32 v1, v18, v34
	ds_write2_b32 v4, v0, v1 offset0:40 offset1:56
	v_add_f32_e32 v0, v14, v34
	v_add_f32_e32 v1, v10, v34
	ds_write2_b32 v4, v0, v1 offset0:72 offset1:88
	v_add_f32_e32 v0, v6, v34
	v_add_f32_e32 v1, v2, v34
	ds_write2_b32 v4, v0, v1 offset0:104 offset1:120
	v_add_f32_e32 v0, v27, v35
	v_add_f32_e32 v1, v31, v35
	ds_write2_b32 v4, v0, v1 offset0:140 offset1:156
	v_add_f32_e32 v0, v23, v35
	v_add_f32_e32 v1, v19, v35
	ds_write2_b32 v4, v0, v1 offset0:172 offset1:188
	v_add_f32_e32 v0, v15, v35
	v_add_f32_e32 v1, v11, v35
	ds_write2_b32 v4, v0, v1 offset0:204 offset1:220
	v_add_f32_e32 v0, v7, v35
	v_add_f32_e32 v1, v3, v35
	v_ashrrev_i32_e32 v13, 4, v65
	ds_write2_b32 v4, v0, v1 offset0:236 offset1:252
	v_add_u32_e32 v14, s4, v13
	v_mov_b64_e32 v[0:1], s[2:3]
	v_mad_i64_i32 v[2:3], s[2:3], v14, s76, v[0:1]
	v_add_f32_e32 v24, v24, v32
	v_add_f32_e32 v28, v28, v32
	v_add_f32_e32 v20, v20, v32
	v_add_f32_e32 v16, v16, v32
	v_add_f32_e32 v12, v12, v32
	v_add_f32_e32 v8, v8, v32
	v_lshl_add_u64 v[2:3], v[2:3], 0, v[192:193]
	ds_write2_b32 v37, v24, v28 offset1:16
	ds_write2_b32 v37, v20, v16 offset0:32 offset1:48
	ds_write2_b32 v37, v12, v8 offset0:64 offset1:80
	s_waitcnt lgkmcnt(0)
	s_barrier
	global_load_dwordx4 v[18:21], v[2:3], off offset:3072
	v_add_u32_e32 v2, 0x200, v65
	v_ashrrev_i32_e32 v38, 4, v2
	v_add_u32_e32 v34, s4, v38
	v_mad_i64_i32 v[2:3], s[2:3], v34, s76, v[0:1]
	v_lshl_add_u64 v[2:3], v[2:3], 0, v[192:193]
	global_load_dwordx4 v[22:25], v[2:3], off offset:3072
	v_add_u32_e32 v2, 0x400, v65
	v_ashrrev_i32_e32 v39, 4, v2
	v_add_u32_e32 v16, s4, v39
	v_mad_i64_i32 v[2:3], s[2:3], v16, s76, v[0:1]
	v_lshl_add_u64 v[2:3], v[2:3], 0, v[192:193]
	global_load_dwordx4 v[4:7], v[2:3], off offset:3072
	v_add_u32_e32 v2, 0x600, v65
	v_ashrrev_i32_e32 v40, 4, v2
	v_add_u32_e32 v10, s4, v40
	v_mad_i64_i32 v[0:1], s[2:3], v10, s76, v[0:1]
	v_lshl_add_u64 v[0:1], v[0:1], 0, v[192:193]
	global_load_dwordx4 v[0:3], v[0:1], off offset:3072
	v_lshl_add_u32 v12, v183, 2, 0
	v_lshl_add_u64 v[8:9], s[0:1], 0, v[192:193]
	s_mov_b64 s[0:1], 0x14000800
	v_lshl_add_u64 v[8:9], v[8:9], 0, s[0:1]
	v_mad_u64_u32 v[30:31], s[0:1], v13, s66, v[12:13]
	ds_read_b128 v[26:29], v30 offset:36864
	ds_read_b128 v[30:33], v30 offset:36880
	v_ashrrev_i32_e32 v15, 31, v14
	v_lshlrev_b64 v[14:15], 12, v[14:15]
	v_lshl_add_u64 v[14:15], v[8:9], 0, v[14:15]
	v_ashrrev_i32_e32 v35, 31, v34
	v_ashrrev_i32_e32 v17, 31, v16
	v_ashrrev_i32_e32 v11, 31, v10
	s_waitcnt vmcnt(0) lgkmcnt(0)
	v_lshlrev_b32_e32 v36, 16, v18
	v_and_b32_e32 v37, 0xffff0000, v18
	v_pk_mul_f32 v[26:27], v[26:27], v[36:37]
	s_nop 0
	v_cvt_pk_bf16_f32 v18, v26, v27
	v_lshlrev_b32_e32 v26, 16, v19
	v_and_b32_e32 v27, 0xffff0000, v19
	v_pk_mul_f32 v[26:27], v[28:29], v[26:27]
	s_nop 0
	v_cvt_pk_bf16_f32 v19, v26, v27
	v_lshlrev_b32_e32 v26, 16, v20
	v_and_b32_e32 v27, 0xffff0000, v20
	v_pk_mul_f32 v[26:27], v[30:31], v[26:27]
	s_nop 0
	v_cvt_pk_bf16_f32 v20, v26, v27
	v_lshlrev_b32_e32 v26, 16, v21
	v_and_b32_e32 v27, 0xffff0000, v21
	v_pk_mul_f32 v[26:27], v[32:33], v[26:27]
	s_nop 0
	v_cvt_pk_bf16_f32 v21, v26, v27
	global_store_dwordx4 v[14:15], v[18:21], off
	v_mad_u64_u32 v[14:15], s[0:1], v38, s66, v[12:13]
	ds_read_b128 v[18:21], v14 offset:36864
	ds_read_b128 v[26:29], v14 offset:36880
	v_lshlrev_b32_e32 v14, 16, v22
	v_and_b32_e32 v15, 0xffff0000, v22
	s_waitcnt lgkmcnt(0)
	v_pk_mul_f32 v[14:15], v[18:19], v[14:15]
	s_nop 0
	v_cvt_pk_bf16_f32 v18, v14, v15
	v_lshlrev_b32_e32 v14, 16, v23
	v_and_b32_e32 v15, 0xffff0000, v23
	v_pk_mul_f32 v[14:15], v[20:21], v[14:15]
	s_nop 0
	v_cvt_pk_bf16_f32 v19, v14, v15
	v_lshlrev_b32_e32 v14, 16, v24
	v_and_b32_e32 v15, 0xffff0000, v24
	v_pk_mul_f32 v[14:15], v[26:27], v[14:15]
	s_nop 0
	v_cvt_pk_bf16_f32 v20, v14, v15
	v_lshlrev_b32_e32 v14, 16, v25
	v_and_b32_e32 v15, 0xffff0000, v25
	v_pk_mul_f32 v[14:15], v[28:29], v[14:15]
	s_nop 0
	v_cvt_pk_bf16_f32 v21, v14, v15
	v_lshlrev_b64 v[14:15], 12, v[34:35]
	v_lshl_add_u64 v[14:15], v[8:9], 0, v[14:15]
	global_store_dwordx4 v[14:15], v[18:21], off
	v_mad_u64_u32 v[14:15], s[0:1], v39, s66, v[12:13]
	ds_read_b128 v[18:21], v14 offset:36864
	ds_read_b128 v[22:25], v14 offset:36880
	v_lshlrev_b32_e32 v14, 16, v4
	v_and_b32_e32 v15, 0xffff0000, v4
	v_mad_u64_u32 v[12:13], s[0:1], v40, s66, v[12:13]
	s_waitcnt lgkmcnt(0)
	v_pk_mul_f32 v[14:15], v[18:19], v[14:15]
	s_nop 0
	v_cvt_pk_bf16_f32 v4, v14, v15
	v_lshlrev_b32_e32 v14, 16, v5
	v_and_b32_e32 v15, 0xffff0000, v5
	v_pk_mul_f32 v[14:15], v[20:21], v[14:15]
	s_nop 0
	v_cvt_pk_bf16_f32 v5, v14, v15
	v_lshlrev_b32_e32 v14, 16, v6
	v_and_b32_e32 v15, 0xffff0000, v6
	v_pk_mul_f32 v[14:15], v[22:23], v[14:15]
	s_nop 0
	v_cvt_pk_bf16_f32 v6, v14, v15
	v_lshlrev_b32_e32 v14, 16, v7
	v_and_b32_e32 v15, 0xffff0000, v7
	v_pk_mul_f32 v[14:15], v[24:25], v[14:15]
	s_nop 0
	v_cvt_pk_bf16_f32 v7, v14, v15
	v_lshlrev_b64 v[14:15], 12, v[16:17]
	v_lshl_add_u64 v[14:15], v[8:9], 0, v[14:15]
	global_store_dwordx4 v[14:15], v[4:7], off
	ds_read_b128 v[4:7], v12 offset:36864
	ds_read_b128 v[12:15], v12 offset:36880
	v_lshlrev_b32_e32 v16, 16, v0
	v_and_b32_e32 v17, 0xffff0000, v0
	s_waitcnt lgkmcnt(0)
	v_pk_mul_f32 v[4:5], v[4:5], v[16:17]
	s_nop 0
	v_cvt_pk_bf16_f32 v0, v4, v5
	v_lshlrev_b32_e32 v4, 16, v1
	v_and_b32_e32 v5, 0xffff0000, v1
	v_pk_mul_f32 v[4:5], v[6:7], v[4:5]
	s_nop 0
	v_cvt_pk_bf16_f32 v1, v4, v5
	v_lshlrev_b32_e32 v4, 16, v2
	v_and_b32_e32 v5, 0xffff0000, v2
	v_pk_mul_f32 v[4:5], v[12:13], v[4:5]
	s_nop 0
	v_cvt_pk_bf16_f32 v2, v4, v5
	v_lshlrev_b32_e32 v4, 16, v3
	v_and_b32_e32 v5, 0xffff0000, v3
	v_pk_mul_f32 v[4:5], v[14:15], v[4:5]
	s_nop 0
	v_cvt_pk_bf16_f32 v3, v4, v5
	v_lshlrev_b64 v[4:5], 12, v[10:11]
	v_lshl_add_u64 v[4:5], v[8:9], 0, v[4:5]
	global_store_dwordx4 v[4:5], v[0:3], off
	s_waitcnt lgkmcnt(0)
	s_barrier

.LBB0_142:
	s_or_b64 exec, exec, s[0:1]
	v_lshlrev_b32_e32 v47, 16, v47
	v_lshlrev_b32_e32 v136, 16, v36
	v_mul_f32_e32 v36, v165, v47
	v_fmac_f32_e32 v36, v163, v136
	s_waitcnt lgkmcnt(1)
	v_lshlrev_b32_e32 v135, 16, v135
	v_fmac_f32_e32 v36, v164, v135
	v_lshlrev_b32_e32 v49, 16, v49
	v_mul_f32_e32 v36, v36, v49
	v_lshlrev_b32_e32 v49, 16, v42
	v_mul_f32_e32 v42, v165, v136
	v_fmac_f32_e32 v42, v163, v49
	v_fmac_f32_e32 v42, v164, v47
	v_lshlrev_b32_e32 v47, 16, v134
	v_mul_f32_e32 v42, v42, v47
	v_lshlrev_b32_e32 v47, 16, v46
	v_mul_f32_e32 v46, v165, v49
	v_fmac_f32_e32 v46, v163, v47
	v_fmac_f32_e32 v46, v164, v136
	v_lshlrev_b32_e32 v133, 16, v133
	v_mul_f32_e32 v46, v46, v133
	v_lshlrev_b32_e32 v133, 16, v45
	v_mul_f32_e32 v45, v165, v47
	v_fmac_f32_e32 v45, v163, v133
	v_fmac_f32_e32 v45, v164, v49
	v_lshlrev_b32_e32 v49, 16, v131
	v_mul_f32_e32 v45, v45, v49
	v_lshlrev_b32_e32 v49, 16, v44
	v_mul_f32_e32 v44, v165, v133
	v_fmac_f32_e32 v44, v163, v49
	v_fmac_f32_e32 v44, v164, v47
	v_lshlrev_b32_e32 v47, 16, v129
	v_mul_f32_e32 v44, v44, v47
	v_lshlrev_b32_e32 v47, 16, v43
	v_mul_f32_e32 v43, v165, v49
	v_fmac_f32_e32 v43, v163, v47
	v_fmac_f32_e32 v43, v164, v133
	v_lshlrev_b32_e32 v127, 16, v127
	v_mul_f32_e32 v43, v43, v127
	v_lshlrev_b32_e32 v127, 16, v41
	v_mul_f32_e32 v41, v165, v47
	v_fmac_f32_e32 v41, v163, v127
	v_fmac_f32_e32 v41, v164, v49
	v_lshlrev_b32_e32 v49, 16, v59
	v_mul_f32_e32 v41, v41, v49
	v_lshlrev_b32_e32 v49, 16, v40
	v_mul_f32_e32 v40, v165, v127
	v_fmac_f32_e32 v40, v163, v49
	v_fmac_f32_e32 v40, v164, v47
	v_lshlrev_b32_e32 v47, 16, v58
	v_mul_f32_e32 v40, v40, v47
	v_lshlrev_b32_e32 v47, 16, v39
	v_mul_f32_e32 v39, v165, v49
	v_fmac_f32_e32 v39, v163, v47
	v_fmac_f32_e32 v39, v164, v127
	v_lshlrev_b32_e32 v56, 16, v56
	v_mul_f32_e32 v39, v39, v56
	v_lshlrev_b32_e32 v56, 16, v38
	v_mul_f32_e32 v38, v165, v47
	v_fmac_f32_e32 v38, v163, v56
	v_fmac_f32_e32 v38, v164, v49
	v_lshlrev_b32_e32 v49, 16, v57
	v_mul_f32_e32 v38, v38, v49
	v_lshlrev_b32_e32 v49, 16, v37
	v_mul_f32_e32 v37, v165, v56
	v_fmac_f32_e32 v37, v163, v49
	v_fmac_f32_e32 v37, v164, v47
	v_lshlrev_b32_e32 v47, 16, v55
	v_mul_f32_e32 v37, v37, v47
	v_lshlrev_b32_e32 v47, 16, v35
	v_mul_f32_e32 v35, v165, v49
	v_fmac_f32_e32 v35, v163, v47
	v_fmac_f32_e32 v35, v164, v56
	v_lshlrev_b32_e32 v54, 16, v54
	v_mul_f32_e32 v35, v35, v54
	v_lshlrev_b32_e32 v34, 16, v34
	v_mul_f32_e32 v54, v165, v47
	v_fmac_f32_e32 v54, v163, v34
	v_fmac_f32_e32 v54, v164, v49
	v_lshlrev_b32_e32 v49, 16, v53
	v_mul_f32_e32 v127, v54, v49
	v_lshlrev_b32_e32 v33, 16, v33
	v_mul_f32_e32 v49, v165, v34
	v_fmac_f32_e32 v49, v163, v33
	v_fmac_f32_e32 v49, v164, v47
	v_lshlrev_b32_e32 v47, 16, v52
	v_mul_f32_e32 v47, v49, v47
	v_lshlrev_b32_e32 v32, 16, v32
	v_mul_f32_e32 v49, v165, v33
	v_fmac_f32_e32 v49, v163, v32
	v_lshlrev_b32_e32 v48, 16, v48
	v_mul_f32_e32 v32, v165, v32
	v_fmac_f32_e32 v32, v163, v48
	v_fmac_f32_e32 v32, v164, v33
	v_lshlrev_b32_e32 v33, 16, v50
	v_readlane_b32 s0, v251, 9
	v_fmac_f32_e32 v49, v164, v34
	v_lshlrev_b32_e32 v34, 16, v51
	v_mul_f32_e32 v32, v32, v33
	v_mov_b32_e32 v33, s0
	s_add_i32 s0, 0, 0x22010
	v_mul_f32_e32 v34, v49, v34
	s_waitcnt lgkmcnt(0)
	s_barrier
	ds_read_b128 v[48:51], v33
	v_mov_b32_e32 v33, s0
	s_add_i32 s0, 0, 0x22020
	ds_read_b128 v[52:55], v33
	v_mov_b32_e32 v33, s0
	s_add_i32 s0, 0, 0x22030
	ds_read_b128 v[56:59], v33
	v_mov_b32_e32 v33, s0
	ds_read_b128 v[134:137], v33
	s_waitcnt lgkmcnt(3)
	v_add_f32_e32 v33, v48, v50
	s_waitcnt lgkmcnt(2)
	v_add_f32_e32 v48, v52, v54
	v_add_f32_e32 v33, v33, v48
	s_waitcnt lgkmcnt(1)
	v_add_f32_e32 v48, v56, v58
	v_add_f32_e32 v33, v33, v48
	s_waitcnt lgkmcnt(0)
	v_add_f32_e32 v48, v134, v136
	v_add_f32_e32 v33, v33, v48
	v_add_f32_e32 v48, v49, v51
	v_add_f32_e32 v49, v53, v55
	v_add_f32_e32 v48, v48, v49
	v_add_f32_e32 v49, v57, v59
	v_add_f32_e32 v48, v48, v49
	v_add_f32_e32 v49, v135, v137
	v_add_f32_e32 v48, v48, v49
	v_mul_f32_e32 v49, 0x3b000000, v33
	v_mul_f32_e32 v49, v49, v49
	s_mov_b32 s12, 0x3b000000
	v_fma_f32 v48, v48, s12, -v49
	v_max_f32_e32 v48, 0, v48
	v_add_f32_e32 v48, 0x358637bd, v48
	v_rsq_f32_e32 v48, v48
	v_fmac_f32_e32 v31, 0xbb000000, v33
	v_cvt_pk_bf16_f32 v14, v14, s0
	ds_write_b16 v175, v14
	v_mul_f32_e32 v31, v31, v48
	v_fma_f32 v31, v143, v31, v142
	v_cvt_pk_bf16_f32 v14, v32, s0
	ds_write_b16 v175, v14 offset:16384
	v_mul_f32_e32 v14, 0xbfb8aa3b, v31
	v_exp_f32_e32 v14, v14
	s_or_b32 s26, s56, s3
	v_readlane_b32 s56, v253, 8
	v_readlane_b32 s62, v253, 14
	v_add_f32_e32 v14, 1.0, v14
	v_rcp_f32_e32 v14, v14
	v_readlane_b32 s63, v253, 15
	s_ashr_i32 s27, s26, 31
	v_mov_b32_e32 v129, v193
	v_mul_f32_e32 v14, v31, v14
	v_cvt_pk_bf16_f32 v14, v14, s0
	v_readlane_b32 s0, v251, 10
	ds_write_b16 v175, v14 offset:32768
	v_mov_b32_e32 v131, v193
	v_mov_b32_e32 v14, s0
	v_readlane_b32 s0, v251, 17
	ds_read_b128 v[48:51], v14
	v_mov_b32_e32 v133, v193
	v_mov_b32_e32 v14, s0
	v_readlane_b32 s0, v251, 24
	ds_read_b128 v[52:55], v14
	v_readlane_b32 s57, v253, 9
	v_mov_b32_e32 v14, s0
	v_readlane_b32 s0, v251, 31
	ds_read_b128 v[56:59], v14
	s_waitcnt lgkmcnt(1)
	v_add_f32_e32 v31, v52, v54
	v_mov_b32_e32 v14, s0
	ds_read_b128 v[134:137], v14
	v_add_f32_e32 v14, v48, v50
	v_add_f32_e32 v14, v14, v31
	s_waitcnt lgkmcnt(1)
	v_add_f32_e32 v31, v56, v58
	v_add_f32_e32 v14, v14, v31
	s_waitcnt lgkmcnt(0)
	v_add_f32_e32 v31, v134, v136
	v_add_f32_e32 v14, v14, v31
	v_add_f32_e32 v31, v49, v51
	v_add_f32_e32 v32, v53, v55
	v_add_f32_e32 v31, v31, v32
	v_add_f32_e32 v32, v57, v59
	v_add_f32_e32 v31, v31, v32
	v_add_f32_e32 v32, v135, v137
	v_add_f32_e32 v31, v31, v32
	v_mul_f32_e32 v32, 0x3b000000, v14
	v_mul_f32_e32 v32, v32, v32
	v_fma_f32 v31, v31, s12, -v32
	v_max_f32_e32 v31, 0, v31
	v_add_f32_e32 v31, 0x358637bd, v31
	v_rsq_f32_e32 v31, v31
	v_fmac_f32_e32 v30, 0xbb000000, v14
	v_cvt_pk_bf16_f32 v15, v15, s0
	ds_write_b16 v175, v15 offset:1024
	v_mul_f32_e32 v14, v30, v31
	v_fma_f32 v14, v143, v14, v142
	v_cvt_pk_bf16_f32 v15, v34, s0
	ds_write_b16 v175, v15 offset:17408
	v_mul_f32_e32 v15, 0xbfb8aa3b, v14
	v_exp_f32_e32 v15, v15
	v_readlane_b32 s58, v253, 10
	v_readlane_b32 s59, v253, 11
	v_readlane_b32 s60, v253, 12
	v_add_f32_e32 v15, 1.0, v15
	v_rcp_f32_e32 v15, v15
	v_readlane_b32 s61, v253, 13
	v_mul_f32_e32 v14, v14, v15
	v_cvt_pk_bf16_f32 v14, v14, s0
	v_readlane_b32 s0, v251, 11
	ds_write_b16 v175, v14 offset:33792
	s_nop 0
	v_mov_b32_e32 v14, s0
	v_readlane_b32 s0, v251, 18
	ds_read_b128 v[30:33], v14
	s_nop 0
	v_mov_b32_e32 v14, s0
	v_readlane_b32 s0, v251, 25
	ds_read_b128 v[48:51], v14
	s_waitcnt lgkmcnt(0)
	v_add_f32_e32 v15, v48, v50
	v_mov_b32_e32 v14, s0
	v_readlane_b32 s0, v251, 32
	ds_read_b128 v[52:55], v14
	s_nop 0
	v_mov_b32_e32 v14, s0
	ds_read_b128 v[56:59], v14
	v_add_f32_e32 v14, v30, v32
	v_add_f32_e32 v14, v14, v15
	s_waitcnt lgkmcnt(1)
	v_add_f32_e32 v15, v52, v54
	v_add_f32_e32 v14, v14, v15
	s_waitcnt lgkmcnt(0)
	v_add_f32_e32 v15, v56, v58
	v_add_f32_e32 v14, v14, v15
	v_add_f32_e32 v15, v31, v33
	v_add_f32_e32 v30, v49, v51
	v_add_f32_e32 v15, v15, v30
	v_add_f32_e32 v30, v53, v55
	v_add_f32_e32 v15, v15, v30
	v_add_f32_e32 v30, v57, v59
	v_add_f32_e32 v15, v15, v30
	v_mul_f32_e32 v30, 0x3b000000, v14
	v_mul_f32_e32 v30, v30, v30
	v_fma_f32 v15, v15, s12, -v30
	v_max_f32_e32 v15, 0, v15
	v_add_f32_e32 v15, 0x358637bd, v15
	v_rsq_f32_e32 v15, v15
	v_fmac_f32_e32 v29, 0xbb000000, v14
	v_cvt_pk_bf16_f32 v12, v12, s0
	ds_write_b16 v175, v12 offset:2048
	v_mul_f32_e32 v14, v29, v15
	v_fma_f32 v14, v143, v14, v142
	v_cvt_pk_bf16_f32 v12, v47, s0
	ds_write_b16 v175, v12 offset:18432
	v_mul_f32_e32 v12, 0xbfb8aa3b, v14
	v_exp_f32_e32 v12, v12
	s_nop 0
	v_add_f32_e32 v12, 1.0, v12
	v_rcp_f32_e32 v12, v12
	s_nop 0
	v_mul_f32_e32 v12, v14, v12
	v_cvt_pk_bf16_f32 v12, v12, s0
	v_readlane_b32 s0, v251, 12
	ds_write_b16 v175, v12 offset:34816
	s_nop 0
	v_mov_b32_e32 v12, s0
	v_readlane_b32 s0, v251, 19
	ds_read_b128 v[30:33], v12
	s_nop 0
	v_mov_b32_e32 v12, s0
	v_readlane_b32 s0, v251, 26
	ds_read_b128 v[48:51], v12
	s_waitcnt lgkmcnt(0)
	v_add_f32_e32 v14, v48, v50
	v_mov_b32_e32 v12, s0
	v_readlane_b32 s0, v251, 33
	ds_read_b128 v[52:55], v12
	v_add_f32_e32 v15, v49, v51
	v_mov_b32_e32 v12, s0
	ds_read_b128 v[56:59], v12
	v_add_f32_e32 v12, v30, v32
	v_add_f32_e32 v12, v12, v14
	s_waitcnt lgkmcnt(1)
	v_add_f32_e32 v14, v52, v54
	v_add_f32_e32 v12, v12, v14
	s_waitcnt lgkmcnt(0)
	v_add_f32_e32 v14, v56, v58
	v_add_f32_e32 v12, v12, v14
	v_add_f32_e32 v14, v31, v33
	v_add_f32_e32 v14, v14, v15
	v_add_f32_e32 v15, v53, v55
	v_add_f32_e32 v14, v14, v15
	v_add_f32_e32 v15, v57, v59
	v_add_f32_e32 v14, v14, v15
	v_mul_f32_e32 v15, 0x3b000000, v12
	v_mul_f32_e32 v15, v15, v15
	v_fma_f32 v14, v14, s12, -v15
	v_max_f32_e32 v14, 0, v14
	v_add_f32_e32 v14, 0x358637bd, v14
	v_rsq_f32_e32 v14, v14
	v_fmac_f32_e32 v28, 0xbb000000, v12
	v_cvt_pk_bf16_f32 v13, v13, s0
	ds_write_b16 v175, v13 offset:3072
	v_mul_f32_e32 v12, v28, v14
	v_fma_f32 v12, v143, v12, v142
	v_cvt_pk_bf16_f32 v13, v127, s0
	ds_write_b16 v175, v13 offset:19456
	v_mul_f32_e32 v13, 0xbfb8aa3b, v12
	v_exp_f32_e32 v13, v13
	v_mov_b32_e32 v127, v193
	v_add_f32_e32 v13, 1.0, v13
	v_rcp_f32_e32 v13, v13
	s_nop 0
	v_mul_f32_e32 v12, v12, v13
	v_cvt_pk_bf16_f32 v12, v12, s0
	v_readlane_b32 s0, v251, 13
	ds_write_b16 v175, v12 offset:35840
	s_nop 0
	v_mov_b32_e32 v12, s0
	v_readlane_b32 s0, v251, 20
	ds_read_b128 v[12:15], v12
	s_nop 0
	v_mov_b32_e32 v28, s0
	v_readlane_b32 s0, v251, 27
	ds_read_b128 v[28:31], v28
	s_waitcnt lgkmcnt(1)
	v_add_f32_e32 v12, v12, v14
	v_mov_b32_e32 v32, s0
	v_readlane_b32 s0, v251, 34
	ds_read_b128 v[48:51], v32
	s_waitcnt lgkmcnt(1)
	v_add_f32_e32 v14, v28, v30
	v_mov_b32_e32 v32, s0
	ds_read_b128 v[52:55], v32
	v_add_f32_e32 v12, v12, v14
	s_waitcnt lgkmcnt(1)
	v_add_f32_e32 v14, v48, v50
	v_add_f32_e32 v12, v12, v14
	v_add_f32_e32 v13, v13, v15
	s_waitcnt lgkmcnt(0)
	v_add_f32_e32 v14, v52, v54
	v_add_f32_e32 v12, v12, v14
	v_add_f32_e32 v14, v29, v31
	v_add_f32_e32 v13, v13, v14
	v_add_f32_e32 v14, v49, v51
	v_add_f32_e32 v13, v13, v14
	v_add_f32_e32 v14, v53, v55
	v_add_f32_e32 v13, v13, v14
	v_mul_f32_e32 v14, 0x3b000000, v12
	v_mul_f32_e32 v14, v14, v14
	v_fma_f32 v13, v13, s12, -v14
	v_max_f32_e32 v13, 0, v13
	v_add_f32_e32 v13, 0x358637bd, v13
	v_rsq_f32_e32 v13, v13
	v_fmac_f32_e32 v27, 0xbb000000, v12
	v_cvt_pk_bf16_f32 v4, v4, s0
	ds_write_b16 v175, v4 offset:4096
	v_mul_f32_e32 v12, v27, v13
	v_fma_f32 v12, v143, v12, v142
	v_cvt_pk_bf16_f32 v4, v35, s0
	ds_write_b16 v175, v4 offset:20480
	v_mul_f32_e32 v4, 0xbfb8aa3b, v12
	v_exp_f32_e32 v4, v4
	s_nop 0
	v_add_f32_e32 v4, 1.0, v4
	v_rcp_f32_e32 v4, v4
	s_nop 0
	v_mul_f32_e32 v4, v12, v4
	v_cvt_pk_bf16_f32 v4, v4, s0
	v_readlane_b32 s0, v251, 14
	ds_write_b16 v175, v4 offset:36864
	s_nop 0
	v_mov_b32_e32 v4, s0
	v_readlane_b32 s0, v251, 21
	ds_read_b128 v[12:15], v4
	s_nop 0
	v_mov_b32_e32 v4, s0
	v_readlane_b32 s0, v251, 28
	ds_read_b128 v[28:31], v4
	s_nop 0
	v_mov_b32_e32 v4, s0
	v_readlane_b32 s0, v251, 35
	ds_read_b128 v[32:35], v4
	s_nop 0
	v_mov_b32_e32 v4, s0
	ds_read_b128 v[48:51], v4
	s_waitcnt lgkmcnt(3)
	v_add_f32_e32 v4, v12, v14
	s_waitcnt lgkmcnt(2)
	v_add_f32_e32 v12, v28, v30
	v_add_f32_e32 v4, v4, v12
	s_waitcnt lgkmcnt(1)
	v_add_f32_e32 v12, v32, v34
	v_add_f32_e32 v4, v4, v12
	s_waitcnt lgkmcnt(0)
	v_add_f32_e32 v12, v48, v50
	v_add_f32_e32 v4, v4, v12
	v_add_f32_e32 v12, v13, v15
	v_add_f32_e32 v13, v29, v31
	v_add_f32_e32 v12, v12, v13
	v_add_f32_e32 v13, v33, v35
	v_add_f32_e32 v12, v12, v13
	v_add_f32_e32 v13, v49, v51
	v_add_f32_e32 v12, v12, v13
	v_mul_f32_e32 v13, 0x3b000000, v4
	v_mul_f32_e32 v13, v13, v13
	v_fma_f32 v12, v12, s12, -v13
	v_max_f32_e32 v12, 0, v12
	v_add_f32_e32 v12, 0x358637bd, v12
	v_rsq_f32_e32 v12, v12
	v_fmac_f32_e32 v26, 0xbb000000, v4
	v_cvt_pk_bf16_f32 v5, v5, s0
	ds_write_b16 v175, v5 offset:5120
	v_mul_f32_e32 v4, v26, v12
	v_fma_f32 v4, v143, v4, v142
	v_cvt_pk_bf16_f32 v5, v37, s0
	ds_write_b16 v175, v5 offset:21504
	v_mul_f32_e32 v5, 0xbfb8aa3b, v4
	v_exp_f32_e32 v5, v5
	s_nop 0
	v_add_f32_e32 v5, 1.0, v5
	v_rcp_f32_e32 v5, v5
	s_nop 0
	v_mul_f32_e32 v4, v4, v5
	v_cvt_pk_bf16_f32 v4, v4, s0
	v_readlane_b32 s0, v251, 15
	ds_write_b16 v175, v4 offset:37888
	s_nop 0
	v_mov_b32_e32 v4, s0
	v_readlane_b32 s0, v251, 22
	ds_read_b128 v[12:15], v4
	s_nop 0
	v_mov_b32_e32 v4, s0
	v_readlane_b32 s0, v251, 29
	ds_read_b128 v[26:29], v4
	s_waitcnt lgkmcnt(0)
	v_add_f32_e32 v5, v26, v28
	v_mov_b32_e32 v4, s0
	v_readlane_b32 s0, v251, 36
	ds_read_b128 v[30:33], v4
	s_nop 0
	v_mov_b32_e32 v4, s0
	ds_read_b128 v[48:51], v4
	v_add_f32_e32 v4, v12, v14
	v_add_f32_e32 v4, v4, v5
	s_waitcnt lgkmcnt(1)
	v_add_f32_e32 v5, v30, v32
	v_add_f32_e32 v4, v4, v5
	s_waitcnt lgkmcnt(0)
	v_add_f32_e32 v5, v48, v50
	v_add_f32_e32 v4, v4, v5
	v_add_f32_e32 v5, v13, v15
	v_add_f32_e32 v12, v27, v29
	v_add_f32_e32 v5, v5, v12
	v_add_f32_e32 v12, v31, v33
	v_add_f32_e32 v5, v5, v12
	v_add_f32_e32 v12, v49, v51
	v_add_f32_e32 v5, v5, v12
	v_mul_f32_e32 v12, 0x3b000000, v4
	v_mul_f32_e32 v12, v12, v12
	v_fma_f32 v5, v5, s12, -v12
	v_max_f32_e32 v5, 0, v5
	v_add_f32_e32 v5, 0x358637bd, v5
	v_rsq_f32_e32 v5, v5
	v_fmac_f32_e32 v25, 0xbb000000, v4
	v_cvt_pk_bf16_f32 v0, v0, s0
	ds_write_b16 v175, v0 offset:6144
	v_mul_f32_e32 v4, v25, v5
	v_fma_f32 v4, v143, v4, v142
	v_cvt_pk_bf16_f32 v0, v38, s0
	ds_write_b16 v175, v0 offset:22528
	v_mul_f32_e32 v0, 0xbfb8aa3b, v4
	v_exp_f32_e32 v0, v0
	s_nop 0
	v_add_f32_e32 v0, 1.0, v0
	v_rcp_f32_e32 v0, v0
	s_nop 0
	v_mul_f32_e32 v0, v4, v0
	v_cvt_pk_bf16_f32 v0, v0, s0
	v_readlane_b32 s0, v251, 16
	ds_write_b16 v175, v0 offset:38912
	s_nop 0
	v_mov_b32_e32 v0, s0
	v_readlane_b32 s0, v251, 23
	ds_read_b128 v[12:15], v0
	s_nop 0
	v_mov_b32_e32 v0, s0
	v_readlane_b32 s0, v251, 30
	ds_read_b128 v[26:29], v0
	s_waitcnt lgkmcnt(0)
	v_add_f32_e32 v4, v26, v28
	v_mov_b32_e32 v0, s0
	v_readlane_b32 s0, v251, 37
	ds_read_b128 v[30:33], v0
	v_add_f32_e32 v5, v27, v29
	v_mov_b32_e32 v0, s0
	ds_read_b128 v[48:51], v0
	v_add_f32_e32 v0, v12, v14
	v_add_f32_e32 v0, v0, v4
	s_waitcnt lgkmcnt(1)
	v_add_f32_e32 v4, v30, v32
	v_add_f32_e32 v0, v0, v4
	s_waitcnt lgkmcnt(0)
	v_add_f32_e32 v4, v48, v50
	v_add_f32_e32 v0, v0, v4
	v_add_f32_e32 v4, v13, v15
	v_add_f32_e32 v4, v4, v5
	v_add_f32_e32 v5, v31, v33
	v_add_f32_e32 v4, v4, v5
	v_add_f32_e32 v5, v49, v51
	v_add_f32_e32 v4, v4, v5
	v_mul_f32_e32 v5, 0x3b000000, v0
	v_mul_f32_e32 v5, v5, v5
	v_fma_f32 v4, v4, s12, -v5
	v_max_f32_e32 v4, 0, v4
	v_add_f32_e32 v4, 0x358637bd, v4
	v_rsq_f32_e32 v4, v4
	v_fmac_f32_e32 v23, 0xbb000000, v0
	v_cvt_pk_bf16_f32 v1, v1, s0
	ds_write_b16 v175, v1 offset:7168
	v_mul_f32_e32 v0, v23, v4
	v_fma_f32 v0, v143, v0, v142
	v_cvt_pk_bf16_f32 v1, v39, s0
	ds_write_b16 v175, v1 offset:23552
	v_mul_f32_e32 v1, 0xbfb8aa3b, v0
	v_exp_f32_e32 v1, v1
	s_nop 0
	v_add_f32_e32 v1, 1.0, v1
	v_rcp_f32_e32 v1, v1
	s_nop 0
	v_mul_f32_e32 v0, v0, v1
	v_cvt_pk_bf16_f32 v0, v0, s0
	v_readlane_b32 s0, v252, 2
	ds_write_b16 v175, v0 offset:39936
	s_nop 0
	v_mov_b32_e32 v0, s0
	v_readlane_b32 s0, v252, 3
	ds_read_b128 v[12:15], v0
	s_nop 0
	v_mov_b32_e32 v0, s0
	v_readlane_b32 s0, v252, 4
	ds_read_b128 v[26:29], v0
	s_waitcnt lgkmcnt(0)
	v_add_f32_e32 v1, v26, v28
	v_mov_b32_e32 v0, s0
	v_readlane_b32 s0, v252, 5
	ds_read_b128 v[30:33], v0
	v_add_f32_e32 v4, v27, v29
	v_mov_b32_e32 v0, s0
	ds_read_b128 v[48:51], v0
	v_add_f32_e32 v0, v12, v14
	v_add_f32_e32 v0, v0, v1
	s_waitcnt lgkmcnt(1)
	v_add_f32_e32 v1, v30, v32
	v_add_f32_e32 v0, v0, v1
	s_waitcnt lgkmcnt(0)
	v_add_f32_e32 v1, v48, v50
	v_add_f32_e32 v0, v0, v1
	v_add_f32_e32 v1, v13, v15
	v_add_f32_e32 v1, v1, v4
	v_add_f32_e32 v4, v31, v33
	v_add_f32_e32 v1, v1, v4
	v_add_f32_e32 v4, v49, v51
	v_add_f32_e32 v1, v1, v4
	v_mul_f32_e32 v4, 0x3b000000, v0
	v_mul_f32_e32 v4, v4, v4
	v_fma_f32 v1, v1, s12, -v4
	v_max_f32_e32 v1, 0, v1
	v_add_f32_e32 v1, 0x358637bd, v1
	v_rsq_f32_e32 v1, v1
	v_fmac_f32_e32 v24, 0xbb000000, v0
	v_mul_f32_e32 v0, v24, v1
	v_cvt_pk_bf16_f32 v1, v10, s0
	v_fma_f32 v0, v143, v0, v142
	ds_write_b16 v175, v1 offset:8192
	v_cvt_pk_bf16_f32 v1, v40, s0
	ds_write_b16 v175, v1 offset:24576
	v_mul_f32_e32 v1, 0xbfb8aa3b, v0
	v_exp_f32_e32 v1, v1
	s_nop 0
	v_add_f32_e32 v1, 1.0, v1
	v_rcp_f32_e32 v1, v1
	s_nop 0
	v_mul_f32_e32 v0, v0, v1
	v_cvt_pk_bf16_f32 v0, v0, s0
	v_readlane_b32 s0, v252, 6
	ds_write_b16 v175, v0 offset:40960
	s_nop 0
	v_mov_b32_e32 v0, s0
	v_readlane_b32 s0, v252, 7
	ds_read_b128 v[12:15], v0
	s_nop 0
	v_mov_b32_e32 v0, s0
	v_readlane_b32 s0, v252, 8
	ds_read_b128 v[24:27], v0
	s_waitcnt lgkmcnt(0)
	v_add_f32_e32 v1, v24, v26
	v_mov_b32_e32 v0, s0
	v_readlane_b32 s0, v252, 9
	ds_read_b128 v[28:31], v0
	v_add_f32_e32 v4, v25, v27
	v_mov_b32_e32 v0, s0
	ds_read_b128 v[32:35], v0
	v_add_f32_e32 v0, v12, v14
	v_add_f32_e32 v0, v0, v1
	s_waitcnt lgkmcnt(1)
	v_add_f32_e32 v1, v28, v30
	v_add_f32_e32 v0, v0, v1
	s_waitcnt lgkmcnt(0)
	v_add_f32_e32 v1, v32, v34
	v_add_f32_e32 v0, v0, v1
	v_add_f32_e32 v1, v13, v15
	v_add_f32_e32 v1, v1, v4
	v_add_f32_e32 v4, v29, v31
	v_add_f32_e32 v1, v1, v4
	v_add_f32_e32 v4, v33, v35
	v_add_f32_e32 v1, v1, v4
	v_mul_f32_e32 v4, 0x3b000000, v0
	v_mul_f32_e32 v4, v4, v4
	v_fma_f32 v1, v1, s12, -v4
	v_max_f32_e32 v1, 0, v1
	v_add_f32_e32 v1, 0x358637bd, v1
	v_rsq_f32_e32 v1, v1
	v_fmac_f32_e32 v22, 0xbb000000, v0
	v_mul_f32_e32 v0, v22, v1
	v_cvt_pk_bf16_f32 v1, v11, s0
	v_fma_f32 v0, v143, v0, v142
	ds_write_b16 v175, v1 offset:9216
	v_cvt_pk_bf16_f32 v1, v41, s0
	ds_write_b16 v175, v1 offset:25600
	v_mul_f32_e32 v1, 0xbfb8aa3b, v0
	v_exp_f32_e32 v1, v1
	s_nop 0
	v_add_f32_e32 v1, 1.0, v1
	v_rcp_f32_e32 v1, v1
	s_nop 0
	v_mul_f32_e32 v0, v0, v1
	v_cvt_pk_bf16_f32 v0, v0, s0
	v_readlane_b32 s0, v252, 10
	ds_write_b16 v175, v0 offset:41984
	s_nop 0
	v_mov_b32_e32 v0, s0
	v_readlane_b32 s0, v252, 11
	ds_read_b128 v[10:13], v0
	s_nop 0
	v_mov_b32_e32 v0, s0
	v_readlane_b32 s0, v252, 12
	ds_read_b128 v[22:25], v0
	s_waitcnt lgkmcnt(0)
	v_add_f32_e32 v1, v22, v24
	v_mov_b32_e32 v0, s0
	v_readlane_b32 s0, v252, 13
	ds_read_b128 v[26:29], v0
	v_add_f32_e32 v4, v23, v25
	v_mov_b32_e32 v0, s0
	ds_read_b128 v[30:33], v0
	v_add_f32_e32 v0, v10, v12
	v_add_f32_e32 v0, v0, v1
	s_waitcnt lgkmcnt(1)
	v_add_f32_e32 v1, v26, v28
	v_add_f32_e32 v0, v0, v1
	s_waitcnt lgkmcnt(0)
	v_add_f32_e32 v1, v30, v32
	v_add_f32_e32 v0, v0, v1
	v_add_f32_e32 v1, v11, v13
	v_add_f32_e32 v1, v1, v4
	v_add_f32_e32 v4, v27, v29
	v_add_f32_e32 v1, v1, v4
	v_add_f32_e32 v4, v31, v33
	v_add_f32_e32 v1, v1, v4
	v_mul_f32_e32 v4, 0x3b000000, v0
	v_mul_f32_e32 v4, v4, v4
	v_fma_f32 v1, v1, s12, -v4
	v_max_f32_e32 v1, 0, v1
	v_add_f32_e32 v1, 0x358637bd, v1
	v_rsq_f32_e32 v1, v1
	v_fmac_f32_e32 v21, 0xbb000000, v0
	v_mul_f32_e32 v0, v21, v1
	v_cvt_pk_bf16_f32 v1, v8, s0
	v_fma_f32 v0, v143, v0, v142
	ds_write_b16 v175, v1 offset:10240
	v_cvt_pk_bf16_f32 v1, v43, s0
	ds_write_b16 v175, v1 offset:26624
	v_mul_f32_e32 v1, 0xbfb8aa3b, v0
	v_exp_f32_e32 v1, v1
	s_nop 0
	v_add_f32_e32 v1, 1.0, v1
	v_rcp_f32_e32 v1, v1
	s_nop 0
	v_mul_f32_e32 v0, v0, v1
	v_cvt_pk_bf16_f32 v0, v0, s0
	v_readlane_b32 s0, v252, 14
	ds_write_b16 v175, v0 offset:43008
	s_nop 0
	v_mov_b32_e32 v0, s0
	v_readlane_b32 s0, v252, 15
	ds_read_b128 v[10:13], v0
	s_nop 0
	v_mov_b32_e32 v0, s0
	v_readlane_b32 s0, v252, 16
	ds_read_b128 v[22:25], v0
	s_waitcnt lgkmcnt(0)
	v_add_f32_e32 v1, v22, v24
	v_mov_b32_e32 v0, s0
	v_readlane_b32 s0, v252, 17
	ds_read_b128 v[26:29], v0
	v_add_f32_e32 v4, v23, v25
	v_mov_b32_e32 v0, s0
	ds_read_b128 v[30:33], v0
	v_add_f32_e32 v0, v10, v12
	v_add_f32_e32 v0, v0, v1
	s_waitcnt lgkmcnt(1)
	v_add_f32_e32 v1, v26, v28
	v_add_f32_e32 v0, v0, v1
	s_waitcnt lgkmcnt(0)
	v_add_f32_e32 v1, v30, v32
	v_add_f32_e32 v0, v0, v1
	v_add_f32_e32 v1, v11, v13
	v_add_f32_e32 v1, v1, v4
	v_add_f32_e32 v4, v27, v29
	v_add_f32_e32 v1, v1, v4
	v_add_f32_e32 v4, v31, v33
	v_add_f32_e32 v1, v1, v4
	v_mul_f32_e32 v4, 0x3b000000, v0
	v_mul_f32_e32 v4, v4, v4
	v_fma_f32 v1, v1, s12, -v4
	v_max_f32_e32 v1, 0, v1
	v_add_f32_e32 v1, 0x358637bd, v1
	v_rsq_f32_e32 v1, v1
	v_fmac_f32_e32 v20, 0xbb000000, v0
	v_mul_f32_e32 v0, v20, v1
	v_cvt_pk_bf16_f32 v1, v9, s0
	v_fma_f32 v0, v143, v0, v142
	ds_write_b16 v175, v1 offset:11264
	v_cvt_pk_bf16_f32 v1, v44, s0
	ds_write_b16 v175, v1 offset:27648
	v_mul_f32_e32 v1, 0xbfb8aa3b, v0
	v_exp_f32_e32 v1, v1
	s_nop 0
	v_add_f32_e32 v1, 1.0, v1
	v_rcp_f32_e32 v1, v1
	s_nop 0
	v_mul_f32_e32 v0, v0, v1
	v_cvt_pk_bf16_f32 v0, v0, s0
	v_readlane_b32 s0, v252, 18
	ds_write_b16 v175, v0 offset:44032
	s_nop 0
	v_mov_b32_e32 v0, s0
	v_readlane_b32 s0, v252, 19
	ds_read_b128 v[8:11], v0
	s_nop 0
	v_mov_b32_e32 v0, s0
	v_readlane_b32 s0, v252, 20
	ds_read_b128 v[12:15], v0
	s_waitcnt lgkmcnt(0)
	v_add_f32_e32 v1, v12, v14
	v_mov_b32_e32 v0, s0
	v_readlane_b32 s0, v252, 21
	ds_read_b128 v[20:23], v0
	v_add_f32_e32 v4, v13, v15
	v_mov_b32_e32 v0, s0
	ds_read_b128 v[24:27], v0
	v_add_f32_e32 v0, v8, v10
	v_add_f32_e32 v0, v0, v1
	s_waitcnt lgkmcnt(1)
	v_add_f32_e32 v1, v20, v22
	v_add_f32_e32 v0, v0, v1
	s_waitcnt lgkmcnt(0)
	v_add_f32_e32 v1, v24, v26
	v_add_f32_e32 v0, v0, v1
	v_add_f32_e32 v1, v9, v11
	v_add_f32_e32 v1, v1, v4
	v_add_f32_e32 v4, v21, v23
	v_add_f32_e32 v1, v1, v4
	v_add_f32_e32 v4, v25, v27
	v_add_f32_e32 v1, v1, v4
	v_mul_f32_e32 v4, 0x3b000000, v0
	v_mul_f32_e32 v4, v4, v4
	v_fma_f32 v1, v1, s12, -v4
	v_max_f32_e32 v1, 0, v1
	v_add_f32_e32 v1, 0x358637bd, v1
	v_rsq_f32_e32 v1, v1
	v_fmac_f32_e32 v19, 0xbb000000, v0
	v_mul_f32_e32 v0, v19, v1
	v_cvt_pk_bf16_f32 v1, v2, s0
	v_fma_f32 v0, v143, v0, v142
	ds_write_b16 v175, v1 offset:12288
	v_cvt_pk_bf16_f32 v1, v45, s0
	ds_write_b16 v175, v1 offset:28672
	v_mul_f32_e32 v1, 0xbfb8aa3b, v0
	v_exp_f32_e32 v1, v1
	s_nop 0
	v_add_f32_e32 v1, 1.0, v1
	v_rcp_f32_e32 v1, v1
	s_nop 0
	v_mul_f32_e32 v0, v0, v1
	v_cvt_pk_bf16_f32 v0, v0, s0
	v_readlane_b32 s0, v252, 22
	ds_write_b16 v175, v0 offset:45056
	s_nop 0
	v_mov_b32_e32 v0, s0
	v_readlane_b32 s0, v252, 23
	ds_read_b128 v[8:11], v0
	s_nop 0
	v_mov_b32_e32 v0, s0
	v_readlane_b32 s0, v252, 24
	ds_read_b128 v[12:15], v0
	s_waitcnt lgkmcnt(0)
	v_add_f32_e32 v1, v12, v14
	v_mov_b32_e32 v0, s0
	v_readlane_b32 s0, v252, 25
	ds_read_b128 v[20:23], v0
	v_add_f32_e32 v2, v13, v15
	v_mov_b32_e32 v0, s0
	ds_read_b128 v[24:27], v0
	v_add_f32_e32 v0, v8, v10
	v_add_f32_e32 v0, v0, v1
	s_waitcnt lgkmcnt(1)
	v_add_f32_e32 v1, v20, v22
	v_add_f32_e32 v0, v0, v1
	s_waitcnt lgkmcnt(0)
	v_add_f32_e32 v1, v24, v26
	v_add_f32_e32 v0, v0, v1
	v_add_f32_e32 v1, v9, v11
	v_add_f32_e32 v1, v1, v2
	v_add_f32_e32 v2, v21, v23
	v_add_f32_e32 v1, v1, v2
	v_add_f32_e32 v2, v25, v27
	v_add_f32_e32 v1, v1, v2
	v_mul_f32_e32 v2, 0x3b000000, v0
	v_mul_f32_e32 v2, v2, v2
	v_fma_f32 v1, v1, s12, -v2
	v_max_f32_e32 v1, 0, v1
	v_add_f32_e32 v1, 0x358637bd, v1
	v_rsq_f32_e32 v1, v1
	v_fmac_f32_e32 v18, 0xbb000000, v0
	v_mul_f32_e32 v0, v18, v1
	v_cvt_pk_bf16_f32 v1, v3, s0
	v_fma_f32 v0, v143, v0, v142
	ds_write_b16 v175, v1 offset:13312
	v_cvt_pk_bf16_f32 v1, v46, s0
	ds_write_b16 v175, v1 offset:29696
	v_mul_f32_e32 v1, 0xbfb8aa3b, v0
	v_exp_f32_e32 v1, v1
	s_nop 0
	v_add_f32_e32 v1, 1.0, v1
	v_rcp_f32_e32 v1, v1
	s_nop 0
	v_mul_f32_e32 v0, v0, v1
	v_cvt_pk_bf16_f32 v0, v0, s0
	v_readlane_b32 s0, v252, 26
	ds_write_b16 v175, v0 offset:46080
	s_nop 0
	v_mov_b32_e32 v0, s0
	v_readlane_b32 s0, v252, 27
	ds_read_b128 v[0:3], v0
	s_nop 0
	v_mov_b32_e32 v4, s0
	v_readlane_b32 s0, v252, 28
	ds_read_b128 v[8:11], v4
	s_waitcnt lgkmcnt(1)
	v_add_f32_e32 v0, v0, v2
	v_mov_b32_e32 v4, s0
	v_readlane_b32 s0, v252, 29
	ds_read_b128 v[12:15], v4
	s_waitcnt lgkmcnt(1)
	v_add_f32_e32 v2, v8, v10
	v_mov_b32_e32 v4, s0
	ds_read_b128 v[18:21], v4
	v_add_f32_e32 v0, v0, v2
	s_waitcnt lgkmcnt(1)
	v_add_f32_e32 v2, v12, v14
	v_add_f32_e32 v0, v0, v2
	v_add_f32_e32 v1, v1, v3
	s_waitcnt lgkmcnt(0)
	v_add_f32_e32 v2, v18, v20
	v_add_f32_e32 v0, v0, v2
	v_add_f32_e32 v2, v9, v11
	v_add_f32_e32 v1, v1, v2
	v_add_f32_e32 v2, v13, v15
	v_add_f32_e32 v1, v1, v2
	v_add_f32_e32 v2, v19, v21
	v_add_f32_e32 v1, v1, v2
	v_mul_f32_e32 v2, 0x3b000000, v0
	v_mul_f32_e32 v2, v2, v2
	v_fma_f32 v1, v1, s12, -v2
	v_max_f32_e32 v1, 0, v1
	v_add_f32_e32 v1, 0x358637bd, v1
	v_rsq_f32_e32 v1, v1
	v_fmac_f32_e32 v17, 0xbb000000, v0
	v_mul_f32_e32 v0, v17, v1
	v_cvt_pk_bf16_f32 v1, v6, s0
	v_fma_f32 v0, v143, v0, v142
	ds_write_b16 v175, v1 offset:14336
	v_cvt_pk_bf16_f32 v1, v42, s0
	ds_write_b16 v175, v1 offset:30720
	v_mul_f32_e32 v1, 0xbfb8aa3b, v0
	v_exp_f32_e32 v1, v1
	s_nop 0
	v_add_f32_e32 v1, 1.0, v1
	v_rcp_f32_e32 v1, v1
	s_nop 0
	v_mul_f32_e32 v0, v0, v1
	v_cvt_pk_bf16_f32 v0, v0, s0
	v_readlane_b32 s0, v252, 30
	ds_write_b16 v175, v0 offset:47104
	s_nop 0
	v_mov_b32_e32 v0, s0
	v_readlane_b32 s0, v252, 31
	ds_read_b128 v[0:3], v0
	s_nop 0
	v_mov_b32_e32 v4, s0
	v_readlane_b32 s0, v252, 32
	ds_read_b128 v[8:11], v4
	s_waitcnt lgkmcnt(1)
	v_add_f32_e32 v0, v0, v2
	v_mov_b32_e32 v4, s0
	v_readlane_b32 s0, v252, 33
	ds_read_b128 v[12:15], v4
	s_waitcnt lgkmcnt(1)
	v_add_f32_e32 v2, v8, v10
	v_mov_b32_e32 v4, s0
	ds_read_b128 v[18:21], v4
	v_add_f32_e32 v0, v0, v2
	s_waitcnt lgkmcnt(1)
	v_add_f32_e32 v2, v12, v14
	v_add_f32_e32 v0, v0, v2
	v_add_f32_e32 v1, v1, v3
	s_waitcnt lgkmcnt(0)
	v_add_f32_e32 v2, v18, v20
	v_add_f32_e32 v0, v0, v2
	v_add_f32_e32 v2, v9, v11
	v_add_f32_e32 v1, v1, v2
	v_add_f32_e32 v2, v13, v15
	v_add_f32_e32 v1, v1, v2
	v_add_f32_e32 v2, v19, v21
	v_add_f32_e32 v1, v1, v2
	v_mul_f32_e32 v2, 0x3b000000, v0
	v_mul_f32_e32 v2, v2, v2
	v_fma_f32 v1, v1, s12, -v2
	v_max_f32_e32 v1, 0, v1
	v_add_f32_e32 v1, 0x358637bd, v1
	v_rsq_f32_e32 v1, v1
	v_fmac_f32_e32 v16, 0xbb000000, v0
	s_lshl_b64 s[12:13], s[26:27], 12
	v_mul_f32_e32 v0, v16, v1
	v_cvt_pk_bf16_f32 v1, v7, s0
	v_fma_f32 v0, v143, v0, v142
	ds_write_b16 v175, v1 offset:15360
	v_cvt_pk_bf16_f32 v1, v36, s0
	ds_write_b16 v175, v1 offset:31744
	v_mul_f32_e32 v1, 0xbfb8aa3b, v0
	v_exp_f32_e32 v1, v1
	s_nop 0
	v_add_f32_e32 v1, 1.0, v1
	v_rcp_f32_e32 v1, v1
	s_nop 0
	v_mul_f32_e32 v0, v0, v1
	v_cvt_pk_bf16_f32 v0, v0, s0
	s_mov_b64 s[0:1], s[62:63]
	ds_write_b16 v175, v0 offset:48128
	s_waitcnt lgkmcnt(0)
	s_barrier
	s_add_u32 s0, s0, s12
	s_addc_u32 s1, s1, s13
	s_add_u32 s0, s0, 0x14000000
	ds_read_b128 v[0:3], v179
	s_addc_u32 s1, s1, 0
	v_lshl_add_u64 v[4:5], s[0:1], 0, v[126:127]
	v_lshl_add_u64 v[6:7], v[96:97], 1, v[4:5]
	v_lshl_add_u64 v[6:7], v[6:7], 0, v[192:193]
	s_waitcnt lgkmcnt(0)
	global_store_dwordx4 v[6:7], v[0:3], off
	ds_read_b128 v[0:3], v180
	v_lshl_add_u64 v[6:7], s[0:1], 0, v[128:129]
	v_lshl_add_u64 v[6:7], v[98:99], 1, v[6:7]
	v_lshl_add_u64 v[6:7], v[6:7], 0, v[192:193]
	s_waitcnt lgkmcnt(0)
	global_store_dwordx4 v[6:7], v[0:3], off
	ds_read_b128 v[0:3], v181
	v_lshl_add_u64 v[6:7], v[100:101], 1, v[4:5]
	v_lshl_add_u64 v[6:7], v[6:7], 0, v[192:193]
	v_lshl_add_u64 v[4:5], v[104:105], 1, v[4:5]
	v_lshl_add_u64 v[4:5], v[4:5], 0, v[192:193]
	s_waitcnt lgkmcnt(0)
	global_store_dwordx4 v[6:7], v[0:3], off
	ds_read_b128 v[0:3], v182
	v_lshl_add_u64 v[6:7], s[0:1], 0, v[130:131]
	v_lshl_add_u64 v[6:7], v[102:103], 1, v[6:7]
	v_lshl_add_u64 v[6:7], v[6:7], 0, v[192:193]
	s_waitcnt lgkmcnt(0)
	global_store_dwordx4 v[6:7], v[0:3], off
	ds_read_b128 v[0:3], v183
	s_waitcnt lgkmcnt(0)
	global_store_dwordx4 v[4:5], v[0:3], off
	ds_read_b128 v[0:3], v184
	v_lshl_add_u64 v[4:5], s[0:1], 0, v[132:133]
	v_lshl_add_u64 v[4:5], v[106:107], 1, v[4:5]
	v_lshl_add_u64 v[4:5], v[4:5], 0, v[192:193]
	s_waitcnt lgkmcnt(0)
	global_store_dwordx4 v[4:5], v[0:3], off
	s_waitcnt lgkmcnt(0)
	s_barrier

.LBB0_144:
	s_mov_b64 s[0:1], -1
	s_cmpk_gt_i32 s52, 0x3ff
	v_lshlrev_b32_e32 v192, 1, v76
	s_cbranch_scc0 .LBB0_289
	s_add_i32 s0, s52, 0xfffffc00
	s_lshl_b32 s3, s0, 3
	v_readlane_b32 s12, v253, 59
	v_readlane_b32 s56, v253, 8
	v_readlane_b32 s13, v253, 60
	s_add_u32 s26, s12, s0
	v_readlane_b32 s62, v253, 14
	v_readlane_b32 s63, v253, 15
	s_addc_u32 s27, s13, 0
	s_mov_b64 s[30:31], s[62:63]
	s_mul_i32 s0, s27, 0x1e00
	s_mul_hi_u32 s1, s26, 0x1e00
	v_readlane_b32 s60, v253, 12
	v_readlane_b32 s61, v253, 13
	s_add_i32 s1, s1, s0
	s_mul_i32 s0, s26, 0x1e00
	v_lshl_add_u64 v[0:1], s[30:31], 0, v[192:193]
	s_mov_b64 s[22:23], 0x18400000
	s_mov_b64 s[12:13], s[60:61]
	s_add_i32 s34, s3, 0x3ff1
	v_lshl_add_u64 v[38:39], v[0:1], 0, s[22:23]
	v_lshl_add_u64 v[36:37], s[0:1], 2, v[120:121]
	v_mov_b32_e32 v4, 0
	v_mov_b32_e32 v0, 0
	v_mov_b32_e32 v12, 0
	v_mov_b32_e32 v13, 0
	v_mov_b32_e32 v14, 0
	v_mov_b32_e32 v15, 0
	v_mov_b32_e32 v8, 0
	v_mov_b32_e32 v9, 0
	v_mov_b32_e32 v10, 0
	v_mov_b32_e32 v11, 0
	v_mov_b32_e32 v5, 0
	v_mov_b32_e32 v6, 0
	v_mov_b32_e32 v7, 0
	v_readlane_b32 s57, v253, 9
	v_readlane_b32 s58, v253, 10
	v_readlane_b32 s59, v253, 11
	s_and_saveexec_b64 s[22:23], s[94:95]
	s_cbranch_execz .LBB0_151
	v_readlane_b32 s24, v254, 17
	v_readlane_b32 s25, v254, 18
	s_and_saveexec_b64 s[28:29], s[24:25]
	s_xor_b64 s[28:29], exec, s[28:29]
	s_cbranch_execz .LBB0_148
	v_add_u32_e32 v1, s34, v78
	v_mad_u64_u32 v[2:3], s[38:39], v1, s76, v[38:39]
	global_load_dwordx4 v[4:7], v[2:3], off

.LBB0_151:
	s_or_b64 exec, exec, s[22:23]
	v_mov_b32_e32 v20, s83
	v_mov_b32_e32 v21, s83
	v_mov_b32_e32 v22, s83
	v_mov_b32_e32 v23, s83
	v_mov_b32_e32 v16, s83
	v_mov_b32_e32 v17, s83
	v_mov_b32_e32 v18, s83
	v_mov_b32_e32 v19, s83
	v_mov_b32_e32 v1, 0
	v_mov_b32_e32 v2, 0
	v_mov_b32_e32 v3, 0
	v_mov_b32_e32 v24, 0
	v_mov_b32_e32 v25, 0
	v_mov_b32_e32 v26, 0
	v_mov_b32_e32 v27, 0
	s_and_saveexec_b64 s[22:23], s[50:51]
	s_cbranch_execz .LBB0_157
	v_readlane_b32 s24, v254, 21
	v_readlane_b32 s25, v254, 22
	s_and_saveexec_b64 s[28:29], s[24:25]
	s_xor_b64 s[28:29], exec, s[28:29]
	s_cbranch_execz .LBB0_154
	v_add_u32_e32 v0, s34, v82
	v_mad_u64_u32 v[0:1], s[38:39], v0, s76, v[38:39]
	global_load_dwordx4 v[24:27], v[0:1], off

.LBB0_157:
	s_or_b64 exec, exec, s[22:23]
	v_mov_b32_e32 v28, 0
	v_mov_b32_e32 v32, 0
	v_mov_b32_e32 v33, 0
	v_mov_b32_e32 v34, 0
	v_mov_b32_e32 v35, 0
	v_mov_b32_e32 v29, 0
	v_mov_b32_e32 v30, 0
	v_mov_b32_e32 v31, 0
	s_and_saveexec_b64 s[22:23], s[92:93]
	s_cbranch_execz .LBB0_163
	v_readlane_b32 s24, v254, 25
	v_readlane_b32 s25, v254, 26
	s_and_saveexec_b64 s[28:29], s[24:25]
	s_xor_b64 s[28:29], exec, s[28:29]
	s_cbranch_execz .LBB0_160
	v_add_u32_e32 v28, s34, v86
	v_mad_u64_u32 v[28:29], s[34:35], v28, s76, v[38:39]
	global_load_dwordx4 v[28:31], v[28:29], off

.LBB0_163:
	s_or_b64 exec, exec, s[22:23]
	s_lshl_b64 s[0:1], s[0:1], 2
	s_add_u32 s0, s12, s0
	s_addc_u32 s1, s13, s1
	v_lshlrev_b32_e32 v134, 2, v76
	v_mov_b32_e32 v135, v193
	v_lshl_add_u64 v[36:37], s[0:1], 0, v[134:135]
	s_mov_b64 s[0:1], 0x6578000
	v_lshl_add_u64 v[36:37], v[36:37], 0, s[0:1]
	s_and_saveexec_b64 s[0:1], s[94:95]
	s_cbranch_execz .LBB0_166
	v_readlane_b32 s12, v254, 15
	s_waitcnt vmcnt(0) lgkmcnt(0)
	v_lshlrev_b32_e32 v38, 16, v4
	v_and_b32_e32 v39, 0xffff0000, v4
	v_lshlrev_b32_e32 v40, 16, v5
	v_and_b32_e32 v41, 0xffff0000, v5
	v_lshlrev_b32_e32 v4, 16, v6
	v_and_b32_e32 v5, 0xffff0000, v6
	v_lshlrev_b32_e32 v6, 16, v7
	v_and_b32_e32 v7, 0xffff0000, v7
	v_readlane_b32 s13, v254, 16
	s_nop 1
	v_cndmask_b32_e64 v7, v7, v15, s[12:13]
	v_cndmask_b32_e64 v6, v6, v14, s[12:13]
	v_cndmask_b32_e64 v5, v5, v13, s[12:13]
	v_cndmask_b32_e64 v4, v4, v12, s[12:13]
	v_cndmask_b32_e64 v11, v41, v11, s[12:13]
	v_cndmask_b32_e64 v10, v40, v10, s[12:13]
	v_cndmask_b32_e64 v9, v39, v9, s[12:13]
	v_cndmask_b32_e64 v8, v38, v8, s[12:13]
	v_readlane_b32 s12, v254, 27
	v_readlane_b32 s13, v254, 28
	ds_write_b128 v187, v[8:11]
	ds_write_b128 v187, v[4:7] offset:16
	s_and_b64 exec, exec, s[12:13]
	s_cbranch_execz .LBB0_166
	v_lshl_add_u64 v[12:13], v[36:37], 0, v[90:91]
	global_store_dwordx4 v[12:13], v[8:11], off
	global_store_dwordx4 v[12:13], v[4:7], off offset:16
.LBB0_166:
	s_or_b64 exec, exec, s[0:1]
	s_and_saveexec_b64 s[0:1], s[50:51]
	s_cbranch_execz .LBB0_169
	v_readlane_b32 s4, v254, 19
	s_waitcnt vmcnt(0) lgkmcnt(0)
	v_lshlrev_b32_e32 v4, 16, v24
	v_and_b32_e32 v5, 0xffff0000, v24
	v_lshlrev_b32_e32 v6, 16, v25
	v_and_b32_e32 v7, 0xffff0000, v25
	v_lshlrev_b32_e32 v8, 16, v26
	v_and_b32_e32 v9, 0xffff0000, v26
	v_lshlrev_b32_e32 v10, 16, v27
	v_and_b32_e32 v11, 0xffff0000, v27
	v_readlane_b32 s5, v254, 20
	v_readlane_b32 s12, v254, 29
	v_readlane_b32 s13, v254, 30
	v_cndmask_b32_e64 v3, v11, v3, s[4:5]
	v_cndmask_b32_e64 v2, v10, v2, s[4:5]
	v_cndmask_b32_e64 v1, v9, v1, s[4:5]
	v_cndmask_b32_e64 v0, v8, v0, s[4:5]
	v_cndmask_b32_e64 v7, v7, v23, s[4:5]
	v_cndmask_b32_e64 v6, v6, v22, s[4:5]
	v_cndmask_b32_e64 v5, v5, v21, s[4:5]
	v_cndmask_b32_e64 v4, v4, v20, s[4:5]
	ds_write_b128 v188, v[4:7]
	ds_write_b128 v188, v[0:3] offset:16
	s_and_b64 exec, exec, s[12:13]
	s_cbranch_execz .LBB0_169
	v_lshl_add_u64 v[8:9], v[36:37], 0, v[92:93]
	global_store_dwordx4 v[8:9], v[4:7], off
	global_store_dwordx4 v[8:9], v[0:3], off offset:16
.LBB0_169:
	s_or_b64 exec, exec, s[0:1]
	s_and_saveexec_b64 s[0:1], s[92:93]
	s_cbranch_execz .LBB0_172
	v_readlane_b32 s4, v254, 23
	s_waitcnt vmcnt(0) lgkmcnt(0)
	v_lshlrev_b32_e32 v4, 16, v28
	v_and_b32_e32 v5, 0xffff0000, v28
	v_lshlrev_b32_e32 v6, 16, v29
	v_and_b32_e32 v7, 0xffff0000, v29
	v_lshlrev_b32_e32 v0, 16, v30
	v_and_b32_e32 v1, 0xffff0000, v30
	v_lshlrev_b32_e32 v2, 16, v31
	v_and_b32_e32 v3, 0xffff0000, v31
	v_readlane_b32 s5, v254, 24
	v_readlane_b32 s12, v254, 31
	v_readlane_b32 s13, v254, 32
	v_cndmask_b32_e64 v3, v3, v35, s[4:5]
	v_cndmask_b32_e64 v2, v2, v34, s[4:5]
	v_cndmask_b32_e64 v1, v1, v33, s[4:5]
	v_cndmask_b32_e64 v0, v0, v32, s[4:5]
	v_cndmask_b32_e64 v7, v7, v19, s[4:5]
	v_cndmask_b32_e64 v6, v6, v18, s[4:5]
	v_cndmask_b32_e64 v5, v5, v17, s[4:5]
	v_cndmask_b32_e64 v4, v4, v16, s[4:5]
	ds_write_b128 v189, v[4:7]
	ds_write_b128 v189, v[0:3] offset:16
	s_and_b64 exec, exec, s[12:13]
	s_cbranch_execz .LBB0_172
	v_lshl_add_u64 v[8:9], v[36:37], 0, v[94:95]
	global_store_dwordx4 v[8:9], v[4:7], off
	global_store_dwordx4 v[8:9], v[0:3], off offset:16

.LBB0_181:
	v_readlane_b32 s56, v253, 8
	v_readlane_b32 s62, v253, 14
	v_readlane_b32 s63, v253, 15
	s_add_i32 s82, s3, 0x4000
	s_mov_b64 s[0:1], s[62:63]
	s_lshl_b64 s[12:13], s[82:83], 12
	s_add_u32 s0, s0, s12
	s_addc_u32 s1, s1, s13
	v_lshl_add_u64 v[8:9], v[64:65], 1, s[0:1]
	v_add_co_u32_e32 v10, vcc, s33, v8
	s_waitcnt vmcnt(0)
	v_cvt_pk_bf16_f32 v6, v6, s0
	v_addc_co_u32_e32 v11, vcc, 0, v9, vcc
	global_store_short v[10:11], v6, off
	v_add_co_u32_e32 v6, vcc, s48, v8
	v_cvt_pk_bf16_f32 v10, v7, s0
	s_nop 0
	v_addc_co_u32_e32 v7, vcc, 0, v9, vcc
	v_cvt_pk_bf16_f32 v4, v4, s0
	s_mov_b32 s0, 0x14002000
	global_store_short v[6:7], v10, off
	v_add_co_u32_e32 v6, vcc, s0, v8
	s_mov_b64 s[12:13], 0x18400400
	s_nop 0
	v_addc_co_u32_e32 v7, vcc, 0, v9, vcc
	global_store_short v[6:7], v4, off
	v_cvt_pk_bf16_f32 v6, v5, s0
	s_mov_b32 s0, 0x14003000
	v_add_co_u32_e32 v4, vcc, s0, v8
	v_cvt_pk_bf16_f32 v2, v2, s0
	s_nop 0
	v_addc_co_u32_e32 v5, vcc, 0, v9, vcc
	s_mov_b32 s0, 0x14004000
	global_store_short v[4:5], v6, off
	v_add_co_u32_e32 v4, vcc, s0, v8
	v_readlane_b32 s60, v253, 12
	s_nop 0
	v_addc_co_u32_e32 v5, vcc, 0, v9, vcc
	global_store_short v[4:5], v2, off
	v_cvt_pk_bf16_f32 v4, v3, s0
	s_mov_b32 s0, 0x14005000
	v_add_co_u32_e32 v2, vcc, s0, v8
	v_cvt_pk_bf16_f32 v0, v0, s0
	s_nop 0
	v_addc_co_u32_e32 v3, vcc, 0, v9, vcc
	s_mov_b32 s0, 0x14006000
	global_store_short v[2:3], v4, off
	v_add_co_u32_e32 v2, vcc, s0, v8
	v_readlane_b32 s61, v253, 13
	s_nop 0
	v_addc_co_u32_e32 v3, vcc, 0, v9, vcc
	global_store_short v[2:3], v0, off
	v_cvt_pk_bf16_f32 v2, v1, s0
	s_mov_b32 s0, 0x14007000
	v_add_co_u32_e32 v0, vcc, s0, v8
	s_mov_b64 s[0:1], s[60:61]
	s_nop 0
	v_addc_co_u32_e32 v1, vcc, 0, v9, vcc
	global_store_short v[0:1], v2, off
	v_lshl_add_u64 v[0:1], s[30:31], 0, v[192:193]
	v_lshl_add_u64 v[26:27], v[0:1], 0, s[12:13]
	s_lshl_b64 s[12:13], s[26:27], 12
	s_add_i32 s28, s3, 0x3ffe
	v_lshl_add_u64 v[24:25], v[122:123], 0, s[12:13]
	v_mov_b32_e32 v4, 0
	v_mov_b32_e32 v0, 0
	v_mov_b32_e32 v12, 0
	v_mov_b32_e32 v13, 0
	v_mov_b32_e32 v14, 0
	v_mov_b32_e32 v15, 0
	v_mov_b32_e32 v8, 0
	v_mov_b32_e32 v9, 0
	v_mov_b32_e32 v10, 0
	v_mov_b32_e32 v11, 0
	v_mov_b32_e32 v5, 0
	v_mov_b32_e32 v6, 0
	v_mov_b32_e32 v7, 0
	v_readlane_b32 s57, v253, 9
	v_readlane_b32 s58, v253, 10
	v_readlane_b32 s59, v253, 11
	s_waitcnt lgkmcnt(0)
	s_barrier
	s_and_saveexec_b64 s[12:13], s[66:67]
	s_cbranch_execz .LBB0_187
	v_readlane_b32 s24, v254, 35
	v_readlane_b32 s25, v254, 36
	s_and_saveexec_b64 s[22:23], s[24:25]
	s_xor_b64 s[22:23], exec, s[22:23]
	s_cbranch_execz .LBB0_184
	v_add_u32_e32 v1, s28, v78
	v_mad_u64_u32 v[2:3], s[34:35], v1, s76, v[26:27]
	global_load_dwordx4 v[4:7], v[2:3], off

.LBB0_187:
	s_or_b64 exec, exec, s[12:13]
	v_mov_b32_e32 v16, s83
	v_mov_b32_e32 v17, s83
	v_mov_b32_e32 v18, s83
	v_mov_b32_e32 v19, s83
	v_mov_b32_e32 v20, s83
	v_mov_b32_e32 v21, s83
	v_mov_b32_e32 v22, s83
	v_mov_b32_e32 v23, s83
	v_mov_b32_e32 v1, 0
	v_mov_b32_e32 v2, 0
	v_mov_b32_e32 v3, 0
	s_and_saveexec_b64 s[12:13], s[8:9]
	s_cbranch_execz .LBB0_193
	v_readlane_b32 s4, v254, 41
	v_readlane_b32 s5, v254, 42
	s_and_saveexec_b64 s[22:23], s[4:5]
	s_xor_b64 s[22:23], exec, s[22:23]
	s_cbranch_execz .LBB0_190
	v_add_u32_e32 v0, s28, v82
	v_mad_u64_u32 v[0:1], s[28:29], v0, s76, v[26:27]
	global_load_dwordx4 v[0:3], v[0:1], off

.LBB0_193:
	s_or_b64 exec, exec, s[12:13]
	s_lshl_b64 s[12:13], s[26:27], 10
	s_lshl_b64 s[12:13], s[12:13], 2
	s_add_u32 s0, s0, s12
	s_addc_u32 s1, s1, s13
	v_mov_b32_e32 v135, v193
	v_lshl_add_u64 v[24:25], s[0:1], 0, v[134:135]
	s_mov_b64 s[0:1], 0x6cf8000
	v_lshl_add_u64 v[24:25], v[24:25], 0, s[0:1]
	s_and_saveexec_b64 s[0:1], s[66:67]
	s_cbranch_execz .LBB0_196
	v_readlane_b32 s4, v254, 33
	s_waitcnt vmcnt(0) lgkmcnt(0)
	v_lshlrev_b32_e32 v26, 16, v4
	v_and_b32_e32 v27, 0xffff0000, v4
	v_lshlrev_b32_e32 v28, 16, v5
	v_and_b32_e32 v29, 0xffff0000, v5
	v_lshlrev_b32_e32 v4, 16, v6
	v_and_b32_e32 v5, 0xffff0000, v6
	v_lshlrev_b32_e32 v6, 16, v7
	v_and_b32_e32 v7, 0xffff0000, v7
	v_readlane_b32 s5, v254, 34
	v_readlane_b32 s12, v254, 27
	v_readlane_b32 s13, v254, 28
	v_cndmask_b32_e64 v7, v7, v15, s[4:5]
	v_cndmask_b32_e64 v6, v6, v14, s[4:5]
	v_cndmask_b32_e64 v5, v5, v13, s[4:5]
	v_cndmask_b32_e64 v4, v4, v12, s[4:5]
	v_cndmask_b32_e64 v11, v29, v11, s[4:5]
	v_cndmask_b32_e64 v10, v28, v10, s[4:5]
	v_cndmask_b32_e64 v9, v27, v9, s[4:5]
	v_cndmask_b32_e64 v8, v26, v8, s[4:5]
	ds_write_b128 v187, v[8:11]
	ds_write_b128 v187, v[4:7] offset:16
	s_and_b64 exec, exec, s[12:13]
	s_cbranch_execz .LBB0_196
	v_lshl_add_u64 v[12:13], v[24:25], 0, v[90:91]
	global_store_dwordx4 v[12:13], v[8:11], off
	global_store_dwordx4 v[12:13], v[4:7], off offset:16
.LBB0_196:
	s_or_b64 exec, exec, s[0:1]
	s_and_saveexec_b64 s[0:1], s[8:9]
	s_cbranch_execz .LBB0_199
	v_readlane_b32 s4, v254, 39
	s_waitcnt vmcnt(0) lgkmcnt(0)
	v_lshlrev_b32_e32 v4, 16, v0
	v_and_b32_e32 v5, 0xffff0000, v0
	v_lshlrev_b32_e32 v6, 16, v1
	v_and_b32_e32 v7, 0xffff0000, v1
	v_lshlrev_b32_e32 v0, 16, v2
	v_and_b32_e32 v1, 0xffff0000, v2
	v_lshlrev_b32_e32 v2, 16, v3
	v_and_b32_e32 v3, 0xffff0000, v3
	v_readlane_b32 s5, v254, 40
	v_readlane_b32 s12, v254, 29
	v_readlane_b32 s13, v254, 30
	v_cndmask_b32_e64 v3, v3, v23, s[4:5]
	v_cndmask_b32_e64 v2, v2, v22, s[4:5]
	v_cndmask_b32_e64 v1, v1, v21, s[4:5]
	v_cndmask_b32_e64 v0, v0, v20, s[4:5]
	v_cndmask_b32_e64 v7, v7, v19, s[4:5]
	v_cndmask_b32_e64 v6, v6, v18, s[4:5]
	v_cndmask_b32_e64 v5, v5, v17, s[4:5]
	v_cndmask_b32_e64 v4, v4, v16, s[4:5]
	ds_write_b128 v188, v[4:7]
	ds_write_b128 v188, v[0:3] offset:16
	s_and_b64 exec, exec, s[12:13]
	s_cbranch_execz .LBB0_199
	v_lshl_add_u64 v[8:9], v[24:25], 0, v[92:93]
	global_store_dwordx4 v[8:9], v[4:7], off
	global_store_dwordx4 v[8:9], v[0:3], off offset:16
.LBB0_199:
	s_or_b64 exec, exec, s[0:1]
	s_waitcnt vmcnt(0) lgkmcnt(0)
	v_mov_b32_e32 v0, 0
	v_add_u32_e32 v127, s82, v78
	v_mov_b32_e32 v1, 0
	v_mov_b32_e32 v2, 0
	v_mov_b32_e32 v3, 0
	s_and_saveexec_b64 s[0:1], s[68:69]
	s_cbranch_execz .LBB0_201
	v_mov_b64_e32 v[0:1], s[30:31]
	v_mad_u64_u32 v[0:1], s[12:13], v127, s76, v[0:1]
	v_lshl_add_u64 v[0:1], v[0:1], 0, v[192:193]
	v_add_co_u32_e32 v0, vcc, 0x18400000, v0
	s_nop 1
	v_addc_co_u32_e32 v1, vcc, 0, v1, vcc
	global_load_dwordx4 v[0:3], v[0:1], off offset:2048

.LBB0_203:
	s_or_b64 exec, exec, s[12:13]
	v_readlane_b32 s56, v253, 8
	v_readlane_b32 s62, v253, 14
	v_readlane_b32 s63, v253, 15
	s_mov_b64 s[12:13], s[62:63]
	s_waitcnt lgkmcnt(0)
	s_barrier
	s_waitcnt vmcnt(0)
	ds_read2st64_b32 v[0:1], v87 offset1:8
	ds_read2st64_b32 v[2:3], v87 offset0:16 offset1:24
	ds_read2st64_b32 v[4:5], v87 offset0:80 offset1:88
	s_lshl_b64 s[28:29], s[0:1], 1
	s_add_u32 s0, s12, s28
	s_addc_u32 s1, s13, s29
	s_waitcnt lgkmcnt(2)
	v_mul_f32_e32 v8, v165, v1
	v_fmac_f32_e32 v8, v163, v0
	v_lshl_add_u64 v[6:7], v[64:65], 1, s[0:1]
	s_waitcnt lgkmcnt(1)
	v_fmac_f32_e32 v8, v164, v2
	s_waitcnt lgkmcnt(0)
	v_mul_f32_e32 v0, v4, v8
	v_add_co_u32_e32 v8, vcc, s33, v6
	v_cvt_pk_bf16_f32 v0, v0, s0
	s_nop 0
	v_addc_co_u32_e32 v9, vcc, 0, v7, vcc
	global_store_short v[8:9], v0, off offset:1024
	v_mul_f32_e32 v0, v165, v2
	v_fmac_f32_e32 v0, v163, v1
	v_fmac_f32_e32 v0, v164, v3
	v_mul_f32_e32 v0, v5, v0
	v_cvt_pk_bf16_f32 v10, v0, s0
	v_add_co_u32_e32 v0, vcc, s48, v6
	ds_read2st64_b32 v[4:5], v87 offset0:32 offset1:40
	ds_read2st64_b32 v[8:9], v87 offset0:96 offset1:104
	v_addc_co_u32_e32 v1, vcc, 0, v7, vcc
	global_store_short v[0:1], v10, off offset:1024
	v_mul_f32_e32 v0, v165, v3
	v_fmac_f32_e32 v0, v163, v2
	s_waitcnt lgkmcnt(0)
	v_fmac_f32_e32 v0, v164, v4
	v_mul_f32_e32 v0, v8, v0
	v_cvt_pk_bf16_f32 v2, v0, s0
	s_mov_b32 s0, 0x14002000
	v_add_co_u32_e32 v0, vcc, s0, v6
	s_mul_hi_u32 s1, s26, 0x3c00
	s_nop 0
	v_addc_co_u32_e32 v1, vcc, 0, v7, vcc
	global_store_short v[0:1], v2, off offset:1024
	v_mul_f32_e32 v0, v165, v4
	v_fmac_f32_e32 v0, v163, v3
	v_fmac_f32_e32 v0, v164, v5
	v_mul_f32_e32 v0, v9, v0
	v_cvt_pk_bf16_f32 v10, v0, s0
	s_mov_b32 s0, 0x14003000
	v_add_co_u32_e32 v0, vcc, s0, v6
	ds_read2st64_b32 v[2:3], v87 offset0:48 offset1:56
	ds_read2st64_b32 v[8:9], v87 offset0:112 offset1:120
	v_addc_co_u32_e32 v1, vcc, 0, v7, vcc
	global_store_short v[0:1], v10, off offset:1024
	v_mul_f32_e32 v0, v165, v5
	v_fmac_f32_e32 v0, v163, v4
	s_waitcnt lgkmcnt(0)
	v_fmac_f32_e32 v0, v164, v2
	v_mul_f32_e32 v0, v8, v0
	v_cvt_pk_bf16_f32 v4, v0, s0
	s_mov_b32 s0, 0x14004000
	v_add_co_u32_e32 v0, vcc, s0, v6
	v_readlane_b32 s60, v253, 12
	s_nop 0
	v_addc_co_u32_e32 v1, vcc, 0, v7, vcc
	global_store_short v[0:1], v4, off offset:1024
	v_mul_f32_e32 v0, v165, v2
	v_fmac_f32_e32 v0, v163, v5
	v_fmac_f32_e32 v0, v164, v3
	v_mul_f32_e32 v0, v9, v0
	v_cvt_pk_bf16_f32 v10, v0, s0
	s_mov_b32 s0, 0x14005000
	v_add_co_u32_e32 v0, vcc, s0, v6
	ds_read2st64_b32 v[4:5], v87 offset0:64 offset1:72
	ds_read2st64_b32 v[8:9], v87 offset0:128 offset1:136
	v_addc_co_u32_e32 v1, vcc, 0, v7, vcc
	global_store_short v[0:1], v10, off offset:1024
	v_mul_f32_e32 v0, v165, v3
	v_fmac_f32_e32 v0, v163, v2
	s_waitcnt lgkmcnt(0)
	v_fmac_f32_e32 v0, v164, v4
	v_mul_f32_e32 v0, v8, v0
	v_cvt_pk_bf16_f32 v2, v0, s0
	s_mov_b32 s0, 0x14006000
	v_add_co_u32_e32 v0, vcc, s0, v6
	v_readlane_b32 s61, v253, 13
	s_nop 0
	v_addc_co_u32_e32 v1, vcc, 0, v7, vcc
	global_store_short v[0:1], v2, off offset:1024
	v_mul_f32_e32 v0, v165, v4
	v_fmac_f32_e32 v0, v163, v3
	v_fmac_f32_e32 v0, v164, v5
	v_mul_f32_e32 v0, v9, v0
	v_cvt_pk_bf16_f32 v2, v0, s0
	s_mov_b32 s0, 0x14007000
	v_add_co_u32_e32 v0, vcc, s0, v6
	s_mul_i32 s0, s27, 0x3c00
	s_nop 0
	v_addc_co_u32_e32 v1, vcc, 0, v7, vcc
	global_store_short v[0:1], v2, off offset:1024
	s_add_i32 s1, s1, s0
	s_mul_i32 s0, s26, 0x3c00
	v_lshl_add_u64 v[0:1], s[30:31], 0, v[192:193]
	s_mov_b64 s[22:23], 0x18401400
	s_mov_b64 s[12:13], s[60:61]
	s_addk_i32 s3, 0x3fe2
	v_lshl_add_u64 v[138:139], v[0:1], 0, s[22:23]
	v_lshl_add_u64 v[136:137], s[0:1], 2, v[124:125]
	v_mov_b32_e32 v4, 0
	v_mov_b32_e32 v0, 0
	v_mov_b32_e32 v8, 0
	v_mov_b32_e32 v9, 0
	v_mov_b32_e32 v10, 0
	v_mov_b32_e32 v11, 0
	v_mov_b32_e32 v12, 0
	v_mov_b32_e32 v13, 0
	v_mov_b32_e32 v14, 0
	v_mov_b32_e32 v15, 0
	v_mov_b32_e32 v5, 0
	v_mov_b32_e32 v6, 0
	v_mov_b32_e32 v7, 0
	v_readlane_b32 s57, v253, 9
	v_readlane_b32 s58, v253, 10
	v_readlane_b32 s59, v253, 11
	s_waitcnt lgkmcnt(0)
	s_barrier
	s_and_saveexec_b64 s[22:23], s[64:65]
	s_cbranch_execz .LBB0_209
	v_readlane_b32 s4, v254, 45
	v_readlane_b32 s5, v254, 46
	s_and_saveexec_b64 s[34:35], s[4:5]
	s_xor_b64 s[34:35], exec, s[34:35]
	s_cbranch_execz .LBB0_206
	v_add_u32_e32 v1, s3, v78
	v_mad_u64_u32 v[2:3], s[38:39], v1, s76, v[138:139]
	global_load_dwordx4 v[4:7], v[2:3], off

.LBB0_209:
	s_or_b64 exec, exec, s[22:23]
	v_mov_b32_e32 v1, 0
	v_mov_b32_e32 v2, 0
	v_mov_b32_e32 v3, 0
	v_mov_b32_e32 v20, 0
	v_mov_b32_e32 v21, 0
	v_mov_b32_e32 v22, 0
	v_mov_b32_e32 v23, 0
	v_mov_b32_e32 v16, 0
	v_mov_b32_e32 v17, 0
	v_mov_b32_e32 v18, 0
	v_mov_b32_e32 v19, 0
	s_and_saveexec_b64 s[22:23], s[36:37]
	s_cbranch_execz .LBB0_215
	v_readlane_b32 s4, v254, 49
	v_readlane_b32 s5, v254, 50
	s_and_saveexec_b64 s[34:35], s[4:5]
	s_xor_b64 s[34:35], exec, s[34:35]
	s_cbranch_execz .LBB0_212
	v_add_u32_e32 v0, s3, v82
	v_mad_u64_u32 v[0:1], s[38:39], v0, s76, v[138:139]
	global_load_dwordx4 v[16:19], v[0:1], off

.LBB0_215:
	s_or_b64 exec, exec, s[22:23]
	v_mov_b32_e32 v28, 0
	v_mov_b32_e32 v24, 0
	v_mov_b32_e32 v32, 0
	v_mov_b32_e32 v33, 0
	v_mov_b32_e32 v34, 0
	v_mov_b32_e32 v35, 0
	v_mov_b32_e32 v36, 0
	v_mov_b32_e32 v37, 0
	v_mov_b32_e32 v38, 0
	v_mov_b32_e32 v39, 0
	v_mov_b32_e32 v29, 0
	v_mov_b32_e32 v30, 0
	v_mov_b32_e32 v31, 0
	s_and_saveexec_b64 s[22:23], s[6:7]
	s_cbranch_execz .LBB0_221
	v_readlane_b32 s4, v254, 53
	v_readlane_b32 s5, v254, 54
	s_and_saveexec_b64 s[34:35], s[4:5]
	s_xor_b64 s[34:35], exec, s[34:35]
	s_cbranch_execz .LBB0_218
	v_add_u32_e32 v25, s3, v86
	v_mad_u64_u32 v[26:27], s[38:39], v25, s76, v[138:139]
	global_load_dwordx4 v[28:31], v[26:27], off

.LBB0_221:
	s_or_b64 exec, exec, s[22:23]
	v_mov_b32_e32 v25, 0
	v_mov_b32_e32 v26, 0
	v_mov_b32_e32 v27, 0
	v_mov_b32_e32 v44, 0
	v_mov_b32_e32 v45, 0
	v_mov_b32_e32 v46, 0
	v_mov_b32_e32 v47, 0
	v_mov_b32_e32 v40, 0
	v_mov_b32_e32 v41, 0
	v_mov_b32_e32 v42, 0
	v_mov_b32_e32 v43, 0
	s_and_saveexec_b64 s[22:23], s[90:91]
	s_cbranch_execz .LBB0_227
	v_readlane_b32 s4, v254, 57
	v_readlane_b32 s5, v254, 58
	s_and_saveexec_b64 s[34:35], s[4:5]
	s_xor_b64 s[34:35], exec, s[34:35]
	s_cbranch_execz .LBB0_224
	v_add_u32_e32 v24, s3, v108
	v_mad_u64_u32 v[24:25], s[38:39], v24, s76, v[138:139]
	global_load_dwordx4 v[40:43], v[24:25], off

.LBB0_227:
	s_or_b64 exec, exec, s[22:23]
	v_mov_b32_e32 v48, 0
	v_mov_b32_e32 v52, 0
	v_mov_b32_e32 v53, 0
	v_mov_b32_e32 v54, 0
	v_mov_b32_e32 v55, 0
	v_mov_b32_e32 v56, 0
	v_mov_b32_e32 v57, 0
	v_mov_b32_e32 v58, 0
	v_mov_b32_e32 v59, 0
	v_mov_b32_e32 v49, 0
	v_mov_b32_e32 v50, 0
	v_mov_b32_e32 v51, 0
	s_and_saveexec_b64 s[22:23], s[96:97]
	s_cbranch_execz .LBB0_233
	v_readlane_b32 s4, v254, 59
	v_readlane_b32 s5, v254, 60
	s_and_saveexec_b64 s[34:35], s[4:5]
	s_xor_b64 s[34:35], exec, s[34:35]
	s_cbranch_execz .LBB0_230
	v_add_u32_e32 v48, s3, v112
	v_mad_u64_u32 v[48:49], s[38:39], v48, s76, v[138:139]
	global_load_dwordx4 v[48:51], v[48:49], off

.LBB0_233:
	s_or_b64 exec, exec, s[22:23]
	s_lshl_b64 s[0:1], s[0:1], 2
	s_add_u32 s0, s12, s0
	s_addc_u32 s1, s13, s1
	v_mov_b32_e32 v135, v193
	v_lshl_add_u64 v[134:135], s[0:1], 0, v[134:135]
	s_mov_b64 s[0:1], 0x6df8000
	v_lshl_add_u64 v[134:135], v[134:135], 0, s[0:1]
	s_and_saveexec_b64 s[0:1], s[64:65]
	s_cbranch_execz .LBB0_236
	v_readlane_b32 s4, v254, 43
	s_waitcnt vmcnt(0) lgkmcnt(0)
	v_lshlrev_b32_e32 v129, 16, v4
	v_and_b32_e32 v131, 0xffff0000, v4
	v_lshlrev_b32_e32 v133, 16, v5
	v_and_b32_e32 v136, 0xffff0000, v5
	v_lshlrev_b32_e32 v4, 16, v6
	v_and_b32_e32 v5, 0xffff0000, v6
	v_lshlrev_b32_e32 v6, 16, v7
	v_and_b32_e32 v7, 0xffff0000, v7
	v_readlane_b32 s5, v254, 44
	v_readlane_b32 s12, v254, 27
	v_readlane_b32 s13, v254, 28
	v_cndmask_b32_e64 v7, v7, v15, s[4:5]
	v_cndmask_b32_e64 v6, v6, v14, s[4:5]
	v_cndmask_b32_e64 v5, v5, v13, s[4:5]
	v_cndmask_b32_e64 v4, v4, v12, s[4:5]
	v_cndmask_b32_e64 v11, v136, v11, s[4:5]
	v_cndmask_b32_e64 v10, v133, v10, s[4:5]
	v_cndmask_b32_e64 v9, v131, v9, s[4:5]
	v_cndmask_b32_e64 v8, v129, v8, s[4:5]
	ds_write_b128 v187, v[8:11]
	ds_write_b128 v187, v[4:7] offset:16
	s_and_b64 exec, exec, s[12:13]
	s_cbranch_execz .LBB0_236
	v_lshl_add_u64 v[12:13], v[134:135], 0, v[90:91]
	global_store_dwordx4 v[12:13], v[8:11], off
	global_store_dwordx4 v[12:13], v[4:7], off offset:16
.LBB0_236:
	s_or_b64 exec, exec, s[0:1]
	s_and_saveexec_b64 s[0:1], s[36:37]
	s_cbranch_execz .LBB0_239
	v_readlane_b32 s4, v254, 47
	s_waitcnt vmcnt(0) lgkmcnt(0)
	v_lshlrev_b32_e32 v8, 16, v16
	v_and_b32_e32 v9, 0xffff0000, v16
	v_lshlrev_b32_e32 v10, 16, v17
	v_and_b32_e32 v11, 0xffff0000, v17
	v_lshlrev_b32_e32 v4, 16, v18
	v_and_b32_e32 v5, 0xffff0000, v18
	v_lshlrev_b32_e32 v6, 16, v19
	v_and_b32_e32 v7, 0xffff0000, v19
	v_readlane_b32 s5, v254, 48
	v_readlane_b32 s12, v254, 29
	v_readlane_b32 s13, v254, 30
	v_cndmask_b32_e64 v7, v7, v23, s[4:5]
	v_cndmask_b32_e64 v6, v6, v22, s[4:5]
	v_cndmask_b32_e64 v5, v5, v21, s[4:5]
	v_cndmask_b32_e64 v4, v4, v20, s[4:5]
	v_cndmask_b32_e64 v3, v11, v3, s[4:5]
	v_cndmask_b32_e64 v2, v10, v2, s[4:5]
	v_cndmask_b32_e64 v1, v9, v1, s[4:5]
	v_cndmask_b32_e64 v0, v8, v0, s[4:5]
	ds_write_b128 v188, v[0:3]
	ds_write_b128 v188, v[4:7] offset:16
	s_and_b64 exec, exec, s[12:13]
	s_cbranch_execz .LBB0_239
	v_lshl_add_u64 v[8:9], v[134:135], 0, v[92:93]
	global_store_dwordx4 v[8:9], v[0:3], off
	global_store_dwordx4 v[8:9], v[4:7], off offset:16
.LBB0_239:
	s_or_b64 exec, exec, s[0:1]
	s_and_saveexec_b64 s[0:1], s[6:7]
	s_cbranch_execz .LBB0_242
	v_readlane_b32 s4, v254, 51
	s_waitcnt vmcnt(0) lgkmcnt(0)
	v_lshlrev_b32_e32 v4, 16, v28
	v_and_b32_e32 v5, 0xffff0000, v28
	v_lshlrev_b32_e32 v6, 16, v29
	v_and_b32_e32 v7, 0xffff0000, v29
	v_lshlrev_b32_e32 v0, 16, v30
	v_and_b32_e32 v1, 0xffff0000, v30
	v_lshlrev_b32_e32 v2, 16, v31
	v_and_b32_e32 v3, 0xffff0000, v31
	v_readlane_b32 s5, v254, 52
	v_readlane_b32 s12, v254, 31
	v_readlane_b32 s13, v254, 32
	v_cndmask_b32_e64 v3, v3, v39, s[4:5]
	v_cndmask_b32_e64 v2, v2, v38, s[4:5]
	v_cndmask_b32_e64 v1, v1, v37, s[4:5]
	v_cndmask_b32_e64 v0, v0, v36, s[4:5]
	v_cndmask_b32_e64 v7, v7, v35, s[4:5]
	v_cndmask_b32_e64 v6, v6, v34, s[4:5]
	v_cndmask_b32_e64 v5, v5, v33, s[4:5]
	v_cndmask_b32_e64 v4, v4, v32, s[4:5]
	ds_write_b128 v189, v[4:7]
	ds_write_b128 v189, v[0:3] offset:16
	s_and_b64 exec, exec, s[12:13]
	s_cbranch_execz .LBB0_242
	v_lshl_add_u64 v[8:9], v[134:135], 0, v[94:95]
	global_store_dwordx4 v[8:9], v[4:7], off
	global_store_dwordx4 v[8:9], v[0:3], off offset:16
.LBB0_242:
	s_or_b64 exec, exec, s[0:1]
	s_and_saveexec_b64 s[0:1], s[90:91]
	s_cbranch_execz .LBB0_245
	v_readlane_b32 s4, v254, 55
	s_waitcnt vmcnt(0) lgkmcnt(0)
	v_lshlrev_b32_e32 v4, 16, v40
	v_and_b32_e32 v5, 0xffff0000, v40
	v_lshlrev_b32_e32 v6, 16, v41
	v_and_b32_e32 v7, 0xffff0000, v41
	v_lshlrev_b32_e32 v0, 16, v42
	v_and_b32_e32 v1, 0xffff0000, v42
	v_lshlrev_b32_e32 v2, 16, v43
	v_and_b32_e32 v3, 0xffff0000, v43
	v_readlane_b32 s5, v254, 56
	s_nop 1
	v_cndmask_b32_e64 v3, v3, v47, s[4:5]
	v_cndmask_b32_e64 v2, v2, v46, s[4:5]
	v_cndmask_b32_e64 v1, v1, v45, s[4:5]
	v_cndmask_b32_e64 v0, v0, v44, s[4:5]
	v_cndmask_b32_e64 v7, v7, v27, s[4:5]
	v_cndmask_b32_e64 v6, v6, v26, s[4:5]
	v_cndmask_b32_e64 v5, v5, v25, s[4:5]
	v_cndmask_b32_e64 v4, v4, v24, s[4:5]
	v_readlane_b32 s4, v254, 61
	v_readlane_b32 s5, v254, 62
	ds_write_b128 v185, v[4:7]
	ds_write_b128 v185, v[0:3] offset:16
	s_and_b64 exec, exec, s[4:5]
	s_cbranch_execz .LBB0_245
	v_lshl_add_u64 v[8:9], v[134:135], 0, v[116:117]
	global_store_dwordx4 v[8:9], v[4:7], off
	global_store_dwordx4 v[8:9], v[0:3], off offset:16
.LBB0_245:
	s_or_b64 exec, exec, s[0:1]
	s_and_saveexec_b64 s[0:1], s[96:97]
	s_cbranch_execz .LBB0_248
	s_waitcnt vmcnt(0) lgkmcnt(0)
	v_lshlrev_b32_e32 v4, 16, v48
	v_and_b32_e32 v5, 0xffff0000, v48
	v_lshlrev_b32_e32 v6, 16, v49
	v_and_b32_e32 v7, 0xffff0000, v49
	v_lshlrev_b32_e32 v0, 16, v50
	v_and_b32_e32 v1, 0xffff0000, v50
	v_lshlrev_b32_e32 v2, 16, v51
	v_and_b32_e32 v3, 0xffff0000, v51
	v_readlane_b32 s4, v254, 63
	v_cndmask_b32_e64 v3, v3, v59, s[54:55]
	v_cndmask_b32_e64 v2, v2, v58, s[54:55]
	v_cndmask_b32_e64 v1, v1, v57, s[54:55]
	v_cndmask_b32_e64 v0, v0, v56, s[54:55]
	v_cndmask_b32_e64 v7, v7, v55, s[54:55]
	v_cndmask_b32_e64 v6, v6, v54, s[54:55]
	v_cndmask_b32_e64 v5, v5, v53, s[54:55]
	v_cndmask_b32_e64 v4, v4, v52, s[54:55]
	v_readlane_b32 s5, v255, 0
	ds_write_b128 v186, v[4:7]
	ds_write_b128 v186, v[0:3] offset:16
	s_and_b64 exec, exec, s[4:5]
	s_cbranch_execz .LBB0_248
	v_lshl_add_u64 v[8:9], v[134:135], 0, v[118:119]
	global_store_dwordx4 v[8:9], v[4:7], off
	global_store_dwordx4 v[8:9], v[0:3], off offset:16

.LBB0_264:
	s_or_b64 exec, exec, s[0:1]
	v_readlane_b32 s56, v253, 8
	v_readlane_b32 s62, v253, 14
	v_readlane_b32 s63, v253, 15
	v_readlane_b32 s3, v251, 9
	s_mov_b64 s[0:1], s[62:63]
	s_waitcnt lgkmcnt(0)
	v_mov_b32_e32 v1, s3
	v_readlane_b32 s3, v251, 10
	s_barrier
	ds_read_b128 v[8:11], v1
	v_mov_b32_e32 v1, s3
	v_readlane_b32 s3, v251, 11
	ds_read_b128 v[12:15], v1
	s_mov_b32 s22, 0x3b000000
	v_mov_b32_e32 v5, s3
	v_readlane_b32 s3, v251, 12
	ds_read_b128 v[16:19], v5
	s_waitcnt lgkmcnt(2)
	v_add_f32_e32 v1, 0, v8
	v_mov_b32_e32 v5, s3
	v_readlane_b32 s3, v251, 13
	ds_read_b128 v[20:23], v5
	s_waitcnt lgkmcnt(2)
	v_add_f32_e32 v1, v1, v12
	v_mov_b32_e32 v5, s3
	v_readlane_b32 s3, v251, 14
	ds_read_b128 v[24:27], v5
	v_add_f32_e32 v3, 0, v9
	v_mov_b32_e32 v5, s3
	v_readlane_b32 s3, v251, 15
	ds_read_b128 v[28:31], v5
	s_waitcnt lgkmcnt(3)
	v_add_f32_e32 v1, v1, v16
	v_mov_b32_e32 v5, s3
	v_readlane_b32 s3, v251, 16
	ds_read_b128 v[40:43], v5
	v_add_f32_e32 v3, v3, v13
	v_mov_b32_e32 v5, s3
	ds_read_b128 v[50:53], v5
	s_waitcnt lgkmcnt(4)
	v_add_f32_e32 v1, v1, v20
	v_add_f32_e32 v3, v3, v17
	s_waitcnt lgkmcnt(3)
	v_add_f32_e32 v1, v1, v24
	v_add_f32_e32 v3, v3, v21
	s_waitcnt lgkmcnt(2)
	v_add_f32_e32 v1, v1, v28
	v_add_f32_e32 v3, v3, v25
	s_waitcnt lgkmcnt(1)
	v_add_f32_e32 v1, v1, v40
	v_add_f32_e32 v3, v3, v29
	s_waitcnt lgkmcnt(0)
	v_add_f32_e32 v1, v1, v50
	v_add_f32_e32 v3, v3, v41
	v_mul_f32_e32 v5, 0x3b000000, v1
	v_add_f32_e32 v3, v3, v51
	v_mul_f32_e32 v5, v5, v5
	v_fma_f32 v3, v3, s22, -v5
	v_max_f32_e32 v3, 0, v3
	v_add_f32_e32 v3, 0x358637bd, v3
	v_rsq_f32_e32 v3, v3
	v_fmac_f32_e32 v0, 0xbb000000, v1
	v_add_f32_e32 v7, 0, v11
	v_add_f32_e32 v7, v7, v15
	v_mul_f32_e32 v0, v0, v3
	v_fma_f32 v3, v143, v0, v142
	v_mul_f32_e32 v0, 0xbfb8aa3b, v3
	v_exp_f32_e32 v0, v0
	v_add_f32_e32 v7, v7, v19
	v_add_f32_e32 v7, v7, v23
	v_add_f32_e32 v7, v7, v27
	v_add_f32_e32 v0, 1.0, v0
	v_rcp_f32_e32 v5, v0
	v_add_f32_e32 v7, v7, v31
	v_add_f32_e32 v7, v7, v43
	v_add_f32_e32 v7, v7, v53
	v_mul_f32_e32 v3, v3, v5
	v_add_f32_e32 v5, 0, v10
	v_add_f32_e32 v5, v5, v14
	v_add_f32_e32 v5, v5, v18
	v_add_f32_e32 v5, v5, v22
	v_add_f32_e32 v5, v5, v26
	v_add_f32_e32 v5, v5, v30
	v_add_f32_e32 v5, v5, v42
	v_add_f32_e32 v5, v5, v52
	v_mul_f32_e32 v8, 0x3b000000, v5
	v_mul_f32_e32 v8, v8, v8
	s_add_u32 s0, s0, s28
	v_fma_f32 v7, v7, s22, -v8
	s_addc_u32 s1, s1, s29
	v_max_f32_e32 v7, 0, v7
	s_add_i32 s13, 0, 0x22010
	v_add_f32_e32 v7, 0x358637bd, v7
	v_fmac_f32_e32 v2, 0xbb000000, v5
	v_mov_b32_e32 v5, s13
	v_rsq_f32_e32 v7, v7
	ds_read_b128 v[8:11], v5
	v_lshl_add_u64 v[0:1], v[64:65], 1, s[0:1]
	v_cvt_pk_bf16_f32 v3, v3, s0
	v_readlane_b32 s0, v251, 17
	v_mul_f32_e32 v2, v2, v7
	v_fma_f32 v2, v143, v2, v142
	v_mov_b32_e32 v7, s0
	v_readlane_b32 s0, v251, 18
	ds_read_b128 v[12:15], v7
	s_waitcnt lgkmcnt(1)
	v_add_f32_e32 v7, 0, v8
	v_add_f32_e32 v8, 0, v9
	v_mov_b32_e32 v9, s0
	v_readlane_b32 s0, v251, 19
	ds_read_b128 v[16:19], v9
	s_waitcnt lgkmcnt(1)
	v_add_f32_e32 v7, v7, v12
	v_mov_b32_e32 v9, s0
	v_readlane_b32 s0, v251, 20
	ds_read_b128 v[20:23], v9
	s_waitcnt lgkmcnt(1)
	v_add_f32_e32 v7, v7, v16
	v_mov_b32_e32 v9, s0
	v_readlane_b32 s0, v251, 21
	ds_read_b128 v[24:27], v9
	v_add_f32_e32 v8, v8, v13
	v_mov_b32_e32 v9, s0
	v_readlane_b32 s0, v251, 22
	ds_read_b128 v[28:31], v9
	s_waitcnt lgkmcnt(2)
	v_add_f32_e32 v7, v7, v20
	v_mov_b32_e32 v9, s0
	v_readlane_b32 s0, v251, 23
	ds_read_b128 v[40:43], v9
	v_add_f32_e32 v8, v8, v17
	v_mov_b32_e32 v9, s0
	ds_read_b128 v[50:53], v9
	s_waitcnt lgkmcnt(3)
	v_add_f32_e32 v7, v7, v24
	v_add_f32_e32 v8, v8, v21
	s_waitcnt lgkmcnt(2)
	v_add_f32_e32 v7, v7, v28
	v_add_f32_e32 v8, v8, v25
	s_waitcnt lgkmcnt(1)
	v_add_f32_e32 v7, v7, v40
	v_add_f32_e32 v8, v8, v29
	s_waitcnt lgkmcnt(0)
	v_add_f32_e32 v7, v7, v50
	v_add_f32_e32 v8, v8, v41
	v_mul_f32_e32 v9, 0x3b000000, v7
	v_add_f32_e32 v8, v8, v51
	v_mul_f32_e32 v9, v9, v9
	v_fma_f32 v8, v8, s22, -v9
	v_max_f32_e32 v8, 0, v8
	v_add_f32_e32 v8, 0x358637bd, v8
	v_mul_f32_e32 v5, 0xbfb8aa3b, v2
	v_rsq_f32_e32 v8, v8
	v_exp_f32_e32 v5, v5
	v_fmac_f32_e32 v4, 0xbb000000, v7
	v_add_co_u32_e32 v54, vcc, s33, v0
	v_mul_f32_e32 v4, v4, v8
	v_add_f32_e32 v5, 1.0, v5
	v_fma_f32 v4, v143, v4, v142
	v_rcp_f32_e32 v5, v5
	v_mul_f32_e32 v7, 0xbfb8aa3b, v4
	v_exp_f32_e32 v7, v7
	v_addc_co_u32_e32 v55, vcc, 0, v1, vcc
	v_mul_f32_e32 v2, v2, v5
	v_cvt_pk_bf16_f32 v5, v2, s0
	v_add_f32_e32 v2, 1.0, v7
	v_rcp_f32_e32 v7, v2
	v_add_co_u32_e32 v2, vcc, s48, v0
	global_store_short v[54:55], v3, off offset:3072
	s_nop 0
	v_addc_co_u32_e32 v3, vcc, 0, v1, vcc
	global_store_short v[2:3], v5, off offset:3072
	v_mul_f32_e32 v2, v4, v7
	v_cvt_pk_bf16_f32 v4, v2, s0
	v_add_f32_e32 v2, 0, v10
	v_add_f32_e32 v3, 0, v11
	v_add_f32_e32 v2, v2, v14
	v_add_f32_e32 v3, v3, v15
	v_add_f32_e32 v2, v2, v18
	v_add_f32_e32 v3, v3, v19
	v_add_f32_e32 v2, v2, v22
	v_add_f32_e32 v3, v3, v23
	v_add_f32_e32 v2, v2, v26
	v_add_f32_e32 v3, v3, v27
	v_add_f32_e32 v2, v2, v30
	v_add_f32_e32 v3, v3, v31
	v_add_f32_e32 v2, v2, v42
	v_add_f32_e32 v3, v3, v43
	v_add_f32_e32 v5, v2, v52
	v_add_f32_e32 v2, v3, v53
	v_mul_f32_e32 v3, 0x3b000000, v5
	v_mul_f32_e32 v3, v3, v3
	v_fma_f32 v2, v2, s22, -v3
	v_max_f32_e32 v2, 0, v2
	v_add_f32_e32 v2, 0x358637bd, v2
	v_rsq_f32_e32 v7, v2
	s_mov_b32 s0, 0x14002000
	v_add_co_u32_e32 v2, vcc, s0, v0
	v_fmac_f32_e32 v32, 0xbb000000, v5
	s_nop 0
	v_addc_co_u32_e32 v3, vcc, 0, v1, vcc
	global_store_short v[2:3], v4, off offset:3072
	v_mul_f32_e32 v2, v32, v7
	v_fma_f32 v7, v143, v2, v142
	v_mul_f32_e32 v2, 0xbfb8aa3b, v7
	v_exp_f32_e32 v8, v2
	s_add_i32 s12, 0, 0x22020
	v_mov_b32_e32 v2, s12
	v_readlane_b32 s0, v251, 24
	v_add_f32_e32 v8, 1.0, v8
	ds_read_b128 v[2:5], v2
	v_rcp_f32_e32 v32, v8
	v_mov_b32_e32 v8, s0
	ds_read_b128 v[8:11], v8
	v_readlane_b32 s0, v251, 25
	s_waitcnt lgkmcnt(0)
	v_add_f32_e32 v2, 0, v2
	v_add_f32_e32 v3, 0, v3
	v_mov_b32_e32 v12, s0
	v_readlane_b32 s0, v251, 26
	ds_read_b128 v[12:15], v12
	v_add_f32_e32 v2, v2, v8
	v_mov_b32_e32 v8, s0
	v_readlane_b32 s0, v251, 27
	ds_read_b128 v[16:19], v8
	s_waitcnt lgkmcnt(0)
	v_add_f32_e32 v2, v2, v12
	v_mov_b32_e32 v8, s0
	v_readlane_b32 s0, v251, 28
	ds_read_b128 v[20:23], v8
	v_add_f32_e32 v3, v3, v9
	v_mov_b32_e32 v8, s0
	v_readlane_b32 s0, v251, 29
	ds_read_b128 v[24:27], v8
	v_add_f32_e32 v2, v2, v16
	v_mov_b32_e32 v8, s0
	v_readlane_b32 s0, v251, 30
	ds_read_b128 v[28:31], v8
	v_add_f32_e32 v3, v3, v13
	v_mov_b32_e32 v8, s0
	ds_read_b128 v[40:43], v8
	s_waitcnt lgkmcnt(0)
	v_add_f32_e32 v2, v2, v20
	v_add_f32_e32 v3, v3, v17
	v_add_f32_e32 v2, v2, v24
	v_add_f32_e32 v3, v3, v21
	v_add_f32_e32 v2, v2, v28
	v_add_f32_e32 v3, v3, v25
	v_add_f32_e32 v2, v2, v40
	v_add_f32_e32 v3, v3, v29
	v_mul_f32_e32 v8, 0x3b000000, v2
	v_add_f32_e32 v3, v3, v41
	v_mul_f32_e32 v8, v8, v8
	v_fma_f32 v3, v3, s22, -v8
	v_max_f32_e32 v3, 0, v3
	v_add_f32_e32 v3, 0x358637bd, v3
	v_rsq_f32_e32 v3, v3
	v_fmac_f32_e32 v34, 0xbb000000, v2
	v_mul_f32_e32 v7, v7, v32
	v_cvt_pk_bf16_f32 v7, v7, s0
	v_mul_f32_e32 v2, v34, v3
	v_fma_f32 v8, v143, v2, v142
	v_mul_f32_e32 v2, 0xbfb8aa3b, v8
	s_mov_b32 s0, 0x14003000
	v_exp_f32_e32 v9, v2
	v_add_co_u32_e32 v2, vcc, s0, v0
	s_add_i32 s3, 0, 0x22030
	s_nop 0
	v_addc_co_u32_e32 v3, vcc, 0, v1, vcc
	global_store_short v[2:3], v7, off offset:3072
	v_add_f32_e32 v3, 0, v4
	v_add_f32_e32 v3, v3, v10
	v_add_f32_e32 v4, 0, v5
	v_add_f32_e32 v3, v3, v14
	v_add_f32_e32 v4, v4, v11
	v_add_f32_e32 v3, v3, v18
	v_add_f32_e32 v4, v4, v15
	v_add_f32_e32 v3, v3, v22
	v_add_f32_e32 v4, v4, v19
	v_add_f32_e32 v3, v3, v26
	v_add_f32_e32 v4, v4, v23
	v_add_f32_e32 v3, v3, v30
	v_add_f32_e32 v4, v4, v27
	v_add_f32_e32 v3, v3, v42
	v_add_f32_e32 v4, v4, v31
	v_mul_f32_e32 v5, 0x3b000000, v3
	v_add_f32_e32 v4, v4, v43
	v_mul_f32_e32 v5, v5, v5
	v_fma_f32 v4, v4, s22, -v5
	v_add_f32_e32 v2, 1.0, v9
	v_max_f32_e32 v4, 0, v4
	v_rcp_f32_e32 v2, v2
	v_add_f32_e32 v4, 0x358637bd, v4
	v_rsq_f32_e32 v4, v4
	v_fmac_f32_e32 v36, 0xbb000000, v3
	v_mul_f32_e32 v2, v8, v2
	v_cvt_pk_bf16_f32 v5, v2, s0
	v_mul_f32_e32 v2, v36, v4
	v_fma_f32 v7, v143, v2, v142
	v_mul_f32_e32 v2, 0xbfb8aa3b, v7
	v_exp_f32_e32 v4, v2
	s_mov_b32 s0, 0x14004000
	v_add_co_u32_e32 v2, vcc, s0, v0
	v_readlane_b32 s57, v253, 9
	s_nop 0
	v_addc_co_u32_e32 v3, vcc, 0, v1, vcc
	global_store_short v[2:3], v5, off offset:3072
	v_add_f32_e32 v2, 1.0, v4
	v_rcp_f32_e32 v8, v2
	v_mov_b32_e32 v2, s3
	ds_read_b128 v[2:5], v2
	v_readlane_b32 s58, v253, 10
	v_mul_f32_e32 v7, v7, v8
	v_cvt_pk_bf16_f32 v7, v7, s0
	v_readlane_b32 s0, v251, 31
	v_readlane_b32 s59, v253, 11
	v_readlane_b32 s60, v253, 12
	v_mov_b32_e32 v8, s0
	ds_read_b128 v[8:11], v8
	v_readlane_b32 s0, v251, 32
	s_waitcnt lgkmcnt(0)
	v_add_f32_e32 v2, 0, v2
	v_add_f32_e32 v3, 0, v3
	v_mov_b32_e32 v12, s0
	v_readlane_b32 s0, v251, 33
	ds_read_b128 v[12:15], v12
	v_add_f32_e32 v2, v2, v8
	v_mov_b32_e32 v8, s0
	v_readlane_b32 s0, v251, 34
	ds_read_b128 v[16:19], v8
	v_add_f32_e32 v3, v3, v9
	v_mov_b32_e32 v8, s0
	v_readlane_b32 s0, v251, 35
	ds_read_b128 v[20:23], v8
	s_waitcnt lgkmcnt(0)
	v_add_f32_e32 v2, v2, v12
	v_mov_b32_e32 v8, s0
	v_readlane_b32 s0, v251, 36
	ds_read_b128 v[24:27], v8
	v_add_f32_e32 v3, v3, v13
	v_mov_b32_e32 v8, s0
	v_readlane_b32 s0, v251, 37
	ds_read_b128 v[28:31], v8
	v_add_f32_e32 v2, v2, v16
	v_mov_b32_e32 v8, s0
	ds_read_b128 v[32:35], v8
	v_add_f32_e32 v3, v3, v17
	v_add_f32_e32 v2, v2, v20
	v_add_f32_e32 v3, v3, v21
	s_waitcnt lgkmcnt(0)
	v_add_f32_e32 v2, v2, v24
	v_add_f32_e32 v3, v3, v25
	v_add_f32_e32 v2, v2, v28
	v_add_f32_e32 v4, 0, v4
	v_add_f32_e32 v3, v3, v29
	v_add_f32_e32 v8, v2, v32
	v_add_f32_e32 v4, v4, v10
	v_add_f32_e32 v2, v3, v33
	v_mul_f32_e32 v3, 0x3b000000, v8
	v_add_f32_e32 v5, 0, v5
	v_add_f32_e32 v4, v4, v14
	v_mul_f32_e32 v3, v3, v3
	v_add_f32_e32 v5, v5, v11
	v_add_f32_e32 v4, v4, v18
	v_fma_f32 v2, v2, s22, -v3
	v_add_f32_e32 v5, v5, v15
	v_add_f32_e32 v4, v4, v22
	v_max_f32_e32 v2, 0, v2
	v_add_f32_e32 v5, v5, v19
	v_add_f32_e32 v4, v4, v26
	v_add_f32_e32 v2, 0x358637bd, v2
	v_add_f32_e32 v5, v5, v23
	v_add_f32_e32 v4, v4, v30
	v_rsq_f32_e32 v9, v2
	v_add_f32_e32 v5, v5, v27
	v_add_f32_e32 v4, v4, v34
	v_add_f32_e32 v5, v5, v31
	v_mul_f32_e32 v10, 0x3b000000, v4
	v_add_f32_e32 v5, v5, v35
	v_mul_f32_e32 v10, v10, v10
	v_fmac_f32_e32 v38, 0xbb000000, v8
	v_fma_f32 v5, v5, s22, -v10
	v_mul_f32_e32 v8, v38, v9
	v_max_f32_e32 v5, 0, v5
	v_fma_f32 v8, v143, v8, v142
	v_add_f32_e32 v5, 0x358637bd, v5
	v_mul_f32_e32 v9, 0xbfb8aa3b, v8
	v_rsq_f32_e32 v5, v5
	v_exp_f32_e32 v9, v9
	v_fmac_f32_e32 v6, 0xbb000000, v4
	s_mov_b32 s0, 0x14005000
	v_mul_f32_e32 v4, v6, v5
	v_add_f32_e32 v9, 1.0, v9
	v_fma_f32 v4, v143, v4, v142
	v_rcp_f32_e32 v9, v9
	v_mul_f32_e32 v5, 0xbfb8aa3b, v4
	v_exp_f32_e32 v5, v5
	v_add_co_u32_e32 v2, vcc, s0, v0
	v_readlane_b32 s61, v253, 13
	s_nop 0
	v_addc_co_u32_e32 v3, vcc, 0, v1, vcc
	global_store_short v[2:3], v7, off offset:3072
	v_mul_f32_e32 v2, v8, v9
	v_cvt_pk_bf16_f32 v6, v2, s0
	v_add_f32_e32 v2, 1.0, v5
	v_rcp_f32_e32 v5, v2
	s_mov_b32 s0, 0x14006000
	v_add_co_u32_e32 v2, vcc, s0, v0
	s_nop 1
	v_addc_co_u32_e32 v3, vcc, 0, v1, vcc
	global_store_short v[2:3], v6, off offset:3072
	v_mul_f32_e32 v2, v4, v5
	v_add_co_u32_e32 v0, vcc, 0x14007000, v0
	v_cvt_pk_bf16_f32 v2, v2, s0
	s_nop 0
	v_addc_co_u32_e32 v1, vcc, 0, v1, vcc
	global_store_short v[0:1], v2, off offset:3072
	v_mov_b32_e32 v0, 0
	v_mov_b32_e32 v1, 0
	v_mov_b32_e32 v2, 0
	v_mov_b32_e32 v3, 0
	s_waitcnt lgkmcnt(0)
	s_barrier
	s_and_saveexec_b64 s[0:1], s[68:69]
	s_cbranch_execz .LBB0_266
	v_mov_b64_e32 v[0:1], s[30:31]
	v_mad_u64_u32 v[0:1], s[22:23], v127, s76, v[0:1]
	v_lshl_add_u64 v[0:1], v[0:1], 0, v[192:193]
	v_add_co_u32_e32 v0, vcc, 0x18401000, v0
	s_nop 1
	v_addc_co_u32_e32 v1, vcc, 0, v1, vcc
	global_load_dwordx4 v[0:3], v[0:1], off

.LBB0_268:
	s_or_b64 exec, exec, s[0:1]
	s_waitcnt vmcnt(0) lgkmcnt(0)
	v_mov_b32_e32 v0, 0
	v_mov_b32_e32 v1, 0
	v_mov_b32_e32 v2, 0
	v_mov_b32_e32 v3, 0
	s_and_saveexec_b64 s[0:1], s[68:69]
	s_cbranch_execz .LBB0_270
	v_mov_b64_e32 v[0:1], s[30:31]
	v_mad_u64_u32 v[0:1], s[22:23], v127, s76, v[0:1]
	v_lshl_add_u64 v[0:1], v[0:1], 0, v[192:193]
	v_add_co_u32_e32 v0, vcc, 0x18400000, v0
	s_nop 1
	v_addc_co_u32_e32 v1, vcc, 0, v1, vcc
	global_load_dwordx4 v[0:3], v[0:1], off offset:3072

.LBB0_288:
	s_or_b64 exec, exec, s[0:1]
	v_readlane_b32 s56, v253, 8
	v_readlane_b32 s60, v253, 12
	v_readlane_b32 s61, v253, 13
	s_mov_b64 s[0:1], s[60:61]
	s_waitcnt lgkmcnt(0)
	s_barrier
	s_lshl_b64 s[22:23], s[26:27], 14
	s_add_u32 s0, s0, s22
	s_addc_u32 s1, s1, s23
	v_lshl_add_u64 v[4:5], v[64:65], 2, s[0:1]
	s_mov_b64 s[0:1], 0x7cf8000
	v_lshl_add_u64 v[18:19], v[4:5], 0, s[0:1]
	v_readlane_b32 s0, v251, 9
	s_mov_b32 s22, 0x3b000000
	v_readlane_b32 s62, v253, 14
	v_mov_b32_e32 v1, s0
	ds_read_b64 v[20:21], v1
	v_readlane_b32 s0, v251, 10
	v_readlane_b32 s63, v253, 15
	v_readlane_b32 s57, v253, 9
	v_mov_b32_e32 v7, s0
	s_waitcnt lgkmcnt(0)
	v_add_f32_e32 v1, 0, v20
	v_add_f32_e32 v3, 0, v21
	ds_read_b64 v[20:21], v7
	v_readlane_b32 s0, v251, 11
	v_readlane_b32 s58, v253, 10
	v_readlane_b32 s59, v253, 11
	v_mov_b32_e32 v7, s0
	s_waitcnt lgkmcnt(0)
	v_add_f32_e32 v1, v1, v20
	v_add_f32_e32 v3, v3, v21
	ds_read_b64 v[20:21], v7
	v_readlane_b32 s0, v251, 12
	s_waitcnt lgkmcnt(0)
	v_add_f32_e32 v1, v1, v20
	v_mov_b32_e32 v7, s0
	v_add_f32_e32 v3, v3, v21
	ds_read_b64 v[20:21], v7
	v_readlane_b32 s0, v251, 13
	s_waitcnt lgkmcnt(0)
	v_add_f32_e32 v1, v1, v20
	v_mov_b32_e32 v7, s0
	v_add_f32_e32 v3, v3, v21
	ds_read_b64 v[20:21], v7
	v_readlane_b32 s0, v251, 14
	s_waitcnt lgkmcnt(0)
	v_add_f32_e32 v1, v1, v20
	v_mov_b32_e32 v7, s0
	v_add_f32_e32 v3, v3, v21
	ds_read_b64 v[20:21], v7
	v_readlane_b32 s0, v251, 15
	s_waitcnt lgkmcnt(0)
	v_add_f32_e32 v1, v1, v20
	v_mov_b32_e32 v7, s0
	v_add_f32_e32 v3, v3, v21
	ds_read_b64 v[20:21], v7
	v_readlane_b32 s0, v251, 16
	s_waitcnt lgkmcnt(0)
	v_add_f32_e32 v1, v1, v20
	v_mov_b32_e32 v7, s0
	v_add_f32_e32 v3, v3, v21
	ds_read_b64 v[20:21], v7
	s_mov_b32 s0, 0x7cf8000
	s_waitcnt lgkmcnt(0)
	v_add_f32_e32 v1, v1, v20
	v_mul_f32_e32 v7, 0x3b000000, v1
	v_add_f32_e32 v3, v3, v21
	v_mul_f32_e32 v7, v7, v7
	v_fma_f32 v3, v3, s22, -v7
	v_max_f32_e32 v3, 0, v3
	v_add_f32_e32 v3, 0x358637bd, v3
	v_rsq_f32_e32 v3, v3
	v_fmac_f32_e32 v16, 0xbb000000, v1
	v_mul_f32_e32 v1, v16, v3
	v_add_co_u32_e32 v16, vcc, s0, v4
	v_fma_f32 v7, v141, v1, v140
	s_nop 0
	v_addc_co_u32_e32 v17, vcc, 0, v5, vcc
	s_add_i32 s0, 0, 0x22008
	global_store_dword v[16:17], v7, off
	v_mov_b32_e32 v1, s0
	ds_read_b64 v[16:17], v1
	v_readlane_b32 s0, v251, 38
	s_waitcnt lgkmcnt(0)
	v_add_f32_e32 v1, 0, v16
	v_mov_b32_e32 v9, s0
	v_add_f32_e32 v3, 0, v17
	ds_read_b64 v[16:17], v9
	v_readlane_b32 s0, v251, 39
	s_waitcnt lgkmcnt(0)
	v_add_f32_e32 v1, v1, v16
	v_mov_b32_e32 v9, s0
	v_add_f32_e32 v3, v3, v17
	ds_read_b64 v[16:17], v9
	v_readlane_b32 s0, v251, 40
	s_waitcnt lgkmcnt(0)
	v_add_f32_e32 v1, v1, v16
	v_mov_b32_e32 v9, s0
	v_add_f32_e32 v3, v3, v17
	ds_read_b64 v[16:17], v9
	v_readlane_b32 s0, v251, 41
	s_waitcnt lgkmcnt(0)
	v_add_f32_e32 v1, v1, v16
	v_mov_b32_e32 v9, s0
	v_add_f32_e32 v3, v3, v17
	ds_read_b64 v[16:17], v9
	v_readlane_b32 s0, v251, 42
	s_waitcnt lgkmcnt(0)
	v_add_f32_e32 v1, v1, v16
	v_mov_b32_e32 v9, s0
	v_add_f32_e32 v3, v3, v17
	ds_read_b64 v[16:17], v9
	v_readlane_b32 s0, v251, 43
	s_waitcnt lgkmcnt(0)
	v_add_f32_e32 v1, v1, v16
	v_mov_b32_e32 v9, s0
	v_add_f32_e32 v3, v3, v17
	ds_read_b64 v[16:17], v9
	v_readlane_b32 s0, v251, 44
	s_waitcnt lgkmcnt(0)
	v_add_f32_e32 v1, v1, v16
	v_mov_b32_e32 v9, s0
	v_add_f32_e32 v3, v3, v17
	ds_read_b64 v[16:17], v9
	v_readlane_b32 s0, v251, 17
	s_waitcnt lgkmcnt(0)
	v_add_f32_e32 v1, v1, v16
	v_mul_f32_e32 v9, 0x3b000000, v1
	v_add_f32_e32 v3, v3, v17
	v_mul_f32_e32 v9, v9, v9
	v_fma_f32 v3, v3, s22, -v9
	v_max_f32_e32 v3, 0, v3
	v_add_f32_e32 v3, 0x358637bd, v3
	v_rsq_f32_e32 v3, v3
	v_fmac_f32_e32 v14, 0xbb000000, v1
	v_mov_b32_e32 v9, s0
	v_readlane_b32 s0, v251, 18
	v_mul_f32_e32 v1, v14, v3
	v_fma_f32 v11, v141, v1, v140
	global_store_dword v[18:19], v11, off offset:2048
	v_mov_b32_e32 v1, s13
	ds_read_b64 v[14:15], v1
	s_waitcnt lgkmcnt(0)
	v_add_f32_e32 v1, 0, v14
	v_add_f32_e32 v3, 0, v15
	ds_read_b64 v[14:15], v9
	v_mov_b32_e32 v9, s0
	v_readlane_b32 s0, v251, 19
	s_waitcnt lgkmcnt(0)
	v_add_f32_e32 v1, v1, v14
	v_add_f32_e32 v3, v3, v15
	ds_read_b64 v[14:15], v9
	v_mov_b32_e32 v9, s0
	v_readlane_b32 s0, v251, 20
	s_waitcnt lgkmcnt(0)
	v_add_f32_e32 v1, v1, v14
	v_add_f32_e32 v3, v3, v15
	ds_read_b64 v[14:15], v9
	v_mov_b32_e32 v9, s0
	v_readlane_b32 s0, v251, 21
	s_waitcnt lgkmcnt(0)
	v_add_f32_e32 v1, v1, v14
	v_add_f32_e32 v3, v3, v15
	ds_read_b64 v[14:15], v9
	v_mov_b32_e32 v9, s0
	v_readlane_b32 s0, v251, 22
	s_waitcnt lgkmcnt(0)
	v_add_f32_e32 v1, v1, v14
	v_add_f32_e32 v3, v3, v15
	ds_read_b64 v[14:15], v9
	v_mov_b32_e32 v9, s0
	v_readlane_b32 s0, v251, 23
	s_waitcnt lgkmcnt(0)
	v_add_f32_e32 v1, v1, v14
	v_add_f32_e32 v3, v3, v15
	ds_read_b64 v[14:15], v9
	v_mov_b32_e32 v9, s0
	s_mov_b32 s0, 0x7cf9000
	s_waitcnt lgkmcnt(0)
	v_add_f32_e32 v1, v1, v14
	v_add_f32_e32 v3, v3, v15
	ds_read_b64 v[14:15], v9
	s_waitcnt lgkmcnt(0)
	v_add_f32_e32 v1, v1, v14
	v_mul_f32_e32 v9, 0x3b000000, v1
	v_add_f32_e32 v3, v3, v15
	v_mul_f32_e32 v9, v9, v9
	v_fma_f32 v3, v3, s22, -v9
	v_max_f32_e32 v3, 0, v3
	v_add_f32_e32 v3, 0x358637bd, v3
	v_rsq_f32_e32 v3, v3
	v_fmac_f32_e32 v12, 0xbb000000, v1
	v_add_co_u32_e32 v14, vcc, s0, v4
	v_mul_f32_e32 v1, v12, v3
	v_fma_f32 v12, v141, v1, v140
	v_addc_co_u32_e32 v15, vcc, 0, v5, vcc
	s_add_i32 s0, 0, 0x22018
	global_store_dword v[14:15], v12, off
	v_mov_b32_e32 v1, s0
	ds_read_b64 v[16:17], v1
	v_readlane_b32 s0, v251, 45
	s_waitcnt lgkmcnt(0)
	v_add_f32_e32 v1, 0, v16
	v_mov_b32_e32 v9, s0
	v_add_f32_e32 v3, 0, v17
	ds_read_b64 v[16:17], v9
	v_readlane_b32 s0, v251, 46
	s_waitcnt lgkmcnt(0)
	v_add_f32_e32 v1, v1, v16
	v_mov_b32_e32 v9, s0
	v_add_f32_e32 v3, v3, v17
	ds_read_b64 v[16:17], v9
	v_readlane_b32 s0, v251, 47
	s_waitcnt lgkmcnt(0)
	v_add_f32_e32 v1, v1, v16
	v_mov_b32_e32 v9, s0
	v_add_f32_e32 v3, v3, v17
	ds_read_b64 v[16:17], v9
	v_readlane_b32 s0, v251, 48
	s_waitcnt lgkmcnt(0)
	v_add_f32_e32 v1, v1, v16
	v_mov_b32_e32 v9, s0
	v_add_f32_e32 v3, v3, v17
	ds_read_b64 v[16:17], v9
	v_readlane_b32 s0, v251, 49
	s_waitcnt lgkmcnt(0)
	v_add_f32_e32 v1, v1, v16
	v_mov_b32_e32 v9, s0
	v_add_f32_e32 v3, v3, v17
	ds_read_b64 v[16:17], v9
	v_readlane_b32 s0, v251, 50
	s_waitcnt lgkmcnt(0)
	v_add_f32_e32 v1, v1, v16
	v_mov_b32_e32 v9, s0
	v_add_f32_e32 v3, v3, v17
	ds_read_b64 v[16:17], v9
	v_readlane_b32 s0, v251, 51
	s_waitcnt lgkmcnt(0)
	v_add_f32_e32 v1, v1, v16
	v_mov_b32_e32 v9, s0
	v_add_f32_e32 v3, v3, v17
	ds_read_b64 v[16:17], v9
	v_readlane_b32 s0, v251, 24
	s_waitcnt lgkmcnt(0)
	v_add_f32_e32 v1, v1, v16
	v_mul_f32_e32 v9, 0x3b000000, v1
	v_add_f32_e32 v3, v3, v17
	v_mul_f32_e32 v9, v9, v9
	v_fma_f32 v3, v3, s22, -v9
	v_max_f32_e32 v3, 0, v3
	v_add_f32_e32 v3, 0x358637bd, v3
	v_rsq_f32_e32 v3, v3
	v_fmac_f32_e32 v10, 0xbb000000, v1
	v_mov_b32_e32 v9, s0
	v_readlane_b32 s0, v251, 25
	v_mul_f32_e32 v1, v10, v3
	v_fma_f32 v10, v141, v1, v140
	global_store_dword v[14:15], v10, off offset:2048
	v_mov_b32_e32 v1, s12
	ds_read_b64 v[14:15], v1
	s_waitcnt lgkmcnt(0)
	v_add_f32_e32 v1, 0, v14
	v_add_f32_e32 v3, 0, v15
	ds_read_b64 v[14:15], v9
	v_mov_b32_e32 v9, s0
	v_readlane_b32 s0, v251, 26
	s_waitcnt lgkmcnt(0)
	v_add_f32_e32 v1, v1, v14
	v_add_f32_e32 v3, v3, v15
	ds_read_b64 v[14:15], v9
	v_mov_b32_e32 v9, s0
	v_readlane_b32 s0, v251, 27
	s_waitcnt lgkmcnt(0)
	v_add_f32_e32 v1, v1, v14
	v_add_f32_e32 v3, v3, v15
	ds_read_b64 v[14:15], v9
	v_mov_b32_e32 v9, s0
	v_readlane_b32 s0, v251, 28
	s_waitcnt lgkmcnt(0)
	v_add_f32_e32 v1, v1, v14
	v_add_f32_e32 v3, v3, v15
	ds_read_b64 v[14:15], v9
	v_mov_b32_e32 v9, s0
	v_readlane_b32 s0, v251, 29
	s_waitcnt lgkmcnt(0)
	v_add_f32_e32 v1, v1, v14
	v_add_f32_e32 v3, v3, v15
	ds_read_b64 v[14:15], v9
	v_mov_b32_e32 v9, s0
	v_readlane_b32 s0, v251, 30
	s_waitcnt lgkmcnt(0)
	v_add_f32_e32 v1, v1, v14
	v_add_f32_e32 v3, v3, v15
	ds_read_b64 v[14:15], v9
	v_mov_b32_e32 v9, s0
	s_mov_b32 s0, 0x7cfa000
	s_waitcnt lgkmcnt(0)
	v_add_f32_e32 v1, v1, v14
	v_add_f32_e32 v3, v3, v15
	ds_read_b64 v[14:15], v9
	s_waitcnt lgkmcnt(0)
	v_add_f32_e32 v1, v1, v14
	v_mul_f32_e32 v9, 0x3b000000, v1
	v_add_f32_e32 v3, v3, v15
	v_mul_f32_e32 v9, v9, v9
	v_fma_f32 v3, v3, s22, -v9
	v_max_f32_e32 v3, 0, v3
	v_add_f32_e32 v3, 0x358637bd, v3
	v_rsq_f32_e32 v3, v3
	v_fmac_f32_e32 v8, 0xbb000000, v1
	v_mul_f32_e32 v1, v8, v3
	v_add_co_u32_e32 v8, vcc, s0, v4
	v_fma_f32 v13, v141, v1, v140
	s_nop 0
	v_addc_co_u32_e32 v9, vcc, 0, v5, vcc
	s_add_i32 s0, 0, 0x22028
	global_store_dword v[8:9], v13, off
	v_mov_b32_e32 v1, s0
	ds_read_b64 v[14:15], v1
	v_readlane_b32 s0, v251, 52
	s_waitcnt lgkmcnt(0)
	v_add_f32_e32 v1, 0, v14
	v_mov_b32_e32 v14, s0
	v_add_f32_e32 v3, 0, v15
	ds_read_b64 v[14:15], v14
	v_readlane_b32 s0, v251, 53
	s_waitcnt lgkmcnt(0)
	v_add_f32_e32 v1, v1, v14
	v_mov_b32_e32 v14, s0
	v_add_f32_e32 v3, v3, v15
	ds_read_b64 v[14:15], v14
	v_readlane_b32 s0, v251, 54
	s_waitcnt lgkmcnt(0)
	v_add_f32_e32 v1, v1, v14
	v_mov_b32_e32 v14, s0
	v_add_f32_e32 v3, v3, v15
	ds_read_b64 v[14:15], v14
	v_readlane_b32 s0, v251, 55
	s_waitcnt lgkmcnt(0)
	v_add_f32_e32 v1, v1, v14
	v_mov_b32_e32 v14, s0
	v_add_f32_e32 v3, v3, v15
	ds_read_b64 v[14:15], v14
	v_readlane_b32 s0, v251, 56
	s_waitcnt lgkmcnt(0)
	v_add_f32_e32 v1, v1, v14
	v_mov_b32_e32 v14, s0
	v_add_f32_e32 v3, v3, v15
	ds_read_b64 v[14:15], v14
	v_readlane_b32 s0, v251, 57
	s_waitcnt lgkmcnt(0)
	v_add_f32_e32 v1, v1, v14
	v_mov_b32_e32 v14, s0
	v_add_f32_e32 v3, v3, v15
	ds_read_b64 v[14:15], v14
	v_readlane_b32 s0, v251, 58
	s_waitcnt lgkmcnt(0)
	v_add_f32_e32 v1, v1, v14
	v_mov_b32_e32 v14, s0
	v_add_f32_e32 v3, v3, v15
	ds_read_b64 v[14:15], v14
	v_readlane_b32 s0, v251, 31
	s_waitcnt lgkmcnt(0)
	v_add_f32_e32 v1, v1, v14
	v_mul_f32_e32 v14, 0x3b000000, v1
	v_add_f32_e32 v3, v3, v15
	v_mul_f32_e32 v14, v14, v14
	v_fma_f32 v3, v3, s22, -v14
	v_max_f32_e32 v3, 0, v3
	v_add_f32_e32 v3, 0x358637bd, v3
	v_rsq_f32_e32 v3, v3
	v_fmac_f32_e32 v6, 0xbb000000, v1
	v_mul_f32_e32 v1, v6, v3
	v_fma_f32 v6, v141, v1, v140
	global_store_dword v[8:9], v6, off offset:2048
	v_mov_b32_e32 v1, s3
	ds_read_b64 v[8:9], v1
	s_waitcnt lgkmcnt(0)
	v_add_f32_e32 v1, 0, v8
	v_mov_b32_e32 v8, s0
	v_add_f32_e32 v3, 0, v9
	ds_read_b64 v[8:9], v8
	v_readlane_b32 s0, v251, 32
	s_waitcnt lgkmcnt(0)
	v_add_f32_e32 v1, v1, v8
	v_mov_b32_e32 v8, s0
	v_add_f32_e32 v3, v3, v9
	ds_read_b64 v[8:9], v8
	v_readlane_b32 s0, v251, 33
	s_waitcnt lgkmcnt(0)
	v_add_f32_e32 v1, v1, v8
	v_mov_b32_e32 v8, s0
	v_add_f32_e32 v3, v3, v9
	ds_read_b64 v[8:9], v8
	v_readlane_b32 s0, v251, 34
	s_waitcnt lgkmcnt(0)
	v_add_f32_e32 v1, v1, v8
	v_mov_b32_e32 v8, s0
	v_add_f32_e32 v3, v3, v9
	ds_read_b64 v[8:9], v8
	v_readlane_b32 s0, v251, 35
	s_waitcnt lgkmcnt(0)
	v_add_f32_e32 v1, v1, v8
	v_mov_b32_e32 v8, s0
	v_add_f32_e32 v3, v3, v9
	ds_read_b64 v[8:9], v8
	v_readlane_b32 s0, v251, 36
	s_waitcnt lgkmcnt(0)
	v_add_f32_e32 v1, v1, v8
	v_mov_b32_e32 v8, s0
	v_add_f32_e32 v3, v3, v9
	ds_read_b64 v[8:9], v8
	v_readlane_b32 s0, v251, 37
	s_waitcnt lgkmcnt(0)
	v_add_f32_e32 v1, v1, v8
	v_mov_b32_e32 v8, s0
	v_add_f32_e32 v3, v3, v9
	ds_read_b64 v[8:9], v8
	s_mov_b32 s0, 0x7cfb000
	s_waitcnt lgkmcnt(0)
	v_add_f32_e32 v1, v1, v8
	v_mul_f32_e32 v8, 0x3b000000, v1
	v_add_f32_e32 v3, v3, v9
	v_mul_f32_e32 v8, v8, v8
	v_fma_f32 v3, v3, s22, -v8
	v_max_f32_e32 v3, 0, v3
	v_add_f32_e32 v3, 0x358637bd, v3
	v_rsq_f32_e32 v3, v3
	v_fmac_f32_e32 v2, 0xbb000000, v1
	v_mul_f32_e32 v1, v2, v3
	v_add_co_u32_e32 v2, vcc, s0, v4
	v_fma_f32 v8, v141, v1, v140
	s_nop 0
	v_addc_co_u32_e32 v3, vcc, 0, v5, vcc
	s_add_i32 s0, 0, 0x22038
	global_store_dword v[2:3], v8, off
	v_mov_b32_e32 v1, s0
	ds_read_b64 v[4:5], v1
	v_readlane_b32 s0, v251, 59
	s_waitcnt lgkmcnt(0)
	v_add_f32_e32 v1, 0, v4
	v_mov_b32_e32 v4, s0
	v_add_f32_e32 v9, 0, v5
	ds_read_b64 v[4:5], v4
	v_readlane_b32 s0, v251, 60
	s_waitcnt lgkmcnt(0)
	v_add_f32_e32 v1, v1, v4
	v_mov_b32_e32 v4, s0
	v_add_f32_e32 v9, v9, v5
	ds_read_b64 v[4:5], v4
	v_readlane_b32 s0, v251, 61
	s_waitcnt lgkmcnt(0)
	v_add_f32_e32 v1, v1, v4
	v_mov_b32_e32 v4, s0
	v_add_f32_e32 v9, v9, v5
	ds_read_b64 v[4:5], v4
	v_readlane_b32 s0, v251, 62
	s_waitcnt lgkmcnt(0)
	v_add_f32_e32 v1, v1, v4
	v_mov_b32_e32 v4, s0
	v_add_f32_e32 v9, v9, v5
	ds_read_b64 v[4:5], v4
	v_readlane_b32 s0, v251, 63
	s_waitcnt lgkmcnt(0)
	v_add_f32_e32 v1, v1, v4
	v_mov_b32_e32 v4, s0
	v_add_f32_e32 v9, v9, v5
	ds_read_b64 v[4:5], v4
	v_readlane_b32 s0, v252, 0
	s_waitcnt lgkmcnt(0)
	v_add_f32_e32 v1, v1, v4
	v_mov_b32_e32 v4, s0
	v_add_f32_e32 v9, v9, v5
	ds_read_b64 v[4:5], v4
	v_readlane_b32 s0, v252, 1
	s_waitcnt lgkmcnt(0)
	v_add_f32_e32 v1, v1, v4
	v_mov_b32_e32 v4, s0
	v_add_f32_e32 v9, v9, v5
	ds_read_b64 v[4:5], v4
	s_mov_b64 s[0:1], s[62:63]
	s_waitcnt lgkmcnt(0)
	v_add_f32_e32 v1, v1, v4
	v_add_f32_e32 v4, v9, v5
	v_mul_f32_e32 v5, 0x3b000000, v1
	v_mul_f32_e32 v5, v5, v5
	v_fma_f32 v4, v4, s22, -v5
	v_max_f32_e32 v4, 0, v4
	v_add_f32_e32 v4, 0x358637bd, v4
	v_rsq_f32_e32 v4, v4
	v_fmac_f32_e32 v0, 0xbb000000, v1
	v_mul_f32_e32 v0, v0, v4
	v_fma_f32 v9, v141, v0, v140
	global_store_dword v[2:3], v9, off offset:2048
	s_add_u32 s0, s0, s28
	s_addc_u32 s1, s1, s29
	v_lshl_add_u64 v[4:5], v[64:65], 1, s[0:1]
	v_readlane_b32 s0, v254, 37
	v_readlane_b32 s1, v254, 38
	s_nop 4
	global_load_dwordx4 v[0:3], v193, s[0:1] offset:16
	global_load_dwordx4 v[14:17], v193, s[0:1]
	global_load_dword v18, v193, s[86:87]
	v_add_co_u32_e32 v20, vcc, s33, v4
	s_waitcnt vmcnt(0)
	v_fma_f32 v14, v7, v18, v14
	ds_read2st64_b32 v[18:19], v87 offset0:64 offset1:72
	v_addc_co_u32_e32 v21, vcc, 0, v5, vcc
	s_waitcnt lgkmcnt(0)
	v_mul_f32_e32 v14, v18, v14
	v_cvt_pk_bf16_f32 v14, v14, s0
	global_store_short v[20:21], v14, off offset:2048
	global_load_dwordx2 v[20:21], v193, s[86:87] offset:512
	s_waitcnt vmcnt(0)
	v_fma_f32 v14, v7, v20, v15
	v_fmac_f32_e32 v14, v11, v21
	v_mul_f32_e32 v14, v19, v14
	v_cvt_pk_bf16_f32 v18, v14, s0
	v_add_co_u32_e32 v14, vcc, s48, v4
	s_nop 1
	v_addc_co_u32_e32 v15, vcc, 0, v5, vcc
	global_store_short v[14:15], v18, off offset:2048
	global_load_dwordx3 v[18:20], v193, s[86:87] offset:1024
	ds_read2st64_b32 v[14:15], v87 offset0:80 offset1:88
	s_waitcnt vmcnt(0)
	v_fma_f32 v16, v7, v18, v16
	v_fmac_f32_e32 v16, v11, v19
	v_fmac_f32_e32 v16, v12, v20
	s_waitcnt lgkmcnt(0)
	v_mul_f32_e32 v14, v14, v16
	v_cvt_pk_bf16_f32 v14, v14, s0
	s_mov_b32 s0, 0x14002000
	v_add_co_u32_e32 v18, vcc, s0, v4
	s_nop 1
	v_addc_co_u32_e32 v19, vcc, 0, v5, vcc
	global_store_short v[18:19], v14, off offset:2048
	global_load_dwordx4 v[18:21], v193, s[86:87] offset:1536
	s_waitcnt vmcnt(0)
	v_fmac_f32_e32 v17, v7, v18
	v_fmac_f32_e32 v17, v11, v19
	v_fmac_f32_e32 v17, v12, v20
	v_fmac_f32_e32 v17, v10, v21
	v_mul_f32_e32 v14, v15, v17
	v_cvt_pk_bf16_f32 v16, v14, s0
	s_mov_b32 s0, 0x14003000
	v_add_co_u32_e32 v14, vcc, s0, v4
	s_nop 1
	v_addc_co_u32_e32 v15, vcc, 0, v5, vcc
	global_store_short v[14:15], v16, off offset:2048
	global_load_dword v18, v193, s[86:87] offset:2064
	s_nop 0
	global_load_dwordx4 v[14:17], v193, s[86:87] offset:2048
	s_waitcnt vmcnt(0)
	v_fma_f32 v0, v7, v14, v0
	v_fmac_f32_e32 v0, v11, v15
	v_fmac_f32_e32 v0, v12, v16
	v_fmac_f32_e32 v0, v10, v17
	v_fmac_f32_e32 v0, v13, v18
	ds_read2st64_b32 v[18:19], v87 offset0:96 offset1:104
	s_waitcnt lgkmcnt(0)
	v_mul_f32_e32 v0, v18, v0
	v_cvt_pk_bf16_f32 v0, v0, s0
	s_mov_b32 s0, 0x14004000
	v_add_co_u32_e32 v14, vcc, s0, v4
	s_nop 1
	v_addc_co_u32_e32 v15, vcc, 0, v5, vcc
	global_store_short v[14:15], v0, off offset:2048
	global_load_dwordx2 v[20:21], v193, s[86:87] offset:2576
	s_nop 0
	global_load_dwordx4 v[14:17], v193, s[86:87] offset:2560
	s_waitcnt vmcnt(0)
	v_fma_f32 v0, v7, v14, v1
	v_fmac_f32_e32 v0, v11, v15
	v_fmac_f32_e32 v0, v12, v16
	v_fmac_f32_e32 v0, v10, v17
	v_fmac_f32_e32 v0, v13, v20
	v_fmac_f32_e32 v0, v6, v21
	v_mul_f32_e32 v0, v19, v0
	v_cvt_pk_bf16_f32 v14, v0, s0
	s_mov_b32 s0, 0x14005000
	v_add_co_u32_e32 v0, vcc, s0, v4
	s_nop 1
	v_addc_co_u32_e32 v1, vcc, 0, v5, vcc
	global_store_short v[0:1], v14, off offset:2048
	global_load_dwordx3 v[18:20], v193, s[86:87] offset:3088
	s_nop 0
	global_load_dwordx4 v[14:17], v193, s[86:87] offset:3072
	ds_read2st64_b32 v[0:1], v87 offset0:112 offset1:120
	s_waitcnt vmcnt(0)
	v_fma_f32 v2, v7, v14, v2
	v_fmac_f32_e32 v2, v11, v15
	v_fmac_f32_e32 v2, v12, v16
	v_fmac_f32_e32 v2, v10, v17
	v_fmac_f32_e32 v2, v13, v18
	v_fmac_f32_e32 v2, v6, v19
	v_fmac_f32_e32 v2, v8, v20
	s_waitcnt lgkmcnt(0)
	v_mul_f32_e32 v0, v0, v2
	v_cvt_pk_bf16_f32 v0, v0, s0
	s_mov_b32 s0, 0x14006000
	v_add_co_u32_e32 v14, vcc, s0, v4
	s_nop 1
	v_addc_co_u32_e32 v15, vcc, 0, v5, vcc
	global_store_short v[14:15], v0, off offset:2048
	global_load_dwordx4 v[14:17], v193, s[86:87] offset:3600
	s_nop 0
	global_load_dwordx4 v[18:21], v193, s[86:87] offset:3584
	s_waitcnt vmcnt(0)
	v_fmac_f32_e32 v3, v7, v18
	v_fmac_f32_e32 v3, v11, v19
	v_fmac_f32_e32 v3, v12, v20
	v_fmac_f32_e32 v3, v10, v21
	v_fmac_f32_e32 v3, v13, v14
	v_fmac_f32_e32 v3, v6, v15
	v_fmac_f32_e32 v3, v8, v16
	v_fmac_f32_e32 v3, v9, v17
	v_mul_f32_e32 v0, v1, v3
	v_cvt_pk_bf16_f32 v2, v0, s0
	v_add_co_u32_e32 v0, vcc, 0x14007000, v4
	s_mov_b64 s[0:1], 0
	s_nop 0
	v_addc_co_u32_e32 v1, vcc, 0, v5, vcc
	global_store_short v[0:1], v2, off offset:2048
	s_waitcnt lgkmcnt(0)
	s_barrier

.LBB0_303:
	s_or_b64 exec, exec, s[22:23]
	v_add3_u32 v6, v0, s3, v1
	v_cmp_lt_i32_e32 vcc, -1, v6
	v_mov_b32_e32 v3, 0
	v_mov_b32_e32 v2, 0
	v_mov_b32_e32 v1, 0
	v_mov_b32_e32 v0, 0
	s_and_saveexec_b64 s[22:23], vcc
	s_cbranch_execz .LBB0_305
	v_add_u32_e32 v2, s56, v6
	v_mov_b64_e32 v[0:1], s[12:13]
	v_mad_i64_i32 v[0:1], s[30:31], v2, s76, v[0:1]
	v_lshl_add_u64 v[0:1], v[4:5], 1, v[0:1]
	v_lshl_add_u64 v[0:1], v[0:1], 0, v[192:193]
	global_load_dwordx4 v[0:3], v[0:1], off

.LBB0_317:
	s_or_b64 exec, exec, s[22:23]
	v_add3_u32 v10, v4, s3, v5
	v_cmp_lt_i32_e32 vcc, -1, v10
	v_mov_b32_e32 v7, 0
	v_mov_b32_e32 v6, 0
	v_mov_b32_e32 v5, 0
	v_mov_b32_e32 v4, 0
	s_and_saveexec_b64 s[22:23], vcc
	s_cbranch_execz .LBB0_319
	v_add_u32_e32 v6, s56, v10
	v_mov_b64_e32 v[4:5], s[12:13]
	v_mad_i64_i32 v[4:5], s[34:35], v6, s76, v[4:5]
	v_lshl_add_u64 v[4:5], v[8:9], 1, v[4:5]
	v_lshl_add_u64 v[4:5], v[4:5], 0, v[192:193]
	global_load_dwordx4 v[4:7], v[4:5], off

.LBB0_331:
	s_or_b64 exec, exec, s[22:23]
	v_add3_u32 v14, v8, s3, v9
	v_cmp_lt_i32_e32 vcc, -1, v14
	v_mov_b32_e32 v11, 0
	v_mov_b32_e32 v10, 0
	v_mov_b32_e32 v9, 0
	v_mov_b32_e32 v8, 0
	s_and_saveexec_b64 s[22:23], vcc
	s_cbranch_execz .LBB0_333
	v_add_u32_e32 v10, s56, v14
	v_mov_b64_e32 v[8:9], s[12:13]
	v_mad_i64_i32 v[8:9], s[38:39], v10, s76, v[8:9]
	v_lshl_add_u64 v[8:9], v[12:13], 1, v[8:9]
	v_lshl_add_u64 v[8:9], v[8:9], 0, v[192:193]
	global_load_dwordx4 v[8:11], v[8:9], off

.LBB0_345:
	s_or_b64 exec, exec, s[22:23]
	v_add3_u32 v18, v12, s3, v13
	v_cmp_lt_i32_e32 vcc, -1, v18
	v_mov_b32_e32 v15, 0
	v_mov_b32_e32 v14, 0
	v_mov_b32_e32 v13, 0
	v_mov_b32_e32 v12, 0
	s_and_saveexec_b64 s[22:23], vcc
	s_cbranch_execz .LBB0_347
	v_add_u32_e32 v14, s56, v18
	v_mov_b64_e32 v[12:13], s[12:13]
	v_mad_i64_i32 v[12:13], s[38:39], v14, s76, v[12:13]
	v_lshl_add_u64 v[12:13], v[16:17], 1, v[12:13]
	v_lshl_add_u64 v[12:13], v[12:13], 0, v[192:193]
	global_load_dwordx4 v[12:15], v[12:13], off

.LBB0_359:
	s_or_b64 exec, exec, s[22:23]
	v_add3_u32 v22, v16, s3, v17
	v_cmp_lt_i32_e32 vcc, -1, v22
	v_mov_b32_e32 v19, 0
	v_mov_b32_e32 v18, 0
	v_mov_b32_e32 v17, 0
	v_mov_b32_e32 v16, 0
	s_and_saveexec_b64 s[22:23], vcc
	s_cbranch_execz .LBB0_361
	v_add_u32_e32 v18, s56, v22
	v_mov_b64_e32 v[16:17], s[12:13]
	v_mad_i64_i32 v[16:17], s[38:39], v18, s76, v[16:17]
	v_lshl_add_u64 v[16:17], v[20:21], 1, v[16:17]
	v_lshl_add_u64 v[16:17], v[16:17], 0, v[192:193]
	global_load_dwordx4 v[16:19], v[16:17], off

.LBB0_373:
	s_or_b64 exec, exec, s[22:23]
	v_add3_u32 v26, v20, s3, v21
	v_cmp_lt_i32_e32 vcc, -1, v26
	v_mov_b32_e32 v23, 0
	v_mov_b32_e32 v22, 0
	v_mov_b32_e32 v21, 0
	v_mov_b32_e32 v20, 0
	s_and_saveexec_b64 s[22:23], vcc
	s_cbranch_execz .LBB0_375
	v_add_u32_e32 v22, s56, v26
	v_mov_b64_e32 v[20:21], s[12:13]
	v_mad_i64_i32 v[20:21], s[38:39], v22, s76, v[20:21]
	v_lshl_add_u64 v[20:21], v[24:25], 1, v[20:21]
	v_lshl_add_u64 v[20:21], v[20:21], 0, v[192:193]
	global_load_dwordx4 v[20:23], v[20:21], off

.LBB0_387:
	s_or_b64 exec, exec, s[88:89]
	v_add3_u32 v37, v24, s3, v25
	v_cmp_lt_i32_e32 vcc, -1, v37
	v_mov_b32_e32 v27, 0
	v_mov_b32_e32 v26, 0
	v_mov_b32_e32 v25, 0
	v_mov_b32_e32 v24, 0
	s_and_saveexec_b64 s[38:39], vcc
	s_cbranch_execz .LBB0_389
	v_add_u32_e32 v26, s56, v37
	v_mov_b64_e32 v[24:25], s[12:13]
	v_mad_i64_i32 v[24:25], s[58:59], v26, s76, v[24:25]
	v_lshl_add_u64 v[24:25], v[28:29], 1, v[24:25]
	v_lshl_add_u64 v[24:25], v[24:25], 0, v[192:193]
	global_load_dwordx4 v[24:27], v[24:25], off

.LBB0_407:
	v_ashrrev_i32_e32 v1, 6, v3
	v_add_u32_e32 v0, 0xffffffbf, v1
	v_subrev_u32_e32 v4, 49, v1
	v_cmp_gt_i32_e32 vcc, 31, v1
	s_movk_i32 s22, 0xffee
	v_cmp_gt_u32_e64 s[28:29], -16, v0
	v_cndmask_b32_e32 v0, v0, v1, vcc
	v_subrev_u32_e32 v5, 31, v1
	v_cmp_gt_u32_e64 s[26:27], s22, v4
	s_nop 1
	v_cndmask_b32_e64 v0, v5, v0, s[26:27]
	v_add_u32_e32 v0, -16, v0
	v_cmp_lt_i32_e64 s[30:31], -1, v0
	s_and_b64 s[28:29], s[28:29], s[30:31]
	s_and_saveexec_b64 s[22:23], s[28:29]
	s_cbranch_execz .LBB0_406
	v_mov_b32_e32 v4, s34
	v_mov_b32_e32 v5, s42
	v_cndmask_b32_e32 v4, v4, v5, vcc
	v_mov_b32_e32 v5, s35
	v_mov_b32_e32 v6, s43
	v_cndmask_b32_e32 v5, v5, v6, vcc
	v_mov_b32_e32 v6, s39
	v_and_b32_e32 v10, 0x1f8, v2
	v_cndmask_b32_e64 v9, v6, v5, s[26:27]
	v_mov_b32_e32 v5, s38
	v_cndmask_b32_e64 v8, v5, v4, s[26:27]
	v_lshlrev_b32_e32 v1, 10, v1
	v_lshlrev_b32_e32 v4, 1, v10
	v_add3_u32 v1, 0, v1, v4
	ds_read_b128 v[4:7], v1
	s_mov_b32 s24, s75
	v_readlane_b32 s68, v253, 8
	v_readlane_b32 s72, v253, 12
	v_readlane_b32 s73, v253, 13
	s_mov_b64 s[26:27], s[72:73]
	v_mov_b32_e32 v1, v193
	v_lshlrev_b64 v[0:1], 11, v[0:1]
	v_lshl_add_u64 v[8:9], v[8:9], 2, s[26:27]
	v_readlane_b32 s71, v253, 11
	v_readlane_b32 s74, v253, 14
	v_readlane_b32 s75, v253, 15
	v_lshl_add_u64 v[0:1], v[8:9], 0, v[0:1]
	v_lshlrev_b32_e32 v8, 2, v10
	v_mov_b32_e32 v9, v193
	s_mov_b32 s75, s24
	s_movk_i32 s71, 0x1bc0
	s_movk_i32 s74, 0x6000
	s_movk_i32 s73, 0x2000
	s_movk_i32 s72, 0x4000
	v_lshl_add_u64 v[0:1], v[0:1], 0, v[8:9]
	s_waitcnt lgkmcnt(0)
	v_lshlrev_b32_e32 v8, 16, v4
	v_and_b32_e32 v9, 0xffff0000, v4
	v_lshlrev_b32_e32 v10, 16, v5
	v_and_b32_e32 v11, 0xffff0000, v5
	v_lshlrev_b32_e32 v4, 16, v6
	v_and_b32_e32 v5, 0xffff0000, v6
	v_lshlrev_b32_e32 v6, 16, v7
	v_and_b32_e32 v7, 0xffff0000, v7
	v_readlane_b32 s69, v253, 9
	v_readlane_b32 s70, v253, 10
	global_store_dwordx4 v[0:1], v[8:11], off
	global_store_dwordx4 v[0:1], v[4:7], off offset:16
	s_branch .LBB0_406

.LBB0_433:
	s_or_b64 exec, exec, s[14:15]
	v_lshlrev_b32_e32 v81, 16, v81
	v_lshlrev_b32_e32 v122, 16, v54
	v_mul_f32_e32 v54, v165, v81
	v_fmac_f32_e32 v54, v163, v122
	s_waitcnt lgkmcnt(1)
	v_lshlrev_b32_e32 v121, 16, v121
	v_fmac_f32_e32 v54, v164, v121
	v_lshlrev_b32_e32 v105, 16, v105
	v_mul_f32_e32 v54, v54, v105
	v_lshlrev_b32_e32 v105, 16, v76
	v_mul_f32_e32 v76, v165, v122
	v_fmac_f32_e32 v76, v163, v105
	v_fmac_f32_e32 v76, v164, v81
	v_lshlrev_b32_e32 v81, 16, v120
	v_mul_f32_e32 v76, v76, v81
	v_lshlrev_b32_e32 v81, 16, v80
	v_mul_f32_e32 v80, v165, v105
	v_fmac_f32_e32 v80, v163, v81
	v_fmac_f32_e32 v80, v164, v122
	v_lshlrev_b32_e32 v119, 16, v119
	v_mul_f32_e32 v80, v80, v119
	v_lshlrev_b32_e32 v119, 16, v79
	v_mul_f32_e32 v79, v165, v81
	v_fmac_f32_e32 v79, v163, v119
	v_fmac_f32_e32 v79, v164, v105
	v_lshlrev_b32_e32 v105, 16, v118
	v_mul_f32_e32 v79, v79, v105
	v_lshlrev_b32_e32 v105, 16, v78
	v_mul_f32_e32 v78, v165, v119
	v_fmac_f32_e32 v78, v163, v105
	v_fmac_f32_e32 v78, v164, v81
	v_lshlrev_b32_e32 v81, 16, v117
	v_mul_f32_e32 v78, v78, v81
	v_lshlrev_b32_e32 v81, 16, v77
	v_mul_f32_e32 v77, v165, v105
	v_fmac_f32_e32 v77, v163, v81
	v_fmac_f32_e32 v77, v164, v119
	v_lshlrev_b32_e32 v116, 16, v116
	v_mul_f32_e32 v77, v77, v116
	v_lshlrev_b32_e32 v116, 16, v59
	v_mul_f32_e32 v59, v165, v81
	v_fmac_f32_e32 v59, v163, v116
	v_fmac_f32_e32 v59, v164, v105
	v_lshlrev_b32_e32 v105, 16, v115
	v_mul_f32_e32 v59, v59, v105
	v_lshlrev_b32_e32 v105, 16, v58
	v_mul_f32_e32 v58, v165, v116
	v_fmac_f32_e32 v58, v163, v105
	v_fmac_f32_e32 v58, v164, v81
	v_lshlrev_b32_e32 v81, 16, v114
	v_mul_f32_e32 v58, v58, v81
	v_lshlrev_b32_e32 v81, 16, v57
	v_mul_f32_e32 v57, v165, v105
	v_fmac_f32_e32 v57, v163, v81
	v_fmac_f32_e32 v57, v164, v116
	v_lshlrev_b32_e32 v113, 16, v113
	v_mul_f32_e32 v57, v57, v113
	v_lshlrev_b32_e32 v113, 16, v56
	v_mul_f32_e32 v56, v165, v81
	v_fmac_f32_e32 v56, v163, v113
	v_fmac_f32_e32 v56, v164, v105
	v_lshlrev_b32_e32 v105, 16, v112
	v_mul_f32_e32 v56, v56, v105
	v_lshlrev_b32_e32 v105, 16, v55
	v_mul_f32_e32 v55, v165, v113
	v_fmac_f32_e32 v55, v163, v105
	v_fmac_f32_e32 v55, v164, v81
	v_lshlrev_b32_e32 v81, 16, v111
	v_mul_f32_e32 v55, v55, v81
	v_lshlrev_b32_e32 v81, 16, v53
	v_mul_f32_e32 v53, v165, v105
	v_fmac_f32_e32 v53, v163, v81
	v_fmac_f32_e32 v53, v164, v113
	v_lshlrev_b32_e32 v110, 16, v110
	v_mul_f32_e32 v53, v53, v110
	v_lshlrev_b32_e32 v52, 16, v52
	v_mul_f32_e32 v110, v165, v81
	v_fmac_f32_e32 v110, v163, v52
	v_fmac_f32_e32 v110, v164, v105
	v_lshlrev_b32_e32 v105, 16, v109
	v_mul_f32_e32 v120, v110, v105
	v_lshlrev_b32_e32 v51, 16, v51
	v_mul_f32_e32 v105, v165, v52
	v_fmac_f32_e32 v105, v163, v51
	v_fmac_f32_e32 v105, v164, v81
	v_lshlrev_b32_e32 v81, 16, v108
	v_mul_f32_e32 v81, v105, v81
	v_lshlrev_b32_e32 v50, 16, v50
	v_mul_f32_e32 v105, v165, v51
	v_fmac_f32_e32 v105, v163, v50
	v_lshlrev_b32_e32 v104, 16, v104
	v_mul_f32_e32 v50, v165, v50
	v_fmac_f32_e32 v50, v163, v104
	v_fmac_f32_e32 v50, v164, v51
	v_lshlrev_b32_e32 v51, 16, v106
	v_readlane_b32 s15, v251, 9
	v_fmac_f32_e32 v105, v164, v52
	v_lshlrev_b32_e32 v52, 16, v107
	v_mul_f32_e32 v50, v50, v51
	v_mov_b32_e32 v51, s15
	s_add_i32 s30, 0, 0x22010
	v_mul_f32_e32 v52, v105, v52
	s_waitcnt lgkmcnt(0)
	s_barrier
	ds_read_b128 v[104:107], v51
	v_mov_b32_e32 v51, s30
	s_add_i32 s29, 0, 0x22020
	ds_read_b128 v[108:111], v51
	v_mov_b32_e32 v51, s29
	s_add_i32 s28, 0, 0x22030
	ds_read_b128 v[112:115], v51
	v_mov_b32_e32 v51, s28
	ds_read_b128 v[116:119], v51
	s_waitcnt lgkmcnt(3)
	v_add_f32_e32 v51, v104, v106
	s_waitcnt lgkmcnt(2)
	v_add_f32_e32 v104, v108, v110
	v_add_f32_e32 v51, v51, v104
	s_waitcnt lgkmcnt(1)
	v_add_f32_e32 v104, v112, v114
	v_add_f32_e32 v51, v51, v104
	s_waitcnt lgkmcnt(0)
	v_add_f32_e32 v104, v116, v118
	v_add_f32_e32 v51, v51, v104
	v_add_f32_e32 v104, v105, v107
	v_add_f32_e32 v105, v109, v111
	v_add_f32_e32 v104, v104, v105
	v_add_f32_e32 v105, v113, v115
	v_add_f32_e32 v104, v104, v105
	v_add_f32_e32 v105, v117, v119
	v_add_f32_e32 v104, v104, v105
	v_mul_f32_e32 v105, 0x3b000000, v51
	v_mul_f32_e32 v105, v105, v105
	s_mov_b32 s16, 0x3b000000
	v_fma_f32 v104, v104, s16, -v105
	v_max_f32_e32 v104, 0, v104
	v_add_f32_e32 v104, 0x358637bd, v104
	v_rsq_f32_e32 v104, v104
	v_fmac_f32_e32 v49, 0xbb000000, v51
	v_cvt_pk_bf16_f32 v14, v14, s0
	ds_write_b16 v86, v14
	v_mul_f32_e32 v49, v49, v104
	v_fma_f32 v49, v143, v49, v142
	v_cvt_pk_bf16_f32 v14, v50, s0
	ds_write_b16 v86, v14 offset:16384
	v_mul_f32_e32 v14, 0xbfb8aa3b, v49
	v_exp_f32_e32 v14, v14
	v_readlane_b32 s15, v251, 10
	v_cvt_pk_bf16_f32 v15, v15, s0
	v_cvt_pk_bf16_f32 v12, v12, s0
	v_add_f32_e32 v14, 1.0, v14
	v_rcp_f32_e32 v14, v14
	v_cvt_pk_bf16_f32 v13, v13, s0
	v_cvt_pk_bf16_f32 v4, v4, s0
	v_cvt_pk_bf16_f32 v5, v5, s0
	v_mul_f32_e32 v14, v49, v14
	v_cvt_pk_bf16_f32 v14, v14, s0
	ds_write_b16 v86, v14 offset:32768
	v_mov_b32_e32 v14, s15
	v_readlane_b32 s15, v251, 17
	ds_read_b128 v[104:107], v14
	v_cvt_pk_bf16_f32 v0, v0, s0
	v_mov_b32_e32 v14, s15
	v_readlane_b32 s15, v251, 24
	ds_read_b128 v[108:111], v14
	v_cvt_pk_bf16_f32 v1, v1, s0
	v_mov_b32_e32 v14, s15
	v_readlane_b32 s15, v251, 31
	ds_read_b128 v[112:115], v14
	s_waitcnt lgkmcnt(1)
	v_add_f32_e32 v49, v108, v110
	v_mov_b32_e32 v14, s15
	ds_read_b128 v[116:119], v14
	v_add_f32_e32 v14, v104, v106
	v_add_f32_e32 v14, v14, v49
	s_waitcnt lgkmcnt(1)
	v_add_f32_e32 v49, v112, v114
	v_add_f32_e32 v14, v14, v49
	s_waitcnt lgkmcnt(0)
	v_add_f32_e32 v49, v116, v118
	v_add_f32_e32 v14, v14, v49
	v_add_f32_e32 v49, v105, v107
	v_add_f32_e32 v50, v109, v111
	v_add_f32_e32 v49, v49, v50
	v_add_f32_e32 v50, v113, v115
	v_add_f32_e32 v49, v49, v50
	v_add_f32_e32 v50, v117, v119
	v_add_f32_e32 v49, v49, v50
	v_mul_f32_e32 v50, 0x3b000000, v14
	v_mul_f32_e32 v50, v50, v50
	v_fma_f32 v49, v49, s16, -v50
	v_max_f32_e32 v49, 0, v49
	v_add_f32_e32 v49, 0x358637bd, v49
	v_rsq_f32_e32 v49, v49
	v_fmac_f32_e32 v47, 0xbb000000, v14
	ds_write_b16 v86, v15 offset:1024
	v_cvt_pk_bf16_f32 v15, v52, s0
	v_mul_f32_e32 v14, v47, v49
	v_fma_f32 v14, v143, v14, v142
	ds_write_b16 v86, v15 offset:17408
	v_mul_f32_e32 v15, 0xbfb8aa3b, v14
	v_exp_f32_e32 v15, v15
	v_readlane_b32 s15, v251, 11
	s_or_b32 s14, s33, s45
	v_lshlrev_b32_e32 v192, 1, v28
	v_add_f32_e32 v15, 1.0, v15
	v_rcp_f32_e32 v15, v15
	v_mov_b32_e32 v49, v193
	v_mul_f32_e32 v14, v14, v15
	v_cvt_pk_bf16_f32 v14, v14, s0
	ds_write_b16 v86, v14 offset:33792
	v_mov_b32_e32 v14, s15
	v_readlane_b32 s15, v251, 18
	ds_read_b128 v[104:107], v14
	s_nop 0
	v_mov_b32_e32 v14, s15
	v_readlane_b32 s15, v251, 25
	ds_read_b128 v[108:111], v14
	s_waitcnt lgkmcnt(0)
	v_add_f32_e32 v15, v108, v110
	v_mov_b32_e32 v14, s15
	v_readlane_b32 s15, v251, 32
	ds_read_b128 v[112:115], v14
	v_add_f32_e32 v47, v109, v111
	v_mov_b32_e32 v14, s15
	ds_read_b128 v[116:119], v14
	v_add_f32_e32 v14, v104, v106
	v_add_f32_e32 v14, v14, v15
	s_waitcnt lgkmcnt(1)
	v_add_f32_e32 v15, v112, v114
	v_add_f32_e32 v14, v14, v15
	s_waitcnt lgkmcnt(0)
	v_add_f32_e32 v15, v116, v118
	v_add_f32_e32 v14, v14, v15
	v_add_f32_e32 v15, v105, v107
	v_add_f32_e32 v15, v15, v47
	v_add_f32_e32 v47, v113, v115
	v_add_f32_e32 v15, v15, v47
	v_add_f32_e32 v47, v117, v119
	v_add_f32_e32 v15, v15, v47
	v_mul_f32_e32 v47, 0x3b000000, v14
	v_mul_f32_e32 v47, v47, v47
	v_fma_f32 v15, v15, s16, -v47
	v_max_f32_e32 v15, 0, v15
	v_add_f32_e32 v15, 0x358637bd, v15
	v_rsq_f32_e32 v15, v15
	v_fmac_f32_e32 v45, 0xbb000000, v14
	ds_write_b16 v86, v12 offset:2048
	v_cvt_pk_bf16_f32 v12, v81, s0
	v_mul_f32_e32 v14, v45, v15
	v_fma_f32 v14, v143, v14, v142
	ds_write_b16 v86, v12 offset:18432
	v_mul_f32_e32 v12, 0xbfb8aa3b, v14
	v_exp_f32_e32 v12, v12
	v_readlane_b32 s15, v251, 12
	v_mov_b32_e32 v45, v193
	v_mov_b32_e32 v47, v193
	v_add_f32_e32 v12, 1.0, v12
	v_rcp_f32_e32 v12, v12
	s_nop 0
	v_mul_f32_e32 v12, v14, v12
	v_cvt_pk_bf16_f32 v12, v12, s0
	ds_write_b16 v86, v12 offset:34816
	v_mov_b32_e32 v12, s15
	v_readlane_b32 s15, v251, 19
	ds_read_b128 v[104:107], v12
	s_nop 0
	v_mov_b32_e32 v12, s15
	v_readlane_b32 s15, v251, 26
	ds_read_b128 v[108:111], v12
	s_waitcnt lgkmcnt(0)
	v_add_f32_e32 v14, v108, v110
	v_mov_b32_e32 v12, s15
	v_readlane_b32 s15, v251, 33
	ds_read_b128 v[112:115], v12
	v_add_f32_e32 v15, v109, v111
	v_mov_b32_e32 v12, s15
	ds_read_b128 v[116:119], v12
	v_add_f32_e32 v12, v104, v106
	v_add_f32_e32 v12, v12, v14
	s_waitcnt lgkmcnt(1)
	v_add_f32_e32 v14, v112, v114
	v_add_f32_e32 v12, v12, v14
	s_waitcnt lgkmcnt(0)
	v_add_f32_e32 v14, v116, v118
	v_add_f32_e32 v12, v12, v14
	v_add_f32_e32 v14, v105, v107
	v_add_f32_e32 v14, v14, v15
	v_add_f32_e32 v15, v113, v115
	v_add_f32_e32 v14, v14, v15
	v_add_f32_e32 v15, v117, v119
	v_add_f32_e32 v14, v14, v15
	v_mul_f32_e32 v15, 0x3b000000, v12
	v_mul_f32_e32 v15, v15, v15
	v_fma_f32 v14, v14, s16, -v15
	v_max_f32_e32 v14, 0, v14
	v_add_f32_e32 v14, 0x358637bd, v14
	v_rsq_f32_e32 v14, v14
	v_fmac_f32_e32 v43, 0xbb000000, v12
	ds_write_b16 v86, v13 offset:3072
	v_cvt_pk_bf16_f32 v13, v120, s0
	v_mul_f32_e32 v12, v43, v14
	v_fma_f32 v12, v143, v12, v142
	ds_write_b16 v86, v13 offset:19456
	v_mul_f32_e32 v13, 0xbfb8aa3b, v12
	v_exp_f32_e32 v13, v13
	v_readlane_b32 s15, v251, 13
	v_add_f32_e32 v13, 1.0, v13
	v_rcp_f32_e32 v13, v13
	s_nop 0
	v_mul_f32_e32 v12, v12, v13
	v_cvt_pk_bf16_f32 v12, v12, s0
	ds_write_b16 v86, v12 offset:35840
	v_mov_b32_e32 v12, s15
	v_readlane_b32 s15, v251, 20
	ds_read_b128 v[12:15], v12
	s_nop 0
	v_mov_b32_e32 v43, s15
	v_readlane_b32 s15, v251, 27
	ds_read_b128 v[104:107], v43
	s_waitcnt lgkmcnt(1)
	v_add_f32_e32 v12, v12, v14
	v_mov_b32_e32 v43, s15
	v_readlane_b32 s15, v251, 34
	ds_read_b128 v[108:111], v43
	s_waitcnt lgkmcnt(1)
	v_add_f32_e32 v14, v104, v106
	v_mov_b32_e32 v43, s15
	ds_read_b128 v[112:115], v43
	v_add_f32_e32 v12, v12, v14
	s_waitcnt lgkmcnt(1)
	v_add_f32_e32 v14, v108, v110
	v_add_f32_e32 v12, v12, v14
	v_add_f32_e32 v13, v13, v15
	s_waitcnt lgkmcnt(0)
	v_add_f32_e32 v14, v112, v114
	v_add_f32_e32 v12, v12, v14
	v_add_f32_e32 v14, v105, v107
	v_add_f32_e32 v13, v13, v14
	v_add_f32_e32 v14, v109, v111
	v_add_f32_e32 v13, v13, v14
	v_add_f32_e32 v14, v113, v115
	v_add_f32_e32 v13, v13, v14
	v_mul_f32_e32 v14, 0x3b000000, v12
	v_mul_f32_e32 v14, v14, v14
	v_fma_f32 v13, v13, s16, -v14
	v_max_f32_e32 v13, 0, v13
	v_add_f32_e32 v13, 0x358637bd, v13
	v_rsq_f32_e32 v13, v13
	v_fmac_f32_e32 v27, 0xbb000000, v12
	ds_write_b16 v86, v4 offset:4096
	v_cvt_pk_bf16_f32 v4, v53, s0
	v_mul_f32_e32 v12, v27, v13
	v_fma_f32 v12, v143, v12, v142
	ds_write_b16 v86, v4 offset:20480
	v_mul_f32_e32 v4, 0xbfb8aa3b, v12
	v_exp_f32_e32 v4, v4
	v_readlane_b32 s15, v251, 14
	v_mov_b32_e32 v43, v193
	v_add_f32_e32 v4, 1.0, v4
	v_rcp_f32_e32 v4, v4
	s_nop 0
	v_mul_f32_e32 v4, v12, v4
	v_cvt_pk_bf16_f32 v4, v4, s0
	ds_write_b16 v86, v4 offset:36864
	v_mov_b32_e32 v4, s15
	v_readlane_b32 s15, v251, 21
	ds_read_b128 v[12:15], v4
	s_nop 0
	v_mov_b32_e32 v4, s15
	v_readlane_b32 s15, v251, 28
	ds_read_b128 v[50:53], v4
	s_nop 0
	v_mov_b32_e32 v4, s15
	v_readlane_b32 s15, v251, 35
	ds_read_b128 v[104:107], v4
	s_nop 0
	v_mov_b32_e32 v4, s15
	ds_read_b128 v[108:111], v4
	s_waitcnt lgkmcnt(3)
	v_add_f32_e32 v4, v12, v14
	s_waitcnt lgkmcnt(2)
	v_add_f32_e32 v12, v50, v52
	v_add_f32_e32 v4, v4, v12
	s_waitcnt lgkmcnt(1)
	v_add_f32_e32 v12, v104, v106
	v_add_f32_e32 v4, v4, v12
	s_waitcnt lgkmcnt(0)
	v_add_f32_e32 v12, v108, v110
	v_add_f32_e32 v4, v4, v12
	v_add_f32_e32 v12, v13, v15
	v_add_f32_e32 v13, v51, v53
	v_add_f32_e32 v12, v12, v13
	v_add_f32_e32 v13, v105, v107
	v_add_f32_e32 v12, v12, v13
	v_add_f32_e32 v13, v109, v111
	v_add_f32_e32 v12, v12, v13
	v_mul_f32_e32 v13, 0x3b000000, v4
	v_mul_f32_e32 v13, v13, v13
	v_fma_f32 v12, v12, s16, -v13
	v_max_f32_e32 v12, 0, v12
	v_add_f32_e32 v12, 0x358637bd, v12
	v_rsq_f32_e32 v12, v12
	v_fmac_f32_e32 v26, 0xbb000000, v4
	ds_write_b16 v86, v5 offset:5120
	v_cvt_pk_bf16_f32 v5, v55, s0
	v_mul_f32_e32 v4, v26, v12
	v_fma_f32 v4, v143, v4, v142
	ds_write_b16 v86, v5 offset:21504
	v_mul_f32_e32 v5, 0xbfb8aa3b, v4
	v_exp_f32_e32 v5, v5
	v_readlane_b32 s15, v251, 15
	v_add_f32_e32 v5, 1.0, v5
	v_rcp_f32_e32 v5, v5
	s_nop 0
	v_mul_f32_e32 v4, v4, v5
	v_cvt_pk_bf16_f32 v4, v4, s0
	ds_write_b16 v86, v4 offset:37888
	v_mov_b32_e32 v4, s15
	v_readlane_b32 s15, v251, 22
	ds_read_b128 v[12:15], v4
	s_nop 0
	v_mov_b32_e32 v4, s15
	v_readlane_b32 s15, v251, 29
	ds_read_b128 v[50:53], v4
	s_waitcnt lgkmcnt(0)
	v_add_f32_e32 v5, v50, v52
	v_mov_b32_e32 v4, s15
	v_readlane_b32 s15, v251, 36
	ds_read_b128 v[104:107], v4
	s_nop 0
	v_mov_b32_e32 v4, s15
	ds_read_b128 v[108:111], v4
	v_add_f32_e32 v4, v12, v14
	v_add_f32_e32 v4, v4, v5
	s_waitcnt lgkmcnt(1)
	v_add_f32_e32 v5, v104, v106
	v_add_f32_e32 v4, v4, v5
	s_waitcnt lgkmcnt(0)
	v_add_f32_e32 v5, v108, v110
	v_add_f32_e32 v4, v4, v5
	v_add_f32_e32 v5, v13, v15
	v_add_f32_e32 v12, v51, v53
	v_add_f32_e32 v5, v5, v12
	v_add_f32_e32 v12, v105, v107
	v_add_f32_e32 v5, v5, v12
	v_add_f32_e32 v12, v109, v111
	v_add_f32_e32 v5, v5, v12
	v_mul_f32_e32 v12, 0x3b000000, v4
	v_mul_f32_e32 v12, v12, v12
	v_fma_f32 v5, v5, s16, -v12
	v_max_f32_e32 v5, 0, v5
	v_add_f32_e32 v5, 0x358637bd, v5
	v_rsq_f32_e32 v5, v5
	v_fmac_f32_e32 v25, 0xbb000000, v4
	ds_write_b16 v86, v0 offset:6144
	v_cvt_pk_bf16_f32 v0, v56, s0
	v_mul_f32_e32 v4, v25, v5
	v_fma_f32 v4, v143, v4, v142
	ds_write_b16 v86, v0 offset:22528
	v_mul_f32_e32 v0, 0xbfb8aa3b, v4
	v_exp_f32_e32 v0, v0
	v_readlane_b32 s15, v251, 16
	v_add_f32_e32 v0, 1.0, v0
	v_rcp_f32_e32 v0, v0
	s_nop 0
	v_mul_f32_e32 v0, v4, v0
	v_cvt_pk_bf16_f32 v0, v0, s0
	ds_write_b16 v86, v0 offset:38912
	v_mov_b32_e32 v0, s15
	v_readlane_b32 s15, v251, 23
	ds_read_b128 v[12:15], v0
	s_nop 0
	v_mov_b32_e32 v0, s15
	v_readlane_b32 s15, v251, 30
	ds_read_b128 v[50:53], v0
	s_waitcnt lgkmcnt(0)
	v_add_f32_e32 v4, v50, v52
	v_mov_b32_e32 v0, s15
	v_readlane_b32 s15, v251, 37
	ds_read_b128 v[104:107], v0
	v_add_f32_e32 v5, v51, v53
	v_mov_b32_e32 v0, s15
	ds_read_b128 v[108:111], v0
	v_add_f32_e32 v0, v12, v14
	v_add_f32_e32 v0, v0, v4
	s_waitcnt lgkmcnt(1)
	v_add_f32_e32 v4, v104, v106
	v_add_f32_e32 v0, v0, v4
	s_waitcnt lgkmcnt(0)
	v_add_f32_e32 v4, v108, v110
	v_add_f32_e32 v0, v0, v4
	v_add_f32_e32 v4, v13, v15
	v_add_f32_e32 v4, v4, v5
	v_add_f32_e32 v5, v105, v107
	v_add_f32_e32 v4, v4, v5
	v_add_f32_e32 v5, v109, v111
	v_add_f32_e32 v4, v4, v5
	v_mul_f32_e32 v5, 0x3b000000, v0
	v_mul_f32_e32 v5, v5, v5
	v_fma_f32 v4, v4, s16, -v5
	v_max_f32_e32 v4, 0, v4
	v_add_f32_e32 v4, 0x358637bd, v4
	v_rsq_f32_e32 v4, v4
	v_fmac_f32_e32 v23, 0xbb000000, v0
	ds_write_b16 v86, v1 offset:7168
	v_cvt_pk_bf16_f32 v1, v57, s0
	v_mul_f32_e32 v0, v23, v4
	v_fma_f32 v0, v143, v0, v142
	ds_write_b16 v86, v1 offset:23552
	v_mul_f32_e32 v1, 0xbfb8aa3b, v0
	v_exp_f32_e32 v1, v1
	v_readlane_b32 s15, v252, 2
	v_add_f32_e32 v1, 1.0, v1
	v_rcp_f32_e32 v1, v1
	s_nop 0
	v_mul_f32_e32 v0, v0, v1
	v_cvt_pk_bf16_f32 v0, v0, s0
	ds_write_b16 v86, v0 offset:39936
	v_mov_b32_e32 v0, s15
	v_readlane_b32 s15, v252, 3
	ds_read_b128 v[12:15], v0
	s_nop 0
	v_mov_b32_e32 v0, s15
	v_readlane_b32 s15, v252, 4
	ds_read_b128 v[50:53], v0
	s_waitcnt lgkmcnt(0)
	v_add_f32_e32 v1, v50, v52
	v_mov_b32_e32 v0, s15
	v_readlane_b32 s15, v252, 5
	ds_read_b128 v[104:107], v0
	v_add_f32_e32 v4, v51, v53
	v_mov_b32_e32 v0, s15
	ds_read_b128 v[108:111], v0
	v_add_f32_e32 v0, v12, v14
	v_add_f32_e32 v0, v0, v1
	s_waitcnt lgkmcnt(1)
	v_add_f32_e32 v1, v104, v106
	v_add_f32_e32 v0, v0, v1
	s_waitcnt lgkmcnt(0)
	v_add_f32_e32 v1, v108, v110
	v_add_f32_e32 v0, v0, v1
	v_add_f32_e32 v1, v13, v15
	v_add_f32_e32 v1, v1, v4
	v_add_f32_e32 v4, v105, v107
	v_add_f32_e32 v1, v1, v4
	v_add_f32_e32 v4, v109, v111
	v_add_f32_e32 v1, v1, v4
	v_mul_f32_e32 v4, 0x3b000000, v0
	v_mul_f32_e32 v4, v4, v4
	v_fma_f32 v1, v1, s16, -v4
	v_max_f32_e32 v1, 0, v1
	v_add_f32_e32 v1, 0x358637bd, v1
	v_rsq_f32_e32 v1, v1
	v_fmac_f32_e32 v24, 0xbb000000, v0
	v_readlane_b32 s15, v252, 6
	v_mul_f32_e32 v0, v24, v1
	v_cvt_pk_bf16_f32 v1, v10, s0
	v_fma_f32 v0, v143, v0, v142
	ds_write_b16 v86, v1 offset:8192
	v_cvt_pk_bf16_f32 v1, v58, s0
	ds_write_b16 v86, v1 offset:24576
	v_mul_f32_e32 v1, 0xbfb8aa3b, v0
	v_exp_f32_e32 v1, v1
	s_nop 0
	v_add_f32_e32 v1, 1.0, v1
	v_rcp_f32_e32 v1, v1
	s_nop 0
	v_mul_f32_e32 v0, v0, v1
	v_cvt_pk_bf16_f32 v0, v0, s0
	ds_write_b16 v86, v0 offset:40960
	v_mov_b32_e32 v0, s15
	v_readlane_b32 s15, v252, 7
	ds_read_b128 v[12:15], v0
	s_nop 0
	v_mov_b32_e32 v0, s15
	v_readlane_b32 s15, v252, 8
	ds_read_b128 v[24:27], v0
	s_waitcnt lgkmcnt(0)
	v_add_f32_e32 v1, v24, v26
	v_mov_b32_e32 v0, s15
	v_readlane_b32 s15, v252, 9
	ds_read_b128 v[50:53], v0
	v_add_f32_e32 v4, v25, v27
	v_mov_b32_e32 v0, s15
	ds_read_b128 v[104:107], v0
	v_add_f32_e32 v0, v12, v14
	v_add_f32_e32 v0, v0, v1
	s_waitcnt lgkmcnt(1)
	v_add_f32_e32 v1, v50, v52
	v_add_f32_e32 v0, v0, v1
	s_waitcnt lgkmcnt(0)
	v_add_f32_e32 v1, v104, v106
	v_add_f32_e32 v0, v0, v1
	v_add_f32_e32 v1, v13, v15
	v_add_f32_e32 v1, v1, v4
	v_add_f32_e32 v4, v51, v53
	v_add_f32_e32 v1, v1, v4
	v_add_f32_e32 v4, v105, v107
	v_add_f32_e32 v1, v1, v4
	v_mul_f32_e32 v4, 0x3b000000, v0
	v_mul_f32_e32 v4, v4, v4
	v_fma_f32 v1, v1, s16, -v4
	v_max_f32_e32 v1, 0, v1
	v_add_f32_e32 v1, 0x358637bd, v1
	v_rsq_f32_e32 v1, v1
	v_fmac_f32_e32 v22, 0xbb000000, v0
	v_readlane_b32 s15, v252, 10
	v_mul_f32_e32 v0, v22, v1
	v_cvt_pk_bf16_f32 v1, v11, s0
	v_fma_f32 v0, v143, v0, v142
	ds_write_b16 v86, v1 offset:9216
	v_cvt_pk_bf16_f32 v1, v59, s0
	ds_write_b16 v86, v1 offset:25600
	v_mul_f32_e32 v1, 0xbfb8aa3b, v0
	v_exp_f32_e32 v1, v1
	s_nop 0
	v_add_f32_e32 v1, 1.0, v1
	v_rcp_f32_e32 v1, v1
	s_nop 0
	v_mul_f32_e32 v0, v0, v1
	v_cvt_pk_bf16_f32 v0, v0, s0
	ds_write_b16 v86, v0 offset:41984
	v_mov_b32_e32 v0, s15
	v_readlane_b32 s15, v252, 11
	ds_read_b128 v[10:13], v0
	s_nop 0
	v_mov_b32_e32 v0, s15
	v_readlane_b32 s15, v252, 12
	ds_read_b128 v[22:25], v0
	s_waitcnt lgkmcnt(0)
	v_add_f32_e32 v1, v22, v24
	v_mov_b32_e32 v0, s15
	v_readlane_b32 s15, v252, 13
	ds_read_b128 v[50:53], v0
	v_add_f32_e32 v4, v23, v25
	v_mov_b32_e32 v0, s15
	ds_read_b128 v[56:59], v0
	v_add_f32_e32 v0, v10, v12
	v_add_f32_e32 v0, v0, v1
	s_waitcnt lgkmcnt(1)
	v_add_f32_e32 v1, v50, v52
	v_add_f32_e32 v0, v0, v1
	s_waitcnt lgkmcnt(0)
	v_add_f32_e32 v1, v56, v58
	v_add_f32_e32 v0, v0, v1
	v_add_f32_e32 v1, v11, v13
	v_add_f32_e32 v1, v1, v4
	v_add_f32_e32 v4, v51, v53
	v_add_f32_e32 v1, v1, v4
	v_add_f32_e32 v4, v57, v59
	v_add_f32_e32 v1, v1, v4
	v_mul_f32_e32 v4, 0x3b000000, v0
	v_mul_f32_e32 v4, v4, v4
	v_fma_f32 v1, v1, s16, -v4
	v_max_f32_e32 v1, 0, v1
	v_add_f32_e32 v1, 0x358637bd, v1
	v_rsq_f32_e32 v1, v1
	v_fmac_f32_e32 v21, 0xbb000000, v0
	v_readlane_b32 s15, v252, 14
	v_mul_f32_e32 v0, v21, v1
	v_cvt_pk_bf16_f32 v1, v8, s0
	v_fma_f32 v0, v143, v0, v142
	ds_write_b16 v86, v1 offset:10240
	v_cvt_pk_bf16_f32 v1, v77, s0
	ds_write_b16 v86, v1 offset:26624
	v_mul_f32_e32 v1, 0xbfb8aa3b, v0
	v_exp_f32_e32 v1, v1
	s_nop 0
	v_add_f32_e32 v1, 1.0, v1
	v_rcp_f32_e32 v1, v1
	s_nop 0
	v_mul_f32_e32 v0, v0, v1
	v_cvt_pk_bf16_f32 v0, v0, s0
	ds_write_b16 v86, v0 offset:43008
	v_mov_b32_e32 v0, s15
	v_readlane_b32 s15, v252, 15
	ds_read_b128 v[10:13], v0
	s_nop 0
	v_mov_b32_e32 v0, s15
	v_readlane_b32 s15, v252, 16
	ds_read_b128 v[22:25], v0
	s_waitcnt lgkmcnt(0)
	v_add_f32_e32 v1, v22, v24
	v_mov_b32_e32 v0, s15
	v_readlane_b32 s15, v252, 17
	ds_read_b128 v[50:53], v0
	v_add_f32_e32 v4, v23, v25
	v_mov_b32_e32 v0, s15
	ds_read_b128 v[56:59], v0
	v_add_f32_e32 v0, v10, v12
	v_add_f32_e32 v0, v0, v1
	s_waitcnt lgkmcnt(1)
	v_add_f32_e32 v1, v50, v52
	v_add_f32_e32 v0, v0, v1
	s_waitcnt lgkmcnt(0)
	v_add_f32_e32 v1, v56, v58
	v_add_f32_e32 v0, v0, v1
	v_add_f32_e32 v1, v11, v13
	v_add_f32_e32 v1, v1, v4
	v_add_f32_e32 v4, v51, v53
	v_add_f32_e32 v1, v1, v4
	v_add_f32_e32 v4, v57, v59
	v_add_f32_e32 v1, v1, v4
	v_mul_f32_e32 v4, 0x3b000000, v0
	v_mul_f32_e32 v4, v4, v4
	v_fma_f32 v1, v1, s16, -v4
	v_max_f32_e32 v1, 0, v1
	v_add_f32_e32 v1, 0x358637bd, v1
	v_rsq_f32_e32 v1, v1
	v_fmac_f32_e32 v20, 0xbb000000, v0
	v_readlane_b32 s15, v252, 18
	v_mul_f32_e32 v0, v20, v1
	v_cvt_pk_bf16_f32 v1, v9, s0
	v_fma_f32 v0, v143, v0, v142
	ds_write_b16 v86, v1 offset:11264
	v_cvt_pk_bf16_f32 v1, v78, s0
	ds_write_b16 v86, v1 offset:27648
	v_mul_f32_e32 v1, 0xbfb8aa3b, v0
	v_exp_f32_e32 v1, v1
	s_nop 0
	v_add_f32_e32 v1, 1.0, v1
	v_rcp_f32_e32 v1, v1
	s_nop 0
	v_mul_f32_e32 v0, v0, v1
	v_cvt_pk_bf16_f32 v0, v0, s0
	ds_write_b16 v86, v0 offset:44032
	v_mov_b32_e32 v0, s15
	v_readlane_b32 s15, v252, 19
	ds_read_b128 v[8:11], v0
	s_nop 0
	v_mov_b32_e32 v0, s15
	v_readlane_b32 s15, v252, 20
	ds_read_b128 v[12:15], v0
	s_waitcnt lgkmcnt(0)
	v_add_f32_e32 v1, v12, v14
	v_mov_b32_e32 v0, s15
	v_readlane_b32 s15, v252, 21
	ds_read_b128 v[20:23], v0
	v_add_f32_e32 v4, v13, v15
	v_mov_b32_e32 v0, s15
	ds_read_b128 v[24:27], v0
	v_add_f32_e32 v0, v8, v10
	v_add_f32_e32 v0, v0, v1
	s_waitcnt lgkmcnt(1)
	v_add_f32_e32 v1, v20, v22
	v_add_f32_e32 v0, v0, v1
	s_waitcnt lgkmcnt(0)
	v_add_f32_e32 v1, v24, v26
	v_add_f32_e32 v0, v0, v1
	v_add_f32_e32 v1, v9, v11
	v_add_f32_e32 v1, v1, v4
	v_add_f32_e32 v4, v21, v23
	v_add_f32_e32 v1, v1, v4
	v_add_f32_e32 v4, v25, v27
	v_add_f32_e32 v1, v1, v4
	v_mul_f32_e32 v4, 0x3b000000, v0
	v_mul_f32_e32 v4, v4, v4
	v_fma_f32 v1, v1, s16, -v4
	v_max_f32_e32 v1, 0, v1
	v_add_f32_e32 v1, 0x358637bd, v1
	v_rsq_f32_e32 v1, v1
	v_fmac_f32_e32 v19, 0xbb000000, v0
	v_readlane_b32 s15, v252, 22
	v_mul_f32_e32 v0, v19, v1
	v_cvt_pk_bf16_f32 v1, v2, s0
	v_fma_f32 v0, v143, v0, v142
	ds_write_b16 v86, v1 offset:12288
	v_cvt_pk_bf16_f32 v1, v79, s0
	ds_write_b16 v86, v1 offset:28672
	v_mul_f32_e32 v1, 0xbfb8aa3b, v0
	v_exp_f32_e32 v1, v1
	s_nop 0
	v_add_f32_e32 v1, 1.0, v1
	v_rcp_f32_e32 v1, v1
	s_nop 0
	v_mul_f32_e32 v0, v0, v1
	v_cvt_pk_bf16_f32 v0, v0, s0
	ds_write_b16 v86, v0 offset:45056
	v_mov_b32_e32 v0, s15
	v_readlane_b32 s15, v252, 23
	ds_read_b128 v[8:11], v0
	s_nop 0
	v_mov_b32_e32 v0, s15
	v_readlane_b32 s15, v252, 24
	ds_read_b128 v[12:15], v0
	s_waitcnt lgkmcnt(0)
	v_add_f32_e32 v1, v12, v14
	v_mov_b32_e32 v0, s15
	v_readlane_b32 s15, v252, 25
	ds_read_b128 v[20:23], v0
	v_add_f32_e32 v2, v13, v15
	v_mov_b32_e32 v0, s15
	ds_read_b128 v[24:27], v0
	v_add_f32_e32 v0, v8, v10
	v_add_f32_e32 v0, v0, v1
	s_waitcnt lgkmcnt(1)
	v_add_f32_e32 v1, v20, v22
	v_add_f32_e32 v0, v0, v1
	s_waitcnt lgkmcnt(0)
	v_add_f32_e32 v1, v24, v26
	v_add_f32_e32 v0, v0, v1
	v_add_f32_e32 v1, v9, v11
	v_add_f32_e32 v1, v1, v2
	v_add_f32_e32 v2, v21, v23
	v_add_f32_e32 v1, v1, v2
	v_add_f32_e32 v2, v25, v27
	v_add_f32_e32 v1, v1, v2
	v_mul_f32_e32 v2, 0x3b000000, v0
	v_mul_f32_e32 v2, v2, v2
	v_fma_f32 v1, v1, s16, -v2
	v_max_f32_e32 v1, 0, v1
	v_add_f32_e32 v1, 0x358637bd, v1
	v_rsq_f32_e32 v1, v1
	v_fmac_f32_e32 v18, 0xbb000000, v0
	v_readlane_b32 s15, v252, 26
	v_mul_f32_e32 v0, v18, v1
	v_cvt_pk_bf16_f32 v1, v3, s0
	v_fma_f32 v0, v143, v0, v142
	ds_write_b16 v86, v1 offset:13312
	v_cvt_pk_bf16_f32 v1, v80, s0
	ds_write_b16 v86, v1 offset:29696
	v_mul_f32_e32 v1, 0xbfb8aa3b, v0
	v_exp_f32_e32 v1, v1
	s_nop 0
	v_add_f32_e32 v1, 1.0, v1
	v_rcp_f32_e32 v1, v1
	s_nop 0
	v_mul_f32_e32 v0, v0, v1
	v_cvt_pk_bf16_f32 v0, v0, s0
	ds_write_b16 v86, v0 offset:46080
	v_mov_b32_e32 v0, s15
	v_readlane_b32 s15, v252, 27
	ds_read_b128 v[0:3], v0
	s_nop 0
	v_mov_b32_e32 v4, s15
	v_readlane_b32 s15, v252, 28
	ds_read_b128 v[8:11], v4
	s_waitcnt lgkmcnt(1)
	v_add_f32_e32 v0, v0, v2
	v_mov_b32_e32 v4, s15
	v_readlane_b32 s15, v252, 29
	ds_read_b128 v[12:15], v4
	s_waitcnt lgkmcnt(1)
	v_add_f32_e32 v2, v8, v10
	v_mov_b32_e32 v4, s15
	ds_read_b128 v[18:21], v4
	v_add_f32_e32 v0, v0, v2
	s_waitcnt lgkmcnt(1)
	v_add_f32_e32 v2, v12, v14
	v_add_f32_e32 v0, v0, v2
	v_add_f32_e32 v1, v1, v3
	s_waitcnt lgkmcnt(0)
	v_add_f32_e32 v2, v18, v20
	v_add_f32_e32 v0, v0, v2
	v_add_f32_e32 v2, v9, v11
	v_add_f32_e32 v1, v1, v2
	v_add_f32_e32 v2, v13, v15
	v_add_f32_e32 v1, v1, v2
	v_add_f32_e32 v2, v19, v21
	v_add_f32_e32 v1, v1, v2
	v_mul_f32_e32 v2, 0x3b000000, v0
	v_mul_f32_e32 v2, v2, v2
	v_fma_f32 v1, v1, s16, -v2
	v_max_f32_e32 v1, 0, v1
	v_add_f32_e32 v1, 0x358637bd, v1
	v_rsq_f32_e32 v1, v1
	v_fmac_f32_e32 v17, 0xbb000000, v0
	v_readlane_b32 s15, v252, 30
	v_mul_f32_e32 v0, v17, v1
	v_cvt_pk_bf16_f32 v1, v6, s0
	v_fma_f32 v0, v143, v0, v142
	ds_write_b16 v86, v1 offset:14336
	v_cvt_pk_bf16_f32 v1, v76, s0
	ds_write_b16 v86, v1 offset:30720
	v_mul_f32_e32 v1, 0xbfb8aa3b, v0
	v_exp_f32_e32 v1, v1
	s_nop 0
	v_add_f32_e32 v1, 1.0, v1
	v_rcp_f32_e32 v1, v1
	s_nop 0
	v_mul_f32_e32 v0, v0, v1
	v_cvt_pk_bf16_f32 v0, v0, s0
	ds_write_b16 v86, v0 offset:47104
	v_mov_b32_e32 v0, s15
	v_readlane_b32 s15, v252, 31
	ds_read_b128 v[0:3], v0
	s_nop 0
	v_mov_b32_e32 v4, s15
	v_readlane_b32 s15, v252, 32
	ds_read_b128 v[8:11], v4
	s_waitcnt lgkmcnt(1)
	v_add_f32_e32 v0, v0, v2
	v_mov_b32_e32 v4, s15
	v_readlane_b32 s15, v252, 33
	ds_read_b128 v[12:15], v4
	s_waitcnt lgkmcnt(1)
	v_add_f32_e32 v2, v8, v10
	v_mov_b32_e32 v4, s15
	ds_read_b128 v[18:21], v4
	v_add_f32_e32 v0, v0, v2
	s_waitcnt lgkmcnt(1)
	v_add_f32_e32 v2, v12, v14
	v_add_f32_e32 v0, v0, v2
	v_add_f32_e32 v1, v1, v3
	s_waitcnt lgkmcnt(0)
	v_add_f32_e32 v2, v18, v20
	v_add_f32_e32 v0, v0, v2
	v_add_f32_e32 v2, v9, v11
	v_add_f32_e32 v1, v1, v2
	v_add_f32_e32 v2, v13, v15
	v_add_f32_e32 v1, v1, v2
	v_add_f32_e32 v2, v19, v21
	v_add_f32_e32 v1, v1, v2
	v_mul_f32_e32 v2, 0x3b000000, v0
	v_mul_f32_e32 v2, v2, v2
	v_fma_f32 v1, v1, s16, -v2
	v_max_f32_e32 v1, 0, v1
	v_add_f32_e32 v1, 0x358637bd, v1
	v_rsq_f32_e32 v1, v1
	v_fmac_f32_e32 v16, 0xbb000000, v0
	s_ashr_i32 s15, s14, 31
	s_mov_b64 s[16:17], s[42:43]
	v_mul_f32_e32 v0, v16, v1
	v_cvt_pk_bf16_f32 v1, v7, s0
	v_fma_f32 v0, v143, v0, v142
	ds_write_b16 v86, v1 offset:15360
	v_cvt_pk_bf16_f32 v1, v54, s0
	ds_write_b16 v86, v1 offset:31744
	v_mul_f32_e32 v1, 0xbfb8aa3b, v0
	v_exp_f32_e32 v1, v1
	s_lshl_b64 s[14:15], s[14:15], 12
	v_add_f32_e32 v1, 1.0, v1
	v_rcp_f32_e32 v1, v1
	s_nop 0
	v_mul_f32_e32 v0, v0, v1
	v_cvt_pk_bf16_f32 v0, v0, s0
	ds_write_b16 v86, v0 offset:48128
	s_waitcnt lgkmcnt(0)
	s_barrier
	s_add_u32 s14, s16, s14
	s_addc_u32 s15, s17, s15
	s_add_u32 s14, s14, 0x14000000
	ds_read_b128 v[0:3], v92
	s_addc_u32 s15, s15, 0
	v_lshl_add_u64 v[4:5], s[14:15], 0, v[42:43]
	v_lshl_add_u64 v[6:7], v[30:31], 1, v[4:5]
	v_lshl_add_u64 v[6:7], v[6:7], 0, v[192:193]
	s_waitcnt lgkmcnt(0)
	global_store_dwordx4 v[6:7], v[0:3], off
	ds_read_b128 v[0:3], v93
	v_lshl_add_u64 v[6:7], s[14:15], 0, v[44:45]
	v_lshl_add_u64 v[6:7], v[32:33], 1, v[6:7]
	v_lshl_add_u64 v[6:7], v[6:7], 0, v[192:193]
	s_add_i32 s54, s54, 1
	s_waitcnt lgkmcnt(0)
	global_store_dwordx4 v[6:7], v[0:3], off
	ds_read_b128 v[0:3], v94
	v_lshl_add_u64 v[6:7], v[34:35], 1, v[4:5]
	v_lshl_add_u64 v[6:7], v[6:7], 0, v[192:193]
	v_lshl_add_u64 v[4:5], v[38:39], 1, v[4:5]
	v_lshl_add_u64 v[4:5], v[4:5], 0, v[192:193]
	s_waitcnt lgkmcnt(0)
	global_store_dwordx4 v[6:7], v[0:3], off
	ds_read_b128 v[0:3], v95
	v_lshl_add_u64 v[6:7], s[14:15], 0, v[46:47]
	v_lshl_add_u64 v[6:7], v[36:37], 1, v[6:7]
	v_lshl_add_u64 v[6:7], v[6:7], 0, v[192:193]
	s_cmp_eq_u32 s54, 4
	s_waitcnt lgkmcnt(0)
	global_store_dwordx4 v[6:7], v[0:3], off
	ds_read_b128 v[0:3], v96
	s_waitcnt lgkmcnt(0)
	global_store_dwordx4 v[4:5], v[0:3], off
	ds_read_b128 v[0:3], v97
	v_lshl_add_u64 v[4:5], s[14:15], 0, v[48:49]
	v_lshl_add_u64 v[4:5], v[40:41], 1, v[4:5]
	v_lshl_add_u64 v[4:5], v[4:5], 0, v[192:193]
	s_waitcnt lgkmcnt(0)
	global_store_dwordx4 v[4:5], v[0:3], off
	s_waitcnt lgkmcnt(0)
	s_barrier
	s_cbranch_scc1 .LBB0_569

.LBB0_447:
	s_or_b64 exec, exec, s[20:21]
	v_add3_u32 v6, v0, s33, v1
	v_cmp_lt_i32_e64 s[14:15], -1, v6
	v_mov_b32_e32 v3, 0
	v_mov_b32_e32 v2, 0
	v_mov_b32_e32 v1, 0
	v_mov_b32_e32 v0, 0
	s_and_saveexec_b64 s[20:21], s[14:15]
	s_cbranch_execz .LBB0_449
	v_add_u32_e32 v2, s45, v6
	v_mov_b64_e32 v[0:1], s[30:31]
	v_mad_i64_i32 v[0:1], s[14:15], v2, s76, v[0:1]
	v_lshl_add_u64 v[0:1], v[4:5], 1, v[0:1]
	v_lshlrev_b32_e32 v192, 1, v28
	v_lshl_add_u64 v[0:1], v[0:1], 0, v[192:193]
	global_load_dwordx4 v[0:3], v[0:1], off

.LBB0_461:
	s_or_b64 exec, exec, s[20:21]
	v_add3_u32 v10, v4, s33, v5
	v_cmp_lt_i32_e64 s[16:17], -1, v10
	v_mov_b32_e32 v7, 0
	v_mov_b32_e32 v6, 0
	v_mov_b32_e32 v5, 0
	v_mov_b32_e32 v4, 0
	s_and_saveexec_b64 s[20:21], s[16:17]
	s_cbranch_execz .LBB0_463
	v_add_u32_e32 v6, s45, v10
	v_mov_b64_e32 v[4:5], s[30:31]
	v_mad_i64_i32 v[4:5], s[16:17], v6, s76, v[4:5]
	v_lshl_add_u64 v[4:5], v[8:9], 1, v[4:5]
	v_lshlrev_b32_e32 v192, 1, v28
	v_lshl_add_u64 v[4:5], v[4:5], 0, v[192:193]
	global_load_dwordx4 v[4:7], v[4:5], off

.LBB0_475:
	s_or_b64 exec, exec, s[22:23]
	v_add3_u32 v14, v8, s33, v9
	v_cmp_lt_i32_e64 s[18:19], -1, v14
	v_mov_b32_e32 v11, 0
	v_mov_b32_e32 v10, 0
	v_mov_b32_e32 v9, 0
	v_mov_b32_e32 v8, 0
	s_and_saveexec_b64 s[22:23], s[18:19]
	s_cbranch_execz .LBB0_477
	v_add_u32_e32 v10, s45, v14
	v_mov_b64_e32 v[8:9], s[30:31]
	v_mad_i64_i32 v[8:9], s[18:19], v10, s76, v[8:9]
	v_lshl_add_u64 v[8:9], v[12:13], 1, v[8:9]
	v_lshlrev_b32_e32 v192, 1, v28
	v_lshl_add_u64 v[8:9], v[8:9], 0, v[192:193]
	global_load_dwordx4 v[8:11], v[8:9], off

.LBB0_489:
	s_or_b64 exec, exec, s[24:25]
	v_add3_u32 v18, v12, s33, v13
	v_cmp_lt_i32_e64 s[20:21], -1, v18
	v_mov_b32_e32 v15, 0
	v_mov_b32_e32 v14, 0
	v_mov_b32_e32 v13, 0
	v_mov_b32_e32 v12, 0
	s_and_saveexec_b64 s[24:25], s[20:21]
	s_cbranch_execz .LBB0_491
	v_add_u32_e32 v14, s45, v18
	v_mov_b64_e32 v[12:13], s[30:31]
	v_mad_i64_i32 v[12:13], s[20:21], v14, s76, v[12:13]
	v_lshl_add_u64 v[12:13], v[16:17], 1, v[12:13]
	v_lshlrev_b32_e32 v192, 1, v28
	v_lshl_add_u64 v[12:13], v[12:13], 0, v[192:193]
	global_load_dwordx4 v[12:15], v[12:13], off

.LBB0_503:
	s_or_b64 exec, exec, s[28:29]
	v_add3_u32 v22, v16, s33, v17
	v_cmp_lt_i32_e64 s[22:23], -1, v22
	v_mov_b32_e32 v19, 0
	v_mov_b32_e32 v18, 0
	v_mov_b32_e32 v17, 0
	v_mov_b32_e32 v16, 0
	s_and_saveexec_b64 s[28:29], s[22:23]
	s_cbranch_execz .LBB0_505
	v_add_u32_e32 v18, s45, v22
	v_mov_b64_e32 v[16:17], s[30:31]
	v_mad_i64_i32 v[16:17], s[22:23], v18, s76, v[16:17]
	v_lshl_add_u64 v[16:17], v[20:21], 1, v[16:17]
	v_lshlrev_b32_e32 v192, 1, v28
	v_lshl_add_u64 v[16:17], v[16:17], 0, v[192:193]
	global_load_dwordx4 v[16:19], v[16:17], off

.LBB0_517:
	s_or_b64 exec, exec, s[36:37]
	v_add3_u32 v26, v20, s33, v21
	v_cmp_lt_i32_e64 s[24:25], -1, v26
	v_mov_b32_e32 v23, 0
	v_mov_b32_e32 v22, 0
	v_mov_b32_e32 v21, 0
	v_mov_b32_e32 v20, 0
	s_and_saveexec_b64 s[36:37], s[24:25]
	s_cbranch_execz .LBB0_519
	v_add_u32_e32 v22, s45, v26
	v_mov_b64_e32 v[20:21], s[30:31]
	v_mad_i64_i32 v[20:21], s[24:25], v22, s76, v[20:21]
	v_lshl_add_u64 v[20:21], v[24:25], 1, v[20:21]
	v_lshlrev_b32_e32 v192, 1, v28
	v_lshl_add_u64 v[20:21], v[20:21], 0, v[192:193]
	global_load_dwordx4 v[20:23], v[20:21], off

.LBB0_531:
	s_or_b64 exec, exec, s[40:41]
	v_add3_u32 v55, v24, s33, v25
	v_cmp_lt_i32_e64 s[28:29], -1, v55
	v_mov_b32_e32 v27, 0
	v_mov_b32_e32 v26, 0
	v_mov_b32_e32 v25, 0
	v_mov_b32_e32 v24, 0
	s_and_saveexec_b64 s[38:39], s[28:29]
	s_cbranch_execz .LBB0_533
	v_add_u32_e32 v26, s45, v55
	v_mov_b64_e32 v[24:25], s[30:31]
	v_mad_i64_i32 v[24:25], s[28:29], v26, s76, v[24:25]
	v_lshl_add_u64 v[24:25], v[50:51], 1, v[24:25]
	v_lshlrev_b32_e32 v192, 1, v28
	v_lshl_add_u64 v[24:25], v[24:25], 0, v[192:193]
	global_load_dwordx4 v[24:27], v[24:25], off

.LBB0_551:
	v_ashrrev_i32_e32 v2, 6, v1
	v_add_u32_e32 v3, 0xffffffbf, v2
	v_subrev_u32_e32 v4, 49, v2
	v_cmp_gt_i32_e32 vcc, 31, v2
	s_movk_i32 s14, 0xffee
	v_cmp_gt_u32_e64 s[16:17], -16, v3
	v_cndmask_b32_e32 v3, v3, v2, vcc
	v_subrev_u32_e32 v5, 31, v2
	v_cmp_gt_u32_e64 s[14:15], s14, v4
	s_nop 1
	v_cndmask_b32_e64 v3, v5, v3, s[14:15]
	v_add_u32_e32 v192, -16, v3
	v_cmp_lt_i32_e64 s[18:19], -1, v192
	s_and_b64 s[18:19], s[16:17], s[18:19]
	s_and_saveexec_b64 s[16:17], s[18:19]
	s_cbranch_execz .LBB0_550
	v_mov_b32_e32 v3, s48
	v_mov_b32_e32 v4, s52
	v_cndmask_b32_e32 v3, v3, v4, vcc
	v_mov_b32_e32 v4, s49
	v_mov_b32_e32 v5, s53
	v_cndmask_b32_e32 v4, v4, v5, vcc
	v_mov_b32_e32 v5, s51
	v_and_b32_e32 v10, 0x1f8, v0
	v_cndmask_b32_e64 v7, v5, v4, s[14:15]
	v_mov_b32_e32 v4, s50
	v_cndmask_b32_e64 v6, v4, v3, s[14:15]
	v_lshlrev_b32_e32 v2, 10, v2
	v_lshlrev_b32_e32 v3, 1, v10
	v_add3_u32 v2, 0, v2, v3
	ds_read_b128 v[2:5], v2
	s_mov_b64 s[14:15], s[40:41]
	v_lshlrev_b64 v[8:9], 11, v[192:193]
	v_lshl_add_u64 v[6:7], v[6:7], 2, s[14:15]
	v_lshl_add_u64 v[6:7], v[6:7], 0, v[8:9]
	v_lshlrev_b32_e32 v192, 2, v10
	v_lshl_add_u64 v[10:11], v[6:7], 0, v[192:193]
	s_waitcnt lgkmcnt(0)
	v_lshlrev_b32_e32 v6, 16, v2
	v_and_b32_e32 v7, 0xffff0000, v2
	v_lshlrev_b32_e32 v8, 16, v3
	v_and_b32_e32 v9, 0xffff0000, v3
	v_lshlrev_b32_e32 v2, 16, v4
	v_and_b32_e32 v3, 0xffff0000, v4
	v_lshlrev_b32_e32 v4, 16, v5
	v_and_b32_e32 v5, 0xffff0000, v5
	global_store_dwordx4 v[10:11], v[6:9], off
	global_store_dwordx4 v[10:11], v[2:5], off offset:16
	s_branch .LBB0_550

.LBB0_569:
	s_cmpk_lt_i32 s3, 0x80
	s_cbranch_scc0 .LBB0_104
	s_lshl_b32 s26, s3, 3
	s_ashr_i32 s0, s3, 31
	v_readlane_b32 s4, v253, 59
	v_readlane_b32 s5, v253, 60
	s_add_u32 s16, s4, s3
	s_addc_u32 s17, s5, s0
	s_mul_i32 s0, s17, 0x1e00
	s_mul_hi_u32 s1, s16, 0x1e00
	s_add_i32 s1, s1, s0
	s_mul_i32 s0, s16, 0x1e00
	v_readlane_b32 s48, v250, 31
	s_lshl_b64 s[8:9], s[0:1], 2
	v_readlane_b32 s52, v250, 35
	v_readlane_b32 s53, v250, 36
	s_add_u32 s0, s52, s8
	s_mov_b64 s[18:19], s[42:43]
	s_addc_u32 s1, s53, s9
	v_lshlrev_b32_e32 v76, 2, v28
	v_mov_b32_e32 v77, v193
	s_mov_b64 s[4:5], 0x18400000
	v_lshl_add_u64 v[0:1], s[18:19], 0, v[192:193]
	v_lshl_add_u64 v[36:37], s[0:1], 0, v[76:77]
	s_movk_i32 s0, 0x5c0
	s_mov_b64 s[10:11], s[40:41]
	s_add_i32 s3, s26, 0x3ff1
	v_lshl_add_u64 v[38:39], v[0:1], 0, s[4:5]
	v_ashrrev_i32_e32 v78, 6, v64
	v_cmp_gt_i32_e32 vcc, s0, v64
	v_mov_b32_e32 v4, 0
	v_mov_b32_e32 v0, 0
	v_mov_b32_e32 v12, 0
	v_mov_b32_e32 v13, 0
	v_mov_b32_e32 v14, 0
	v_mov_b32_e32 v15, 0
	v_mov_b32_e32 v8, 0
	v_mov_b32_e32 v9, 0
	v_mov_b32_e32 v10, 0
	v_mov_b32_e32 v11, 0
	v_mov_b32_e32 v5, 0
	v_mov_b32_e32 v6, 0
	v_mov_b32_e32 v7, 0
	v_readlane_b32 s49, v250, 32
	v_readlane_b32 s50, v250, 33
	v_readlane_b32 s51, v250, 34
	v_readlane_b32 s54, v250, 37
	v_readlane_b32 s55, v250, 38
	v_readlane_b32 s56, v250, 39
	v_readlane_b32 s57, v250, 40
	v_readlane_b32 s58, v250, 41
	v_readlane_b32 s59, v250, 42
	v_readlane_b32 s60, v250, 43
	v_readlane_b32 s61, v250, 44
	v_readlane_b32 s62, v250, 45
	v_readlane_b32 s63, v250, 46
	s_and_saveexec_b64 s[4:5], vcc
	s_cbranch_execz .LBB0_576
	v_cmp_lt_i32_e64 s[0:1], 14, v78
	s_and_saveexec_b64 s[6:7], s[0:1]
	s_xor_b64 s[0:1], exec, s[6:7]
	s_cbranch_execz .LBB0_573
	v_add_u32_e32 v1, s3, v78
	v_mad_i64_i32 v[2:3], s[6:7], v1, s76, v[38:39]
	global_load_dwordx4 v[4:7], v[2:3], off

.LBB0_576:
	s_or_b64 exec, exec, s[4:5]
	s_movk_i32 s0, 0x3c0
	v_mov_b32_e32 v20, s83
	v_mov_b32_e32 v21, s83
	v_mov_b32_e32 v22, s83
	v_mov_b32_e32 v23, s83
	v_mov_b32_e32 v16, s83
	v_mov_b32_e32 v17, s83
	v_mov_b32_e32 v18, s83
	v_mov_b32_e32 v19, s83
	v_ashrrev_i32_e32 v80, 6, v82
	v_cmp_gt_i32_e64 s[0:1], s0, v64
	v_mov_b32_e32 v1, 0
	v_mov_b32_e32 v2, 0
	v_mov_b32_e32 v3, 0
	v_mov_b32_e32 v24, 0
	v_mov_b32_e32 v25, 0
	v_mov_b32_e32 v26, 0
	v_mov_b32_e32 v27, 0
	s_and_saveexec_b64 s[6:7], s[0:1]
	s_cbranch_execz .LBB0_582
	v_cmp_lt_i32_e64 s[4:5], 14, v80
	s_and_saveexec_b64 s[12:13], s[4:5]
	s_xor_b64 s[4:5], exec, s[12:13]
	s_cbranch_execz .LBB0_579
	v_add_u32_e32 v0, s3, v80
	v_mad_i64_i32 v[0:1], s[12:13], v0, s76, v[38:39]
	global_load_dwordx4 v[24:27], v[0:1], off

.LBB0_582:
	s_or_b64 exec, exec, s[6:7]
	s_movk_i32 s4, 0x1c0
	v_ashrrev_i32_e32 v82, 6, v29
	v_cmp_gt_i32_e64 s[4:5], s4, v64
	v_mov_b32_e32 v28, 0
	v_mov_b32_e32 v32, 0
	v_mov_b32_e32 v33, 0
	v_mov_b32_e32 v34, 0
	v_mov_b32_e32 v35, 0
	v_mov_b32_e32 v29, 0
	v_mov_b32_e32 v30, 0
	v_mov_b32_e32 v31, 0
	s_and_saveexec_b64 s[12:13], s[4:5]
	s_cbranch_execz .LBB0_588
	v_cmp_lt_i32_e64 s[6:7], 14, v82
	s_and_saveexec_b64 s[14:15], s[6:7]
	s_xor_b64 s[6:7], exec, s[14:15]
	s_cbranch_execz .LBB0_585
	v_add_u32_e32 v28, s3, v82
	v_mad_i64_i32 v[28:29], s[14:15], v28, s76, v[38:39]
	global_load_dwordx4 v[28:31], v[28:29], off

.LBB0_588:
	s_or_b64 exec, exec, s[12:13]
	s_add_u32 s6, s10, s8
	s_addc_u32 s7, s11, s9
	v_mov_b32_e32 v77, v193
	v_add_u32_e32 v95, 0, v76
	v_lshl_add_u64 v[36:37], s[6:7], 0, v[76:77]
	s_mov_b64 s[6:7], 0x6578000
	v_lshl_add_u64 v[36:37], v[36:37], 0, s[6:7]
	v_lshl_add_u32 v96, v78, 11, v95
	s_and_saveexec_b64 s[6:7], vcc
	s_cbranch_execz .LBB0_591
	s_waitcnt vmcnt(0) lgkmcnt(0)
	v_lshlrev_b32_e32 v38, 16, v4
	v_and_b32_e32 v39, 0xffff0000, v4
	v_lshlrev_b32_e32 v40, 16, v5
	v_and_b32_e32 v41, 0xffff0000, v5
	v_lshlrev_b32_e32 v4, 16, v6
	v_and_b32_e32 v5, 0xffff0000, v6
	v_lshlrev_b32_e32 v6, 16, v7
	v_and_b32_e32 v7, 0xffff0000, v7
	v_cmp_gt_i32_e32 vcc, 15, v78
	s_nop 1
	v_cndmask_b32_e32 v7, v7, v15, vcc
	v_cndmask_b32_e32 v6, v6, v14, vcc
	v_cndmask_b32_e32 v5, v5, v13, vcc
	v_cndmask_b32_e32 v4, v4, v12, vcc
	v_cndmask_b32_e32 v11, v41, v11, vcc
	v_cndmask_b32_e32 v10, v40, v10, vcc
	v_cndmask_b32_e32 v9, v39, v9, vcc
	v_cndmask_b32_e32 v8, v38, v8, vcc
	v_cmp_lt_i32_e32 vcc, 7, v78
	ds_write_b128 v96, v[8:11]
	ds_write_b128 v96, v[4:7] offset:16
	s_and_b64 exec, exec, vcc
	s_cbranch_execz .LBB0_591
	v_add_u32_e32 v12, -8, v78
	v_mov_b32_e32 v13, v193
	v_lshlrev_b64 v[12:13], 11, v[12:13]
	v_lshl_add_u64 v[12:13], v[36:37], 0, v[12:13]
	global_store_dwordx4 v[12:13], v[8:11], off
	global_store_dwordx4 v[12:13], v[4:7], off offset:16
.LBB0_591:
	s_or_b64 exec, exec, s[6:7]
	v_lshl_add_u32 v97, v80, 11, v95
	s_and_saveexec_b64 s[6:7], s[0:1]
	s_cbranch_execz .LBB0_594
	s_waitcnt vmcnt(0) lgkmcnt(0)
	v_lshlrev_b32_e32 v4, 16, v24
	v_and_b32_e32 v5, 0xffff0000, v24
	v_lshlrev_b32_e32 v6, 16, v25
	v_and_b32_e32 v7, 0xffff0000, v25
	v_lshlrev_b32_e32 v8, 16, v26
	v_and_b32_e32 v9, 0xffff0000, v26
	v_lshlrev_b32_e32 v10, 16, v27
	v_and_b32_e32 v11, 0xffff0000, v27
	v_cmp_gt_i32_e32 vcc, 15, v80
	s_nop 1
	v_cndmask_b32_e32 v3, v11, v3, vcc
	v_cndmask_b32_e32 v2, v10, v2, vcc
	v_cndmask_b32_e32 v1, v9, v1, vcc
	v_cndmask_b32_e32 v0, v8, v0, vcc
	v_cndmask_b32_e32 v7, v7, v23, vcc
	v_cndmask_b32_e32 v6, v6, v22, vcc
	v_cndmask_b32_e32 v5, v5, v21, vcc
	v_cndmask_b32_e32 v4, v4, v20, vcc
	v_cmp_lt_i32_e32 vcc, 7, v80
	ds_write_b128 v97, v[4:7]
	ds_write_b128 v97, v[0:3] offset:16
	s_and_b64 exec, exec, vcc
	s_cbranch_execz .LBB0_594
	v_add_u32_e32 v8, -8, v80
	v_mov_b32_e32 v9, v193
	v_lshlrev_b64 v[8:9], 11, v[8:9]
	v_lshl_add_u64 v[8:9], v[36:37], 0, v[8:9]
	global_store_dwordx4 v[8:9], v[4:7], off
	global_store_dwordx4 v[8:9], v[0:3], off offset:16
.LBB0_594:
	s_or_b64 exec, exec, s[6:7]
	v_lshl_add_u32 v104, v82, 11, v95
	s_and_saveexec_b64 s[0:1], s[4:5]
	s_cbranch_execz .LBB0_597
	s_waitcnt vmcnt(0) lgkmcnt(0)
	v_lshlrev_b32_e32 v4, 16, v28
	v_and_b32_e32 v5, 0xffff0000, v28
	v_lshlrev_b32_e32 v6, 16, v29
	v_and_b32_e32 v7, 0xffff0000, v29
	v_lshlrev_b32_e32 v0, 16, v30
	v_and_b32_e32 v1, 0xffff0000, v30
	v_lshlrev_b32_e32 v2, 16, v31
	v_and_b32_e32 v3, 0xffff0000, v31
	v_cmp_gt_i32_e32 vcc, 15, v82
	s_nop 1
	v_cndmask_b32_e32 v3, v3, v35, vcc
	v_cndmask_b32_e32 v2, v2, v34, vcc
	v_cndmask_b32_e32 v1, v1, v33, vcc
	v_cndmask_b32_e32 v0, v0, v32, vcc
	v_cndmask_b32_e32 v7, v7, v19, vcc
	v_cndmask_b32_e32 v6, v6, v18, vcc
	v_cndmask_b32_e32 v5, v5, v17, vcc
	v_cndmask_b32_e32 v4, v4, v16, vcc
	v_cmp_lt_i32_e32 vcc, 7, v82
	ds_write_b128 v104, v[4:7]
	ds_write_b128 v104, v[0:3] offset:16
	s_and_b64 exec, exec, vcc
	s_cbranch_execz .LBB0_597
	v_add_u32_e32 v8, -8, v82
	v_mov_b32_e32 v9, v193
	v_lshlrev_b64 v[8:9], 11, v[8:9]
	v_lshl_add_u64 v[8:9], v[36:37], 0, v[8:9]
	global_store_dwordx4 v[8:9], v[4:7], off
	global_store_dwordx4 v[8:9], v[0:3], off offset:16

.LBB0_606:
	s_add_i32 s6, s26, 0x4000
	s_mov_b64 s[0:1], s[42:43]
	s_ashr_i32 s7, s6, 31
	s_lshl_b64 s[4:5], s[6:7], 12
	s_add_u32 s0, s0, s4
	s_addc_u32 s1, s1, s5
	v_lshl_add_u64 v[8:9], v[64:65], 1, s[0:1]
	s_waitcnt vmcnt(0)
	v_cvt_pk_bf16_f32 v6, v6, s0
	s_brev_b32 s0, 40
	v_add_co_u32_e32 v10, vcc, s0, v8
	v_readlane_b32 s48, v250, 31
	s_nop 0
	v_addc_co_u32_e32 v11, vcc, 0, v9, vcc
	global_store_short v[10:11], v6, off
	v_cvt_pk_bf16_f32 v10, v7, s0
	s_mov_b32 s0, 0x14001000
	v_add_co_u32_e32 v6, vcc, s0, v8
	v_cvt_pk_bf16_f32 v4, v4, s0
	s_nop 0
	v_addc_co_u32_e32 v7, vcc, 0, v9, vcc
	s_mov_b32 s0, 0x14002000
	global_store_short v[6:7], v10, off
	v_add_co_u32_e32 v6, vcc, s0, v8
	v_readlane_b32 s54, v250, 37
	s_nop 0
	v_addc_co_u32_e32 v7, vcc, 0, v9, vcc
	global_store_short v[6:7], v4, off
	v_cvt_pk_bf16_f32 v6, v5, s0
	s_mov_b32 s0, 0x14003000
	v_add_co_u32_e32 v4, vcc, s0, v8
	v_cvt_pk_bf16_f32 v2, v2, s0
	s_nop 0
	v_addc_co_u32_e32 v5, vcc, 0, v9, vcc
	s_mov_b32 s0, 0x14004000
	global_store_short v[4:5], v6, off
	v_add_co_u32_e32 v4, vcc, s0, v8
	v_readlane_b32 s55, v250, 38
	s_nop 0
	v_addc_co_u32_e32 v5, vcc, 0, v9, vcc
	global_store_short v[4:5], v2, off
	v_cvt_pk_bf16_f32 v4, v3, s0
	s_mov_b32 s0, 0x14005000
	v_add_co_u32_e32 v2, vcc, s0, v8
	v_cvt_pk_bf16_f32 v0, v0, s0
	s_nop 0
	v_addc_co_u32_e32 v3, vcc, 0, v9, vcc
	s_mov_b32 s0, 0x14006000
	global_store_short v[2:3], v4, off
	v_add_co_u32_e32 v2, vcc, s0, v8
	v_mov_b32_e32 v77, v193
	s_nop 0
	v_addc_co_u32_e32 v3, vcc, 0, v9, vcc
	global_store_short v[2:3], v0, off
	v_cvt_pk_bf16_f32 v2, v1, s0
	s_mov_b32 s0, 0x14007000
	v_add_co_u32_e32 v0, vcc, s0, v8
	s_lshl_b64 s[0:1], s[16:17], 12
	s_add_u32 s0, s54, s0
	v_addc_co_u32_e32 v1, vcc, 0, v9, vcc
	s_addc_u32 s1, s55, s1
	global_store_short v[0:1], v2, off
	v_lshl_add_u64 v[0:1], s[18:19], 0, v[192:193]
	s_mov_b64 s[4:5], 0x18400400
	v_lshl_add_u64 v[24:25], s[0:1], 0, v[76:77]
	s_movk_i32 s0, 0x280
	s_mov_b64 s[8:9], s[40:41]
	s_add_i32 s3, s26, 0x3ffe
	v_lshl_add_u64 v[26:27], v[0:1], 0, s[4:5]
	v_cmp_gt_i32_e32 vcc, s0, v64
	v_mov_b32_e32 v4, 0
	v_mov_b32_e32 v0, 0
	v_mov_b32_e32 v12, 0
	v_mov_b32_e32 v13, 0
	v_mov_b32_e32 v14, 0
	v_mov_b32_e32 v15, 0
	v_mov_b32_e32 v8, 0
	v_mov_b32_e32 v9, 0
	v_mov_b32_e32 v10, 0
	v_mov_b32_e32 v11, 0
	v_mov_b32_e32 v5, 0
	v_mov_b32_e32 v6, 0
	v_mov_b32_e32 v7, 0
	s_waitcnt lgkmcnt(0)
	s_barrier
	v_readlane_b32 s49, v250, 32
	v_readlane_b32 s50, v250, 33
	v_readlane_b32 s51, v250, 34
	v_readlane_b32 s52, v250, 35
	v_readlane_b32 s53, v250, 36
	v_readlane_b32 s56, v250, 39
	v_readlane_b32 s57, v250, 40
	v_readlane_b32 s58, v250, 41
	v_readlane_b32 s59, v250, 42
	v_readlane_b32 s60, v250, 43
	v_readlane_b32 s61, v250, 44
	v_readlane_b32 s62, v250, 45
	v_readlane_b32 s63, v250, 46
	s_and_saveexec_b64 s[4:5], vcc
	s_cbranch_execz .LBB0_612
	v_cmp_lt_i32_e64 s[0:1], 1, v78
	s_and_saveexec_b64 s[10:11], s[0:1]
	s_xor_b64 s[0:1], exec, s[10:11]
	s_cbranch_execz .LBB0_609
	v_add_u32_e32 v1, s3, v78
	v_mad_i64_i32 v[2:3], s[10:11], v1, s76, v[26:27]
	global_load_dwordx4 v[4:7], v[2:3], off

.LBB0_612:
	s_or_b64 exec, exec, s[4:5]
	s_movk_i32 s0, 0x80
	v_mov_b32_e32 v16, s83
	v_mov_b32_e32 v17, s83
	v_mov_b32_e32 v18, s83
	v_mov_b32_e32 v19, s83
	v_mov_b32_e32 v20, s83
	v_mov_b32_e32 v21, s83
	v_mov_b32_e32 v22, s83
	v_mov_b32_e32 v23, s83
	v_cmp_gt_i32_e64 s[0:1], s0, v64
	v_mov_b32_e32 v1, 0
	v_mov_b32_e32 v2, 0
	v_mov_b32_e32 v3, 0
	s_and_saveexec_b64 s[10:11], s[0:1]
	s_cbranch_execz .LBB0_618
	v_cmp_lt_i32_e64 s[4:5], 1, v80
	s_and_saveexec_b64 s[12:13], s[4:5]
	s_xor_b64 s[4:5], exec, s[12:13]
	s_cbranch_execz .LBB0_615
	v_add_u32_e32 v0, s3, v80
	v_mad_i64_i32 v[0:1], s[12:13], v0, s76, v[26:27]
	global_load_dwordx4 v[0:3], v[0:1], off

.LBB0_618:
	s_or_b64 exec, exec, s[10:11]
	s_lshl_b64 s[4:5], s[16:17], 10
	s_lshl_b64 s[4:5], s[4:5], 2
	s_add_u32 s4, s8, s4
	s_addc_u32 s5, s9, s5
	v_mov_b32_e32 v77, v193
	v_lshl_add_u64 v[24:25], s[4:5], 0, v[76:77]
	s_mov_b64 s[4:5], 0x6cf8000
	v_lshl_add_u64 v[24:25], v[24:25], 0, s[4:5]
	s_and_saveexec_b64 s[4:5], vcc
	s_cbranch_execz .LBB0_621
	s_waitcnt vmcnt(0) lgkmcnt(0)
	v_lshlrev_b32_e32 v26, 16, v4
	v_and_b32_e32 v27, 0xffff0000, v4
	v_lshlrev_b32_e32 v28, 16, v5
	v_and_b32_e32 v29, 0xffff0000, v5
	v_lshlrev_b32_e32 v4, 16, v6
	v_and_b32_e32 v5, 0xffff0000, v6
	v_lshlrev_b32_e32 v6, 16, v7
	v_and_b32_e32 v7, 0xffff0000, v7
	v_cmp_gt_i32_e32 vcc, 2, v78
	s_nop 1
	v_cndmask_b32_e32 v7, v7, v15, vcc
	v_cndmask_b32_e32 v6, v6, v14, vcc
	v_cndmask_b32_e32 v5, v5, v13, vcc
	v_cndmask_b32_e32 v4, v4, v12, vcc
	v_cndmask_b32_e32 v11, v29, v11, vcc
	v_cndmask_b32_e32 v10, v28, v10, vcc
	v_cndmask_b32_e32 v9, v27, v9, vcc
	v_cndmask_b32_e32 v8, v26, v8, vcc
	v_cmp_lt_i32_e32 vcc, 7, v78
	ds_write_b128 v96, v[8:11]
	ds_write_b128 v96, v[4:7] offset:16
	s_and_b64 exec, exec, vcc
	s_cbranch_execz .LBB0_621
	v_add_u32_e32 v12, -8, v78
	v_mov_b32_e32 v13, v193
	v_lshlrev_b64 v[12:13], 11, v[12:13]
	v_lshl_add_u64 v[12:13], v[24:25], 0, v[12:13]
	global_store_dwordx4 v[12:13], v[8:11], off
	global_store_dwordx4 v[12:13], v[4:7], off offset:16
.LBB0_621:
	s_or_b64 exec, exec, s[4:5]
	s_and_saveexec_b64 s[4:5], s[0:1]
	s_cbranch_execz .LBB0_624
	s_waitcnt vmcnt(0) lgkmcnt(0)
	v_lshlrev_b32_e32 v4, 16, v0
	v_and_b32_e32 v5, 0xffff0000, v0
	v_lshlrev_b32_e32 v6, 16, v1
	v_and_b32_e32 v7, 0xffff0000, v1
	v_lshlrev_b32_e32 v0, 16, v2
	v_and_b32_e32 v1, 0xffff0000, v2
	v_lshlrev_b32_e32 v2, 16, v3
	v_and_b32_e32 v3, 0xffff0000, v3
	v_cmp_gt_i32_e32 vcc, 2, v80
	s_nop 1
	v_cndmask_b32_e32 v3, v3, v23, vcc
	v_cndmask_b32_e32 v2, v2, v22, vcc
	v_cndmask_b32_e32 v1, v1, v21, vcc
	v_cndmask_b32_e32 v0, v0, v20, vcc
	v_cndmask_b32_e32 v7, v7, v19, vcc
	v_cndmask_b32_e32 v6, v6, v18, vcc
	v_cndmask_b32_e32 v5, v5, v17, vcc
	v_cndmask_b32_e32 v4, v4, v16, vcc
	v_cmp_lt_i32_e32 vcc, 7, v80
	ds_write_b128 v97, v[4:7]
	ds_write_b128 v97, v[0:3] offset:16
	s_and_b64 exec, exec, vcc
	s_cbranch_execz .LBB0_624
	v_add_u32_e32 v8, -8, v80
	v_mov_b32_e32 v9, v193
	v_lshlrev_b64 v[8:9], 11, v[8:9]
	v_lshl_add_u64 v[8:9], v[24:25], 0, v[8:9]
	global_store_dwordx4 v[8:9], v[4:7], off
	global_store_dwordx4 v[8:9], v[0:3], off offset:16
.LBB0_624:
	s_or_b64 exec, exec, s[4:5]
	s_movk_i32 s0, 0x200
	v_cmp_gt_i32_e32 vcc, s0, v64
	v_cmp_lt_i32_e64 s[0:1], -1, v78
	s_and_b64 s[20:21], vcc, s[0:1]
	s_waitcnt vmcnt(0) lgkmcnt(0)
	v_mov_b32_e32 v0, 0
	v_add_u32_e32 v93, s6, v78
	v_mov_b32_e32 v1, 0
	v_mov_b32_e32 v2, 0
	v_mov_b32_e32 v3, 0
	s_and_saveexec_b64 s[0:1], s[20:21]
	s_cbranch_execz .LBB0_626
	v_mov_b64_e32 v[0:1], s[18:19]
	v_mad_i64_i32 v[0:1], s[4:5], v93, s76, v[0:1]
	v_lshl_add_u64 v[0:1], v[0:1], 0, v[192:193]
	v_add_co_u32_e32 v0, vcc, 0x18400000, v0
	s_nop 1
	v_addc_co_u32_e32 v1, vcc, 0, v1, vcc
	global_load_dwordx4 v[0:3], v[0:1], off offset:2048

.LBB0_628:
	s_or_b64 exec, exec, s[6:7]
	s_mov_b64 s[6:7], s[42:43]
	s_waitcnt lgkmcnt(0)
	s_barrier
	s_waitcnt vmcnt(0)
	ds_read2st64_b32 v[0:1], v92 offset1:8
	ds_read2st64_b32 v[2:3], v92 offset0:16 offset1:24
	ds_read2st64_b32 v[4:5], v92 offset0:80 offset1:88
	s_lshl_b64 s[14:15], s[4:5], 1
	s_add_u32 s4, s6, s14
	s_addc_u32 s5, s7, s15
	s_waitcnt lgkmcnt(2)
	v_mul_f32_e32 v8, v165, v1
	v_fmac_f32_e32 v8, v163, v0
	v_lshl_add_u64 v[6:7], v[64:65], 1, s[4:5]
	s_waitcnt lgkmcnt(1)
	v_fmac_f32_e32 v8, v164, v2
	s_brev_b32 s3, 40
	s_waitcnt lgkmcnt(0)
	v_mul_f32_e32 v0, v4, v8
	v_add_co_u32_e32 v8, vcc, s3, v6
	v_cvt_pk_bf16_f32 v0, v0, s0
	s_nop 0
	v_addc_co_u32_e32 v9, vcc, 0, v7, vcc
	global_store_short v[8:9], v0, off offset:1024
	v_mul_f32_e32 v0, v165, v2
	v_fmac_f32_e32 v0, v163, v1
	v_fmac_f32_e32 v0, v164, v3
	v_mul_f32_e32 v0, v5, v0
	s_mov_b32 s3, 0x14001000
	v_cvt_pk_bf16_f32 v10, v0, s0
	v_add_co_u32_e32 v0, vcc, s3, v6
	ds_read2st64_b32 v[4:5], v92 offset0:32 offset1:40
	ds_read2st64_b32 v[8:9], v92 offset0:96 offset1:104
	v_addc_co_u32_e32 v1, vcc, 0, v7, vcc
	global_store_short v[0:1], v10, off offset:1024
	v_mul_f32_e32 v0, v165, v3
	v_fmac_f32_e32 v0, v163, v2
	s_waitcnt lgkmcnt(0)
	v_fmac_f32_e32 v0, v164, v4
	v_mul_f32_e32 v0, v8, v0
	s_mov_b32 s3, 0x14002000
	v_cvt_pk_bf16_f32 v2, v0, s0
	v_add_co_u32_e32 v0, vcc, s3, v6
	s_mov_b32 s3, 0x14003000
	s_nop 0
	v_addc_co_u32_e32 v1, vcc, 0, v7, vcc
	global_store_short v[0:1], v2, off offset:1024
	v_mul_f32_e32 v0, v165, v4
	v_fmac_f32_e32 v0, v163, v3
	v_fmac_f32_e32 v0, v164, v5
	v_mul_f32_e32 v0, v9, v0
	v_cvt_pk_bf16_f32 v10, v0, s0
	v_add_co_u32_e32 v0, vcc, s3, v6
	ds_read2st64_b32 v[2:3], v92 offset0:48 offset1:56
	ds_read2st64_b32 v[8:9], v92 offset0:112 offset1:120
	v_addc_co_u32_e32 v1, vcc, 0, v7, vcc
	global_store_short v[0:1], v10, off offset:1024
	v_mul_f32_e32 v0, v165, v5
	v_fmac_f32_e32 v0, v163, v4
	s_waitcnt lgkmcnt(0)
	v_fmac_f32_e32 v0, v164, v2
	v_mul_f32_e32 v0, v8, v0
	s_mov_b32 s3, 0x14004000
	v_cvt_pk_bf16_f32 v4, v0, s0
	v_add_co_u32_e32 v0, vcc, s3, v6
	s_mov_b32 s3, 0x14005000
	s_nop 0
	v_addc_co_u32_e32 v1, vcc, 0, v7, vcc
	global_store_short v[0:1], v4, off offset:1024
	v_mul_f32_e32 v0, v165, v2
	v_fmac_f32_e32 v0, v163, v5
	v_fmac_f32_e32 v0, v164, v3
	v_mul_f32_e32 v0, v9, v0
	v_cvt_pk_bf16_f32 v10, v0, s0
	v_add_co_u32_e32 v0, vcc, s3, v6
	ds_read2st64_b32 v[4:5], v92 offset0:64 offset1:72
	ds_read2st64_b32 v[8:9], v92 offset0:128 offset1:136
	v_addc_co_u32_e32 v1, vcc, 0, v7, vcc
	global_store_short v[0:1], v10, off offset:1024
	v_mul_f32_e32 v0, v165, v3
	v_fmac_f32_e32 v0, v163, v2
	s_waitcnt lgkmcnt(0)
	v_fmac_f32_e32 v0, v164, v4
	v_mul_f32_e32 v0, v8, v0
	s_mov_b32 s3, 0x14006000
	v_cvt_pk_bf16_f32 v2, v0, s0
	v_add_co_u32_e32 v0, vcc, s3, v6
	s_mov_b32 s3, 0x14007000
	s_nop 0
	v_addc_co_u32_e32 v1, vcc, 0, v7, vcc
	global_store_short v[0:1], v2, off offset:1024
	v_mul_f32_e32 v0, v165, v4
	v_fmac_f32_e32 v0, v163, v3
	v_fmac_f32_e32 v0, v164, v5
	v_mul_f32_e32 v0, v9, v0
	v_cvt_pk_bf16_f32 v2, v0, s0
	v_add_co_u32_e32 v0, vcc, s3, v6
	s_mul_i32 s3, s17, 0x3c00
	s_mul_hi_u32 s4, s16, 0x3c00
	s_add_i32 s5, s4, s3
	s_mul_i32 s4, s16, 0x3c00
	v_readlane_b32 s48, v250, 31
	s_lshl_b64 s[22:23], s[4:5], 2
	v_readlane_b32 s56, v250, 39
	v_readlane_b32 s57, v250, 40
	s_add_u32 s4, s56, s22
	v_addc_co_u32_e32 v1, vcc, 0, v7, vcc
	s_addc_u32 s5, s57, s23
	v_mov_b32_e32 v77, v193
	global_store_short v[0:1], v2, off offset:1024
	v_lshl_add_u64 v[0:1], s[18:19], 0, v[192:193]
	s_mov_b64 s[6:7], 0x18401400
	v_lshl_add_u64 v[84:85], s[4:5], 0, v[76:77]
	s_movk_i32 s4, 0x980
	s_mov_b64 s[24:25], s[40:41]
	s_add_i32 s3, s26, 0x3fe2
	v_lshl_add_u64 v[86:87], v[0:1], 0, s[6:7]
	v_cmp_gt_i32_e32 vcc, s4, v64
	v_mov_b32_e32 v4, 0
	v_mov_b32_e32 v0, 0
	v_mov_b32_e32 v8, 0
	v_mov_b32_e32 v9, 0
	v_mov_b32_e32 v10, 0
	v_mov_b32_e32 v11, 0
	v_mov_b32_e32 v12, 0
	v_mov_b32_e32 v13, 0
	v_mov_b32_e32 v14, 0
	v_mov_b32_e32 v15, 0
	v_mov_b32_e32 v5, 0
	v_mov_b32_e32 v6, 0
	v_mov_b32_e32 v7, 0
	s_waitcnt lgkmcnt(0)
	s_barrier
	v_readlane_b32 s49, v250, 32
	v_readlane_b32 s50, v250, 33
	v_readlane_b32 s51, v250, 34
	v_readlane_b32 s52, v250, 35
	v_readlane_b32 s53, v250, 36
	v_readlane_b32 s54, v250, 37
	v_readlane_b32 s55, v250, 38
	v_readlane_b32 s58, v250, 41
	v_readlane_b32 s59, v250, 42
	v_readlane_b32 s60, v250, 43
	v_readlane_b32 s61, v250, 44
	v_readlane_b32 s62, v250, 45
	v_readlane_b32 s63, v250, 46
	s_and_saveexec_b64 s[6:7], vcc
	s_cbranch_execz .LBB0_634
	v_cmp_lt_i32_e64 s[4:5], 29, v78
	s_and_saveexec_b64 s[8:9], s[4:5]
	s_xor_b64 s[4:5], exec, s[8:9]
	s_cbranch_execz .LBB0_631
	v_add_u32_e32 v1, s3, v78
	v_mad_i64_i32 v[2:3], s[8:9], v1, s76, v[86:87]
	global_load_dwordx4 v[4:7], v[2:3], off

.LBB0_634:
	s_or_b64 exec, exec, s[6:7]
	s_movk_i32 s4, 0x780
	v_cmp_gt_i32_e64 s[10:11], s4, v64
	v_mov_b32_e32 v1, 0
	v_mov_b32_e32 v2, 0
	v_mov_b32_e32 v3, 0
	v_mov_b32_e32 v20, 0
	v_mov_b32_e32 v21, 0
	v_mov_b32_e32 v22, 0
	v_mov_b32_e32 v23, 0
	v_mov_b32_e32 v16, 0
	v_mov_b32_e32 v17, 0
	v_mov_b32_e32 v18, 0
	v_mov_b32_e32 v19, 0
	s_and_saveexec_b64 s[6:7], s[10:11]
	s_cbranch_execz .LBB0_640
	v_cmp_lt_i32_e64 s[4:5], 29, v80
	s_and_saveexec_b64 s[8:9], s[4:5]
	s_xor_b64 s[4:5], exec, s[8:9]
	s_cbranch_execz .LBB0_637
	v_add_u32_e32 v0, s3, v80
	v_mad_i64_i32 v[0:1], s[8:9], v0, s76, v[86:87]
	global_load_dwordx4 v[16:19], v[0:1], off

.LBB0_640:
	s_or_b64 exec, exec, s[6:7]
	s_movk_i32 s4, 0x580
	v_cmp_gt_i32_e64 s[4:5], s4, v64
	v_mov_b32_e32 v28, 0
	v_mov_b32_e32 v24, 0
	v_mov_b32_e32 v32, 0
	v_mov_b32_e32 v33, 0
	v_mov_b32_e32 v34, 0
	v_mov_b32_e32 v35, 0
	v_mov_b32_e32 v36, 0
	v_mov_b32_e32 v37, 0
	v_mov_b32_e32 v38, 0
	v_mov_b32_e32 v39, 0
	v_mov_b32_e32 v29, 0
	v_mov_b32_e32 v30, 0
	v_mov_b32_e32 v31, 0
	s_and_saveexec_b64 s[8:9], s[4:5]
	s_cbranch_execz .LBB0_646
	v_cmp_lt_i32_e64 s[6:7], 29, v82
	s_and_saveexec_b64 s[12:13], s[6:7]
	s_xor_b64 s[6:7], exec, s[12:13]
	s_cbranch_execz .LBB0_643
	v_add_u32_e32 v25, s3, v82
	v_mad_i64_i32 v[26:27], s[12:13], v25, s76, v[86:87]
	global_load_dwordx4 v[28:31], v[26:27], off

.LBB0_646:
	s_or_b64 exec, exec, s[8:9]
	s_movk_i32 s6, 0x380
	v_ashrrev_i32_e32 v88, 6, v88
	v_cmp_gt_i32_e64 s[6:7], s6, v64
	v_mov_b32_e32 v25, 0
	v_mov_b32_e32 v26, 0
	v_mov_b32_e32 v27, 0
	v_mov_b32_e32 v44, 0
	v_mov_b32_e32 v45, 0
	v_mov_b32_e32 v46, 0
	v_mov_b32_e32 v47, 0
	v_mov_b32_e32 v40, 0
	v_mov_b32_e32 v41, 0
	v_mov_b32_e32 v42, 0
	v_mov_b32_e32 v43, 0
	s_and_saveexec_b64 s[12:13], s[6:7]
	s_cbranch_execz .LBB0_652
	v_cmp_lt_i32_e64 s[8:9], 29, v88
	s_and_saveexec_b64 s[26:27], s[8:9]
	s_xor_b64 s[8:9], exec, s[26:27]
	s_cbranch_execz .LBB0_649
	v_add_u32_e32 v24, s3, v88
	v_mad_i64_i32 v[24:25], s[26:27], v24, s76, v[86:87]
	global_load_dwordx4 v[40:43], v[24:25], off

.LBB0_652:
	s_or_b64 exec, exec, s[12:13]
	s_movk_i32 s8, 0x180
	v_ashrrev_i32_e32 v90, 6, v90
	v_cmp_gt_i32_e64 s[8:9], s8, v64
	v_mov_b32_e32 v48, 0
	v_mov_b32_e32 v52, 0
	v_mov_b32_e32 v53, 0
	v_mov_b32_e32 v54, 0
	v_mov_b32_e32 v55, 0
	v_mov_b32_e32 v56, 0
	v_mov_b32_e32 v57, 0
	v_mov_b32_e32 v58, 0
	v_mov_b32_e32 v59, 0
	v_mov_b32_e32 v49, 0
	v_mov_b32_e32 v50, 0
	v_mov_b32_e32 v51, 0
	s_and_saveexec_b64 s[26:27], s[8:9]
	s_cbranch_execz .LBB0_658
	v_cmp_lt_i32_e64 s[12:13], 29, v90
	s_and_saveexec_b64 s[34:35], s[12:13]
	s_xor_b64 s[12:13], exec, s[34:35]
	s_cbranch_execz .LBB0_655
	v_add_u32_e32 v48, s3, v90
	v_mad_i64_i32 v[48:49], s[34:35], v48, s76, v[86:87]
	global_load_dwordx4 v[48:51], v[48:49], off

.LBB0_658:
	s_or_b64 exec, exec, s[26:27]
	s_add_u32 s12, s24, s22
	s_addc_u32 s13, s25, s23
	v_mov_b32_e32 v77, v193
	v_lshl_add_u64 v[84:85], s[12:13], 0, v[76:77]
	s_mov_b64 s[12:13], 0x6df8000
	v_lshl_add_u64 v[84:85], v[84:85], 0, s[12:13]
	s_and_saveexec_b64 s[12:13], vcc
	s_cbranch_execz .LBB0_661
	s_waitcnt vmcnt(0) lgkmcnt(0)
	v_lshlrev_b32_e32 v77, 16, v4
	v_and_b32_e32 v79, 0xffff0000, v4
	v_lshlrev_b32_e32 v81, 16, v5
	v_and_b32_e32 v83, 0xffff0000, v5
	v_lshlrev_b32_e32 v4, 16, v6
	v_and_b32_e32 v5, 0xffff0000, v6
	v_lshlrev_b32_e32 v6, 16, v7
	v_and_b32_e32 v7, 0xffff0000, v7
	v_cmp_gt_i32_e32 vcc, 30, v78
	s_nop 1
	v_cndmask_b32_e32 v7, v7, v15, vcc
	v_cndmask_b32_e32 v6, v6, v14, vcc
	v_cndmask_b32_e32 v5, v5, v13, vcc
	v_cndmask_b32_e32 v4, v4, v12, vcc
	v_cndmask_b32_e32 v11, v83, v11, vcc
	v_cndmask_b32_e32 v10, v81, v10, vcc
	v_cndmask_b32_e32 v9, v79, v9, vcc
	v_cndmask_b32_e32 v8, v77, v8, vcc
	v_cmp_lt_i32_e32 vcc, 7, v78
	ds_write_b128 v96, v[8:11]
	ds_write_b128 v96, v[4:7] offset:16
	s_and_b64 exec, exec, vcc
	s_cbranch_execz .LBB0_661
	v_add_u32_e32 v12, -8, v78
	v_mov_b32_e32 v13, v193
	v_lshlrev_b64 v[12:13], 11, v[12:13]
	v_lshl_add_u64 v[12:13], v[84:85], 0, v[12:13]
	global_store_dwordx4 v[12:13], v[8:11], off
	global_store_dwordx4 v[12:13], v[4:7], off offset:16
.LBB0_661:
	s_or_b64 exec, exec, s[12:13]
	s_and_saveexec_b64 s[12:13], s[10:11]
	s_cbranch_execz .LBB0_664
	s_waitcnt vmcnt(0) lgkmcnt(0)
	v_lshlrev_b32_e32 v8, 16, v16
	v_and_b32_e32 v9, 0xffff0000, v16
	v_lshlrev_b32_e32 v10, 16, v17
	v_and_b32_e32 v11, 0xffff0000, v17
	v_lshlrev_b32_e32 v4, 16, v18
	v_and_b32_e32 v5, 0xffff0000, v18
	v_lshlrev_b32_e32 v6, 16, v19
	v_and_b32_e32 v7, 0xffff0000, v19
	v_cmp_gt_i32_e32 vcc, 30, v80
	s_nop 1
	v_cndmask_b32_e32 v7, v7, v23, vcc
	v_cndmask_b32_e32 v6, v6, v22, vcc
	v_cndmask_b32_e32 v5, v5, v21, vcc
	v_cndmask_b32_e32 v4, v4, v20, vcc
	v_cndmask_b32_e32 v3, v11, v3, vcc
	v_cndmask_b32_e32 v2, v10, v2, vcc
	v_cndmask_b32_e32 v1, v9, v1, vcc
	v_cndmask_b32_e32 v0, v8, v0, vcc
	v_cmp_lt_i32_e32 vcc, 7, v80
	ds_write_b128 v97, v[0:3]
	ds_write_b128 v97, v[4:7] offset:16
	s_and_b64 exec, exec, vcc
	s_cbranch_execz .LBB0_664
	v_add_u32_e32 v8, -8, v80
	v_mov_b32_e32 v9, v193
	v_lshlrev_b64 v[8:9], 11, v[8:9]
	v_lshl_add_u64 v[8:9], v[84:85], 0, v[8:9]
	global_store_dwordx4 v[8:9], v[0:3], off
	global_store_dwordx4 v[8:9], v[4:7], off offset:16
.LBB0_664:
	s_or_b64 exec, exec, s[12:13]
	s_and_saveexec_b64 s[10:11], s[4:5]
	s_cbranch_execz .LBB0_667
	s_waitcnt vmcnt(0) lgkmcnt(0)
	v_lshlrev_b32_e32 v4, 16, v28
	v_and_b32_e32 v5, 0xffff0000, v28
	v_lshlrev_b32_e32 v6, 16, v29
	v_and_b32_e32 v7, 0xffff0000, v29
	v_lshlrev_b32_e32 v0, 16, v30
	v_and_b32_e32 v1, 0xffff0000, v30
	v_lshlrev_b32_e32 v2, 16, v31
	v_and_b32_e32 v3, 0xffff0000, v31
	v_cmp_gt_i32_e32 vcc, 30, v82
	s_nop 1
	v_cndmask_b32_e32 v3, v3, v39, vcc
	v_cndmask_b32_e32 v2, v2, v38, vcc
	v_cndmask_b32_e32 v1, v1, v37, vcc
	v_cndmask_b32_e32 v0, v0, v36, vcc
	v_cndmask_b32_e32 v7, v7, v35, vcc
	v_cndmask_b32_e32 v6, v6, v34, vcc
	v_cndmask_b32_e32 v5, v5, v33, vcc
	v_cndmask_b32_e32 v4, v4, v32, vcc
	v_cmp_lt_i32_e32 vcc, 7, v82
	ds_write_b128 v104, v[4:7]
	ds_write_b128 v104, v[0:3] offset:16
	s_and_b64 exec, exec, vcc
	s_cbranch_execz .LBB0_667
	v_add_u32_e32 v8, -8, v82
	v_mov_b32_e32 v9, v193
	v_lshlrev_b64 v[8:9], 11, v[8:9]
	v_lshl_add_u64 v[8:9], v[84:85], 0, v[8:9]
	global_store_dwordx4 v[8:9], v[4:7], off
	global_store_dwordx4 v[8:9], v[0:3], off offset:16
.LBB0_667:
	s_or_b64 exec, exec, s[10:11]
	s_and_saveexec_b64 s[4:5], s[6:7]
	s_cbranch_execz .LBB0_670
	s_waitcnt vmcnt(0) lgkmcnt(0)
	v_lshlrev_b32_e32 v4, 16, v40
	v_and_b32_e32 v5, 0xffff0000, v40
	v_lshlrev_b32_e32 v6, 16, v41
	v_and_b32_e32 v7, 0xffff0000, v41
	v_lshlrev_b32_e32 v0, 16, v42
	v_and_b32_e32 v1, 0xffff0000, v42
	v_lshlrev_b32_e32 v2, 16, v43
	v_and_b32_e32 v3, 0xffff0000, v43
	v_cmp_gt_i32_e32 vcc, 30, v88
	v_lshl_add_u32 v8, v88, 11, v95
	s_nop 0
	v_cndmask_b32_e32 v3, v3, v47, vcc
	v_cndmask_b32_e32 v2, v2, v46, vcc
	v_cndmask_b32_e32 v1, v1, v45, vcc
	v_cndmask_b32_e32 v0, v0, v44, vcc
	v_cndmask_b32_e32 v7, v7, v27, vcc
	v_cndmask_b32_e32 v6, v6, v26, vcc
	v_cndmask_b32_e32 v5, v5, v25, vcc
	v_cndmask_b32_e32 v4, v4, v24, vcc
	v_cmp_lt_i32_e32 vcc, 7, v88
	ds_write_b128 v8, v[4:7]
	ds_write_b128 v8, v[0:3] offset:16
	s_and_b64 exec, exec, vcc
	s_cbranch_execz .LBB0_670
	v_add_u32_e32 v8, -8, v88
	v_mov_b32_e32 v9, v193
	v_lshlrev_b64 v[8:9], 11, v[8:9]
	v_lshl_add_u64 v[8:9], v[84:85], 0, v[8:9]
	global_store_dwordx4 v[8:9], v[4:7], off
	global_store_dwordx4 v[8:9], v[0:3], off offset:16
.LBB0_670:
	s_or_b64 exec, exec, s[4:5]
	s_and_saveexec_b64 s[4:5], s[8:9]
	s_cbranch_execz .LBB0_673
	s_waitcnt vmcnt(0) lgkmcnt(0)
	v_lshlrev_b32_e32 v4, 16, v48
	v_and_b32_e32 v5, 0xffff0000, v48
	v_lshlrev_b32_e32 v6, 16, v49
	v_and_b32_e32 v7, 0xffff0000, v49
	v_lshlrev_b32_e32 v0, 16, v50
	v_and_b32_e32 v1, 0xffff0000, v50
	v_lshlrev_b32_e32 v2, 16, v51
	v_and_b32_e32 v3, 0xffff0000, v51
	v_cmp_gt_i32_e32 vcc, 30, v90
	v_lshl_add_u32 v8, v90, 11, v95
	s_nop 0
	v_cndmask_b32_e32 v3, v3, v59, vcc
	v_cndmask_b32_e32 v2, v2, v58, vcc
	v_cndmask_b32_e32 v1, v1, v57, vcc
	v_cndmask_b32_e32 v0, v0, v56, vcc
	v_cndmask_b32_e32 v7, v7, v55, vcc
	v_cndmask_b32_e32 v6, v6, v54, vcc
	v_cndmask_b32_e32 v5, v5, v53, vcc
	v_cndmask_b32_e32 v4, v4, v52, vcc
	v_cmp_lt_i32_e32 vcc, 7, v90
	ds_write_b128 v8, v[4:7]
	ds_write_b128 v8, v[0:3] offset:16
	s_and_b64 exec, exec, vcc
	s_cbranch_execz .LBB0_673
	v_add_u32_e32 v8, -8, v90
	v_mov_b32_e32 v9, v193
	v_lshlrev_b64 v[8:9], 11, v[8:9]
	v_lshl_add_u64 v[8:9], v[84:85], 0, v[8:9]
	global_store_dwordx4 v[8:9], v[4:7], off
	global_store_dwordx4 v[8:9], v[0:3], off offset:16

.LBB0_689:
	s_or_b64 exec, exec, s[6:7]
	v_readlane_b32 s8, v251, 9
	s_mov_b64 s[6:7], s[42:43]
	s_waitcnt lgkmcnt(0)
	v_mov_b32_e32 v0, s8
	v_readlane_b32 s8, v251, 10
	s_barrier
	ds_read_b128 v[0:3], v0
	v_mov_b32_e32 v4, s8
	ds_read_b128 v[4:7], v4
	v_readlane_b32 s8, v251, 11
	s_add_u32 s6, s6, s14
	s_waitcnt lgkmcnt(1)
	v_add_f32_e32 v0, 0, v0
	v_mov_b32_e32 v8, s8
	v_readlane_b32 s8, v251, 12
	ds_read_b128 v[8:11], v8
	s_waitcnt lgkmcnt(1)
	v_add_f32_e32 v0, v0, v4
	v_mov_b32_e32 v4, s8
	v_readlane_b32 s8, v251, 13
	ds_read_b128 v[12:15], v4
	v_add_f32_e32 v1, 0, v1
	v_mov_b32_e32 v4, s8
	v_readlane_b32 s8, v251, 14
	ds_read_b128 v[16:19], v4
	s_waitcnt lgkmcnt(2)
	v_add_f32_e32 v0, v0, v8
	v_mov_b32_e32 v4, s8
	v_readlane_b32 s8, v251, 15
	ds_read_b128 v[26:29], v4
	v_add_f32_e32 v1, v1, v5
	v_mov_b32_e32 v4, s8
	v_readlane_b32 s8, v251, 16
	ds_read_b128 v[40:43], v4
	s_waitcnt lgkmcnt(3)
	v_add_f32_e32 v0, v0, v12
	v_mov_b32_e32 v4, s8
	ds_read_b128 v[44:47], v4
	v_add_f32_e32 v1, v1, v9
	s_waitcnt lgkmcnt(3)
	v_add_f32_e32 v0, v0, v16
	v_add_f32_e32 v1, v1, v13
	s_waitcnt lgkmcnt(2)
	v_add_f32_e32 v0, v0, v26
	v_add_f32_e32 v1, v1, v17
	s_waitcnt lgkmcnt(1)
	v_add_f32_e32 v0, v0, v40
	v_add_f32_e32 v1, v1, v27
	s_waitcnt lgkmcnt(0)
	v_add_f32_e32 v0, v0, v44
	v_add_f32_e32 v1, v1, v41
	v_mul_f32_e32 v4, 0x3b000000, v0
	v_add_f32_e32 v1, v1, v45
	v_mul_f32_e32 v4, v4, v4
	s_mov_b32 s8, 0x3b000000
	v_fma_f32 v1, v1, s8, -v4
	v_max_f32_e32 v1, 0, v1
	v_add_f32_e32 v1, 0x358637bd, v1
	v_rsq_f32_e32 v1, v1
	v_fmac_f32_e32 v24, 0xbb000000, v0
	v_add_f32_e32 v2, 0, v2
	v_add_f32_e32 v2, v2, v6
	v_mul_f32_e32 v0, v24, v1
	v_fma_f32 v4, v143, v0, v142
	v_mul_f32_e32 v0, 0xbfb8aa3b, v4
	v_exp_f32_e32 v0, v0
	v_add_f32_e32 v3, 0, v3
	v_add_f32_e32 v2, v2, v10
	v_add_f32_e32 v3, v3, v7
	v_add_f32_e32 v0, 1.0, v0
	v_rcp_f32_e32 v5, v0
	v_add_f32_e32 v2, v2, v14
	v_add_f32_e32 v3, v3, v11
	v_add_f32_e32 v2, v2, v18
	v_add_f32_e32 v3, v3, v15
	v_add_f32_e32 v2, v2, v28
	v_add_f32_e32 v3, v3, v19
	v_add_f32_e32 v2, v2, v42
	v_mul_f32_e32 v4, v4, v5
	v_add_f32_e32 v3, v3, v29
	v_add_f32_e32 v2, v2, v46
	v_cvt_pk_bf16_f32 v21, v4, s0
	v_add_f32_e32 v3, v3, v43
	v_mul_f32_e32 v4, 0x3b000000, v2
	v_add_f32_e32 v3, v3, v47
	v_mul_f32_e32 v4, v4, v4
	v_fma_f32 v3, v3, s8, -v4
	v_max_f32_e32 v3, 0, v3
	v_add_f32_e32 v3, 0x358637bd, v3
	v_rsq_f32_e32 v3, v3
	v_fmac_f32_e32 v30, 0xbb000000, v2
	s_addc_u32 s7, s7, s15
	v_lshl_add_u64 v[0:1], v[64:65], 1, s[6:7]
	v_mul_f32_e32 v2, v30, v3
	s_brev_b32 s6, 40
	v_fma_f32 v30, v143, v2, v142
	v_add_co_u32_e32 v18, vcc, s6, v0
	v_mov_b32_e32 v2, s30
	v_mul_f32_e32 v6, 0xbfb8aa3b, v30
	v_readlane_b32 s6, v251, 17
	ds_read_b128 v[2:5], v2
	v_exp_f32_e32 v31, v6
	v_mov_b32_e32 v6, s6
	ds_read_b128 v[6:9], v6
	v_readlane_b32 s6, v251, 18
	s_waitcnt lgkmcnt(1)
	v_add_f32_e32 v2, 0, v2
	v_add_f32_e32 v3, 0, v3
	v_mov_b32_e32 v10, s6
	v_readlane_b32 s6, v251, 19
	ds_read_b128 v[10:13], v10
	s_waitcnt lgkmcnt(1)
	v_add_f32_e32 v2, v2, v6
	v_mov_b32_e32 v6, s6
	v_readlane_b32 s6, v251, 20
	ds_read_b128 v[14:17], v6
	s_waitcnt lgkmcnt(1)
	v_add_f32_e32 v2, v2, v10
	v_mov_b32_e32 v6, s6
	v_readlane_b32 s6, v251, 21
	ds_read_b128 v[22:25], v6
	v_add_f32_e32 v3, v3, v7
	v_mov_b32_e32 v6, s6
	v_readlane_b32 s6, v251, 22
	ds_read_b128 v[26:29], v6
	s_waitcnt lgkmcnt(2)
	v_add_f32_e32 v2, v2, v14
	v_mov_b32_e32 v6, s6
	v_readlane_b32 s6, v251, 23
	ds_read_b128 v[40:43], v6
	v_add_f32_e32 v3, v3, v11
	v_mov_b32_e32 v6, s6
	ds_read_b128 v[44:47], v6
	s_waitcnt lgkmcnt(3)
	v_add_f32_e32 v2, v2, v22
	v_add_f32_e32 v3, v3, v15
	s_waitcnt lgkmcnt(2)
	v_add_f32_e32 v2, v2, v26
	v_add_f32_e32 v3, v3, v23
	s_waitcnt lgkmcnt(1)
	v_add_f32_e32 v2, v2, v40
	v_add_f32_e32 v3, v3, v27
	s_waitcnt lgkmcnt(0)
	v_add_f32_e32 v2, v2, v44
	v_add_f32_e32 v3, v3, v41
	v_mul_f32_e32 v6, 0x3b000000, v2
	v_add_f32_e32 v3, v3, v45
	v_mul_f32_e32 v6, v6, v6
	v_fma_f32 v3, v3, s8, -v6
	v_max_f32_e32 v3, 0, v3
	v_add_f32_e32 v3, 0x358637bd, v3
	v_rsq_f32_e32 v3, v3
	v_fmac_f32_e32 v32, 0xbb000000, v2
	v_add_f32_e32 v6, 1.0, v31
	v_rcp_f32_e32 v6, v6
	v_mul_f32_e32 v2, v32, v3
	v_fma_f32 v7, v143, v2, v142
	v_mul_f32_e32 v2, 0xbfb8aa3b, v7
	v_exp_f32_e32 v2, v2
	v_addc_co_u32_e32 v19, vcc, 0, v1, vcc
	s_mov_b32 s6, 0x14001000
	v_add_f32_e32 v2, 1.0, v2
	v_rcp_f32_e32 v10, v2
	v_mul_f32_e32 v3, v30, v6
	v_add_co_u32_e32 v2, vcc, s6, v0
	v_cvt_pk_bf16_f32 v6, v3, s0
	s_nop 0
	v_addc_co_u32_e32 v3, vcc, 0, v1, vcc
	global_store_short v[2:3], v6, off offset:3072
	v_mul_f32_e32 v2, v7, v10
	v_cvt_pk_bf16_f32 v6, v2, s0
	v_add_f32_e32 v2, 0, v4
	v_add_f32_e32 v3, 0, v5
	v_add_f32_e32 v2, v2, v8
	v_add_f32_e32 v3, v3, v9
	v_add_f32_e32 v2, v2, v12
	v_add_f32_e32 v3, v3, v13
	v_add_f32_e32 v2, v2, v16
	v_add_f32_e32 v3, v3, v17
	v_add_f32_e32 v2, v2, v24
	v_add_f32_e32 v3, v3, v25
	v_add_f32_e32 v2, v2, v28
	v_add_f32_e32 v3, v3, v29
	v_add_f32_e32 v2, v2, v42
	v_add_f32_e32 v3, v3, v43
	v_add_f32_e32 v4, v2, v46
	v_add_f32_e32 v2, v3, v47
	v_mul_f32_e32 v3, 0x3b000000, v4
	v_mul_f32_e32 v3, v3, v3
	v_fma_f32 v2, v2, s8, -v3
	v_max_f32_e32 v2, 0, v2
	v_add_f32_e32 v2, 0x358637bd, v2
	v_rsq_f32_e32 v5, v2
	v_fmac_f32_e32 v34, 0xbb000000, v4
	global_store_short v[18:19], v21, off offset:3072
	s_mov_b32 s6, 0x14002000
	v_mul_f32_e32 v4, v34, v5
	v_fma_f32 v18, v143, v4, v142
	v_mul_f32_e32 v4, 0xbfb8aa3b, v18
	v_exp_f32_e32 v7, v4
	v_add_co_u32_e32 v2, vcc, s6, v0
	v_readlane_b32 s6, v251, 24
	s_nop 0
	v_addc_co_u32_e32 v3, vcc, 0, v1, vcc
	global_store_short v[2:3], v6, off offset:3072
	v_mov_b32_e32 v2, s29
	v_add_f32_e32 v6, 1.0, v7
	ds_read_b128 v[2:5], v2
	v_rcp_f32_e32 v19, v6
	v_mov_b32_e32 v6, s6
	ds_read_b128 v[6:9], v6
	v_readlane_b32 s6, v251, 25
	s_waitcnt lgkmcnt(0)
	v_add_f32_e32 v2, 0, v2
	v_add_f32_e32 v3, 0, v3
	v_mov_b32_e32 v10, s6
	v_readlane_b32 s6, v251, 26
	ds_read_b128 v[10:13], v10
	v_add_f32_e32 v2, v2, v6
	v_mov_b32_e32 v6, s6
	v_readlane_b32 s6, v251, 27
	ds_read_b128 v[14:17], v6
	s_waitcnt lgkmcnt(0)
	v_add_f32_e32 v2, v2, v10
	v_mov_b32_e32 v6, s6
	v_readlane_b32 s6, v251, 28
	ds_read_b128 v[22:25], v6
	v_add_f32_e32 v3, v3, v7
	v_mov_b32_e32 v6, s6
	v_readlane_b32 s6, v251, 29
	ds_read_b128 v[26:29], v6
	v_add_f32_e32 v2, v2, v14
	v_mov_b32_e32 v6, s6
	v_readlane_b32 s6, v251, 30
	ds_read_b128 v[30:33], v6
	v_add_f32_e32 v3, v3, v11
	v_mov_b32_e32 v6, s6
	ds_read_b128 v[40:43], v6
	s_waitcnt lgkmcnt(0)
	v_add_f32_e32 v2, v2, v22
	v_add_f32_e32 v3, v3, v15
	v_add_f32_e32 v2, v2, v26
	v_add_f32_e32 v3, v3, v23
	v_add_f32_e32 v2, v2, v30
	v_add_f32_e32 v3, v3, v27
	v_add_f32_e32 v2, v2, v40
	v_add_f32_e32 v3, v3, v31
	v_mul_f32_e32 v6, 0x3b000000, v2
	v_add_f32_e32 v3, v3, v41
	v_mul_f32_e32 v6, v6, v6
	v_fma_f32 v3, v3, s8, -v6
	v_max_f32_e32 v3, 0, v3
	v_add_f32_e32 v3, 0x358637bd, v3
	v_rsq_f32_e32 v3, v3
	v_fmac_f32_e32 v36, 0xbb000000, v2
	s_mov_b32 s6, 0x14003000
	v_mul_f32_e32 v6, v18, v19
	v_mul_f32_e32 v2, v36, v3
	v_fma_f32 v7, v143, v2, v142
	v_mul_f32_e32 v2, 0xbfb8aa3b, v7
	v_exp_f32_e32 v10, v2
	v_add_co_u32_e32 v2, vcc, s6, v0
	v_cvt_pk_bf16_f32 v6, v6, s0
	s_nop 0
	v_addc_co_u32_e32 v3, vcc, 0, v1, vcc
	global_store_short v[2:3], v6, off offset:3072
	v_add_f32_e32 v3, 0, v4
	v_add_f32_e32 v3, v3, v8
	v_add_f32_e32 v4, 0, v5
	v_add_f32_e32 v3, v3, v12
	v_add_f32_e32 v4, v4, v9
	v_add_f32_e32 v3, v3, v16
	v_add_f32_e32 v4, v4, v13
	v_add_f32_e32 v3, v3, v24
	v_add_f32_e32 v4, v4, v17
	v_add_f32_e32 v3, v3, v28
	v_add_f32_e32 v4, v4, v25
	v_add_f32_e32 v3, v3, v32
	v_add_f32_e32 v4, v4, v29
	v_add_f32_e32 v3, v3, v42
	v_add_f32_e32 v4, v4, v33
	v_mul_f32_e32 v5, 0x3b000000, v3
	v_add_f32_e32 v4, v4, v43
	v_mul_f32_e32 v5, v5, v5
	v_fma_f32 v4, v4, s8, -v5
	v_add_f32_e32 v2, 1.0, v10
	v_max_f32_e32 v4, 0, v4
	v_rcp_f32_e32 v2, v2
	v_add_f32_e32 v4, 0x358637bd, v4
	v_rsq_f32_e32 v4, v4
	v_fmac_f32_e32 v20, 0xbb000000, v3
	v_mul_f32_e32 v2, v7, v2
	v_cvt_pk_bf16_f32 v5, v2, s0
	v_mul_f32_e32 v2, v20, v4
	v_fma_f32 v6, v143, v2, v142
	v_mul_f32_e32 v2, 0xbfb8aa3b, v6
	v_exp_f32_e32 v4, v2
	s_mov_b32 s6, 0x14004000
	v_add_co_u32_e32 v2, vcc, s6, v0
	v_add_f32_e32 v4, 1.0, v4
	v_rcp_f32_e32 v7, v4
	v_addc_co_u32_e32 v3, vcc, 0, v1, vcc
	global_store_short v[2:3], v5, off offset:3072
	v_mov_b32_e32 v2, s28
	v_mul_f32_e32 v6, v6, v7
	v_readlane_b32 s6, v251, 31
	ds_read_b128 v[2:5], v2
	v_cvt_pk_bf16_f32 v34, v6, s0
	v_mov_b32_e32 v6, s6
	ds_read_b128 v[6:9], v6
	v_readlane_b32 s6, v251, 32
	s_waitcnt lgkmcnt(0)
	v_add_f32_e32 v2, 0, v2
	v_add_f32_e32 v3, 0, v3
	v_mov_b32_e32 v10, s6
	v_readlane_b32 s6, v251, 33
	ds_read_b128 v[10:13], v10
	v_add_f32_e32 v2, v2, v6
	v_mov_b32_e32 v6, s6
	v_readlane_b32 s6, v251, 34
	ds_read_b128 v[14:17], v6
	v_add_f32_e32 v3, v3, v7
	v_mov_b32_e32 v6, s6
	v_readlane_b32 s6, v251, 35
	ds_read_b128 v[18:21], v6
	s_waitcnt lgkmcnt(0)
	v_add_f32_e32 v2, v2, v10
	v_mov_b32_e32 v6, s6
	v_readlane_b32 s6, v251, 36
	ds_read_b128 v[22:25], v6
	v_add_f32_e32 v3, v3, v11
	v_mov_b32_e32 v6, s6
	v_readlane_b32 s6, v251, 37
	ds_read_b128 v[26:29], v6
	v_add_f32_e32 v2, v2, v14
	v_mov_b32_e32 v6, s6
	ds_read_b128 v[30:33], v6
	v_add_f32_e32 v3, v3, v15
	v_add_f32_e32 v2, v2, v18
	v_add_f32_e32 v3, v3, v19
	s_waitcnt lgkmcnt(0)
	v_add_f32_e32 v2, v2, v22
	v_add_f32_e32 v3, v3, v23
	v_add_f32_e32 v2, v2, v26
	v_add_f32_e32 v4, 0, v4
	v_add_f32_e32 v3, v3, v27
	v_add_f32_e32 v6, v2, v30
	v_add_f32_e32 v4, v4, v8
	v_add_f32_e32 v2, v3, v31
	v_mul_f32_e32 v3, 0x3b000000, v6
	v_add_f32_e32 v5, 0, v5
	v_add_f32_e32 v4, v4, v12
	v_mul_f32_e32 v3, v3, v3
	v_add_f32_e32 v5, v5, v9
	v_add_f32_e32 v4, v4, v16
	v_fma_f32 v2, v2, s8, -v3
	v_add_f32_e32 v5, v5, v13
	v_add_f32_e32 v4, v4, v20
	v_max_f32_e32 v2, 0, v2
	v_add_f32_e32 v5, v5, v17
	v_add_f32_e32 v4, v4, v24
	v_add_f32_e32 v2, 0x358637bd, v2
	v_add_f32_e32 v5, v5, v21
	v_add_f32_e32 v4, v4, v28
	v_rsq_f32_e32 v7, v2
	v_add_f32_e32 v5, v5, v25
	v_add_f32_e32 v4, v4, v32
	v_add_f32_e32 v5, v5, v29
	v_mul_f32_e32 v8, 0x3b000000, v4
	v_add_f32_e32 v5, v5, v33
	v_mul_f32_e32 v8, v8, v8
	v_fmac_f32_e32 v38, 0xbb000000, v6
	v_fma_f32 v5, v5, s8, -v8
	v_mul_f32_e32 v6, v38, v7
	v_max_f32_e32 v5, 0, v5
	v_fma_f32 v6, v143, v6, v142
	v_add_f32_e32 v5, 0x358637bd, v5
	v_mul_f32_e32 v7, 0xbfb8aa3b, v6
	v_rsq_f32_e32 v5, v5
	v_exp_f32_e32 v7, v7
	v_fmac_f32_e32 v60, 0xbb000000, v4
	s_mov_b32 s6, 0x14005000
	v_mul_f32_e32 v4, v60, v5
	v_add_f32_e32 v7, 1.0, v7
	v_fmac_f32_e32 v142, v143, v4
	v_rcp_f32_e32 v7, v7
	v_mul_f32_e32 v4, 0xbfb8aa3b, v142
	v_exp_f32_e32 v4, v4
	v_add_co_u32_e32 v2, vcc, s6, v0
	s_mov_b32 s6, 0x14006000
	s_nop 0
	v_addc_co_u32_e32 v3, vcc, 0, v1, vcc
	global_store_short v[2:3], v34, off offset:3072
	v_mul_f32_e32 v2, v6, v7
	v_cvt_pk_bf16_f32 v5, v2, s0
	v_add_f32_e32 v2, 1.0, v4
	v_rcp_f32_e32 v4, v2
	v_add_co_u32_e32 v2, vcc, s6, v0
	s_nop 1
	v_addc_co_u32_e32 v3, vcc, 0, v1, vcc
	global_store_short v[2:3], v5, off offset:3072
	v_mul_f32_e32 v2, v142, v4
	v_add_co_u32_e32 v0, vcc, 0x14007000, v0
	v_cvt_pk_bf16_f32 v2, v2, s0
	s_nop 0
	v_addc_co_u32_e32 v1, vcc, 0, v1, vcc
	global_store_short v[0:1], v2, off offset:3072
	v_mov_b32_e32 v0, 0
	v_mov_b32_e32 v1, 0
	v_mov_b32_e32 v2, 0
	v_mov_b32_e32 v3, 0
	s_waitcnt lgkmcnt(0)
	s_barrier
	s_and_saveexec_b64 s[6:7], s[20:21]
	s_cbranch_execz .LBB0_691
	v_mov_b64_e32 v[0:1], s[18:19]
	v_mad_i64_i32 v[0:1], s[8:9], v93, s76, v[0:1]
	v_lshl_add_u64 v[0:1], v[0:1], 0, v[192:193]
	v_add_co_u32_e32 v0, vcc, 0x18401000, v0
	s_nop 1
	v_addc_co_u32_e32 v1, vcc, 0, v1, vcc
	global_load_dwordx4 v[0:3], v[0:1], off

.LBB0_693:
	s_or_b64 exec, exec, s[6:7]
	s_waitcnt vmcnt(0) lgkmcnt(0)
	v_mov_b32_e32 v0, 0
	v_mov_b32_e32 v1, 0
	v_mov_b32_e32 v2, 0
	v_mov_b32_e32 v3, 0
	s_and_saveexec_b64 s[6:7], s[20:21]
	s_cbranch_execz .LBB0_695
	v_mov_b64_e32 v[0:1], s[18:19]
	v_mad_i64_i32 v[0:1], s[8:9], v93, s76, v[0:1]
	v_lshl_add_u64 v[0:1], v[0:1], 0, v[192:193]
	v_add_co_u32_e32 v0, vcc, 0x18400000, v0
	s_nop 1
	v_addc_co_u32_e32 v1, vcc, 0, v1, vcc
	global_load_dwordx4 v[0:3], v[0:1], off offset:3072

.Lpro_lds:
	s_lshl_b64 s[0:1], s[8:9], 1
	s_add_u32 s0, s4, s0
	s_addc_u32 s1, s5, s1
	v_add_u32_e32 v6, s27, v33
	ds_write_b16 v42, v0 offset:492
	s_waitcnt lgkmcnt(0)
	s_barrier
	v_lshl_add_u64 v[4:5], s[0:1], 0, v[192:193]
	ds_read2_b32 v[0:1], v40 offset1:1
	ds_read2_b32 v[2:3], v40 offset0:2 offset1:3
	v_ashrrev_i32_e32 v9, 31, v6
	v_mad_u64_u32 v[6:7], s[0:1], v6, s26, 0
	v_mov_b32_e32 v8, v7
	v_mad_u64_u32 v[8:9], s[0:1], v9, s26, v[8:9]
	v_mov_b32_e32 v7, v8
	v_lshl_add_u64 v[6:7], v[6:7], 1, v[4:5]
	s_waitcnt lgkmcnt(0)
	global_store_dwordx4 v[6:7], v[0:3], off
	v_add_u32_e32 v6, s27, v39
	ds_read2_b32 v[0:1], v41 offset1:1
	ds_read2_b32 v[2:3], v41 offset0:2 offset1:3
	v_ashrrev_i32_e32 v9, 31, v6
	v_mad_u64_u32 v[6:7], s[0:1], v6, s26, 0
	v_mov_b32_e32 v8, v7
	v_mad_u64_u32 v[8:9], s[0:1], v9, s26, v[8:9]
	v_mov_b32_e32 v7, v8
	v_lshl_add_u64 v[4:5], v[6:7], 1, v[4:5]
	s_waitcnt lgkmcnt(0)
	global_store_dwordx4 v[4:5], v[0:3], off
	s_waitcnt vmcnt(2)
	v_mov_b64_e32 v[12:13], v[20:21]
	v_mov_b64_e32 v[8:9], v[16:17]
	v_mov_b64_e32 v[4:5], v[28:29]
	v_mov_b64_e32 v[0:1], v[24:25]
	s_andn2_b64 vcc, exec, s[10:11]
	v_mov_b64_e32 v[14:15], v[22:23]
	v_mov_b64_e32 v[10:11], v[18:19]
	v_mov_b64_e32 v[6:7], v[30:31]
	v_mov_b64_e32 v[2:3], v[26:27]
	s_mov_b64 s[6:7], s[14:15]
	s_mov_b64 s[4:5], s[12:13]
	s_mov_b32 s26, s49
	s_mov_b32 s8, s23
	s_mov_b32 s27, s22
	s_waitcnt lgkmcnt(0)
	s_barrier
	s_cbranch_vccz .LBB0_842
.LBB0_778:
	v_mov_b32_e32 v46, 1.0
	v_mov_b32_e32 v47, 1.0
	v_mov_b32_e32 v52, 1.0
	v_mov_b32_e32 v53, 1.0
	s_cmp_eq_u64 s[6:7], 0
	s_cbranch_scc1 .Lpro_g_skip
	v_add_u32_e32 v48, s8, v34
	v_ashrrev_i32_e32 v49, 31, v48
	v_lshl_add_u64 v[48:49], v[48:49], 2, s[6:7]
	global_load_dword v46, v[48:49], off
	global_load_dword v47, v[48:49], off offset:64
	global_load_dword v52, v[48:49], off offset:128
	global_load_dword v53, v[48:49], off offset:192

.LBB0_831:
	s_waitcnt vmcnt(4)
	s_branch .Lpro_body

.Lpro_body:
	s_ashr_i32 s9, s8, 31
	v_mul_f32_e32 v12, v12, v46
	v_cvt_pk_bf16_f32 v12, v12, s0
	ds_write_b16 v42, v12
	v_mul_f32_e32 v12, v13, v46
	v_cvt_pk_bf16_f32 v12, v12, s0
	ds_write_b16 v42, v12 offset:132
	v_mul_f32_e32 v12, v14, v46
	v_cvt_pk_bf16_f32 v12, v12, s0
	ds_write_b16 v42, v12 offset:264
	v_mul_f32_e32 v12, v15, v46
	v_cvt_pk_bf16_f32 v12, v12, s0
	ds_write_b16 v42, v12 offset:396
	v_mul_f32_e32 v8, v8, v47
	v_cvt_pk_bf16_f32 v8, v8, s0
	ds_write_b16 v42, v8 offset:32
	v_mul_f32_e32 v8, v9, v47
	v_cvt_pk_bf16_f32 v8, v8, s0
	ds_write_b16 v42, v8 offset:164
	v_mul_f32_e32 v8, v10, v47
	v_cvt_pk_bf16_f32 v8, v8, s0
	ds_write_b16 v42, v8 offset:296
	v_mul_f32_e32 v8, v11, v47
	v_cvt_pk_bf16_f32 v8, v8, s0
	ds_write_b16 v42, v8 offset:428
	v_mul_f32_e32 v4, v4, v52
	v_cvt_pk_bf16_f32 v4, v4, s0
	ds_write_b16 v42, v4 offset:64
	v_mul_f32_e32 v4, v5, v52
	v_cvt_pk_bf16_f32 v4, v4, s0
	ds_write_b16 v42, v4 offset:196
	v_mul_f32_e32 v4, v6, v52
	v_cvt_pk_bf16_f32 v4, v4, s0
	ds_write_b16 v42, v4 offset:328
	v_mul_f32_e32 v4, v7, v52
	v_cvt_pk_bf16_f32 v4, v4, s0
	ds_write_b16 v42, v4 offset:460
	v_mul_f32_e32 v0, v0, v53
	v_cvt_pk_bf16_f32 v0, v0, s0
	ds_write_b16 v42, v0 offset:96
	v_mul_f32_e32 v0, v1, v53
	v_cvt_pk_bf16_f32 v0, v0, s0
	ds_write_b16 v42, v0 offset:228
	v_mul_f32_e32 v0, v2, v53
	v_cvt_pk_bf16_f32 v0, v0, s0
	ds_write_b16 v42, v0 offset:360
	v_mul_f32_e32 v0, v3, v53
	v_cvt_pk_bf16_f32 v0, v0, s0
	s_branch .Lpro_lds

.LBB0_865:
	v_lshl_add_u64 v[4:5], v[2:3], 0, s[12:13]
	global_load_dword v12, v[4:5], off
	ds_read_b128 v[28:31], v26
	ds_read_b128 v[34:37], v26 offset:16
	s_mov_b32 s14, 0xf000
	s_add_u32 s12, s12, 0x10000
	s_addc_u32 s13, s13, 0
	s_cmp_eq_u32 s12, 0x80000
	s_waitcnt vmcnt(0) lgkmcnt(1)
	v_pk_fma_f32 v[14:15], v[12:13], v[28:29], v[14:15] op_sel_hi:[0,1,1]
	v_pk_fma_f32 v[28:29], v[12:13], v[30:31], v[8:9] op_sel_hi:[0,1,1]
	s_waitcnt lgkmcnt(0)
	v_pk_fma_f32 v[30:31], v[12:13], v[34:35], v[10:11] op_sel_hi:[0,1,1]
	v_pk_fma_f32 v[34:35], v[12:13], v[36:37], v[6:7] op_sel_hi:[0,1,1]
	v_add_co_u32_e32 v36, vcc, s73, v4
	s_nop 1
	v_addc_co_u32_e32 v37, vcc, 0, v5, vcc
	global_load_dword v40, v[36:37], off offset:-4096
	ds_read_b128 v[6:9], v26 offset:528
	ds_read_b128 v[10:13], v26 offset:544
	global_load_dword v36, v[36:37], off
	s_waitcnt vmcnt(1) lgkmcnt(1)
	v_pk_fma_f32 v[14:15], v[40:41], v[6:7], v[14:15] op_sel_hi:[0,1,1]
	v_pk_fma_f32 v[28:29], v[40:41], v[8:9], v[28:29] op_sel_hi:[0,1,1]
	s_waitcnt lgkmcnt(0)
	v_pk_fma_f32 v[30:31], v[40:41], v[10:11], v[30:31] op_sel_hi:[0,1,1]
	v_pk_fma_f32 v[34:35], v[40:41], v[12:13], v[34:35] op_sel_hi:[0,1,1]
	ds_read_b128 v[6:9], v26 offset:1056
	ds_read_b128 v[10:13], v26 offset:1072
	s_waitcnt vmcnt(0) lgkmcnt(1)
	v_pk_fma_f32 v[14:15], v[36:37], v[6:7], v[14:15] op_sel_hi:[0,1,1]
	v_pk_fma_f32 v[28:29], v[36:37], v[8:9], v[28:29] op_sel_hi:[0,1,1]
	s_waitcnt lgkmcnt(0)
	v_pk_fma_f32 v[30:31], v[36:37], v[10:11], v[30:31] op_sel_hi:[0,1,1]
	v_pk_fma_f32 v[34:35], v[36:37], v[12:13], v[34:35] op_sel_hi:[0,1,1]
	v_add_co_u32_e32 v36, vcc, s72, v4
	s_nop 1
	v_addc_co_u32_e32 v37, vcc, 0, v5, vcc
	global_load_dword v40, v[36:37], off offset:-4096
	ds_read_b128 v[6:9], v26 offset:1584
	ds_read_b128 v[10:13], v26 offset:1600
	global_load_dword v36, v[36:37], off
	s_waitcnt vmcnt(1) lgkmcnt(1)
	v_pk_fma_f32 v[14:15], v[40:41], v[6:7], v[14:15] op_sel_hi:[0,1,1]
	v_pk_fma_f32 v[28:29], v[40:41], v[8:9], v[28:29] op_sel_hi:[0,1,1]
	s_waitcnt lgkmcnt(0)
	v_pk_fma_f32 v[30:31], v[40:41], v[10:11], v[30:31] op_sel_hi:[0,1,1]
	v_pk_fma_f32 v[34:35], v[40:41], v[12:13], v[34:35] op_sel_hi:[0,1,1]
	ds_read_b128 v[6:9], v26 offset:2112
	ds_read_b128 v[10:13], v26 offset:2128
	s_waitcnt vmcnt(0) lgkmcnt(1)
	v_pk_fma_f32 v[14:15], v[36:37], v[6:7], v[14:15] op_sel_hi:[0,1,1]
	v_pk_fma_f32 v[28:29], v[36:37], v[8:9], v[28:29] op_sel_hi:[0,1,1]
	s_waitcnt lgkmcnt(0)
	v_pk_fma_f32 v[30:31], v[36:37], v[10:11], v[30:31] op_sel_hi:[0,1,1]
	v_pk_fma_f32 v[34:35], v[36:37], v[12:13], v[34:35] op_sel_hi:[0,1,1]
	v_add_co_u32_e32 v36, vcc, s74, v4
	s_nop 1
	v_addc_co_u32_e32 v37, vcc, 0, v5, vcc
	global_load_dword v40, v[36:37], off offset:-4096
	ds_read_b128 v[6:9], v26 offset:2640
	ds_read_b128 v[10:13], v26 offset:2656
	global_load_dword v36, v[36:37], off
	s_waitcnt vmcnt(1) lgkmcnt(1)
	v_pk_fma_f32 v[14:15], v[40:41], v[6:7], v[14:15] op_sel_hi:[0,1,1]
	v_pk_fma_f32 v[28:29], v[40:41], v[8:9], v[28:29] op_sel_hi:[0,1,1]
	s_waitcnt lgkmcnt(0)
	v_pk_fma_f32 v[30:31], v[40:41], v[10:11], v[30:31] op_sel_hi:[0,1,1]
	v_pk_fma_f32 v[34:35], v[40:41], v[12:13], v[34:35] op_sel_hi:[0,1,1]
	ds_read_b128 v[6:9], v26 offset:3168
	ds_read_b128 v[10:13], v26 offset:3184
	s_waitcnt vmcnt(0) lgkmcnt(1)
	v_pk_fma_f32 v[14:15], v[36:37], v[6:7], v[14:15] op_sel_hi:[0,1,1]
	v_pk_fma_f32 v[28:29], v[36:37], v[8:9], v[28:29] op_sel_hi:[0,1,1]
	s_waitcnt lgkmcnt(0)
	v_pk_fma_f32 v[30:31], v[36:37], v[10:11], v[30:31] op_sel_hi:[0,1,1]
	v_pk_fma_f32 v[34:35], v[36:37], v[12:13], v[34:35] op_sel_hi:[0,1,1]
	v_add_co_u32_e32 v36, vcc, s77, v4
	s_nop 1
	v_addc_co_u32_e32 v37, vcc, 0, v5, vcc
	global_load_dword v40, v[36:37], off offset:-4096
	ds_read_b128 v[6:9], v26 offset:3696
	ds_read_b128 v[10:13], v26 offset:3712
	global_load_dword v36, v[36:37], off
	s_waitcnt vmcnt(1) lgkmcnt(1)
	v_pk_fma_f32 v[14:15], v[40:41], v[6:7], v[14:15] op_sel_hi:[0,1,1]
	v_pk_fma_f32 v[28:29], v[40:41], v[8:9], v[28:29] op_sel_hi:[0,1,1]
	s_waitcnt lgkmcnt(0)
	v_pk_fma_f32 v[30:31], v[40:41], v[10:11], v[30:31] op_sel_hi:[0,1,1]
	v_pk_fma_f32 v[34:35], v[40:41], v[12:13], v[34:35] op_sel_hi:[0,1,1]
	ds_read_b128 v[6:9], v26 offset:4224
	ds_read_b128 v[10:13], v26 offset:4240
	s_waitcnt vmcnt(0) lgkmcnt(1)
	v_pk_fma_f32 v[14:15], v[36:37], v[6:7], v[14:15] op_sel_hi:[0,1,1]
	v_pk_fma_f32 v[28:29], v[36:37], v[8:9], v[28:29] op_sel_hi:[0,1,1]
	s_waitcnt lgkmcnt(0)
	v_pk_fma_f32 v[30:31], v[36:37], v[10:11], v[30:31] op_sel_hi:[0,1,1]
	v_pk_fma_f32 v[34:35], v[36:37], v[12:13], v[34:35] op_sel_hi:[0,1,1]
	v_add_co_u32_e32 v36, vcc, s79, v4
	s_nop 1
	v_addc_co_u32_e32 v37, vcc, 0, v5, vcc
	global_load_dword v40, v[36:37], off offset:-4096
	ds_read_b128 v[6:9], v26 offset:4752
	ds_read_b128 v[10:13], v26 offset:4768
	global_load_dword v36, v[36:37], off
	s_waitcnt vmcnt(1) lgkmcnt(1)
	v_pk_fma_f32 v[14:15], v[40:41], v[6:7], v[14:15] op_sel_hi:[0,1,1]
	v_pk_fma_f32 v[28:29], v[40:41], v[8:9], v[28:29] op_sel_hi:[0,1,1]
	s_waitcnt lgkmcnt(0)
	v_pk_fma_f32 v[30:31], v[40:41], v[10:11], v[30:31] op_sel_hi:[0,1,1]
	v_pk_fma_f32 v[34:35], v[40:41], v[12:13], v[34:35] op_sel_hi:[0,1,1]
	ds_read_b128 v[6:9], v26 offset:5280
	ds_read_b128 v[10:13], v26 offset:5296
	s_waitcnt vmcnt(0) lgkmcnt(1)
	v_pk_fma_f32 v[14:15], v[36:37], v[6:7], v[14:15] op_sel_hi:[0,1,1]
	v_pk_fma_f32 v[28:29], v[36:37], v[8:9], v[28:29] op_sel_hi:[0,1,1]
	s_waitcnt lgkmcnt(0)
	v_pk_fma_f32 v[30:31], v[36:37], v[10:11], v[30:31] op_sel_hi:[0,1,1]
	v_pk_fma_f32 v[34:35], v[36:37], v[12:13], v[34:35] op_sel_hi:[0,1,1]
	v_add_co_u32_e32 v36, vcc, s81, v4
	s_nop 1
	v_addc_co_u32_e32 v37, vcc, 0, v5, vcc
	global_load_dword v40, v[36:37], off offset:-4096
	ds_read_b128 v[6:9], v26 offset:5808
	ds_read_b128 v[10:13], v26 offset:5824
	global_load_dword v36, v[36:37], off
	s_waitcnt vmcnt(1) lgkmcnt(1)
	v_pk_fma_f32 v[14:15], v[40:41], v[6:7], v[14:15] op_sel_hi:[0,1,1]
	v_pk_fma_f32 v[28:29], v[40:41], v[8:9], v[28:29] op_sel_hi:[0,1,1]
	s_waitcnt lgkmcnt(0)
	v_pk_fma_f32 v[30:31], v[40:41], v[10:11], v[30:31] op_sel_hi:[0,1,1]
	v_pk_fma_f32 v[34:35], v[40:41], v[12:13], v[34:35] op_sel_hi:[0,1,1]
	ds_read_b128 v[6:9], v26 offset:6336
	ds_read_b128 v[10:13], v26 offset:6352
	s_waitcnt vmcnt(0) lgkmcnt(1)
	v_pk_fma_f32 v[14:15], v[36:37], v[6:7], v[14:15] op_sel_hi:[0,1,1]
	v_pk_fma_f32 v[28:29], v[36:37], v[8:9], v[28:29] op_sel_hi:[0,1,1]
	s_waitcnt lgkmcnt(0)
	v_pk_fma_f32 v[30:31], v[36:37], v[10:11], v[30:31] op_sel_hi:[0,1,1]
	v_pk_fma_f32 v[34:35], v[36:37], v[12:13], v[34:35] op_sel_hi:[0,1,1]
	v_add_co_u32_e32 v36, vcc, s16, v4
	s_nop 1
	v_addc_co_u32_e32 v37, vcc, 0, v5, vcc
	global_load_dword v40, v[36:37], off offset:-4096
	ds_read_b128 v[6:9], v26 offset:6864
	ds_read_b128 v[10:13], v26 offset:6880
	global_load_dword v36, v[36:37], off
	v_add_co_u32_e32 v4, vcc, s14, v4
	s_waitcnt vmcnt(1) lgkmcnt(1)
	v_pk_fma_f32 v[14:15], v[40:41], v[6:7], v[14:15] op_sel_hi:[0,1,1]
	v_addc_co_u32_e32 v5, vcc, 0, v5, vcc
	v_pk_fma_f32 v[28:29], v[40:41], v[8:9], v[28:29] op_sel_hi:[0,1,1]
	s_waitcnt lgkmcnt(0)
	v_pk_fma_f32 v[30:31], v[40:41], v[10:11], v[30:31] op_sel_hi:[0,1,1]
	v_pk_fma_f32 v[34:35], v[40:41], v[12:13], v[34:35] op_sel_hi:[0,1,1]
	ds_read_b128 v[6:9], v26 offset:7392
	ds_read_b128 v[10:13], v26 offset:7408
	global_load_dword v4, v[4:5], off
	s_waitcnt vmcnt(1) lgkmcnt(1)
	v_pk_fma_f32 v[6:7], v[36:37], v[6:7], v[14:15] op_sel_hi:[0,1,1]
	v_pk_fma_f32 v[8:9], v[36:37], v[8:9], v[28:29] op_sel_hi:[0,1,1]
	s_waitcnt lgkmcnt(0)
	v_pk_fma_f32 v[10:11], v[36:37], v[10:11], v[30:31] op_sel_hi:[0,1,1]
	v_pk_fma_f32 v[12:13], v[36:37], v[12:13], v[34:35] op_sel_hi:[0,1,1]
	ds_read_b128 v[28:31], v26 offset:7920
	ds_read_b128 v[34:37], v26 offset:7936
	v_add_u32_e32 v26, 0x2100, v26
	s_waitcnt vmcnt(0) lgkmcnt(1)
	v_pk_fma_f32 v[14:15], v[4:5], v[28:29], v[6:7] op_sel_hi:[0,1,1]
	v_pk_fma_f32 v[8:9], v[4:5], v[30:31], v[8:9] op_sel_hi:[0,1,1]
	s_waitcnt lgkmcnt(0)
	v_pk_fma_f32 v[10:11], v[4:5], v[34:35], v[10:11] op_sel_hi:[0,1,1]
	v_pk_fma_f32 v[6:7], v[4:5], v[36:37], v[12:13] op_sel_hi:[0,1,1]
	s_cbranch_scc0 .LBB0_865
	s_lshl_b32 s12, s33, 5
	s_and_b32 s12, s12, 0x3e0
	v_or_b32_e32 v2, s12, v38
	s_lshl_b64 s[12:13], s[18:19], 22
	s_add_u32 s12, s34, s12
	s_addc_u32 s13, s35, s13
	v_lshlrev_b32_e32 v192, 12, v2
	v_lshl_add_u64 v[2:3], s[12:13], 0, v[192:193]
	s_lshl_b32 s82, s37, 1
	v_readlane_b32 s12, v250, 21
	v_lshl_add_u64 v[2:3], v[2:3], 0, s[82:83]
	s_add_i32 s33, s33, s70
	s_add_i32 s36, s36, s12
	v_lshl_add_u64 v[12:13], v[0:1], 1, v[2:3]
	v_cvt_pk_bf16_f32 v2, v14, v15
	v_cvt_pk_bf16_f32 v3, v8, v9
	v_cvt_pk_bf16_f32 v4, v10, v11
	v_cvt_pk_bf16_f32 v5, v6, v7
	s_cmpk_gt_i32 s33, 0xff
	global_store_dwordx4 v[12:13], v[2:5], off
	s_cbranch_scc0 .LBB0_846
	v_readlane_b32 s36, v253, 8
	v_readlane_b32 s42, v253, 14
	v_readlane_b32 s43, v253, 15
	v_readlane_b32 s37, v253, 9
	v_readlane_b32 s38, v253, 10
	v_readlane_b32 s39, v253, 11
	v_readlane_b32 s40, v253, 12
	v_readlane_b32 s41, v253, 13
	s_branch .LBB0_721

.LBB0_870:
	s_or_b64 exec, exec, s[6:7]
	v_readlane_b32 s6, v250, 22
	v_readlane_b32 s7, v250, 23
	v_add_u32_e32 v0, s86, v0
	global_store_short v[4:5], v1, off
	v_lshl_add_u64 v[2:3], v[2:3], 0, s[6:7]
	s_mov_b32 s6, 0x1ffff
	v_cmp_lt_i32_e32 vcc, s6, v0
	v_readlane_b32 s6, v250, 24
	v_readlane_b32 s7, v250, 25
	s_or_b64 s[4:5], vcc, s[4:5]
	s_nop 0
	v_lshl_add_u64 v[4:5], v[4:5], 0, s[6:7]
	s_andn2_b64 exec, exec, s[4:5]
	s_cbranch_execz .LBB0_873

.LBB0_882:
	s_waitcnt lgkmcnt(0)
	global_load_dwordx4 v[28:31], v27, s[14:15]
	global_load_dwordx4 v[32:35], v27, s[14:15] offset:1024
	global_load_dwordx4 v[36:39], v27, s[14:15] offset:2048
	global_load_dwordx4 v[40:43], v27, s[14:15] offset:3072
	global_load_dwordx4 v[12:15], v27, s[16:17]
	global_load_dwordx4 v[8:11], v27, s[16:17] offset:1024
	global_load_dwordx4 v[4:7], v27, s[16:17] offset:2048
	global_load_dwordx4 v[0:3], v27, s[16:17] offset:3072
	s_lshl_b64 s[14:15], s[10:11], 11
	s_waitcnt vmcnt(0)
	v_mul_f32_e32 v44, v29, v29
	v_mul_f32_e32 v45, v31, v31
	v_mul_f32_e32 v46, v33, v33
	v_mul_f32_e32 v47, v35, v35
	v_mul_f32_e32 v48, v37, v37
	v_mul_f32_e32 v49, v39, v39
	v_fmac_f32_e32 v45, v30, v30
	v_fmac_f32_e32 v46, v32, v32
	v_fmac_f32_e32 v47, v34, v34
	v_fmac_f32_e32 v44, v28, v28
	v_mul_f32_e32 v50, v41, v41
	v_mul_f32_e32 v51, v43, v43
	v_fmac_f32_e32 v48, v36, v36
	v_fmac_f32_e32 v49, v38, v38
	v_add_f32_e32 v46, v46, v47
	v_add_f32_e32 v44, v44, v45
	v_fmac_f32_e32 v50, v40, v40
	v_fmac_f32_e32 v51, v42, v42
	v_add_f32_e32 v47, v48, v49
	v_add_f32_e32 v44, v44, v46
	v_add_f32_e32 v48, v50, v51
	v_add_f32_e32 v44, v44, v47
	v_add_f32_e32 v44, v44, v48
	ds_bpermute_b32 v45, v17, v44
	v_cvt_pk_bf16_f32 v28, v28, v29
	v_cvt_pk_bf16_f32 v29, v30, v31
	v_cvt_pk_bf16_f32 v30, v36, v37
	v_cvt_pk_bf16_f32 v31, v38, v39
	s_waitcnt lgkmcnt(0)
	v_add_f32_e32 v44, v44, v45
	ds_bpermute_b32 v45, v22, v44
	s_waitcnt lgkmcnt(0)
	v_add_f32_e32 v46, v44, v45
	ds_bpermute_b32 v47, v23, v46
	v_lshl_add_u64 v[44:45], v[18:19], 0, s[14:15]
	global_store_dwordx2 v[44:45], v[28:29], off
	v_cvt_pk_bf16_f32 v28, v32, v33
	v_cvt_pk_bf16_f32 v29, v34, v35
	s_waitcnt lgkmcnt(0)
	v_add_f32_e32 v46, v46, v47
	ds_bpermute_b32 v47, v24, v46
	global_store_dwordx2 v[44:45], v[28:29], off offset:512
	global_store_dwordx2 v[44:45], v[30:31], off offset:1024
	v_cvt_pk_bf16_f32 v30, v40, v41
	v_cvt_pk_bf16_f32 v31, v42, v43
	s_waitcnt lgkmcnt(0)
	v_add_f32_e32 v32, v46, v47
	ds_bpermute_b32 v33, v25, v32
	global_store_dwordx2 v[44:45], v[30:31], off offset:1536
	s_waitcnt lgkmcnt(0)
	v_add_f32_e32 v28, v32, v33
	ds_bpermute_b32 v29, v26, v28
	s_and_saveexec_b64 s[14:15], s[4:5]
	s_cbranch_execz .LBB0_884
	s_waitcnt lgkmcnt(0)
	v_add_f32_e32 v28, v28, v29
	s_lshl_b64 s[10:11], s[10:11], 6
	v_cndmask_b32_e64 v30, 0, v28, s[0:1]
	v_lshl_add_u64 v[28:29], v[20:21], 0, s[10:11]
	global_store_dword v[28:29], v30, off
	s_or_b64 exec, exec, s[14:15]
	s_andn2_b64 vcc, exec, s[12:13]
	s_cbranch_vccnz .LBB0_876
	s_branch .LBB0_885

.LBB0_885:
	v_mul_f32_e32 v30, v9, v9
	v_mul_f32_e32 v31, v11, v11
	v_fmac_f32_e32 v30, v8, v8
	v_fmac_f32_e32 v31, v10, v10
	v_mul_f32_e32 v28, v13, v13
	s_waitcnt lgkmcnt(0)
	v_mul_f32_e32 v29, v15, v15
	v_add_f32_e32 v30, v30, v31
	v_mul_f32_e32 v31, v5, v5
	v_mul_f32_e32 v32, v7, v7
	v_fmac_f32_e32 v29, v14, v14
	v_fmac_f32_e32 v31, v4, v4
	v_fmac_f32_e32 v32, v6, v6
	v_fmac_f32_e32 v28, v12, v12
	v_add_f32_e32 v31, v31, v32
	v_mul_f32_e32 v32, v1, v1
	v_mul_f32_e32 v33, v3, v3
	v_add_f32_e32 v28, v28, v29
	v_fmac_f32_e32 v32, v0, v0
	v_fmac_f32_e32 v33, v2, v2
	v_add_f32_e32 v28, v28, v30
	v_add_f32_e32 v32, v32, v33
	v_add_f32_e32 v28, v28, v31
	v_add_f32_e32 v28, v28, v32
	ds_bpermute_b32 v29, v17, v28
	s_ashr_i32 s9, s8, 31
	s_lshl_b64 s[10:11], s[8:9], 11
	v_cvt_pk_bf16_f32 v12, v12, v13
	v_cvt_pk_bf16_f32 v13, v14, v15
	s_waitcnt lgkmcnt(0)
	v_add_f32_e32 v28, v28, v29
	ds_bpermute_b32 v29, v22, v28
	v_cvt_pk_bf16_f32 v8, v8, v9
	v_cvt_pk_bf16_f32 v9, v10, v11
	v_cvt_pk_bf16_f32 v0, v0, v1
	v_cvt_pk_bf16_f32 v1, v2, v3
	s_waitcnt lgkmcnt(0)
	v_add_f32_e32 v30, v28, v29
	ds_bpermute_b32 v31, v23, v30
	v_lshl_add_u64 v[28:29], v[18:19], 0, s[10:11]
	global_store_dwordx2 v[28:29], v[12:13], off
	global_store_dwordx2 v[28:29], v[8:9], off offset:512
	v_cvt_pk_bf16_f32 v8, v4, v5
	s_waitcnt lgkmcnt(0)
	v_add_f32_e32 v30, v30, v31
	ds_bpermute_b32 v31, v24, v30
	v_cvt_pk_bf16_f32 v9, v6, v7
	global_store_dwordx2 v[28:29], v[8:9], off offset:1024
	global_store_dwordx2 v[28:29], v[0:1], off offset:1536
	s_waitcnt lgkmcnt(0)
	v_add_f32_e32 v12, v30, v31
	ds_bpermute_b32 v13, v25, v12
	s_waitcnt lgkmcnt(0)
	v_add_f32_e32 v4, v12, v13
	ds_bpermute_b32 v5, v26, v4
	s_and_saveexec_b64 s[10:11], s[4:5]
	s_cbranch_execz .LBB0_875
	s_waitcnt lgkmcnt(0)
	v_add_f32_e32 v0, v4, v5
	s_lshl_b64 s[12:13], s[8:9], 6
	v_cndmask_b32_e64 v2, 0, v0, s[0:1]
	v_lshl_add_u64 v[0:1], v[20:21], 0, s[12:13]
	global_store_dword v[0:1], v2, off
	s_branch .LBB0_875

.LBB0_890:
	s_waitcnt lgkmcnt(0)
	global_load_dwordx4 v[10:13], v[2:3], off offset:-3072
	global_load_dwordx4 v[14:17], v[2:3], off offset:-2048
	global_load_dwordx4 v[18:21], v[2:3], off offset:-1024
	global_load_dwordx4 v[22:25], v[2:3], off
	s_mov_b32 s0, 0x6000000
	s_waitcnt vmcnt(0)
	v_mul_f32_e32 v26, v11, v11
	v_mul_f32_e32 v27, v13, v13
	v_mul_f32_e32 v28, v15, v15
	v_mul_f32_e32 v29, v17, v17
	v_mul_f32_e32 v30, v19, v19
	v_mul_f32_e32 v31, v21, v21
	v_fmac_f32_e32 v27, v12, v12
	v_fmac_f32_e32 v28, v14, v14
	v_fmac_f32_e32 v29, v16, v16
	v_fmac_f32_e32 v26, v10, v10
	v_mul_f32_e32 v32, v23, v23
	v_mul_f32_e32 v33, v25, v25
	v_fmac_f32_e32 v30, v18, v18
	v_fmac_f32_e32 v31, v20, v20
	v_add_f32_e32 v28, v28, v29
	v_add_f32_e32 v26, v26, v27
	v_fmac_f32_e32 v32, v22, v22
	v_fmac_f32_e32 v33, v24, v24
	v_add_f32_e32 v29, v30, v31
	v_add_f32_e32 v26, v26, v28
	v_add_f32_e32 v30, v32, v33
	v_add_f32_e32 v26, v26, v29
	v_add_f32_e32 v26, v26, v30
	ds_bpermute_b32 v27, v4, v26
	v_cvt_pk_bf16_f32 v10, v10, v11
	v_cvt_pk_bf16_f32 v11, v12, v13
	s_waitcnt lgkmcnt(0)
	v_add_f32_e32 v26, v26, v27
	ds_bpermute_b32 v27, v5, v26
	s_waitcnt lgkmcnt(0)
	v_add_f32_e32 v28, v26, v27
	ds_bpermute_b32 v29, v6, v28
	v_lshl_add_u64 v[26:27], s[2:3], 0, v[0:1]
	v_add_co_u32_e64 v12, s[0:1], s0, v26
	s_waitcnt lgkmcnt(0)
	v_add_f32_e32 v28, v28, v29
	ds_bpermute_b32 v29, v7, v28
	v_addc_co_u32_e64 v13, s[0:1], 0, v27, s[0:1]
	global_store_dwordx2 v[12:13], v[10:11], off
	v_cvt_pk_bf16_f32 v10, v14, v15
	s_waitcnt lgkmcnt(0)
	v_add_f32_e32 v26, v28, v29
	ds_bpermute_b32 v27, v8, v26
	v_cvt_pk_bf16_f32 v11, v16, v17
	global_store_dwordx2 v[12:13], v[10:11], off offset:512
	v_cvt_pk_bf16_f32 v14, v18, v19
	v_cvt_pk_bf16_f32 v15, v20, v21
	s_waitcnt lgkmcnt(0)
	v_add_f32_e32 v10, v26, v27
	ds_bpermute_b32 v11, v9, v10
	global_store_dwordx2 v[12:13], v[14:15], off offset:1024
	v_cvt_pk_bf16_f32 v14, v22, v23
	v_cvt_pk_bf16_f32 v15, v24, v25
	global_store_dwordx2 v[12:13], v[14:15], off offset:1536
	s_and_saveexec_b64 s[0:1], vcc
	s_cbranch_execz .LBB0_889
	s_add_u32 s8, s2, s4
	s_addc_u32 s9, s3, s5
	s_waitcnt lgkmcnt(0)
	v_add_f32_e32 v12, v10, v11
	v_mov_b64_e32 v[10:11], s[8:9]
	global_store_dword v[10:11], v12, off
	s_branch .LBB0_889

.LBB0_927:
	s_abs_i32 s1, s28
	s_mul_hi_u32 s14, s1, s62
	v_mov_b32_e32 v33, v214
	s_mul_i32 s15, s14, s74
	s_sub_i32 s1, s1, s15
	v_readfirstlane_b32 s44, v33
	s_bfe_u32 s45, s44, 0x20006
	s_ashr_i32 s50, s44, 8
	s_ashr_i32 s0, s28, 31
	s_add_i32 s15, s14, 1
	s_sub_i32 s20, s1, s74
	s_cmp_ge_u32 s1, s74
	s_cselect_b32 s14, s15, s14
	s_cselect_b32 s1, s20, s1
	s_add_i32 s15, s14, 1
	s_cmp_ge_u32 s1, s74
	s_cselect_b32 s1, s15, s14
	s_xor_b32 s1, s1, s0
	s_sub_i32 s0, s1, s0
	s_mul_i32 s1, s0, s74
	s_lshl_b32 s0, s0, 6
	v_ashrrev_i32_e32 v34, 5, v33
	s_lshl_b32 s51, s45, 4
	v_add_u32_e32 v0, s0, v34
	s_sub_i32 s14, s28, s1
	s_or_b32 s15, s0, s51
	v_ashrrev_i32_e32 v3, 31, v0
	v_mad_u64_u32 v[0:1], s[0:1], v0, s71, 0
	v_mov_b32_e32 v2, v1
	v_mad_u64_u32 v[2:3], s[0:1], v3, s71, v[2:3]
	v_mov_b32_e32 v1, v2
	v_lshlrev_b32_e32 v2, 3, v33
	v_and_b32_e32 v32, 0xf8, v2
	v_lshl_add_u64 v[0:1], v[0:1], 1, s[6:7]
	v_lshlrev_b32_e32 v192, 1, v32
	s_lshl_b32 s0, s14, 6
	v_lshl_add_u64 v[68:69], v[0:1], 0, v[192:193]
	v_add_u32_e32 v0, s0, v34
	v_ashrrev_i32_e32 v3, 31, v0
	v_mad_u64_u32 v[0:1], s[20:21], v0, s71, 0
	v_mov_b32_e32 v2, v1
	v_readlane_b32 s52, v253, 8
	v_mad_u64_u32 v[2:3], s[20:21], v3, s71, v[2:3]
	v_readlane_b32 s58, v253, 14
	v_readlane_b32 s59, v253, 15
	v_mov_b32_e32 v1, v2
	s_mov_b64 s[30:31], s[58:59]
	v_lshl_add_u64 v[0:1], v[0:1], 1, s[10:11]
	v_lshl_add_u64 v[70:71], v[0:1], 0, v[192:193]
	global_load_dwordx4 v[0:3], v[68:69], off
	global_load_dwordx4 v[4:7], v[70:71], off
	s_lshl_b32 s20, s60, 1
	s_mov_b32 s21, s83
	v_lshl_add_u64 v[8:9], v[68:69], 0, s[20:21]
	global_load_dwordx4 v[8:11], v[8:9], off
	v_lshl_add_u64 v[12:13], v[70:71], 0, s[20:21]
	s_lshl_b32 s40, s61, 1
	s_mov_b32 s41, s83
	global_load_dwordx4 v[12:15], v[12:13], off
	v_lshl_add_u64 v[16:17], v[68:69], 0, s[40:41]
	global_load_dwordx4 v[16:19], v[16:17], off
	v_lshl_add_u64 v[20:21], v[70:71], 0, s[40:41]
	global_load_dwordx4 v[20:23], v[20:21], off
	v_lshl_add_u64 v[24:25], v[68:69], 0, s[36:37]
	global_load_dwordx4 v[24:27], v[24:25], off
	v_lshl_add_u64 v[28:29], v[70:71], 0, s[36:37]
	global_load_dwordx4 v[28:31], v[28:29], off
	v_readlane_b32 s53, v253, 9
	s_movk_i32 s1, 0x108
	v_and_b32_e32 v74, 15, v33
	v_and_b32_e32 v51, 63, v33
	v_bfe_u32 v35, v33, 4, 2
	v_mad_u64_u32 v[32:33], s[52:53], v34, s1, v[32:33]
	v_lshl_add_u32 v75, v32, 1, 0
	s_waitcnt lgkmcnt(0)
	s_barrier
	s_add_i32 s1, s15, 0x4000
	v_or_b32_e32 v48, s1, v74
	s_ashr_i32 s1, s0, 31
	v_lshlrev_b32_e32 v192, 3, v35
	v_mov_b32_e32 v52, 0
	v_mul_u32_u24_e32 v76, 0x210, v74
	v_ashrrev_i32_e32 v49, 31, v48
	v_lshlrev_b32_e32 v50, 2, v35
	s_movk_i32 s82, 0x100
	v_mov_b32_e32 v53, v52
	v_mov_b32_e32 v54, v52
	v_mov_b32_e32 v55, v52
	v_mov_b32_e32 v56, v52
	v_mov_b32_e32 v57, v52
	v_mov_b32_e32 v58, v52
	v_mov_b32_e32 v59, v52
	v_mov_b32_e32 v60, v52
	v_mov_b32_e32 v61, v52
	v_mov_b32_e32 v62, v52
	v_mov_b32_e32 v63, v52
	v_mov_b32_e32 v64, v52
	v_mov_b32_e32 v65, v52
	v_mov_b32_e32 v66, v52
	s_waitcnt vmcnt(0)
	ds_write_b128 v75, v[0:3]
	ds_write_b128 v75, v[4:7] offset:33792
	ds_write_b128 v75, v[8:11] offset:8448
	ds_write_b128 v75, v[12:15] offset:42240
	ds_write_b128 v75, v[16:19] offset:16896
	ds_write_b128 v75, v[20:23] offset:50688
	ds_write_b128 v75, v[24:27] offset:25344
	ds_write_b128 v75, v[28:31] offset:59136
	v_or_b32_e32 v0, s51, v74
	v_mul_u32_u24_e32 v77, 0x210, v0
	v_mov_b64_e32 v[0:1], s[30:31]
	v_mad_i64_i32 v[0:1], s[52:53], v48, s76, v[0:1]
	v_lshl_add_u64 v[0:1], s[0:1], 1, v[0:1]
	s_lshl_b32 s51, s50, 7
	v_lshl_add_u64 v[0:1], v[0:1], 0, v[192:193]
	s_mov_b64 s[52:53], 0x18401800
	s_mov_b32 s1, 2
	v_lshl_add_u64 v[72:73], v[0:1], 0, s[52:53]
	s_mov_b32 s52, 0
	s_lshl_b32 s51, s51, 1
	s_mov_b32 s53, 0
	v_mov_b32_e32 v67, v52
	v_mov_b32_e32 v44, v52
	v_mov_b32_e32 v45, v52
	v_mov_b32_e32 v46, v52
	v_mov_b32_e32 v47, v52
	v_mov_b32_e32 v40, v52
	v_mov_b32_e32 v41, v52
	v_mov_b32_e32 v42, v52
	v_mov_b32_e32 v43, v52
	v_mov_b32_e32 v36, v52
	v_mov_b32_e32 v37, v52
	v_mov_b32_e32 v38, v52
	v_mov_b32_e32 v39, v52
	v_mov_b32_e32 v32, v52
	v_mov_b32_e32 v33, v52
	v_mov_b32_e32 v34, v52
	v_mov_b32_e32 v35, v52
	v_readlane_b32 s54, v253, 10
	v_readlane_b32 s55, v253, 11
	v_readlane_b32 s56, v253, 12
	v_readlane_b32 s57, v253, 13
	s_waitcnt lgkmcnt(0)
	s_barrier
	s_branch .LBB0_929
.LBB0_929:
	s_mov_b64 s[54:55], 0x200
	v_lshlrev_b32_e32 v78, 1, v192
	v_add_u32_e32 v79, 0x10800, v75
	s_mov_b32 s53, 0
	s_add_i32 s56, s80, -1
	s_mov_b32 s82, 0
	v_add3_u32 v84, s51, v77, v78
	v_add3_u32 v85, s51, v76, v78
	v_lshl_add_u64 v[68:69], v[68:69], 0, s[54:55]
	v_lshl_add_u64 v[70:71], v[70:71], 0, s[54:55]
	v_add_u32_e32 v86, 0x10800, v84
	v_add_u32_e32 v87, 0x10800, v85
	v_lshl_add_u64 v[104:105], v[68:69], 0, s[20:21]
	v_lshl_add_u64 v[108:109], v[70:71], 0, s[20:21]
	v_lshl_add_u64 v[112:113], v[68:69], 0, s[40:41]
	v_lshl_add_u64 v[116:117], v[70:71], 0, s[40:41]
	v_lshl_add_u64 v[120:121], v[68:69], 0, s[36:37]
	v_lshl_add_u64 v[124:125], v[70:71], 0, s[36:37]
	global_load_dwordx4 v[96:99], v[68:69], off
	global_load_dwordx4 v[100:103], v[70:71], off
	global_load_dwordx4 v[104:107], v[104:105], off
	global_load_dwordx4 v[108:111], v[108:109], off
	global_load_dwordx4 v[112:115], v[112:113], off
	global_load_dwordx4 v[116:119], v[116:117], off
	global_load_dwordx4 v[120:123], v[120:121], off
	global_load_dwordx4 v[124:127], v[124:125], off
	v_lshl_add_u64 v[68:69], v[68:69], 0, s[54:55]
	v_lshl_add_u64 v[70:71], v[70:71], 0, s[54:55]
	v_lshl_add_u64 v[8:9], v[68:69], 0, s[20:21]
	v_lshl_add_u64 v[12:13], v[70:71], 0, s[20:21]
	v_lshl_add_u64 v[16:17], v[68:69], 0, s[40:41]
	v_lshl_add_u64 v[20:21], v[70:71], 0, s[40:41]
	v_lshl_add_u64 v[24:25], v[68:69], 0, s[36:37]
	v_lshl_add_u64 v[28:29], v[70:71], 0, s[36:37]
	global_load_dwordx4 v[0:3], v[68:69], off
	global_load_dwordx4 v[4:7], v[70:71], off
	global_load_dwordx4 v[8:11], v[8:9], off
	global_load_dwordx4 v[12:15], v[12:13], off
	global_load_dwordx4 v[16:19], v[16:17], off
	global_load_dwordx4 v[20:23], v[20:21], off
	global_load_dwordx4 v[24:27], v[24:25], off
	global_load_dwordx4 v[28:31], v[28:29], off
	v_lshl_add_u64 v[68:69], v[68:69], 0, s[54:55]
	v_lshl_add_u64 v[70:71], v[70:71], 0, s[54:55]
	s_and_b64 vcc, exec, s[38:39]
	s_cbranch_vccnz .Lmini_plain_pair
.Lmini_gate_pair:
	v_lshl_add_u64 v[88:89], v[72:73], 0, s[82:83]
	global_load_dwordx2 v[80:81], v[88:89], off
	global_load_dwordx2 v[82:83], v[88:89], off offset:32
	global_load_dwordx2 v[90:91], v[88:89], off offset:64
	global_load_dwordx2 v[92:93], v[88:89], off offset:96
	ds_read_b128 v[128:131], v84
	ds_read_b128 v[144:147], v85 offset:33792
	ds_read_b128 v[148:151], v85 offset:42240
	ds_read_b128 v[152:155], v85 offset:50688
	ds_read_b128 v[156:159], v85 offset:59136
	ds_read_b128 v[132:135], v84 offset:64
	ds_read_b128 v[160:163], v85 offset:33856
	ds_read_b128 v[164:167], v85 offset:42304
	ds_read_b128 v[168:171], v85 offset:50752
	ds_read_b128 v[172:175], v85 offset:59200
	ds_read_b128 v[136:139], v84 offset:128
	ds_read_b128 v[176:179], v85 offset:33920
	ds_read_b128 v[180:183], v85 offset:42368
	ds_read_b128 v[184:187], v85 offset:50816
	ds_read_b128 v[188:191], v85 offset:59264
	s_waitcnt lgkmcnt(10)
	v_mfma_f32_16x16x32_bf16 v[44:47], v[144:147], v[128:131], v[44:47]
	v_mfma_f32_16x16x32_bf16 v[40:43], v[148:151], v[128:131], v[40:43]
	v_mfma_f32_16x16x32_bf16 v[36:39], v[152:155], v[128:131], v[36:39]
	v_mfma_f32_16x16x32_bf16 v[32:35], v[156:159], v[128:131], v[32:35]
	ds_read_b128 v[140:143], v84 offset:192
	ds_read_b128 v[144:147], v85 offset:33984
	ds_read_b128 v[148:151], v85 offset:42432
	ds_read_b128 v[152:155], v85 offset:50880
	ds_read_b128 v[156:159], v85 offset:59328
	s_waitcnt lgkmcnt(10)
	v_mfma_f32_16x16x32_bf16 v[44:47], v[160:163], v[132:135], v[44:47]
	v_mfma_f32_16x16x32_bf16 v[40:43], v[164:167], v[132:135], v[40:43]
	v_mfma_f32_16x16x32_bf16 v[36:39], v[168:171], v[132:135], v[36:39]
	v_mfma_f32_16x16x32_bf16 v[32:35], v[172:175], v[132:135], v[32:35]
	s_waitcnt lgkmcnt(5)
	v_mfma_f32_16x16x32_bf16 v[44:47], v[176:179], v[136:139], v[44:47]
	v_mfma_f32_16x16x32_bf16 v[40:43], v[180:183], v[136:139], v[40:43]
	v_mfma_f32_16x16x32_bf16 v[36:39], v[184:187], v[136:139], v[36:39]
	v_mfma_f32_16x16x32_bf16 v[32:35], v[188:191], v[136:139], v[32:35]
	s_waitcnt lgkmcnt(0)
	v_mfma_f32_16x16x32_bf16 v[44:47], v[144:147], v[140:143], v[44:47]
	v_mfma_f32_16x16x32_bf16 v[40:43], v[148:151], v[140:143], v[40:43]
	v_mfma_f32_16x16x32_bf16 v[36:39], v[152:155], v[140:143], v[36:39]
	v_mfma_f32_16x16x32_bf16 v[32:35], v[156:159], v[140:143], v[32:35]
	s_cmp_eq_u32 s53, s56
	s_cbranch_scc1 .Lmini_gate_w1_last
	s_waitcnt vmcnt(12)
	s_branch .Lmini_gate_w1_done
.Lmini_gate_w1_last:
	s_waitcnt vmcnt(4)
.Lmini_gate_w1_done:
	ds_write_b128 v79, v[96:99]
	ds_write_b128 v79, v[100:103] offset:33792
	ds_write_b128 v79, v[104:107] offset:8448
	ds_write_b128 v79, v[108:111] offset:42240
	ds_write_b128 v79, v[112:115] offset:16896
	ds_write_b128 v79, v[116:119] offset:50688
	ds_write_b128 v79, v[120:123] offset:25344
	ds_write_b128 v79, v[124:127] offset:59136
	s_waitcnt lgkmcnt(0)
	s_barrier
	s_cmp_eq_u32 s53, s56
	s_cbranch_scc1 .Lmini_gate_odd
	v_lshl_add_u64 v[104:105], v[68:69], 0, s[20:21]
	v_lshl_add_u64 v[108:109], v[70:71], 0, s[20:21]
	v_lshl_add_u64 v[112:113], v[68:69], 0, s[40:41]
	v_lshl_add_u64 v[116:117], v[70:71], 0, s[40:41]
	v_lshl_add_u64 v[120:121], v[68:69], 0, s[36:37]
	v_lshl_add_u64 v[124:125], v[70:71], 0, s[36:37]
	global_load_dwordx4 v[96:99], v[68:69], off
	global_load_dwordx4 v[100:103], v[70:71], off
	global_load_dwordx4 v[104:107], v[104:105], off
	global_load_dwordx4 v[108:111], v[108:109], off
	global_load_dwordx4 v[112:115], v[112:113], off
	global_load_dwordx4 v[116:119], v[116:117], off
	global_load_dwordx4 v[120:123], v[120:121], off
	global_load_dwordx4 v[124:127], v[124:125], off
	v_lshl_add_u64 v[68:69], v[68:69], 0, s[54:55]
	v_lshl_add_u64 v[70:71], v[70:71], 0, s[54:55]
.Lmini_gate_odd:
	ds_read_b128 v[128:131], v86
	ds_read_b128 v[144:147], v87 offset:33792
	ds_read_b128 v[148:151], v87 offset:42240
	ds_read_b128 v[152:155], v87 offset:50688
	ds_read_b128 v[156:159], v87 offset:59136
	ds_read_b128 v[132:135], v86 offset:64
	ds_read_b128 v[160:163], v87 offset:33856
	ds_read_b128 v[164:167], v87 offset:42304
	ds_read_b128 v[168:171], v87 offset:50752
	ds_read_b128 v[172:175], v87 offset:59200
	ds_read_b128 v[136:139], v86 offset:128
	ds_read_b128 v[176:179], v87 offset:33920
	ds_read_b128 v[180:183], v87 offset:42368
	ds_read_b128 v[184:187], v87 offset:50816
	ds_read_b128 v[188:191], v87 offset:59264
	s_waitcnt lgkmcnt(10)
	v_mfma_f32_16x16x32_bf16 v[44:47], v[144:147], v[128:131], v[44:47]
	v_mfma_f32_16x16x32_bf16 v[40:43], v[148:151], v[128:131], v[40:43]
	v_mfma_f32_16x16x32_bf16 v[36:39], v[152:155], v[128:131], v[36:39]
	v_mfma_f32_16x16x32_bf16 v[32:35], v[156:159], v[128:131], v[32:35]
	ds_read_b128 v[140:143], v86 offset:192
	ds_read_b128 v[144:147], v87 offset:33984
	ds_read_b128 v[148:151], v87 offset:42432
	ds_read_b128 v[152:155], v87 offset:50880
	ds_read_b128 v[156:159], v87 offset:59328
	s_waitcnt lgkmcnt(10)
	v_mfma_f32_16x16x32_bf16 v[44:47], v[160:163], v[132:135], v[44:47]
	v_mfma_f32_16x16x32_bf16 v[40:43], v[164:167], v[132:135], v[40:43]
	v_mfma_f32_16x16x32_bf16 v[36:39], v[168:171], v[132:135], v[36:39]
	v_mfma_f32_16x16x32_bf16 v[32:35], v[172:175], v[132:135], v[32:35]
	s_waitcnt lgkmcnt(5)
	v_mfma_f32_16x16x32_bf16 v[44:47], v[176:179], v[136:139], v[44:47]
	v_mfma_f32_16x16x32_bf16 v[40:43], v[180:183], v[136:139], v[40:43]
	v_mfma_f32_16x16x32_bf16 v[36:39], v[184:187], v[136:139], v[36:39]
	v_mfma_f32_16x16x32_bf16 v[32:35], v[188:191], v[136:139], v[32:35]
	s_waitcnt lgkmcnt(0)
	v_mfma_f32_16x16x32_bf16 v[44:47], v[144:147], v[140:143], v[44:47]
	v_mfma_f32_16x16x32_bf16 v[40:43], v[148:151], v[140:143], v[40:43]
	v_mfma_f32_16x16x32_bf16 v[36:39], v[152:155], v[140:143], v[36:39]
	v_mfma_f32_16x16x32_bf16 v[32:35], v[156:159], v[140:143], v[32:35]
	s_cmp_eq_u32 s53, s56
	s_cbranch_scc1 .Lmini_gate_g_last
	s_waitcnt vmcnt(8)
	s_branch .Lmini_gate_g_done

.Lmini_gate_g_done:
	s_nop 7
	v_lshlrev_b32_e32 v94, 16, v80
	v_and_b32_e32 v95, 0xffff0000, v80
	v_pk_fma_f32 v[52:53], v[44:45], v[94:95], v[52:53]
	v_lshlrev_b32_e32 v94, 16, v81
	v_and_b32_e32 v95, 0xffff0000, v81
	v_pk_fma_f32 v[54:55], v[46:47], v[94:95], v[54:55]
	v_lshlrev_b32_e32 v94, 16, v82
	v_and_b32_e32 v95, 0xffff0000, v82
	v_pk_fma_f32 v[56:57], v[40:41], v[94:95], v[56:57]
	v_lshlrev_b32_e32 v94, 16, v83
	v_and_b32_e32 v95, 0xffff0000, v83
	v_pk_fma_f32 v[58:59], v[42:43], v[94:95], v[58:59]
	v_lshlrev_b32_e32 v94, 16, v90
	v_and_b32_e32 v95, 0xffff0000, v90
	v_pk_fma_f32 v[60:61], v[36:37], v[94:95], v[60:61]
	v_lshlrev_b32_e32 v94, 16, v91
	v_and_b32_e32 v95, 0xffff0000, v91
	v_pk_fma_f32 v[62:63], v[38:39], v[94:95], v[62:63]
	v_lshlrev_b32_e32 v94, 16, v92
	v_and_b32_e32 v95, 0xffff0000, v92
	v_pk_fma_f32 v[64:65], v[32:33], v[94:95], v[64:65]
	v_lshlrev_b32_e32 v94, 16, v93
	v_and_b32_e32 v95, 0xffff0000, v93
	v_pk_fma_f32 v[66:67], v[34:35], v[94:95], v[66:67]
	v_mov_b32_e32 v32, 0
	v_mov_b32_e32 v33, 0
	v_mov_b32_e32 v34, 0
	v_mov_b32_e32 v35, 0
	v_mov_b32_e32 v36, 0
	v_mov_b32_e32 v37, 0
	v_mov_b32_e32 v38, 0
	v_mov_b32_e32 v39, 0
	v_mov_b32_e32 v40, 0
	v_mov_b32_e32 v41, 0
	v_mov_b32_e32 v42, 0
	v_mov_b32_e32 v43, 0
	v_mov_b32_e32 v44, 0
	v_mov_b32_e32 v45, 0
	v_mov_b32_e32 v46, 0
	v_mov_b32_e32 v47, 0
	s_cmp_eq_u32 s53, s56
	s_cbranch_scc1 .Lmini_done
	ds_write_b128 v75, v[0:3]
	ds_write_b128 v75, v[4:7] offset:33792
	ds_write_b128 v75, v[8:11] offset:8448
	ds_write_b128 v75, v[12:15] offset:42240
	ds_write_b128 v75, v[16:19] offset:16896
	ds_write_b128 v75, v[20:23] offset:50688
	ds_write_b128 v75, v[24:27] offset:25344
	ds_write_b128 v75, v[28:31] offset:59136
	s_waitcnt lgkmcnt(0)
	s_barrier
	s_add_i32 s53, s53, 2
	s_addk_i32 s82, 0x800
	s_cmp_eq_u32 s53, s56
	s_cbranch_scc1 .Lmini_gate_pair
	v_lshl_add_u64 v[8:9], v[68:69], 0, s[20:21]
	v_lshl_add_u64 v[12:13], v[70:71], 0, s[20:21]
	v_lshl_add_u64 v[16:17], v[68:69], 0, s[40:41]
	v_lshl_add_u64 v[20:21], v[70:71], 0, s[40:41]
	v_lshl_add_u64 v[24:25], v[68:69], 0, s[36:37]
	v_lshl_add_u64 v[28:29], v[70:71], 0, s[36:37]
	global_load_dwordx4 v[0:3], v[68:69], off
	global_load_dwordx4 v[4:7], v[70:71], off
	global_load_dwordx4 v[8:11], v[8:9], off
	global_load_dwordx4 v[12:15], v[12:13], off
	global_load_dwordx4 v[16:19], v[16:17], off
	global_load_dwordx4 v[20:23], v[20:21], off
	global_load_dwordx4 v[24:27], v[24:25], off
	global_load_dwordx4 v[28:31], v[28:29], off
	v_lshl_add_u64 v[68:69], v[68:69], 0, s[54:55]
	v_lshl_add_u64 v[70:71], v[70:71], 0, s[54:55]
	s_branch .Lmini_gate_pair
.Lmini_plain_pair:
	ds_read_b128 v[128:131], v84
	ds_read_b128 v[144:147], v85 offset:33792
	ds_read_b128 v[148:151], v85 offset:42240
	ds_read_b128 v[152:155], v85 offset:50688
	ds_read_b128 v[156:159], v85 offset:59136
	ds_read_b128 v[132:135], v84 offset:64
	ds_read_b128 v[160:163], v85 offset:33856
	ds_read_b128 v[164:167], v85 offset:42304
	ds_read_b128 v[168:171], v85 offset:50752
	ds_read_b128 v[172:175], v85 offset:59200
	ds_read_b128 v[136:139], v84 offset:128
	ds_read_b128 v[176:179], v85 offset:33920
	ds_read_b128 v[180:183], v85 offset:42368
	ds_read_b128 v[184:187], v85 offset:50816
	ds_read_b128 v[188:191], v85 offset:59264
	s_waitcnt lgkmcnt(10)
	v_mfma_f32_16x16x32_bf16 v[44:47], v[144:147], v[128:131], v[44:47]
	v_mfma_f32_16x16x32_bf16 v[40:43], v[148:151], v[128:131], v[40:43]
	v_mfma_f32_16x16x32_bf16 v[36:39], v[152:155], v[128:131], v[36:39]
	v_mfma_f32_16x16x32_bf16 v[32:35], v[156:159], v[128:131], v[32:35]
	ds_read_b128 v[140:143], v84 offset:192
	ds_read_b128 v[144:147], v85 offset:33984
	ds_read_b128 v[148:151], v85 offset:42432
	ds_read_b128 v[152:155], v85 offset:50880
	ds_read_b128 v[156:159], v85 offset:59328
	s_waitcnt lgkmcnt(10)
	v_mfma_f32_16x16x32_bf16 v[44:47], v[160:163], v[132:135], v[44:47]
	v_mfma_f32_16x16x32_bf16 v[40:43], v[164:167], v[132:135], v[40:43]
	v_mfma_f32_16x16x32_bf16 v[36:39], v[168:171], v[132:135], v[36:39]
	v_mfma_f32_16x16x32_bf16 v[32:35], v[172:175], v[132:135], v[32:35]
	s_waitcnt lgkmcnt(5)
	v_mfma_f32_16x16x32_bf16 v[44:47], v[176:179], v[136:139], v[44:47]
	v_mfma_f32_16x16x32_bf16 v[40:43], v[180:183], v[136:139], v[40:43]
	v_mfma_f32_16x16x32_bf16 v[36:39], v[184:187], v[136:139], v[36:39]
	v_mfma_f32_16x16x32_bf16 v[32:35], v[188:191], v[136:139], v[32:35]
	s_waitcnt lgkmcnt(0)
	v_mfma_f32_16x16x32_bf16 v[44:47], v[144:147], v[140:143], v[44:47]
	v_mfma_f32_16x16x32_bf16 v[40:43], v[148:151], v[140:143], v[40:43]
	v_mfma_f32_16x16x32_bf16 v[36:39], v[152:155], v[140:143], v[36:39]
	v_mfma_f32_16x16x32_bf16 v[32:35], v[156:159], v[140:143], v[32:35]
	s_cmp_eq_u32 s53, s56
	s_cbranch_scc1 .Lmini_plain_w1_last
	s_waitcnt vmcnt(8)
	s_branch .Lmini_plain_w1_done

.Lmini_plain_odd:
	ds_read_b128 v[128:131], v86
	ds_read_b128 v[144:147], v87 offset:33792
	ds_read_b128 v[148:151], v87 offset:42240
	ds_read_b128 v[152:155], v87 offset:50688
	ds_read_b128 v[156:159], v87 offset:59136
	ds_read_b128 v[132:135], v86 offset:64
	ds_read_b128 v[160:163], v87 offset:33856
	ds_read_b128 v[164:167], v87 offset:42304
	ds_read_b128 v[168:171], v87 offset:50752
	ds_read_b128 v[172:175], v87 offset:59200
	ds_read_b128 v[136:139], v86 offset:128
	ds_read_b128 v[176:179], v87 offset:33920
	ds_read_b128 v[180:183], v87 offset:42368
	ds_read_b128 v[184:187], v87 offset:50816
	ds_read_b128 v[188:191], v87 offset:59264
	s_waitcnt lgkmcnt(10)
	v_mfma_f32_16x16x32_bf16 v[44:47], v[144:147], v[128:131], v[44:47]
	v_mfma_f32_16x16x32_bf16 v[40:43], v[148:151], v[128:131], v[40:43]
	v_mfma_f32_16x16x32_bf16 v[36:39], v[152:155], v[128:131], v[36:39]
	v_mfma_f32_16x16x32_bf16 v[32:35], v[156:159], v[128:131], v[32:35]
	ds_read_b128 v[140:143], v86 offset:192
	ds_read_b128 v[144:147], v87 offset:33984
	ds_read_b128 v[148:151], v87 offset:42432
	ds_read_b128 v[152:155], v87 offset:50880
	ds_read_b128 v[156:159], v87 offset:59328
	s_waitcnt lgkmcnt(10)
	v_mfma_f32_16x16x32_bf16 v[44:47], v[160:163], v[132:135], v[44:47]
	v_mfma_f32_16x16x32_bf16 v[40:43], v[164:167], v[132:135], v[40:43]
	v_mfma_f32_16x16x32_bf16 v[36:39], v[168:171], v[132:135], v[36:39]
	v_mfma_f32_16x16x32_bf16 v[32:35], v[172:175], v[132:135], v[32:35]
	s_waitcnt lgkmcnt(5)
	v_mfma_f32_16x16x32_bf16 v[44:47], v[176:179], v[136:139], v[44:47]
	v_mfma_f32_16x16x32_bf16 v[40:43], v[180:183], v[136:139], v[40:43]
	v_mfma_f32_16x16x32_bf16 v[36:39], v[184:187], v[136:139], v[36:39]
	v_mfma_f32_16x16x32_bf16 v[32:35], v[188:191], v[136:139], v[32:35]
	s_waitcnt lgkmcnt(0)
	v_mfma_f32_16x16x32_bf16 v[44:47], v[144:147], v[140:143], v[44:47]
	v_mfma_f32_16x16x32_bf16 v[40:43], v[148:151], v[140:143], v[40:43]
	v_mfma_f32_16x16x32_bf16 v[36:39], v[152:155], v[140:143], v[36:39]
	v_mfma_f32_16x16x32_bf16 v[32:35], v[156:159], v[140:143], v[32:35]
	s_cmp_eq_u32 s53, s56
	s_cbranch_scc1 .Lmini_done
	s_waitcnt vmcnt(8)
	ds_write_b128 v75, v[0:3]
	ds_write_b128 v75, v[4:7] offset:33792
	ds_write_b128 v75, v[8:11] offset:8448
	ds_write_b128 v75, v[12:15] offset:42240
	ds_write_b128 v75, v[16:19] offset:16896
	ds_write_b128 v75, v[20:23] offset:50688
	ds_write_b128 v75, v[24:27] offset:25344
	ds_write_b128 v75, v[28:31] offset:59136
	s_waitcnt lgkmcnt(0)
	s_barrier
	s_add_i32 s53, s53, 2
	s_cmp_eq_u32 s53, s56
	s_cbranch_scc1 .Lmini_plain_pair
	v_lshl_add_u64 v[8:9], v[68:69], 0, s[20:21]
	v_lshl_add_u64 v[12:13], v[70:71], 0, s[20:21]
	v_lshl_add_u64 v[16:17], v[68:69], 0, s[40:41]
	v_lshl_add_u64 v[20:21], v[70:71], 0, s[40:41]
	v_lshl_add_u64 v[24:25], v[68:69], 0, s[36:37]
	v_lshl_add_u64 v[28:29], v[70:71], 0, s[36:37]
	global_load_dwordx4 v[0:3], v[68:69], off
	global_load_dwordx4 v[4:7], v[70:71], off
	global_load_dwordx4 v[8:11], v[8:9], off
	global_load_dwordx4 v[12:15], v[12:13], off
	global_load_dwordx4 v[16:19], v[16:17], off
	global_load_dwordx4 v[20:23], v[20:21], off
	global_load_dwordx4 v[24:27], v[24:25], off
	global_load_dwordx4 v[28:31], v[28:29], off
	v_lshl_add_u64 v[68:69], v[68:69], 0, s[54:55]
	v_lshl_add_u64 v[70:71], v[70:71], 0, s[54:55]
	s_branch .Lmini_plain_pair
.Lmini_done:
	s_nop 7
	v_mov_b32_e32 v12, v44
	v_mov_b32_e32 v13, v45
	v_mov_b32_e32 v14, v46
	v_mov_b32_e32 v15, v47
	v_mov_b32_e32 v8, v40
	v_mov_b32_e32 v9, v41
	v_mov_b32_e32 v10, v42
	v_mov_b32_e32 v11, v43
	v_mov_b32_e32 v4, v36
	v_mov_b32_e32 v5, v37
	v_mov_b32_e32 v6, v38
	v_mov_b32_e32 v7, v39
	v_mov_b32_e32 v0, v32
	v_mov_b32_e32 v1, v33
	v_mov_b32_e32 v2, v34
	v_mov_b32_e32 v3, v35
	s_add_i32 s82, s80, 1
	s_lshl_b32 s82, s82, 8

.LBB0_941:
	s_andn2_b64 vcc, exec, s[20:21]
	s_cbranch_vccnz .LBB0_943
	v_lshlrev_b64 v[0:1], 11, v[48:49]
	v_lshl_add_u64 v[0:1], s[30:31], 0, v[0:1]
	v_ashrrev_i32_e32 v21, 31, v20
	v_lshl_add_u64 v[0:1], v[20:21], 1, v[0:1]
	s_mov_b64 s[0:1], 0xda00000
	v_lshl_add_u64 v[2:3], v[0:1], 0, s[0:1]
	v_add_co_u32_e32 v0, vcc, 0xda00000, v0
	v_cvt_pk_bf16_f32 v22, v18, v19
	v_cvt_pk_bf16_f32 v23, v16, v17
	v_addc_co_u32_e32 v1, vcc, 0, v1, vcc
	global_store_dwordx2 v[0:1], v[22:23], off
	v_cvt_pk_bf16_f32 v0, v12, v13
	v_cvt_pk_bf16_f32 v1, v14, v15
	global_store_dwordx2 v[2:3], v[0:1], off offset:32
	v_cvt_pk_bf16_f32 v0, v8, v9
	v_cvt_pk_bf16_f32 v1, v10, v11
	global_store_dwordx2 v[2:3], v[0:1], off offset:64
	v_cvt_pk_bf16_f32 v0, v4, v5
	v_cvt_pk_bf16_f32 v1, v6, v7
	global_store_dwordx2 v[2:3], v[0:1], off offset:96
	s_cbranch_execnz .LBB0_953
	s_branch .LBB0_944

.LBB0_944:
	v_lshlrev_b64 v[0:1], 6, v[48:49]
	v_lshl_add_u64 v[0:1], s[30:31], 0, v[0:1]
	v_lshlrev_b32_e32 v192, 2, v50
	v_lshl_add_u64 v[0:1], v[0:1], 0, v[192:193]
	v_add_co_u32_e32 v0, vcc, 0x5d00000, v0
	s_nop 1
	v_addc_co_u32_e32 v1, vcc, 0, v1, vcc
	global_load_dwordx4 v[0:3], v[0:1], off
	v_cmp_lt_i32_e32 vcc, v223, v218
	s_waitcnt vmcnt(0) lgkmcnt(0)
	v_mov_b32_e32 v22, v1
	v_mov_b32_e32 v23, v2
	v_mov_b32_e32 v1, v3
	v_pk_add_f32 v[0:1], v[22:23], v[0:1]
	s_nop 0
	v_add_f32_e32 v0, v0, v1
	v_cndmask_b32_e32 v1, v217, v223, vcc
	v_lshlrev_b32_e32 v1, 2, v1
	ds_bpermute_b32 v1, v1, v0
	v_cmp_lt_i32_e32 vcc, v224, v218
	s_waitcnt lgkmcnt(0)
	v_add_f32_e32 v0, v0, v1
	v_cndmask_b32_e32 v1, v217, v224, vcc
	v_lshlrev_b32_e32 v1, 2, v1
	ds_bpermute_b32 v1, v1, v0
	s_andn2_b64 vcc, exec, s[2:3]
	s_waitcnt lgkmcnt(0)
	v_add_f32_e32 v0, v0, v1
	v_fmamk_f32 v0, v0, 0x3a800000, v215
	v_rsq_f32_e32 v0, v0
	s_nop 0
	v_mul_f32_e32 v0, s17, v0
	v_pk_mul_f32 v[22:23], v[16:17], v[0:1] op_sel_hi:[1,0]
	v_pk_mul_f32 v[24:25], v[18:19], v[0:1] op_sel_hi:[1,0]
	v_cndmask_b32_e64 v1, 0, 1, s[2:3]
	v_cmp_ne_u32_e64 s[0:1], 1, v1
	s_cbranch_vccnz .LBB0_946
	v_max_f32_e32 v1, v24, v24
	v_max_f32_e32 v2, 0, v1
	v_max_f32_e32 v1, v25, v25
	v_max_f32_e32 v3, 0, v1
	v_max_f32_e32 v1, v22, v22
	v_max_f32_e32 v22, 0, v1
	v_max_f32_e32 v1, v23, v23
	v_max_f32_e32 v23, 0, v1
	v_pk_mul_f32 v[22:23], v[22:23], v[22:23]
	v_pk_mul_f32 v[24:25], v[2:3], v[2:3]
.LBB0_946:
	s_add_u32 s20, s30, s29
	s_addc_u32 s21, s31, 0
	v_lshlrev_b64 v[2:3], s33, v[48:49]
	v_ashrrev_i32_e32 v21, 31, v20
	v_lshl_add_u64 v[2:3], s[20:21], 0, v[2:3]
	v_mov_b32_e32 v1, v0
	v_lshl_add_u64 v[2:3], v[20:21], 1, v[2:3]
	v_cvt_pk_bf16_f32 v24, v24, v25
	v_cvt_pk_bf16_f32 v25, v22, v23
	v_mov_b32_e32 v22, v0
	v_mov_b32_e32 v23, v0
	global_store_dwordx2 v[2:3], v[24:25], off
	v_pk_mul_f32 v[24:25], v[14:15], v[22:23]
	s_and_b64 vcc, exec, s[0:1]
	v_pk_mul_f32 v[26:27], v[12:13], v[0:1]
	s_cbranch_vccnz .LBB0_948
	v_max_f32_e32 v21, v26, v26
	v_max_f32_e32 v26, 0, v21
	v_max_f32_e32 v21, v27, v27
	v_max_f32_e32 v27, 0, v21
	v_max_f32_e32 v21, v24, v24
	v_max_f32_e32 v24, 0, v21
	v_max_f32_e32 v21, v25, v25
	v_max_f32_e32 v25, 0, v21
	v_pk_mul_f32 v[24:25], v[24:25], v[24:25]
	v_pk_mul_f32 v[26:27], v[26:27], v[26:27]
.LBB0_948:
	s_nop 0
	v_cvt_pk_bf16_f32 v26, v26, v27
	v_cvt_pk_bf16_f32 v27, v24, v25
	v_pk_mul_f32 v[22:23], v[10:11], v[22:23]
	s_and_b64 vcc, exec, s[0:1]
	v_pk_mul_f32 v[24:25], v[8:9], v[0:1]
	global_store_dwordx2 v[2:3], v[26:27], off offset:32
	s_cbranch_vccnz .LBB0_950
	v_max_f32_e32 v21, v24, v24
	v_max_f32_e32 v24, 0, v21
	v_max_f32_e32 v21, v25, v25
	v_max_f32_e32 v25, 0, v21
	v_max_f32_e32 v21, v22, v22
	v_max_f32_e32 v22, 0, v21
	v_max_f32_e32 v21, v23, v23
	v_max_f32_e32 v23, 0, v21
	v_pk_mul_f32 v[22:23], v[22:23], v[22:23]
	v_pk_mul_f32 v[24:25], v[24:25], v[24:25]
.LBB0_950:
	s_nop 0
	v_cvt_pk_bf16_f32 v24, v24, v25
	v_cvt_pk_bf16_f32 v25, v22, v23
	v_mov_b32_e32 v22, v0
	v_mov_b32_e32 v23, v0
	v_pk_mul_f32 v[22:23], v[6:7], v[22:23]
	s_and_b64 vcc, exec, s[0:1]
	v_pk_mul_f32 v[0:1], v[4:5], v[0:1]
	global_store_dwordx2 v[2:3], v[24:25], off offset:64
	s_cbranch_vccnz .LBB0_952
	v_max_f32_e32 v21, v22, v22
	v_max_f32_e32 v0, v0, v0
	v_max_f32_e32 v1, v1, v1
	v_max_f32_e32 v22, 0, v21
	v_max_f32_e32 v21, v23, v23
	v_max_f32_e32 v0, 0, v0
	v_max_f32_e32 v1, 0, v1
	v_max_f32_e32 v23, 0, v21
	v_pk_mul_f32 v[22:23], v[22:23], v[22:23]
	v_pk_mul_f32 v[0:1], v[0:1], v[0:1]
.LBB0_952:
	s_nop 0
	v_cvt_pk_bf16_f32 v0, v0, v1
	v_cvt_pk_bf16_f32 v1, v22, v23
	global_store_dwordx2 v[2:3], v[0:1], off offset:96

.LBB0_958:
	v_lshlrev_b64 v[24:25], 11, v[48:49]
	v_lshl_add_u64 v[24:25], s[30:31], 0, v[24:25]
	v_lshl_add_u64 v[20:21], v[20:21], 1, v[24:25]
	s_andn2_b64 vcc, exec, s[20:21]
	s_mov_b64 s[20:21], 0xb800000
	v_lshl_add_u64 v[20:21], v[20:21], 0, s[20:21]
	s_cbranch_vccnz .LBB0_960
	s_waitcnt vmcnt(0)
	global_load_dwordx2 v[2:3], v[20:21], off
	s_waitcnt vmcnt(0) lgkmcnt(0)
	v_lshlrev_b32_e32 v0, 16, v2
	v_and_b32_e32 v1, 0xffff0000, v2
	v_lshlrev_b32_e32 v2, 16, v3
	v_and_b32_e32 v3, 0xffff0000, v3
.LBB0_960:
	s_waitcnt vmcnt(0)
	v_pk_add_f32 v[2:3], v[16:17], v[2:3]
	v_pk_add_f32 v[0:1], v[18:19], v[0:1]
	v_cvt_pk_bf16_f32 v17, v2, v3
	v_cvt_pk_bf16_f32 v16, v0, v1
	s_and_b64 vcc, exec, s[0:1]
	global_store_dwordx2 v[20:21], v[16:17], off
	s_cbranch_vccnz .LBB0_971
	global_load_dwordx4 v[0:3], v[22:23], off offset:64
	s_cbranch_execnz .LBB0_963
.LBB0_962:
	s_waitcnt vmcnt(0)
	global_load_dwordx2 v[2:3], v[20:21], off offset:32
	s_waitcnt vmcnt(0) lgkmcnt(0)
	v_lshlrev_b32_e32 v0, 16, v2
	v_and_b32_e32 v1, 0xffff0000, v2
	v_lshlrev_b32_e32 v2, 16, v3
	v_and_b32_e32 v3, 0xffff0000, v3
.LBB0_963:
	s_waitcnt vmcnt(0)
	v_pk_add_f32 v[2:3], v[14:15], v[2:3]
	v_pk_add_f32 v[0:1], v[12:13], v[0:1]
	v_cvt_pk_bf16_f32 v13, v2, v3
	v_cvt_pk_bf16_f32 v12, v0, v1
	s_and_b64 vcc, exec, s[0:1]
	global_store_dwordx2 v[20:21], v[12:13], off offset:32
	s_cbranch_vccnz .LBB0_972
	global_load_dwordx4 v[0:3], v[22:23], off offset:128
	s_cbranch_execnz .LBB0_966
.LBB0_965:
	s_waitcnt vmcnt(0)
	global_load_dwordx2 v[2:3], v[20:21], off offset:64
	s_waitcnt vmcnt(0) lgkmcnt(0)
	v_lshlrev_b32_e32 v0, 16, v2
	v_and_b32_e32 v1, 0xffff0000, v2
	v_lshlrev_b32_e32 v2, 16, v3
	v_and_b32_e32 v3, 0xffff0000, v3
.LBB0_966:
	s_waitcnt vmcnt(0)
	v_pk_add_f32 v[2:3], v[10:11], v[2:3]
	v_pk_add_f32 v[0:1], v[8:9], v[0:1]
	v_cvt_pk_bf16_f32 v9, v2, v3
	v_cvt_pk_bf16_f32 v8, v0, v1
	s_and_b64 vcc, exec, s[0:1]
	global_store_dwordx2 v[20:21], v[8:9], off offset:64
	s_cbranch_vccnz .LBB0_973
	global_load_dwordx4 v[0:3], v[22:23], off offset:192
	s_cbranch_execnz .LBB0_969
.LBB0_968:
	s_waitcnt vmcnt(0)
	global_load_dwordx2 v[2:3], v[20:21], off offset:96
	s_waitcnt vmcnt(0) lgkmcnt(0)
	v_lshlrev_b32_e32 v0, 16, v2
	v_and_b32_e32 v1, 0xffff0000, v2
	v_lshlrev_b32_e32 v2, 16, v3
	v_and_b32_e32 v3, 0xffff0000, v3
.LBB0_969:
	v_and_b32_e32 v11, 0xffff0000, v16
	v_lshlrev_b32_e32 v10, 16, v16
	v_and_b32_e32 v15, 0xffff0000, v17
	v_mul_f32_e32 v11, v11, v11
	v_lshlrev_b32_e32 v14, 16, v17
	v_fmac_f32_e32 v11, v10, v10
	v_mul_f32_e32 v10, v15, v15
	v_fmac_f32_e32 v10, v14, v14
	v_add_f32_e32 v10, v11, v10
	v_lshlrev_b32_e32 v11, 16, v12
	v_and_b32_e32 v12, 0xffff0000, v12
	v_lshlrev_b32_e32 v14, 16, v13
	v_and_b32_e32 v13, 0xffff0000, v13
	v_mul_f32_e32 v12, v12, v12
	v_fmac_f32_e32 v12, v11, v11
	v_mul_f32_e32 v11, v13, v13
	v_fmac_f32_e32 v11, v14, v14
	s_waitcnt vmcnt(0)
	v_pk_add_f32 v[0:1], v[4:5], v[0:1]
	v_add_f32_e32 v11, v12, v11
	v_pk_add_f32 v[2:3], v[6:7], v[2:3]
	v_cvt_pk_bf16_f32 v4, v0, v1
	v_add_f32_e32 v10, v10, v11
	v_lshlrev_b32_e32 v11, 16, v8
	v_and_b32_e32 v8, 0xffff0000, v8
	v_lshlrev_b32_e32 v12, 16, v9
	v_and_b32_e32 v9, 0xffff0000, v9
	v_cvt_pk_bf16_f32 v5, v2, v3
	v_and_b32_e32 v1, 0xffff0000, v4
	v_mul_f32_e32 v8, v8, v8
	v_mul_f32_e32 v9, v9, v9
	v_lshlrev_b32_e32 v0, 16, v4
	v_and_b32_e32 v3, 0xffff0000, v5
	v_mul_f32_e32 v1, v1, v1
	v_fmac_f32_e32 v8, v11, v11
	v_fmac_f32_e32 v9, v12, v12
	v_lshlrev_b32_e32 v2, 16, v5
	v_fmac_f32_e32 v1, v0, v0
	v_mul_f32_e32 v0, v3, v3
	v_add_f32_e32 v8, v8, v9
	v_fmac_f32_e32 v0, v2, v2
	v_cmp_lt_i32_e32 vcc, v223, v218
	v_add_f32_e32 v8, v10, v8
	v_add_f32_e32 v0, v1, v0
	v_cndmask_b32_e32 v1, v217, v223, vcc
	v_add_f32_e32 v0, v8, v0
	v_lshlrev_b32_e32 v1, 2, v1
	ds_bpermute_b32 v1, v1, v0
	v_cmp_lt_i32_e32 vcc, v224, v218
	global_store_dwordx2 v[20:21], v[4:5], off offset:96
	s_waitcnt lgkmcnt(0)
	v_add_f32_e32 v0, v0, v1
	v_cndmask_b32_e32 v1, v217, v224, vcc
	v_lshlrev_b32_e32 v1, 2, v1
	ds_bpermute_b32 v1, v1, v0
	v_cmp_gt_u32_e32 vcc, 16, v51
	s_and_saveexec_b64 s[0:1], vcc
	s_cbranch_execz .LBB0_925
	s_waitcnt lgkmcnt(0)
	v_add_f32_e32 v2, v0, v1
	v_lshlrev_b64 v[0:1], 6, v[48:49]
	v_lshl_add_u64 v[0:1], s[30:31], 0, v[0:1]
	s_ashr_i32 s15, s14, 31
	v_lshl_add_u64 v[0:1], s[14:15], 2, v[0:1]
	v_add_co_u32_e32 v0, vcc, 0x5d00000, v0
	s_nop 1
	v_addc_co_u32_e32 v1, vcc, 0, v1, vcc
	global_store_dword v[0:1], v2, off
	s_branch .LBB0_925

.LBB0_1051:
	s_cmp_eq_u32 s50, 0
	s_cselect_b64 s[20:21], -1, 0
	s_or_b64 s[20:21], s[34:35], s[20:21]
	s_and_b32 s54, s93, 6
	s_cmp_lg_u32 s54, 0
	s_cselect_b64 vcc, -1, 0
	s_or_b64 s[20:21], s[20:21], vcc
	s_and_b64 vcc, exec, s[20:21]
	s_cbranch_vccnz .LBB0_1050
	v_mov_b32_e32 v202, v194
	v_mov_b32_e32 v128, v198
	s_nop 0
	v_ashrrev_i32_e32 v129, 31, v128
	v_add_u32_e32 v130, s63, v202
	v_lshlrev_b64 v[212:213], 1, v[128:129]
	v_mad_i64_i32 v[128:129], s[20:21], v130, s76, v[212:213]
	s_add_u32 s20, s79, s50
	s_addc_u32 s21, s92, s51
	v_lshl_add_u64 v[128:129], s[20:21], 0, v[128:129]
	v_add_co_u32_e32 v128, vcc, s78, v128
	s_nop 1
	v_addc_co_u32_e32 v129, vcc, 0, v129, vcc
	global_load_dwordx4 v[188:191], v[128:129], off
	global_load_dwordx4 v[184:187], v[128:129], off offset:2048
	global_load_dwordx4 v[180:183], v[128:129], off offset:256
	global_load_dwordx4 v[176:179], v[128:129], off offset:2304
	v_add_u32_e32 v128, 16, v130
	v_mad_i64_i32 v[128:129], vcc, v128, s76, v[212:213]
	v_lshl_add_u64 v[128:129], s[20:21], 0, v[128:129]
	v_add_co_u32_e32 v128, vcc, s78, v128
	s_waitcnt vmcnt(0) lgkmcnt(0)
	v_lshlrev_b32_e32 v205, 16, v188
	v_addc_co_u32_e32 v129, vcc, 0, v129, vcc
	global_load_dwordx4 v[172:175], v[128:129], off
	global_load_dwordx4 v[168:171], v[128:129], off offset:2048
	global_load_dwordx4 v[164:167], v[128:129], off offset:256
	global_load_dwordx4 v[160:163], v[128:129], off offset:2304
	v_max_f32_e32 v205, v205, v205
	v_max_f32_e32 v242, 0x1e3ce508, v205
	v_lshlrev_b32_e32 v205, 16, v184
	v_and_b32_e32 v184, 0xffff0000, v184
	v_max_f32_e32 v184, v184, v184
	v_max_f32_e32 v184, 0x1e3ce508, v184
	v_and_b32_e32 v188, 0xffff0000, v188
	v_rcp_f32_e32 v245, v184
	v_lshlrev_b32_e32 v184, 16, v189
	v_max_f32_e32 v188, v188, v188
	v_max_f32_e32 v184, v184, v184
	v_max_f32_e32 v243, 0x1e3ce508, v188
	v_max_f32_e32 v188, 0x1e3ce508, v184
	v_lshlrev_b32_e32 v184, 16, v185
	v_and_b32_e32 v185, 0xffff0000, v185
	v_max_f32_e32 v184, v184, v184
	v_max_f32_e32 v185, v185, v185
	v_max_f32_e32 v184, 0x1e3ce508, v184
	v_max_f32_e32 v185, 0x1e3ce508, v185
	v_rcp_f32_e32 v184, v184
	v_rcp_f32_e32 v185, v185
	v_add_u32_e32 v128, 32, v130
	v_and_b32_e32 v189, 0xffff0000, v189
	v_mad_i64_i32 v[128:129], vcc, v128, s76, v[212:213]
	v_max_f32_e32 v189, v189, v189
	v_lshl_add_u64 v[128:129], s[20:21], 0, v[128:129]
	v_max_f32_e32 v189, 0x1e3ce508, v189
	v_add_co_u32_e32 v128, vcc, s78, v128
	v_pk_mul_f32 v[184:185], v[188:189], v[184:185]
	s_nop 0
	v_addc_co_u32_e32 v129, vcc, 0, v129, vcc
	v_pk_mul_f32 v[126:127], v[126:127], v[184:185]
	v_lshlrev_b32_e32 v185, 16, v186
	v_and_b32_e32 v186, 0xffff0000, v186
	global_load_dwordx4 v[156:159], v[128:129], off
	global_load_dwordx4 v[152:155], v[128:129], off offset:2048
	global_load_dwordx4 v[144:147], v[128:129], off offset:256
	global_load_dwordx4 v[136:139], v[128:129], off offset:2304
	v_max_f32_e32 v186, v186, v186
	v_max_f32_e32 v186, 0x1e3ce508, v186
	v_max_f32_e32 v185, v185, v185
	v_rcp_f32_e32 v189, v186
	v_lshlrev_b32_e32 v186, 16, v191
	v_max_f32_e32 v185, 0x1e3ce508, v185
	v_max_f32_e32 v186, v186, v186
	v_lshlrev_b32_e32 v184, 16, v190
	v_rcp_f32_e32 v188, v185
	v_and_b32_e32 v185, 0xffff0000, v190
	v_max_f32_e32 v190, 0x1e3ce508, v186
	v_lshlrev_b32_e32 v186, 16, v187
	v_and_b32_e32 v187, 0xffff0000, v187
	v_max_f32_e32 v186, v186, v186
	v_max_f32_e32 v187, v187, v187
	v_max_f32_e32 v184, v184, v184
	v_max_f32_e32 v185, v185, v185
	v_max_f32_e32 v186, 0x1e3ce508, v186
	v_max_f32_e32 v187, 0x1e3ce508, v187
	v_max_f32_e32 v184, 0x1e3ce508, v184
	v_max_f32_e32 v185, 0x1e3ce508, v185
	v_rcp_f32_e32 v186, v186
	v_rcp_f32_e32 v187, v187
	v_and_b32_e32 v191, 0xffff0000, v191
	v_pk_mul_f32 v[184:185], v[184:185], v[188:189]
	v_max_f32_e32 v191, v191, v191
	v_pk_mul_f32 v[120:121], v[120:121], v[184:185]
	v_lshlrev_b32_e32 v185, 16, v176
	v_and_b32_e32 v176, 0xffff0000, v176
	v_max_f32_e32 v191, 0x1e3ce508, v191
	v_max_f32_e32 v176, v176, v176
	v_pk_mul_f32 v[186:187], v[190:191], v[186:187]
	v_max_f32_e32 v176, 0x1e3ce508, v176
	v_pk_mul_f32 v[122:123], v[122:123], v[186:187]
	v_lshlrev_b32_e32 v184, 16, v180
	v_max_f32_e32 v185, v185, v185
	v_and_b32_e32 v180, 0xffff0000, v180
	v_rcp_f32_e32 v187, v176
	v_lshlrev_b32_e32 v176, 16, v181
	v_max_f32_e32 v185, 0x1e3ce508, v185
	v_max_f32_e32 v180, v180, v180
	v_max_f32_e32 v176, v176, v176
	v_rcp_f32_e32 v186, v185
	v_max_f32_e32 v185, 0x1e3ce508, v180
	v_max_f32_e32 v180, 0x1e3ce508, v176
	v_lshlrev_b32_e32 v176, 16, v177
	v_and_b32_e32 v177, 0xffff0000, v177
	v_max_f32_e32 v176, v176, v176
	v_max_f32_e32 v177, v177, v177
	v_max_f32_e32 v176, 0x1e3ce508, v176
	v_max_f32_e32 v177, 0x1e3ce508, v177
	v_rcp_f32_e32 v176, v176
	v_rcp_f32_e32 v177, v177
	v_and_b32_e32 v181, 0xffff0000, v181
	v_max_f32_e32 v181, v181, v181
	v_max_f32_e32 v181, 0x1e3ce508, v181
	v_pk_mul_f32 v[176:177], v[180:181], v[176:177]
	v_add_u32_e32 v128, 48, v130
	v_pk_mul_f32 v[94:95], v[94:95], v[176:177]
	v_lshlrev_b32_e32 v177, 16, v178
	v_and_b32_e32 v178, 0xffff0000, v178
	v_max_f32_e32 v178, v178, v178
	v_max_f32_e32 v178, 0x1e3ce508, v178
	v_max_f32_e32 v177, v177, v177
	v_rcp_f32_e32 v181, v178
	v_lshlrev_b32_e32 v178, 16, v183
	v_max_f32_e32 v177, 0x1e3ce508, v177
	v_max_f32_e32 v178, v178, v178
	v_lshlrev_b32_e32 v176, 16, v182
	v_rcp_f32_e32 v180, v177
	v_and_b32_e32 v177, 0xffff0000, v182
	v_max_f32_e32 v182, 0x1e3ce508, v178
	v_lshlrev_b32_e32 v178, 16, v179
	v_and_b32_e32 v179, 0xffff0000, v179
	v_max_f32_e32 v178, v178, v178
	v_max_f32_e32 v179, v179, v179
	v_max_f32_e32 v176, v176, v176
	v_max_f32_e32 v177, v177, v177
	v_max_f32_e32 v178, 0x1e3ce508, v178
	v_max_f32_e32 v179, 0x1e3ce508, v179
	v_max_f32_e32 v176, 0x1e3ce508, v176
	v_max_f32_e32 v177, 0x1e3ce508, v177
	v_rcp_f32_e32 v178, v178
	v_rcp_f32_e32 v179, v179
	v_and_b32_e32 v183, 0xffff0000, v183
	v_pk_mul_f32 v[176:177], v[176:177], v[180:181]
	v_max_f32_e32 v183, v183, v183
	v_pk_mul_f32 v[88:89], v[88:89], v[176:177]
	s_waitcnt vmcnt(0) lgkmcnt(0)
	v_lshlrev_b32_e32 v177, 16, v168
	v_and_b32_e32 v168, 0xffff0000, v168
	v_max_f32_e32 v183, 0x1e3ce508, v183
	v_max_f32_e32 v168, v168, v168
	v_pk_mul_f32 v[178:179], v[182:183], v[178:179]
	v_max_f32_e32 v168, 0x1e3ce508, v168
	v_pk_mul_f32 v[90:91], v[90:91], v[178:179]
	v_lshlrev_b32_e32 v176, 16, v172
	v_max_f32_e32 v177, v177, v177
	v_and_b32_e32 v172, 0xffff0000, v172
	v_rcp_f32_e32 v179, v168
	v_lshlrev_b32_e32 v168, 16, v173
	v_max_f32_e32 v177, 0x1e3ce508, v177
	v_max_f32_e32 v172, v172, v172
	v_max_f32_e32 v168, v168, v168
	v_rcp_f32_e32 v178, v177
	v_max_f32_e32 v177, 0x1e3ce508, v172
	v_max_f32_e32 v172, 0x1e3ce508, v168
	v_lshlrev_b32_e32 v168, 16, v169
	v_and_b32_e32 v169, 0xffff0000, v169
	v_max_f32_e32 v168, v168, v168
	v_max_f32_e32 v169, v169, v169
	v_max_f32_e32 v168, 0x1e3ce508, v168
	v_max_f32_e32 v169, 0x1e3ce508, v169
	v_rcp_f32_e32 v168, v168
	v_rcp_f32_e32 v169, v169
	v_and_b32_e32 v173, 0xffff0000, v173
	v_max_f32_e32 v173, v173, v173
	v_max_f32_e32 v173, 0x1e3ce508, v173
	v_pk_mul_f32 v[168:169], v[172:173], v[168:169]
	v_mad_i64_i32 v[128:129], vcc, v128, s76, v[212:213]
	v_pk_mul_f32 v[118:119], v[118:119], v[168:169]
	v_lshlrev_b32_e32 v169, 16, v170
	v_and_b32_e32 v170, 0xffff0000, v170
	v_lshl_add_u64 v[128:129], s[20:21], 0, v[128:129]
	v_max_f32_e32 v170, v170, v170
	v_add_co_u32_e32 v132, vcc, s78, v128
	v_max_f32_e32 v170, 0x1e3ce508, v170
	s_nop 0
	v_addc_co_u32_e32 v133, vcc, 0, v129, vcc
	v_max_f32_e32 v169, v169, v169
	v_rcp_f32_e32 v173, v170
	v_lshlrev_b32_e32 v170, 16, v175
	global_load_dwordx4 v[148:151], v[132:133], off
	global_load_dwordx4 v[140:143], v[132:133], off offset:2048
	global_load_dwordx4 v[128:131], v[132:133], off offset:256
	s_nop 0
	global_load_dwordx4 v[132:135], v[132:133], off offset:2304
	v_max_f32_e32 v169, 0x1e3ce508, v169
	v_max_f32_e32 v170, v170, v170
	v_lshlrev_b32_e32 v168, 16, v174
	v_rcp_f32_e32 v172, v169
	v_and_b32_e32 v169, 0xffff0000, v174
	v_max_f32_e32 v174, 0x1e3ce508, v170
	v_lshlrev_b32_e32 v170, 16, v171
	v_and_b32_e32 v171, 0xffff0000, v171
	v_max_f32_e32 v170, v170, v170
	v_max_f32_e32 v171, v171, v171
	v_max_f32_e32 v168, v168, v168
	v_max_f32_e32 v169, v169, v169
	v_max_f32_e32 v170, 0x1e3ce508, v170
	v_max_f32_e32 v171, 0x1e3ce508, v171
	v_max_f32_e32 v168, 0x1e3ce508, v168
	v_max_f32_e32 v169, 0x1e3ce508, v169
	v_rcp_f32_e32 v170, v170
	v_rcp_f32_e32 v171, v171
	v_and_b32_e32 v175, 0xffff0000, v175
	v_pk_mul_f32 v[168:169], v[168:169], v[172:173]
	v_max_f32_e32 v175, v175, v175
	v_pk_mul_f32 v[112:113], v[112:113], v[168:169]
	v_lshlrev_b32_e32 v169, 16, v160
	v_and_b32_e32 v160, 0xffff0000, v160
	v_max_f32_e32 v175, 0x1e3ce508, v175
	v_max_f32_e32 v160, v160, v160
	v_pk_mul_f32 v[170:171], v[174:175], v[170:171]
	v_max_f32_e32 v160, 0x1e3ce508, v160
	v_pk_mul_f32 v[114:115], v[114:115], v[170:171]
	v_lshlrev_b32_e32 v168, 16, v164
	v_max_f32_e32 v169, v169, v169
	v_and_b32_e32 v164, 0xffff0000, v164
	v_rcp_f32_e32 v171, v160
	v_lshlrev_b32_e32 v160, 16, v165
	v_max_f32_e32 v169, 0x1e3ce508, v169
	v_max_f32_e32 v164, v164, v164
	v_max_f32_e32 v160, v160, v160
	v_rcp_f32_e32 v170, v169
	v_max_f32_e32 v169, 0x1e3ce508, v164
	v_max_f32_e32 v164, 0x1e3ce508, v160
	v_lshlrev_b32_e32 v160, 16, v161
	v_and_b32_e32 v161, 0xffff0000, v161
	v_max_f32_e32 v160, v160, v160
	v_max_f32_e32 v161, v161, v161
	v_max_f32_e32 v160, 0x1e3ce508, v160
	v_max_f32_e32 v161, 0x1e3ce508, v161
	v_rcp_f32_e32 v160, v160
	v_rcp_f32_e32 v161, v161
	v_and_b32_e32 v165, 0xffff0000, v165
	v_max_f32_e32 v165, v165, v165
	v_max_f32_e32 v165, 0x1e3ce508, v165
	v_pk_mul_f32 v[160:161], v[164:165], v[160:161]
	v_max_f32_e32 v184, v184, v184
	v_pk_mul_f32 v[86:87], v[86:87], v[160:161]
	v_lshlrev_b32_e32 v161, 16, v162
	v_and_b32_e32 v162, 0xffff0000, v162
	v_max_f32_e32 v162, v162, v162
	v_max_f32_e32 v162, 0x1e3ce508, v162
	v_max_f32_e32 v161, v161, v161
	v_rcp_f32_e32 v165, v162
	v_lshlrev_b32_e32 v162, 16, v167
	v_max_f32_e32 v161, 0x1e3ce508, v161
	v_max_f32_e32 v162, v162, v162
	v_lshlrev_b32_e32 v160, 16, v166
	v_rcp_f32_e32 v164, v161
	v_and_b32_e32 v161, 0xffff0000, v166
	v_max_f32_e32 v166, 0x1e3ce508, v162
	v_lshlrev_b32_e32 v162, 16, v163
	v_and_b32_e32 v163, 0xffff0000, v163
	v_max_f32_e32 v162, v162, v162
	v_max_f32_e32 v163, v163, v163
	v_max_f32_e32 v160, v160, v160
	v_max_f32_e32 v161, v161, v161
	v_max_f32_e32 v162, 0x1e3ce508, v162
	v_max_f32_e32 v163, 0x1e3ce508, v163
	v_max_f32_e32 v160, 0x1e3ce508, v160
	v_max_f32_e32 v161, 0x1e3ce508, v161
	v_rcp_f32_e32 v162, v162
	v_rcp_f32_e32 v163, v163
	v_and_b32_e32 v167, 0xffff0000, v167
	v_pk_mul_f32 v[160:161], v[160:161], v[164:165]
	v_max_f32_e32 v167, v167, v167
	v_pk_mul_f32 v[80:81], v[80:81], v[160:161]
	v_lshlrev_b32_e32 v161, 16, v152
	v_and_b32_e32 v152, 0xffff0000, v152
	v_max_f32_e32 v167, 0x1e3ce508, v167
	v_max_f32_e32 v152, v152, v152
	v_pk_mul_f32 v[162:163], v[166:167], v[162:163]
	v_max_f32_e32 v152, 0x1e3ce508, v152
	v_pk_mul_f32 v[82:83], v[82:83], v[162:163]
	v_lshlrev_b32_e32 v160, 16, v156
	v_max_f32_e32 v161, v161, v161
	v_and_b32_e32 v156, 0xffff0000, v156
	v_rcp_f32_e32 v163, v152
	v_lshlrev_b32_e32 v152, 16, v157
	v_max_f32_e32 v161, 0x1e3ce508, v161
	v_max_f32_e32 v156, v156, v156
	v_max_f32_e32 v152, v152, v152
	v_rcp_f32_e32 v162, v161
	v_max_f32_e32 v161, 0x1e3ce508, v156
	v_max_f32_e32 v156, 0x1e3ce508, v152
	v_lshlrev_b32_e32 v152, 16, v153
	v_and_b32_e32 v153, 0xffff0000, v153
	v_max_f32_e32 v152, v152, v152
	v_max_f32_e32 v153, v153, v153
	v_max_f32_e32 v152, 0x1e3ce508, v152
	v_max_f32_e32 v153, 0x1e3ce508, v153
	v_rcp_f32_e32 v152, v152
	v_rcp_f32_e32 v153, v153
	v_and_b32_e32 v157, 0xffff0000, v157
	v_max_f32_e32 v157, v157, v157
	v_max_f32_e32 v157, 0x1e3ce508, v157
	v_pk_mul_f32 v[152:153], v[156:157], v[152:153]
	v_max_f32_e32 v176, v176, v176
	v_pk_mul_f32 v[110:111], v[110:111], v[152:153]
	v_lshlrev_b32_e32 v153, 16, v154
	v_and_b32_e32 v154, 0xffff0000, v154
	v_max_f32_e32 v154, v154, v154
	v_max_f32_e32 v154, 0x1e3ce508, v154
	v_max_f32_e32 v153, v153, v153
	v_rcp_f32_e32 v157, v154
	v_lshlrev_b32_e32 v154, 16, v159
	v_max_f32_e32 v153, 0x1e3ce508, v153
	v_max_f32_e32 v154, v154, v154
	v_lshlrev_b32_e32 v152, 16, v158
	v_rcp_f32_e32 v156, v153
	v_and_b32_e32 v153, 0xffff0000, v158
	v_max_f32_e32 v158, 0x1e3ce508, v154
	v_lshlrev_b32_e32 v154, 16, v155
	v_and_b32_e32 v155, 0xffff0000, v155
	v_max_f32_e32 v154, v154, v154
	v_max_f32_e32 v155, v155, v155
	v_max_f32_e32 v152, v152, v152
	v_max_f32_e32 v153, v153, v153
	v_max_f32_e32 v154, 0x1e3ce508, v154
	v_max_f32_e32 v155, 0x1e3ce508, v155
	v_max_f32_e32 v152, 0x1e3ce508, v152
	v_max_f32_e32 v153, 0x1e3ce508, v153
	v_rcp_f32_e32 v154, v154
	v_rcp_f32_e32 v155, v155
	v_and_b32_e32 v159, 0xffff0000, v159
	v_pk_mul_f32 v[152:153], v[152:153], v[156:157]
	v_max_f32_e32 v159, v159, v159
	v_pk_mul_f32 v[104:105], v[104:105], v[152:153]
	v_lshlrev_b32_e32 v153, 16, v136
	v_and_b32_e32 v136, 0xffff0000, v136
	v_max_f32_e32 v159, 0x1e3ce508, v159
	v_max_f32_e32 v136, v136, v136
	v_pk_mul_f32 v[154:155], v[158:159], v[154:155]
	v_max_f32_e32 v136, 0x1e3ce508, v136
	v_pk_mul_f32 v[106:107], v[106:107], v[154:155]
	v_lshlrev_b32_e32 v152, 16, v144
	v_max_f32_e32 v153, v153, v153
	v_and_b32_e32 v144, 0xffff0000, v144
	v_rcp_f32_e32 v155, v136
	v_lshlrev_b32_e32 v136, 16, v145
	v_max_f32_e32 v153, 0x1e3ce508, v153
	v_max_f32_e32 v144, v144, v144
	v_max_f32_e32 v136, v136, v136
	v_rcp_f32_e32 v154, v153
	v_max_f32_e32 v153, 0x1e3ce508, v144
	v_max_f32_e32 v144, 0x1e3ce508, v136
	v_lshlrev_b32_e32 v136, 16, v137
	v_and_b32_e32 v137, 0xffff0000, v137
	v_max_f32_e32 v136, v136, v136
	v_max_f32_e32 v137, v137, v137
	v_max_f32_e32 v136, 0x1e3ce508, v136
	v_max_f32_e32 v137, 0x1e3ce508, v137
	v_rcp_f32_e32 v136, v136
	v_rcp_f32_e32 v137, v137
	v_and_b32_e32 v145, 0xffff0000, v145
	v_max_f32_e32 v145, v145, v145
	v_max_f32_e32 v145, 0x1e3ce508, v145
	v_pk_mul_f32 v[136:137], v[144:145], v[136:137]
	v_max_f32_e32 v184, 0x1e3ce508, v184
	v_pk_mul_f32 v[78:79], v[78:79], v[136:137]
	v_lshlrev_b32_e32 v137, 16, v138
	v_and_b32_e32 v138, 0xffff0000, v138
	v_max_f32_e32 v138, v138, v138
	v_max_f32_e32 v138, 0x1e3ce508, v138
	v_max_f32_e32 v137, v137, v137
	v_rcp_f32_e32 v145, v138
	v_lshlrev_b32_e32 v138, 16, v147
	v_max_f32_e32 v137, 0x1e3ce508, v137
	v_max_f32_e32 v138, v138, v138
	v_lshlrev_b32_e32 v136, 16, v146
	v_rcp_f32_e32 v144, v137
	v_and_b32_e32 v137, 0xffff0000, v146
	v_max_f32_e32 v146, 0x1e3ce508, v138
	v_lshlrev_b32_e32 v138, 16, v139
	v_and_b32_e32 v139, 0xffff0000, v139
	v_max_f32_e32 v138, v138, v138
	v_max_f32_e32 v139, v139, v139
	v_max_f32_e32 v138, 0x1e3ce508, v138
	v_max_f32_e32 v139, 0x1e3ce508, v139
	v_rcp_f32_e32 v138, v138
	v_rcp_f32_e32 v139, v139
	v_and_b32_e32 v147, 0xffff0000, v147
	v_max_f32_e32 v136, v136, v136
	v_max_f32_e32 v137, v137, v137
	v_max_f32_e32 v147, v147, v147
	v_max_f32_e32 v136, 0x1e3ce508, v136
	v_max_f32_e32 v137, 0x1e3ce508, v137
	v_max_f32_e32 v147, 0x1e3ce508, v147
	v_pk_mul_f32 v[136:137], v[136:137], v[144:145]
	v_pk_mul_f32 v[138:139], v[146:147], v[138:139]
	v_pk_mul_f32 v[72:73], v[72:73], v[136:137]
	v_pk_mul_f32 v[74:75], v[74:75], v[138:139]
	s_waitcnt vmcnt(0) lgkmcnt(0)
	v_lshlrev_b32_e32 v137, 16, v140
	v_and_b32_e32 v139, 0xffff0000, v140
	v_lshlrev_b32_e32 v140, 16, v149
	v_max_f32_e32 v140, v140, v140
	v_max_f32_e32 v144, 0x1e3ce508, v140
	v_lshlrev_b32_e32 v140, 16, v141
	v_and_b32_e32 v141, 0xffff0000, v141
	v_max_f32_e32 v137, v137, v137
	v_max_f32_e32 v139, v139, v139
	v_max_f32_e32 v140, v140, v140
	v_max_f32_e32 v141, v141, v141
	v_max_f32_e32 v137, 0x1e3ce508, v137
	v_max_f32_e32 v139, 0x1e3ce508, v139
	v_max_f32_e32 v140, 0x1e3ce508, v140
	v_max_f32_e32 v141, 0x1e3ce508, v141
	v_rcp_f32_e32 v138, v137
	v_rcp_f32_e32 v139, v139
	v_rcp_f32_e32 v140, v140
	v_rcp_f32_e32 v141, v141
	v_lshlrev_b32_e32 v136, 16, v148
	v_and_b32_e32 v137, 0xffff0000, v148
	v_and_b32_e32 v145, 0xffff0000, v149
	v_max_f32_e32 v136, v136, v136
	v_max_f32_e32 v137, v137, v137
	v_max_f32_e32 v145, v145, v145
	v_max_f32_e32 v136, 0x1e3ce508, v136
	v_max_f32_e32 v137, 0x1e3ce508, v137
	v_max_f32_e32 v145, 0x1e3ce508, v145
	v_pk_mul_f32 v[136:137], v[136:137], v[138:139]
	v_pk_mul_f32 v[138:139], v[144:145], v[140:141]
	v_pk_mul_f32 v[100:101], v[100:101], v[136:137]
	v_pk_mul_f32 v[102:103], v[102:103], v[138:139]
	v_lshlrev_b32_e32 v137, 16, v142
	v_and_b32_e32 v139, 0xffff0000, v142
	v_max_f32_e32 v137, v137, v137
	v_max_f32_e32 v139, v139, v139
	v_max_f32_e32 v137, 0x1e3ce508, v137
	v_max_f32_e32 v139, 0x1e3ce508, v139
	v_rcp_f32_e32 v138, v137
	v_rcp_f32_e32 v139, v139
	v_lshlrev_b32_e32 v141, 16, v143
	v_and_b32_e32 v143, 0xffff0000, v143
	v_lshlrev_b32_e32 v136, 16, v150
	v_and_b32_e32 v137, 0xffff0000, v150
	v_max_f32_e32 v141, v141, v141
	v_max_f32_e32 v143, v143, v143
	v_max_f32_e32 v136, v136, v136
	v_max_f32_e32 v137, v137, v137
	v_max_f32_e32 v141, 0x1e3ce508, v141
	v_max_f32_e32 v143, 0x1e3ce508, v143
	v_max_f32_e32 v136, 0x1e3ce508, v136
	v_max_f32_e32 v137, 0x1e3ce508, v137
	v_rcp_f32_e32 v142, v141
	v_rcp_f32_e32 v143, v143
	v_lshlrev_b32_e32 v140, 16, v151
	v_and_b32_e32 v141, 0xffff0000, v151
	v_pk_mul_f32 v[136:137], v[136:137], v[138:139]
	v_max_f32_e32 v140, v140, v140
	v_max_f32_e32 v141, v141, v141
	v_pk_mul_f32 v[96:97], v[96:97], v[136:137]
	v_lshlrev_b32_e32 v137, 16, v132
	v_max_f32_e32 v140, 0x1e3ce508, v140
	v_max_f32_e32 v141, 0x1e3ce508, v141
	v_lshlrev_b32_e32 v136, 16, v128
	v_max_f32_e32 v137, v137, v137
	v_and_b32_e32 v128, 0xffff0000, v128
	v_pk_mul_f32 v[138:139], v[140:141], v[142:143]
	v_max_f32_e32 v137, 0x1e3ce508, v137
	v_max_f32_e32 v128, v128, v128
	v_pk_mul_f32 v[98:99], v[98:99], v[138:139]
	v_rcp_f32_e32 v138, v137
	v_max_f32_e32 v137, 0x1e3ce508, v128
	v_and_b32_e32 v128, 0xffff0000, v132
	v_lshlrev_b32_e32 v132, 16, v133
	v_and_b32_e32 v133, 0xffff0000, v133
	v_max_f32_e32 v132, v132, v132
	v_max_f32_e32 v133, v133, v133
	v_max_f32_e32 v128, v128, v128
	v_max_f32_e32 v132, 0x1e3ce508, v132
	v_max_f32_e32 v133, 0x1e3ce508, v133
	v_max_f32_e32 v128, 0x1e3ce508, v128
	v_rcp_f32_e32 v132, v132
	v_rcp_f32_e32 v133, v133
	v_rcp_f32_e32 v139, v128
	v_lshlrev_b32_e32 v128, 16, v129
	v_and_b32_e32 v129, 0xffff0000, v129
	v_max_f32_e32 v128, v128, v128
	v_max_f32_e32 v129, v129, v129
	v_max_f32_e32 v128, 0x1e3ce508, v128
	v_max_f32_e32 v129, 0x1e3ce508, v129
	v_pk_mul_f32 v[128:129], v[128:129], v[132:133]
	v_max_f32_e32 v176, 0x1e3ce508, v176
	v_pk_mul_f32 v[70:71], v[70:71], v[128:129]
	v_lshlrev_b32_e32 v129, 16, v134
	v_max_f32_e32 v129, v129, v129
	v_max_f32_e32 v129, 0x1e3ce508, v129
	v_lshlrev_b32_e32 v128, 16, v130
	v_rcp_f32_e32 v132, v129
	v_and_b32_e32 v129, 0xffff0000, v130
	v_and_b32_e32 v130, 0xffff0000, v134
	v_lshlrev_b32_e32 v134, 16, v135
	v_and_b32_e32 v135, 0xffff0000, v135
	v_max_f32_e32 v134, v134, v134
	v_max_f32_e32 v135, v135, v135
	v_max_f32_e32 v130, v130, v130
	v_max_f32_e32 v134, 0x1e3ce508, v134
	v_max_f32_e32 v135, 0x1e3ce508, v135
	v_max_f32_e32 v130, 0x1e3ce508, v130
	v_rcp_f32_e32 v134, v134
	v_rcp_f32_e32 v135, v135
	v_rcp_f32_e32 v133, v130
	v_lshlrev_b32_e32 v130, 16, v131
	v_and_b32_e32 v131, 0xffff0000, v131
	v_max_f32_e32 v130, v130, v130
	v_max_f32_e32 v131, v131, v131
	v_max_f32_e32 v128, v128, v128
	v_max_f32_e32 v129, v129, v129
	v_max_f32_e32 v130, 0x1e3ce508, v130
	v_max_f32_e32 v131, 0x1e3ce508, v131
	v_max_f32_e32 v128, 0x1e3ce508, v128
	v_max_f32_e32 v129, 0x1e3ce508, v129
	v_pk_mul_f32 v[130:131], v[130:131], v[134:135]
	v_pk_mul_f32 v[128:129], v[128:129], v[132:133]
	v_pk_mul_f32 v[66:67], v[66:67], v[130:131]
	v_add_u32_e32 v130, s77, v202
	v_pk_mul_f32 v[64:65], v[64:65], v[128:129]
	v_mad_i64_i32 v[128:129], vcc, v130, s76, v[212:213]
	v_lshl_add_u64 v[128:129], s[20:21], 0, v[128:129]
	v_add_co_u32_e32 v128, vcc, s78, v128
	v_pk_mul_f32 v[184:185], v[184:185], v[186:187]
	v_pk_mul_f32 v[176:177], v[176:177], v[178:179]
	v_addc_co_u32_e32 v129, vcc, 0, v129, vcc
	v_pk_mul_f32 v[92:93], v[92:93], v[184:185]
	v_pk_mul_f32 v[116:117], v[116:117], v[176:177]
	global_load_dwordx4 v[180:183], v[128:129], off
	global_load_dwordx4 v[176:179], v[128:129], off offset:2048
	global_load_dwordx4 v[188:191], v[128:129], off offset:256
	global_load_dwordx4 v[184:187], v[128:129], off offset:2304
	v_add_u32_e32 v128, 16, v130
	v_mad_i64_i32 v[128:129], vcc, v128, s76, v[212:213]
	v_max_f32_e32 v168, v168, v168
	v_max_f32_e32 v160, v160, v160
	v_lshl_add_u64 v[128:129], s[20:21], 0, v[128:129]
	v_max_f32_e32 v168, 0x1e3ce508, v168
	v_max_f32_e32 v160, 0x1e3ce508, v160
	v_add_co_u32_e32 v128, vcc, s78, v128
	v_pk_mul_f32 v[168:169], v[168:169], v[170:171]
	v_pk_mul_f32 v[160:161], v[160:161], v[162:163]
	v_addc_co_u32_e32 v129, vcc, 0, v129, vcc
	v_pk_mul_f32 v[84:85], v[84:85], v[168:169]
	v_pk_mul_f32 v[108:109], v[108:109], v[160:161]
	global_load_dwordx4 v[172:175], v[128:129], off
	global_load_dwordx4 v[168:171], v[128:129], off offset:2048
	global_load_dwordx4 v[164:167], v[128:129], off offset:256
	global_load_dwordx4 v[160:163], v[128:129], off offset:2304
	v_add_u32_e32 v128, 32, v130
	v_mad_i64_i32 v[128:129], vcc, v128, s76, v[212:213]
	v_max_f32_e32 v205, v205, v205
	v_max_f32_e32 v152, v152, v152
	v_lshl_add_u64 v[128:129], s[20:21], 0, v[128:129]
	v_max_f32_e32 v205, 0x1e3ce508, v205
	v_max_f32_e32 v152, 0x1e3ce508, v152
	v_add_co_u32_e32 v128, vcc, s78, v128
	v_rcp_f32_e32 v244, v205
	v_pk_mul_f32 v[152:153], v[152:153], v[154:155]
	v_addc_co_u32_e32 v129, vcc, 0, v129, vcc
	v_pk_mul_f32 v[76:77], v[76:77], v[152:153]
	global_load_dwordx4 v[156:159], v[128:129], off
	global_load_dwordx4 v[152:155], v[128:129], off offset:2048
	global_load_dwordx4 v[148:151], v[128:129], off offset:256
	global_load_dwordx4 v[144:147], v[128:129], off offset:2304
	v_add_u32_e32 v128, 48, v130
	v_mad_i64_i32 v[128:129], vcc, v128, s76, v[212:213]
	v_pk_mul_f32 v[242:243], v[242:243], v[244:245]
	v_max_f32_e32 v136, v136, v136
	v_pk_mul_f32 v[124:125], v[124:125], v[242:243]
	v_lshl_add_u64 v[128:129], s[20:21], 0, v[128:129]
	v_max_f32_e32 v136, 0x1e3ce508, v136
	v_add_co_u32_e32 v128, vcc, s78, v128
	v_pk_mul_f32 v[136:137], v[136:137], v[138:139]
	s_nop 0
	v_addc_co_u32_e32 v129, vcc, 0, v129, vcc
	v_pk_mul_f32 v[68:69], v[68:69], v[136:137]
	global_load_dwordx4 v[140:143], v[128:129], off
	global_load_dwordx4 v[136:139], v[128:129], off offset:2048
	global_load_dwordx4 v[132:135], v[128:129], off offset:256
	s_nop 0
	global_load_dwordx4 v[128:131], v[128:129], off offset:2304
	s_waitcnt vmcnt(0) lgkmcnt(0)
	v_lshlrev_b32_e32 v202, 16, v180
	v_max_f32_e32 v202, v202, v202
	v_max_f32_e32 v212, 0x1e3ce508, v202
	v_lshlrev_b32_e32 v202, 16, v176
	v_and_b32_e32 v176, 0xffff0000, v176
	v_max_f32_e32 v176, v176, v176
	v_max_f32_e32 v176, 0x1e3ce508, v176
	v_and_b32_e32 v180, 0xffff0000, v180
	v_rcp_f32_e32 v243, v176
	v_lshlrev_b32_e32 v176, 16, v181
	v_max_f32_e32 v180, v180, v180
	v_max_f32_e32 v176, v176, v176
	v_max_f32_e32 v213, 0x1e3ce508, v180
	v_max_f32_e32 v180, 0x1e3ce508, v176
	v_lshlrev_b32_e32 v176, 16, v177
	v_and_b32_e32 v177, 0xffff0000, v177
	v_max_f32_e32 v176, v176, v176
	v_max_f32_e32 v177, v177, v177
	v_max_f32_e32 v176, 0x1e3ce508, v176
	v_max_f32_e32 v177, 0x1e3ce508, v177
	v_rcp_f32_e32 v176, v176
	v_rcp_f32_e32 v177, v177
	v_and_b32_e32 v181, 0xffff0000, v181
	v_max_f32_e32 v181, v181, v181
	v_max_f32_e32 v181, 0x1e3ce508, v181
	v_pk_mul_f32 v[176:177], v[180:181], v[176:177]
	v_max_f32_e32 v202, v202, v202
	v_pk_mul_f32 v[62:63], v[62:63], v[176:177]
	v_lshlrev_b32_e32 v177, 16, v178
	v_and_b32_e32 v178, 0xffff0000, v178
	v_max_f32_e32 v178, v178, v178
	v_max_f32_e32 v178, 0x1e3ce508, v178
	v_max_f32_e32 v177, v177, v177
	v_rcp_f32_e32 v181, v178
	v_lshlrev_b32_e32 v178, 16, v183
	v_max_f32_e32 v177, 0x1e3ce508, v177
	v_max_f32_e32 v178, v178, v178
	v_lshlrev_b32_e32 v176, 16, v182
	v_rcp_f32_e32 v180, v177
	v_and_b32_e32 v177, 0xffff0000, v182
	v_max_f32_e32 v182, 0x1e3ce508, v178
	v_lshlrev_b32_e32 v178, 16, v179
	v_and_b32_e32 v179, 0xffff0000, v179
	v_max_f32_e32 v178, v178, v178
	v_max_f32_e32 v179, v179, v179
	v_max_f32_e32 v178, 0x1e3ce508, v178
	v_max_f32_e32 v179, 0x1e3ce508, v179
	v_rcp_f32_e32 v178, v178
	v_rcp_f32_e32 v179, v179
	v_and_b32_e32 v183, 0xffff0000, v183
	v_max_f32_e32 v176, v176, v176
	v_max_f32_e32 v177, v177, v177
	v_max_f32_e32 v183, v183, v183
	v_max_f32_e32 v176, 0x1e3ce508, v176
	v_max_f32_e32 v177, 0x1e3ce508, v177
	v_max_f32_e32 v183, 0x1e3ce508, v183
	v_pk_mul_f32 v[176:177], v[176:177], v[180:181]
	v_pk_mul_f32 v[178:179], v[182:183], v[178:179]
	v_pk_mul_f32 v[56:57], v[56:57], v[176:177]
	v_pk_mul_f32 v[58:59], v[58:59], v[178:179]
	v_lshlrev_b32_e32 v177, 16, v184
	v_and_b32_e32 v179, 0xffff0000, v184
	v_lshlrev_b32_e32 v181, 16, v185
	v_and_b32_e32 v183, 0xffff0000, v185
	v_max_f32_e32 v177, v177, v177
	v_max_f32_e32 v179, v179, v179
	v_max_f32_e32 v181, v181, v181
	v_max_f32_e32 v183, v183, v183
	v_max_f32_e32 v177, 0x1e3ce508, v177
	v_max_f32_e32 v179, 0x1e3ce508, v179
	v_max_f32_e32 v181, 0x1e3ce508, v181
	v_max_f32_e32 v183, 0x1e3ce508, v183
	v_rcp_f32_e32 v178, v177
	v_rcp_f32_e32 v179, v179
	v_rcp_f32_e32 v182, v181
	v_rcp_f32_e32 v183, v183
	v_lshlrev_b32_e32 v176, 16, v188
	v_and_b32_e32 v177, 0xffff0000, v188
	v_lshlrev_b32_e32 v180, 16, v189
	v_and_b32_e32 v181, 0xffff0000, v189
	v_max_f32_e32 v176, v176, v176
	v_max_f32_e32 v177, v177, v177
	v_max_f32_e32 v180, v180, v180
	v_max_f32_e32 v181, v181, v181
	v_max_f32_e32 v176, 0x1e3ce508, v176
	v_max_f32_e32 v177, 0x1e3ce508, v177
	v_max_f32_e32 v180, 0x1e3ce508, v180
	v_max_f32_e32 v181, 0x1e3ce508, v181
	v_pk_mul_f32 v[176:177], v[176:177], v[178:179]
	v_pk_mul_f32 v[178:179], v[180:181], v[182:183]
	v_pk_mul_f32 v[28:29], v[28:29], v[176:177]
	v_pk_mul_f32 v[30:31], v[30:31], v[178:179]
	v_lshlrev_b32_e32 v177, 16, v186
	v_and_b32_e32 v179, 0xffff0000, v186
	v_max_f32_e32 v177, v177, v177
	v_max_f32_e32 v179, v179, v179
	v_max_f32_e32 v177, 0x1e3ce508, v177
	v_max_f32_e32 v179, 0x1e3ce508, v179
	v_rcp_f32_e32 v178, v177
	v_rcp_f32_e32 v179, v179
	v_lshlrev_b32_e32 v181, 16, v187
	v_and_b32_e32 v183, 0xffff0000, v187
	v_lshlrev_b32_e32 v176, 16, v190
	v_and_b32_e32 v177, 0xffff0000, v190
	v_max_f32_e32 v181, v181, v181
	v_max_f32_e32 v183, v183, v183
	v_max_f32_e32 v176, v176, v176
	v_max_f32_e32 v177, v177, v177
	v_max_f32_e32 v181, 0x1e3ce508, v181
	v_max_f32_e32 v183, 0x1e3ce508, v183
	v_max_f32_e32 v176, 0x1e3ce508, v176
	v_max_f32_e32 v177, 0x1e3ce508, v177
	v_rcp_f32_e32 v182, v181
	v_rcp_f32_e32 v183, v183
	v_lshlrev_b32_e32 v180, 16, v191
	v_and_b32_e32 v181, 0xffff0000, v191
	v_pk_mul_f32 v[176:177], v[176:177], v[178:179]
	v_max_f32_e32 v180, v180, v180
	v_max_f32_e32 v181, v181, v181
	v_pk_mul_f32 v[24:25], v[24:25], v[176:177]
	v_lshlrev_b32_e32 v177, 16, v168
	v_and_b32_e32 v168, 0xffff0000, v168
	v_max_f32_e32 v180, 0x1e3ce508, v180
	v_max_f32_e32 v181, 0x1e3ce508, v181
	v_max_f32_e32 v168, v168, v168
	v_pk_mul_f32 v[178:179], v[180:181], v[182:183]
	v_max_f32_e32 v168, 0x1e3ce508, v168
	v_pk_mul_f32 v[26:27], v[26:27], v[178:179]
	v_lshlrev_b32_e32 v176, 16, v172
	v_max_f32_e32 v177, v177, v177
	v_and_b32_e32 v172, 0xffff0000, v172
	v_rcp_f32_e32 v179, v168
	v_lshlrev_b32_e32 v168, 16, v173
	v_max_f32_e32 v177, 0x1e3ce508, v177
	v_max_f32_e32 v172, v172, v172
	v_max_f32_e32 v168, v168, v168
	v_rcp_f32_e32 v178, v177
	v_max_f32_e32 v177, 0x1e3ce508, v172
	v_max_f32_e32 v172, 0x1e3ce508, v168
	v_lshlrev_b32_e32 v168, 16, v169
	v_and_b32_e32 v169, 0xffff0000, v169
	v_max_f32_e32 v168, v168, v168
	v_max_f32_e32 v169, v169, v169
	v_max_f32_e32 v168, 0x1e3ce508, v168
	v_max_f32_e32 v169, 0x1e3ce508, v169
	v_rcp_f32_e32 v168, v168
	v_rcp_f32_e32 v169, v169
	v_and_b32_e32 v173, 0xffff0000, v173
	v_max_f32_e32 v173, v173, v173
	v_max_f32_e32 v173, 0x1e3ce508, v173
	v_pk_mul_f32 v[168:169], v[172:173], v[168:169]
	v_max_f32_e32 v202, 0x1e3ce508, v202
	v_pk_mul_f32 v[54:55], v[54:55], v[168:169]
	v_lshlrev_b32_e32 v169, 16, v170
	v_and_b32_e32 v170, 0xffff0000, v170
	v_max_f32_e32 v170, v170, v170
	v_max_f32_e32 v170, 0x1e3ce508, v170
	v_max_f32_e32 v169, v169, v169
	v_rcp_f32_e32 v173, v170
	v_lshlrev_b32_e32 v170, 16, v175
	v_max_f32_e32 v169, 0x1e3ce508, v169
	v_max_f32_e32 v170, v170, v170
	v_lshlrev_b32_e32 v168, 16, v174
	v_rcp_f32_e32 v172, v169
	v_and_b32_e32 v169, 0xffff0000, v174
	v_max_f32_e32 v174, 0x1e3ce508, v170
	v_lshlrev_b32_e32 v170, 16, v171
	v_and_b32_e32 v171, 0xffff0000, v171
	v_max_f32_e32 v170, v170, v170
	v_max_f32_e32 v171, v171, v171
	v_max_f32_e32 v168, v168, v168
	v_max_f32_e32 v169, v169, v169
	v_max_f32_e32 v170, 0x1e3ce508, v170
	v_max_f32_e32 v171, 0x1e3ce508, v171
	v_max_f32_e32 v168, 0x1e3ce508, v168
	v_max_f32_e32 v169, 0x1e3ce508, v169
	v_rcp_f32_e32 v170, v170
	v_rcp_f32_e32 v171, v171
	v_and_b32_e32 v175, 0xffff0000, v175
	v_pk_mul_f32 v[168:169], v[168:169], v[172:173]
	v_max_f32_e32 v175, v175, v175
	v_pk_mul_f32 v[48:49], v[48:49], v[168:169]
	v_lshlrev_b32_e32 v169, 16, v160
	v_and_b32_e32 v160, 0xffff0000, v160
	v_max_f32_e32 v175, 0x1e3ce508, v175
	v_max_f32_e32 v160, v160, v160
	v_pk_mul_f32 v[170:171], v[174:175], v[170:171]
	v_max_f32_e32 v160, 0x1e3ce508, v160
	v_pk_mul_f32 v[50:51], v[50:51], v[170:171]
	v_lshlrev_b32_e32 v168, 16, v164
	v_max_f32_e32 v169, v169, v169
	v_and_b32_e32 v164, 0xffff0000, v164
	v_rcp_f32_e32 v171, v160
	v_lshlrev_b32_e32 v160, 16, v165
	v_max_f32_e32 v169, 0x1e3ce508, v169
	v_max_f32_e32 v164, v164, v164
	v_max_f32_e32 v160, v160, v160
	v_rcp_f32_e32 v170, v169
	v_max_f32_e32 v169, 0x1e3ce508, v164
	v_max_f32_e32 v164, 0x1e3ce508, v160
	v_lshlrev_b32_e32 v160, 16, v161
	v_and_b32_e32 v161, 0xffff0000, v161
	v_max_f32_e32 v160, v160, v160
	v_max_f32_e32 v161, v161, v161
	v_max_f32_e32 v160, 0x1e3ce508, v160
	v_max_f32_e32 v161, 0x1e3ce508, v161
	v_rcp_f32_e32 v160, v160
	v_rcp_f32_e32 v161, v161
	v_and_b32_e32 v165, 0xffff0000, v165
	v_max_f32_e32 v165, v165, v165
	v_max_f32_e32 v165, 0x1e3ce508, v165
	v_pk_mul_f32 v[160:161], v[164:165], v[160:161]
	v_rcp_f32_e32 v242, v202
	v_pk_mul_f32 v[22:23], v[22:23], v[160:161]
	v_lshlrev_b32_e32 v161, 16, v162
	v_and_b32_e32 v162, 0xffff0000, v162
	v_max_f32_e32 v162, v162, v162
	v_max_f32_e32 v162, 0x1e3ce508, v162
	v_max_f32_e32 v161, v161, v161
	v_rcp_f32_e32 v165, v162
	v_lshlrev_b32_e32 v162, 16, v167
	v_max_f32_e32 v161, 0x1e3ce508, v161
	v_max_f32_e32 v162, v162, v162
	v_lshlrev_b32_e32 v160, 16, v166
	v_rcp_f32_e32 v164, v161
	v_and_b32_e32 v161, 0xffff0000, v166
	v_max_f32_e32 v166, 0x1e3ce508, v162
	v_lshlrev_b32_e32 v162, 16, v163
	v_and_b32_e32 v163, 0xffff0000, v163
	v_max_f32_e32 v162, v162, v162
	v_max_f32_e32 v163, v163, v163
	v_max_f32_e32 v160, v160, v160
	v_max_f32_e32 v161, v161, v161
	v_max_f32_e32 v162, 0x1e3ce508, v162
	v_max_f32_e32 v163, 0x1e3ce508, v163
	v_max_f32_e32 v160, 0x1e3ce508, v160
	v_max_f32_e32 v161, 0x1e3ce508, v161
	v_rcp_f32_e32 v162, v162
	v_rcp_f32_e32 v163, v163
	v_and_b32_e32 v167, 0xffff0000, v167
	v_pk_mul_f32 v[160:161], v[160:161], v[164:165]
	v_max_f32_e32 v167, v167, v167
	v_pk_mul_f32 v[16:17], v[16:17], v[160:161]
	v_lshlrev_b32_e32 v161, 16, v152
	v_and_b32_e32 v152, 0xffff0000, v152
	v_max_f32_e32 v167, 0x1e3ce508, v167
	v_max_f32_e32 v152, v152, v152
	v_pk_mul_f32 v[162:163], v[166:167], v[162:163]
	v_max_f32_e32 v152, 0x1e3ce508, v152
	v_pk_mul_f32 v[18:19], v[18:19], v[162:163]
	v_lshlrev_b32_e32 v160, 16, v156
	v_max_f32_e32 v161, v161, v161
	v_and_b32_e32 v156, 0xffff0000, v156
	v_rcp_f32_e32 v163, v152
	v_lshlrev_b32_e32 v152, 16, v157
	v_max_f32_e32 v161, 0x1e3ce508, v161
	v_max_f32_e32 v156, v156, v156
	v_max_f32_e32 v152, v152, v152
	v_rcp_f32_e32 v162, v161
	v_max_f32_e32 v161, 0x1e3ce508, v156
	v_max_f32_e32 v156, 0x1e3ce508, v152
	v_lshlrev_b32_e32 v152, 16, v153
	v_and_b32_e32 v153, 0xffff0000, v153
	v_max_f32_e32 v152, v152, v152
	v_max_f32_e32 v153, v153, v153
	v_max_f32_e32 v152, 0x1e3ce508, v152
	v_max_f32_e32 v153, 0x1e3ce508, v153
	v_rcp_f32_e32 v152, v152
	v_rcp_f32_e32 v153, v153
	v_and_b32_e32 v157, 0xffff0000, v157
	v_max_f32_e32 v157, v157, v157
	v_max_f32_e32 v157, 0x1e3ce508, v157
	v_pk_mul_f32 v[152:153], v[156:157], v[152:153]
	v_max_f32_e32 v176, v176, v176
	v_pk_mul_f32 v[46:47], v[46:47], v[152:153]
	v_lshlrev_b32_e32 v153, 16, v154
	v_and_b32_e32 v154, 0xffff0000, v154
	v_max_f32_e32 v154, v154, v154
	v_max_f32_e32 v154, 0x1e3ce508, v154
	v_max_f32_e32 v153, v153, v153
	v_rcp_f32_e32 v157, v154
	v_lshlrev_b32_e32 v154, 16, v159
	v_max_f32_e32 v153, 0x1e3ce508, v153
	v_max_f32_e32 v154, v154, v154
	v_lshlrev_b32_e32 v152, 16, v158
	v_rcp_f32_e32 v156, v153
	v_and_b32_e32 v153, 0xffff0000, v158
	v_max_f32_e32 v158, 0x1e3ce508, v154
	v_lshlrev_b32_e32 v154, 16, v155
	v_and_b32_e32 v155, 0xffff0000, v155
	v_max_f32_e32 v154, v154, v154
	v_max_f32_e32 v155, v155, v155
	v_max_f32_e32 v152, v152, v152
	v_max_f32_e32 v153, v153, v153
	v_max_f32_e32 v154, 0x1e3ce508, v154
	v_max_f32_e32 v155, 0x1e3ce508, v155
	v_max_f32_e32 v152, 0x1e3ce508, v152
	v_max_f32_e32 v153, 0x1e3ce508, v153
	v_rcp_f32_e32 v154, v154
	v_rcp_f32_e32 v155, v155
	v_and_b32_e32 v159, 0xffff0000, v159
	v_pk_mul_f32 v[152:153], v[152:153], v[156:157]
	v_max_f32_e32 v159, v159, v159
	v_pk_mul_f32 v[40:41], v[40:41], v[152:153]
	v_lshlrev_b32_e32 v153, 16, v144
	v_and_b32_e32 v144, 0xffff0000, v144
	v_max_f32_e32 v159, 0x1e3ce508, v159
	v_max_f32_e32 v144, v144, v144
	v_pk_mul_f32 v[154:155], v[158:159], v[154:155]
	v_max_f32_e32 v144, 0x1e3ce508, v144
	v_pk_mul_f32 v[42:43], v[42:43], v[154:155]
	v_lshlrev_b32_e32 v152, 16, v148
	v_max_f32_e32 v153, v153, v153
	v_and_b32_e32 v148, 0xffff0000, v148
	v_rcp_f32_e32 v155, v144
	v_lshlrev_b32_e32 v144, 16, v149
	v_max_f32_e32 v153, 0x1e3ce508, v153
	v_max_f32_e32 v148, v148, v148
	v_max_f32_e32 v144, v144, v144
	v_rcp_f32_e32 v154, v153
	v_max_f32_e32 v153, 0x1e3ce508, v148
	v_max_f32_e32 v148, 0x1e3ce508, v144
	v_lshlrev_b32_e32 v144, 16, v145
	v_and_b32_e32 v145, 0xffff0000, v145
	v_max_f32_e32 v144, v144, v144
	v_max_f32_e32 v145, v145, v145
	v_max_f32_e32 v144, 0x1e3ce508, v144
	v_max_f32_e32 v145, 0x1e3ce508, v145
	v_rcp_f32_e32 v144, v144
	v_rcp_f32_e32 v145, v145
	v_and_b32_e32 v149, 0xffff0000, v149
	v_max_f32_e32 v149, v149, v149
	v_max_f32_e32 v149, 0x1e3ce508, v149
	v_pk_mul_f32 v[144:145], v[148:149], v[144:145]
	v_max_f32_e32 v168, v168, v168
	v_pk_mul_f32 v[14:15], v[14:15], v[144:145]
	v_lshlrev_b32_e32 v145, 16, v146
	v_and_b32_e32 v146, 0xffff0000, v146
	v_max_f32_e32 v146, v146, v146
	v_max_f32_e32 v146, 0x1e3ce508, v146
	v_max_f32_e32 v145, v145, v145
	v_rcp_f32_e32 v149, v146
	v_lshlrev_b32_e32 v146, 16, v151
	v_max_f32_e32 v145, 0x1e3ce508, v145
	v_max_f32_e32 v146, v146, v146
	v_lshlrev_b32_e32 v144, 16, v150
	v_rcp_f32_e32 v148, v145
	v_and_b32_e32 v145, 0xffff0000, v150
	v_max_f32_e32 v150, 0x1e3ce508, v146
	v_lshlrev_b32_e32 v146, 16, v147
	v_and_b32_e32 v147, 0xffff0000, v147
	v_max_f32_e32 v146, v146, v146
	v_max_f32_e32 v147, v147, v147
	v_max_f32_e32 v144, v144, v144
	v_max_f32_e32 v145, v145, v145
	v_max_f32_e32 v146, 0x1e3ce508, v146
	v_max_f32_e32 v147, 0x1e3ce508, v147
	v_max_f32_e32 v144, 0x1e3ce508, v144
	v_max_f32_e32 v145, 0x1e3ce508, v145
	v_rcp_f32_e32 v146, v146
	v_rcp_f32_e32 v147, v147
	v_and_b32_e32 v151, 0xffff0000, v151
	v_pk_mul_f32 v[144:145], v[144:145], v[148:149]
	v_max_f32_e32 v151, v151, v151
	v_pk_mul_f32 v[8:9], v[8:9], v[144:145]
	v_lshlrev_b32_e32 v145, 16, v136
	v_and_b32_e32 v136, 0xffff0000, v136
	v_max_f32_e32 v151, 0x1e3ce508, v151
	v_max_f32_e32 v136, v136, v136
	v_pk_mul_f32 v[146:147], v[150:151], v[146:147]
	v_max_f32_e32 v136, 0x1e3ce508, v136
	v_pk_mul_f32 v[10:11], v[10:11], v[146:147]
	v_lshlrev_b32_e32 v144, 16, v140
	v_max_f32_e32 v145, v145, v145
	v_and_b32_e32 v140, 0xffff0000, v140
	v_rcp_f32_e32 v147, v136
	v_lshlrev_b32_e32 v136, 16, v141
	v_max_f32_e32 v145, 0x1e3ce508, v145
	v_max_f32_e32 v140, v140, v140
	v_max_f32_e32 v136, v136, v136
	v_rcp_f32_e32 v146, v145
	v_max_f32_e32 v145, 0x1e3ce508, v140
	v_max_f32_e32 v140, 0x1e3ce508, v136
	v_lshlrev_b32_e32 v136, 16, v137
	v_and_b32_e32 v137, 0xffff0000, v137
	v_max_f32_e32 v136, v136, v136
	v_max_f32_e32 v137, v137, v137
	v_max_f32_e32 v136, 0x1e3ce508, v136
	v_max_f32_e32 v137, 0x1e3ce508, v137
	v_rcp_f32_e32 v136, v136
	v_rcp_f32_e32 v137, v137
	v_and_b32_e32 v141, 0xffff0000, v141
	v_max_f32_e32 v141, v141, v141
	v_max_f32_e32 v141, 0x1e3ce508, v141
	v_pk_mul_f32 v[136:137], v[140:141], v[136:137]
	v_max_f32_e32 v160, v160, v160
	v_pk_mul_f32 v[38:39], v[38:39], v[136:137]
	v_lshlrev_b32_e32 v137, 16, v138
	v_and_b32_e32 v138, 0xffff0000, v138
	v_max_f32_e32 v138, v138, v138
	v_max_f32_e32 v138, 0x1e3ce508, v138
	v_max_f32_e32 v137, v137, v137
	v_rcp_f32_e32 v141, v138
	v_lshlrev_b32_e32 v138, 16, v143
	v_max_f32_e32 v137, 0x1e3ce508, v137
	v_max_f32_e32 v138, v138, v138
	v_lshlrev_b32_e32 v136, 16, v142
	v_rcp_f32_e32 v140, v137
	v_and_b32_e32 v137, 0xffff0000, v142
	v_max_f32_e32 v142, 0x1e3ce508, v138
	v_lshlrev_b32_e32 v138, 16, v139
	v_and_b32_e32 v139, 0xffff0000, v139
	v_max_f32_e32 v138, v138, v138
	v_max_f32_e32 v139, v139, v139
	v_max_f32_e32 v136, v136, v136
	v_max_f32_e32 v137, v137, v137
	v_max_f32_e32 v138, 0x1e3ce508, v138
	v_max_f32_e32 v139, 0x1e3ce508, v139
	v_max_f32_e32 v136, 0x1e3ce508, v136
	v_max_f32_e32 v137, 0x1e3ce508, v137
	v_rcp_f32_e32 v138, v138
	v_rcp_f32_e32 v139, v139
	v_and_b32_e32 v143, 0xffff0000, v143
	v_pk_mul_f32 v[136:137], v[136:137], v[140:141]
	v_max_f32_e32 v143, v143, v143
	v_pk_mul_f32 v[32:33], v[32:33], v[136:137]
	v_lshlrev_b32_e32 v137, 16, v128
	v_and_b32_e32 v128, 0xffff0000, v128
	v_max_f32_e32 v143, 0x1e3ce508, v143
	v_max_f32_e32 v128, v128, v128
	v_pk_mul_f32 v[138:139], v[142:143], v[138:139]
	v_max_f32_e32 v128, 0x1e3ce508, v128
	v_pk_mul_f32 v[34:35], v[34:35], v[138:139]
	v_lshlrev_b32_e32 v136, 16, v132
	v_max_f32_e32 v137, v137, v137
	v_and_b32_e32 v132, 0xffff0000, v132
	v_rcp_f32_e32 v139, v128
	v_lshlrev_b32_e32 v128, 16, v133
	v_max_f32_e32 v137, 0x1e3ce508, v137
	v_max_f32_e32 v132, v132, v132
	v_max_f32_e32 v128, v128, v128
	v_rcp_f32_e32 v138, v137
	v_max_f32_e32 v137, 0x1e3ce508, v132
	v_max_f32_e32 v132, 0x1e3ce508, v128
	v_lshlrev_b32_e32 v128, 16, v129
	v_and_b32_e32 v129, 0xffff0000, v129
	v_max_f32_e32 v128, v128, v128
	v_max_f32_e32 v129, v129, v129
	v_max_f32_e32 v128, 0x1e3ce508, v128
	v_max_f32_e32 v129, 0x1e3ce508, v129
	v_rcp_f32_e32 v128, v128
	v_rcp_f32_e32 v129, v129
	v_and_b32_e32 v133, 0xffff0000, v133
	v_max_f32_e32 v133, v133, v133
	v_max_f32_e32 v133, 0x1e3ce508, v133
	v_pk_mul_f32 v[128:129], v[132:133], v[128:129]
	v_max_f32_e32 v152, v152, v152
	v_pk_mul_f32 v[6:7], v[6:7], v[128:129]
	v_lshlrev_b32_e32 v129, 16, v130
	v_and_b32_e32 v130, 0xffff0000, v130
	v_max_f32_e32 v130, v130, v130
	v_max_f32_e32 v130, 0x1e3ce508, v130
	v_max_f32_e32 v129, v129, v129
	v_rcp_f32_e32 v133, v130
	v_lshlrev_b32_e32 v130, 16, v135
	v_max_f32_e32 v129, 0x1e3ce508, v129
	v_max_f32_e32 v130, v130, v130
	v_lshlrev_b32_e32 v128, 16, v134
	v_rcp_f32_e32 v132, v129
	v_and_b32_e32 v129, 0xffff0000, v134
	v_max_f32_e32 v134, 0x1e3ce508, v130
	v_lshlrev_b32_e32 v130, 16, v131
	v_and_b32_e32 v131, 0xffff0000, v131
	v_max_f32_e32 v130, v130, v130
	v_max_f32_e32 v131, v131, v131
	v_max_f32_e32 v130, 0x1e3ce508, v130
	v_max_f32_e32 v131, 0x1e3ce508, v131
	v_rcp_f32_e32 v130, v130
	v_rcp_f32_e32 v131, v131
	v_and_b32_e32 v135, 0xffff0000, v135
	v_max_f32_e32 v144, v144, v144
	v_max_f32_e32 v136, v136, v136
	v_max_f32_e32 v128, v128, v128
	v_max_f32_e32 v129, v129, v129
	v_max_f32_e32 v135, v135, v135
	v_max_f32_e32 v176, 0x1e3ce508, v176
	v_max_f32_e32 v168, 0x1e3ce508, v168
	v_max_f32_e32 v160, 0x1e3ce508, v160
	v_max_f32_e32 v152, 0x1e3ce508, v152
	v_max_f32_e32 v144, 0x1e3ce508, v144
	v_max_f32_e32 v136, 0x1e3ce508, v136
	v_max_f32_e32 v128, 0x1e3ce508, v128
	v_max_f32_e32 v129, 0x1e3ce508, v129
	v_max_f32_e32 v135, 0x1e3ce508, v135
	v_pk_mul_f32 v[212:213], v[212:213], v[242:243]
	v_pk_mul_f32 v[176:177], v[176:177], v[178:179]
	v_pk_mul_f32 v[168:169], v[168:169], v[170:171]
	v_pk_mul_f32 v[160:161], v[160:161], v[162:163]
	v_pk_mul_f32 v[152:153], v[152:153], v[154:155]
	v_pk_mul_f32 v[144:145], v[144:145], v[146:147]
	v_pk_mul_f32 v[136:137], v[136:137], v[138:139]
	v_pk_mul_f32 v[128:129], v[128:129], v[132:133]
	v_pk_mul_f32 v[130:131], v[134:135], v[130:131]
	v_pk_mul_f32 v[60:61], v[60:61], v[212:213]
	v_pk_mul_f32 v[52:53], v[52:53], v[176:177]
	v_pk_mul_f32 v[20:21], v[20:21], v[168:169]
	v_pk_mul_f32 v[44:45], v[44:45], v[160:161]
	v_pk_mul_f32 v[12:13], v[12:13], v[152:153]
	v_pk_mul_f32 v[36:37], v[36:37], v[144:145]
	v_pk_mul_f32 v[4:5], v[4:5], v[136:137]
	v_pk_mul_f32 v[2:3], v[2:3], v[130:131]
	v_pk_mul_f32 v[0:1], v[0:1], v[128:129]
	s_branch .LBB0_1050

.LBB0_1055:
	v_mov_b32_e32 v174, v198
	v_mov_b32_e32 v172, v194
	s_mov_b64 s[20:21], -1
	s_mov_b64 s[50:51], 0
	s_cmp_lt_i32 s28, 8
	s_mov_b64 s[30:31], 0
	s_cbranch_scc1 .LBB0_1086
	s_cmp_gt_i32 s28, 8
	s_cbranch_scc0 .LBB0_1156
	s_cmp_eq_u32 s28, 9
	s_mov_b64 s[30:31], -1
	s_cbranch_scc0 .LBB0_1059
	v_readlane_b32 s16, v254, 27
	s_add_u32 s16, s16, s0
	v_readlane_b32 s17, v254, 29
	v_ashrrev_i32_e32 v175, 31, v174
	s_addc_u32 s17, s17, s1
	v_lshlrev_b64 v[156:157], 1, v[174:175]
	v_lshl_add_u64 v[160:161], s[16:17], 0, v[156:157]
	v_add_u32_e32 v158, s63, v172
	v_mad_i64_i32 v[128:129], s[16:17], v158, s76, v[160:161]
	global_load_dwordx4 v[176:179], v[128:129], off
	global_load_dwordx4 v[152:155], v[128:129], off offset:256
	v_add_u32_e32 v166, 16, v158
	v_mad_i64_i32 v[128:129], s[16:17], v166, s76, v[160:161]
	global_load_dwordx4 v[148:151], v[128:129], off
	global_load_dwordx4 v[144:147], v[128:129], off offset:256
	v_add_u32_e32 v164, 32, v158
	v_mad_i64_i32 v[128:129], s[16:17], v164, s76, v[160:161]
	global_load_dwordx4 v[140:143], v[128:129], off
	global_load_dwordx4 v[136:139], v[128:129], off offset:256
	v_ashrrev_i32_e32 v159, 31, v158
	v_lshlrev_b64 v[168:169], 11, v[158:159]
	v_add_u32_e32 v162, 48, v158
	v_mad_i64_i32 v[128:129], s[16:17], v162, s76, v[160:161]
	global_load_dwordx4 v[132:135], v[128:129], off
	s_nop 0
	global_load_dwordx4 v[128:131], v[128:129], off offset:256
	v_lshl_add_u64 v[168:169], s[22:23], 0, v[168:169]
	v_lshl_add_u64 v[168:169], v[168:169], 0, s[0:1]
	v_lshl_add_u64 v[168:169], v[168:169], 0, v[156:157]
	v_ashrrev_i32_e32 v167, 31, v166
	v_ashrrev_i32_e32 v165, 31, v164
	v_ashrrev_i32_e32 v163, 31, v162
	s_mov_b64 s[30:31], 0
	s_waitcnt vmcnt(0) lgkmcnt(0)
	v_lshlrev_b32_e32 v159, 16, v176
	v_max_f32_e32 v159, v159, v159
	v_max_f32_e32 v170, 0x1e3ce508, v159
	v_and_b32_e32 v159, 0xffff0000, v176
	v_max_f32_e32 v159, v159, v159
	v_max_f32_e32 v171, 0x1e3ce508, v159
	v_lshlrev_b32_e32 v159, 16, v177
	v_pk_mul_f32 v[170:171], v[124:125], v[170:171]
	v_max_f32_e32 v159, v159, v159
	v_cvt_pk_bf16_f32 v176, v170, v171
	v_max_f32_e32 v170, 0x1e3ce508, v159
	v_and_b32_e32 v159, 0xffff0000, v177
	v_max_f32_e32 v159, v159, v159
	v_max_f32_e32 v171, 0x1e3ce508, v159
	v_lshlrev_b32_e32 v159, 16, v178
	v_pk_mul_f32 v[170:171], v[126:127], v[170:171]
	v_max_f32_e32 v159, v159, v159
	v_cvt_pk_bf16_f32 v177, v170, v171
	v_max_f32_e32 v170, 0x1e3ce508, v159
	v_and_b32_e32 v159, 0xffff0000, v178
	v_max_f32_e32 v159, v159, v159
	v_max_f32_e32 v171, 0x1e3ce508, v159
	v_lshlrev_b32_e32 v159, 16, v179
	v_pk_mul_f32 v[170:171], v[120:121], v[170:171]
	v_max_f32_e32 v159, v159, v159
	v_cvt_pk_bf16_f32 v178, v170, v171
	v_max_f32_e32 v170, 0x1e3ce508, v159
	v_and_b32_e32 v159, 0xffff0000, v179
	v_max_f32_e32 v159, v159, v159
	v_max_f32_e32 v171, 0x1e3ce508, v159
	v_lshlrev_b32_e32 v159, 16, v152
	v_and_b32_e32 v152, 0xffff0000, v152
	v_pk_mul_f32 v[170:171], v[122:123], v[170:171]
	v_max_f32_e32 v159, v159, v159
	v_max_f32_e32 v152, v152, v152
	v_cvt_pk_bf16_f32 v179, v170, v171
	v_max_f32_e32 v170, 0x1e3ce508, v159
	v_max_f32_e32 v171, 0x1e3ce508, v152
	v_lshlrev_b32_e32 v159, 16, v153
	v_and_b32_e32 v153, 0xffff0000, v153
	v_pk_mul_f32 v[170:171], v[92:93], v[170:171]
	v_max_f32_e32 v159, v159, v159
	v_max_f32_e32 v153, v153, v153
	v_cvt_pk_bf16_f32 v152, v170, v171
	v_max_f32_e32 v170, 0x1e3ce508, v159
	v_max_f32_e32 v171, 0x1e3ce508, v153
	v_lshlrev_b32_e32 v159, 16, v154
	v_and_b32_e32 v154, 0xffff0000, v154
	v_pk_mul_f32 v[170:171], v[94:95], v[170:171]
	v_max_f32_e32 v159, v159, v159
	v_max_f32_e32 v154, v154, v154
	v_cvt_pk_bf16_f32 v153, v170, v171
	v_max_f32_e32 v170, 0x1e3ce508, v159
	v_max_f32_e32 v171, 0x1e3ce508, v154
	v_lshlrev_b32_e32 v159, 16, v155
	v_and_b32_e32 v155, 0xffff0000, v155
	v_pk_mul_f32 v[170:171], v[88:89], v[170:171]
	v_max_f32_e32 v159, v159, v159
	v_max_f32_e32 v155, v155, v155
	v_cvt_pk_bf16_f32 v154, v170, v171
	v_max_f32_e32 v170, 0x1e3ce508, v159
	v_max_f32_e32 v171, 0x1e3ce508, v155
	v_pk_mul_f32 v[170:171], v[90:91], v[170:171]
	global_store_dwordx4 v[168:169], v[176:179], off
	v_cvt_pk_bf16_f32 v155, v170, v171
	global_store_dwordx4 v[168:169], v[152:155], off offset:256
	s_nop 1
	v_lshlrev_b32_e32 v154, 16, v148
	v_and_b32_e32 v148, 0xffff0000, v148
	v_max_f32_e32 v154, v154, v154
	v_max_f32_e32 v148, v148, v148
	v_max_f32_e32 v154, 0x1e3ce508, v154
	v_max_f32_e32 v155, 0x1e3ce508, v148
	v_pk_mul_f32 v[154:155], v[116:117], v[154:155]
	v_lshlrev_b64 v[152:153], 11, v[166:167]
	v_cvt_pk_bf16_f32 v148, v154, v155
	v_lshlrev_b32_e32 v154, 16, v149
	v_and_b32_e32 v149, 0xffff0000, v149
	v_max_f32_e32 v154, v154, v154
	v_max_f32_e32 v149, v149, v149
	v_max_f32_e32 v154, 0x1e3ce508, v154
	v_max_f32_e32 v155, 0x1e3ce508, v149
	v_pk_mul_f32 v[154:155], v[118:119], v[154:155]
	v_lshl_add_u64 v[152:153], s[22:23], 0, v[152:153]
	v_cvt_pk_bf16_f32 v149, v154, v155
	v_lshlrev_b32_e32 v154, 16, v150
	v_and_b32_e32 v150, 0xffff0000, v150
	v_max_f32_e32 v154, v154, v154
	v_max_f32_e32 v150, v150, v150
	v_max_f32_e32 v154, 0x1e3ce508, v154
	v_max_f32_e32 v155, 0x1e3ce508, v150
	v_pk_mul_f32 v[154:155], v[112:113], v[154:155]
	v_lshl_add_u64 v[152:153], v[152:153], 0, s[0:1]
	v_cvt_pk_bf16_f32 v150, v154, v155
	v_lshlrev_b32_e32 v154, 16, v151
	v_and_b32_e32 v151, 0xffff0000, v151
	v_max_f32_e32 v154, v154, v154
	v_max_f32_e32 v151, v151, v151
	v_max_f32_e32 v154, 0x1e3ce508, v154
	v_max_f32_e32 v155, 0x1e3ce508, v151
	v_pk_mul_f32 v[154:155], v[114:115], v[154:155]
	v_lshl_add_u64 v[152:153], v[152:153], 0, v[156:157]
	v_cvt_pk_bf16_f32 v151, v154, v155
	global_store_dwordx4 v[152:153], v[148:151], off
	v_add_u32_e32 v166, s77, v172
	v_ashrrev_i32_e32 v167, 31, v166
	v_lshlrev_b32_e32 v148, 16, v144
	v_and_b32_e32 v144, 0xffff0000, v144
	v_max_f32_e32 v148, v148, v148
	v_max_f32_e32 v144, v144, v144
	v_max_f32_e32 v148, 0x1e3ce508, v148
	v_max_f32_e32 v149, 0x1e3ce508, v144
	v_pk_mul_f32 v[148:149], v[84:85], v[148:149]
	s_nop 0
	v_cvt_pk_bf16_f32 v144, v148, v149
	v_lshlrev_b32_e32 v148, 16, v145
	v_and_b32_e32 v145, 0xffff0000, v145
	v_max_f32_e32 v148, v148, v148
	v_max_f32_e32 v145, v145, v145
	v_max_f32_e32 v148, 0x1e3ce508, v148
	v_max_f32_e32 v149, 0x1e3ce508, v145
	v_pk_mul_f32 v[148:149], v[86:87], v[148:149]
	s_nop 0
	v_cvt_pk_bf16_f32 v145, v148, v149
	v_lshlrev_b32_e32 v148, 16, v146
	v_and_b32_e32 v146, 0xffff0000, v146
	v_max_f32_e32 v148, v148, v148
	v_max_f32_e32 v146, v146, v146
	v_max_f32_e32 v148, 0x1e3ce508, v148
	v_max_f32_e32 v149, 0x1e3ce508, v146
	v_pk_mul_f32 v[148:149], v[80:81], v[148:149]
	s_nop 0
	v_cvt_pk_bf16_f32 v146, v148, v149
	v_lshlrev_b32_e32 v148, 16, v147
	v_and_b32_e32 v147, 0xffff0000, v147
	v_max_f32_e32 v148, v148, v148
	v_max_f32_e32 v147, v147, v147
	v_max_f32_e32 v148, 0x1e3ce508, v148
	v_max_f32_e32 v149, 0x1e3ce508, v147
	v_pk_mul_f32 v[148:149], v[82:83], v[148:149]
	s_nop 0
	v_cvt_pk_bf16_f32 v147, v148, v149
	global_store_dwordx4 v[152:153], v[144:147], off offset:256
	s_nop 1
	v_lshlrev_b32_e32 v146, 16, v140
	v_and_b32_e32 v140, 0xffff0000, v140
	v_max_f32_e32 v146, v146, v146
	v_max_f32_e32 v140, v140, v140
	v_max_f32_e32 v146, 0x1e3ce508, v146
	v_max_f32_e32 v147, 0x1e3ce508, v140
	v_pk_mul_f32 v[146:147], v[108:109], v[146:147]
	v_lshlrev_b64 v[144:145], 11, v[164:165]
	v_cvt_pk_bf16_f32 v140, v146, v147
	v_lshlrev_b32_e32 v146, 16, v141
	v_and_b32_e32 v141, 0xffff0000, v141
	v_max_f32_e32 v146, v146, v146
	v_max_f32_e32 v141, v141, v141
	v_max_f32_e32 v146, 0x1e3ce508, v146
	v_max_f32_e32 v147, 0x1e3ce508, v141
	v_pk_mul_f32 v[146:147], v[110:111], v[146:147]
	v_lshl_add_u64 v[144:145], s[22:23], 0, v[144:145]
	v_cvt_pk_bf16_f32 v141, v146, v147
	v_lshlrev_b32_e32 v146, 16, v142
	v_and_b32_e32 v142, 0xffff0000, v142
	v_max_f32_e32 v146, v146, v146
	v_max_f32_e32 v142, v142, v142
	v_max_f32_e32 v146, 0x1e3ce508, v146
	v_max_f32_e32 v147, 0x1e3ce508, v142
	v_pk_mul_f32 v[146:147], v[104:105], v[146:147]
	v_lshl_add_u64 v[144:145], v[144:145], 0, s[0:1]
	v_cvt_pk_bf16_f32 v142, v146, v147
	v_lshlrev_b32_e32 v146, 16, v143
	v_and_b32_e32 v143, 0xffff0000, v143
	v_max_f32_e32 v146, v146, v146
	v_max_f32_e32 v143, v143, v143
	v_max_f32_e32 v146, 0x1e3ce508, v146
	v_max_f32_e32 v147, 0x1e3ce508, v143
	v_pk_mul_f32 v[146:147], v[106:107], v[146:147]
	v_lshl_add_u64 v[144:145], v[144:145], 0, v[156:157]
	v_cvt_pk_bf16_f32 v143, v146, v147
	global_store_dwordx4 v[144:145], v[140:143], off
	s_nop 1
	v_lshlrev_b32_e32 v140, 16, v136
	v_and_b32_e32 v136, 0xffff0000, v136
	v_max_f32_e32 v140, v140, v140
	v_max_f32_e32 v136, v136, v136
	v_max_f32_e32 v140, 0x1e3ce508, v140
	v_max_f32_e32 v141, 0x1e3ce508, v136
	v_pk_mul_f32 v[140:141], v[76:77], v[140:141]
	s_nop 0
	v_cvt_pk_bf16_f32 v136, v140, v141
	v_lshlrev_b32_e32 v140, 16, v137
	v_and_b32_e32 v137, 0xffff0000, v137
	v_max_f32_e32 v140, v140, v140
	v_max_f32_e32 v137, v137, v137
	v_max_f32_e32 v140, 0x1e3ce508, v140
	v_max_f32_e32 v141, 0x1e3ce508, v137
	v_pk_mul_f32 v[140:141], v[78:79], v[140:141]
	s_nop 0
	v_cvt_pk_bf16_f32 v137, v140, v141
	v_lshlrev_b32_e32 v140, 16, v138
	v_and_b32_e32 v138, 0xffff0000, v138
	v_max_f32_e32 v140, v140, v140
	v_max_f32_e32 v138, v138, v138
	v_max_f32_e32 v140, 0x1e3ce508, v140
	v_max_f32_e32 v141, 0x1e3ce508, v138
	v_pk_mul_f32 v[140:141], v[72:73], v[140:141]
	s_nop 0
	v_cvt_pk_bf16_f32 v138, v140, v141
	v_lshlrev_b32_e32 v140, 16, v139
	v_and_b32_e32 v139, 0xffff0000, v139
	v_max_f32_e32 v140, v140, v140
	v_max_f32_e32 v139, v139, v139
	v_max_f32_e32 v140, 0x1e3ce508, v140
	v_max_f32_e32 v141, 0x1e3ce508, v139
	v_pk_mul_f32 v[140:141], v[74:75], v[140:141]
	s_nop 0
	v_cvt_pk_bf16_f32 v139, v140, v141
	global_store_dwordx4 v[144:145], v[136:139], off offset:256
	s_nop 1
	v_lshlrev_b32_e32 v138, 16, v132
	v_and_b32_e32 v132, 0xffff0000, v132
	v_max_f32_e32 v138, v138, v138
	v_max_f32_e32 v132, v132, v132
	v_max_f32_e32 v138, 0x1e3ce508, v138
	v_max_f32_e32 v139, 0x1e3ce508, v132
	v_pk_mul_f32 v[138:139], v[100:101], v[138:139]
	v_lshlrev_b64 v[136:137], 11, v[162:163]
	v_cvt_pk_bf16_f32 v132, v138, v139
	v_lshlrev_b32_e32 v138, 16, v133
	v_and_b32_e32 v133, 0xffff0000, v133
	v_max_f32_e32 v138, v138, v138
	v_max_f32_e32 v133, v133, v133
	v_max_f32_e32 v138, 0x1e3ce508, v138
	v_max_f32_e32 v139, 0x1e3ce508, v133
	v_pk_mul_f32 v[138:139], v[102:103], v[138:139]
	v_lshl_add_u64 v[136:137], s[22:23], 0, v[136:137]
	v_cvt_pk_bf16_f32 v133, v138, v139
	v_lshlrev_b32_e32 v138, 16, v134
	v_and_b32_e32 v134, 0xffff0000, v134
	v_max_f32_e32 v138, v138, v138
	v_max_f32_e32 v134, v134, v134
	v_max_f32_e32 v138, 0x1e3ce508, v138
	v_max_f32_e32 v139, 0x1e3ce508, v134
	v_pk_mul_f32 v[138:139], v[96:97], v[138:139]
	v_lshl_add_u64 v[136:137], v[136:137], 0, s[0:1]
	v_cvt_pk_bf16_f32 v134, v138, v139
	v_lshlrev_b32_e32 v138, 16, v135
	v_and_b32_e32 v135, 0xffff0000, v135
	v_max_f32_e32 v138, v138, v138
	v_max_f32_e32 v135, v135, v135
	v_max_f32_e32 v138, 0x1e3ce508, v138
	v_max_f32_e32 v139, 0x1e3ce508, v135
	v_pk_mul_f32 v[138:139], v[98:99], v[138:139]
	v_lshl_add_u64 v[136:137], v[136:137], 0, v[156:157]
	v_cvt_pk_bf16_f32 v135, v138, v139
	global_store_dwordx4 v[136:137], v[132:135], off
	s_nop 1
	v_lshlrev_b32_e32 v132, 16, v128
	v_and_b32_e32 v128, 0xffff0000, v128
	v_max_f32_e32 v132, v132, v132
	v_max_f32_e32 v128, v128, v128
	v_max_f32_e32 v132, 0x1e3ce508, v132
	v_max_f32_e32 v133, 0x1e3ce508, v128
	v_pk_mul_f32 v[132:133], v[68:69], v[132:133]
	s_nop 0
	v_cvt_pk_bf16_f32 v128, v132, v133
	v_lshlrev_b32_e32 v132, 16, v129
	v_and_b32_e32 v129, 0xffff0000, v129
	v_max_f32_e32 v132, v132, v132
	v_max_f32_e32 v129, v129, v129
	v_max_f32_e32 v132, 0x1e3ce508, v132
	v_max_f32_e32 v133, 0x1e3ce508, v129
	v_pk_mul_f32 v[132:133], v[70:71], v[132:133]
	s_nop 0
	v_cvt_pk_bf16_f32 v129, v132, v133
	v_lshlrev_b32_e32 v132, 16, v130
	v_and_b32_e32 v130, 0xffff0000, v130
	v_max_f32_e32 v132, v132, v132
	v_max_f32_e32 v130, v130, v130
	v_max_f32_e32 v132, 0x1e3ce508, v132
	v_max_f32_e32 v133, 0x1e3ce508, v130
	v_pk_mul_f32 v[132:133], v[64:65], v[132:133]
	s_nop 0
	v_cvt_pk_bf16_f32 v130, v132, v133
	v_lshlrev_b32_e32 v132, 16, v131
	v_and_b32_e32 v131, 0xffff0000, v131
	v_max_f32_e32 v132, v132, v132
	v_max_f32_e32 v131, v131, v131
	v_max_f32_e32 v132, 0x1e3ce508, v132
	v_max_f32_e32 v133, 0x1e3ce508, v131
	v_pk_mul_f32 v[132:133], v[66:67], v[132:133]
	s_nop 0
	v_cvt_pk_bf16_f32 v131, v132, v133
	global_store_dwordx4 v[136:137], v[128:131], off offset:256
	s_nop 1
	v_mad_i64_i32 v[128:129], s[16:17], v166, s76, v[160:161]
	global_load_dwordx4 v[144:147], v[128:129], off
	global_load_dwordx4 v[148:151], v[128:129], off offset:256
	v_add_u32_e32 v128, 16, v166
	v_mad_i64_i32 v[128:129], s[16:17], v128, s76, v[160:161]
	global_load_dwordx4 v[152:155], v[128:129], off
	global_load_dwordx4 v[162:165], v[128:129], off offset:256
	v_add_u32_e32 v128, 32, v166
	v_mad_i64_i32 v[128:129], s[16:17], v128, s76, v[160:161]
	global_load_dwordx4 v[140:143], v[128:129], off
	global_load_dwordx4 v[136:139], v[128:129], off offset:256
	v_add_u32_e32 v128, 48, v166
	v_mad_i64_i32 v[128:129], s[16:17], v128, s76, v[160:161]
	v_lshlrev_b64 v[160:161], 11, v[166:167]
	v_lshl_add_u64 v[160:161], s[22:23], 0, v[160:161]
	v_lshl_add_u64 v[160:161], v[160:161], 0, s[0:1]
	v_lshl_add_u64 v[160:161], v[160:161], 0, v[156:157]
	global_load_dwordx4 v[132:135], v[128:129], off
	s_nop 0
	global_load_dwordx4 v[128:131], v[128:129], off offset:256
	s_waitcnt vmcnt(0) lgkmcnt(0)
	v_lshlrev_b32_e32 v159, 16, v144
	v_and_b32_e32 v144, 0xffff0000, v144
	v_max_f32_e32 v159, v159, v159
	v_max_f32_e32 v144, v144, v144
	v_max_f32_e32 v166, 0x1e3ce508, v159
	v_max_f32_e32 v167, 0x1e3ce508, v144
	v_lshlrev_b32_e32 v159, 16, v145
	v_and_b32_e32 v145, 0xffff0000, v145
	v_pk_mul_f32 v[166:167], v[60:61], v[166:167]
	v_max_f32_e32 v159, v159, v159
	v_max_f32_e32 v145, v145, v145
	v_cvt_pk_bf16_f32 v144, v166, v167
	v_max_f32_e32 v166, 0x1e3ce508, v159
	v_max_f32_e32 v167, 0x1e3ce508, v145
	v_lshlrev_b32_e32 v159, 16, v146
	v_and_b32_e32 v146, 0xffff0000, v146
	v_pk_mul_f32 v[166:167], v[62:63], v[166:167]
	v_max_f32_e32 v159, v159, v159
	v_max_f32_e32 v146, v146, v146
	v_cvt_pk_bf16_f32 v145, v166, v167
	v_max_f32_e32 v166, 0x1e3ce508, v159
	v_max_f32_e32 v167, 0x1e3ce508, v146
	v_lshlrev_b32_e32 v159, 16, v147
	v_and_b32_e32 v147, 0xffff0000, v147
	v_pk_mul_f32 v[166:167], v[56:57], v[166:167]
	v_max_f32_e32 v159, v159, v159
	v_max_f32_e32 v147, v147, v147
	v_cvt_pk_bf16_f32 v146, v166, v167
	v_max_f32_e32 v166, 0x1e3ce508, v159
	v_max_f32_e32 v167, 0x1e3ce508, v147
	v_pk_mul_f32 v[166:167], v[58:59], v[166:167]
	s_nop 0
	v_cvt_pk_bf16_f32 v147, v166, v167
	global_store_dwordx4 v[160:161], v[144:147], off
	s_nop 1
	v_lshlrev_b32_e32 v144, 16, v148
	v_and_b32_e32 v145, 0xffff0000, v148
	v_max_f32_e32 v144, v144, v144
	v_max_f32_e32 v145, v145, v145
	v_max_f32_e32 v144, 0x1e3ce508, v144
	v_max_f32_e32 v145, 0x1e3ce508, v145
	v_pk_mul_f32 v[144:145], v[28:29], v[144:145]
	s_nop 0
	v_cvt_pk_bf16_f32 v144, v144, v145
	v_lshlrev_b32_e32 v145, 16, v149
	v_max_f32_e32 v145, v145, v145
	v_max_f32_e32 v146, 0x1e3ce508, v145
	v_and_b32_e32 v145, 0xffff0000, v149
	v_max_f32_e32 v145, v145, v145
	v_max_f32_e32 v147, 0x1e3ce508, v145
	v_pk_mul_f32 v[146:147], v[30:31], v[146:147]
	s_nop 0
	v_cvt_pk_bf16_f32 v145, v146, v147
	v_lshlrev_b32_e32 v146, 16, v150
	v_and_b32_e32 v147, 0xffff0000, v150
	v_max_f32_e32 v146, v146, v146
	v_max_f32_e32 v147, v147, v147
	v_max_f32_e32 v146, 0x1e3ce508, v146
	v_max_f32_e32 v147, 0x1e3ce508, v147
	v_pk_mul_f32 v[146:147], v[24:25], v[146:147]
	s_nop 0
	v_cvt_pk_bf16_f32 v146, v146, v147
	v_lshlrev_b32_e32 v147, 16, v151
	v_max_f32_e32 v147, v147, v147
	v_max_f32_e32 v148, 0x1e3ce508, v147
	v_and_b32_e32 v147, 0xffff0000, v151
	v_max_f32_e32 v147, v147, v147
	v_max_f32_e32 v149, 0x1e3ce508, v147
	v_pk_mul_f32 v[148:149], v[26:27], v[148:149]
	s_nop 0
	v_cvt_pk_bf16_f32 v147, v148, v149
	global_store_dwordx4 v[160:161], v[144:147], off offset:256
	s_nop 1
	v_add_u32_e32 v144, 0x90, v158
	v_ashrrev_i32_e32 v145, 31, v144
	v_lshlrev_b64 v[144:145], 11, v[144:145]
	v_lshl_add_u64 v[144:145], s[22:23], 0, v[144:145]
	v_lshl_add_u64 v[144:145], v[144:145], 0, s[0:1]
	v_lshl_add_u64 v[148:149], v[144:145], 0, v[156:157]
	v_lshlrev_b32_e32 v144, 16, v152
	v_and_b32_e32 v145, 0xffff0000, v152
	v_max_f32_e32 v144, v144, v144
	v_max_f32_e32 v145, v145, v145
	v_max_f32_e32 v144, 0x1e3ce508, v144
	v_max_f32_e32 v145, 0x1e3ce508, v145
	v_pk_mul_f32 v[144:145], v[52:53], v[144:145]
	s_nop 0
	v_cvt_pk_bf16_f32 v144, v144, v145
	v_lshlrev_b32_e32 v145, 16, v153
	v_max_f32_e32 v145, v145, v145
	v_max_f32_e32 v146, 0x1e3ce508, v145
	v_and_b32_e32 v145, 0xffff0000, v153
	v_max_f32_e32 v145, v145, v145
	v_max_f32_e32 v147, 0x1e3ce508, v145
	v_pk_mul_f32 v[146:147], v[54:55], v[146:147]
	s_nop 0
	v_cvt_pk_bf16_f32 v145, v146, v147
	v_lshlrev_b32_e32 v146, 16, v154
	v_and_b32_e32 v147, 0xffff0000, v154
	v_max_f32_e32 v146, v146, v146
	v_max_f32_e32 v147, v147, v147
	v_max_f32_e32 v146, 0x1e3ce508, v146
	v_max_f32_e32 v147, 0x1e3ce508, v147
	v_pk_mul_f32 v[146:147], v[48:49], v[146:147]
	s_nop 0
	v_cvt_pk_bf16_f32 v146, v146, v147
	v_lshlrev_b32_e32 v147, 16, v155
	v_max_f32_e32 v147, v147, v147
	v_max_f32_e32 v150, 0x1e3ce508, v147
	v_and_b32_e32 v147, 0xffff0000, v155
	v_max_f32_e32 v147, v147, v147
	v_max_f32_e32 v151, 0x1e3ce508, v147
	v_pk_mul_f32 v[150:151], v[50:51], v[150:151]
	s_nop 0
	v_cvt_pk_bf16_f32 v147, v150, v151
	global_store_dwordx4 v[148:149], v[144:147], off
	s_nop 1
	v_lshlrev_b32_e32 v144, 16, v162
	v_and_b32_e32 v145, 0xffff0000, v162
	v_max_f32_e32 v144, v144, v144
	v_max_f32_e32 v145, v145, v145
	v_max_f32_e32 v144, 0x1e3ce508, v144
	v_max_f32_e32 v145, 0x1e3ce508, v145
	v_pk_mul_f32 v[144:145], v[20:21], v[144:145]
	s_nop 0
	v_cvt_pk_bf16_f32 v144, v144, v145
	v_lshlrev_b32_e32 v145, 16, v163
	v_max_f32_e32 v145, v145, v145
	v_max_f32_e32 v146, 0x1e3ce508, v145
	v_and_b32_e32 v145, 0xffff0000, v163
	v_max_f32_e32 v145, v145, v145
	v_max_f32_e32 v147, 0x1e3ce508, v145
	v_pk_mul_f32 v[146:147], v[22:23], v[146:147]
	s_nop 0
	v_cvt_pk_bf16_f32 v145, v146, v147
	v_lshlrev_b32_e32 v146, 16, v164
	v_and_b32_e32 v147, 0xffff0000, v164
	v_max_f32_e32 v146, v146, v146
	v_max_f32_e32 v147, v147, v147
	v_max_f32_e32 v146, 0x1e3ce508, v146
	v_max_f32_e32 v147, 0x1e3ce508, v147
	v_pk_mul_f32 v[146:147], v[16:17], v[146:147]
	s_nop 0
	v_cvt_pk_bf16_f32 v146, v146, v147
	v_lshlrev_b32_e32 v147, 16, v165
	v_max_f32_e32 v147, v147, v147
	v_max_f32_e32 v150, 0x1e3ce508, v147
	v_and_b32_e32 v147, 0xffff0000, v165
	v_max_f32_e32 v147, v147, v147
	v_max_f32_e32 v151, 0x1e3ce508, v147
	v_pk_mul_f32 v[150:151], v[18:19], v[150:151]
	s_nop 0
	v_cvt_pk_bf16_f32 v147, v150, v151
	global_store_dwordx4 v[148:149], v[144:147], off offset:256
	s_nop 1
	v_lshlrev_b32_e32 v146, 16, v140
	v_and_b32_e32 v140, 0xffff0000, v140
	v_max_f32_e32 v146, v146, v146
	v_max_f32_e32 v140, v140, v140
	v_max_f32_e32 v146, 0x1e3ce508, v146
	v_max_f32_e32 v147, 0x1e3ce508, v140
	v_pk_mul_f32 v[146:147], v[44:45], v[146:147]
	v_add_u32_e32 v144, 0xa0, v158
	v_cvt_pk_bf16_f32 v140, v146, v147
	v_lshlrev_b32_e32 v146, 16, v141
	v_and_b32_e32 v141, 0xffff0000, v141
	v_max_f32_e32 v146, v146, v146
	v_max_f32_e32 v141, v141, v141
	v_max_f32_e32 v146, 0x1e3ce508, v146
	v_max_f32_e32 v147, 0x1e3ce508, v141
	v_pk_mul_f32 v[146:147], v[46:47], v[146:147]
	v_ashrrev_i32_e32 v145, 31, v144
	v_cvt_pk_bf16_f32 v141, v146, v147
	v_lshlrev_b32_e32 v146, 16, v142
	v_and_b32_e32 v142, 0xffff0000, v142
	v_max_f32_e32 v146, v146, v146
	v_max_f32_e32 v142, v142, v142
	v_max_f32_e32 v146, 0x1e3ce508, v146
	v_max_f32_e32 v147, 0x1e3ce508, v142
	v_pk_mul_f32 v[146:147], v[40:41], v[146:147]
	v_lshlrev_b64 v[144:145], 11, v[144:145]
	v_cvt_pk_bf16_f32 v142, v146, v147
	v_lshlrev_b32_e32 v146, 16, v143
	v_and_b32_e32 v143, 0xffff0000, v143
	v_max_f32_e32 v146, v146, v146
	v_max_f32_e32 v143, v143, v143
	v_lshl_add_u64 v[144:145], s[22:23], 0, v[144:145]
	v_max_f32_e32 v146, 0x1e3ce508, v146
	v_max_f32_e32 v147, 0x1e3ce508, v143
	v_lshl_add_u64 v[144:145], v[144:145], 0, s[0:1]
	v_pk_mul_f32 v[146:147], v[42:43], v[146:147]
	v_lshl_add_u64 v[144:145], v[144:145], 0, v[156:157]
	v_cvt_pk_bf16_f32 v143, v146, v147
	global_store_dwordx4 v[144:145], v[140:143], off
	s_nop 1
	v_lshlrev_b32_e32 v140, 16, v136
	v_and_b32_e32 v136, 0xffff0000, v136
	v_max_f32_e32 v140, v140, v140
	v_max_f32_e32 v136, v136, v136
	v_max_f32_e32 v140, 0x1e3ce508, v140
	v_max_f32_e32 v141, 0x1e3ce508, v136
	v_pk_mul_f32 v[140:141], v[12:13], v[140:141]
	s_nop 0
	v_cvt_pk_bf16_f32 v136, v140, v141
	v_lshlrev_b32_e32 v140, 16, v137
	v_and_b32_e32 v137, 0xffff0000, v137
	v_max_f32_e32 v140, v140, v140
	v_max_f32_e32 v137, v137, v137
	v_max_f32_e32 v140, 0x1e3ce508, v140
	v_max_f32_e32 v141, 0x1e3ce508, v137
	v_pk_mul_f32 v[140:141], v[14:15], v[140:141]
	s_nop 0
	v_cvt_pk_bf16_f32 v137, v140, v141
	v_lshlrev_b32_e32 v140, 16, v138
	v_and_b32_e32 v138, 0xffff0000, v138
	v_max_f32_e32 v140, v140, v140
	v_max_f32_e32 v138, v138, v138
	v_max_f32_e32 v140, 0x1e3ce508, v140
	v_max_f32_e32 v141, 0x1e3ce508, v138
	v_pk_mul_f32 v[140:141], v[8:9], v[140:141]
	s_nop 0
	v_cvt_pk_bf16_f32 v138, v140, v141
	v_lshlrev_b32_e32 v140, 16, v139
	v_and_b32_e32 v139, 0xffff0000, v139
	v_max_f32_e32 v140, v140, v140
	v_max_f32_e32 v139, v139, v139
	v_max_f32_e32 v140, 0x1e3ce508, v140
	v_max_f32_e32 v141, 0x1e3ce508, v139
	v_pk_mul_f32 v[140:141], v[10:11], v[140:141]
	s_nop 0
	v_cvt_pk_bf16_f32 v139, v140, v141
	global_store_dwordx4 v[144:145], v[136:139], off offset:256
	s_nop 1
	v_lshlrev_b32_e32 v138, 16, v132
	v_and_b32_e32 v132, 0xffff0000, v132
	v_max_f32_e32 v138, v138, v138
	v_max_f32_e32 v132, v132, v132
	v_max_f32_e32 v138, 0x1e3ce508, v138
	v_max_f32_e32 v139, 0x1e3ce508, v132
	v_pk_mul_f32 v[138:139], v[36:37], v[138:139]
	v_add_u32_e32 v136, 0xb0, v158
	v_cvt_pk_bf16_f32 v132, v138, v139
	v_lshlrev_b32_e32 v138, 16, v133
	v_and_b32_e32 v133, 0xffff0000, v133
	v_max_f32_e32 v138, v138, v138
	v_max_f32_e32 v133, v133, v133
	v_max_f32_e32 v138, 0x1e3ce508, v138
	v_max_f32_e32 v139, 0x1e3ce508, v133
	v_pk_mul_f32 v[138:139], v[38:39], v[138:139]
	v_ashrrev_i32_e32 v137, 31, v136
	v_cvt_pk_bf16_f32 v133, v138, v139
	v_lshlrev_b32_e32 v138, 16, v134
	v_and_b32_e32 v134, 0xffff0000, v134
	v_max_f32_e32 v138, v138, v138
	v_max_f32_e32 v134, v134, v134
	v_max_f32_e32 v138, 0x1e3ce508, v138
	v_max_f32_e32 v139, 0x1e3ce508, v134
	v_pk_mul_f32 v[138:139], v[32:33], v[138:139]
	v_lshlrev_b64 v[136:137], 11, v[136:137]
	v_cvt_pk_bf16_f32 v134, v138, v139
	v_lshlrev_b32_e32 v138, 16, v135
	v_and_b32_e32 v135, 0xffff0000, v135
	v_max_f32_e32 v138, v138, v138
	v_max_f32_e32 v135, v135, v135
	v_lshl_add_u64 v[136:137], s[22:23], 0, v[136:137]
	v_max_f32_e32 v138, 0x1e3ce508, v138
	v_max_f32_e32 v139, 0x1e3ce508, v135
	v_lshl_add_u64 v[136:137], v[136:137], 0, s[0:1]
	v_pk_mul_f32 v[138:139], v[34:35], v[138:139]
	v_lshl_add_u64 v[136:137], v[136:137], 0, v[156:157]
	v_cvt_pk_bf16_f32 v135, v138, v139
	global_store_dwordx4 v[136:137], v[132:135], off
	s_nop 1
	v_lshlrev_b32_e32 v132, 16, v128
	v_and_b32_e32 v128, 0xffff0000, v128
	v_max_f32_e32 v132, v132, v132
	v_max_f32_e32 v128, v128, v128
	v_max_f32_e32 v132, 0x1e3ce508, v132
	v_max_f32_e32 v133, 0x1e3ce508, v128
	v_pk_mul_f32 v[132:133], v[4:5], v[132:133]
	s_nop 0
	v_cvt_pk_bf16_f32 v128, v132, v133
	v_lshlrev_b32_e32 v132, 16, v129
	v_and_b32_e32 v129, 0xffff0000, v129
	v_max_f32_e32 v132, v132, v132
	v_max_f32_e32 v129, v129, v129
	v_max_f32_e32 v132, 0x1e3ce508, v132
	v_max_f32_e32 v133, 0x1e3ce508, v129
	v_pk_mul_f32 v[132:133], v[6:7], v[132:133]
	s_nop 0
	v_cvt_pk_bf16_f32 v129, v132, v133
	v_lshlrev_b32_e32 v132, 16, v130
	v_and_b32_e32 v130, 0xffff0000, v130
	v_max_f32_e32 v132, v132, v132
	v_max_f32_e32 v130, v130, v130
	v_max_f32_e32 v132, 0x1e3ce508, v132
	v_max_f32_e32 v133, 0x1e3ce508, v130
	v_pk_mul_f32 v[132:133], v[0:1], v[132:133]
	s_nop 0
	v_cvt_pk_bf16_f32 v130, v132, v133
	v_lshlrev_b32_e32 v132, 16, v131
	v_and_b32_e32 v131, 0xffff0000, v131
	v_max_f32_e32 v132, v132, v132
	v_max_f32_e32 v131, v131, v131
	v_max_f32_e32 v132, 0x1e3ce508, v132
	v_max_f32_e32 v133, 0x1e3ce508, v131
	v_pk_mul_f32 v[132:133], v[2:3], v[132:133]
	s_nop 0
	v_cvt_pk_bf16_f32 v131, v132, v133
	global_store_dwordx4 v[136:137], v[128:131], off offset:256

.LBB0_1062:
	v_readlane_b32 s0, v250, 54
	v_add_u32_e32 v162, 16, v144
	v_add_u32_e32 v158, 32, v144
	v_add_u32_e32 v154, 48, v144
	v_add_u32_e32 v146, 0x80, v144
	v_add_u32_e32 v150, 0x90, v144
	v_mov_b32_e32 v128, s0
	v_ashrrev_i32_e32 v163, 31, v162
	v_ashrrev_i32_e32 v159, 31, v158
	v_ashrrev_i32_e32 v155, 31, v154
	v_ashrrev_i32_e32 v147, 31, v146
	v_ashrrev_i32_e32 v151, 31, v150
	ds_read_b32 v156, v128
	s_waitcnt lgkmcnt(0)
	v_lshlrev_b64 v[128:129], 6, v[144:145]
	v_lshlrev_b64 v[130:131], 6, v[162:163]
	v_lshlrev_b64 v[136:137], 6, v[158:159]
	v_lshlrev_b64 v[138:139], 6, v[154:155]
	v_lshlrev_b64 v[146:147], 6, v[146:147]
	v_lshlrev_b64 v[148:149], 6, v[150:151]
	v_lshl_add_u64 v[128:129], v[210:211], 0, v[128:129]
	v_lshl_add_u64 v[132:133], v[210:211], 0, v[130:131]
	v_lshl_add_u64 v[136:137], v[210:211], 0, v[136:137]
	v_lshl_add_u64 v[140:141], v[210:211], 0, v[138:139]
	v_lshl_add_u64 v[146:147], v[210:211], 0, v[146:147]
	v_lshl_add_u64 v[148:149], v[210:211], 0, v[148:149]
	global_load_dwordx4 v[128:131], v[128:129], off
	s_nop 0
	global_load_dwordx4 v[132:135], v[132:133], off
	s_nop 0
	global_load_dwordx4 v[136:139], v[136:137], off
	s_nop 0
	global_load_dwordx4 v[140:143], v[140:141], off
	s_nop 0
	global_load_dwordx4 v[164:167], v[146:147], off
	global_load_dwordx4 v[168:171], v[148:149], off
	v_add_u32_e32 v148, 0xa0, v144
	v_ashrrev_i32_e32 v149, 31, v148
	v_lshlrev_b64 v[146:147], 6, v[148:149]
	v_lshl_add_u64 v[146:147], v[210:211], 0, v[146:147]
	global_load_dwordx4 v[176:179], v[146:147], off
	v_add_u32_e32 v146, 0xb0, v144
	v_ashrrev_i32_e32 v147, 31, v146
	v_lshlrev_b64 v[152:153], 6, v[146:147]
	v_lshl_add_u64 v[152:153], v[210:211], 0, v[152:153]
	global_load_dwordx4 v[180:183], v[152:153], off
	v_cmp_lt_i32_e32 vcc, v223, v218
	v_readfirstlane_b32 s0, v156
	s_mov_b64 s[20:21], -1
	v_cndmask_b32_e32 v147, v217, v223, vcc
	v_lshlrev_b32_e32 v147, 2, v147
	v_cmp_lt_i32_e32 vcc, v224, v218
	s_mov_b64 s[30:31], 0
	s_cmp_lt_i32 s28, 2
	v_cndmask_b32_e32 v149, v217, v224, vcc
	v_lshlrev_b32_e32 v149, 2, v149
	s_waitcnt vmcnt(0) lgkmcnt(0)
	v_add_f32_e32 v128, v128, v129
	v_add_f32_e32 v129, v130, v131
	v_add_f32_e32 v130, v132, v133
	v_add_f32_e32 v131, v134, v135
	v_add_f32_e32 v132, v136, v137
	v_add_f32_e32 v133, v138, v139
	v_add_f32_e32 v134, v140, v141
	v_add_f32_e32 v135, v142, v143
	v_add_f32_e32 v136, v164, v165
	v_add_f32_e32 v137, v166, v167
	v_add_f32_e32 v138, v168, v169
	v_add_f32_e32 v139, v170, v171
	v_add_f32_e32 v140, v176, v177
	v_add_f32_e32 v141, v178, v179
	v_add_f32_e32 v142, v180, v181
	v_add_f32_e32 v143, v182, v183
	v_add_f32_e32 v128, v128, v129
	v_add_f32_e32 v130, v130, v131
	v_add_f32_e32 v131, v132, v133
	v_add_f32_e32 v132, v134, v135
	v_add_f32_e32 v133, v136, v137
	v_add_f32_e32 v134, v138, v139
	v_add_f32_e32 v136, v140, v141
	v_add_f32_e32 v139, v142, v143
	ds_bpermute_b32 v129, v147, v128
	ds_bpermute_b32 v135, v147, v130
	ds_bpermute_b32 v137, v147, v131
	ds_bpermute_b32 v142, v147, v132
	ds_bpermute_b32 v143, v147, v133
	ds_bpermute_b32 v151, v147, v134
	ds_bpermute_b32 v152, v147, v136
	ds_bpermute_b32 v147, v147, v139
	s_waitcnt lgkmcnt(7)
	v_add_f32_e32 v140, v128, v129
	s_waitcnt lgkmcnt(6)
	v_add_f32_e32 v138, v130, v135
	s_waitcnt lgkmcnt(5)
	v_add_f32_e32 v137, v131, v137
	s_waitcnt lgkmcnt(4)
	v_add_f32_e32 v135, v132, v142
	s_waitcnt lgkmcnt(3)
	v_add_f32_e32 v132, v133, v143
	s_waitcnt lgkmcnt(2)
	v_add_f32_e32 v130, v134, v151
	s_waitcnt lgkmcnt(1)
	v_add_f32_e32 v129, v136, v152
	s_waitcnt lgkmcnt(0)
	v_add_f32_e32 v128, v139, v147
	ds_bpermute_b32 v141, v149, v140
	ds_bpermute_b32 v143, v149, v138
	ds_bpermute_b32 v142, v149, v137
	ds_bpermute_b32 v139, v149, v135
	ds_bpermute_b32 v136, v149, v132
	ds_bpermute_b32 v134, v149, v130
	ds_bpermute_b32 v133, v149, v129
	ds_bpermute_b32 v131, v149, v128
	s_waitcnt lgkmcnt(7)
	v_add_f32_e32 v140, v140, v141
	s_waitcnt lgkmcnt(6)
	v_add_f32_e32 v138, v138, v143
	s_waitcnt lgkmcnt(5)
	v_add_f32_e32 v137, v137, v142
	s_waitcnt lgkmcnt(4)
	v_add_f32_e32 v135, v135, v139
	s_waitcnt lgkmcnt(3)
	v_add_f32_e32 v132, v132, v136
	s_waitcnt lgkmcnt(2)
	v_add_f32_e32 v130, v130, v134
	s_waitcnt lgkmcnt(1)
	v_add_f32_e32 v129, v129, v133
	s_waitcnt lgkmcnt(0)
	v_add_f32_e32 v128, v128, v131
	v_fmamk_f32 v140, v140, 0x3a800000, v215
	v_fmamk_f32 v138, v138, 0x3a800000, v215
	v_fmamk_f32 v137, v137, 0x3a800000, v215
	v_fmamk_f32 v135, v135, 0x3a800000, v215
	v_fmamk_f32 v132, v132, 0x3a800000, v215
	v_fmamk_f32 v130, v130, 0x3a800000, v215
	v_fmamk_f32 v129, v129, 0x3a800000, v215
	v_fmamk_f32 v128, v128, 0x3a800000, v215
	v_rsq_f32_e32 v140, v140
	v_rsq_f32_e32 v138, v138
	v_rsq_f32_e32 v137, v137
	v_rsq_f32_e32 v135, v135
	v_rsq_f32_e32 v132, v132
	v_rsq_f32_e32 v130, v130
	v_rsq_f32_e32 v129, v129
	v_rsq_f32_e32 v128, v128
	v_mul_f32_e32 v176, s0, v140
	v_mul_f32_e32 v170, s0, v138
	v_mul_f32_e32 v168, s0, v137
	v_mul_f32_e32 v166, s0, v135
	v_mul_f32_e32 v164, s0, v132
	v_mul_f32_e32 v160, s0, v130
	v_mul_f32_e32 v156, s0, v129
	v_mul_f32_e32 v152, s0, v128
	s_mov_b64 s[0:1], 0
	s_cbranch_scc1 .LBB0_1075
	s_cmp_gt_i32 s28, 2
	s_cbranch_scc0 .LBB0_1072
	s_cmp_gt_i32 s28, 6
	s_cbranch_scc0 .LBB0_1068
	s_cmp_eq_u32 s28, 7
	s_mov_b64 s[0:1], -1
	s_cbranch_scc0 .LBB0_1067
	v_readlane_b32 s0, v251, 4
	s_ashr_i32 s67, s66, 31
	v_ashrrev_i32_e32 v175, 31, v174
	v_mov_b32_e32 v128, s0
	ds_read_b32 v128, v128
	v_readlane_b32 s0, v251, 5
	s_lshl_b64 s[20:21], s[66:67], 1
	v_mul_f32_e32 v132, v126, v176
	s_waitcnt lgkmcnt(0)
	v_mov_b32_e32 v128, s0
	ds_read_b32 v128, v128
	v_readlane_b32 s0, v251, 6
	v_mul_f32_e32 v133, v127, v176
	v_mul_f32_e32 v136, v120, v176
	s_waitcnt lgkmcnt(0)
	v_mov_b32_e32 v128, s0
	v_readlane_b32 s0, v251, 7
	ds_read_b32 v128, v128
	v_mul_f32_e32 v137, v121, v176
	v_mov_b32_e32 v129, s0
	v_readlane_b32 s0, v250, 53
	ds_read_b32 v129, v129
	v_mul_f32_e32 v138, v122, v176
	v_mov_b32_e32 v130, s0
	ds_read_b32 v130, v130
	s_waitcnt lgkmcnt(2)
	v_readfirstlane_b32 s0, v128
	s_waitcnt lgkmcnt(1)
	v_readfirstlane_b32 s1, v129
	v_mul_f32_e32 v139, v123, v176
	v_max_f32_e32 v132, 0, v132
	s_waitcnt lgkmcnt(0)
	v_readfirstlane_b32 s5, v130
	v_max_f32_e32 v133, 0, v133
	v_max_f32_e32 v136, 0, v136
	v_mad_i64_i32 v[128:129], s[16:17], s5, v144, 0
	v_lshl_add_u64 v[128:129], v[128:129], 1, s[0:1]
	v_lshl_add_u64 v[130:131], v[128:129], 0, s[20:21]
	v_lshlrev_b64 v[128:129], 1, v[174:175]
	v_lshl_add_u64 v[134:135], v[130:131], 0, v[128:129]
	v_mul_f32_e32 v130, v124, v176
	v_mul_f32_e32 v131, v125, v176
	v_max_f32_e32 v130, 0, v130
	v_max_f32_e32 v131, 0, v131
	v_max_f32_e32 v137, 0, v137
	v_max_f32_e32 v138, 0, v138
	v_max_f32_e32 v139, 0, v139
	v_pk_mul_f32 v[130:131], v[130:131], v[130:131]
	v_pk_mul_f32 v[132:133], v[132:133], v[132:133]
	v_pk_mul_f32 v[136:137], v[136:137], v[136:137]
	v_pk_mul_f32 v[138:139], v[138:139], v[138:139]
	v_cvt_pk_bf16_f32 v130, v130, v131
	v_cvt_pk_bf16_f32 v131, v132, v133
	v_cvt_pk_bf16_f32 v132, v136, v137
	v_cvt_pk_bf16_f32 v133, v138, v139
	global_store_dwordx4 v[134:135], v[130:133], off
	v_mul_f32_e32 v136, v88, v176
	v_mul_f32_e32 v137, v89, v176
	v_mul_f32_e32 v130, v92, v176
	v_mul_f32_e32 v131, v93, v176
	v_mul_f32_e32 v132, v94, v176
	v_mul_f32_e32 v133, v95, v176
	v_mul_f32_e32 v138, v90, v176
	v_mul_f32_e32 v139, v91, v176
	v_max_f32_e32 v130, 0, v130
	v_max_f32_e32 v131, 0, v131
	v_max_f32_e32 v132, 0, v132
	v_max_f32_e32 v133, 0, v133
	v_max_f32_e32 v136, 0, v136
	v_max_f32_e32 v137, 0, v137
	v_max_f32_e32 v138, 0, v138
	v_max_f32_e32 v139, 0, v139
	v_pk_mul_f32 v[130:131], v[130:131], v[130:131]
	v_pk_mul_f32 v[132:133], v[132:133], v[132:133]
	v_pk_mul_f32 v[136:137], v[136:137], v[136:137]
	v_pk_mul_f32 v[138:139], v[138:139], v[138:139]
	v_cvt_pk_bf16_f32 v130, v130, v131
	v_cvt_pk_bf16_f32 v131, v132, v133
	v_cvt_pk_bf16_f32 v132, v136, v137
	v_cvt_pk_bf16_f32 v133, v138, v139
	global_store_dwordx4 v[134:135], v[130:133], off offset:256
	v_mul_f32_e32 v136, v112, v170
	v_mul_f32_e32 v137, v113, v170
	v_mad_i64_i32 v[130:131], s[16:17], s5, v162, 0
	v_lshl_add_u64 v[130:131], v[130:131], 1, s[0:1]
	v_lshl_add_u64 v[130:131], v[130:131], 0, s[20:21]
	v_lshl_add_u64 v[134:135], v[130:131], 0, v[128:129]
	v_mul_f32_e32 v130, v116, v170
	v_mul_f32_e32 v131, v117, v170
	v_mul_f32_e32 v132, v118, v170
	v_mul_f32_e32 v133, v119, v170
	v_mul_f32_e32 v138, v114, v170
	v_mul_f32_e32 v139, v115, v170
	v_max_f32_e32 v130, 0, v130
	v_max_f32_e32 v131, 0, v131
	v_max_f32_e32 v132, 0, v132
	v_max_f32_e32 v133, 0, v133
	v_max_f32_e32 v136, 0, v136
	v_max_f32_e32 v137, 0, v137
	v_max_f32_e32 v138, 0, v138
	v_max_f32_e32 v139, 0, v139
	v_pk_mul_f32 v[130:131], v[130:131], v[130:131]
	v_pk_mul_f32 v[132:133], v[132:133], v[132:133]
	v_pk_mul_f32 v[136:137], v[136:137], v[136:137]
	v_pk_mul_f32 v[138:139], v[138:139], v[138:139]
	v_cvt_pk_bf16_f32 v130, v130, v131
	v_cvt_pk_bf16_f32 v131, v132, v133
	v_cvt_pk_bf16_f32 v132, v136, v137
	v_cvt_pk_bf16_f32 v133, v138, v139
	global_store_dwordx4 v[134:135], v[130:133], off
	v_mul_f32_e32 v136, v80, v170
	v_mul_f32_e32 v137, v81, v170
	v_mul_f32_e32 v130, v84, v170
	v_mul_f32_e32 v131, v85, v170
	v_mul_f32_e32 v132, v86, v170
	v_mul_f32_e32 v133, v87, v170
	v_mul_f32_e32 v138, v82, v170
	v_mul_f32_e32 v139, v83, v170
	v_max_f32_e32 v130, 0, v130
	v_max_f32_e32 v131, 0, v131
	v_max_f32_e32 v132, 0, v132
	v_max_f32_e32 v133, 0, v133
	v_max_f32_e32 v136, 0, v136
	v_max_f32_e32 v137, 0, v137
	v_max_f32_e32 v138, 0, v138
	v_max_f32_e32 v139, 0, v139
	v_pk_mul_f32 v[130:131], v[130:131], v[130:131]
	v_pk_mul_f32 v[132:133], v[132:133], v[132:133]
	v_pk_mul_f32 v[136:137], v[136:137], v[136:137]
	v_pk_mul_f32 v[138:139], v[138:139], v[138:139]
	v_cvt_pk_bf16_f32 v130, v130, v131
	v_cvt_pk_bf16_f32 v131, v132, v133
	v_cvt_pk_bf16_f32 v132, v136, v137
	v_cvt_pk_bf16_f32 v133, v138, v139
	global_store_dwordx4 v[134:135], v[130:133], off offset:256
	v_mul_f32_e32 v136, v104, v168
	v_mul_f32_e32 v137, v105, v168
	v_mad_i64_i32 v[130:131], s[16:17], s5, v158, 0
	v_lshl_add_u64 v[130:131], v[130:131], 1, s[0:1]
	v_lshl_add_u64 v[130:131], v[130:131], 0, s[20:21]
	v_lshl_add_u64 v[134:135], v[130:131], 0, v[128:129]
	v_mul_f32_e32 v130, v108, v168
	v_mul_f32_e32 v131, v109, v168
	v_mul_f32_e32 v132, v110, v168
	v_mul_f32_e32 v133, v111, v168
	v_mul_f32_e32 v138, v106, v168
	v_mul_f32_e32 v139, v107, v168
	v_max_f32_e32 v130, 0, v130
	v_max_f32_e32 v131, 0, v131
	v_max_f32_e32 v132, 0, v132
	v_max_f32_e32 v133, 0, v133
	v_max_f32_e32 v136, 0, v136
	v_max_f32_e32 v137, 0, v137
	v_max_f32_e32 v138, 0, v138
	v_max_f32_e32 v139, 0, v139
	v_pk_mul_f32 v[130:131], v[130:131], v[130:131]
	v_pk_mul_f32 v[132:133], v[132:133], v[132:133]
	v_pk_mul_f32 v[136:137], v[136:137], v[136:137]
	v_pk_mul_f32 v[138:139], v[138:139], v[138:139]
	v_cvt_pk_bf16_f32 v130, v130, v131
	v_cvt_pk_bf16_f32 v131, v132, v133
	v_cvt_pk_bf16_f32 v132, v136, v137
	v_cvt_pk_bf16_f32 v133, v138, v139
	global_store_dwordx4 v[134:135], v[130:133], off
	v_mul_f32_e32 v136, v72, v168
	v_mul_f32_e32 v137, v73, v168
	v_mul_f32_e32 v130, v76, v168
	v_mul_f32_e32 v131, v77, v168
	v_mul_f32_e32 v132, v78, v168
	v_mul_f32_e32 v133, v79, v168
	v_mul_f32_e32 v138, v74, v168
	v_mul_f32_e32 v139, v75, v168
	v_max_f32_e32 v130, 0, v130
	v_max_f32_e32 v131, 0, v131
	v_max_f32_e32 v132, 0, v132
	v_max_f32_e32 v133, 0, v133
	v_max_f32_e32 v136, 0, v136
	v_max_f32_e32 v137, 0, v137
	v_max_f32_e32 v138, 0, v138
	v_max_f32_e32 v139, 0, v139
	v_pk_mul_f32 v[130:131], v[130:131], v[130:131]
	v_pk_mul_f32 v[132:133], v[132:133], v[132:133]
	v_pk_mul_f32 v[136:137], v[136:137], v[136:137]
	v_pk_mul_f32 v[138:139], v[138:139], v[138:139]
	v_cvt_pk_bf16_f32 v130, v130, v131
	v_cvt_pk_bf16_f32 v131, v132, v133
	v_cvt_pk_bf16_f32 v132, v136, v137
	v_cvt_pk_bf16_f32 v133, v138, v139
	global_store_dwordx4 v[134:135], v[130:133], off offset:256
	v_mul_f32_e32 v136, v96, v166
	v_mul_f32_e32 v137, v97, v166
	v_mad_i64_i32 v[130:131], s[16:17], s5, v154, 0
	v_lshl_add_u64 v[130:131], v[130:131], 1, s[0:1]
	v_lshl_add_u64 v[130:131], v[130:131], 0, s[20:21]
	v_lshl_add_u64 v[134:135], v[130:131], 0, v[128:129]
	v_mul_f32_e32 v130, v100, v166
	v_mul_f32_e32 v131, v101, v166
	v_mul_f32_e32 v132, v102, v166
	v_mul_f32_e32 v133, v103, v166
	v_mul_f32_e32 v138, v98, v166
	v_mul_f32_e32 v139, v99, v166
	v_max_f32_e32 v130, 0, v130
	v_max_f32_e32 v131, 0, v131
	v_max_f32_e32 v132, 0, v132
	v_max_f32_e32 v133, 0, v133
	v_max_f32_e32 v136, 0, v136
	v_max_f32_e32 v137, 0, v137
	v_max_f32_e32 v138, 0, v138
	v_max_f32_e32 v139, 0, v139
	v_pk_mul_f32 v[130:131], v[130:131], v[130:131]
	v_pk_mul_f32 v[132:133], v[132:133], v[132:133]
	v_pk_mul_f32 v[136:137], v[136:137], v[136:137]
	v_pk_mul_f32 v[138:139], v[138:139], v[138:139]
	v_cvt_pk_bf16_f32 v130, v130, v131
	v_cvt_pk_bf16_f32 v131, v132, v133
	v_cvt_pk_bf16_f32 v132, v136, v137
	v_cvt_pk_bf16_f32 v133, v138, v139
	global_store_dwordx4 v[134:135], v[130:133], off
	v_mul_f32_e32 v136, v64, v166
	v_mul_f32_e32 v137, v65, v166
	v_mul_f32_e32 v130, v68, v166
	v_mul_f32_e32 v131, v69, v166
	v_mul_f32_e32 v132, v70, v166
	v_mul_f32_e32 v133, v71, v166
	v_mul_f32_e32 v138, v66, v166
	v_mul_f32_e32 v139, v67, v166
	v_max_f32_e32 v130, 0, v130
	v_max_f32_e32 v131, 0, v131
	v_max_f32_e32 v132, 0, v132
	v_max_f32_e32 v133, 0, v133
	v_max_f32_e32 v136, 0, v136
	v_max_f32_e32 v137, 0, v137
	v_max_f32_e32 v138, 0, v138
	v_max_f32_e32 v139, 0, v139
	v_pk_mul_f32 v[130:131], v[130:131], v[130:131]
	v_pk_mul_f32 v[132:133], v[132:133], v[132:133]
	v_pk_mul_f32 v[136:137], v[136:137], v[136:137]
	v_pk_mul_f32 v[138:139], v[138:139], v[138:139]
	v_cvt_pk_bf16_f32 v130, v130, v131
	v_cvt_pk_bf16_f32 v131, v132, v133
	v_cvt_pk_bf16_f32 v132, v136, v137
	v_cvt_pk_bf16_f32 v133, v138, v139
	global_store_dwordx4 v[134:135], v[130:133], off offset:256
	v_mul_f32_e32 v136, v56, v164
	v_mul_f32_e32 v137, v57, v164
	v_add_u32_e32 v130, s77, v172
	v_mad_i64_i32 v[130:131], s[16:17], s5, v130, 0
	v_lshl_add_u64 v[130:131], v[130:131], 1, s[0:1]
	v_lshl_add_u64 v[130:131], v[130:131], 0, s[20:21]
	v_lshl_add_u64 v[134:135], v[130:131], 0, v[128:129]
	v_mul_f32_e32 v130, v60, v164
	v_mul_f32_e32 v131, v61, v164
	v_mul_f32_e32 v132, v62, v164
	v_mul_f32_e32 v133, v63, v164
	v_mul_f32_e32 v138, v58, v164
	v_mul_f32_e32 v139, v59, v164
	v_max_f32_e32 v130, 0, v130
	v_max_f32_e32 v131, 0, v131
	v_max_f32_e32 v132, 0, v132
	v_max_f32_e32 v133, 0, v133
	v_max_f32_e32 v136, 0, v136
	v_max_f32_e32 v137, 0, v137
	v_max_f32_e32 v138, 0, v138
	v_max_f32_e32 v139, 0, v139
	v_pk_mul_f32 v[130:131], v[130:131], v[130:131]
	v_pk_mul_f32 v[132:133], v[132:133], v[132:133]
	v_pk_mul_f32 v[136:137], v[136:137], v[136:137]
	v_pk_mul_f32 v[138:139], v[138:139], v[138:139]
	v_cvt_pk_bf16_f32 v130, v130, v131
	v_cvt_pk_bf16_f32 v131, v132, v133
	v_cvt_pk_bf16_f32 v132, v136, v137
	v_cvt_pk_bf16_f32 v133, v138, v139
	global_store_dwordx4 v[134:135], v[130:133], off
	v_mul_f32_e32 v136, v24, v164
	v_mul_f32_e32 v137, v25, v164
	v_mul_f32_e32 v130, v28, v164
	v_mul_f32_e32 v131, v29, v164
	v_mul_f32_e32 v132, v30, v164
	v_mul_f32_e32 v133, v31, v164
	v_mul_f32_e32 v138, v26, v164
	v_mul_f32_e32 v139, v27, v164
	v_max_f32_e32 v130, 0, v130
	v_max_f32_e32 v131, 0, v131
	v_max_f32_e32 v132, 0, v132
	v_max_f32_e32 v133, 0, v133
	v_max_f32_e32 v136, 0, v136
	v_max_f32_e32 v137, 0, v137
	v_max_f32_e32 v138, 0, v138
	v_max_f32_e32 v139, 0, v139
	v_pk_mul_f32 v[130:131], v[130:131], v[130:131]
	v_pk_mul_f32 v[132:133], v[132:133], v[132:133]
	v_pk_mul_f32 v[136:137], v[136:137], v[136:137]
	v_pk_mul_f32 v[138:139], v[138:139], v[138:139]
	v_cvt_pk_bf16_f32 v130, v130, v131
	v_cvt_pk_bf16_f32 v131, v132, v133
	v_cvt_pk_bf16_f32 v132, v136, v137
	v_cvt_pk_bf16_f32 v133, v138, v139
	global_store_dwordx4 v[134:135], v[130:133], off offset:256
	v_mul_f32_e32 v136, v48, v160
	v_mul_f32_e32 v137, v49, v160
	v_mad_i64_i32 v[130:131], s[16:17], s5, v150, 0
	v_lshl_add_u64 v[130:131], v[130:131], 1, s[0:1]
	v_lshl_add_u64 v[130:131], v[130:131], 0, s[20:21]
	v_lshl_add_u64 v[134:135], v[130:131], 0, v[128:129]
	v_mul_f32_e32 v130, v52, v160
	v_mul_f32_e32 v131, v53, v160
	v_mul_f32_e32 v132, v54, v160
	v_mul_f32_e32 v133, v55, v160
	v_mul_f32_e32 v138, v50, v160
	v_mul_f32_e32 v139, v51, v160
	v_max_f32_e32 v130, 0, v130
	v_max_f32_e32 v131, 0, v131
	v_max_f32_e32 v132, 0, v132
	v_max_f32_e32 v133, 0, v133
	v_max_f32_e32 v136, 0, v136
	v_max_f32_e32 v137, 0, v137
	v_max_f32_e32 v138, 0, v138
	v_max_f32_e32 v139, 0, v139
	v_pk_mul_f32 v[130:131], v[130:131], v[130:131]
	v_pk_mul_f32 v[132:133], v[132:133], v[132:133]
	v_pk_mul_f32 v[136:137], v[136:137], v[136:137]
	v_pk_mul_f32 v[138:139], v[138:139], v[138:139]
	v_cvt_pk_bf16_f32 v130, v130, v131
	v_cvt_pk_bf16_f32 v131, v132, v133
	v_cvt_pk_bf16_f32 v132, v136, v137
	v_cvt_pk_bf16_f32 v133, v138, v139
	global_store_dwordx4 v[134:135], v[130:133], off
	v_mul_f32_e32 v136, v16, v160
	v_mul_f32_e32 v137, v17, v160
	v_mul_f32_e32 v130, v20, v160
	v_mul_f32_e32 v131, v21, v160
	v_mul_f32_e32 v132, v22, v160
	v_mul_f32_e32 v133, v23, v160
	v_mul_f32_e32 v138, v18, v160
	v_mul_f32_e32 v139, v19, v160
	v_max_f32_e32 v130, 0, v130
	v_max_f32_e32 v131, 0, v131
	v_max_f32_e32 v132, 0, v132
	v_max_f32_e32 v133, 0, v133
	v_max_f32_e32 v136, 0, v136
	v_max_f32_e32 v137, 0, v137
	v_max_f32_e32 v138, 0, v138
	v_max_f32_e32 v139, 0, v139
	v_pk_mul_f32 v[130:131], v[130:131], v[130:131]
	v_pk_mul_f32 v[132:133], v[132:133], v[132:133]
	v_pk_mul_f32 v[136:137], v[136:137], v[136:137]
	v_pk_mul_f32 v[138:139], v[138:139], v[138:139]
	v_cvt_pk_bf16_f32 v130, v130, v131
	v_cvt_pk_bf16_f32 v131, v132, v133
	v_cvt_pk_bf16_f32 v132, v136, v137
	v_cvt_pk_bf16_f32 v133, v138, v139
	global_store_dwordx4 v[134:135], v[130:133], off offset:256
	v_mul_f32_e32 v136, v40, v156
	v_mul_f32_e32 v137, v41, v156
	v_mad_i64_i32 v[130:131], s[16:17], s5, v148, 0
	v_lshl_add_u64 v[130:131], v[130:131], 1, s[0:1]
	v_lshl_add_u64 v[130:131], v[130:131], 0, s[20:21]
	v_lshl_add_u64 v[134:135], v[130:131], 0, v[128:129]
	v_mul_f32_e32 v130, v44, v156
	v_mul_f32_e32 v131, v45, v156
	v_mul_f32_e32 v132, v46, v156
	v_mul_f32_e32 v133, v47, v156
	v_mul_f32_e32 v138, v42, v156
	v_mul_f32_e32 v139, v43, v156
	v_max_f32_e32 v130, 0, v130
	v_max_f32_e32 v131, 0, v131
	v_max_f32_e32 v132, 0, v132
	v_max_f32_e32 v133, 0, v133
	v_max_f32_e32 v136, 0, v136
	v_max_f32_e32 v137, 0, v137
	v_max_f32_e32 v138, 0, v138
	v_max_f32_e32 v139, 0, v139
	v_pk_mul_f32 v[130:131], v[130:131], v[130:131]
	v_pk_mul_f32 v[132:133], v[132:133], v[132:133]
	v_pk_mul_f32 v[136:137], v[136:137], v[136:137]
	v_pk_mul_f32 v[138:139], v[138:139], v[138:139]
	v_cvt_pk_bf16_f32 v130, v130, v131
	v_cvt_pk_bf16_f32 v131, v132, v133
	v_cvt_pk_bf16_f32 v132, v136, v137
	v_cvt_pk_bf16_f32 v133, v138, v139
	global_store_dwordx4 v[134:135], v[130:133], off
	v_mul_f32_e32 v136, v8, v156
	v_mul_f32_e32 v137, v9, v156
	v_mul_f32_e32 v130, v12, v156
	v_mul_f32_e32 v131, v13, v156
	v_mul_f32_e32 v132, v14, v156
	v_mul_f32_e32 v133, v15, v156
	v_mul_f32_e32 v138, v10, v156
	v_mul_f32_e32 v139, v11, v156
	v_max_f32_e32 v130, 0, v130
	v_max_f32_e32 v131, 0, v131
	v_max_f32_e32 v132, 0, v132
	v_max_f32_e32 v133, 0, v133
	v_max_f32_e32 v136, 0, v136
	v_max_f32_e32 v137, 0, v137
	v_max_f32_e32 v138, 0, v138
	v_max_f32_e32 v139, 0, v139
	v_pk_mul_f32 v[130:131], v[130:131], v[130:131]
	v_pk_mul_f32 v[132:133], v[132:133], v[132:133]
	v_pk_mul_f32 v[136:137], v[136:137], v[136:137]
	v_pk_mul_f32 v[138:139], v[138:139], v[138:139]
	v_cvt_pk_bf16_f32 v130, v130, v131
	v_cvt_pk_bf16_f32 v131, v132, v133
	v_cvt_pk_bf16_f32 v132, v136, v137
	v_cvt_pk_bf16_f32 v133, v138, v139
	global_store_dwordx4 v[134:135], v[130:133], off offset:256
	v_mul_f32_e32 v134, v32, v152
	v_mul_f32_e32 v135, v33, v152
	v_mad_i64_i32 v[130:131], s[16:17], s5, v146, 0
	v_lshl_add_u64 v[130:131], v[130:131], 1, s[0:1]
	v_lshl_add_u64 v[130:131], v[130:131], 0, s[20:21]
	v_lshl_add_u64 v[132:133], v[130:131], 0, v[128:129]
	v_mul_f32_e32 v128, v36, v152
	v_mul_f32_e32 v129, v37, v152
	v_mul_f32_e32 v130, v38, v152
	v_mul_f32_e32 v131, v39, v152
	v_mul_f32_e32 v136, v34, v152
	v_mul_f32_e32 v137, v35, v152
	v_max_f32_e32 v128, 0, v128
	v_max_f32_e32 v129, 0, v129
	v_max_f32_e32 v130, 0, v130
	v_max_f32_e32 v131, 0, v131
	v_max_f32_e32 v134, 0, v134
	v_max_f32_e32 v135, 0, v135
	v_max_f32_e32 v136, 0, v136
	v_max_f32_e32 v137, 0, v137
	v_pk_mul_f32 v[128:129], v[128:129], v[128:129]
	v_pk_mul_f32 v[130:131], v[130:131], v[130:131]
	v_pk_mul_f32 v[134:135], v[134:135], v[134:135]
	v_pk_mul_f32 v[136:137], v[136:137], v[136:137]
	v_cvt_pk_bf16_f32 v128, v128, v129
	v_cvt_pk_bf16_f32 v129, v130, v131
	v_cvt_pk_bf16_f32 v130, v134, v135
	v_cvt_pk_bf16_f32 v131, v136, v137
	global_store_dwordx4 v[132:133], v[128:131], off
	v_mul_f32_e32 v134, v0, v152
	v_mul_f32_e32 v135, v1, v152
	v_mul_f32_e32 v128, v4, v152
	v_mul_f32_e32 v129, v5, v152
	v_mul_f32_e32 v130, v6, v152
	v_mul_f32_e32 v131, v7, v152
	v_mul_f32_e32 v136, v2, v152
	v_mul_f32_e32 v137, v3, v152
	v_max_f32_e32 v128, 0, v128
	v_max_f32_e32 v129, 0, v129
	v_max_f32_e32 v130, 0, v130
	v_max_f32_e32 v131, 0, v131
	v_max_f32_e32 v134, 0, v134
	v_max_f32_e32 v135, 0, v135
	v_max_f32_e32 v136, 0, v136
	v_max_f32_e32 v137, 0, v137
	v_pk_mul_f32 v[128:129], v[128:129], v[128:129]
	v_pk_mul_f32 v[130:131], v[130:131], v[130:131]
	v_pk_mul_f32 v[134:135], v[134:135], v[134:135]
	v_pk_mul_f32 v[136:137], v[136:137], v[136:137]
	v_cvt_pk_bf16_f32 v128, v128, v129
	v_cvt_pk_bf16_f32 v129, v130, v131
	v_cvt_pk_bf16_f32 v130, v134, v135
	v_cvt_pk_bf16_f32 v131, v136, v137
	global_store_dwordx4 v[132:133], v[128:131], off offset:256
	s_mov_b64 s[0:1], 0

.LBB0_1068:
	s_and_b64 vcc, exec, s[20:21]
	s_cbranch_vccz .LBB0_1071
	s_cmp_eq_u32 s28, 3
	s_mov_b64 s[0:1], -1
	s_cbranch_scc0 .LBB0_1071
	v_readlane_b32 s0, v251, 6
	s_ashr_i32 s67, s66, 31
	s_lshl_b64 s[20:21], s[66:67], 1
	v_mov_b32_e32 v128, s0
	v_readlane_b32 s0, v251, 7
	ds_read_b32 v128, v128
	v_pk_mul_f32 v[132:133], v[92:93], v[176:177] op_sel_hi:[1,0]
	v_mov_b32_e32 v129, s0
	v_readlane_b32 s0, v250, 53
	ds_read_b32 v129, v129
	v_pk_mul_f32 v[134:135], v[94:95], v[176:177] op_sel_hi:[1,0]
	v_mov_b32_e32 v130, s0
	ds_read_b32 v130, v130
	s_waitcnt lgkmcnt(0)
	v_readfirstlane_b32 s0, v128
	v_readfirstlane_b32 s1, v129
	v_pk_mul_f32 v[136:137], v[88:89], v[176:177] op_sel_hi:[1,0]
	v_ashrrev_i32_e32 v175, 31, v174
	v_readfirstlane_b32 s5, v130
	v_pk_mul_f32 v[138:139], v[90:91], v[176:177] op_sel_hi:[1,0]
	s_nop 0
	v_mad_i64_i32 v[128:129], s[16:17], s5, v144, 0
	v_lshl_add_u64 v[128:129], v[128:129], 1, s[0:1]
	v_lshl_add_u64 v[130:131], v[128:129], 0, s[20:21]
	v_pk_mul_f32 v[128:129], v[124:125], v[176:177] op_sel_hi:[1,0]
	s_nop 0
	v_pk_mul_f32 v[132:133], v[128:129], v[132:133]
	v_pk_mul_f32 v[128:129], v[126:127], v[176:177] op_sel_hi:[1,0]
	s_nop 0
	v_pk_mul_f32 v[134:135], v[128:129], v[134:135]
	v_pk_mul_f32 v[128:129], v[120:121], v[176:177] op_sel_hi:[1,0]
	s_nop 0
	v_pk_mul_f32 v[136:137], v[128:129], v[136:137]
	v_pk_mul_f32 v[128:129], v[122:123], v[176:177] op_sel_hi:[1,0]
	s_nop 0
	v_pk_mul_f32 v[138:139], v[128:129], v[138:139]
	v_lshlrev_b64 v[128:129], 1, v[174:175]
	v_lshl_add_u64 v[140:141], v[130:131], 0, v[128:129]
	v_cvt_pk_bf16_f32 v130, v132, v133
	v_cvt_pk_bf16_f32 v131, v134, v135
	v_cvt_pk_bf16_f32 v132, v136, v137
	v_cvt_pk_bf16_f32 v133, v138, v139
	global_store_dwordx4 v[140:141], v[130:133], off
	v_pk_mul_f32 v[134:135], v[84:85], v[170:171] op_sel_hi:[1,0]
	v_pk_mul_f32 v[136:137], v[86:87], v[170:171] op_sel_hi:[1,0]
	v_pk_mul_f32 v[132:133], v[116:117], v[170:171] op_sel_hi:[1,0]
	v_mad_i64_i32 v[130:131], s[16:17], s5, v162, 0
	v_pk_mul_f32 v[132:133], v[132:133], v[134:135]
	v_pk_mul_f32 v[134:135], v[118:119], v[170:171] op_sel_hi:[1,0]
	v_pk_mul_f32 v[138:139], v[80:81], v[170:171] op_sel_hi:[1,0]
	v_pk_mul_f32 v[134:135], v[134:135], v[136:137]
	v_pk_mul_f32 v[136:137], v[112:113], v[170:171] op_sel_hi:[1,0]
	v_lshl_add_u64 v[130:131], v[130:131], 1, s[0:1]
	v_pk_mul_f32 v[136:137], v[136:137], v[138:139]
	v_pk_mul_f32 v[138:139], v[114:115], v[170:171] op_sel_hi:[1,0]
	v_pk_mul_f32 v[140:141], v[82:83], v[170:171] op_sel_hi:[1,0]
	v_lshl_add_u64 v[130:131], v[130:131], 0, s[20:21]
	v_pk_mul_f32 v[138:139], v[138:139], v[140:141]
	v_lshl_add_u64 v[140:141], v[130:131], 0, v[128:129]
	v_cvt_pk_bf16_f32 v130, v132, v133
	v_cvt_pk_bf16_f32 v131, v134, v135
	v_cvt_pk_bf16_f32 v132, v136, v137
	v_cvt_pk_bf16_f32 v133, v138, v139
	global_store_dwordx4 v[140:141], v[130:133], off
	v_pk_mul_f32 v[134:135], v[76:77], v[168:169] op_sel_hi:[1,0]
	v_pk_mul_f32 v[136:137], v[78:79], v[168:169] op_sel_hi:[1,0]
	v_pk_mul_f32 v[132:133], v[108:109], v[168:169] op_sel_hi:[1,0]
	v_mad_i64_i32 v[130:131], s[16:17], s5, v158, 0
	v_pk_mul_f32 v[132:133], v[132:133], v[134:135]
	v_pk_mul_f32 v[134:135], v[110:111], v[168:169] op_sel_hi:[1,0]
	v_pk_mul_f32 v[138:139], v[72:73], v[168:169] op_sel_hi:[1,0]
	v_pk_mul_f32 v[134:135], v[134:135], v[136:137]
	v_pk_mul_f32 v[136:137], v[104:105], v[168:169] op_sel_hi:[1,0]
	v_lshl_add_u64 v[130:131], v[130:131], 1, s[0:1]
	v_pk_mul_f32 v[136:137], v[136:137], v[138:139]
	v_pk_mul_f32 v[138:139], v[106:107], v[168:169] op_sel_hi:[1,0]
	v_pk_mul_f32 v[140:141], v[74:75], v[168:169] op_sel_hi:[1,0]
	v_lshl_add_u64 v[130:131], v[130:131], 0, s[20:21]
	v_pk_mul_f32 v[138:139], v[138:139], v[140:141]
	v_lshl_add_u64 v[140:141], v[130:131], 0, v[128:129]
	v_cvt_pk_bf16_f32 v130, v132, v133
	v_cvt_pk_bf16_f32 v131, v134, v135
	v_cvt_pk_bf16_f32 v132, v136, v137
	v_cvt_pk_bf16_f32 v133, v138, v139
	global_store_dwordx4 v[140:141], v[130:133], off
	v_pk_mul_f32 v[134:135], v[68:69], v[166:167] op_sel_hi:[1,0]
	v_pk_mul_f32 v[136:137], v[70:71], v[166:167] op_sel_hi:[1,0]
	v_pk_mul_f32 v[132:133], v[100:101], v[166:167] op_sel_hi:[1,0]
	v_mad_i64_i32 v[130:131], s[16:17], s5, v154, 0
	v_pk_mul_f32 v[132:133], v[132:133], v[134:135]
	v_pk_mul_f32 v[134:135], v[102:103], v[166:167] op_sel_hi:[1,0]
	v_pk_mul_f32 v[138:139], v[64:65], v[166:167] op_sel_hi:[1,0]
	v_pk_mul_f32 v[134:135], v[134:135], v[136:137]
	v_pk_mul_f32 v[136:137], v[96:97], v[166:167] op_sel_hi:[1,0]
	v_lshl_add_u64 v[130:131], v[130:131], 1, s[0:1]
	v_pk_mul_f32 v[136:137], v[136:137], v[138:139]
	v_pk_mul_f32 v[138:139], v[98:99], v[166:167] op_sel_hi:[1,0]
	v_pk_mul_f32 v[140:141], v[66:67], v[166:167] op_sel_hi:[1,0]
	v_lshl_add_u64 v[130:131], v[130:131], 0, s[20:21]
	v_pk_mul_f32 v[138:139], v[138:139], v[140:141]
	v_lshl_add_u64 v[140:141], v[130:131], 0, v[128:129]
	v_cvt_pk_bf16_f32 v130, v132, v133
	v_cvt_pk_bf16_f32 v131, v134, v135
	v_cvt_pk_bf16_f32 v132, v136, v137
	v_cvt_pk_bf16_f32 v133, v138, v139
	global_store_dwordx4 v[140:141], v[130:133], off
	v_pk_mul_f32 v[134:135], v[28:29], v[164:165] op_sel_hi:[1,0]
	v_pk_mul_f32 v[136:137], v[30:31], v[164:165] op_sel_hi:[1,0]
	v_pk_mul_f32 v[132:133], v[60:61], v[164:165] op_sel_hi:[1,0]
	v_add_u32_e32 v130, s77, v172
	v_pk_mul_f32 v[132:133], v[132:133], v[134:135]
	v_pk_mul_f32 v[134:135], v[62:63], v[164:165] op_sel_hi:[1,0]
	v_mad_i64_i32 v[130:131], s[16:17], s5, v130, 0
	v_pk_mul_f32 v[134:135], v[134:135], v[136:137]
	v_pk_mul_f32 v[136:137], v[56:57], v[164:165] op_sel_hi:[1,0]
	v_pk_mul_f32 v[138:139], v[24:25], v[164:165] op_sel_hi:[1,0]
	v_lshl_add_u64 v[130:131], v[130:131], 1, s[0:1]
	v_pk_mul_f32 v[136:137], v[136:137], v[138:139]
	v_pk_mul_f32 v[138:139], v[58:59], v[164:165] op_sel_hi:[1,0]
	v_pk_mul_f32 v[140:141], v[26:27], v[164:165] op_sel_hi:[1,0]
	v_lshl_add_u64 v[130:131], v[130:131], 0, s[20:21]
	v_pk_mul_f32 v[138:139], v[138:139], v[140:141]
	v_lshl_add_u64 v[140:141], v[130:131], 0, v[128:129]
	v_cvt_pk_bf16_f32 v130, v132, v133
	v_cvt_pk_bf16_f32 v131, v134, v135
	v_cvt_pk_bf16_f32 v132, v136, v137
	v_cvt_pk_bf16_f32 v133, v138, v139
	global_store_dwordx4 v[140:141], v[130:133], off
	v_pk_mul_f32 v[134:135], v[20:21], v[160:161] op_sel_hi:[1,0]
	v_pk_mul_f32 v[136:137], v[22:23], v[160:161] op_sel_hi:[1,0]
	v_pk_mul_f32 v[132:133], v[52:53], v[160:161] op_sel_hi:[1,0]
	v_mad_i64_i32 v[130:131], s[16:17], s5, v150, 0
	v_pk_mul_f32 v[132:133], v[132:133], v[134:135]
	v_pk_mul_f32 v[134:135], v[54:55], v[160:161] op_sel_hi:[1,0]
	v_pk_mul_f32 v[138:139], v[16:17], v[160:161] op_sel_hi:[1,0]
	v_pk_mul_f32 v[134:135], v[134:135], v[136:137]
	v_pk_mul_f32 v[136:137], v[48:49], v[160:161] op_sel_hi:[1,0]
	v_lshl_add_u64 v[130:131], v[130:131], 1, s[0:1]
	v_pk_mul_f32 v[136:137], v[136:137], v[138:139]
	v_pk_mul_f32 v[138:139], v[50:51], v[160:161] op_sel_hi:[1,0]
	v_pk_mul_f32 v[140:141], v[18:19], v[160:161] op_sel_hi:[1,0]
	v_lshl_add_u64 v[130:131], v[130:131], 0, s[20:21]
	v_pk_mul_f32 v[138:139], v[138:139], v[140:141]
	v_lshl_add_u64 v[140:141], v[130:131], 0, v[128:129]
	v_cvt_pk_bf16_f32 v130, v132, v133
	v_cvt_pk_bf16_f32 v131, v134, v135
	v_cvt_pk_bf16_f32 v132, v136, v137
	v_cvt_pk_bf16_f32 v133, v138, v139
	global_store_dwordx4 v[140:141], v[130:133], off
	v_pk_mul_f32 v[134:135], v[12:13], v[156:157] op_sel_hi:[1,0]
	v_pk_mul_f32 v[136:137], v[14:15], v[156:157] op_sel_hi:[1,0]
	v_pk_mul_f32 v[132:133], v[44:45], v[156:157] op_sel_hi:[1,0]
	v_mad_i64_i32 v[130:131], s[16:17], s5, v148, 0
	v_pk_mul_f32 v[132:133], v[132:133], v[134:135]
	v_pk_mul_f32 v[134:135], v[46:47], v[156:157] op_sel_hi:[1,0]
	v_pk_mul_f32 v[138:139], v[8:9], v[156:157] op_sel_hi:[1,0]
	v_pk_mul_f32 v[134:135], v[134:135], v[136:137]
	v_pk_mul_f32 v[136:137], v[40:41], v[156:157] op_sel_hi:[1,0]
	v_lshl_add_u64 v[130:131], v[130:131], 1, s[0:1]
	v_pk_mul_f32 v[136:137], v[136:137], v[138:139]
	v_pk_mul_f32 v[138:139], v[42:43], v[156:157] op_sel_hi:[1,0]
	v_pk_mul_f32 v[140:141], v[10:11], v[156:157] op_sel_hi:[1,0]
	v_lshl_add_u64 v[130:131], v[130:131], 0, s[20:21]
	v_pk_mul_f32 v[138:139], v[138:139], v[140:141]
	v_lshl_add_u64 v[140:141], v[130:131], 0, v[128:129]
	v_cvt_pk_bf16_f32 v130, v132, v133
	v_cvt_pk_bf16_f32 v131, v134, v135
	v_cvt_pk_bf16_f32 v132, v136, v137
	v_cvt_pk_bf16_f32 v133, v138, v139
	global_store_dwordx4 v[140:141], v[130:133], off
	v_pk_mul_f32 v[134:135], v[4:5], v[152:153] op_sel_hi:[1,0]
	v_pk_mul_f32 v[136:137], v[6:7], v[152:153] op_sel_hi:[1,0]
	v_pk_mul_f32 v[132:133], v[36:37], v[152:153] op_sel_hi:[1,0]
	v_mad_i64_i32 v[130:131], s[16:17], s5, v146, 0
	v_pk_mul_f32 v[132:133], v[132:133], v[134:135]
	v_pk_mul_f32 v[134:135], v[38:39], v[152:153] op_sel_hi:[1,0]
	v_pk_mul_f32 v[138:139], v[0:1], v[152:153] op_sel_hi:[1,0]
	v_pk_mul_f32 v[134:135], v[134:135], v[136:137]
	v_pk_mul_f32 v[136:137], v[32:33], v[152:153] op_sel_hi:[1,0]
	v_lshl_add_u64 v[130:131], v[130:131], 1, s[0:1]
	v_pk_mul_f32 v[136:137], v[136:137], v[138:139]
	v_pk_mul_f32 v[138:139], v[34:35], v[152:153] op_sel_hi:[1,0]
	v_pk_mul_f32 v[140:141], v[2:3], v[152:153] op_sel_hi:[1,0]
	v_lshl_add_u64 v[130:131], v[130:131], 0, s[20:21]
	v_pk_mul_f32 v[138:139], v[138:139], v[140:141]
	v_lshl_add_u64 v[140:141], v[130:131], 0, v[128:129]
	v_cvt_pk_bf16_f32 v128, v132, v133
	v_cvt_pk_bf16_f32 v129, v134, v135
	v_cvt_pk_bf16_f32 v130, v136, v137
	v_cvt_pk_bf16_f32 v131, v138, v139
	global_store_dwordx4 v[140:141], v[128:131], off
	s_mov_b64 s[0:1], 0

.LBB0_1072:
	s_and_b64 vcc, exec, s[20:21]
	s_cbranch_vccz .LBB0_1074
	v_readlane_b32 s5, v251, 4
	v_readlane_b32 s16, v251, 7
	s_ashr_i32 s67, s66, 31
	v_mov_b32_e32 v128, s5
	ds_read_b32 v128, v128
	v_readlane_b32 s5, v251, 5
	v_ashrrev_i32_e32 v175, 31, v174
	v_lshlrev_b64 v[178:179], 1, v[174:175]
	v_mov_b32_e32 v129, s5
	ds_read_b32 v129, v129
	v_readlane_b32 s5, v251, 6
	s_waitcnt lgkmcnt(0)
	v_readfirstlane_b32 s20, v129
	v_mov_b32_e32 v130, s5
	v_readfirstlane_b32 s5, v128
	v_mov_b32_e32 v128, s16
	v_readlane_b32 s16, v250, 53
	ds_read_b32 v147, v130
	ds_read_b32 v149, v128
	v_mov_b32_e32 v128, s16
	s_lshl_b64 s[16:17], s[66:67], 2
	s_add_u32 s16, s5, s16
	s_addc_u32 s17, s20, s17
	ds_read_b32 v151, v128
	v_lshl_add_u64 v[128:129], v[174:175], 2, s[16:17]
	s_movk_i32 s5, 0xd000
	v_add_co_u32_e32 v130, vcc, s5, v128
	s_movk_i32 s16, 0xd000
	s_nop 0
	v_addc_co_u32_e32 v131, vcc, -1, v129, vcc
	global_load_dwordx4 v[140:143], v[130:131], off
	s_mov_b32 s17, -1
	v_lshl_add_u64 v[128:129], v[128:129], 0, s[16:17]
	global_load_dwordx4 v[136:139], v[128:129], off offset:16
	global_load_dwordx4 v[132:135], v[128:129], off offset:512
	s_nop 0
	global_load_dwordx4 v[128:131], v[128:129], off offset:528
	s_waitcnt lgkmcnt(0)
	v_readfirstlane_b32 s20, v147
	v_readfirstlane_b32 s21, v149
	v_readfirstlane_b32 s5, v151
	s_lshl_b64 s[50:51], s[66:67], 1
	s_waitcnt vmcnt(0)
	v_fma_f32 v147, v124, v176, v140
	v_fma_f32 v149, v125, v176, v141
	v_fma_f32 v151, v126, v176, v142
	v_fma_f32 v153, v127, v176, v143
	v_fma_f32 v155, v120, v176, v136
	v_fma_f32 v157, v121, v176, v137
	v_mul_f32_e32 v147, 0xbfb8aa3b, v147
	v_mul_f32_e32 v149, 0xbfb8aa3b, v149
	v_mul_f32_e32 v151, 0xbfb8aa3b, v151
	v_mul_f32_e32 v153, 0xbfb8aa3b, v153
	v_mul_f32_e32 v155, 0xbfb8aa3b, v155
	v_mul_f32_e32 v157, 0xbfb8aa3b, v157
	v_exp_f32_e32 v147, v147
	v_exp_f32_e32 v149, v149
	v_exp_f32_e32 v151, v151
	v_exp_f32_e32 v153, v153
	v_exp_f32_e32 v155, v155
	v_exp_f32_e32 v157, v157
	v_add_f32_e32 v147, 1.0, v147
	v_add_f32_e32 v149, 1.0, v149
	v_add_f32_e32 v151, 1.0, v151
	v_add_f32_e32 v153, 1.0, v153
	v_add_f32_e32 v155, 1.0, v155
	v_add_f32_e32 v157, 1.0, v157
	v_rcp_f32_e32 v147, v147
	v_rcp_f32_e32 v149, v149
	v_rcp_f32_e32 v151, v151
	v_rcp_f32_e32 v153, v153
	v_rcp_f32_e32 v155, v155
	v_rcp_f32_e32 v157, v157
	v_fma_f32 v159, v122, v176, v138
	v_fma_f32 v161, v123, v176, v139
	v_fma_f32 v167, v94, v176, v134
	v_fma_f32 v169, v95, v176, v135
	v_fma_f32 v171, v88, v176, v128
	v_mul_f32_e32 v159, 0xbfb8aa3b, v159
	v_mul_f32_e32 v161, 0xbfb8aa3b, v161
	v_cvt_pk_bf16_f32 v182, v147, v149
	v_cvt_pk_bf16_f32 v183, v151, v153
	v_cvt_pk_bf16_f32 v184, v155, v157
	v_fma_f32 v147, v89, v176, v129
	v_fma_f32 v153, v90, v176, v130
	v_fma_f32 v155, v91, v176, v131
	v_mul_f32_e32 v167, 0xbfb8aa3b, v167
	v_mul_f32_e32 v169, 0xbfb8aa3b, v169
	v_mul_f32_e32 v171, 0xbfb8aa3b, v171
	v_exp_f32_e32 v159, v159
	v_exp_f32_e32 v161, v161
	v_mul_f32_e32 v147, 0xbfb8aa3b, v147
	v_mul_f32_e32 v153, 0xbfb8aa3b, v153
	v_mul_f32_e32 v155, 0xbfb8aa3b, v155
	v_exp_f32_e32 v167, v167
	v_exp_f32_e32 v169, v169
	v_exp_f32_e32 v171, v171
	v_exp_f32_e32 v147, v147
	v_exp_f32_e32 v153, v153
	v_exp_f32_e32 v155, v155
	v_add_f32_e32 v159, 1.0, v159
	v_add_f32_e32 v161, 1.0, v161
	v_add_f32_e32 v167, 1.0, v167
	v_add_f32_e32 v169, 1.0, v169
	v_rcp_f32_e32 v159, v159
	v_rcp_f32_e32 v161, v161
	v_add_f32_e32 v151, 1.0, v171
	v_add_f32_e32 v147, 1.0, v147
	v_add_f32_e32 v153, 1.0, v153
	v_add_f32_e32 v155, 1.0, v155
	v_mad_i64_i32 v[180:181], s[16:17], s5, v144, 0
	v_fma_f32 v163, v92, v176, v132
	v_fma_f32 v165, v93, v176, v133
	v_rcp_f32_e32 v167, v167
	v_rcp_f32_e32 v149, v169
	v_rcp_f32_e32 v151, v151
	v_rcp_f32_e32 v147, v147
	v_rcp_f32_e32 v153, v153
	v_rcp_f32_e32 v155, v155
	v_lshl_add_u64 v[180:181], v[180:181], 1, s[20:21]
	v_mul_f32_e32 v163, 0xbfb8aa3b, v163
	v_mul_f32_e32 v165, 0xbfb8aa3b, v165
	v_lshl_add_u64 v[180:181], v[180:181], 0, s[50:51]
	v_exp_f32_e32 v163, v163
	v_exp_f32_e32 v165, v165
	v_lshl_add_u64 v[180:181], v[180:181], 0, v[178:179]
	v_cvt_pk_bf16_f32 v185, v159, v161
	global_store_dwordx4 v[180:181], v[182:185], off
	v_fma_f32 v157, v113, v170, v137
	v_fma_f32 v159, v114, v170, v138
	v_cvt_pk_bf16_f32 v183, v167, v149
	v_cvt_pk_bf16_f32 v184, v151, v147
	v_cvt_pk_bf16_f32 v185, v153, v155
	v_fma_f32 v147, v116, v170, v140
	v_fma_f32 v149, v117, v170, v141
	v_fma_f32 v151, v118, v170, v142
	v_fma_f32 v153, v119, v170, v143
	v_fma_f32 v155, v112, v170, v136
	v_fma_f32 v161, v115, v170, v139
	v_mul_f32_e32 v147, 0xbfb8aa3b, v147
	v_mul_f32_e32 v149, 0xbfb8aa3b, v149
	v_mul_f32_e32 v151, 0xbfb8aa3b, v151
	v_mul_f32_e32 v153, 0xbfb8aa3b, v153
	v_mul_f32_e32 v155, 0xbfb8aa3b, v155
	v_mul_f32_e32 v157, 0xbfb8aa3b, v157
	v_mul_f32_e32 v159, 0xbfb8aa3b, v159
	v_mul_f32_e32 v161, 0xbfb8aa3b, v161
	v_add_f32_e32 v163, 1.0, v163
	v_add_f32_e32 v165, 1.0, v165
	v_exp_f32_e32 v147, v147
	v_exp_f32_e32 v149, v149
	v_exp_f32_e32 v151, v151
	v_exp_f32_e32 v153, v153
	v_exp_f32_e32 v155, v155
	v_exp_f32_e32 v157, v157
	v_exp_f32_e32 v159, v159
	v_exp_f32_e32 v161, v161
	v_rcp_f32_e32 v163, v163
	v_rcp_f32_e32 v165, v165
	v_add_f32_e32 v147, 1.0, v147
	v_add_f32_e32 v149, 1.0, v149
	v_add_f32_e32 v151, 1.0, v151
	v_add_f32_e32 v153, 1.0, v153
	v_add_f32_e32 v155, 1.0, v155
	v_add_f32_e32 v157, 1.0, v157
	v_add_f32_e32 v159, 1.0, v159
	v_add_f32_e32 v161, 1.0, v161
	v_cvt_pk_bf16_f32 v182, v163, v165
	v_rcp_f32_e32 v147, v147
	v_rcp_f32_e32 v149, v149
	v_rcp_f32_e32 v151, v151
	v_rcp_f32_e32 v153, v153
	v_rcp_f32_e32 v155, v155
	v_rcp_f32_e32 v157, v157
	v_rcp_f32_e32 v159, v159
	v_rcp_f32_e32 v161, v161
	global_store_dwordx4 v[180:181], v[182:185], off offset:256
	v_mad_i64_i32 v[180:181], s[16:17], s5, v162, 0
	v_lshl_add_u64 v[180:181], v[180:181], 1, s[20:21]
	v_lshl_add_u64 v[180:181], v[180:181], 0, s[50:51]
	v_lshl_add_u64 v[184:185], v[180:181], 0, v[178:179]
	v_cvt_pk_bf16_f32 v180, v147, v149
	v_cvt_pk_bf16_f32 v181, v151, v153
	v_cvt_pk_bf16_f32 v182, v155, v157
	v_cvt_pk_bf16_f32 v183, v159, v161
	v_fma_f32 v147, v84, v170, v132
	v_fma_f32 v149, v85, v170, v133
	v_fma_f32 v151, v86, v170, v134
	v_fma_f32 v153, v87, v170, v135
	v_fma_f32 v155, v80, v170, v128
	v_fma_f32 v157, v81, v170, v129
	v_fma_f32 v159, v82, v170, v130
	v_fma_f32 v161, v83, v170, v131
	v_mul_f32_e32 v147, 0xbfb8aa3b, v147
	v_mul_f32_e32 v149, 0xbfb8aa3b, v149
	v_mul_f32_e32 v151, 0xbfb8aa3b, v151
	v_mul_f32_e32 v153, 0xbfb8aa3b, v153
	v_mul_f32_e32 v155, 0xbfb8aa3b, v155
	v_mul_f32_e32 v157, 0xbfb8aa3b, v157
	v_mul_f32_e32 v159, 0xbfb8aa3b, v159
	v_mul_f32_e32 v161, 0xbfb8aa3b, v161
	v_exp_f32_e32 v147, v147
	v_exp_f32_e32 v149, v149
	v_exp_f32_e32 v151, v151
	v_exp_f32_e32 v153, v153
	v_exp_f32_e32 v155, v155
	v_exp_f32_e32 v157, v157
	v_exp_f32_e32 v159, v159
	v_exp_f32_e32 v161, v161
	v_add_f32_e32 v147, 1.0, v147
	v_add_f32_e32 v149, 1.0, v149
	v_add_f32_e32 v151, 1.0, v151
	v_add_f32_e32 v153, 1.0, v153
	v_add_f32_e32 v155, 1.0, v155
	v_add_f32_e32 v157, 1.0, v157
	v_add_f32_e32 v159, 1.0, v159
	v_add_f32_e32 v161, 1.0, v161
	v_rcp_f32_e32 v147, v147
	v_rcp_f32_e32 v149, v149
	v_rcp_f32_e32 v151, v151
	v_rcp_f32_e32 v153, v153
	v_rcp_f32_e32 v155, v155
	v_rcp_f32_e32 v157, v157
	v_rcp_f32_e32 v159, v159
	v_rcp_f32_e32 v161, v161
	global_store_dwordx4 v[184:185], v[180:183], off
	s_nop 1
	v_cvt_pk_bf16_f32 v180, v147, v149
	v_cvt_pk_bf16_f32 v181, v151, v153
	v_cvt_pk_bf16_f32 v182, v155, v157
	v_cvt_pk_bf16_f32 v183, v159, v161
	v_fma_f32 v147, v108, v168, v140
	v_fma_f32 v149, v109, v168, v141
	v_fma_f32 v151, v110, v168, v142
	v_fma_f32 v153, v111, v168, v143
	v_fma_f32 v155, v104, v168, v136
	v_fma_f32 v157, v105, v168, v137
	v_fma_f32 v159, v106, v168, v138
	v_fma_f32 v161, v107, v168, v139
	v_mul_f32_e32 v147, 0xbfb8aa3b, v147
	v_mul_f32_e32 v149, 0xbfb8aa3b, v149
	v_mul_f32_e32 v151, 0xbfb8aa3b, v151
	v_mul_f32_e32 v153, 0xbfb8aa3b, v153
	v_mul_f32_e32 v155, 0xbfb8aa3b, v155
	v_mul_f32_e32 v157, 0xbfb8aa3b, v157
	v_mul_f32_e32 v159, 0xbfb8aa3b, v159
	v_mul_f32_e32 v161, 0xbfb8aa3b, v161
	v_exp_f32_e32 v147, v147
	v_exp_f32_e32 v149, v149
	v_exp_f32_e32 v151, v151
	v_exp_f32_e32 v153, v153
	v_exp_f32_e32 v155, v155
	v_exp_f32_e32 v157, v157
	v_exp_f32_e32 v159, v159
	v_exp_f32_e32 v161, v161
	v_add_f32_e32 v147, 1.0, v147
	v_add_f32_e32 v149, 1.0, v149
	v_add_f32_e32 v151, 1.0, v151
	v_add_f32_e32 v153, 1.0, v153
	v_add_f32_e32 v155, 1.0, v155
	v_add_f32_e32 v157, 1.0, v157
	v_add_f32_e32 v159, 1.0, v159
	v_add_f32_e32 v161, 1.0, v161
	v_rcp_f32_e32 v147, v147
	v_rcp_f32_e32 v149, v149
	v_rcp_f32_e32 v151, v151
	v_rcp_f32_e32 v153, v153
	v_rcp_f32_e32 v155, v155
	v_rcp_f32_e32 v157, v157
	v_rcp_f32_e32 v159, v159
	v_rcp_f32_e32 v161, v161
	global_store_dwordx4 v[184:185], v[180:183], off offset:256
	s_nop 1
	v_mad_i64_i32 v[180:181], s[16:17], s5, v158, 0
	v_lshl_add_u64 v[180:181], v[180:181], 1, s[20:21]
	v_lshl_add_u64 v[180:181], v[180:181], 0, s[50:51]
	v_lshl_add_u64 v[184:185], v[180:181], 0, v[178:179]
	v_cvt_pk_bf16_f32 v180, v147, v149
	v_cvt_pk_bf16_f32 v181, v151, v153
	v_cvt_pk_bf16_f32 v182, v155, v157
	v_cvt_pk_bf16_f32 v183, v159, v161
	v_fma_f32 v147, v76, v168, v132
	v_fma_f32 v149, v77, v168, v133
	v_fma_f32 v151, v78, v168, v134
	v_fma_f32 v153, v79, v168, v135
	v_fma_f32 v155, v72, v168, v128
	v_fma_f32 v157, v73, v168, v129
	v_fma_f32 v159, v74, v168, v130
	v_fma_f32 v161, v75, v168, v131
	v_mul_f32_e32 v147, 0xbfb8aa3b, v147
	v_mul_f32_e32 v149, 0xbfb8aa3b, v149
	v_mul_f32_e32 v151, 0xbfb8aa3b, v151
	v_mul_f32_e32 v153, 0xbfb8aa3b, v153
	v_mul_f32_e32 v155, 0xbfb8aa3b, v155
	v_mul_f32_e32 v157, 0xbfb8aa3b, v157
	v_mul_f32_e32 v159, 0xbfb8aa3b, v159
	v_mul_f32_e32 v161, 0xbfb8aa3b, v161
	v_exp_f32_e32 v147, v147
	v_exp_f32_e32 v149, v149
	v_exp_f32_e32 v151, v151
	v_exp_f32_e32 v153, v153
	v_exp_f32_e32 v155, v155
	v_exp_f32_e32 v157, v157
	v_exp_f32_e32 v159, v159
	v_exp_f32_e32 v161, v161
	v_add_f32_e32 v147, 1.0, v147
	v_add_f32_e32 v149, 1.0, v149
	v_add_f32_e32 v151, 1.0, v151
	v_add_f32_e32 v153, 1.0, v153
	v_add_f32_e32 v155, 1.0, v155
	v_add_f32_e32 v157, 1.0, v157
	v_add_f32_e32 v159, 1.0, v159
	v_add_f32_e32 v161, 1.0, v161
	v_rcp_f32_e32 v147, v147
	v_rcp_f32_e32 v149, v149
	v_rcp_f32_e32 v151, v151
	v_rcp_f32_e32 v153, v153
	v_rcp_f32_e32 v155, v155
	v_rcp_f32_e32 v157, v157
	v_rcp_f32_e32 v159, v159
	v_rcp_f32_e32 v161, v161
	global_store_dwordx4 v[184:185], v[180:183], off
	s_nop 1
	v_cvt_pk_bf16_f32 v180, v147, v149
	v_cvt_pk_bf16_f32 v181, v151, v153
	v_cvt_pk_bf16_f32 v182, v155, v157
	v_cvt_pk_bf16_f32 v183, v159, v161
	v_fma_f32 v147, v100, v166, v140
	v_fma_f32 v149, v101, v166, v141
	v_fma_f32 v151, v102, v166, v142
	v_fma_f32 v153, v103, v166, v143
	v_fma_f32 v155, v96, v166, v136
	v_fma_f32 v157, v97, v166, v137
	v_fma_f32 v159, v98, v166, v138
	v_fma_f32 v161, v99, v166, v139
	v_mul_f32_e32 v147, 0xbfb8aa3b, v147
	v_mul_f32_e32 v149, 0xbfb8aa3b, v149
	v_mul_f32_e32 v151, 0xbfb8aa3b, v151
	v_mul_f32_e32 v153, 0xbfb8aa3b, v153
	v_mul_f32_e32 v155, 0xbfb8aa3b, v155
	v_mul_f32_e32 v157, 0xbfb8aa3b, v157
	v_mul_f32_e32 v159, 0xbfb8aa3b, v159
	v_mul_f32_e32 v161, 0xbfb8aa3b, v161
	v_exp_f32_e32 v147, v147
	v_exp_f32_e32 v149, v149
	v_exp_f32_e32 v151, v151
	v_exp_f32_e32 v153, v153
	v_exp_f32_e32 v155, v155
	v_exp_f32_e32 v157, v157
	v_exp_f32_e32 v159, v159
	v_exp_f32_e32 v161, v161
	v_add_f32_e32 v147, 1.0, v147
	v_add_f32_e32 v149, 1.0, v149
	v_add_f32_e32 v151, 1.0, v151
	v_add_f32_e32 v153, 1.0, v153
	v_add_f32_e32 v155, 1.0, v155
	v_add_f32_e32 v157, 1.0, v157
	v_add_f32_e32 v159, 1.0, v159
	v_add_f32_e32 v161, 1.0, v161
	v_rcp_f32_e32 v147, v147
	v_rcp_f32_e32 v149, v149
	v_rcp_f32_e32 v151, v151
	v_rcp_f32_e32 v153, v153
	v_rcp_f32_e32 v155, v155
	v_rcp_f32_e32 v157, v157
	v_rcp_f32_e32 v159, v159
	v_rcp_f32_e32 v161, v161
	global_store_dwordx4 v[184:185], v[180:183], off offset:256
	s_nop 1
	v_mad_i64_i32 v[180:181], s[16:17], s5, v154, 0
	v_lshl_add_u64 v[180:181], v[180:181], 1, s[20:21]
	v_lshl_add_u64 v[180:181], v[180:181], 0, s[50:51]
	v_lshl_add_u64 v[184:185], v[180:181], 0, v[178:179]
	v_cvt_pk_bf16_f32 v180, v147, v149
	v_cvt_pk_bf16_f32 v181, v151, v153
	v_cvt_pk_bf16_f32 v182, v155, v157
	v_cvt_pk_bf16_f32 v183, v159, v161
	v_fma_f32 v147, v68, v166, v132
	v_fma_f32 v149, v69, v166, v133
	v_fma_f32 v151, v70, v166, v134
	v_fma_f32 v153, v71, v166, v135
	v_fma_f32 v155, v64, v166, v128
	v_fma_f32 v157, v65, v166, v129
	v_fma_f32 v159, v66, v166, v130
	v_fma_f32 v161, v67, v166, v131
	v_mul_f32_e32 v147, 0xbfb8aa3b, v147
	v_mul_f32_e32 v149, 0xbfb8aa3b, v149
	v_mul_f32_e32 v151, 0xbfb8aa3b, v151
	v_mul_f32_e32 v153, 0xbfb8aa3b, v153
	v_mul_f32_e32 v155, 0xbfb8aa3b, v155
	v_mul_f32_e32 v157, 0xbfb8aa3b, v157
	v_mul_f32_e32 v159, 0xbfb8aa3b, v159
	v_mul_f32_e32 v161, 0xbfb8aa3b, v161
	v_exp_f32_e32 v147, v147
	v_exp_f32_e32 v149, v149
	v_exp_f32_e32 v151, v151
	v_exp_f32_e32 v153, v153
	v_exp_f32_e32 v155, v155
	v_exp_f32_e32 v157, v157
	v_exp_f32_e32 v159, v159
	v_exp_f32_e32 v161, v161
	v_add_f32_e32 v147, 1.0, v147
	v_add_f32_e32 v149, 1.0, v149
	v_add_f32_e32 v151, 1.0, v151
	v_add_f32_e32 v153, 1.0, v153
	v_add_f32_e32 v155, 1.0, v155
	v_add_f32_e32 v157, 1.0, v157
	v_add_f32_e32 v159, 1.0, v159
	v_add_f32_e32 v161, 1.0, v161
	v_rcp_f32_e32 v147, v147
	v_rcp_f32_e32 v149, v149
	v_rcp_f32_e32 v151, v151
	v_rcp_f32_e32 v153, v153
	v_rcp_f32_e32 v155, v155
	v_rcp_f32_e32 v157, v157
	v_rcp_f32_e32 v159, v159
	v_rcp_f32_e32 v161, v161
	global_store_dwordx4 v[184:185], v[180:183], off
	s_nop 1
	v_cvt_pk_bf16_f32 v180, v147, v149
	v_cvt_pk_bf16_f32 v181, v151, v153
	v_cvt_pk_bf16_f32 v182, v155, v157
	v_cvt_pk_bf16_f32 v183, v159, v161
	v_add_u32_e32 v147, s77, v172
	v_fma_f32 v151, v62, v164, v142
	v_fma_f32 v153, v63, v164, v143
	global_store_dwordx4 v[184:185], v[180:183], off offset:256
	v_fma_f32 v149, v61, v164, v141
	v_mul_f32_e32 v151, 0xbfb8aa3b, v151
	v_mad_i64_i32 v[180:181], s[16:17], s5, v147, 0
	v_fma_f32 v147, v60, v164, v140
	v_mul_f32_e32 v153, 0xbfb8aa3b, v153
	v_mul_f32_e32 v147, 0xbfb8aa3b, v147
	v_mul_f32_e32 v149, 0xbfb8aa3b, v149
	v_exp_f32_e32 v151, v151
	v_exp_f32_e32 v153, v153
	v_exp_f32_e32 v147, v147
	v_exp_f32_e32 v149, v149
	v_add_f32_e32 v151, 1.0, v151
	v_add_f32_e32 v153, 1.0, v153
	v_add_f32_e32 v147, 1.0, v147
	v_add_f32_e32 v149, 1.0, v149
	v_rcp_f32_e32 v151, v151
	v_fma_f32 v155, v56, v164, v136
	v_fma_f32 v157, v57, v164, v137
	v_rcp_f32_e32 v153, v153
	v_fma_f32 v159, v58, v164, v138
	v_fma_f32 v161, v59, v164, v139
	v_rcp_f32_e32 v147, v147
	v_rcp_f32_e32 v149, v149
	v_mul_f32_e32 v155, 0xbfb8aa3b, v155
	v_mul_f32_e32 v157, 0xbfb8aa3b, v157
	v_mul_f32_e32 v159, 0xbfb8aa3b, v159
	v_mul_f32_e32 v161, 0xbfb8aa3b, v161
	v_lshl_add_u64 v[180:181], v[180:181], 1, s[20:21]
	v_exp_f32_e32 v155, v155
	v_exp_f32_e32 v157, v157
	v_exp_f32_e32 v159, v159
	v_exp_f32_e32 v161, v161
	v_lshl_add_u64 v[180:181], v[180:181], 0, s[50:51]
	v_lshl_add_u64 v[184:185], v[180:181], 0, v[178:179]
	v_cvt_pk_bf16_f32 v181, v151, v153
	v_fma_f32 v151, v30, v164, v134
	v_fma_f32 v153, v31, v164, v135
	v_cvt_pk_bf16_f32 v180, v147, v149
	v_fma_f32 v147, v28, v164, v132
	v_fma_f32 v149, v29, v164, v133
	v_mul_f32_e32 v151, 0xbfb8aa3b, v151
	v_mul_f32_e32 v153, 0xbfb8aa3b, v153
	v_add_f32_e32 v155, 1.0, v155
	v_add_f32_e32 v157, 1.0, v157
	v_add_f32_e32 v159, 1.0, v159
	v_add_f32_e32 v161, 1.0, v161
	v_mul_f32_e32 v147, 0xbfb8aa3b, v147
	v_mul_f32_e32 v149, 0xbfb8aa3b, v149
	v_exp_f32_e32 v151, v151
	v_exp_f32_e32 v153, v153
	v_rcp_f32_e32 v155, v155
	v_rcp_f32_e32 v157, v157
	v_rcp_f32_e32 v159, v159
	v_rcp_f32_e32 v161, v161
	v_exp_f32_e32 v147, v147
	v_exp_f32_e32 v149, v149
	v_add_f32_e32 v151, 1.0, v151
	v_add_f32_e32 v153, 1.0, v153
	v_cvt_pk_bf16_f32 v182, v155, v157
	v_cvt_pk_bf16_f32 v183, v159, v161
	v_add_f32_e32 v147, 1.0, v147
	v_add_f32_e32 v149, 1.0, v149
	v_rcp_f32_e32 v151, v151
	v_fma_f32 v155, v24, v164, v128
	v_fma_f32 v157, v25, v164, v129
	v_rcp_f32_e32 v153, v153
	v_fma_f32 v159, v26, v164, v130
	v_fma_f32 v161, v27, v164, v131
	v_rcp_f32_e32 v147, v147
	v_rcp_f32_e32 v149, v149
	v_mul_f32_e32 v155, 0xbfb8aa3b, v155
	v_mul_f32_e32 v157, 0xbfb8aa3b, v157
	v_mul_f32_e32 v159, 0xbfb8aa3b, v159
	v_mul_f32_e32 v161, 0xbfb8aa3b, v161
	v_exp_f32_e32 v155, v155
	v_exp_f32_e32 v157, v157
	v_exp_f32_e32 v159, v159
	v_exp_f32_e32 v161, v161
	global_store_dwordx4 v[184:185], v[180:183], off
	v_add_f32_e32 v155, 1.0, v155
	v_add_f32_e32 v157, 1.0, v157
	v_cvt_pk_bf16_f32 v181, v151, v153
	v_fma_f32 v151, v54, v160, v142
	v_fma_f32 v153, v55, v160, v143
	v_cvt_pk_bf16_f32 v180, v147, v149
	v_fma_f32 v147, v52, v160, v140
	v_fma_f32 v149, v53, v160, v141
	v_mul_f32_e32 v151, 0xbfb8aa3b, v151
	v_mul_f32_e32 v153, 0xbfb8aa3b, v153
	v_add_f32_e32 v159, 1.0, v159
	v_add_f32_e32 v161, 1.0, v161
	v_mul_f32_e32 v147, 0xbfb8aa3b, v147
	v_mul_f32_e32 v149, 0xbfb8aa3b, v149
	v_exp_f32_e32 v151, v151
	v_exp_f32_e32 v153, v153
	v_rcp_f32_e32 v155, v155
	v_rcp_f32_e32 v157, v157
	v_rcp_f32_e32 v159, v159
	v_rcp_f32_e32 v161, v161
	v_exp_f32_e32 v147, v147
	v_exp_f32_e32 v149, v149
	v_add_f32_e32 v151, 1.0, v151
	v_add_f32_e32 v153, 1.0, v153
	v_cvt_pk_bf16_f32 v182, v155, v157
	v_cvt_pk_bf16_f32 v183, v159, v161
	v_add_f32_e32 v147, 1.0, v147
	v_add_f32_e32 v149, 1.0, v149
	v_rcp_f32_e32 v151, v151
	v_fma_f32 v155, v48, v160, v136
	v_fma_f32 v157, v49, v160, v137
	v_rcp_f32_e32 v153, v153
	v_fma_f32 v159, v50, v160, v138
	v_fma_f32 v161, v51, v160, v139
	global_store_dwordx4 v[184:185], v[180:183], off offset:256
	v_rcp_f32_e32 v147, v147
	v_rcp_f32_e32 v149, v149
	v_mad_i64_i32 v[180:181], s[16:17], s5, v150, 0
	v_mul_f32_e32 v155, 0xbfb8aa3b, v155
	v_mul_f32_e32 v157, 0xbfb8aa3b, v157
	v_mul_f32_e32 v159, 0xbfb8aa3b, v159
	v_mul_f32_e32 v161, 0xbfb8aa3b, v161
	v_lshl_add_u64 v[180:181], v[180:181], 1, s[20:21]
	v_exp_f32_e32 v155, v155
	v_exp_f32_e32 v157, v157
	v_exp_f32_e32 v159, v159
	v_exp_f32_e32 v161, v161
	v_lshl_add_u64 v[180:181], v[180:181], 0, s[50:51]
	v_lshl_add_u64 v[184:185], v[180:181], 0, v[178:179]
	v_cvt_pk_bf16_f32 v181, v151, v153
	v_fma_f32 v151, v22, v160, v134
	v_fma_f32 v153, v23, v160, v135
	v_cvt_pk_bf16_f32 v180, v147, v149
	v_fma_f32 v147, v20, v160, v132
	v_fma_f32 v149, v21, v160, v133
	v_mul_f32_e32 v151, 0xbfb8aa3b, v151
	v_mul_f32_e32 v153, 0xbfb8aa3b, v153
	v_add_f32_e32 v155, 1.0, v155
	v_add_f32_e32 v157, 1.0, v157
	v_add_f32_e32 v159, 1.0, v159
	v_add_f32_e32 v161, 1.0, v161
	v_mul_f32_e32 v147, 0xbfb8aa3b, v147
	v_mul_f32_e32 v149, 0xbfb8aa3b, v149
	v_exp_f32_e32 v151, v151
	v_exp_f32_e32 v153, v153
	v_rcp_f32_e32 v155, v155
	v_rcp_f32_e32 v157, v157
	v_rcp_f32_e32 v159, v159
	v_rcp_f32_e32 v161, v161
	v_exp_f32_e32 v147, v147
	v_exp_f32_e32 v149, v149
	v_add_f32_e32 v151, 1.0, v151
	v_add_f32_e32 v153, 1.0, v153
	v_cvt_pk_bf16_f32 v182, v155, v157
	v_cvt_pk_bf16_f32 v183, v159, v161
	v_add_f32_e32 v147, 1.0, v147
	v_add_f32_e32 v149, 1.0, v149
	v_rcp_f32_e32 v151, v151
	v_fma_f32 v155, v16, v160, v128
	v_fma_f32 v157, v17, v160, v129
	v_rcp_f32_e32 v153, v153
	v_fma_f32 v159, v18, v160, v130
	v_fma_f32 v161, v19, v160, v131
	v_rcp_f32_e32 v147, v147
	v_rcp_f32_e32 v149, v149
	v_mul_f32_e32 v155, 0xbfb8aa3b, v155
	v_mul_f32_e32 v157, 0xbfb8aa3b, v157
	v_mul_f32_e32 v159, 0xbfb8aa3b, v159
	v_mul_f32_e32 v161, 0xbfb8aa3b, v161
	v_exp_f32_e32 v155, v155
	v_exp_f32_e32 v157, v157
	v_exp_f32_e32 v159, v159
	v_exp_f32_e32 v161, v161
	global_store_dwordx4 v[184:185], v[180:183], off
	v_add_f32_e32 v155, 1.0, v155
	v_add_f32_e32 v157, 1.0, v157
	v_cvt_pk_bf16_f32 v181, v151, v153
	v_fma_f32 v151, v46, v156, v142
	v_fma_f32 v153, v47, v156, v143
	v_cvt_pk_bf16_f32 v180, v147, v149
	v_fma_f32 v147, v44, v156, v140
	v_fma_f32 v149, v45, v156, v141
	v_mul_f32_e32 v151, 0xbfb8aa3b, v151
	v_mul_f32_e32 v153, 0xbfb8aa3b, v153
	v_add_f32_e32 v159, 1.0, v159
	v_add_f32_e32 v161, 1.0, v161
	v_mul_f32_e32 v147, 0xbfb8aa3b, v147
	v_mul_f32_e32 v149, 0xbfb8aa3b, v149
	v_exp_f32_e32 v151, v151
	v_exp_f32_e32 v153, v153
	v_rcp_f32_e32 v155, v155
	v_rcp_f32_e32 v157, v157
	v_rcp_f32_e32 v159, v159
	v_rcp_f32_e32 v161, v161
	v_exp_f32_e32 v147, v147
	v_exp_f32_e32 v149, v149
	v_add_f32_e32 v151, 1.0, v151
	v_add_f32_e32 v153, 1.0, v153
	v_cvt_pk_bf16_f32 v182, v155, v157
	v_cvt_pk_bf16_f32 v183, v159, v161
	v_add_f32_e32 v147, 1.0, v147
	v_add_f32_e32 v149, 1.0, v149
	v_rcp_f32_e32 v151, v151
	v_rcp_f32_e32 v153, v153
	global_store_dwordx4 v[184:185], v[180:183], off offset:256
	v_rcp_f32_e32 v147, v147
	v_rcp_f32_e32 v149, v149
	v_mad_i64_i32 v[180:181], s[16:17], s5, v148, 0
	v_fma_f32 v155, v40, v156, v136
	v_fma_f32 v157, v41, v156, v137
	v_fma_f32 v159, v42, v156, v138
	v_fma_f32 v161, v43, v156, v139
	v_lshl_add_u64 v[180:181], v[180:181], 1, s[20:21]
	v_mul_f32_e32 v155, 0xbfb8aa3b, v155
	v_mul_f32_e32 v157, 0xbfb8aa3b, v157
	v_mul_f32_e32 v159, 0xbfb8aa3b, v159
	v_mul_f32_e32 v161, 0xbfb8aa3b, v161
	v_lshl_add_u64 v[180:181], v[180:181], 0, s[50:51]
	v_exp_f32_e32 v155, v155
	v_exp_f32_e32 v157, v157
	v_exp_f32_e32 v159, v159
	v_exp_f32_e32 v161, v161
	v_lshl_add_u64 v[184:185], v[180:181], 0, v[178:179]
	v_cvt_pk_bf16_f32 v181, v151, v153
	v_fma_f32 v151, v14, v156, v134
	v_fma_f32 v153, v15, v156, v135
	v_cvt_pk_bf16_f32 v180, v147, v149
	v_fma_f32 v147, v12, v156, v132
	v_fma_f32 v149, v13, v156, v133
	v_mul_f32_e32 v151, 0xbfb8aa3b, v151
	v_mul_f32_e32 v153, 0xbfb8aa3b, v153
	v_mul_f32_e32 v147, 0xbfb8aa3b, v147
	v_mul_f32_e32 v149, 0xbfb8aa3b, v149
	v_exp_f32_e32 v151, v151
	v_exp_f32_e32 v153, v153
	v_add_f32_e32 v155, 1.0, v155
	v_add_f32_e32 v157, 1.0, v157
	v_add_f32_e32 v159, 1.0, v159
	v_add_f32_e32 v161, 1.0, v161
	v_exp_f32_e32 v147, v147
	v_exp_f32_e32 v149, v149
	v_rcp_f32_e32 v155, v155
	v_rcp_f32_e32 v157, v157
	v_rcp_f32_e32 v159, v159
	v_rcp_f32_e32 v161, v161
	v_fma_f32 v136, v32, v152, v136
	v_mul_f32_e32 v136, 0xbfb8aa3b, v136
	v_fma_f32 v137, v33, v152, v137
	v_add_f32_e32 v151, 1.0, v151
	v_add_f32_e32 v153, 1.0, v153
	v_exp_f32_e32 v136, v136
	v_mul_f32_e32 v137, 0xbfb8aa3b, v137
	v_add_f32_e32 v147, 1.0, v147
	v_add_f32_e32 v149, 1.0, v149
	v_rcp_f32_e32 v151, v151
	v_rcp_f32_e32 v153, v153
	v_exp_f32_e32 v137, v137
	v_cvt_pk_bf16_f32 v182, v155, v157
	v_cvt_pk_bf16_f32 v183, v159, v161
	v_rcp_f32_e32 v147, v147
	v_rcp_f32_e32 v149, v149
	v_fma_f32 v155, v8, v156, v128
	v_fma_f32 v157, v9, v156, v129
	v_fma_f32 v159, v10, v156, v130
	v_fma_f32 v161, v11, v156, v131
	v_mul_f32_e32 v155, 0xbfb8aa3b, v155
	v_mul_f32_e32 v157, 0xbfb8aa3b, v157
	v_mul_f32_e32 v159, 0xbfb8aa3b, v159
	v_mul_f32_e32 v161, 0xbfb8aa3b, v161
	v_exp_f32_e32 v155, v155
	v_exp_f32_e32 v157, v157
	v_exp_f32_e32 v159, v159
	v_exp_f32_e32 v161, v161
	v_fma_f32 v140, v36, v152, v140
	v_add_f32_e32 v136, 1.0, v136
	global_store_dwordx4 v[184:185], v[180:183], off
	v_mul_f32_e32 v140, 0xbfb8aa3b, v140
	v_fma_f32 v142, v38, v152, v142
	v_cvt_pk_bf16_f32 v181, v151, v153
	v_rcp_f32_e32 v151, v136
	v_add_f32_e32 v136, 1.0, v137
	v_fma_f32 v137, v34, v152, v138
	v_cvt_pk_bf16_f32 v180, v147, v149
	v_exp_f32_e32 v147, v140
	v_fma_f32 v140, v37, v152, v141
	v_fmac_f32_e32 v143, v39, v152
	v_mul_f32_e32 v137, 0xbfb8aa3b, v137
	v_fmac_f32_e32 v139, v35, v152
	v_mul_f32_e32 v140, 0xbfb8aa3b, v140
	v_mul_f32_e32 v142, 0xbfb8aa3b, v142
	v_mul_f32_e32 v143, 0xbfb8aa3b, v143
	v_exp_f32_e32 v137, v137
	v_mul_f32_e32 v138, 0xbfb8aa3b, v139
	v_add_f32_e32 v155, 1.0, v155
	v_add_f32_e32 v157, 1.0, v157
	v_add_f32_e32 v159, 1.0, v159
	v_add_f32_e32 v161, 1.0, v161
	v_exp_f32_e32 v149, v140
	v_exp_f32_e32 v142, v142
	v_exp_f32_e32 v143, v143
	v_exp_f32_e32 v138, v138
	v_rcp_f32_e32 v155, v155
	v_rcp_f32_e32 v157, v157
	v_rcp_f32_e32 v159, v159
	v_rcp_f32_e32 v161, v161
	v_rcp_f32_e32 v139, v136
	v_add_f32_e32 v136, 1.0, v137
	v_fma_f32 v128, v0, v152, v128
	v_add_f32_e32 v147, 1.0, v147
	v_add_f32_e32 v149, 1.0, v149
	v_add_f32_e32 v142, 1.0, v142
	v_add_f32_e32 v143, 1.0, v143
	v_rcp_f32_e32 v153, v136
	v_add_f32_e32 v136, 1.0, v138
	v_mul_f32_e32 v128, 0xbfb8aa3b, v128
	v_fma_f32 v129, v1, v152, v129
	v_cvt_pk_bf16_f32 v182, v155, v157
	v_cvt_pk_bf16_f32 v183, v159, v161
	v_rcp_f32_e32 v147, v147
	v_rcp_f32_e32 v149, v149
	v_rcp_f32_e32 v142, v142
	v_rcp_f32_e32 v143, v143
	v_rcp_f32_e32 v155, v136
	v_exp_f32_e32 v128, v128
	v_mul_f32_e32 v129, 0xbfb8aa3b, v129
	global_store_dwordx4 v[184:185], v[180:183], off offset:256
	v_exp_f32_e32 v129, v129
	v_cvt_pk_bf16_f32 v136, v147, v149
	v_mad_i64_i32 v[180:181], s[16:17], s5, v146, 0
	v_lshl_add_u64 v[180:181], v[180:181], 1, s[20:21]
	v_lshl_add_u64 v[180:181], v[180:181], 0, s[50:51]
	v_lshl_add_u64 v[140:141], v[180:181], 0, v[178:179]
	v_cvt_pk_bf16_f32 v137, v142, v143
	v_cvt_pk_bf16_f32 v138, v151, v139
	v_cvt_pk_bf16_f32 v139, v153, v155
	v_add_f32_e32 v128, 1.0, v128
	global_store_dwordx4 v[140:141], v[136:139], off
	v_fma_f32 v132, v4, v152, v132
	v_fma_f32 v133, v5, v152, v133
	v_rcp_f32_e32 v136, v128
	v_add_f32_e32 v128, 1.0, v129
	v_fma_f32 v129, v2, v152, v130
	v_fma_f32 v134, v6, v152, v134
	v_fmac_f32_e32 v135, v7, v152
	v_mul_f32_e32 v129, 0xbfb8aa3b, v129
	v_fmac_f32_e32 v131, v3, v152
	v_mul_f32_e32 v132, 0xbfb8aa3b, v132
	v_mul_f32_e32 v133, 0xbfb8aa3b, v133
	v_mul_f32_e32 v134, 0xbfb8aa3b, v134
	v_mul_f32_e32 v135, 0xbfb8aa3b, v135
	v_exp_f32_e32 v129, v129
	v_mul_f32_e32 v130, 0xbfb8aa3b, v131
	v_exp_f32_e32 v132, v132
	v_exp_f32_e32 v133, v133
	v_exp_f32_e32 v134, v134
	v_exp_f32_e32 v135, v135
	v_exp_f32_e32 v130, v130
	v_rcp_f32_e32 v131, v128
	v_add_f32_e32 v128, 1.0, v129
	v_add_f32_e32 v132, 1.0, v132
	v_add_f32_e32 v133, 1.0, v133
	v_add_f32_e32 v134, 1.0, v134
	v_add_f32_e32 v135, 1.0, v135
	v_rcp_f32_e32 v137, v128
	v_add_f32_e32 v128, 1.0, v130
	v_rcp_f32_e32 v132, v132
	v_rcp_f32_e32 v133, v133
	v_rcp_f32_e32 v134, v134
	v_rcp_f32_e32 v135, v135
	v_rcp_f32_e32 v138, v128
	v_cvt_pk_bf16_f32 v128, v132, v133
	v_cvt_pk_bf16_f32 v130, v136, v131
	v_cvt_pk_bf16_f32 v129, v134, v135
	v_cvt_pk_bf16_f32 v131, v137, v138
	global_store_dwordx4 v[140:141], v[128:131], off offset:256

.LBB0_1075:
	s_and_b64 vcc, exec, s[20:21]
	s_cbranch_vccz .LBB0_1080
	s_cmp_gt_i32 s28, 0
	s_mov_b64 s[20:21], -1
	s_cbranch_scc0 .LBB0_1078
	v_pk_mul_f32 v[132:133], v[124:125], v[176:177] op_sel_hi:[1,0]
	v_readlane_b32 s5, v251, 4
	v_mul_f32_e32 v134, 0x3d372713, v132
	v_mul_f32_e32 v135, 0x3d372713, v133
	v_mul_f32_e32 v134, v132, v134
	v_mul_f32_e32 v135, v133, v135
	v_fma_f32 v134, v132, v134, v132
	v_fma_f32 v135, v133, v135, v133
	v_mul_f32_e32 v134, 0x3fcc422a, v134
	v_mul_f32_e32 v135, 0x3fcc422a, v135
	v_mul_f32_e32 v134, 0xbfb8aa3b, v134
	v_mul_f32_e32 v135, 0xbfb8aa3b, v135
	v_exp_f32_e32 v134, v134
	v_exp_f32_e32 v135, v135
	v_mov_b32_e32 v128, s5
	ds_read_b32 v128, v128
	v_add_f32_e32 v134, 1.0, v134
	v_add_f32_e32 v135, 1.0, v135
	v_rcp_f32_e32 v134, v134
	v_rcp_f32_e32 v135, v135
	v_readlane_b32 s5, v251, 5
	s_ashr_i32 s67, s66, 31
	v_ashrrev_i32_e32 v175, 31, v174
	v_pk_mul_f32 v[132:133], v[132:133], v[134:135]
	v_pk_mul_f32 v[134:135], v[126:127], v[176:177] op_sel_hi:[1,0]
	s_waitcnt lgkmcnt(0)
	v_mov_b32_e32 v128, s5
	v_mul_f32_e32 v136, 0x3d372713, v134
	v_mul_f32_e32 v137, 0x3d372713, v135
	v_mul_f32_e32 v136, v134, v136
	v_mul_f32_e32 v137, v135, v137
	v_fma_f32 v136, v134, v136, v134
	v_fma_f32 v137, v135, v137, v135
	v_mul_f32_e32 v136, 0x3fcc422a, v136
	v_mul_f32_e32 v137, 0x3fcc422a, v137
	v_mul_f32_e32 v136, 0xbfb8aa3b, v136
	v_mul_f32_e32 v137, 0xbfb8aa3b, v137
	v_exp_f32_e32 v136, v136
	v_exp_f32_e32 v137, v137
	ds_read_b32 v128, v128
	v_readlane_b32 s5, v251, 6
	v_add_f32_e32 v136, 1.0, v136
	v_add_f32_e32 v137, 1.0, v137
	v_rcp_f32_e32 v136, v136
	v_rcp_f32_e32 v137, v137
	s_waitcnt lgkmcnt(0)
	v_mov_b32_e32 v128, s5
	ds_read_b32 v128, v128
	v_readlane_b32 s5, v251, 7
	v_pk_mul_f32 v[134:135], v[134:135], v[136:137]
	v_pk_mul_f32 v[136:137], v[120:121], v[176:177] op_sel_hi:[1,0]
	s_lshl_b64 s[50:51], s[66:67], 1
	v_mul_f32_e32 v138, 0x3d372713, v136
	v_mul_f32_e32 v139, 0x3d372713, v137
	v_mul_f32_e32 v138, v136, v138
	v_mul_f32_e32 v139, v137, v139
	v_fma_f32 v138, v136, v138, v136
	v_fma_f32 v139, v137, v139, v137
	v_mul_f32_e32 v138, 0x3fcc422a, v138
	v_mul_f32_e32 v139, 0x3fcc422a, v139
	v_mul_f32_e32 v138, 0xbfb8aa3b, v138
	v_mul_f32_e32 v139, 0xbfb8aa3b, v139
	v_exp_f32_e32 v138, v138
	v_exp_f32_e32 v139, v139
	s_waitcnt lgkmcnt(0)
	v_readfirstlane_b32 s30, v128
	v_mov_b32_e32 v128, s5
	v_add_f32_e32 v138, 1.0, v138
	v_add_f32_e32 v139, 1.0, v139
	v_rcp_f32_e32 v138, v138
	v_rcp_f32_e32 v139, v139
	ds_read_b32 v128, v128
	v_readlane_b32 s5, v250, 53
	v_cvt_pk_bf16_f32 v132, v132, v133
	v_pk_mul_f32 v[136:137], v[136:137], v[138:139]
	v_pk_mul_f32 v[138:139], v[122:123], v[176:177] op_sel_hi:[1,0]
	s_waitcnt lgkmcnt(0)
	v_readfirstlane_b32 s31, v128
	v_mul_f32_e32 v140, 0x3d372713, v138
	v_mul_f32_e32 v141, 0x3d372713, v139
	v_mul_f32_e32 v140, v138, v140
	v_mul_f32_e32 v141, v139, v141
	v_fma_f32 v140, v138, v140, v138
	v_fma_f32 v141, v139, v141, v139
	v_mul_f32_e32 v140, 0x3fcc422a, v140
	v_mul_f32_e32 v141, 0x3fcc422a, v141
	v_mul_f32_e32 v140, 0xbfb8aa3b, v140
	v_mul_f32_e32 v141, 0xbfb8aa3b, v141
	v_mov_b32_e32 v128, s5
	v_exp_f32_e32 v140, v140
	v_exp_f32_e32 v141, v141
	ds_read_b32 v128, v128
	v_cvt_pk_bf16_f32 v133, v134, v135
	v_add_f32_e32 v140, 1.0, v140
	v_add_f32_e32 v141, 1.0, v141
	v_rcp_f32_e32 v140, v140
	v_rcp_f32_e32 v141, v141
	s_waitcnt lgkmcnt(0)
	v_readfirstlane_b32 s5, v128
	v_cvt_pk_bf16_f32 v134, v136, v137
	s_mov_b64 s[20:21], 0
	v_mad_i64_i32 v[128:129], s[16:17], s5, v144, 0
	v_lshl_add_u64 v[128:129], v[128:129], 1, s[30:31]
	v_lshl_add_u64 v[130:131], v[128:129], 0, s[50:51]
	v_lshlrev_b64 v[128:129], 1, v[174:175]
	v_pk_mul_f32 v[138:139], v[138:139], v[140:141]
	v_lshl_add_u64 v[130:131], v[130:131], 0, v[128:129]
	v_cvt_pk_bf16_f32 v135, v138, v139
	global_store_dwordx4 v[130:131], v[132:135], off
	s_nop 1
	v_pk_mul_f32 v[132:133], v[92:93], v[176:177] op_sel_hi:[1,0]
	s_nop 0
	v_mul_f32_e32 v134, 0x3d372713, v132
	v_mul_f32_e32 v135, 0x3d372713, v133
	v_mul_f32_e32 v134, v132, v134
	v_mul_f32_e32 v135, v133, v135
	v_fma_f32 v134, v132, v134, v132
	v_fma_f32 v135, v133, v135, v133
	v_mul_f32_e32 v134, 0x3fcc422a, v134
	v_mul_f32_e32 v135, 0x3fcc422a, v135
	v_mul_f32_e32 v134, 0xbfb8aa3b, v134
	v_mul_f32_e32 v135, 0xbfb8aa3b, v135
	v_exp_f32_e32 v134, v134
	v_exp_f32_e32 v135, v135
	v_add_f32_e32 v134, 1.0, v134
	v_add_f32_e32 v135, 1.0, v135
	v_rcp_f32_e32 v134, v134
	v_rcp_f32_e32 v135, v135
	s_nop 0
	v_pk_mul_f32 v[132:133], v[132:133], v[134:135]
	v_pk_mul_f32 v[134:135], v[94:95], v[176:177] op_sel_hi:[1,0]
	v_cvt_pk_bf16_f32 v132, v132, v133
	v_mul_f32_e32 v136, 0x3d372713, v134
	v_mul_f32_e32 v137, 0x3d372713, v135
	v_mul_f32_e32 v136, v134, v136
	v_mul_f32_e32 v137, v135, v137
	v_fma_f32 v136, v134, v136, v134
	v_fma_f32 v137, v135, v137, v135
	v_mul_f32_e32 v136, 0x3fcc422a, v136
	v_mul_f32_e32 v137, 0x3fcc422a, v137
	v_mul_f32_e32 v136, 0xbfb8aa3b, v136
	v_mul_f32_e32 v137, 0xbfb8aa3b, v137
	v_exp_f32_e32 v136, v136
	v_exp_f32_e32 v137, v137
	v_add_f32_e32 v136, 1.0, v136
	v_add_f32_e32 v137, 1.0, v137
	v_rcp_f32_e32 v136, v136
	v_rcp_f32_e32 v137, v137
	s_nop 0
	v_pk_mul_f32 v[134:135], v[134:135], v[136:137]
	v_pk_mul_f32 v[136:137], v[88:89], v[176:177] op_sel_hi:[1,0]
	v_cvt_pk_bf16_f32 v133, v134, v135
	v_mul_f32_e32 v138, 0x3d372713, v136
	v_mul_f32_e32 v139, 0x3d372713, v137
	v_mul_f32_e32 v138, v136, v138
	v_mul_f32_e32 v139, v137, v139
	v_fma_f32 v138, v136, v138, v136
	v_fma_f32 v139, v137, v139, v137
	v_mul_f32_e32 v138, 0x3fcc422a, v138
	v_mul_f32_e32 v139, 0x3fcc422a, v139
	v_mul_f32_e32 v138, 0xbfb8aa3b, v138
	v_mul_f32_e32 v139, 0xbfb8aa3b, v139
	v_exp_f32_e32 v138, v138
	v_exp_f32_e32 v139, v139
	v_add_f32_e32 v138, 1.0, v138
	v_add_f32_e32 v139, 1.0, v139
	v_rcp_f32_e32 v138, v138
	v_rcp_f32_e32 v139, v139
	s_nop 0
	v_pk_mul_f32 v[136:137], v[136:137], v[138:139]
	v_pk_mul_f32 v[138:139], v[90:91], v[176:177] op_sel_hi:[1,0]
	v_cvt_pk_bf16_f32 v134, v136, v137
	v_mul_f32_e32 v140, 0x3d372713, v138
	v_mul_f32_e32 v141, 0x3d372713, v139
	v_mul_f32_e32 v140, v138, v140
	v_mul_f32_e32 v141, v139, v141
	v_fma_f32 v140, v138, v140, v138
	v_fma_f32 v141, v139, v141, v139
	v_mul_f32_e32 v140, 0x3fcc422a, v140
	v_mul_f32_e32 v141, 0x3fcc422a, v141
	v_mul_f32_e32 v140, 0xbfb8aa3b, v140
	v_mul_f32_e32 v141, 0xbfb8aa3b, v141
	v_exp_f32_e32 v140, v140
	v_exp_f32_e32 v141, v141
	v_add_f32_e32 v140, 1.0, v140
	v_add_f32_e32 v141, 1.0, v141
	v_rcp_f32_e32 v140, v140
	v_rcp_f32_e32 v141, v141
	s_nop 0
	v_pk_mul_f32 v[138:139], v[138:139], v[140:141]
	s_nop 0
	v_cvt_pk_bf16_f32 v135, v138, v139
	global_store_dwordx4 v[130:131], v[132:135], off offset:256
	v_mad_i64_i32 v[130:131], s[16:17], s5, v162, 0
	s_nop 0
	v_pk_mul_f32 v[132:133], v[116:117], v[170:171] op_sel_hi:[1,0]
	v_lshl_add_u64 v[130:131], v[130:131], 1, s[30:31]
	v_mul_f32_e32 v134, 0x3d372713, v132
	v_mul_f32_e32 v135, 0x3d372713, v133
	v_mul_f32_e32 v134, v132, v134
	v_mul_f32_e32 v135, v133, v135
	v_fma_f32 v134, v132, v134, v132
	v_fma_f32 v135, v133, v135, v133
	v_mul_f32_e32 v134, 0x3fcc422a, v134
	v_mul_f32_e32 v135, 0x3fcc422a, v135
	v_mul_f32_e32 v134, 0xbfb8aa3b, v134
	v_mul_f32_e32 v135, 0xbfb8aa3b, v135
	v_exp_f32_e32 v134, v134
	v_exp_f32_e32 v135, v135
	v_lshl_add_u64 v[130:131], v[130:131], 0, s[50:51]
	v_lshl_add_u64 v[130:131], v[130:131], 0, v[128:129]
	v_add_f32_e32 v134, 1.0, v134
	v_add_f32_e32 v135, 1.0, v135
	v_rcp_f32_e32 v134, v134
	v_rcp_f32_e32 v135, v135
	s_nop 0
	v_pk_mul_f32 v[132:133], v[132:133], v[134:135]
	v_pk_mul_f32 v[134:135], v[118:119], v[170:171] op_sel_hi:[1,0]
	v_cvt_pk_bf16_f32 v132, v132, v133
	v_mul_f32_e32 v136, 0x3d372713, v134
	v_mul_f32_e32 v137, 0x3d372713, v135
	v_mul_f32_e32 v136, v134, v136
	v_mul_f32_e32 v137, v135, v137
	v_fma_f32 v136, v134, v136, v134
	v_fma_f32 v137, v135, v137, v135
	v_mul_f32_e32 v136, 0x3fcc422a, v136
	v_mul_f32_e32 v137, 0x3fcc422a, v137
	v_mul_f32_e32 v136, 0xbfb8aa3b, v136
	v_mul_f32_e32 v137, 0xbfb8aa3b, v137
	v_exp_f32_e32 v136, v136
	v_exp_f32_e32 v137, v137
	v_add_f32_e32 v136, 1.0, v136
	v_add_f32_e32 v137, 1.0, v137
	v_rcp_f32_e32 v136, v136
	v_rcp_f32_e32 v137, v137
	s_nop 0
	v_pk_mul_f32 v[134:135], v[134:135], v[136:137]
	v_pk_mul_f32 v[136:137], v[112:113], v[170:171] op_sel_hi:[1,0]
	v_cvt_pk_bf16_f32 v133, v134, v135
	v_mul_f32_e32 v138, 0x3d372713, v136
	v_mul_f32_e32 v139, 0x3d372713, v137
	v_mul_f32_e32 v138, v136, v138
	v_mul_f32_e32 v139, v137, v139
	v_fma_f32 v138, v136, v138, v136
	v_fma_f32 v139, v137, v139, v137
	v_mul_f32_e32 v138, 0x3fcc422a, v138
	v_mul_f32_e32 v139, 0x3fcc422a, v139
	v_mul_f32_e32 v138, 0xbfb8aa3b, v138
	v_mul_f32_e32 v139, 0xbfb8aa3b, v139
	v_exp_f32_e32 v138, v138
	v_exp_f32_e32 v139, v139
	v_add_f32_e32 v138, 1.0, v138
	v_add_f32_e32 v139, 1.0, v139
	v_rcp_f32_e32 v138, v138
	v_rcp_f32_e32 v139, v139
	s_nop 0
	v_pk_mul_f32 v[136:137], v[136:137], v[138:139]
	v_pk_mul_f32 v[138:139], v[114:115], v[170:171] op_sel_hi:[1,0]
	v_cvt_pk_bf16_f32 v134, v136, v137
	v_mul_f32_e32 v140, 0x3d372713, v138
	v_mul_f32_e32 v141, 0x3d372713, v139
	v_mul_f32_e32 v140, v138, v140
	v_mul_f32_e32 v141, v139, v141
	v_fma_f32 v140, v138, v140, v138
	v_fma_f32 v141, v139, v141, v139
	v_mul_f32_e32 v140, 0x3fcc422a, v140
	v_mul_f32_e32 v141, 0x3fcc422a, v141
	v_mul_f32_e32 v140, 0xbfb8aa3b, v140
	v_mul_f32_e32 v141, 0xbfb8aa3b, v141
	v_exp_f32_e32 v140, v140
	v_exp_f32_e32 v141, v141
	v_add_f32_e32 v140, 1.0, v140
	v_add_f32_e32 v141, 1.0, v141
	v_rcp_f32_e32 v140, v140
	v_rcp_f32_e32 v141, v141
	s_nop 0
	v_pk_mul_f32 v[138:139], v[138:139], v[140:141]
	s_nop 0
	v_cvt_pk_bf16_f32 v135, v138, v139
	global_store_dwordx4 v[130:131], v[132:135], off
	s_nop 1
	v_pk_mul_f32 v[132:133], v[84:85], v[170:171] op_sel_hi:[1,0]
	s_nop 0
	v_mul_f32_e32 v134, 0x3d372713, v132
	v_mul_f32_e32 v135, 0x3d372713, v133
	v_mul_f32_e32 v134, v132, v134
	v_mul_f32_e32 v135, v133, v135
	v_fma_f32 v134, v132, v134, v132
	v_fma_f32 v135, v133, v135, v133
	v_mul_f32_e32 v134, 0x3fcc422a, v134
	v_mul_f32_e32 v135, 0x3fcc422a, v135
	v_mul_f32_e32 v134, 0xbfb8aa3b, v134
	v_mul_f32_e32 v135, 0xbfb8aa3b, v135
	v_exp_f32_e32 v134, v134
	v_exp_f32_e32 v135, v135
	v_add_f32_e32 v134, 1.0, v134
	v_add_f32_e32 v135, 1.0, v135
	v_rcp_f32_e32 v134, v134
	v_rcp_f32_e32 v135, v135
	s_nop 0
	v_pk_mul_f32 v[132:133], v[132:133], v[134:135]
	v_pk_mul_f32 v[134:135], v[86:87], v[170:171] op_sel_hi:[1,0]
	v_cvt_pk_bf16_f32 v132, v132, v133
	v_mul_f32_e32 v136, 0x3d372713, v134
	v_mul_f32_e32 v137, 0x3d372713, v135
	v_mul_f32_e32 v136, v134, v136
	v_mul_f32_e32 v137, v135, v137
	v_fma_f32 v136, v134, v136, v134
	v_fma_f32 v137, v135, v137, v135
	v_mul_f32_e32 v136, 0x3fcc422a, v136
	v_mul_f32_e32 v137, 0x3fcc422a, v137
	v_mul_f32_e32 v136, 0xbfb8aa3b, v136
	v_mul_f32_e32 v137, 0xbfb8aa3b, v137
	v_exp_f32_e32 v136, v136
	v_exp_f32_e32 v137, v137
	v_add_f32_e32 v136, 1.0, v136
	v_add_f32_e32 v137, 1.0, v137
	v_rcp_f32_e32 v136, v136
	v_rcp_f32_e32 v137, v137
	s_nop 0
	v_pk_mul_f32 v[134:135], v[134:135], v[136:137]
	v_pk_mul_f32 v[136:137], v[80:81], v[170:171] op_sel_hi:[1,0]
	v_cvt_pk_bf16_f32 v133, v134, v135
	v_mul_f32_e32 v138, 0x3d372713, v136
	v_mul_f32_e32 v139, 0x3d372713, v137
	v_mul_f32_e32 v138, v136, v138
	v_mul_f32_e32 v139, v137, v139
	v_fma_f32 v138, v136, v138, v136
	v_fma_f32 v139, v137, v139, v137
	v_mul_f32_e32 v138, 0x3fcc422a, v138
	v_mul_f32_e32 v139, 0x3fcc422a, v139
	v_mul_f32_e32 v138, 0xbfb8aa3b, v138
	v_mul_f32_e32 v139, 0xbfb8aa3b, v139
	v_exp_f32_e32 v138, v138
	v_exp_f32_e32 v139, v139
	v_add_f32_e32 v138, 1.0, v138
	v_add_f32_e32 v139, 1.0, v139
	v_rcp_f32_e32 v138, v138
	v_rcp_f32_e32 v139, v139
	s_nop 0
	v_pk_mul_f32 v[136:137], v[136:137], v[138:139]
	v_pk_mul_f32 v[138:139], v[82:83], v[170:171] op_sel_hi:[1,0]
	v_cvt_pk_bf16_f32 v134, v136, v137
	v_mul_f32_e32 v140, 0x3d372713, v138
	v_mul_f32_e32 v141, 0x3d372713, v139
	v_mul_f32_e32 v140, v138, v140
	v_mul_f32_e32 v141, v139, v141
	v_fma_f32 v140, v138, v140, v138
	v_fma_f32 v141, v139, v141, v139
	v_mul_f32_e32 v140, 0x3fcc422a, v140
	v_mul_f32_e32 v141, 0x3fcc422a, v141
	v_mul_f32_e32 v140, 0xbfb8aa3b, v140
	v_mul_f32_e32 v141, 0xbfb8aa3b, v141
	v_exp_f32_e32 v140, v140
	v_exp_f32_e32 v141, v141
	v_add_f32_e32 v140, 1.0, v140
	v_add_f32_e32 v141, 1.0, v141
	v_rcp_f32_e32 v140, v140
	v_rcp_f32_e32 v141, v141
	s_nop 0
	v_pk_mul_f32 v[138:139], v[138:139], v[140:141]
	s_nop 0
	v_cvt_pk_bf16_f32 v135, v138, v139
	global_store_dwordx4 v[130:131], v[132:135], off offset:256
	v_mad_i64_i32 v[130:131], s[16:17], s5, v158, 0
	s_nop 0
	v_pk_mul_f32 v[132:133], v[108:109], v[168:169] op_sel_hi:[1,0]
	v_lshl_add_u64 v[130:131], v[130:131], 1, s[30:31]
	v_mul_f32_e32 v134, 0x3d372713, v132
	v_mul_f32_e32 v135, 0x3d372713, v133
	v_mul_f32_e32 v134, v132, v134
	v_mul_f32_e32 v135, v133, v135
	v_fma_f32 v134, v132, v134, v132
	v_fma_f32 v135, v133, v135, v133
	v_mul_f32_e32 v134, 0x3fcc422a, v134
	v_mul_f32_e32 v135, 0x3fcc422a, v135
	v_mul_f32_e32 v134, 0xbfb8aa3b, v134
	v_mul_f32_e32 v135, 0xbfb8aa3b, v135
	v_exp_f32_e32 v134, v134
	v_exp_f32_e32 v135, v135
	v_lshl_add_u64 v[130:131], v[130:131], 0, s[50:51]
	v_lshl_add_u64 v[130:131], v[130:131], 0, v[128:129]
	v_add_f32_e32 v134, 1.0, v134
	v_add_f32_e32 v135, 1.0, v135
	v_rcp_f32_e32 v134, v134
	v_rcp_f32_e32 v135, v135
	s_nop 0
	v_pk_mul_f32 v[132:133], v[132:133], v[134:135]
	v_pk_mul_f32 v[134:135], v[110:111], v[168:169] op_sel_hi:[1,0]
	v_cvt_pk_bf16_f32 v132, v132, v133
	v_mul_f32_e32 v136, 0x3d372713, v134
	v_mul_f32_e32 v137, 0x3d372713, v135
	v_mul_f32_e32 v136, v134, v136
	v_mul_f32_e32 v137, v135, v137
	v_fma_f32 v136, v134, v136, v134
	v_fma_f32 v137, v135, v137, v135
	v_mul_f32_e32 v136, 0x3fcc422a, v136
	v_mul_f32_e32 v137, 0x3fcc422a, v137
	v_mul_f32_e32 v136, 0xbfb8aa3b, v136
	v_mul_f32_e32 v137, 0xbfb8aa3b, v137
	v_exp_f32_e32 v136, v136
	v_exp_f32_e32 v137, v137
	v_add_f32_e32 v136, 1.0, v136
	v_add_f32_e32 v137, 1.0, v137
	v_rcp_f32_e32 v136, v136
	v_rcp_f32_e32 v137, v137
	s_nop 0
	v_pk_mul_f32 v[134:135], v[134:135], v[136:137]
	v_pk_mul_f32 v[136:137], v[104:105], v[168:169] op_sel_hi:[1,0]
	v_cvt_pk_bf16_f32 v133, v134, v135
	v_mul_f32_e32 v138, 0x3d372713, v136
	v_mul_f32_e32 v139, 0x3d372713, v137
	v_mul_f32_e32 v138, v136, v138
	v_mul_f32_e32 v139, v137, v139
	v_fma_f32 v138, v136, v138, v136
	v_fma_f32 v139, v137, v139, v137
	v_mul_f32_e32 v138, 0x3fcc422a, v138
	v_mul_f32_e32 v139, 0x3fcc422a, v139
	v_mul_f32_e32 v138, 0xbfb8aa3b, v138
	v_mul_f32_e32 v139, 0xbfb8aa3b, v139
	v_exp_f32_e32 v138, v138
	v_exp_f32_e32 v139, v139
	v_add_f32_e32 v138, 1.0, v138
	v_add_f32_e32 v139, 1.0, v139
	v_rcp_f32_e32 v138, v138
	v_rcp_f32_e32 v139, v139
	s_nop 0
	v_pk_mul_f32 v[136:137], v[136:137], v[138:139]
	v_pk_mul_f32 v[138:139], v[106:107], v[168:169] op_sel_hi:[1,0]
	v_cvt_pk_bf16_f32 v134, v136, v137
	v_mul_f32_e32 v140, 0x3d372713, v138
	v_mul_f32_e32 v141, 0x3d372713, v139
	v_mul_f32_e32 v140, v138, v140
	v_mul_f32_e32 v141, v139, v141
	v_fma_f32 v140, v138, v140, v138
	v_fma_f32 v141, v139, v141, v139
	v_mul_f32_e32 v140, 0x3fcc422a, v140
	v_mul_f32_e32 v141, 0x3fcc422a, v141
	v_mul_f32_e32 v140, 0xbfb8aa3b, v140
	v_mul_f32_e32 v141, 0xbfb8aa3b, v141
	v_exp_f32_e32 v140, v140
	v_exp_f32_e32 v141, v141
	v_add_f32_e32 v140, 1.0, v140
	v_add_f32_e32 v141, 1.0, v141
	v_rcp_f32_e32 v140, v140
	v_rcp_f32_e32 v141, v141
	s_nop 0
	v_pk_mul_f32 v[138:139], v[138:139], v[140:141]
	s_nop 0
	v_cvt_pk_bf16_f32 v135, v138, v139
	global_store_dwordx4 v[130:131], v[132:135], off
	s_nop 1
	v_pk_mul_f32 v[132:133], v[76:77], v[168:169] op_sel_hi:[1,0]
	s_nop 0
	v_mul_f32_e32 v134, 0x3d372713, v132
	v_mul_f32_e32 v135, 0x3d372713, v133
	v_mul_f32_e32 v134, v132, v134
	v_mul_f32_e32 v135, v133, v135
	v_fma_f32 v134, v132, v134, v132
	v_fma_f32 v135, v133, v135, v133
	v_mul_f32_e32 v134, 0x3fcc422a, v134
	v_mul_f32_e32 v135, 0x3fcc422a, v135
	v_mul_f32_e32 v134, 0xbfb8aa3b, v134
	v_mul_f32_e32 v135, 0xbfb8aa3b, v135
	v_exp_f32_e32 v134, v134
	v_exp_f32_e32 v135, v135
	v_add_f32_e32 v134, 1.0, v134
	v_add_f32_e32 v135, 1.0, v135
	v_rcp_f32_e32 v134, v134
	v_rcp_f32_e32 v135, v135
	s_nop 0
	v_pk_mul_f32 v[132:133], v[132:133], v[134:135]
	v_pk_mul_f32 v[134:135], v[78:79], v[168:169] op_sel_hi:[1,0]
	v_cvt_pk_bf16_f32 v132, v132, v133
	v_mul_f32_e32 v136, 0x3d372713, v134
	v_mul_f32_e32 v137, 0x3d372713, v135
	v_mul_f32_e32 v136, v134, v136
	v_mul_f32_e32 v137, v135, v137
	v_fma_f32 v136, v134, v136, v134
	v_fma_f32 v137, v135, v137, v135
	v_mul_f32_e32 v136, 0x3fcc422a, v136
	v_mul_f32_e32 v137, 0x3fcc422a, v137
	v_mul_f32_e32 v136, 0xbfb8aa3b, v136
	v_mul_f32_e32 v137, 0xbfb8aa3b, v137
	v_exp_f32_e32 v136, v136
	v_exp_f32_e32 v137, v137
	v_add_f32_e32 v136, 1.0, v136
	v_add_f32_e32 v137, 1.0, v137
	v_rcp_f32_e32 v136, v136
	v_rcp_f32_e32 v137, v137
	s_nop 0
	v_pk_mul_f32 v[134:135], v[134:135], v[136:137]
	v_pk_mul_f32 v[136:137], v[72:73], v[168:169] op_sel_hi:[1,0]
	v_cvt_pk_bf16_f32 v133, v134, v135
	v_mul_f32_e32 v138, 0x3d372713, v136
	v_mul_f32_e32 v139, 0x3d372713, v137
	v_mul_f32_e32 v138, v136, v138
	v_mul_f32_e32 v139, v137, v139
	v_fma_f32 v138, v136, v138, v136
	v_fma_f32 v139, v137, v139, v137
	v_mul_f32_e32 v138, 0x3fcc422a, v138
	v_mul_f32_e32 v139, 0x3fcc422a, v139
	v_mul_f32_e32 v138, 0xbfb8aa3b, v138
	v_mul_f32_e32 v139, 0xbfb8aa3b, v139
	v_exp_f32_e32 v138, v138
	v_exp_f32_e32 v139, v139
	v_add_f32_e32 v138, 1.0, v138
	v_add_f32_e32 v139, 1.0, v139
	v_rcp_f32_e32 v138, v138
	v_rcp_f32_e32 v139, v139
	s_nop 0
	v_pk_mul_f32 v[136:137], v[136:137], v[138:139]
	v_pk_mul_f32 v[138:139], v[74:75], v[168:169] op_sel_hi:[1,0]
	v_cvt_pk_bf16_f32 v134, v136, v137
	v_mul_f32_e32 v140, 0x3d372713, v138
	v_mul_f32_e32 v141, 0x3d372713, v139
	v_mul_f32_e32 v140, v138, v140
	v_mul_f32_e32 v141, v139, v141
	v_fma_f32 v140, v138, v140, v138
	v_fma_f32 v141, v139, v141, v139
	v_mul_f32_e32 v140, 0x3fcc422a, v140
	v_mul_f32_e32 v141, 0x3fcc422a, v141
	v_mul_f32_e32 v140, 0xbfb8aa3b, v140
	v_mul_f32_e32 v141, 0xbfb8aa3b, v141
	v_exp_f32_e32 v140, v140
	v_exp_f32_e32 v141, v141
	v_add_f32_e32 v140, 1.0, v140
	v_add_f32_e32 v141, 1.0, v141
	v_rcp_f32_e32 v140, v140
	v_rcp_f32_e32 v141, v141
	s_nop 0
	v_pk_mul_f32 v[138:139], v[138:139], v[140:141]
	s_nop 0
	v_cvt_pk_bf16_f32 v135, v138, v139
	global_store_dwordx4 v[130:131], v[132:135], off offset:256
	v_mad_i64_i32 v[130:131], s[16:17], s5, v154, 0
	s_nop 0
	v_pk_mul_f32 v[132:133], v[100:101], v[166:167] op_sel_hi:[1,0]
	v_lshl_add_u64 v[130:131], v[130:131], 1, s[30:31]
	v_mul_f32_e32 v134, 0x3d372713, v132
	v_mul_f32_e32 v135, 0x3d372713, v133
	v_mul_f32_e32 v134, v132, v134
	v_mul_f32_e32 v135, v133, v135
	v_fma_f32 v134, v132, v134, v132
	v_fma_f32 v135, v133, v135, v133
	v_mul_f32_e32 v134, 0x3fcc422a, v134
	v_mul_f32_e32 v135, 0x3fcc422a, v135
	v_mul_f32_e32 v134, 0xbfb8aa3b, v134
	v_mul_f32_e32 v135, 0xbfb8aa3b, v135
	v_exp_f32_e32 v134, v134
	v_exp_f32_e32 v135, v135
	v_lshl_add_u64 v[130:131], v[130:131], 0, s[50:51]
	v_lshl_add_u64 v[130:131], v[130:131], 0, v[128:129]
	v_add_f32_e32 v134, 1.0, v134
	v_add_f32_e32 v135, 1.0, v135
	v_rcp_f32_e32 v134, v134
	v_rcp_f32_e32 v135, v135
	s_nop 0
	v_pk_mul_f32 v[132:133], v[132:133], v[134:135]
	v_pk_mul_f32 v[134:135], v[102:103], v[166:167] op_sel_hi:[1,0]
	v_cvt_pk_bf16_f32 v132, v132, v133
	v_mul_f32_e32 v136, 0x3d372713, v134
	v_mul_f32_e32 v137, 0x3d372713, v135
	v_mul_f32_e32 v136, v134, v136
	v_mul_f32_e32 v137, v135, v137
	v_fma_f32 v136, v134, v136, v134
	v_fma_f32 v137, v135, v137, v135
	v_mul_f32_e32 v136, 0x3fcc422a, v136
	v_mul_f32_e32 v137, 0x3fcc422a, v137
	v_mul_f32_e32 v136, 0xbfb8aa3b, v136
	v_mul_f32_e32 v137, 0xbfb8aa3b, v137
	v_exp_f32_e32 v136, v136
	v_exp_f32_e32 v137, v137
	v_add_f32_e32 v136, 1.0, v136
	v_add_f32_e32 v137, 1.0, v137
	v_rcp_f32_e32 v136, v136
	v_rcp_f32_e32 v137, v137
	s_nop 0
	v_pk_mul_f32 v[134:135], v[134:135], v[136:137]
	v_pk_mul_f32 v[136:137], v[96:97], v[166:167] op_sel_hi:[1,0]
	v_cvt_pk_bf16_f32 v133, v134, v135
	v_mul_f32_e32 v138, 0x3d372713, v136
	v_mul_f32_e32 v139, 0x3d372713, v137
	v_mul_f32_e32 v138, v136, v138
	v_mul_f32_e32 v139, v137, v139
	v_fma_f32 v138, v136, v138, v136
	v_fma_f32 v139, v137, v139, v137
	v_mul_f32_e32 v138, 0x3fcc422a, v138
	v_mul_f32_e32 v139, 0x3fcc422a, v139
	v_mul_f32_e32 v138, 0xbfb8aa3b, v138
	v_mul_f32_e32 v139, 0xbfb8aa3b, v139
	v_exp_f32_e32 v138, v138
	v_exp_f32_e32 v139, v139
	v_add_f32_e32 v138, 1.0, v138
	v_add_f32_e32 v139, 1.0, v139
	v_rcp_f32_e32 v138, v138
	v_rcp_f32_e32 v139, v139
	s_nop 0
	v_pk_mul_f32 v[136:137], v[136:137], v[138:139]
	v_pk_mul_f32 v[138:139], v[98:99], v[166:167] op_sel_hi:[1,0]
	v_cvt_pk_bf16_f32 v134, v136, v137
	v_mul_f32_e32 v140, 0x3d372713, v138
	v_mul_f32_e32 v141, 0x3d372713, v139
	v_mul_f32_e32 v140, v138, v140
	v_mul_f32_e32 v141, v139, v141
	v_fma_f32 v140, v138, v140, v138
	v_fma_f32 v141, v139, v141, v139
	v_mul_f32_e32 v140, 0x3fcc422a, v140
	v_mul_f32_e32 v141, 0x3fcc422a, v141
	v_mul_f32_e32 v140, 0xbfb8aa3b, v140
	v_mul_f32_e32 v141, 0xbfb8aa3b, v141
	v_exp_f32_e32 v140, v140
	v_exp_f32_e32 v141, v141
	v_add_f32_e32 v140, 1.0, v140
	v_add_f32_e32 v141, 1.0, v141
	v_rcp_f32_e32 v140, v140
	v_rcp_f32_e32 v141, v141
	s_nop 0
	v_pk_mul_f32 v[138:139], v[138:139], v[140:141]
	s_nop 0
	v_cvt_pk_bf16_f32 v135, v138, v139
	global_store_dwordx4 v[130:131], v[132:135], off
	s_nop 1
	v_pk_mul_f32 v[132:133], v[68:69], v[166:167] op_sel_hi:[1,0]
	s_nop 0
	v_mul_f32_e32 v134, 0x3d372713, v132
	v_mul_f32_e32 v135, 0x3d372713, v133
	v_mul_f32_e32 v134, v132, v134
	v_mul_f32_e32 v135, v133, v135
	v_fma_f32 v134, v132, v134, v132
	v_fma_f32 v135, v133, v135, v133
	v_mul_f32_e32 v134, 0x3fcc422a, v134
	v_mul_f32_e32 v135, 0x3fcc422a, v135
	v_mul_f32_e32 v134, 0xbfb8aa3b, v134
	v_mul_f32_e32 v135, 0xbfb8aa3b, v135
	v_exp_f32_e32 v134, v134
	v_exp_f32_e32 v135, v135
	v_add_f32_e32 v134, 1.0, v134
	v_add_f32_e32 v135, 1.0, v135
	v_rcp_f32_e32 v134, v134
	v_rcp_f32_e32 v135, v135
	s_nop 0
	v_pk_mul_f32 v[132:133], v[132:133], v[134:135]
	v_pk_mul_f32 v[134:135], v[70:71], v[166:167] op_sel_hi:[1,0]
	v_cvt_pk_bf16_f32 v132, v132, v133
	v_mul_f32_e32 v136, 0x3d372713, v134
	v_mul_f32_e32 v137, 0x3d372713, v135
	v_mul_f32_e32 v136, v134, v136
	v_mul_f32_e32 v137, v135, v137
	v_fma_f32 v136, v134, v136, v134
	v_fma_f32 v137, v135, v137, v135
	v_mul_f32_e32 v136, 0x3fcc422a, v136
	v_mul_f32_e32 v137, 0x3fcc422a, v137
	v_mul_f32_e32 v136, 0xbfb8aa3b, v136
	v_mul_f32_e32 v137, 0xbfb8aa3b, v137
	v_exp_f32_e32 v136, v136
	v_exp_f32_e32 v137, v137
	v_add_f32_e32 v136, 1.0, v136
	v_add_f32_e32 v137, 1.0, v137
	v_rcp_f32_e32 v136, v136
	v_rcp_f32_e32 v137, v137
	s_nop 0
	v_pk_mul_f32 v[134:135], v[134:135], v[136:137]
	v_pk_mul_f32 v[136:137], v[64:65], v[166:167] op_sel_hi:[1,0]
	v_cvt_pk_bf16_f32 v133, v134, v135
	v_mul_f32_e32 v138, 0x3d372713, v136
	v_mul_f32_e32 v139, 0x3d372713, v137
	v_mul_f32_e32 v138, v136, v138
	v_mul_f32_e32 v139, v137, v139
	v_fma_f32 v138, v136, v138, v136
	v_fma_f32 v139, v137, v139, v137
	v_mul_f32_e32 v138, 0x3fcc422a, v138
	v_mul_f32_e32 v139, 0x3fcc422a, v139
	v_mul_f32_e32 v138, 0xbfb8aa3b, v138
	v_mul_f32_e32 v139, 0xbfb8aa3b, v139
	v_exp_f32_e32 v138, v138
	v_exp_f32_e32 v139, v139
	v_add_f32_e32 v138, 1.0, v138
	v_add_f32_e32 v139, 1.0, v139
	v_rcp_f32_e32 v138, v138
	v_rcp_f32_e32 v139, v139
	s_nop 0
	v_pk_mul_f32 v[136:137], v[136:137], v[138:139]
	v_pk_mul_f32 v[138:139], v[66:67], v[166:167] op_sel_hi:[1,0]
	v_cvt_pk_bf16_f32 v134, v136, v137
	v_mul_f32_e32 v140, 0x3d372713, v138
	v_mul_f32_e32 v141, 0x3d372713, v139
	v_mul_f32_e32 v140, v138, v140
	v_mul_f32_e32 v141, v139, v141
	v_fma_f32 v140, v138, v140, v138
	v_fma_f32 v141, v139, v141, v139
	v_mul_f32_e32 v140, 0x3fcc422a, v140
	v_mul_f32_e32 v141, 0x3fcc422a, v141
	v_mul_f32_e32 v140, 0xbfb8aa3b, v140
	v_mul_f32_e32 v141, 0xbfb8aa3b, v141
	v_exp_f32_e32 v140, v140
	v_exp_f32_e32 v141, v141
	v_add_f32_e32 v140, 1.0, v140
	v_add_f32_e32 v141, 1.0, v141
	v_rcp_f32_e32 v140, v140
	v_rcp_f32_e32 v141, v141
	s_nop 0
	v_pk_mul_f32 v[138:139], v[138:139], v[140:141]
	s_nop 0
	v_cvt_pk_bf16_f32 v135, v138, v139
	global_store_dwordx4 v[130:131], v[132:135], off offset:256
	v_add_u32_e32 v130, s77, v172
	v_mad_i64_i32 v[130:131], s[16:17], s5, v130, 0
	v_pk_mul_f32 v[132:133], v[60:61], v[164:165] op_sel_hi:[1,0]
	v_lshl_add_u64 v[130:131], v[130:131], 1, s[30:31]
	v_mul_f32_e32 v134, 0x3d372713, v132
	v_mul_f32_e32 v135, 0x3d372713, v133
	v_mul_f32_e32 v134, v132, v134
	v_mul_f32_e32 v135, v133, v135
	v_fma_f32 v134, v132, v134, v132
	v_fma_f32 v135, v133, v135, v133
	v_mul_f32_e32 v134, 0x3fcc422a, v134
	v_mul_f32_e32 v135, 0x3fcc422a, v135
	v_mul_f32_e32 v134, 0xbfb8aa3b, v134
	v_mul_f32_e32 v135, 0xbfb8aa3b, v135
	v_exp_f32_e32 v134, v134
	v_exp_f32_e32 v135, v135
	v_lshl_add_u64 v[130:131], v[130:131], 0, s[50:51]
	v_lshl_add_u64 v[130:131], v[130:131], 0, v[128:129]
	v_add_f32_e32 v134, 1.0, v134
	v_add_f32_e32 v135, 1.0, v135
	v_rcp_f32_e32 v134, v134
	v_rcp_f32_e32 v135, v135
	s_nop 0
	v_pk_mul_f32 v[132:133], v[132:133], v[134:135]
	v_pk_mul_f32 v[134:135], v[62:63], v[164:165] op_sel_hi:[1,0]
	v_cvt_pk_bf16_f32 v132, v132, v133
	v_mul_f32_e32 v136, 0x3d372713, v134
	v_mul_f32_e32 v137, 0x3d372713, v135
	v_mul_f32_e32 v136, v134, v136
	v_mul_f32_e32 v137, v135, v137
	v_fma_f32 v136, v134, v136, v134
	v_fma_f32 v137, v135, v137, v135
	v_mul_f32_e32 v136, 0x3fcc422a, v136
	v_mul_f32_e32 v137, 0x3fcc422a, v137
	v_mul_f32_e32 v136, 0xbfb8aa3b, v136
	v_mul_f32_e32 v137, 0xbfb8aa3b, v137
	v_exp_f32_e32 v136, v136
	v_exp_f32_e32 v137, v137
	v_add_f32_e32 v136, 1.0, v136
	v_add_f32_e32 v137, 1.0, v137
	v_rcp_f32_e32 v136, v136
	v_rcp_f32_e32 v137, v137
	s_nop 0
	v_pk_mul_f32 v[134:135], v[134:135], v[136:137]
	v_pk_mul_f32 v[136:137], v[56:57], v[164:165] op_sel_hi:[1,0]
	v_cvt_pk_bf16_f32 v133, v134, v135
	v_mul_f32_e32 v138, 0x3d372713, v136
	v_mul_f32_e32 v139, 0x3d372713, v137
	v_mul_f32_e32 v138, v136, v138
	v_mul_f32_e32 v139, v137, v139
	v_fma_f32 v138, v136, v138, v136
	v_fma_f32 v139, v137, v139, v137
	v_mul_f32_e32 v138, 0x3fcc422a, v138
	v_mul_f32_e32 v139, 0x3fcc422a, v139
	v_mul_f32_e32 v138, 0xbfb8aa3b, v138
	v_mul_f32_e32 v139, 0xbfb8aa3b, v139
	v_exp_f32_e32 v138, v138
	v_exp_f32_e32 v139, v139
	v_add_f32_e32 v138, 1.0, v138
	v_add_f32_e32 v139, 1.0, v139
	v_rcp_f32_e32 v138, v138
	v_rcp_f32_e32 v139, v139
	s_nop 0
	v_pk_mul_f32 v[136:137], v[136:137], v[138:139]
	v_pk_mul_f32 v[138:139], v[58:59], v[164:165] op_sel_hi:[1,0]
	v_cvt_pk_bf16_f32 v134, v136, v137
	v_mul_f32_e32 v140, 0x3d372713, v138
	v_mul_f32_e32 v141, 0x3d372713, v139
	v_mul_f32_e32 v140, v138, v140
	v_mul_f32_e32 v141, v139, v141
	v_fma_f32 v140, v138, v140, v138
	v_fma_f32 v141, v139, v141, v139
	v_mul_f32_e32 v140, 0x3fcc422a, v140
	v_mul_f32_e32 v141, 0x3fcc422a, v141
	v_mul_f32_e32 v140, 0xbfb8aa3b, v140
	v_mul_f32_e32 v141, 0xbfb8aa3b, v141
	v_exp_f32_e32 v140, v140
	v_exp_f32_e32 v141, v141
	v_add_f32_e32 v140, 1.0, v140
	v_add_f32_e32 v141, 1.0, v141
	v_rcp_f32_e32 v140, v140
	v_rcp_f32_e32 v141, v141
	s_nop 0
	v_pk_mul_f32 v[138:139], v[138:139], v[140:141]
	s_nop 0
	v_cvt_pk_bf16_f32 v135, v138, v139
	global_store_dwordx4 v[130:131], v[132:135], off
	s_nop 1
	v_pk_mul_f32 v[132:133], v[28:29], v[164:165] op_sel_hi:[1,0]
	s_nop 0
	v_mul_f32_e32 v134, 0x3d372713, v132
	v_mul_f32_e32 v135, 0x3d372713, v133
	v_mul_f32_e32 v134, v132, v134
	v_mul_f32_e32 v135, v133, v135
	v_fma_f32 v134, v132, v134, v132
	v_fma_f32 v135, v133, v135, v133
	v_mul_f32_e32 v134, 0x3fcc422a, v134
	v_mul_f32_e32 v135, 0x3fcc422a, v135
	v_mul_f32_e32 v134, 0xbfb8aa3b, v134
	v_mul_f32_e32 v135, 0xbfb8aa3b, v135
	v_exp_f32_e32 v134, v134
	v_exp_f32_e32 v135, v135
	v_add_f32_e32 v134, 1.0, v134
	v_add_f32_e32 v135, 1.0, v135
	v_rcp_f32_e32 v134, v134
	v_rcp_f32_e32 v135, v135
	s_nop 0
	v_pk_mul_f32 v[132:133], v[132:133], v[134:135]
	v_pk_mul_f32 v[134:135], v[30:31], v[164:165] op_sel_hi:[1,0]
	v_cvt_pk_bf16_f32 v132, v132, v133
	v_mul_f32_e32 v136, 0x3d372713, v134
	v_mul_f32_e32 v137, 0x3d372713, v135
	v_mul_f32_e32 v136, v134, v136
	v_mul_f32_e32 v137, v135, v137
	v_fma_f32 v136, v134, v136, v134
	v_fma_f32 v137, v135, v137, v135
	v_mul_f32_e32 v136, 0x3fcc422a, v136
	v_mul_f32_e32 v137, 0x3fcc422a, v137
	v_mul_f32_e32 v136, 0xbfb8aa3b, v136
	v_mul_f32_e32 v137, 0xbfb8aa3b, v137
	v_exp_f32_e32 v136, v136
	v_exp_f32_e32 v137, v137
	v_add_f32_e32 v136, 1.0, v136
	v_add_f32_e32 v137, 1.0, v137
	v_rcp_f32_e32 v136, v136
	v_rcp_f32_e32 v137, v137
	s_nop 0
	v_pk_mul_f32 v[134:135], v[134:135], v[136:137]
	v_pk_mul_f32 v[136:137], v[24:25], v[164:165] op_sel_hi:[1,0]
	v_cvt_pk_bf16_f32 v133, v134, v135
	v_mul_f32_e32 v138, 0x3d372713, v136
	v_mul_f32_e32 v139, 0x3d372713, v137
	v_mul_f32_e32 v138, v136, v138
	v_mul_f32_e32 v139, v137, v139
	v_fma_f32 v138, v136, v138, v136
	v_fma_f32 v139, v137, v139, v137
	v_mul_f32_e32 v138, 0x3fcc422a, v138
	v_mul_f32_e32 v139, 0x3fcc422a, v139
	v_mul_f32_e32 v138, 0xbfb8aa3b, v138
	v_mul_f32_e32 v139, 0xbfb8aa3b, v139
	v_exp_f32_e32 v138, v138
	v_exp_f32_e32 v139, v139
	v_add_f32_e32 v138, 1.0, v138
	v_add_f32_e32 v139, 1.0, v139
	v_rcp_f32_e32 v138, v138
	v_rcp_f32_e32 v139, v139
	s_nop 0
	v_pk_mul_f32 v[136:137], v[136:137], v[138:139]
	v_pk_mul_f32 v[138:139], v[26:27], v[164:165] op_sel_hi:[1,0]
	v_cvt_pk_bf16_f32 v134, v136, v137
	v_mul_f32_e32 v140, 0x3d372713, v138
	v_mul_f32_e32 v141, 0x3d372713, v139
	v_mul_f32_e32 v140, v138, v140
	v_mul_f32_e32 v141, v139, v141
	v_fma_f32 v140, v138, v140, v138
	v_fma_f32 v141, v139, v141, v139
	v_mul_f32_e32 v140, 0x3fcc422a, v140
	v_mul_f32_e32 v141, 0x3fcc422a, v141
	v_mul_f32_e32 v140, 0xbfb8aa3b, v140
	v_mul_f32_e32 v141, 0xbfb8aa3b, v141
	v_exp_f32_e32 v140, v140
	v_exp_f32_e32 v141, v141
	v_add_f32_e32 v140, 1.0, v140
	v_add_f32_e32 v141, 1.0, v141
	v_rcp_f32_e32 v140, v140
	v_rcp_f32_e32 v141, v141
	s_nop 0
	v_pk_mul_f32 v[138:139], v[138:139], v[140:141]
	s_nop 0
	v_cvt_pk_bf16_f32 v135, v138, v139
	global_store_dwordx4 v[130:131], v[132:135], off offset:256
	v_mad_i64_i32 v[130:131], s[16:17], s5, v150, 0
	s_nop 0
	v_pk_mul_f32 v[132:133], v[52:53], v[160:161] op_sel_hi:[1,0]
	v_lshl_add_u64 v[130:131], v[130:131], 1, s[30:31]
	v_mul_f32_e32 v134, 0x3d372713, v132
	v_mul_f32_e32 v135, 0x3d372713, v133
	v_mul_f32_e32 v134, v132, v134
	v_mul_f32_e32 v135, v133, v135
	v_fma_f32 v134, v132, v134, v132
	v_fma_f32 v135, v133, v135, v133
	v_mul_f32_e32 v134, 0x3fcc422a, v134
	v_mul_f32_e32 v135, 0x3fcc422a, v135
	v_mul_f32_e32 v134, 0xbfb8aa3b, v134
	v_mul_f32_e32 v135, 0xbfb8aa3b, v135
	v_exp_f32_e32 v134, v134
	v_exp_f32_e32 v135, v135
	v_lshl_add_u64 v[130:131], v[130:131], 0, s[50:51]
	v_lshl_add_u64 v[130:131], v[130:131], 0, v[128:129]
	v_add_f32_e32 v134, 1.0, v134
	v_add_f32_e32 v135, 1.0, v135
	v_rcp_f32_e32 v134, v134
	v_rcp_f32_e32 v135, v135
	s_nop 0
	v_pk_mul_f32 v[132:133], v[132:133], v[134:135]
	v_pk_mul_f32 v[134:135], v[54:55], v[160:161] op_sel_hi:[1,0]
	v_cvt_pk_bf16_f32 v132, v132, v133
	v_mul_f32_e32 v136, 0x3d372713, v134
	v_mul_f32_e32 v137, 0x3d372713, v135
	v_mul_f32_e32 v136, v134, v136
	v_mul_f32_e32 v137, v135, v137
	v_fma_f32 v136, v134, v136, v134
	v_fma_f32 v137, v135, v137, v135
	v_mul_f32_e32 v136, 0x3fcc422a, v136
	v_mul_f32_e32 v137, 0x3fcc422a, v137
	v_mul_f32_e32 v136, 0xbfb8aa3b, v136
	v_mul_f32_e32 v137, 0xbfb8aa3b, v137
	v_exp_f32_e32 v136, v136
	v_exp_f32_e32 v137, v137
	v_add_f32_e32 v136, 1.0, v136
	v_add_f32_e32 v137, 1.0, v137
	v_rcp_f32_e32 v136, v136
	v_rcp_f32_e32 v137, v137
	s_nop 0
	v_pk_mul_f32 v[134:135], v[134:135], v[136:137]
	v_pk_mul_f32 v[136:137], v[48:49], v[160:161] op_sel_hi:[1,0]
	v_cvt_pk_bf16_f32 v133, v134, v135
	v_mul_f32_e32 v138, 0x3d372713, v136
	v_mul_f32_e32 v139, 0x3d372713, v137
	v_mul_f32_e32 v138, v136, v138
	v_mul_f32_e32 v139, v137, v139
	v_fma_f32 v138, v136, v138, v136
	v_fma_f32 v139, v137, v139, v137
	v_mul_f32_e32 v138, 0x3fcc422a, v138
	v_mul_f32_e32 v139, 0x3fcc422a, v139
	v_mul_f32_e32 v138, 0xbfb8aa3b, v138
	v_mul_f32_e32 v139, 0xbfb8aa3b, v139
	v_exp_f32_e32 v138, v138
	v_exp_f32_e32 v139, v139
	v_add_f32_e32 v138, 1.0, v138
	v_add_f32_e32 v139, 1.0, v139
	v_rcp_f32_e32 v138, v138
	v_rcp_f32_e32 v139, v139
	s_nop 0
	v_pk_mul_f32 v[136:137], v[136:137], v[138:139]
	v_pk_mul_f32 v[138:139], v[50:51], v[160:161] op_sel_hi:[1,0]
	v_cvt_pk_bf16_f32 v134, v136, v137
	v_mul_f32_e32 v140, 0x3d372713, v138
	v_mul_f32_e32 v141, 0x3d372713, v139
	v_mul_f32_e32 v140, v138, v140
	v_mul_f32_e32 v141, v139, v141
	v_fma_f32 v140, v138, v140, v138
	v_fma_f32 v141, v139, v141, v139
	v_mul_f32_e32 v140, 0x3fcc422a, v140
	v_mul_f32_e32 v141, 0x3fcc422a, v141
	v_mul_f32_e32 v140, 0xbfb8aa3b, v140
	v_mul_f32_e32 v141, 0xbfb8aa3b, v141
	v_exp_f32_e32 v140, v140
	v_exp_f32_e32 v141, v141
	v_add_f32_e32 v140, 1.0, v140
	v_add_f32_e32 v141, 1.0, v141
	v_rcp_f32_e32 v140, v140
	v_rcp_f32_e32 v141, v141
	s_nop 0
	v_pk_mul_f32 v[138:139], v[138:139], v[140:141]
	s_nop 0
	v_cvt_pk_bf16_f32 v135, v138, v139
	global_store_dwordx4 v[130:131], v[132:135], off
	s_nop 1
	v_pk_mul_f32 v[132:133], v[20:21], v[160:161] op_sel_hi:[1,0]
	s_nop 0
	v_mul_f32_e32 v134, 0x3d372713, v132
	v_mul_f32_e32 v135, 0x3d372713, v133
	v_mul_f32_e32 v134, v132, v134
	v_mul_f32_e32 v135, v133, v135
	v_fma_f32 v134, v132, v134, v132
	v_fma_f32 v135, v133, v135, v133
	v_mul_f32_e32 v134, 0x3fcc422a, v134
	v_mul_f32_e32 v135, 0x3fcc422a, v135
	v_mul_f32_e32 v134, 0xbfb8aa3b, v134
	v_mul_f32_e32 v135, 0xbfb8aa3b, v135
	v_exp_f32_e32 v134, v134
	v_exp_f32_e32 v135, v135
	v_add_f32_e32 v134, 1.0, v134
	v_add_f32_e32 v135, 1.0, v135
	v_rcp_f32_e32 v134, v134
	v_rcp_f32_e32 v135, v135
	s_nop 0
	v_pk_mul_f32 v[132:133], v[132:133], v[134:135]
	v_pk_mul_f32 v[134:135], v[22:23], v[160:161] op_sel_hi:[1,0]
	v_cvt_pk_bf16_f32 v132, v132, v133
	v_mul_f32_e32 v136, 0x3d372713, v134
	v_mul_f32_e32 v137, 0x3d372713, v135
	v_mul_f32_e32 v136, v134, v136
	v_mul_f32_e32 v137, v135, v137
	v_fma_f32 v136, v134, v136, v134
	v_fma_f32 v137, v135, v137, v135
	v_mul_f32_e32 v136, 0x3fcc422a, v136
	v_mul_f32_e32 v137, 0x3fcc422a, v137
	v_mul_f32_e32 v136, 0xbfb8aa3b, v136
	v_mul_f32_e32 v137, 0xbfb8aa3b, v137
	v_exp_f32_e32 v136, v136
	v_exp_f32_e32 v137, v137
	v_add_f32_e32 v136, 1.0, v136
	v_add_f32_e32 v137, 1.0, v137
	v_rcp_f32_e32 v136, v136
	v_rcp_f32_e32 v137, v137
	s_nop 0
	v_pk_mul_f32 v[134:135], v[134:135], v[136:137]
	v_pk_mul_f32 v[136:137], v[16:17], v[160:161] op_sel_hi:[1,0]
	v_cvt_pk_bf16_f32 v133, v134, v135
	v_mul_f32_e32 v138, 0x3d372713, v136
	v_mul_f32_e32 v139, 0x3d372713, v137
	v_mul_f32_e32 v138, v136, v138
	v_mul_f32_e32 v139, v137, v139
	v_fma_f32 v138, v136, v138, v136
	v_fma_f32 v139, v137, v139, v137
	v_mul_f32_e32 v138, 0x3fcc422a, v138
	v_mul_f32_e32 v139, 0x3fcc422a, v139
	v_mul_f32_e32 v138, 0xbfb8aa3b, v138
	v_mul_f32_e32 v139, 0xbfb8aa3b, v139
	v_exp_f32_e32 v138, v138
	v_exp_f32_e32 v139, v139
	v_add_f32_e32 v138, 1.0, v138
	v_add_f32_e32 v139, 1.0, v139
	v_rcp_f32_e32 v138, v138
	v_rcp_f32_e32 v139, v139
	s_nop 0
	v_pk_mul_f32 v[136:137], v[136:137], v[138:139]
	v_pk_mul_f32 v[138:139], v[18:19], v[160:161] op_sel_hi:[1,0]
	v_cvt_pk_bf16_f32 v134, v136, v137
	v_mul_f32_e32 v140, 0x3d372713, v138
	v_mul_f32_e32 v141, 0x3d372713, v139
	v_mul_f32_e32 v140, v138, v140
	v_mul_f32_e32 v141, v139, v141
	v_fma_f32 v140, v138, v140, v138
	v_fma_f32 v141, v139, v141, v139
	v_mul_f32_e32 v140, 0x3fcc422a, v140
	v_mul_f32_e32 v141, 0x3fcc422a, v141
	v_mul_f32_e32 v140, 0xbfb8aa3b, v140
	v_mul_f32_e32 v141, 0xbfb8aa3b, v141
	v_exp_f32_e32 v140, v140
	v_exp_f32_e32 v141, v141
	v_add_f32_e32 v140, 1.0, v140
	v_add_f32_e32 v141, 1.0, v141
	v_rcp_f32_e32 v140, v140
	v_rcp_f32_e32 v141, v141
	s_nop 0
	v_pk_mul_f32 v[138:139], v[138:139], v[140:141]
	s_nop 0
	v_cvt_pk_bf16_f32 v135, v138, v139
	global_store_dwordx4 v[130:131], v[132:135], off offset:256
	v_mad_i64_i32 v[130:131], s[16:17], s5, v148, 0
	s_nop 0
	v_pk_mul_f32 v[132:133], v[44:45], v[156:157] op_sel_hi:[1,0]
	v_lshl_add_u64 v[130:131], v[130:131], 1, s[30:31]
	v_mul_f32_e32 v134, 0x3d372713, v132
	v_mul_f32_e32 v135, 0x3d372713, v133
	v_mul_f32_e32 v134, v132, v134
	v_mul_f32_e32 v135, v133, v135
	v_fma_f32 v134, v132, v134, v132
	v_fma_f32 v135, v133, v135, v133
	v_mul_f32_e32 v134, 0x3fcc422a, v134
	v_mul_f32_e32 v135, 0x3fcc422a, v135
	v_mul_f32_e32 v134, 0xbfb8aa3b, v134
	v_mul_f32_e32 v135, 0xbfb8aa3b, v135
	v_exp_f32_e32 v134, v134
	v_exp_f32_e32 v135, v135
	v_lshl_add_u64 v[130:131], v[130:131], 0, s[50:51]
	v_lshl_add_u64 v[130:131], v[130:131], 0, v[128:129]
	v_add_f32_e32 v134, 1.0, v134
	v_add_f32_e32 v135, 1.0, v135
	v_rcp_f32_e32 v134, v134
	v_rcp_f32_e32 v135, v135
	s_nop 0
	v_pk_mul_f32 v[132:133], v[132:133], v[134:135]
	v_pk_mul_f32 v[134:135], v[46:47], v[156:157] op_sel_hi:[1,0]
	v_cvt_pk_bf16_f32 v132, v132, v133
	v_mul_f32_e32 v136, 0x3d372713, v134
	v_mul_f32_e32 v137, 0x3d372713, v135
	v_mul_f32_e32 v136, v134, v136
	v_mul_f32_e32 v137, v135, v137
	v_fma_f32 v136, v134, v136, v134
	v_fma_f32 v137, v135, v137, v135
	v_mul_f32_e32 v136, 0x3fcc422a, v136
	v_mul_f32_e32 v137, 0x3fcc422a, v137
	v_mul_f32_e32 v136, 0xbfb8aa3b, v136
	v_mul_f32_e32 v137, 0xbfb8aa3b, v137
	v_exp_f32_e32 v136, v136
	v_exp_f32_e32 v137, v137
	v_add_f32_e32 v136, 1.0, v136
	v_add_f32_e32 v137, 1.0, v137
	v_rcp_f32_e32 v136, v136
	v_rcp_f32_e32 v137, v137
	s_nop 0
	v_pk_mul_f32 v[134:135], v[134:135], v[136:137]
	v_pk_mul_f32 v[136:137], v[40:41], v[156:157] op_sel_hi:[1,0]
	v_cvt_pk_bf16_f32 v133, v134, v135
	v_mul_f32_e32 v138, 0x3d372713, v136
	v_mul_f32_e32 v139, 0x3d372713, v137
	v_mul_f32_e32 v138, v136, v138
	v_mul_f32_e32 v139, v137, v139
	v_fma_f32 v138, v136, v138, v136
	v_fma_f32 v139, v137, v139, v137
	v_mul_f32_e32 v138, 0x3fcc422a, v138
	v_mul_f32_e32 v139, 0x3fcc422a, v139
	v_mul_f32_e32 v138, 0xbfb8aa3b, v138
	v_mul_f32_e32 v139, 0xbfb8aa3b, v139
	v_exp_f32_e32 v138, v138
	v_exp_f32_e32 v139, v139
	v_add_f32_e32 v138, 1.0, v138
	v_add_f32_e32 v139, 1.0, v139
	v_rcp_f32_e32 v138, v138
	v_rcp_f32_e32 v139, v139
	s_nop 0
	v_pk_mul_f32 v[136:137], v[136:137], v[138:139]
	v_pk_mul_f32 v[138:139], v[42:43], v[156:157] op_sel_hi:[1,0]
	v_cvt_pk_bf16_f32 v134, v136, v137
	v_mul_f32_e32 v140, 0x3d372713, v138
	v_mul_f32_e32 v141, 0x3d372713, v139
	v_mul_f32_e32 v140, v138, v140
	v_mul_f32_e32 v141, v139, v141
	v_fma_f32 v140, v138, v140, v138
	v_fma_f32 v141, v139, v141, v139
	v_mul_f32_e32 v140, 0x3fcc422a, v140
	v_mul_f32_e32 v141, 0x3fcc422a, v141
	v_mul_f32_e32 v140, 0xbfb8aa3b, v140
	v_mul_f32_e32 v141, 0xbfb8aa3b, v141
	v_exp_f32_e32 v140, v140
	v_exp_f32_e32 v141, v141
	v_add_f32_e32 v140, 1.0, v140
	v_add_f32_e32 v141, 1.0, v141
	v_rcp_f32_e32 v140, v140
	v_rcp_f32_e32 v141, v141
	s_nop 0
	v_pk_mul_f32 v[138:139], v[138:139], v[140:141]
	s_nop 0
	v_cvt_pk_bf16_f32 v135, v138, v139
	global_store_dwordx4 v[130:131], v[132:135], off
	s_nop 1
	v_pk_mul_f32 v[132:133], v[12:13], v[156:157] op_sel_hi:[1,0]
	s_nop 0
	v_mul_f32_e32 v134, 0x3d372713, v132
	v_mul_f32_e32 v135, 0x3d372713, v133
	v_mul_f32_e32 v134, v132, v134
	v_mul_f32_e32 v135, v133, v135
	v_fma_f32 v134, v132, v134, v132
	v_fma_f32 v135, v133, v135, v133
	v_mul_f32_e32 v134, 0x3fcc422a, v134
	v_mul_f32_e32 v135, 0x3fcc422a, v135
	v_mul_f32_e32 v134, 0xbfb8aa3b, v134
	v_mul_f32_e32 v135, 0xbfb8aa3b, v135
	v_exp_f32_e32 v134, v134
	v_exp_f32_e32 v135, v135
	v_add_f32_e32 v134, 1.0, v134
	v_add_f32_e32 v135, 1.0, v135
	v_rcp_f32_e32 v134, v134
	v_rcp_f32_e32 v135, v135
	s_nop 0
	v_pk_mul_f32 v[132:133], v[132:133], v[134:135]
	v_pk_mul_f32 v[134:135], v[14:15], v[156:157] op_sel_hi:[1,0]
	v_cvt_pk_bf16_f32 v132, v132, v133
	v_mul_f32_e32 v136, 0x3d372713, v134
	v_mul_f32_e32 v137, 0x3d372713, v135
	v_mul_f32_e32 v136, v134, v136
	v_mul_f32_e32 v137, v135, v137
	v_fma_f32 v136, v134, v136, v134
	v_fma_f32 v137, v135, v137, v135
	v_mul_f32_e32 v136, 0x3fcc422a, v136
	v_mul_f32_e32 v137, 0x3fcc422a, v137
	v_mul_f32_e32 v136, 0xbfb8aa3b, v136
	v_mul_f32_e32 v137, 0xbfb8aa3b, v137
	v_exp_f32_e32 v136, v136
	v_exp_f32_e32 v137, v137
	v_add_f32_e32 v136, 1.0, v136
	v_add_f32_e32 v137, 1.0, v137
	v_rcp_f32_e32 v136, v136
	v_rcp_f32_e32 v137, v137
	s_nop 0
	v_pk_mul_f32 v[134:135], v[134:135], v[136:137]
	v_pk_mul_f32 v[136:137], v[8:9], v[156:157] op_sel_hi:[1,0]
	v_cvt_pk_bf16_f32 v133, v134, v135
	v_mul_f32_e32 v138, 0x3d372713, v136
	v_mul_f32_e32 v139, 0x3d372713, v137
	v_mul_f32_e32 v138, v136, v138
	v_mul_f32_e32 v139, v137, v139
	v_fma_f32 v138, v136, v138, v136
	v_fma_f32 v139, v137, v139, v137
	v_mul_f32_e32 v138, 0x3fcc422a, v138
	v_mul_f32_e32 v139, 0x3fcc422a, v139
	v_mul_f32_e32 v138, 0xbfb8aa3b, v138
	v_mul_f32_e32 v139, 0xbfb8aa3b, v139
	v_exp_f32_e32 v138, v138
	v_exp_f32_e32 v139, v139
	v_add_f32_e32 v138, 1.0, v138
	v_add_f32_e32 v139, 1.0, v139
	v_rcp_f32_e32 v138, v138
	v_rcp_f32_e32 v139, v139
	s_nop 0
	v_pk_mul_f32 v[136:137], v[136:137], v[138:139]
	v_pk_mul_f32 v[138:139], v[10:11], v[156:157] op_sel_hi:[1,0]
	v_cvt_pk_bf16_f32 v134, v136, v137
	v_mul_f32_e32 v140, 0x3d372713, v138
	v_mul_f32_e32 v141, 0x3d372713, v139
	v_mul_f32_e32 v140, v138, v140
	v_mul_f32_e32 v141, v139, v141
	v_fma_f32 v140, v138, v140, v138
	v_fma_f32 v141, v139, v141, v139
	v_mul_f32_e32 v140, 0x3fcc422a, v140
	v_mul_f32_e32 v141, 0x3fcc422a, v141
	v_mul_f32_e32 v140, 0xbfb8aa3b, v140
	v_mul_f32_e32 v141, 0xbfb8aa3b, v141
	v_exp_f32_e32 v140, v140
	v_exp_f32_e32 v141, v141
	v_add_f32_e32 v140, 1.0, v140
	v_add_f32_e32 v141, 1.0, v141
	v_rcp_f32_e32 v140, v140
	v_rcp_f32_e32 v141, v141
	s_nop 0
	v_pk_mul_f32 v[138:139], v[138:139], v[140:141]
	s_nop 0
	v_cvt_pk_bf16_f32 v135, v138, v139
	global_store_dwordx4 v[130:131], v[132:135], off offset:256
	v_mad_i64_i32 v[130:131], s[16:17], s5, v146, 0
	v_lshl_add_u64 v[130:131], v[130:131], 1, s[30:31]
	v_lshl_add_u64 v[130:131], v[130:131], 0, s[50:51]
	v_lshl_add_u64 v[128:129], v[130:131], 0, v[128:129]
	v_pk_mul_f32 v[130:131], v[36:37], v[152:153] op_sel_hi:[1,0]
	s_nop 0
	v_mul_f32_e32 v132, 0x3d372713, v130
	v_mul_f32_e32 v133, 0x3d372713, v131
	v_mul_f32_e32 v132, v130, v132
	v_mul_f32_e32 v133, v131, v133
	v_fma_f32 v132, v130, v132, v130
	v_fma_f32 v133, v131, v133, v131
	v_mul_f32_e32 v132, 0x3fcc422a, v132
	v_mul_f32_e32 v133, 0x3fcc422a, v133
	v_mul_f32_e32 v132, 0xbfb8aa3b, v132
	v_mul_f32_e32 v133, 0xbfb8aa3b, v133
	v_exp_f32_e32 v132, v132
	v_exp_f32_e32 v133, v133
	v_add_f32_e32 v132, 1.0, v132
	v_add_f32_e32 v133, 1.0, v133
	v_rcp_f32_e32 v132, v132
	v_rcp_f32_e32 v133, v133
	s_nop 0
	v_pk_mul_f32 v[130:131], v[130:131], v[132:133]
	v_pk_mul_f32 v[132:133], v[38:39], v[152:153] op_sel_hi:[1,0]
	v_cvt_pk_bf16_f32 v130, v130, v131
	v_mul_f32_e32 v134, 0x3d372713, v132
	v_mul_f32_e32 v135, 0x3d372713, v133
	v_mul_f32_e32 v134, v132, v134
	v_mul_f32_e32 v135, v133, v135
	v_fma_f32 v134, v132, v134, v132
	v_fma_f32 v135, v133, v135, v133
	v_mul_f32_e32 v134, 0x3fcc422a, v134
	v_mul_f32_e32 v135, 0x3fcc422a, v135
	v_mul_f32_e32 v134, 0xbfb8aa3b, v134
	v_mul_f32_e32 v135, 0xbfb8aa3b, v135
	v_exp_f32_e32 v134, v134
	v_exp_f32_e32 v135, v135
	v_add_f32_e32 v134, 1.0, v134
	v_add_f32_e32 v135, 1.0, v135
	v_rcp_f32_e32 v134, v134
	v_rcp_f32_e32 v135, v135
	s_nop 0
	v_pk_mul_f32 v[132:133], v[132:133], v[134:135]
	v_pk_mul_f32 v[134:135], v[32:33], v[152:153] op_sel_hi:[1,0]
	v_cvt_pk_bf16_f32 v131, v132, v133
	v_mul_f32_e32 v136, 0x3d372713, v134
	v_mul_f32_e32 v137, 0x3d372713, v135
	v_mul_f32_e32 v136, v134, v136
	v_mul_f32_e32 v137, v135, v137
	v_fma_f32 v136, v134, v136, v134
	v_fma_f32 v137, v135, v137, v135
	v_mul_f32_e32 v136, 0x3fcc422a, v136
	v_mul_f32_e32 v137, 0x3fcc422a, v137
	v_mul_f32_e32 v136, 0xbfb8aa3b, v136
	v_mul_f32_e32 v137, 0xbfb8aa3b, v137
	v_exp_f32_e32 v136, v136
	v_exp_f32_e32 v137, v137
	v_add_f32_e32 v136, 1.0, v136
	v_add_f32_e32 v137, 1.0, v137
	v_rcp_f32_e32 v136, v136
	v_rcp_f32_e32 v137, v137
	s_nop 0
	v_pk_mul_f32 v[134:135], v[134:135], v[136:137]
	v_pk_mul_f32 v[136:137], v[34:35], v[152:153] op_sel_hi:[1,0]
	v_cvt_pk_bf16_f32 v132, v134, v135
	v_mul_f32_e32 v138, 0x3d372713, v136
	v_mul_f32_e32 v139, 0x3d372713, v137
	v_mul_f32_e32 v138, v136, v138
	v_mul_f32_e32 v139, v137, v139
	v_fma_f32 v138, v136, v138, v136
	v_fma_f32 v139, v137, v139, v137
	v_mul_f32_e32 v138, 0x3fcc422a, v138
	v_mul_f32_e32 v139, 0x3fcc422a, v139
	v_mul_f32_e32 v138, 0xbfb8aa3b, v138
	v_mul_f32_e32 v139, 0xbfb8aa3b, v139
	v_exp_f32_e32 v138, v138
	v_exp_f32_e32 v139, v139
	v_add_f32_e32 v138, 1.0, v138
	v_add_f32_e32 v139, 1.0, v139
	v_rcp_f32_e32 v138, v138
	v_rcp_f32_e32 v139, v139
	s_nop 0
	v_pk_mul_f32 v[136:137], v[136:137], v[138:139]
	s_nop 0
	v_cvt_pk_bf16_f32 v133, v136, v137
	global_store_dwordx4 v[128:129], v[130:133], off
	s_nop 1
	v_pk_mul_f32 v[130:131], v[4:5], v[152:153] op_sel_hi:[1,0]
	s_nop 0
	v_mul_f32_e32 v132, 0x3d372713, v130
	v_mul_f32_e32 v133, 0x3d372713, v131
	v_mul_f32_e32 v132, v130, v132
	v_mul_f32_e32 v133, v131, v133
	v_fma_f32 v132, v130, v132, v130
	v_fma_f32 v133, v131, v133, v131
	v_mul_f32_e32 v132, 0x3fcc422a, v132
	v_mul_f32_e32 v133, 0x3fcc422a, v133
	v_mul_f32_e32 v132, 0xbfb8aa3b, v132
	v_mul_f32_e32 v133, 0xbfb8aa3b, v133
	v_exp_f32_e32 v132, v132
	v_exp_f32_e32 v133, v133
	v_add_f32_e32 v132, 1.0, v132
	v_add_f32_e32 v133, 1.0, v133
	v_rcp_f32_e32 v132, v132
	v_rcp_f32_e32 v133, v133
	s_nop 0
	v_pk_mul_f32 v[130:131], v[130:131], v[132:133]
	v_pk_mul_f32 v[132:133], v[6:7], v[152:153] op_sel_hi:[1,0]
	v_cvt_pk_bf16_f32 v130, v130, v131
	v_mul_f32_e32 v134, 0x3d372713, v132
	v_mul_f32_e32 v135, 0x3d372713, v133
	v_mul_f32_e32 v134, v132, v134
	v_mul_f32_e32 v135, v133, v135
	v_fma_f32 v134, v132, v134, v132
	v_fma_f32 v135, v133, v135, v133
	v_mul_f32_e32 v134, 0x3fcc422a, v134
	v_mul_f32_e32 v135, 0x3fcc422a, v135
	v_mul_f32_e32 v134, 0xbfb8aa3b, v134
	v_mul_f32_e32 v135, 0xbfb8aa3b, v135
	v_exp_f32_e32 v134, v134
	v_exp_f32_e32 v135, v135
	v_add_f32_e32 v134, 1.0, v134
	v_add_f32_e32 v135, 1.0, v135
	v_rcp_f32_e32 v134, v134
	v_rcp_f32_e32 v135, v135
	s_nop 0
	v_pk_mul_f32 v[132:133], v[132:133], v[134:135]
	v_pk_mul_f32 v[134:135], v[0:1], v[152:153] op_sel_hi:[1,0]
	v_cvt_pk_bf16_f32 v131, v132, v133
	v_mul_f32_e32 v136, 0x3d372713, v134
	v_mul_f32_e32 v137, 0x3d372713, v135
	v_mul_f32_e32 v136, v134, v136
	v_mul_f32_e32 v137, v135, v137
	v_fma_f32 v136, v134, v136, v134
	v_fma_f32 v137, v135, v137, v135
	v_mul_f32_e32 v136, 0x3fcc422a, v136
	v_mul_f32_e32 v137, 0x3fcc422a, v137
	v_mul_f32_e32 v136, 0xbfb8aa3b, v136
	v_mul_f32_e32 v137, 0xbfb8aa3b, v137
	v_exp_f32_e32 v136, v136
	v_exp_f32_e32 v137, v137
	v_add_f32_e32 v136, 1.0, v136
	v_add_f32_e32 v137, 1.0, v137
	v_rcp_f32_e32 v136, v136
	v_rcp_f32_e32 v137, v137
	s_nop 0
	v_pk_mul_f32 v[134:135], v[134:135], v[136:137]
	v_pk_mul_f32 v[136:137], v[2:3], v[152:153] op_sel_hi:[1,0]
	v_cvt_pk_bf16_f32 v132, v134, v135
	v_mul_f32_e32 v138, 0x3d372713, v136
	v_mul_f32_e32 v139, 0x3d372713, v137
	v_mul_f32_e32 v138, v136, v138
	v_mul_f32_e32 v139, v137, v139
	v_fma_f32 v138, v136, v138, v136
	v_fma_f32 v139, v137, v139, v137
	v_mul_f32_e32 v138, 0x3fcc422a, v138
	v_mul_f32_e32 v139, 0x3fcc422a, v139
	v_mul_f32_e32 v138, 0xbfb8aa3b, v138
	v_mul_f32_e32 v139, 0xbfb8aa3b, v139
	v_exp_f32_e32 v138, v138
	v_exp_f32_e32 v139, v139
	v_add_f32_e32 v138, 1.0, v138
	v_add_f32_e32 v139, 1.0, v139
	v_rcp_f32_e32 v138, v138
	v_rcp_f32_e32 v139, v139
	s_nop 0
	v_pk_mul_f32 v[136:137], v[136:137], v[138:139]
	s_nop 0
	v_cvt_pk_bf16_f32 v133, v136, v137
	global_store_dwordx4 v[128:129], v[130:133], off offset:256

.LBB0_1080:
	s_and_b64 vcc, exec, s[0:1]
	v_ashrrev_i32_e32 v175, 31, v174
	v_add_u32_e32 v130, s77, v172
	s_cbranch_vccz .LBB0_1082
	v_readlane_b32 s0, v251, 6
	v_mul_f32_e32 v132, v93, v176
	v_mul_f32_e32 v132, 0xbfb8aa3b, v132
	v_mov_b32_e32 v128, s0
	v_readlane_b32 s0, v251, 7
	ds_read_b32 v128, v128
	v_exp_f32_e32 v134, v132
	v_mov_b32_e32 v129, s0
	v_readlane_b32 s0, v250, 53
	ds_read_b32 v129, v129
	s_ashr_i32 s67, s66, 31
	v_mov_b32_e32 v131, s0
	ds_read_b32 v131, v131
	s_waitcnt lgkmcnt(0)
	v_readfirstlane_b32 s0, v128
	v_readfirstlane_b32 s1, v129
	s_lshl_b64 s[20:21], s[66:67], 1
	v_mul_f32_e32 v136, v95, v176
	v_readfirstlane_b32 s5, v131
	v_mul_f32_e32 v131, v92, v176
	v_mul_f32_e32 v131, 0xbfb8aa3b, v131
	v_exp_f32_e32 v131, v131
	v_mad_i64_i32 v[128:129], s[16:17], s5, v144, 0
	v_lshl_add_u64 v[128:129], v[128:129], 1, s[0:1]
	v_lshl_add_u64 v[132:133], v[128:129], 0, s[20:21]
	v_add_f32_e32 v128, 1.0, v131
	v_mul_f32_e32 v131, v94, v176
	v_add_f32_e32 v129, 1.0, v134
	v_mul_f32_e32 v131, 0xbfb8aa3b, v131
	v_rcp_f32_e32 v128, v128
	v_rcp_f32_e32 v129, v129
	v_exp_f32_e32 v131, v131
	v_mul_f32_e32 v136, 0xbfb8aa3b, v136
	v_exp_f32_e32 v136, v136
	v_pk_mul_f32 v[134:135], v[124:125], v[176:177] op_sel_hi:[1,0]
	v_mul_f32_e32 v138, v89, v176
	v_pk_mul_f32 v[134:135], v[134:135], v[128:129]
	v_add_f32_e32 v128, 1.0, v131
	v_mul_f32_e32 v131, v88, v176
	v_add_f32_e32 v129, 1.0, v136
	v_mul_f32_e32 v131, 0xbfb8aa3b, v131
	v_rcp_f32_e32 v128, v128
	v_rcp_f32_e32 v129, v129
	v_exp_f32_e32 v131, v131
	v_mul_f32_e32 v138, 0xbfb8aa3b, v138
	v_exp_f32_e32 v138, v138
	v_pk_mul_f32 v[136:137], v[126:127], v[176:177] op_sel_hi:[1,0]
	v_pk_mul_f32 v[140:141], v[120:121], v[176:177] op_sel_hi:[1,0]
	v_pk_mul_f32 v[136:137], v[136:137], v[128:129]
	v_add_f32_e32 v128, 1.0, v131
	v_mul_f32_e32 v131, v90, v176
	v_add_f32_e32 v129, 1.0, v138
	v_mul_f32_e32 v131, 0xbfb8aa3b, v131
	v_mul_f32_e32 v138, v91, v176
	v_exp_f32_e32 v131, v131
	v_mul_f32_e32 v138, 0xbfb8aa3b, v138
	v_exp_f32_e32 v139, v138
	v_rcp_f32_e32 v128, v128
	v_add_f32_e32 v131, 1.0, v131
	v_rcp_f32_e32 v129, v129
	v_rcp_f32_e32 v138, v131
	v_add_f32_e32 v131, 1.0, v139
	v_rcp_f32_e32 v139, v131
	v_pk_mul_f32 v[140:141], v[140:141], v[128:129]
	v_pk_mul_f32 v[128:129], v[122:123], v[176:177] op_sel_hi:[1,0]
	v_mul_f32_e32 v131, v84, v170
	v_pk_mul_f32 v[138:139], v[128:129], v[138:139]
	v_lshlrev_b64 v[128:129], 1, v[174:175]
	v_lshl_add_u64 v[142:143], v[132:133], 0, v[128:129]
	v_cvt_pk_bf16_f32 v132, v134, v135
	v_cvt_pk_bf16_f32 v133, v136, v137
	v_cvt_pk_bf16_f32 v134, v140, v141
	v_cvt_pk_bf16_f32 v135, v138, v139
	global_store_dwordx4 v[142:143], v[132:135], off
	v_mul_f32_e32 v131, 0xbfb8aa3b, v131
	v_exp_f32_e32 v131, v131
	v_mul_f32_e32 v134, v85, v170
	v_mul_f32_e32 v134, 0xbfb8aa3b, v134
	v_exp_f32_e32 v135, v134
	v_add_f32_e32 v131, 1.0, v131
	v_rcp_f32_e32 v134, v131
	v_mul_f32_e32 v138, v87, v170
	v_add_f32_e32 v131, 1.0, v135
	v_rcp_f32_e32 v135, v131
	v_mul_f32_e32 v131, v86, v170
	v_mul_f32_e32 v131, 0xbfb8aa3b, v131
	v_exp_f32_e32 v131, v131
	v_mul_f32_e32 v138, 0xbfb8aa3b, v138
	v_exp_f32_e32 v138, v138
	v_pk_mul_f32 v[136:137], v[116:117], v[170:171] op_sel_hi:[1,0]
	v_add_f32_e32 v131, 1.0, v131
	v_pk_mul_f32 v[134:135], v[136:137], v[134:135]
	v_rcp_f32_e32 v136, v131
	v_add_f32_e32 v131, 1.0, v138
	v_rcp_f32_e32 v137, v131
	v_mul_f32_e32 v131, v80, v170
	v_mul_f32_e32 v131, 0xbfb8aa3b, v131
	v_mul_f32_e32 v140, v81, v170
	v_exp_f32_e32 v131, v131
	v_mul_f32_e32 v140, 0xbfb8aa3b, v140
	v_exp_f32_e32 v140, v140
	v_pk_mul_f32 v[138:139], v[118:119], v[170:171] op_sel_hi:[1,0]
	v_add_f32_e32 v131, 1.0, v131
	v_pk_mul_f32 v[136:137], v[138:139], v[136:137]
	v_mul_f32_e32 v139, v82, v170
	v_mul_f32_e32 v139, 0xbfb8aa3b, v139
	v_rcp_f32_e32 v138, v131
	v_add_f32_e32 v131, 1.0, v140
	v_exp_f32_e32 v140, v139
	v_mul_f32_e32 v139, v83, v170
	v_mul_f32_e32 v139, 0xbfb8aa3b, v139
	v_exp_f32_e32 v141, v139
	v_rcp_f32_e32 v139, v131
	v_add_f32_e32 v131, 1.0, v140
	v_rcp_f32_e32 v140, v131
	v_add_f32_e32 v131, 1.0, v141
	v_rcp_f32_e32 v141, v131
	v_mad_i64_i32 v[132:133], s[16:17], s5, v162, 0
	v_pk_mul_f32 v[142:143], v[112:113], v[170:171] op_sel_hi:[1,0]
	v_lshl_add_u64 v[132:133], v[132:133], 1, s[0:1]
	v_pk_mul_f32 v[138:139], v[142:143], v[138:139]
	v_pk_mul_f32 v[142:143], v[114:115], v[170:171] op_sel_hi:[1,0]
	v_lshl_add_u64 v[132:133], v[132:133], 0, s[20:21]
	v_pk_mul_f32 v[140:141], v[142:143], v[140:141]
	v_lshl_add_u64 v[142:143], v[132:133], 0, v[128:129]
	v_cvt_pk_bf16_f32 v132, v134, v135
	v_cvt_pk_bf16_f32 v133, v136, v137
	v_cvt_pk_bf16_f32 v134, v138, v139
	v_cvt_pk_bf16_f32 v135, v140, v141
	v_mul_f32_e32 v131, v76, v168
	global_store_dwordx4 v[142:143], v[132:135], off
	v_mul_f32_e32 v131, 0xbfb8aa3b, v131
	v_exp_f32_e32 v131, v131
	v_mul_f32_e32 v134, v77, v168
	v_mul_f32_e32 v134, 0xbfb8aa3b, v134
	v_exp_f32_e32 v135, v134
	v_add_f32_e32 v131, 1.0, v131
	v_rcp_f32_e32 v134, v131
	v_mul_f32_e32 v138, v79, v168
	v_add_f32_e32 v131, 1.0, v135
	v_rcp_f32_e32 v135, v131
	v_mul_f32_e32 v131, v78, v168
	v_mul_f32_e32 v131, 0xbfb8aa3b, v131
	v_exp_f32_e32 v131, v131
	v_mul_f32_e32 v138, 0xbfb8aa3b, v138
	v_exp_f32_e32 v138, v138
	v_pk_mul_f32 v[136:137], v[108:109], v[168:169] op_sel_hi:[1,0]
	v_add_f32_e32 v131, 1.0, v131
	v_pk_mul_f32 v[134:135], v[136:137], v[134:135]
	v_rcp_f32_e32 v136, v131
	v_add_f32_e32 v131, 1.0, v138
	v_rcp_f32_e32 v137, v131
	v_mul_f32_e32 v131, v72, v168
	v_mul_f32_e32 v131, 0xbfb8aa3b, v131
	v_mul_f32_e32 v140, v73, v168
	v_exp_f32_e32 v131, v131
	v_mul_f32_e32 v140, 0xbfb8aa3b, v140
	v_exp_f32_e32 v140, v140
	v_pk_mul_f32 v[138:139], v[110:111], v[168:169] op_sel_hi:[1,0]
	v_add_f32_e32 v131, 1.0, v131
	v_pk_mul_f32 v[136:137], v[138:139], v[136:137]
	v_mul_f32_e32 v139, v74, v168
	v_mul_f32_e32 v139, 0xbfb8aa3b, v139
	v_rcp_f32_e32 v138, v131
	v_add_f32_e32 v131, 1.0, v140
	v_exp_f32_e32 v140, v139
	v_mul_f32_e32 v139, v75, v168
	v_mul_f32_e32 v139, 0xbfb8aa3b, v139
	v_exp_f32_e32 v141, v139
	v_rcp_f32_e32 v139, v131
	v_add_f32_e32 v131, 1.0, v140
	v_rcp_f32_e32 v140, v131
	v_add_f32_e32 v131, 1.0, v141
	v_rcp_f32_e32 v141, v131
	v_mad_i64_i32 v[132:133], s[16:17], s5, v158, 0
	v_pk_mul_f32 v[142:143], v[104:105], v[168:169] op_sel_hi:[1,0]
	v_lshl_add_u64 v[132:133], v[132:133], 1, s[0:1]
	v_pk_mul_f32 v[138:139], v[142:143], v[138:139]
	v_pk_mul_f32 v[142:143], v[106:107], v[168:169] op_sel_hi:[1,0]
	v_lshl_add_u64 v[132:133], v[132:133], 0, s[20:21]
	v_pk_mul_f32 v[140:141], v[142:143], v[140:141]
	v_lshl_add_u64 v[142:143], v[132:133], 0, v[128:129]
	v_cvt_pk_bf16_f32 v132, v134, v135
	v_cvt_pk_bf16_f32 v133, v136, v137
	v_cvt_pk_bf16_f32 v134, v138, v139
	v_cvt_pk_bf16_f32 v135, v140, v141
	v_mul_f32_e32 v131, v68, v166
	global_store_dwordx4 v[142:143], v[132:135], off
	v_mul_f32_e32 v131, 0xbfb8aa3b, v131
	v_exp_f32_e32 v131, v131
	v_mul_f32_e32 v134, v69, v166
	v_mul_f32_e32 v134, 0xbfb8aa3b, v134
	v_exp_f32_e32 v135, v134
	v_add_f32_e32 v131, 1.0, v131
	v_rcp_f32_e32 v134, v131
	v_mul_f32_e32 v138, v71, v166
	v_add_f32_e32 v131, 1.0, v135
	v_rcp_f32_e32 v135, v131
	v_mul_f32_e32 v131, v70, v166
	v_mul_f32_e32 v131, 0xbfb8aa3b, v131
	v_exp_f32_e32 v131, v131
	v_mul_f32_e32 v138, 0xbfb8aa3b, v138
	v_exp_f32_e32 v138, v138
	v_pk_mul_f32 v[136:137], v[100:101], v[166:167] op_sel_hi:[1,0]
	v_add_f32_e32 v131, 1.0, v131
	v_pk_mul_f32 v[134:135], v[136:137], v[134:135]
	v_rcp_f32_e32 v136, v131
	v_add_f32_e32 v131, 1.0, v138
	v_rcp_f32_e32 v137, v131
	v_mul_f32_e32 v131, v64, v166
	v_mul_f32_e32 v131, 0xbfb8aa3b, v131
	v_mul_f32_e32 v140, v65, v166
	v_exp_f32_e32 v131, v131
	v_mul_f32_e32 v140, 0xbfb8aa3b, v140
	v_exp_f32_e32 v140, v140
	v_pk_mul_f32 v[138:139], v[102:103], v[166:167] op_sel_hi:[1,0]
	v_add_f32_e32 v131, 1.0, v131
	v_pk_mul_f32 v[136:137], v[138:139], v[136:137]
	v_mul_f32_e32 v139, v66, v166
	v_mul_f32_e32 v139, 0xbfb8aa3b, v139
	v_rcp_f32_e32 v138, v131
	v_add_f32_e32 v131, 1.0, v140
	v_exp_f32_e32 v140, v139
	v_mul_f32_e32 v139, v67, v166
	v_mul_f32_e32 v139, 0xbfb8aa3b, v139
	v_exp_f32_e32 v141, v139
	v_rcp_f32_e32 v139, v131
	v_add_f32_e32 v131, 1.0, v140
	v_rcp_f32_e32 v140, v131
	v_add_f32_e32 v131, 1.0, v141
	v_rcp_f32_e32 v141, v131
	v_mad_i64_i32 v[132:133], s[16:17], s5, v154, 0
	v_pk_mul_f32 v[142:143], v[96:97], v[166:167] op_sel_hi:[1,0]
	v_lshl_add_u64 v[132:133], v[132:133], 1, s[0:1]
	v_pk_mul_f32 v[138:139], v[142:143], v[138:139]
	v_pk_mul_f32 v[142:143], v[98:99], v[166:167] op_sel_hi:[1,0]
	v_lshl_add_u64 v[132:133], v[132:133], 0, s[20:21]
	v_pk_mul_f32 v[140:141], v[142:143], v[140:141]
	v_lshl_add_u64 v[142:143], v[132:133], 0, v[128:129]
	v_cvt_pk_bf16_f32 v132, v134, v135
	v_cvt_pk_bf16_f32 v133, v136, v137
	v_cvt_pk_bf16_f32 v134, v138, v139
	v_cvt_pk_bf16_f32 v135, v140, v141
	v_mul_f32_e32 v131, v28, v164
	global_store_dwordx4 v[142:143], v[132:135], off
	v_mul_f32_e32 v131, 0xbfb8aa3b, v131
	v_exp_f32_e32 v131, v131
	v_mul_f32_e32 v134, v29, v164
	v_mul_f32_e32 v134, 0xbfb8aa3b, v134
	v_exp_f32_e32 v135, v134
	v_add_f32_e32 v131, 1.0, v131
	v_rcp_f32_e32 v134, v131
	v_mul_f32_e32 v138, v31, v164
	v_add_f32_e32 v131, 1.0, v135
	v_rcp_f32_e32 v135, v131
	v_mul_f32_e32 v131, v30, v164
	v_mul_f32_e32 v131, 0xbfb8aa3b, v131
	v_exp_f32_e32 v131, v131
	v_mul_f32_e32 v138, 0xbfb8aa3b, v138
	v_exp_f32_e32 v138, v138
	v_pk_mul_f32 v[136:137], v[60:61], v[164:165] op_sel_hi:[1,0]
	v_add_f32_e32 v131, 1.0, v131
	v_pk_mul_f32 v[134:135], v[136:137], v[134:135]
	v_rcp_f32_e32 v136, v131
	v_add_f32_e32 v131, 1.0, v138
	v_rcp_f32_e32 v137, v131
	v_mul_f32_e32 v131, v24, v164
	v_mul_f32_e32 v131, 0xbfb8aa3b, v131
	v_mul_f32_e32 v140, v25, v164
	v_exp_f32_e32 v131, v131
	v_mul_f32_e32 v140, 0xbfb8aa3b, v140
	v_exp_f32_e32 v140, v140
	v_pk_mul_f32 v[138:139], v[62:63], v[164:165] op_sel_hi:[1,0]
	v_add_f32_e32 v131, 1.0, v131
	v_pk_mul_f32 v[136:137], v[138:139], v[136:137]
	v_mul_f32_e32 v139, v26, v164
	v_mul_f32_e32 v139, 0xbfb8aa3b, v139
	v_rcp_f32_e32 v138, v131
	v_add_f32_e32 v131, 1.0, v140
	v_exp_f32_e32 v140, v139
	v_mul_f32_e32 v139, v27, v164
	v_mul_f32_e32 v139, 0xbfb8aa3b, v139
	v_exp_f32_e32 v141, v139
	v_rcp_f32_e32 v139, v131
	v_add_f32_e32 v131, 1.0, v140
	v_rcp_f32_e32 v140, v131
	v_add_f32_e32 v131, 1.0, v141
	v_rcp_f32_e32 v141, v131
	v_mad_i64_i32 v[132:133], s[16:17], s5, v130, 0
	v_pk_mul_f32 v[142:143], v[56:57], v[164:165] op_sel_hi:[1,0]
	v_lshl_add_u64 v[132:133], v[132:133], 1, s[0:1]
	v_pk_mul_f32 v[138:139], v[142:143], v[138:139]
	v_pk_mul_f32 v[142:143], v[58:59], v[164:165] op_sel_hi:[1,0]
	v_lshl_add_u64 v[132:133], v[132:133], 0, s[20:21]
	v_pk_mul_f32 v[140:141], v[142:143], v[140:141]
	v_lshl_add_u64 v[142:143], v[132:133], 0, v[128:129]
	v_cvt_pk_bf16_f32 v132, v134, v135
	v_cvt_pk_bf16_f32 v133, v136, v137
	v_cvt_pk_bf16_f32 v134, v138, v139
	v_cvt_pk_bf16_f32 v135, v140, v141
	v_mul_f32_e32 v131, v20, v160
	global_store_dwordx4 v[142:143], v[132:135], off
	v_mul_f32_e32 v131, 0xbfb8aa3b, v131
	v_exp_f32_e32 v131, v131
	v_mul_f32_e32 v134, v21, v160
	v_mul_f32_e32 v134, 0xbfb8aa3b, v134
	v_exp_f32_e32 v135, v134
	v_add_f32_e32 v131, 1.0, v131
	v_rcp_f32_e32 v134, v131
	v_mul_f32_e32 v138, v23, v160
	v_add_f32_e32 v131, 1.0, v135
	v_rcp_f32_e32 v135, v131
	v_mul_f32_e32 v131, v22, v160
	v_mul_f32_e32 v131, 0xbfb8aa3b, v131
	v_exp_f32_e32 v131, v131
	v_mul_f32_e32 v138, 0xbfb8aa3b, v138
	v_exp_f32_e32 v138, v138
	v_pk_mul_f32 v[136:137], v[52:53], v[160:161] op_sel_hi:[1,0]
	v_add_f32_e32 v131, 1.0, v131
	v_pk_mul_f32 v[134:135], v[136:137], v[134:135]
	v_rcp_f32_e32 v136, v131
	v_add_f32_e32 v131, 1.0, v138
	v_rcp_f32_e32 v137, v131
	v_mul_f32_e32 v131, v16, v160
	v_mul_f32_e32 v131, 0xbfb8aa3b, v131
	v_mul_f32_e32 v140, v17, v160
	v_exp_f32_e32 v131, v131
	v_mul_f32_e32 v140, 0xbfb8aa3b, v140
	v_exp_f32_e32 v140, v140
	v_pk_mul_f32 v[138:139], v[54:55], v[160:161] op_sel_hi:[1,0]
	v_add_f32_e32 v131, 1.0, v131
	v_pk_mul_f32 v[136:137], v[138:139], v[136:137]
	v_mul_f32_e32 v139, v18, v160
	v_mul_f32_e32 v139, 0xbfb8aa3b, v139
	v_rcp_f32_e32 v138, v131
	v_add_f32_e32 v131, 1.0, v140
	v_exp_f32_e32 v140, v139
	v_mul_f32_e32 v139, v19, v160
	v_mul_f32_e32 v139, 0xbfb8aa3b, v139
	v_exp_f32_e32 v141, v139
	v_rcp_f32_e32 v139, v131
	v_add_f32_e32 v131, 1.0, v140
	v_rcp_f32_e32 v140, v131
	v_add_f32_e32 v131, 1.0, v141
	v_rcp_f32_e32 v141, v131
	v_mad_i64_i32 v[132:133], s[16:17], s5, v150, 0
	v_pk_mul_f32 v[142:143], v[48:49], v[160:161] op_sel_hi:[1,0]
	v_lshl_add_u64 v[132:133], v[132:133], 1, s[0:1]
	v_pk_mul_f32 v[138:139], v[142:143], v[138:139]
	v_pk_mul_f32 v[142:143], v[50:51], v[160:161] op_sel_hi:[1,0]
	v_lshl_add_u64 v[132:133], v[132:133], 0, s[20:21]
	v_pk_mul_f32 v[140:141], v[142:143], v[140:141]
	v_lshl_add_u64 v[142:143], v[132:133], 0, v[128:129]
	v_cvt_pk_bf16_f32 v132, v134, v135
	v_cvt_pk_bf16_f32 v133, v136, v137
	v_cvt_pk_bf16_f32 v134, v138, v139
	v_cvt_pk_bf16_f32 v135, v140, v141
	v_mul_f32_e32 v131, v12, v156
	global_store_dwordx4 v[142:143], v[132:135], off
	v_mul_f32_e32 v131, 0xbfb8aa3b, v131
	v_exp_f32_e32 v131, v131
	v_mul_f32_e32 v134, v13, v156
	v_mul_f32_e32 v134, 0xbfb8aa3b, v134
	v_exp_f32_e32 v135, v134
	v_add_f32_e32 v131, 1.0, v131
	v_rcp_f32_e32 v134, v131
	v_mul_f32_e32 v138, v15, v156
	v_add_f32_e32 v131, 1.0, v135
	v_rcp_f32_e32 v135, v131
	v_mul_f32_e32 v131, v14, v156
	v_mul_f32_e32 v131, 0xbfb8aa3b, v131
	v_exp_f32_e32 v131, v131
	v_mul_f32_e32 v138, 0xbfb8aa3b, v138
	v_exp_f32_e32 v138, v138
	v_pk_mul_f32 v[136:137], v[44:45], v[156:157] op_sel_hi:[1,0]
	v_add_f32_e32 v131, 1.0, v131
	v_pk_mul_f32 v[134:135], v[136:137], v[134:135]
	v_rcp_f32_e32 v136, v131
	v_add_f32_e32 v131, 1.0, v138
	v_rcp_f32_e32 v137, v131
	v_mul_f32_e32 v131, v8, v156
	v_mul_f32_e32 v131, 0xbfb8aa3b, v131
	v_mul_f32_e32 v140, v9, v156
	v_exp_f32_e32 v131, v131
	v_mul_f32_e32 v140, 0xbfb8aa3b, v140
	v_exp_f32_e32 v140, v140
	v_pk_mul_f32 v[138:139], v[46:47], v[156:157] op_sel_hi:[1,0]
	v_add_f32_e32 v131, 1.0, v131
	v_pk_mul_f32 v[136:137], v[138:139], v[136:137]
	v_mul_f32_e32 v139, v10, v156
	v_mul_f32_e32 v139, 0xbfb8aa3b, v139
	v_rcp_f32_e32 v138, v131
	v_add_f32_e32 v131, 1.0, v140
	v_exp_f32_e32 v140, v139
	v_mul_f32_e32 v139, v11, v156
	v_mul_f32_e32 v139, 0xbfb8aa3b, v139
	v_exp_f32_e32 v141, v139
	v_rcp_f32_e32 v139, v131
	v_add_f32_e32 v131, 1.0, v140
	v_rcp_f32_e32 v140, v131
	v_add_f32_e32 v131, 1.0, v141
	v_rcp_f32_e32 v141, v131
	v_mad_i64_i32 v[132:133], s[16:17], s5, v148, 0
	v_pk_mul_f32 v[142:143], v[40:41], v[156:157] op_sel_hi:[1,0]
	v_lshl_add_u64 v[132:133], v[132:133], 1, s[0:1]
	v_pk_mul_f32 v[138:139], v[142:143], v[138:139]
	v_pk_mul_f32 v[142:143], v[42:43], v[156:157] op_sel_hi:[1,0]
	v_lshl_add_u64 v[132:133], v[132:133], 0, s[20:21]
	v_pk_mul_f32 v[140:141], v[142:143], v[140:141]
	v_lshl_add_u64 v[142:143], v[132:133], 0, v[128:129]
	v_cvt_pk_bf16_f32 v132, v134, v135
	v_cvt_pk_bf16_f32 v133, v136, v137
	v_cvt_pk_bf16_f32 v134, v138, v139
	v_cvt_pk_bf16_f32 v135, v140, v141
	v_mul_f32_e32 v131, v4, v152
	global_store_dwordx4 v[142:143], v[132:135], off
	v_mul_f32_e32 v131, 0xbfb8aa3b, v131
	v_exp_f32_e32 v131, v131
	v_mul_f32_e32 v134, v5, v152
	v_mul_f32_e32 v134, 0xbfb8aa3b, v134
	v_exp_f32_e32 v135, v134
	v_add_f32_e32 v131, 1.0, v131
	v_rcp_f32_e32 v134, v131
	v_mul_f32_e32 v138, v7, v152
	v_add_f32_e32 v131, 1.0, v135
	v_rcp_f32_e32 v135, v131
	v_mul_f32_e32 v131, v6, v152
	v_mul_f32_e32 v131, 0xbfb8aa3b, v131
	v_exp_f32_e32 v131, v131
	v_mul_f32_e32 v138, 0xbfb8aa3b, v138
	v_exp_f32_e32 v138, v138
	v_pk_mul_f32 v[136:137], v[36:37], v[152:153] op_sel_hi:[1,0]
	v_add_f32_e32 v131, 1.0, v131
	v_pk_mul_f32 v[134:135], v[136:137], v[134:135]
	v_rcp_f32_e32 v136, v131
	v_add_f32_e32 v131, 1.0, v138
	v_rcp_f32_e32 v137, v131
	v_mul_f32_e32 v131, v0, v152
	v_mul_f32_e32 v131, 0xbfb8aa3b, v131
	v_mul_f32_e32 v140, v1, v152
	v_exp_f32_e32 v131, v131
	v_mul_f32_e32 v140, 0xbfb8aa3b, v140
	v_exp_f32_e32 v140, v140
	v_pk_mul_f32 v[138:139], v[38:39], v[152:153] op_sel_hi:[1,0]
	v_add_f32_e32 v131, 1.0, v131
	v_pk_mul_f32 v[136:137], v[138:139], v[136:137]
	v_mul_f32_e32 v139, v2, v152
	v_mul_f32_e32 v139, 0xbfb8aa3b, v139
	v_rcp_f32_e32 v138, v131
	v_add_f32_e32 v131, 1.0, v140
	v_exp_f32_e32 v140, v139
	v_mul_f32_e32 v139, v3, v152
	v_mul_f32_e32 v139, 0xbfb8aa3b, v139
	v_exp_f32_e32 v141, v139
	v_rcp_f32_e32 v139, v131
	v_add_f32_e32 v131, 1.0, v140
	v_rcp_f32_e32 v140, v131
	v_add_f32_e32 v131, 1.0, v141
	v_rcp_f32_e32 v141, v131
	v_mad_i64_i32 v[132:133], s[16:17], s5, v146, 0
	v_pk_mul_f32 v[142:143], v[32:33], v[152:153] op_sel_hi:[1,0]
	v_lshl_add_u64 v[132:133], v[132:133], 1, s[0:1]
	v_pk_mul_f32 v[138:139], v[142:143], v[138:139]
	v_pk_mul_f32 v[142:143], v[34:35], v[152:153] op_sel_hi:[1,0]
	v_lshl_add_u64 v[132:133], v[132:133], 0, s[20:21]
	v_pk_mul_f32 v[140:141], v[142:143], v[140:141]
	v_lshl_add_u64 v[128:129], v[132:133], 0, v[128:129]
	v_cvt_pk_bf16_f32 v132, v134, v135
	v_cvt_pk_bf16_f32 v133, v136, v137
	v_cvt_pk_bf16_f32 v134, v138, v139
	v_cvt_pk_bf16_f32 v135, v140, v141
	global_store_dwordx4 v[128:129], v[132:135], off
	s_mov_b64 s[30:31], 0
.LBB0_1082:
	s_andn2_b64 vcc, exec, s[30:31]
	s_cbranch_vccnz .LBB0_1084
	v_readlane_b32 s0, v251, 4
	s_ashr_i32 s67, s66, 31
	s_lshl_b64 s[20:21], s[66:67], 1
	v_mov_b32_e32 v128, s0
	ds_read_b32 v128, v128
	v_readlane_b32 s0, v251, 5
	v_pk_mul_f32 v[134:135], v[126:127], v[176:177] op_sel_hi:[1,0]
	v_pk_mul_f32 v[138:139], v[120:121], v[176:177] op_sel_hi:[1,0]
	s_waitcnt lgkmcnt(0)
	v_mov_b32_e32 v128, s0
	ds_read_b32 v128, v128
	v_readlane_b32 s0, v251, 6
	v_pk_mul_f32 v[140:141], v[122:123], v[176:177] op_sel_hi:[1,0]
	s_waitcnt lgkmcnt(0)
	v_mov_b32_e32 v128, s0
	v_readlane_b32 s0, v251, 7
	ds_read_b32 v128, v128
	s_nop 0
	v_mov_b32_e32 v129, s0
	v_readlane_b32 s0, v250, 53
	ds_read_b32 v129, v129
	s_waitcnt lgkmcnt(0)
	v_readfirstlane_b32 s1, v129
	v_mov_b32_e32 v131, s0
	ds_read_b32 v131, v131
	v_readfirstlane_b32 s0, v128
	s_waitcnt lgkmcnt(0)
	v_readfirstlane_b32 s5, v131
	s_nop 1
	v_mad_i64_i32 v[128:129], s[16:17], s5, v144, 0
	v_lshl_add_u64 v[128:129], v[128:129], 1, s[0:1]
	v_lshl_add_u64 v[132:133], v[128:129], 0, s[20:21]
	v_lshlrev_b64 v[128:129], 1, v[174:175]
	v_lshl_add_u64 v[136:137], v[132:133], 0, v[128:129]
	v_pk_mul_f32 v[132:133], v[124:125], v[176:177] op_sel_hi:[1,0]
	v_mad_i64_i32 v[130:131], s[16:17], s5, v130, 0
	v_cvt_pk_bf16_f32 v132, v132, v133
	v_cvt_pk_bf16_f32 v133, v134, v135
	v_cvt_pk_bf16_f32 v134, v138, v139
	v_cvt_pk_bf16_f32 v135, v140, v141
	global_store_dwordx4 v[136:137], v[132:135], off
	v_pk_mul_f32 v[138:139], v[88:89], v[176:177] op_sel_hi:[1,0]
	v_pk_mul_f32 v[140:141], v[90:91], v[176:177] op_sel_hi:[1,0]
	v_pk_mul_f32 v[132:133], v[92:93], v[176:177] op_sel_hi:[1,0]
	v_pk_mul_f32 v[134:135], v[94:95], v[176:177] op_sel_hi:[1,0]
	v_cvt_pk_bf16_f32 v132, v132, v133
	v_cvt_pk_bf16_f32 v133, v134, v135
	v_cvt_pk_bf16_f32 v134, v138, v139
	v_cvt_pk_bf16_f32 v135, v140, v141
	global_store_dwordx4 v[136:137], v[132:135], off offset:256
	v_pk_mul_f32 v[138:139], v[112:113], v[170:171] op_sel_hi:[1,0]
	v_pk_mul_f32 v[140:141], v[114:115], v[170:171] op_sel_hi:[1,0]
	v_mad_i64_i32 v[132:133], s[16:17], s5, v162, 0
	v_lshl_add_u64 v[132:133], v[132:133], 1, s[0:1]
	v_lshl_add_u64 v[132:133], v[132:133], 0, s[20:21]
	v_lshl_add_u64 v[136:137], v[132:133], 0, v[128:129]
	v_pk_mul_f32 v[132:133], v[116:117], v[170:171] op_sel_hi:[1,0]
	v_pk_mul_f32 v[134:135], v[118:119], v[170:171] op_sel_hi:[1,0]
	v_cvt_pk_bf16_f32 v132, v132, v133
	v_cvt_pk_bf16_f32 v133, v134, v135
	v_cvt_pk_bf16_f32 v134, v138, v139
	v_cvt_pk_bf16_f32 v135, v140, v141
	global_store_dwordx4 v[136:137], v[132:135], off
	v_pk_mul_f32 v[138:139], v[80:81], v[170:171] op_sel_hi:[1,0]
	v_pk_mul_f32 v[140:141], v[82:83], v[170:171] op_sel_hi:[1,0]
	v_pk_mul_f32 v[132:133], v[84:85], v[170:171] op_sel_hi:[1,0]
	v_pk_mul_f32 v[134:135], v[86:87], v[170:171] op_sel_hi:[1,0]
	v_cvt_pk_bf16_f32 v132, v132, v133
	v_cvt_pk_bf16_f32 v133, v134, v135
	v_cvt_pk_bf16_f32 v134, v138, v139
	v_cvt_pk_bf16_f32 v135, v140, v141
	global_store_dwordx4 v[136:137], v[132:135], off offset:256
	v_pk_mul_f32 v[138:139], v[104:105], v[168:169] op_sel_hi:[1,0]
	v_pk_mul_f32 v[140:141], v[106:107], v[168:169] op_sel_hi:[1,0]
	v_mad_i64_i32 v[132:133], s[16:17], s5, v158, 0
	v_lshl_add_u64 v[132:133], v[132:133], 1, s[0:1]
	v_lshl_add_u64 v[132:133], v[132:133], 0, s[20:21]
	v_lshl_add_u64 v[136:137], v[132:133], 0, v[128:129]
	v_pk_mul_f32 v[132:133], v[108:109], v[168:169] op_sel_hi:[1,0]
	v_pk_mul_f32 v[134:135], v[110:111], v[168:169] op_sel_hi:[1,0]
	v_cvt_pk_bf16_f32 v132, v132, v133
	v_cvt_pk_bf16_f32 v133, v134, v135
	v_cvt_pk_bf16_f32 v134, v138, v139
	v_cvt_pk_bf16_f32 v135, v140, v141
	global_store_dwordx4 v[136:137], v[132:135], off
	v_pk_mul_f32 v[138:139], v[72:73], v[168:169] op_sel_hi:[1,0]
	v_pk_mul_f32 v[140:141], v[74:75], v[168:169] op_sel_hi:[1,0]
	v_pk_mul_f32 v[132:133], v[76:77], v[168:169] op_sel_hi:[1,0]
	v_pk_mul_f32 v[134:135], v[78:79], v[168:169] op_sel_hi:[1,0]
	v_cvt_pk_bf16_f32 v132, v132, v133
	v_cvt_pk_bf16_f32 v133, v134, v135
	v_cvt_pk_bf16_f32 v134, v138, v139
	v_cvt_pk_bf16_f32 v135, v140, v141
	global_store_dwordx4 v[136:137], v[132:135], off offset:256
	v_pk_mul_f32 v[138:139], v[96:97], v[166:167] op_sel_hi:[1,0]
	v_pk_mul_f32 v[140:141], v[98:99], v[166:167] op_sel_hi:[1,0]
	v_mad_i64_i32 v[132:133], s[16:17], s5, v154, 0
	v_lshl_add_u64 v[132:133], v[132:133], 1, s[0:1]
	v_lshl_add_u64 v[132:133], v[132:133], 0, s[20:21]
	v_lshl_add_u64 v[136:137], v[132:133], 0, v[128:129]
	v_pk_mul_f32 v[132:133], v[100:101], v[166:167] op_sel_hi:[1,0]
	v_pk_mul_f32 v[134:135], v[102:103], v[166:167] op_sel_hi:[1,0]
	v_cvt_pk_bf16_f32 v132, v132, v133
	v_cvt_pk_bf16_f32 v133, v134, v135
	v_cvt_pk_bf16_f32 v134, v138, v139
	v_cvt_pk_bf16_f32 v135, v140, v141
	global_store_dwordx4 v[136:137], v[132:135], off
	v_pk_mul_f32 v[138:139], v[64:65], v[166:167] op_sel_hi:[1,0]
	v_pk_mul_f32 v[140:141], v[66:67], v[166:167] op_sel_hi:[1,0]
	v_pk_mul_f32 v[132:133], v[68:69], v[166:167] op_sel_hi:[1,0]
	v_pk_mul_f32 v[134:135], v[70:71], v[166:167] op_sel_hi:[1,0]
	v_lshl_add_u64 v[130:131], v[130:131], 1, s[0:1]
	v_cvt_pk_bf16_f32 v132, v132, v133
	v_cvt_pk_bf16_f32 v133, v134, v135
	v_cvt_pk_bf16_f32 v134, v138, v139
	v_cvt_pk_bf16_f32 v135, v140, v141
	v_lshl_add_u64 v[130:131], v[130:131], 0, s[20:21]
	global_store_dwordx4 v[136:137], v[132:135], off offset:256
	v_pk_mul_f32 v[136:137], v[56:57], v[164:165] op_sel_hi:[1,0]
	v_pk_mul_f32 v[138:139], v[58:59], v[164:165] op_sel_hi:[1,0]
	v_lshl_add_u64 v[134:135], v[130:131], 0, v[128:129]
	v_pk_mul_f32 v[130:131], v[60:61], v[164:165] op_sel_hi:[1,0]
	v_pk_mul_f32 v[132:133], v[62:63], v[164:165] op_sel_hi:[1,0]
	v_cvt_pk_bf16_f32 v130, v130, v131
	v_cvt_pk_bf16_f32 v131, v132, v133
	v_cvt_pk_bf16_f32 v132, v136, v137
	v_cvt_pk_bf16_f32 v133, v138, v139
	global_store_dwordx4 v[134:135], v[130:133], off
	v_pk_mul_f32 v[136:137], v[24:25], v[164:165] op_sel_hi:[1,0]
	v_pk_mul_f32 v[138:139], v[26:27], v[164:165] op_sel_hi:[1,0]
	v_pk_mul_f32 v[130:131], v[28:29], v[164:165] op_sel_hi:[1,0]
	v_pk_mul_f32 v[132:133], v[30:31], v[164:165] op_sel_hi:[1,0]
	v_cvt_pk_bf16_f32 v130, v130, v131
	v_cvt_pk_bf16_f32 v131, v132, v133
	v_cvt_pk_bf16_f32 v132, v136, v137
	v_cvt_pk_bf16_f32 v133, v138, v139
	global_store_dwordx4 v[134:135], v[130:133], off offset:256
	v_pk_mul_f32 v[136:137], v[48:49], v[160:161] op_sel_hi:[1,0]
	v_pk_mul_f32 v[138:139], v[50:51], v[160:161] op_sel_hi:[1,0]
	v_mad_i64_i32 v[130:131], s[16:17], s5, v150, 0
	v_lshl_add_u64 v[130:131], v[130:131], 1, s[0:1]
	v_lshl_add_u64 v[130:131], v[130:131], 0, s[20:21]
	v_lshl_add_u64 v[134:135], v[130:131], 0, v[128:129]
	v_pk_mul_f32 v[130:131], v[52:53], v[160:161] op_sel_hi:[1,0]
	v_pk_mul_f32 v[132:133], v[54:55], v[160:161] op_sel_hi:[1,0]
	v_cvt_pk_bf16_f32 v130, v130, v131
	v_cvt_pk_bf16_f32 v131, v132, v133
	v_cvt_pk_bf16_f32 v132, v136, v137
	v_cvt_pk_bf16_f32 v133, v138, v139
	global_store_dwordx4 v[134:135], v[130:133], off
	v_pk_mul_f32 v[136:137], v[16:17], v[160:161] op_sel_hi:[1,0]
	v_pk_mul_f32 v[138:139], v[18:19], v[160:161] op_sel_hi:[1,0]
	v_pk_mul_f32 v[130:131], v[20:21], v[160:161] op_sel_hi:[1,0]
	v_pk_mul_f32 v[132:133], v[22:23], v[160:161] op_sel_hi:[1,0]
	v_cvt_pk_bf16_f32 v130, v130, v131
	v_cvt_pk_bf16_f32 v131, v132, v133
	v_cvt_pk_bf16_f32 v132, v136, v137
	v_cvt_pk_bf16_f32 v133, v138, v139
	global_store_dwordx4 v[134:135], v[130:133], off offset:256
	v_pk_mul_f32 v[136:137], v[40:41], v[156:157] op_sel_hi:[1,0]
	v_pk_mul_f32 v[138:139], v[42:43], v[156:157] op_sel_hi:[1,0]
	v_mad_i64_i32 v[130:131], s[16:17], s5, v148, 0
	v_lshl_add_u64 v[130:131], v[130:131], 1, s[0:1]
	v_lshl_add_u64 v[130:131], v[130:131], 0, s[20:21]
	v_lshl_add_u64 v[134:135], v[130:131], 0, v[128:129]
	v_pk_mul_f32 v[130:131], v[44:45], v[156:157] op_sel_hi:[1,0]
	v_pk_mul_f32 v[132:133], v[46:47], v[156:157] op_sel_hi:[1,0]
	v_cvt_pk_bf16_f32 v130, v130, v131
	v_cvt_pk_bf16_f32 v131, v132, v133
	v_cvt_pk_bf16_f32 v132, v136, v137
	v_cvt_pk_bf16_f32 v133, v138, v139
	global_store_dwordx4 v[134:135], v[130:133], off
	v_pk_mul_f32 v[136:137], v[8:9], v[156:157] op_sel_hi:[1,0]
	v_pk_mul_f32 v[138:139], v[10:11], v[156:157] op_sel_hi:[1,0]
	v_pk_mul_f32 v[130:131], v[12:13], v[156:157] op_sel_hi:[1,0]
	v_pk_mul_f32 v[132:133], v[14:15], v[156:157] op_sel_hi:[1,0]
	v_cvt_pk_bf16_f32 v130, v130, v131
	v_cvt_pk_bf16_f32 v131, v132, v133
	v_cvt_pk_bf16_f32 v132, v136, v137
	v_cvt_pk_bf16_f32 v133, v138, v139
	global_store_dwordx4 v[134:135], v[130:133], off offset:256
	v_pk_mul_f32 v[134:135], v[32:33], v[152:153] op_sel_hi:[1,0]
	v_pk_mul_f32 v[136:137], v[34:35], v[152:153] op_sel_hi:[1,0]
	v_mad_i64_i32 v[130:131], s[16:17], s5, v146, 0
	v_lshl_add_u64 v[130:131], v[130:131], 1, s[0:1]
	v_lshl_add_u64 v[130:131], v[130:131], 0, s[20:21]
	v_lshl_add_u64 v[132:133], v[130:131], 0, v[128:129]
	v_pk_mul_f32 v[128:129], v[36:37], v[152:153] op_sel_hi:[1,0]
	v_pk_mul_f32 v[130:131], v[38:39], v[152:153] op_sel_hi:[1,0]
	v_cvt_pk_bf16_f32 v128, v128, v129
	v_cvt_pk_bf16_f32 v129, v130, v131
	v_cvt_pk_bf16_f32 v130, v134, v135
	v_cvt_pk_bf16_f32 v131, v136, v137
	global_store_dwordx4 v[132:133], v[128:131], off
	v_pk_mul_f32 v[134:135], v[0:1], v[152:153] op_sel_hi:[1,0]
	v_pk_mul_f32 v[136:137], v[2:3], v[152:153] op_sel_hi:[1,0]
	v_pk_mul_f32 v[128:129], v[4:5], v[152:153] op_sel_hi:[1,0]
	v_pk_mul_f32 v[130:131], v[6:7], v[152:153] op_sel_hi:[1,0]
	v_cvt_pk_bf16_f32 v128, v128, v129
	v_cvt_pk_bf16_f32 v129, v130, v131
	v_cvt_pk_bf16_f32 v130, v134, v135
	v_cvt_pk_bf16_f32 v131, v136, v137
	global_store_dwordx4 v[132:133], v[128:131], off offset:256

.LBB0_1088:
	s_and_b64 vcc, exec, s[50:51]
	s_cbranch_vccz .LBB0_1085
	s_waitcnt lgkmcnt(0)
	v_lshl_add_u64 v[128:129], v[144:145], 2, s[90:91]
	global_load_dword v130, v[128:129], off
	s_lshl_b32 s0, s66, 3
	v_add_u32_e32 v131, s4, v174
	s_add_i32 s16, s81, s0
	s_movk_i32 s0, 0x3ff
	v_cmp_lt_i32_e32 vcc, s0, v131
	s_movk_i32 s0, 0x400
	v_cmp_gt_i32_e64 s[0:1], s0, v131
	s_ashr_i32 s67, s66, 31
	v_mov_b32_e32 v129, v193
	v_cndmask_b32_e64 v128, v238, v239, s[0:1]
	s_lshl_b64 s[20:21], s[66:67], 23
	v_lshl_add_u64 v[128:129], s[86:87], 0, v[128:129]
	v_lshlrev_b64 v[146:147], 12, v[144:145]
	v_and_b32_e32 v132, 0x3ff, v131
	v_lshlrev_b32_e32 v131, 8, v131
	s_ashr_i32 s17, s16, 31
	v_lshl_add_u64 v[142:143], v[128:129], 0, s[20:21]
	v_mov_b32_e32 v139, v193
	v_lshlrev_b32_e32 v138, 2, v132
	v_and_b32_e32 v131, 0x30000, v131
	s_lshl_b64 s[30:31], s[16:17], 18
	v_lshl_add_u64 v[128:129], v[142:143], 0, v[146:147]
	v_or_b32_e32 v150, s30, v131
	v_mov_b32_e32 v151, s31
	v_lshl_add_u64 v[140:141], v[128:129], 0, v[138:139]
	v_ashrrev_i32_e32 v173, 31, v172
	v_lshlrev_b32_sdwa v136, v240, v174 dst_sel:DWORD dst_unused:UNUSED_PAD src0_sel:DWORD src1_sel:BYTE_0
	s_waitcnt vmcnt(0) lgkmcnt(0)
	v_fmamk_f32 v130, v130, 0x3a800000, v215
	v_rsq_f32_e32 v148, v130
	s_nop 0
	v_pk_mul_f32 v[134:135], v[126:127], v[148:149] op_sel_hi:[1,0]
	v_pk_mul_f32 v[132:133], v[124:125], v[148:149] op_sel_hi:[1,0]
	v_pk_mul_f32 v[130:131], v[122:123], v[148:149] op_sel_hi:[1,0]
	v_pk_mul_f32 v[128:129], v[120:121], v[148:149] op_sel_hi:[1,0]
	global_store_dwordx4 v[140:141], v[132:135], off
	global_store_dwordx4 v[140:141], v[128:131], off offset:16
	v_lshl_add_u64 v[140:141], v[150:151], 1, s[96:97]
	s_and_saveexec_b64 s[0:1], vcc
	s_xor_b64 s[0:1], exec, s[0:1]
	s_cbranch_execz .LBB0_1091
	v_mov_b32_e32 v137, v193
	v_lshl_add_u64 v[144:145], v[140:141], 0, v[136:137]
	v_lshl_add_u64 v[144:145], v[172:173], 1, v[144:145]
	v_cvt_pk_bf16_f32 v128, v128, s0
	global_store_short v[144:145], v128, off offset:2048
	v_cvt_pk_bf16_f32 v128, v133, s0
	global_store_short v[144:145], v128, off offset:512
	v_cvt_pk_bf16_f32 v128, v129, s0
	global_store_short v[144:145], v128, off offset:2560
	v_cvt_pk_bf16_f32 v128, v134, s0
	global_store_short v[144:145], v128, off offset:1024
	v_cvt_pk_bf16_f32 v128, v130, s0
	global_store_short v[144:145], v128, off offset:3072
	v_cvt_pk_bf16_f32 v128, v135, s0
	v_cvt_pk_bf16_f32 v132, v132, s0
	global_store_short v[144:145], v128, off offset:1536
	v_cvt_pk_bf16_f32 v128, v131, s0
	global_store_short v[144:145], v132, off
	global_store_short v[144:145], v128, off offset:3584
.LBB0_1091:
	s_or_saveexec_b64 s[0:1], s[0:1]
	v_lshlrev_b64 v[160:161], 9, v[172:173]
	v_lshlrev_b32_sdwa v144, v216, v174 dst_sel:DWORD dst_unused:UNUSED_PAD src0_sel:DWORD src1_sel:BYTE_0
	v_lshl_add_u64 v[150:151], v[150:151], 1, s[12:13]
	s_xor_b64 exec, exec, s[0:1]
	s_cbranch_execz .LBB0_1093
	v_cvt_pk_bf16_f32 v132, v132, v133
	v_cvt_pk_bf16_f32 v133, v134, v135
	v_cvt_pk_bf16_f32 v134, v128, v129
	v_lshl_add_u64 v[128:129], v[150:151], 0, v[160:161]
	v_mov_b32_e32 v145, v193
	v_cvt_pk_bf16_f32 v135, v130, v131
	v_lshl_add_u64 v[128:129], v[128:129], 0, v[144:145]
	global_store_dwordx4 v[128:129], v[132:135], off
.LBB0_1093:
	s_or_b64 exec, exec, s[0:1]
	v_add_u32_e32 v137, 0x80, v174
	v_add_u32_e32 v139, s4, v137
	s_movk_i32 s4, 0x400
	v_mov_b32_e32 v149, v148
	v_mov_b32_e32 v132, v148
	v_mov_b32_e32 v133, v148
	v_cmp_gt_i32_e64 s[4:5], s4, v139
	v_pk_mul_f32 v[130:131], v[94:95], v[132:133]
	v_pk_mul_f32 v[128:129], v[92:93], v[148:149]
	v_pk_mul_f32 v[134:135], v[90:91], v[132:133]
	v_pk_mul_f32 v[132:133], v[88:89], v[148:149]
	v_cndmask_b32_e64 v148, v238, v239, s[4:5]
	v_mov_b32_e32 v149, v193
	s_movk_i32 s0, 0x3ff
	v_lshl_add_u64 v[148:149], s[86:87], 0, v[148:149]
	v_cmp_lt_i32_e64 s[0:1], s0, v139
	v_lshl_add_u64 v[152:153], v[148:149], 0, s[20:21]
	v_and_b32_e32 v145, 0x3ff, v139
	v_lshlrev_b32_e32 v139, 8, v139
	v_lshl_add_u64 v[146:147], v[152:153], 0, v[146:147]
	v_lshlrev_b32_e32 v154, 2, v145
	v_mov_b32_e32 v155, v193
	v_and_b32_e32 v139, 0x30000, v139
	v_lshl_add_u64 v[146:147], v[146:147], 0, v[154:155]
	v_or_b32_e32 v158, s30, v139
	v_mov_b32_e32 v159, s31
	global_store_dwordx4 v[146:147], v[128:131], off
	global_store_dwordx4 v[146:147], v[132:135], off offset:16
	v_lshlrev_b32_sdwa v146, v240, v137 dst_sel:DWORD dst_unused:UNUSED_PAD src0_sel:DWORD src1_sel:BYTE_0
	v_lshl_add_u64 v[148:149], v[158:159], 1, s[96:97]
	s_and_saveexec_b64 s[4:5], s[0:1]
	s_xor_b64 s[4:5], exec, s[4:5]
	s_cbranch_execz .LBB0_1095
	v_mov_b32_e32 v147, v193
	v_lshl_add_u64 v[156:157], v[148:149], 0, v[146:147]
	v_lshl_add_u64 v[156:157], v[172:173], 1, v[156:157]
	v_cvt_pk_bf16_f32 v128, v128, s0
	global_store_short v[156:157], v128, off
	v_cvt_pk_bf16_f32 v128, v132, s0
	global_store_short v[156:157], v128, off offset:2048
	v_cvt_pk_bf16_f32 v128, v129, s0
	global_store_short v[156:157], v128, off offset:512
	v_cvt_pk_bf16_f32 v128, v133, s0
	global_store_short v[156:157], v128, off offset:2560
	v_cvt_pk_bf16_f32 v128, v130, s0
	global_store_short v[156:157], v128, off offset:1024
	v_cvt_pk_bf16_f32 v128, v134, s0
	global_store_short v[156:157], v128, off offset:3072
	v_cvt_pk_bf16_f32 v128, v131, s0
	global_store_short v[156:157], v128, off offset:1536
	v_cvt_pk_bf16_f32 v128, v135, s0
	global_store_short v[156:157], v128, off offset:3584
.LBB0_1095:
	s_or_saveexec_b64 s[4:5], s[4:5]
	v_lshlrev_b32_sdwa v156, v216, v137 dst_sel:DWORD dst_unused:UNUSED_PAD src0_sel:DWORD src1_sel:BYTE_0
	v_lshl_add_u64 v[158:159], v[158:159], 1, s[12:13]
	s_xor_b64 exec, exec, s[4:5]
	s_cbranch_execz .LBB0_1097
	v_cvt_pk_bf16_f32 v128, v128, v129
	v_cvt_pk_bf16_f32 v129, v130, v131
	v_cvt_pk_bf16_f32 v130, v132, v133
	v_lshl_add_u64 v[132:133], v[158:159], 0, v[160:161]
	v_mov_b32_e32 v157, v193
	v_cvt_pk_bf16_f32 v131, v134, v135
	v_lshl_add_u64 v[132:133], v[132:133], 0, v[156:157]
	global_store_dwordx4 v[132:133], v[128:131], off
.LBB0_1097:
	s_or_b64 exec, exec, s[4:5]
	v_add_u32_e32 v164, 16, v172
	v_add_u32_e32 v128, s63, v164
	v_ashrrev_i32_e32 v129, 31, v128
	v_lshl_add_u64 v[130:131], v[128:129], 2, s[90:91]
	global_load_dword v130, v[130:131], off
	v_lshlrev_b64 v[160:161], 12, v[128:129]
	v_mov_b32_e32 v139, v193
	v_lshl_add_u64 v[128:129], v[142:143], 0, v[160:161]
	v_lshl_add_u64 v[166:167], v[128:129], 0, v[138:139]
	s_waitcnt vmcnt(0) lgkmcnt(0)
	v_fmamk_f32 v130, v130, 0x3a800000, v215
	v_rsq_f32_e32 v162, v130
	s_nop 0
	v_pk_mul_f32 v[134:135], v[118:119], v[162:163] op_sel_hi:[1,0]
	v_pk_mul_f32 v[132:133], v[116:117], v[162:163] op_sel_hi:[1,0]
	v_pk_mul_f32 v[130:131], v[114:115], v[162:163] op_sel_hi:[1,0]
	v_pk_mul_f32 v[128:129], v[112:113], v[162:163] op_sel_hi:[1,0]
	global_store_dwordx4 v[166:167], v[132:135], off
	global_store_dwordx4 v[166:167], v[128:131], off offset:16
	s_and_saveexec_b64 s[4:5], vcc
	s_xor_b64 s[4:5], exec, s[4:5]
	s_cbranch_execz .LBB0_1099
	v_mov_b32_e32 v137, v193
	v_lshl_add_u64 v[166:167], v[140:141], 0, v[136:137]
	v_lshl_add_u64 v[166:167], v[172:173], 1, v[166:167]
	v_cvt_pk_bf16_f32 v128, v128, s0
	global_store_short v[166:167], v128, off offset:2080
	v_cvt_pk_bf16_f32 v128, v133, s0
	global_store_short v[166:167], v128, off offset:544
	v_cvt_pk_bf16_f32 v128, v129, s0
	global_store_short v[166:167], v128, off offset:2592
	v_cvt_pk_bf16_f32 v128, v134, s0
	global_store_short v[166:167], v128, off offset:1056
	v_cvt_pk_bf16_f32 v128, v130, s0
	global_store_short v[166:167], v128, off offset:3104
	v_cvt_pk_bf16_f32 v128, v135, s0
	v_cvt_pk_bf16_f32 v132, v132, s0
	global_store_short v[166:167], v128, off offset:1568
	v_cvt_pk_bf16_f32 v128, v131, s0
	global_store_short v[166:167], v132, off offset:32
	global_store_short v[166:167], v128, off offset:3616
.LBB0_1099:
	s_or_saveexec_b64 s[4:5], s[4:5]
	v_ashrrev_i32_e32 v165, 31, v164
	v_lshlrev_b64 v[164:165], 9, v[164:165]
	s_xor_b64 exec, exec, s[4:5]
	s_cbranch_execz .LBB0_1101
	v_cvt_pk_bf16_f32 v132, v132, v133
	v_cvt_pk_bf16_f32 v133, v134, v135
	v_cvt_pk_bf16_f32 v134, v128, v129
	v_lshl_add_u64 v[128:129], v[150:151], 0, v[164:165]
	v_mov_b32_e32 v145, v193
	v_cvt_pk_bf16_f32 v135, v130, v131
	v_lshl_add_u64 v[128:129], v[128:129], 0, v[144:145]
	global_store_dwordx4 v[128:129], v[132:135], off
.LBB0_1101:
	s_or_b64 exec, exec, s[4:5]
	v_mov_b32_e32 v163, v162
	v_mov_b32_e32 v132, v162
	v_mov_b32_e32 v133, v162
	v_lshl_add_u64 v[160:161], v[152:153], 0, v[160:161]
	v_mov_b32_e32 v155, v193
	v_pk_mul_f32 v[130:131], v[86:87], v[132:133]
	v_pk_mul_f32 v[128:129], v[84:85], v[162:163]
	v_pk_mul_f32 v[134:135], v[82:83], v[132:133]
	v_pk_mul_f32 v[132:133], v[80:81], v[162:163]
	v_lshl_add_u64 v[160:161], v[160:161], 0, v[154:155]
	global_store_dwordx4 v[160:161], v[128:131], off
	global_store_dwordx4 v[160:161], v[132:135], off offset:16
	s_and_saveexec_b64 s[4:5], s[0:1]
	s_xor_b64 s[4:5], exec, s[4:5]
	s_cbranch_execz .LBB0_1103
	v_mov_b32_e32 v147, v193
	v_lshl_add_u64 v[160:161], v[148:149], 0, v[146:147]
	v_lshl_add_u64 v[160:161], v[172:173], 1, v[160:161]
	v_cvt_pk_bf16_f32 v128, v128, s0
	global_store_short v[160:161], v128, off offset:32
	v_cvt_pk_bf16_f32 v128, v132, s0
	global_store_short v[160:161], v128, off offset:2080
	v_cvt_pk_bf16_f32 v128, v129, s0
	global_store_short v[160:161], v128, off offset:544
	v_cvt_pk_bf16_f32 v128, v133, s0
	global_store_short v[160:161], v128, off offset:2592
	v_cvt_pk_bf16_f32 v128, v130, s0
	global_store_short v[160:161], v128, off offset:1056
	v_cvt_pk_bf16_f32 v128, v134, s0
	global_store_short v[160:161], v128, off offset:3104
	v_cvt_pk_bf16_f32 v128, v131, s0
	global_store_short v[160:161], v128, off offset:1568
	v_cvt_pk_bf16_f32 v128, v135, s0
	global_store_short v[160:161], v128, off offset:3616
.LBB0_1103:
	s_andn2_saveexec_b64 s[4:5], s[4:5]
	s_cbranch_execz .LBB0_1105
	v_cvt_pk_bf16_f32 v128, v128, v129
	v_cvt_pk_bf16_f32 v129, v130, v131
	v_cvt_pk_bf16_f32 v130, v132, v133
	v_lshl_add_u64 v[132:133], v[158:159], 0, v[164:165]
	v_mov_b32_e32 v157, v193
	v_cvt_pk_bf16_f32 v131, v134, v135
	v_lshl_add_u64 v[132:133], v[132:133], 0, v[156:157]
	global_store_dwordx4 v[132:133], v[128:131], off
.LBB0_1105:
	s_or_b64 exec, exec, s[4:5]
	v_add_u32_e32 v164, 32, v172
	v_add_u32_e32 v128, s63, v164
	v_ashrrev_i32_e32 v129, 31, v128
	v_lshl_add_u64 v[130:131], v[128:129], 2, s[90:91]
	global_load_dword v130, v[130:131], off
	v_lshlrev_b64 v[160:161], 12, v[128:129]
	v_mov_b32_e32 v139, v193
	v_lshl_add_u64 v[128:129], v[142:143], 0, v[160:161]
	v_lshl_add_u64 v[166:167], v[128:129], 0, v[138:139]
	s_waitcnt vmcnt(0) lgkmcnt(0)
	v_fmamk_f32 v130, v130, 0x3a800000, v215
	v_rsq_f32_e32 v162, v130
	s_nop 0
	v_pk_mul_f32 v[134:135], v[110:111], v[162:163] op_sel_hi:[1,0]
	v_pk_mul_f32 v[132:133], v[108:109], v[162:163] op_sel_hi:[1,0]
	v_pk_mul_f32 v[130:131], v[106:107], v[162:163] op_sel_hi:[1,0]
	v_pk_mul_f32 v[128:129], v[104:105], v[162:163] op_sel_hi:[1,0]
	global_store_dwordx4 v[166:167], v[132:135], off
	global_store_dwordx4 v[166:167], v[128:131], off offset:16
	s_and_saveexec_b64 s[4:5], vcc
	s_xor_b64 s[4:5], exec, s[4:5]
	s_cbranch_execz .LBB0_1107
	v_mov_b32_e32 v137, v193
	v_lshl_add_u64 v[166:167], v[140:141], 0, v[136:137]
	v_lshl_add_u64 v[166:167], v[172:173], 1, v[166:167]
	v_cvt_pk_bf16_f32 v128, v128, s0
	global_store_short v[166:167], v128, off offset:2112
	v_cvt_pk_bf16_f32 v128, v133, s0
	global_store_short v[166:167], v128, off offset:576
	v_cvt_pk_bf16_f32 v128, v129, s0
	global_store_short v[166:167], v128, off offset:2624
	v_cvt_pk_bf16_f32 v128, v134, s0
	global_store_short v[166:167], v128, off offset:1088
	v_cvt_pk_bf16_f32 v128, v130, s0
	global_store_short v[166:167], v128, off offset:3136
	v_cvt_pk_bf16_f32 v128, v135, s0
	v_cvt_pk_bf16_f32 v132, v132, s0
	global_store_short v[166:167], v128, off offset:1600
	v_cvt_pk_bf16_f32 v128, v131, s0
	global_store_short v[166:167], v132, off offset:64
	global_store_short v[166:167], v128, off offset:3648

.LBB0_1109:
	s_or_b64 exec, exec, s[4:5]
	v_mov_b32_e32 v163, v162
	v_mov_b32_e32 v132, v162
	v_mov_b32_e32 v133, v162
	v_lshl_add_u64 v[160:161], v[152:153], 0, v[160:161]
	v_mov_b32_e32 v155, v193
	v_pk_mul_f32 v[130:131], v[78:79], v[132:133]
	v_pk_mul_f32 v[128:129], v[76:77], v[162:163]
	v_pk_mul_f32 v[134:135], v[74:75], v[132:133]
	v_pk_mul_f32 v[132:133], v[72:73], v[162:163]
	v_lshl_add_u64 v[160:161], v[160:161], 0, v[154:155]
	global_store_dwordx4 v[160:161], v[128:131], off
	global_store_dwordx4 v[160:161], v[132:135], off offset:16
	s_and_saveexec_b64 s[4:5], s[0:1]
	s_xor_b64 s[4:5], exec, s[4:5]
	s_cbranch_execz .LBB0_1111
	v_mov_b32_e32 v147, v193
	v_lshl_add_u64 v[160:161], v[148:149], 0, v[146:147]
	v_lshl_add_u64 v[160:161], v[172:173], 1, v[160:161]
	v_cvt_pk_bf16_f32 v128, v128, s0
	global_store_short v[160:161], v128, off offset:64
	v_cvt_pk_bf16_f32 v128, v132, s0
	global_store_short v[160:161], v128, off offset:2112
	v_cvt_pk_bf16_f32 v128, v129, s0
	global_store_short v[160:161], v128, off offset:576
	v_cvt_pk_bf16_f32 v128, v133, s0
	global_store_short v[160:161], v128, off offset:2624
	v_cvt_pk_bf16_f32 v128, v130, s0
	global_store_short v[160:161], v128, off offset:1088
	v_cvt_pk_bf16_f32 v128, v134, s0
	global_store_short v[160:161], v128, off offset:3136
	v_cvt_pk_bf16_f32 v128, v131, s0
	global_store_short v[160:161], v128, off offset:1600
	v_cvt_pk_bf16_f32 v128, v135, s0
	global_store_short v[160:161], v128, off offset:3648

.LBB0_1113:
	s_or_b64 exec, exec, s[4:5]
	v_add_u32_e32 v164, 48, v172
	v_add_u32_e32 v128, s63, v164
	v_ashrrev_i32_e32 v129, 31, v128
	v_lshl_add_u64 v[130:131], v[128:129], 2, s[90:91]
	global_load_dword v130, v[130:131], off
	v_lshlrev_b64 v[160:161], 12, v[128:129]
	v_mov_b32_e32 v139, v193
	v_lshl_add_u64 v[128:129], v[142:143], 0, v[160:161]
	v_lshl_add_u64 v[166:167], v[128:129], 0, v[138:139]
	s_waitcnt vmcnt(0) lgkmcnt(0)
	v_fmamk_f32 v130, v130, 0x3a800000, v215
	v_rsq_f32_e32 v162, v130
	s_nop 0
	v_pk_mul_f32 v[134:135], v[102:103], v[162:163] op_sel_hi:[1,0]
	v_pk_mul_f32 v[132:133], v[100:101], v[162:163] op_sel_hi:[1,0]
	v_pk_mul_f32 v[130:131], v[98:99], v[162:163] op_sel_hi:[1,0]
	v_pk_mul_f32 v[128:129], v[96:97], v[162:163] op_sel_hi:[1,0]
	global_store_dwordx4 v[166:167], v[132:135], off
	global_store_dwordx4 v[166:167], v[128:131], off offset:16
	s_and_saveexec_b64 s[4:5], vcc
	s_xor_b64 s[4:5], exec, s[4:5]
	s_cbranch_execz .LBB0_1115
	v_mov_b32_e32 v137, v193
	v_lshl_add_u64 v[166:167], v[140:141], 0, v[136:137]
	v_lshl_add_u64 v[166:167], v[172:173], 1, v[166:167]
	v_cvt_pk_bf16_f32 v128, v128, s0
	global_store_short v[166:167], v128, off offset:2144
	v_cvt_pk_bf16_f32 v128, v133, s0
	global_store_short v[166:167], v128, off offset:608
	v_cvt_pk_bf16_f32 v128, v129, s0
	global_store_short v[166:167], v128, off offset:2656
	v_cvt_pk_bf16_f32 v128, v134, s0
	global_store_short v[166:167], v128, off offset:1120
	v_cvt_pk_bf16_f32 v128, v130, s0
	global_store_short v[166:167], v128, off offset:3168
	v_cvt_pk_bf16_f32 v128, v135, s0
	v_cvt_pk_bf16_f32 v132, v132, s0
	global_store_short v[166:167], v128, off offset:1632
	v_cvt_pk_bf16_f32 v128, v131, s0
	global_store_short v[166:167], v132, off offset:96
	global_store_short v[166:167], v128, off offset:3680

.LBB0_1117:
	s_or_b64 exec, exec, s[4:5]
	v_mov_b32_e32 v163, v162
	v_mov_b32_e32 v132, v162
	v_mov_b32_e32 v133, v162
	v_lshl_add_u64 v[160:161], v[152:153], 0, v[160:161]
	v_mov_b32_e32 v155, v193
	v_pk_mul_f32 v[130:131], v[70:71], v[132:133]
	v_pk_mul_f32 v[128:129], v[68:69], v[162:163]
	v_pk_mul_f32 v[134:135], v[66:67], v[132:133]
	v_pk_mul_f32 v[132:133], v[64:65], v[162:163]
	v_lshl_add_u64 v[160:161], v[160:161], 0, v[154:155]
	global_store_dwordx4 v[160:161], v[128:131], off
	global_store_dwordx4 v[160:161], v[132:135], off offset:16
	s_and_saveexec_b64 s[4:5], s[0:1]
	s_xor_b64 s[4:5], exec, s[4:5]
	s_cbranch_execz .LBB0_1119
	v_mov_b32_e32 v147, v193
	v_lshl_add_u64 v[160:161], v[148:149], 0, v[146:147]
	v_lshl_add_u64 v[160:161], v[172:173], 1, v[160:161]
	v_cvt_pk_bf16_f32 v128, v128, s0
	global_store_short v[160:161], v128, off offset:96
	v_cvt_pk_bf16_f32 v128, v132, s0
	global_store_short v[160:161], v128, off offset:2144
	v_cvt_pk_bf16_f32 v128, v129, s0
	global_store_short v[160:161], v128, off offset:608
	v_cvt_pk_bf16_f32 v128, v133, s0
	global_store_short v[160:161], v128, off offset:2656
	v_cvt_pk_bf16_f32 v128, v130, s0
	global_store_short v[160:161], v128, off offset:1120
	v_cvt_pk_bf16_f32 v128, v134, s0
	global_store_short v[160:161], v128, off offset:3168
	v_cvt_pk_bf16_f32 v128, v131, s0
	global_store_short v[160:161], v128, off offset:1632
	v_cvt_pk_bf16_f32 v128, v135, s0
	global_store_short v[160:161], v128, off offset:3680

.LBB0_1121:
	s_or_b64 exec, exec, s[4:5]
	v_add_u32_e32 v164, 0x80, v172
	v_add_u32_e32 v128, s63, v164
	v_ashrrev_i32_e32 v129, 31, v128
	v_lshl_add_u64 v[130:131], v[128:129], 2, s[90:91]
	global_load_dword v130, v[130:131], off
	v_lshlrev_b64 v[160:161], 12, v[128:129]
	v_mov_b32_e32 v139, v193
	v_lshl_add_u64 v[128:129], v[142:143], 0, v[160:161]
	v_lshl_add_u64 v[166:167], v[128:129], 0, v[138:139]
	s_waitcnt vmcnt(0) lgkmcnt(0)
	v_fmamk_f32 v130, v130, 0x3a800000, v215
	v_rsq_f32_e32 v162, v130
	s_nop 0
	v_pk_mul_f32 v[134:135], v[62:63], v[162:163] op_sel_hi:[1,0]
	v_pk_mul_f32 v[132:133], v[60:61], v[162:163] op_sel_hi:[1,0]
	v_pk_mul_f32 v[130:131], v[58:59], v[162:163] op_sel_hi:[1,0]
	v_pk_mul_f32 v[128:129], v[56:57], v[162:163] op_sel_hi:[1,0]
	global_store_dwordx4 v[166:167], v[132:135], off
	global_store_dwordx4 v[166:167], v[128:131], off offset:16
	s_and_saveexec_b64 s[4:5], vcc
	s_xor_b64 s[4:5], exec, s[4:5]
	s_cbranch_execz .LBB0_1123
	v_mov_b32_e32 v137, v193
	v_lshl_add_u64 v[166:167], v[140:141], 0, v[136:137]
	v_lshl_add_u64 v[166:167], v[172:173], 1, v[166:167]
	v_cvt_pk_bf16_f32 v128, v128, s0
	global_store_short v[166:167], v128, off offset:2304
	v_cvt_pk_bf16_f32 v128, v133, s0
	global_store_short v[166:167], v128, off offset:768
	v_cvt_pk_bf16_f32 v128, v129, s0
	global_store_short v[166:167], v128, off offset:2816
	v_cvt_pk_bf16_f32 v128, v134, s0
	global_store_short v[166:167], v128, off offset:1280
	v_cvt_pk_bf16_f32 v128, v130, s0
	global_store_short v[166:167], v128, off offset:3328
	v_cvt_pk_bf16_f32 v128, v135, s0
	v_cvt_pk_bf16_f32 v132, v132, s0
	global_store_short v[166:167], v128, off offset:1792
	v_cvt_pk_bf16_f32 v128, v131, s0
	global_store_short v[166:167], v132, off offset:256
	global_store_short v[166:167], v128, off offset:3840

.LBB0_1125:
	s_or_b64 exec, exec, s[4:5]
	v_mov_b32_e32 v163, v162
	v_mov_b32_e32 v132, v162
	v_mov_b32_e32 v133, v162
	v_lshl_add_u64 v[160:161], v[152:153], 0, v[160:161]
	v_mov_b32_e32 v155, v193
	v_pk_mul_f32 v[130:131], v[30:31], v[132:133]
	v_pk_mul_f32 v[128:129], v[28:29], v[162:163]
	v_pk_mul_f32 v[134:135], v[26:27], v[132:133]
	v_pk_mul_f32 v[132:133], v[24:25], v[162:163]
	v_lshl_add_u64 v[160:161], v[160:161], 0, v[154:155]
	global_store_dwordx4 v[160:161], v[128:131], off
	global_store_dwordx4 v[160:161], v[132:135], off offset:16
	s_and_saveexec_b64 s[4:5], s[0:1]
	s_xor_b64 s[4:5], exec, s[4:5]
	s_cbranch_execz .LBB0_1127
	v_mov_b32_e32 v147, v193
	v_lshl_add_u64 v[160:161], v[148:149], 0, v[146:147]
	v_lshl_add_u64 v[160:161], v[172:173], 1, v[160:161]
	v_cvt_pk_bf16_f32 v128, v128, s0
	global_store_short v[160:161], v128, off offset:256
	v_cvt_pk_bf16_f32 v128, v132, s0
	global_store_short v[160:161], v128, off offset:2304
	v_cvt_pk_bf16_f32 v128, v129, s0
	global_store_short v[160:161], v128, off offset:768
	v_cvt_pk_bf16_f32 v128, v133, s0
	global_store_short v[160:161], v128, off offset:2816
	v_cvt_pk_bf16_f32 v128, v130, s0
	global_store_short v[160:161], v128, off offset:1280
	v_cvt_pk_bf16_f32 v128, v134, s0
	global_store_short v[160:161], v128, off offset:3328
	v_cvt_pk_bf16_f32 v128, v131, s0
	global_store_short v[160:161], v128, off offset:1792
	v_cvt_pk_bf16_f32 v128, v135, s0
	global_store_short v[160:161], v128, off offset:3840

.LBB0_1129:
	s_or_b64 exec, exec, s[4:5]
	v_add_u32_e32 v164, 0x90, v172
	v_add_u32_e32 v128, s63, v164
	v_ashrrev_i32_e32 v129, 31, v128
	v_lshl_add_u64 v[130:131], v[128:129], 2, s[90:91]
	global_load_dword v130, v[130:131], off
	v_lshlrev_b64 v[160:161], 12, v[128:129]
	v_mov_b32_e32 v139, v193
	v_lshl_add_u64 v[128:129], v[142:143], 0, v[160:161]
	v_lshl_add_u64 v[166:167], v[128:129], 0, v[138:139]
	s_waitcnt vmcnt(0) lgkmcnt(0)
	v_fmamk_f32 v130, v130, 0x3a800000, v215
	v_rsq_f32_e32 v162, v130
	s_nop 0
	v_pk_mul_f32 v[134:135], v[54:55], v[162:163] op_sel_hi:[1,0]
	v_pk_mul_f32 v[132:133], v[52:53], v[162:163] op_sel_hi:[1,0]
	v_pk_mul_f32 v[130:131], v[50:51], v[162:163] op_sel_hi:[1,0]
	v_pk_mul_f32 v[128:129], v[48:49], v[162:163] op_sel_hi:[1,0]
	global_store_dwordx4 v[166:167], v[132:135], off
	global_store_dwordx4 v[166:167], v[128:131], off offset:16
	s_and_saveexec_b64 s[4:5], vcc
	s_xor_b64 s[4:5], exec, s[4:5]
	s_cbranch_execz .LBB0_1131
	v_mov_b32_e32 v137, v193
	v_lshl_add_u64 v[166:167], v[140:141], 0, v[136:137]
	v_lshl_add_u64 v[166:167], v[172:173], 1, v[166:167]
	v_cvt_pk_bf16_f32 v128, v128, s0
	global_store_short v[166:167], v128, off offset:2336
	v_cvt_pk_bf16_f32 v128, v133, s0
	global_store_short v[166:167], v128, off offset:800
	v_cvt_pk_bf16_f32 v128, v129, s0
	global_store_short v[166:167], v128, off offset:2848
	v_cvt_pk_bf16_f32 v128, v134, s0
	global_store_short v[166:167], v128, off offset:1312
	v_cvt_pk_bf16_f32 v128, v130, s0
	global_store_short v[166:167], v128, off offset:3360
	v_cvt_pk_bf16_f32 v128, v135, s0
	v_cvt_pk_bf16_f32 v132, v132, s0
	global_store_short v[166:167], v128, off offset:1824
	v_cvt_pk_bf16_f32 v128, v131, s0
	global_store_short v[166:167], v132, off offset:288
	global_store_short v[166:167], v128, off offset:3872

.LBB0_1133:
	s_or_b64 exec, exec, s[4:5]
	v_mov_b32_e32 v163, v162
	v_mov_b32_e32 v132, v162
	v_mov_b32_e32 v133, v162
	v_lshl_add_u64 v[160:161], v[152:153], 0, v[160:161]
	v_mov_b32_e32 v155, v193
	v_pk_mul_f32 v[130:131], v[22:23], v[132:133]
	v_pk_mul_f32 v[128:129], v[20:21], v[162:163]
	v_pk_mul_f32 v[134:135], v[18:19], v[132:133]
	v_pk_mul_f32 v[132:133], v[16:17], v[162:163]
	v_lshl_add_u64 v[160:161], v[160:161], 0, v[154:155]
	global_store_dwordx4 v[160:161], v[128:131], off
	global_store_dwordx4 v[160:161], v[132:135], off offset:16
	s_and_saveexec_b64 s[4:5], s[0:1]
	s_xor_b64 s[4:5], exec, s[4:5]
	s_cbranch_execz .LBB0_1135
	v_mov_b32_e32 v147, v193
	v_lshl_add_u64 v[160:161], v[148:149], 0, v[146:147]
	v_lshl_add_u64 v[160:161], v[172:173], 1, v[160:161]
	v_cvt_pk_bf16_f32 v128, v128, s0
	global_store_short v[160:161], v128, off offset:288
	v_cvt_pk_bf16_f32 v128, v132, s0
	global_store_short v[160:161], v128, off offset:2336
	v_cvt_pk_bf16_f32 v128, v129, s0
	global_store_short v[160:161], v128, off offset:800
	v_cvt_pk_bf16_f32 v128, v133, s0
	global_store_short v[160:161], v128, off offset:2848
	v_cvt_pk_bf16_f32 v128, v130, s0
	global_store_short v[160:161], v128, off offset:1312
	v_cvt_pk_bf16_f32 v128, v134, s0
	global_store_short v[160:161], v128, off offset:3360
	v_cvt_pk_bf16_f32 v128, v131, s0
	global_store_short v[160:161], v128, off offset:1824
	v_cvt_pk_bf16_f32 v128, v135, s0
	global_store_short v[160:161], v128, off offset:3872

.LBB0_1137:
	s_or_b64 exec, exec, s[4:5]
	v_add_u32_e32 v164, 0xa0, v172
	v_add_u32_e32 v128, s63, v164
	v_ashrrev_i32_e32 v129, 31, v128
	v_lshl_add_u64 v[130:131], v[128:129], 2, s[90:91]
	global_load_dword v130, v[130:131], off
	v_lshlrev_b64 v[160:161], 12, v[128:129]
	v_mov_b32_e32 v139, v193
	v_lshl_add_u64 v[128:129], v[142:143], 0, v[160:161]
	v_lshl_add_u64 v[166:167], v[128:129], 0, v[138:139]
	s_waitcnt vmcnt(0) lgkmcnt(0)
	v_fmamk_f32 v130, v130, 0x3a800000, v215
	v_rsq_f32_e32 v162, v130
	s_nop 0
	v_pk_mul_f32 v[134:135], v[46:47], v[162:163] op_sel_hi:[1,0]
	v_pk_mul_f32 v[132:133], v[44:45], v[162:163] op_sel_hi:[1,0]
	v_pk_mul_f32 v[130:131], v[42:43], v[162:163] op_sel_hi:[1,0]
	v_pk_mul_f32 v[128:129], v[40:41], v[162:163] op_sel_hi:[1,0]
	global_store_dwordx4 v[166:167], v[132:135], off
	global_store_dwordx4 v[166:167], v[128:131], off offset:16
	s_and_saveexec_b64 s[4:5], vcc
	s_xor_b64 s[4:5], exec, s[4:5]
	s_cbranch_execz .LBB0_1139
	v_mov_b32_e32 v137, v193
	v_lshl_add_u64 v[166:167], v[140:141], 0, v[136:137]
	v_lshl_add_u64 v[166:167], v[172:173], 1, v[166:167]
	v_cvt_pk_bf16_f32 v128, v128, s0
	global_store_short v[166:167], v128, off offset:2368
	v_cvt_pk_bf16_f32 v128, v133, s0
	global_store_short v[166:167], v128, off offset:832
	v_cvt_pk_bf16_f32 v128, v129, s0
	global_store_short v[166:167], v128, off offset:2880
	v_cvt_pk_bf16_f32 v128, v134, s0
	global_store_short v[166:167], v128, off offset:1344
	v_cvt_pk_bf16_f32 v128, v130, s0
	global_store_short v[166:167], v128, off offset:3392
	v_cvt_pk_bf16_f32 v128, v135, s0
	v_cvt_pk_bf16_f32 v132, v132, s0
	global_store_short v[166:167], v128, off offset:1856
	v_cvt_pk_bf16_f32 v128, v131, s0
	global_store_short v[166:167], v132, off offset:320
	global_store_short v[166:167], v128, off offset:3904

.LBB0_1141:
	s_or_b64 exec, exec, s[4:5]
	v_mov_b32_e32 v163, v162
	v_mov_b32_e32 v132, v162
	v_mov_b32_e32 v133, v162
	v_lshl_add_u64 v[160:161], v[152:153], 0, v[160:161]
	v_mov_b32_e32 v155, v193
	v_pk_mul_f32 v[130:131], v[14:15], v[132:133]
	v_pk_mul_f32 v[128:129], v[12:13], v[162:163]
	v_pk_mul_f32 v[134:135], v[10:11], v[132:133]
	v_pk_mul_f32 v[132:133], v[8:9], v[162:163]
	v_lshl_add_u64 v[160:161], v[160:161], 0, v[154:155]
	global_store_dwordx4 v[160:161], v[128:131], off
	global_store_dwordx4 v[160:161], v[132:135], off offset:16
	s_and_saveexec_b64 s[4:5], s[0:1]
	s_xor_b64 s[4:5], exec, s[4:5]
	s_cbranch_execz .LBB0_1143
	v_mov_b32_e32 v147, v193
	v_lshl_add_u64 v[160:161], v[148:149], 0, v[146:147]
	v_lshl_add_u64 v[160:161], v[172:173], 1, v[160:161]
	v_cvt_pk_bf16_f32 v128, v128, s0
	global_store_short v[160:161], v128, off offset:320
	v_cvt_pk_bf16_f32 v128, v132, s0
	global_store_short v[160:161], v128, off offset:2368
	v_cvt_pk_bf16_f32 v128, v129, s0
	global_store_short v[160:161], v128, off offset:832
	v_cvt_pk_bf16_f32 v128, v133, s0
	global_store_short v[160:161], v128, off offset:2880
	v_cvt_pk_bf16_f32 v128, v130, s0
	global_store_short v[160:161], v128, off offset:1344
	v_cvt_pk_bf16_f32 v128, v134, s0
	global_store_short v[160:161], v128, off offset:3392
	v_cvt_pk_bf16_f32 v128, v131, s0
	global_store_short v[160:161], v128, off offset:1856
	v_cvt_pk_bf16_f32 v128, v135, s0
	global_store_short v[160:161], v128, off offset:3904

.LBB0_1145:
	s_or_b64 exec, exec, s[4:5]
	v_add_u32_e32 v164, 0xb0, v172
	v_add_u32_e32 v128, s63, v164
	v_ashrrev_i32_e32 v129, 31, v128
	v_lshl_add_u64 v[130:131], v[128:129], 2, s[90:91]
	global_load_dword v130, v[130:131], off
	v_lshlrev_b64 v[160:161], 12, v[128:129]
	v_mov_b32_e32 v139, v193
	v_lshl_add_u64 v[128:129], v[142:143], 0, v[160:161]
	v_lshl_add_u64 v[138:139], v[128:129], 0, v[138:139]
	s_waitcnt vmcnt(0) lgkmcnt(0)
	v_fmamk_f32 v130, v130, 0x3a800000, v215
	v_rsq_f32_e32 v162, v130
	s_nop 0
	v_pk_mul_f32 v[134:135], v[38:39], v[162:163] op_sel_hi:[1,0]
	v_pk_mul_f32 v[132:133], v[36:37], v[162:163] op_sel_hi:[1,0]
	v_pk_mul_f32 v[130:131], v[34:35], v[162:163] op_sel_hi:[1,0]
	v_pk_mul_f32 v[128:129], v[32:33], v[162:163] op_sel_hi:[1,0]
	global_store_dwordx4 v[138:139], v[132:135], off
	global_store_dwordx4 v[138:139], v[128:131], off offset:16
	s_and_saveexec_b64 s[4:5], vcc
	s_xor_b64 s[4:5], exec, s[4:5]
	s_cbranch_execz .LBB0_1147
	v_mov_b32_e32 v137, v193
	v_lshl_add_u64 v[136:137], v[140:141], 0, v[136:137]
	v_lshl_add_u64 v[136:137], v[172:173], 1, v[136:137]
	v_cvt_pk_bf16_f32 v128, v128, s0
	global_store_short v[136:137], v128, off offset:2400
	v_cvt_pk_bf16_f32 v128, v133, s0
	global_store_short v[136:137], v128, off offset:864
	v_cvt_pk_bf16_f32 v128, v129, s0
	global_store_short v[136:137], v128, off offset:2912
	v_cvt_pk_bf16_f32 v128, v134, s0
	global_store_short v[136:137], v128, off offset:1376
	v_cvt_pk_bf16_f32 v128, v130, s0
	global_store_short v[136:137], v128, off offset:3424
	v_cvt_pk_bf16_f32 v128, v135, s0
	v_cvt_pk_bf16_f32 v132, v132, s0
	global_store_short v[136:137], v128, off offset:1888
	v_cvt_pk_bf16_f32 v128, v131, s0
	global_store_short v[136:137], v132, off offset:352
	global_store_short v[136:137], v128, off offset:3936
.LBB0_1147:
	s_or_saveexec_b64 s[4:5], s[4:5]
	v_ashrrev_i32_e32 v165, 31, v164
	v_lshlrev_b64 v[136:137], 9, v[164:165]
	s_xor_b64 exec, exec, s[4:5]
	s_cbranch_execz .LBB0_1149
	v_cvt_pk_bf16_f32 v132, v132, v133
	v_cvt_pk_bf16_f32 v133, v134, v135
	v_cvt_pk_bf16_f32 v134, v128, v129
	v_lshl_add_u64 v[128:129], v[150:151], 0, v[136:137]
	v_mov_b32_e32 v145, v193
	v_cvt_pk_bf16_f32 v135, v130, v131
	v_lshl_add_u64 v[128:129], v[128:129], 0, v[144:145]
	global_store_dwordx4 v[128:129], v[132:135], off
.LBB0_1149:
	s_or_b64 exec, exec, s[4:5]
	v_mov_b32_e32 v163, v162
	v_mov_b32_e32 v132, v162
	v_mov_b32_e32 v133, v162
	v_lshl_add_u64 v[138:139], v[152:153], 0, v[160:161]
	v_mov_b32_e32 v155, v193
	v_pk_mul_f32 v[130:131], v[6:7], v[132:133]
	v_pk_mul_f32 v[128:129], v[4:5], v[162:163]
	v_pk_mul_f32 v[134:135], v[2:3], v[132:133]
	v_pk_mul_f32 v[132:133], v[0:1], v[162:163]
	v_lshl_add_u64 v[138:139], v[138:139], 0, v[154:155]
	global_store_dwordx4 v[138:139], v[128:131], off
	global_store_dwordx4 v[138:139], v[132:135], off offset:16
	s_and_saveexec_b64 s[4:5], s[0:1]
	s_xor_b64 s[0:1], exec, s[4:5]
	s_cbranch_execz .LBB0_1151
	v_mov_b32_e32 v147, v193
	v_lshl_add_u64 v[136:137], v[148:149], 0, v[146:147]
	v_lshl_add_u64 v[136:137], v[172:173], 1, v[136:137]
	v_cvt_pk_bf16_f32 v128, v128, s0
	global_store_short v[136:137], v128, off offset:352
	v_cvt_pk_bf16_f32 v128, v132, s0
	global_store_short v[136:137], v128, off offset:2400
	v_cvt_pk_bf16_f32 v128, v129, s0
	global_store_short v[136:137], v128, off offset:864
	v_cvt_pk_bf16_f32 v128, v133, s0
	global_store_short v[136:137], v128, off offset:2912
	v_cvt_pk_bf16_f32 v128, v130, s0
	global_store_short v[136:137], v128, off offset:1376
	v_cvt_pk_bf16_f32 v128, v134, s0
	global_store_short v[136:137], v128, off offset:3424
	v_cvt_pk_bf16_f32 v128, v131, s0
	global_store_short v[136:137], v128, off offset:1888
	v_cvt_pk_bf16_f32 v128, v135, s0
	global_store_short v[136:137], v128, off offset:3936
.LBB0_1151:
	s_andn2_saveexec_b64 s[0:1], s[0:1]
	s_cbranch_execz .LBB0_1153
	v_cvt_pk_bf16_f32 v128, v128, v129
	v_cvt_pk_bf16_f32 v129, v130, v131
	v_cvt_pk_bf16_f32 v130, v132, v133
	v_lshl_add_u64 v[132:133], v[158:159], 0, v[136:137]
	v_mov_b32_e32 v157, v193
	v_cvt_pk_bf16_f32 v131, v134, v135
	v_lshl_add_u64 v[132:133], v[132:133], 0, v[156:157]
	global_store_dwordx4 v[132:133], v[128:131], off

.LBB0_1164:
	v_ashrrev_i32_e32 v175, 31, v174
	v_lshl_add_u64 v[128:129], v[174:175], 1, s[24:25]
	s_andn2_b64 vcc, exec, s[0:1]
	v_lshl_add_u64 v[178:179], s[4:5], 1, v[128:129]
	s_cbranch_vccnz .LBB0_1166
	v_lshlrev_b64 v[128:129], 11, v[180:181]
	v_lshl_add_u64 v[128:129], v[178:179], 0, v[128:129]
	global_load_dwordx4 v[156:159], v[128:129], off
	global_load_dwordx4 v[152:155], v[128:129], off offset:256
	v_add_u32_e32 v128, 16, v180
	v_ashrrev_i32_e32 v129, 31, v128
	v_lshlrev_b64 v[128:129], 11, v[128:129]
	v_lshl_add_u64 v[128:129], v[178:179], 0, v[128:129]
	global_load_dwordx4 v[148:151], v[128:129], off
	global_load_dwordx4 v[144:147], v[128:129], off offset:256
	v_add_u32_e32 v128, 32, v180
	v_ashrrev_i32_e32 v129, 31, v128
	v_lshlrev_b64 v[128:129], 11, v[128:129]
	v_lshl_add_u64 v[128:129], v[178:179], 0, v[128:129]
	global_load_dwordx4 v[140:143], v[128:129], off
	global_load_dwordx4 v[136:139], v[128:129], off offset:256
	v_add_u32_e32 v128, 48, v180
	v_ashrrev_i32_e32 v129, 31, v128
	v_lshlrev_b64 v[128:129], 11, v[128:129]
	v_lshl_add_u64 v[128:129], v[178:179], 0, v[128:129]
	global_load_dwordx4 v[132:135], v[128:129], off
	s_nop 0
	global_load_dwordx4 v[128:131], v[128:129], off offset:256
.LBB0_1166:
	v_lshlrev_b64 v[160:161], 10, v[180:181]
	v_lshl_add_u64 v[176:177], v[174:175], 0, s[4:5]
	v_lshl_add_u64 v[168:169], v[176:177], 0, v[160:161]
	v_cndmask_b32_e64 v160, 0, 1, s[20:21]
	v_cmp_ne_u32_e64 s[0:1], 1, v160
	s_andn2_b64 vcc, exec, s[20:21]
	v_lshl_add_u64 v[184:185], v[168:169], 2, s[64:65]
	s_cbranch_vccnz .LBB0_1242
	global_load_dwordx4 v[160:163], v[184:185], off
	global_load_dwordx4 v[164:167], v[184:185], off offset:16
	s_cbranch_execnz .LBB0_1169

.LBB0_1169:
	s_waitcnt vmcnt(0) lgkmcnt(0)
	v_pk_add_f32 v[162:163], v[126:127], v[162:163]
	v_pk_add_f32 v[160:161], v[124:125], v[160:161]
	v_pk_add_f32 v[166:167], v[122:123], v[166:167]
	v_pk_add_f32 v[164:165], v[120:121], v[164:165]
	v_lshl_add_u64 v[182:183], v[168:169], 1, s[24:25]
	v_cvt_pk_bf16_f32 v168, v160, v161
	v_cvt_pk_bf16_f32 v169, v162, v163
	v_cvt_pk_bf16_f32 v170, v164, v165
	v_cvt_pk_bf16_f32 v171, v166, v167
	s_and_b64 vcc, exec, s[0:1]
	global_store_dwordx4 v[182:183], v[168:171], off
	s_cbranch_vccnz .LBB0_1243
	global_load_dwordx4 v[160:163], v[184:185], off offset:512
	global_load_dwordx4 v[164:167], v[184:185], off offset:528
	s_cbranch_execnz .LBB0_1172

.LBB0_1172:
	v_lshlrev_b32_e32 v173, 16, v168
	v_and_b32_e32 v168, 0xffff0000, v168
	v_lshlrev_b32_e32 v175, 16, v169
	v_and_b32_e32 v169, 0xffff0000, v169
	v_mul_f32_e32 v168, v168, v168
	v_mul_f32_e32 v169, v169, v169
	v_lshlrev_b32_e32 v184, 16, v170
	v_and_b32_e32 v170, 0xffff0000, v170
	v_fmac_f32_e32 v168, v173, v173
	v_fmac_f32_e32 v169, v175, v175
	v_add_f32_e32 v168, v168, v169
	v_mul_f32_e32 v169, v170, v170
	v_lshlrev_b32_e32 v185, 16, v171
	v_and_b32_e32 v171, 0xffff0000, v171
	v_fmac_f32_e32 v169, v184, v184
	v_add_f32_e32 v168, v169, v168
	v_mul_f32_e32 v169, v171, v171
	v_fmac_f32_e32 v169, v185, v185
	v_cmp_lt_i32_e32 vcc, v223, v218
	v_add_f32_e32 v170, v169, v168
	s_waitcnt vmcnt(0) lgkmcnt(0)
	v_pk_add_f32 v[160:161], v[92:93], v[160:161]
	v_cndmask_b32_e32 v168, v217, v223, vcc
	v_lshlrev_b32_e32 v173, 2, v168
	v_pk_add_f32 v[168:169], v[94:95], v[162:163]
	v_cvt_pk_bf16_f32 v162, v160, v161
	v_pk_add_f32 v[166:167], v[90:91], v[166:167]
	v_pk_add_f32 v[164:165], v[88:89], v[164:165]
	v_cvt_pk_bf16_f32 v163, v168, v169
	v_and_b32_e32 v161, 0xffff0000, v162
	v_cvt_pk_bf16_f32 v164, v164, v165
	v_cvt_pk_bf16_f32 v165, v166, v167
	v_lshlrev_b32_e32 v160, 16, v162
	v_and_b32_e32 v167, 0xffff0000, v163
	v_mul_f32_e32 v161, v161, v161
	v_lshlrev_b32_e32 v166, 16, v163
	v_fmac_f32_e32 v161, v160, v160
	v_mul_f32_e32 v160, v167, v167
	v_and_b32_e32 v169, 0xffff0000, v164
	v_fmac_f32_e32 v160, v166, v166
	v_lshlrev_b32_e32 v168, 16, v164
	v_add_f32_e32 v160, v161, v160
	v_mul_f32_e32 v161, v169, v169
	v_and_b32_e32 v175, 0xffff0000, v165
	v_fmac_f32_e32 v161, v168, v168
	v_lshlrev_b32_e32 v171, 16, v165
	v_add_f32_e32 v160, v161, v160
	v_mul_f32_e32 v161, v175, v175
	v_fmac_f32_e32 v161, v171, v171
	v_add_f32_e32 v160, v161, v160
	v_add_f32_e32 v160, v170, v160
	ds_bpermute_b32 v161, v173, v160
	v_cmp_lt_i32_e32 vcc, v224, v218
	global_store_dwordx4 v[182:183], v[162:165], off offset:256
	s_waitcnt lgkmcnt(0)
	v_add_f32_e32 v160, v160, v161
	v_cndmask_b32_e32 v166, v217, v224, vcc
	v_lshlrev_b32_e32 v175, 2, v166
	ds_bpermute_b32 v161, v175, v160
	s_and_saveexec_b64 s[20:21], s[40:41]
	s_cbranch_execz .LBB0_1174
	s_waitcnt lgkmcnt(0)
	v_add_f32_e32 v162, v160, v161
	s_lshl_b32 s16, s75, 2
	v_lshlrev_b64 v[160:161], 6, v[180:181]
	s_ashr_i32 s17, s16, 31
	v_lshl_add_u64 v[160:161], s[26:27], 0, v[160:161]
	v_lshl_add_u64 v[160:161], s[16:17], 2, v[160:161]
	s_lshl_b32 s82, s56, 2
	v_lshl_add_u64 v[160:161], v[160:161], 0, s[82:83]
	global_store_dword v[160:161], v162, off
.LBB0_1174:
	s_or_b64 exec, exec, s[20:21]
	s_or_b32 s5, s63, 16
	v_add_u32_e32 v180, s5, v172
	v_ashrrev_i32_e32 v181, 31, v180
	s_waitcnt lgkmcnt(0)
	v_lshlrev_b64 v[160:161], 10, v[180:181]
	v_lshl_add_u64 v[168:169], v[160:161], 0, v[176:177]
	s_and_b64 vcc, exec, s[0:1]
	v_lshl_add_u64 v[184:185], v[168:169], 2, s[64:65]
	s_cbranch_vccnz .LBB0_1244
	global_load_dwordx4 v[160:163], v[184:185], off
	global_load_dwordx4 v[164:167], v[184:185], off offset:16
	s_cbranch_execnz .LBB0_1177

.LBB0_1177:
	s_waitcnt vmcnt(0) lgkmcnt(0)
	v_pk_add_f32 v[162:163], v[118:119], v[162:163]
	v_pk_add_f32 v[160:161], v[116:117], v[160:161]
	v_pk_add_f32 v[166:167], v[114:115], v[166:167]
	v_pk_add_f32 v[164:165], v[112:113], v[164:165]
	v_lshl_add_u64 v[182:183], v[168:169], 1, s[24:25]
	v_cvt_pk_bf16_f32 v168, v160, v161
	v_cvt_pk_bf16_f32 v169, v162, v163
	v_cvt_pk_bf16_f32 v170, v164, v165
	v_cvt_pk_bf16_f32 v171, v166, v167
	s_and_b64 vcc, exec, s[0:1]
	global_store_dwordx4 v[182:183], v[168:171], off
	s_cbranch_vccnz .LBB0_1245
	global_load_dwordx4 v[160:163], v[184:185], off offset:512
	global_load_dwordx4 v[164:167], v[184:185], off offset:528
	s_cbranch_execnz .LBB0_1180

.LBB0_1180:
	v_lshlrev_b32_e32 v184, 16, v168
	v_and_b32_e32 v168, 0xffff0000, v168
	v_lshlrev_b32_e32 v185, 16, v169
	v_and_b32_e32 v169, 0xffff0000, v169
	v_mul_f32_e32 v168, v168, v168
	v_mul_f32_e32 v169, v169, v169
	v_lshlrev_b32_e32 v186, 16, v170
	v_and_b32_e32 v170, 0xffff0000, v170
	v_fmac_f32_e32 v168, v184, v184
	v_fmac_f32_e32 v169, v185, v185
	v_add_f32_e32 v168, v168, v169
	v_mul_f32_e32 v169, v170, v170
	v_lshlrev_b32_e32 v187, 16, v171
	v_and_b32_e32 v171, 0xffff0000, v171
	v_fmac_f32_e32 v169, v186, v186
	v_add_f32_e32 v168, v169, v168
	v_mul_f32_e32 v169, v171, v171
	v_fmac_f32_e32 v169, v187, v187
	s_waitcnt vmcnt(0) lgkmcnt(0)
	v_pk_add_f32 v[160:161], v[84:85], v[160:161]
	v_add_f32_e32 v170, v169, v168
	v_pk_add_f32 v[168:169], v[86:87], v[162:163]
	v_cvt_pk_bf16_f32 v162, v160, v161
	v_pk_add_f32 v[166:167], v[82:83], v[166:167]
	v_pk_add_f32 v[164:165], v[80:81], v[164:165]
	v_cvt_pk_bf16_f32 v163, v168, v169
	v_and_b32_e32 v161, 0xffff0000, v162
	v_cvt_pk_bf16_f32 v164, v164, v165
	v_cvt_pk_bf16_f32 v165, v166, v167
	v_lshlrev_b32_e32 v160, 16, v162
	v_and_b32_e32 v167, 0xffff0000, v163
	v_mul_f32_e32 v161, v161, v161
	v_lshlrev_b32_e32 v166, 16, v163
	v_fmac_f32_e32 v161, v160, v160
	v_mul_f32_e32 v160, v167, v167
	v_and_b32_e32 v169, 0xffff0000, v164
	v_fmac_f32_e32 v160, v166, v166
	v_lshlrev_b32_e32 v168, 16, v164
	v_add_f32_e32 v160, v161, v160
	v_mul_f32_e32 v161, v169, v169
	v_and_b32_e32 v184, 0xffff0000, v165
	v_fmac_f32_e32 v161, v168, v168
	v_lshlrev_b32_e32 v171, 16, v165
	v_add_f32_e32 v160, v161, v160
	v_mul_f32_e32 v161, v184, v184
	v_fmac_f32_e32 v161, v171, v171
	v_add_f32_e32 v160, v161, v160
	v_add_f32_e32 v160, v170, v160
	ds_bpermute_b32 v161, v173, v160
	global_store_dwordx4 v[182:183], v[162:165], off offset:256
	s_waitcnt lgkmcnt(0)
	v_add_f32_e32 v160, v160, v161
	ds_bpermute_b32 v161, v175, v160
	s_and_saveexec_b64 s[20:21], s[40:41]
	s_cbranch_execz .LBB0_1182
	s_waitcnt lgkmcnt(0)
	v_add_f32_e32 v162, v160, v161
	s_lshl_b32 s16, s75, 2
	v_lshlrev_b64 v[160:161], 6, v[180:181]
	s_ashr_i32 s17, s16, 31
	v_lshl_add_u64 v[160:161], s[26:27], 0, v[160:161]
	v_lshl_add_u64 v[160:161], s[16:17], 2, v[160:161]
	s_lshl_b32 s82, s56, 2
	v_lshl_add_u64 v[160:161], v[160:161], 0, s[82:83]
	global_store_dword v[160:161], v162, off

.LBB0_1184:
	s_or_b32 s16, s63, 32
	v_add_u32_e32 v180, s16, v172
	v_ashrrev_i32_e32 v181, 31, v180
	s_waitcnt lgkmcnt(0)
	v_lshlrev_b64 v[160:161], 10, v[180:181]
	v_lshl_add_u64 v[168:169], v[160:161], 0, v[176:177]
	s_and_b64 vcc, exec, s[0:1]
	v_lshl_add_u64 v[184:185], v[168:169], 2, s[64:65]
	s_cbranch_vccnz .LBB0_1246
	global_load_dwordx4 v[160:163], v[184:185], off
	global_load_dwordx4 v[164:167], v[184:185], off offset:16
	s_cbranch_execnz .LBB0_1187

.LBB0_1187:
	s_waitcnt vmcnt(0) lgkmcnt(0)
	v_pk_add_f32 v[162:163], v[110:111], v[162:163]
	v_pk_add_f32 v[160:161], v[108:109], v[160:161]
	v_pk_add_f32 v[166:167], v[106:107], v[166:167]
	v_pk_add_f32 v[164:165], v[104:105], v[164:165]
	v_lshl_add_u64 v[182:183], v[168:169], 1, s[24:25]
	v_cvt_pk_bf16_f32 v168, v160, v161
	v_cvt_pk_bf16_f32 v169, v162, v163
	v_cvt_pk_bf16_f32 v170, v164, v165
	v_cvt_pk_bf16_f32 v171, v166, v167
	s_and_b64 vcc, exec, s[0:1]
	global_store_dwordx4 v[182:183], v[168:171], off
	s_cbranch_vccnz .LBB0_1247
	global_load_dwordx4 v[160:163], v[184:185], off offset:512
	global_load_dwordx4 v[164:167], v[184:185], off offset:528
	s_cbranch_execnz .LBB0_1190

.LBB0_1190:
	v_lshlrev_b32_e32 v184, 16, v168
	v_and_b32_e32 v168, 0xffff0000, v168
	v_lshlrev_b32_e32 v185, 16, v169
	v_and_b32_e32 v169, 0xffff0000, v169
	v_mul_f32_e32 v168, v168, v168
	v_mul_f32_e32 v169, v169, v169
	v_lshlrev_b32_e32 v186, 16, v170
	v_and_b32_e32 v170, 0xffff0000, v170
	v_fmac_f32_e32 v168, v184, v184
	v_fmac_f32_e32 v169, v185, v185
	v_add_f32_e32 v168, v168, v169
	v_mul_f32_e32 v169, v170, v170
	v_lshlrev_b32_e32 v187, 16, v171
	v_and_b32_e32 v171, 0xffff0000, v171
	v_fmac_f32_e32 v169, v186, v186
	v_add_f32_e32 v168, v169, v168
	v_mul_f32_e32 v169, v171, v171
	v_fmac_f32_e32 v169, v187, v187
	s_waitcnt vmcnt(0) lgkmcnt(0)
	v_pk_add_f32 v[160:161], v[76:77], v[160:161]
	v_add_f32_e32 v170, v169, v168
	v_pk_add_f32 v[168:169], v[78:79], v[162:163]
	v_cvt_pk_bf16_f32 v162, v160, v161
	v_pk_add_f32 v[166:167], v[74:75], v[166:167]
	v_pk_add_f32 v[164:165], v[72:73], v[164:165]
	v_cvt_pk_bf16_f32 v163, v168, v169
	v_and_b32_e32 v161, 0xffff0000, v162
	v_cvt_pk_bf16_f32 v164, v164, v165
	v_cvt_pk_bf16_f32 v165, v166, v167
	v_lshlrev_b32_e32 v160, 16, v162
	v_and_b32_e32 v167, 0xffff0000, v163
	v_mul_f32_e32 v161, v161, v161
	v_lshlrev_b32_e32 v166, 16, v163
	v_fmac_f32_e32 v161, v160, v160
	v_mul_f32_e32 v160, v167, v167
	v_and_b32_e32 v169, 0xffff0000, v164
	v_fmac_f32_e32 v160, v166, v166
	v_lshlrev_b32_e32 v168, 16, v164
	v_add_f32_e32 v160, v161, v160
	v_mul_f32_e32 v161, v169, v169
	v_and_b32_e32 v184, 0xffff0000, v165
	v_fmac_f32_e32 v161, v168, v168
	v_lshlrev_b32_e32 v171, 16, v165
	v_add_f32_e32 v160, v161, v160
	v_mul_f32_e32 v161, v184, v184
	v_fmac_f32_e32 v161, v171, v171
	v_add_f32_e32 v160, v161, v160
	v_add_f32_e32 v160, v170, v160
	ds_bpermute_b32 v161, v173, v160
	global_store_dwordx4 v[182:183], v[162:165], off offset:256
	s_waitcnt lgkmcnt(0)
	v_add_f32_e32 v160, v160, v161
	ds_bpermute_b32 v161, v175, v160
	s_and_saveexec_b64 s[20:21], s[40:41]
	s_cbranch_execz .LBB0_1192
	s_waitcnt lgkmcnt(0)
	v_add_f32_e32 v162, v160, v161
	s_lshl_b32 s54, s75, 2
	v_lshlrev_b64 v[160:161], 6, v[180:181]
	s_ashr_i32 s55, s54, 31
	v_lshl_add_u64 v[160:161], s[26:27], 0, v[160:161]
	v_lshl_add_u64 v[160:161], s[54:55], 2, v[160:161]
	s_lshl_b32 s82, s56, 2
	v_lshl_add_u64 v[160:161], v[160:161], 0, s[82:83]
	global_store_dword v[160:161], v162, off
.LBB0_1192:
	s_or_b64 exec, exec, s[20:21]
	s_or_b32 s17, s63, 48
	v_add_u32_e32 v180, s17, v172
	v_ashrrev_i32_e32 v181, 31, v180
	s_waitcnt lgkmcnt(0)
	v_lshlrev_b64 v[160:161], 10, v[180:181]
	v_lshl_add_u64 v[168:169], v[160:161], 0, v[176:177]
	s_and_b64 vcc, exec, s[0:1]
	v_lshl_add_u64 v[184:185], v[168:169], 2, s[64:65]
	s_cbranch_vccnz .LBB0_1248
	global_load_dwordx4 v[160:163], v[184:185], off
	global_load_dwordx4 v[164:167], v[184:185], off offset:16
	s_cbranch_execnz .LBB0_1195

.LBB0_1195:
	s_waitcnt vmcnt(0) lgkmcnt(0)
	v_pk_add_f32 v[162:163], v[102:103], v[162:163]
	v_pk_add_f32 v[160:161], v[100:101], v[160:161]
	v_pk_add_f32 v[166:167], v[98:99], v[166:167]
	v_pk_add_f32 v[164:165], v[96:97], v[164:165]
	v_lshl_add_u64 v[182:183], v[168:169], 1, s[24:25]
	v_cvt_pk_bf16_f32 v168, v160, v161
	v_cvt_pk_bf16_f32 v169, v162, v163
	v_cvt_pk_bf16_f32 v170, v164, v165
	v_cvt_pk_bf16_f32 v171, v166, v167
	s_and_b64 vcc, exec, s[0:1]
	global_store_dwordx4 v[182:183], v[168:171], off
	s_cbranch_vccnz .LBB0_1249
	global_load_dwordx4 v[160:163], v[184:185], off offset:512
	global_load_dwordx4 v[164:167], v[184:185], off offset:528
	s_cbranch_execnz .LBB0_1198

.LBB0_1198:
	v_lshlrev_b32_e32 v184, 16, v168
	v_and_b32_e32 v168, 0xffff0000, v168
	v_lshlrev_b32_e32 v185, 16, v169
	v_and_b32_e32 v169, 0xffff0000, v169
	v_mul_f32_e32 v168, v168, v168
	v_mul_f32_e32 v169, v169, v169
	v_lshlrev_b32_e32 v186, 16, v170
	v_and_b32_e32 v170, 0xffff0000, v170
	v_fmac_f32_e32 v168, v184, v184
	v_fmac_f32_e32 v169, v185, v185
	v_add_f32_e32 v168, v168, v169
	v_mul_f32_e32 v169, v170, v170
	v_lshlrev_b32_e32 v187, 16, v171
	v_and_b32_e32 v171, 0xffff0000, v171
	v_fmac_f32_e32 v169, v186, v186
	v_add_f32_e32 v168, v169, v168
	v_mul_f32_e32 v169, v171, v171
	v_fmac_f32_e32 v169, v187, v187
	s_waitcnt vmcnt(0) lgkmcnt(0)
	v_pk_add_f32 v[160:161], v[68:69], v[160:161]
	v_add_f32_e32 v170, v169, v168
	v_pk_add_f32 v[168:169], v[70:71], v[162:163]
	v_cvt_pk_bf16_f32 v162, v160, v161
	v_pk_add_f32 v[166:167], v[66:67], v[166:167]
	v_pk_add_f32 v[164:165], v[64:65], v[164:165]
	v_cvt_pk_bf16_f32 v163, v168, v169
	v_and_b32_e32 v161, 0xffff0000, v162
	v_cvt_pk_bf16_f32 v164, v164, v165
	v_cvt_pk_bf16_f32 v165, v166, v167
	v_lshlrev_b32_e32 v160, 16, v162
	v_and_b32_e32 v167, 0xffff0000, v163
	v_mul_f32_e32 v161, v161, v161
	v_lshlrev_b32_e32 v166, 16, v163
	v_fmac_f32_e32 v161, v160, v160
	v_mul_f32_e32 v160, v167, v167
	v_and_b32_e32 v169, 0xffff0000, v164
	v_fmac_f32_e32 v160, v166, v166
	v_lshlrev_b32_e32 v168, 16, v164
	v_add_f32_e32 v160, v161, v160
	v_mul_f32_e32 v161, v169, v169
	v_and_b32_e32 v184, 0xffff0000, v165
	v_fmac_f32_e32 v161, v168, v168
	v_lshlrev_b32_e32 v171, 16, v165
	v_add_f32_e32 v160, v161, v160
	v_mul_f32_e32 v161, v184, v184
	v_fmac_f32_e32 v161, v171, v171
	v_add_f32_e32 v160, v161, v160
	v_add_f32_e32 v160, v170, v160
	ds_bpermute_b32 v161, v173, v160
	global_store_dwordx4 v[182:183], v[162:165], off offset:256
	s_waitcnt lgkmcnt(0)
	v_add_f32_e32 v160, v160, v161
	ds_bpermute_b32 v161, v175, v160
	s_and_saveexec_b64 s[20:21], s[40:41]
	s_cbranch_execz .LBB0_1200
	s_waitcnt lgkmcnt(0)
	v_add_f32_e32 v162, v160, v161
	s_lshl_b32 s54, s75, 2
	v_lshlrev_b64 v[160:161], 6, v[180:181]
	s_ashr_i32 s55, s54, 31
	v_lshl_add_u64 v[160:161], s[26:27], 0, v[160:161]
	v_lshl_add_u64 v[160:161], s[54:55], 2, v[160:161]
	s_lshl_b32 s82, s56, 2
	v_lshl_add_u64 v[160:161], v[160:161], 0, s[82:83]
	global_store_dword v[160:161], v162, off

.LBB0_1204:
	v_lshlrev_b64 v[128:129], 11, v[168:169]
	v_lshl_add_u64 v[128:129], v[178:179], 0, v[128:129]
	global_load_dwordx4 v[156:159], v[128:129], off
	global_load_dwordx4 v[152:155], v[128:129], off offset:256
	v_add_u32_e32 v128, 16, v168
	v_ashrrev_i32_e32 v129, 31, v128
	v_lshlrev_b64 v[128:129], 11, v[128:129]
	v_lshl_add_u64 v[128:129], v[178:179], 0, v[128:129]
	global_load_dwordx4 v[148:151], v[128:129], off
	global_load_dwordx4 v[144:147], v[128:129], off offset:256
	v_add_u32_e32 v128, 32, v168
	v_ashrrev_i32_e32 v129, 31, v128
	v_lshlrev_b64 v[128:129], 11, v[128:129]
	v_lshl_add_u64 v[128:129], v[178:179], 0, v[128:129]
	global_load_dwordx4 v[140:143], v[128:129], off
	global_load_dwordx4 v[136:139], v[128:129], off offset:256
	v_add_u32_e32 v128, 48, v168
	v_ashrrev_i32_e32 v129, 31, v128
	v_lshlrev_b64 v[128:129], 11, v[128:129]
	v_lshl_add_u64 v[128:129], v[178:179], 0, v[128:129]
	global_load_dwordx4 v[132:135], v[128:129], off
	s_nop 0
	global_load_dwordx4 v[128:131], v[128:129], off offset:256
.LBB0_1205:
	s_waitcnt lgkmcnt(0)
	v_lshlrev_b64 v[160:161], 10, v[168:169]
	v_lshl_add_u64 v[170:171], v[160:161], 0, v[176:177]
	s_and_b64 vcc, exec, s[0:1]
	v_lshl_add_u64 v[178:179], v[170:171], 2, s[64:65]
	s_cbranch_vccnz .LBB0_1251
	global_load_dwordx4 v[160:163], v[178:179], off
	global_load_dwordx4 v[164:167], v[178:179], off offset:16
	s_cbranch_execnz .LBB0_1208

.LBB0_1208:
	s_waitcnt vmcnt(0) lgkmcnt(0)
	v_pk_add_f32 v[156:157], v[62:63], v[162:163]
	v_pk_add_f32 v[158:159], v[60:61], v[160:161]
	v_pk_add_f32 v[160:161], v[58:59], v[166:167]
	v_pk_add_f32 v[162:163], v[56:57], v[164:165]
	v_lshl_add_u64 v[170:171], v[170:171], 1, s[24:25]
	v_cvt_pk_bf16_f32 v164, v158, v159
	v_cvt_pk_bf16_f32 v165, v156, v157
	v_cvt_pk_bf16_f32 v166, v162, v163
	v_cvt_pk_bf16_f32 v167, v160, v161
	s_and_b64 vcc, exec, s[0:1]
	global_store_dwordx4 v[170:171], v[164:167], off
	s_cbranch_vccnz .LBB0_1252
	global_load_dwordx4 v[156:159], v[178:179], off offset:512
	global_load_dwordx4 v[160:163], v[178:179], off offset:528
	s_cbranch_execnz .LBB0_1211

.LBB0_1211:
	v_and_b32_e32 v153, 0xffff0000, v164
	v_lshlrev_b32_e32 v152, 16, v164
	v_and_b32_e32 v155, 0xffff0000, v165
	v_mul_f32_e32 v153, v153, v153
	v_lshlrev_b32_e32 v154, 16, v165
	v_fmac_f32_e32 v153, v152, v152
	v_mul_f32_e32 v152, v155, v155
	v_and_b32_e32 v165, 0xffff0000, v166
	v_fmac_f32_e32 v152, v154, v154
	v_lshlrev_b32_e32 v164, 16, v166
	v_add_f32_e32 v152, v153, v152
	v_mul_f32_e32 v153, v165, v165
	v_lshlrev_b32_e32 v166, 16, v167
	v_and_b32_e32 v167, 0xffff0000, v167
	v_fmac_f32_e32 v153, v164, v164
	v_add_f32_e32 v152, v153, v152
	v_mul_f32_e32 v153, v167, v167
	v_fmac_f32_e32 v153, v166, v166
	s_waitcnt vmcnt(0) lgkmcnt(0)
	v_pk_add_f32 v[154:155], v[28:29], v[156:157]
	v_add_f32_e32 v164, v153, v152
	v_pk_add_f32 v[152:153], v[30:31], v[158:159]
	v_cvt_pk_bf16_f32 v154, v154, v155
	v_pk_add_f32 v[158:159], v[26:27], v[162:163]
	v_pk_add_f32 v[156:157], v[24:25], v[160:161]
	v_cvt_pk_bf16_f32 v155, v152, v153
	v_and_b32_e32 v153, 0xffff0000, v154
	v_cvt_pk_bf16_f32 v156, v156, v157
	v_cvt_pk_bf16_f32 v157, v158, v159
	v_lshlrev_b32_e32 v152, 16, v154
	v_and_b32_e32 v159, 0xffff0000, v155
	v_mul_f32_e32 v153, v153, v153
	v_lshlrev_b32_e32 v158, 16, v155
	v_fmac_f32_e32 v153, v152, v152
	v_mul_f32_e32 v152, v159, v159
	v_and_b32_e32 v161, 0xffff0000, v156
	v_fmac_f32_e32 v152, v158, v158
	v_lshlrev_b32_e32 v160, 16, v156
	v_add_f32_e32 v152, v153, v152
	v_mul_f32_e32 v153, v161, v161
	v_and_b32_e32 v163, 0xffff0000, v157
	v_fmac_f32_e32 v153, v160, v160
	v_lshlrev_b32_e32 v162, 16, v157
	v_add_f32_e32 v152, v153, v152
	v_mul_f32_e32 v153, v163, v163
	v_fmac_f32_e32 v153, v162, v162
	v_add_f32_e32 v152, v153, v152
	v_add_f32_e32 v152, v164, v152
	ds_bpermute_b32 v153, v173, v152
	global_store_dwordx4 v[170:171], v[154:157], off offset:256
	s_waitcnt lgkmcnt(0)
	v_add_f32_e32 v152, v152, v153
	ds_bpermute_b32 v153, v175, v152
	s_and_saveexec_b64 s[20:21], s[40:41]
	s_cbranch_execz .LBB0_1213
	s_waitcnt lgkmcnt(0)
	v_add_f32_e32 v154, v152, v153
	s_lshl_b32 s54, s75, 2
	v_lshlrev_b64 v[152:153], 6, v[168:169]
	s_ashr_i32 s55, s54, 31
	v_lshl_add_u64 v[152:153], s[26:27], 0, v[152:153]
	v_lshl_add_u64 v[152:153], s[54:55], 2, v[152:153]
	s_lshl_b32 s82, s56, 2
	v_lshl_add_u64 v[152:153], v[152:153], 0, s[82:83]
	global_store_dword v[152:153], v154, off
.LBB0_1213:
	s_or_b64 exec, exec, s[20:21]
	v_add_u32_e32 v160, s5, v180
	v_ashrrev_i32_e32 v161, 31, v160
	s_waitcnt lgkmcnt(0)
	v_lshlrev_b64 v[152:153], 10, v[160:161]
	v_lshl_add_u64 v[162:163], v[152:153], 0, v[176:177]
	s_and_b64 vcc, exec, s[0:1]
	v_lshl_add_u64 v[164:165], v[162:163], 2, s[64:65]
	s_cbranch_vccnz .LBB0_1253
	global_load_dwordx4 v[152:155], v[164:165], off
	global_load_dwordx4 v[156:159], v[164:165], off offset:16
	s_cbranch_execnz .LBB0_1216

.LBB0_1216:
	s_waitcnt vmcnt(0) lgkmcnt(0)
	v_pk_add_f32 v[148:149], v[54:55], v[154:155]
	v_pk_add_f32 v[150:151], v[52:53], v[152:153]
	v_pk_add_f32 v[152:153], v[50:51], v[158:159]
	v_pk_add_f32 v[154:155], v[48:49], v[156:157]
	v_lshl_add_u64 v[162:163], v[162:163], 1, s[24:25]
	v_cvt_pk_bf16_f32 v156, v150, v151
	v_cvt_pk_bf16_f32 v157, v148, v149
	v_cvt_pk_bf16_f32 v158, v154, v155
	v_cvt_pk_bf16_f32 v159, v152, v153
	s_and_b64 vcc, exec, s[0:1]
	global_store_dwordx4 v[162:163], v[156:159], off
	s_cbranch_vccnz .LBB0_1254
	global_load_dwordx4 v[148:151], v[164:165], off offset:512
	global_load_dwordx4 v[152:155], v[164:165], off offset:528
	s_cbranch_execnz .LBB0_1219

.LBB0_1219:
	v_and_b32_e32 v145, 0xffff0000, v156
	v_lshlrev_b32_e32 v144, 16, v156
	v_and_b32_e32 v147, 0xffff0000, v157
	v_mul_f32_e32 v145, v145, v145
	v_lshlrev_b32_e32 v146, 16, v157
	v_fmac_f32_e32 v145, v144, v144
	v_mul_f32_e32 v144, v147, v147
	v_and_b32_e32 v157, 0xffff0000, v158
	v_fmac_f32_e32 v144, v146, v146
	v_lshlrev_b32_e32 v156, 16, v158
	v_add_f32_e32 v144, v145, v144
	v_mul_f32_e32 v145, v157, v157
	v_lshlrev_b32_e32 v158, 16, v159
	v_and_b32_e32 v159, 0xffff0000, v159
	v_fmac_f32_e32 v145, v156, v156
	v_add_f32_e32 v144, v145, v144
	v_mul_f32_e32 v145, v159, v159
	v_fmac_f32_e32 v145, v158, v158
	s_waitcnt vmcnt(0) lgkmcnt(0)
	v_pk_add_f32 v[146:147], v[20:21], v[148:149]
	v_add_f32_e32 v156, v145, v144
	v_pk_add_f32 v[144:145], v[22:23], v[150:151]
	v_cvt_pk_bf16_f32 v146, v146, v147
	v_pk_add_f32 v[150:151], v[18:19], v[154:155]
	v_pk_add_f32 v[148:149], v[16:17], v[152:153]
	v_cvt_pk_bf16_f32 v147, v144, v145
	v_and_b32_e32 v145, 0xffff0000, v146
	v_cvt_pk_bf16_f32 v148, v148, v149
	v_cvt_pk_bf16_f32 v149, v150, v151
	v_lshlrev_b32_e32 v144, 16, v146
	v_and_b32_e32 v151, 0xffff0000, v147
	v_mul_f32_e32 v145, v145, v145
	v_lshlrev_b32_e32 v150, 16, v147
	v_fmac_f32_e32 v145, v144, v144
	v_mul_f32_e32 v144, v151, v151
	v_and_b32_e32 v153, 0xffff0000, v148
	v_fmac_f32_e32 v144, v150, v150
	v_lshlrev_b32_e32 v152, 16, v148
	v_add_f32_e32 v144, v145, v144
	v_mul_f32_e32 v145, v153, v153
	v_and_b32_e32 v155, 0xffff0000, v149
	v_fmac_f32_e32 v145, v152, v152
	v_lshlrev_b32_e32 v154, 16, v149
	v_add_f32_e32 v144, v145, v144
	v_mul_f32_e32 v145, v155, v155
	v_fmac_f32_e32 v145, v154, v154
	v_add_f32_e32 v144, v145, v144
	v_add_f32_e32 v144, v156, v144
	ds_bpermute_b32 v145, v173, v144
	global_store_dwordx4 v[162:163], v[146:149], off offset:256
	s_waitcnt lgkmcnt(0)
	v_add_f32_e32 v144, v144, v145
	ds_bpermute_b32 v145, v175, v144
	s_and_saveexec_b64 s[20:21], s[40:41]
	s_cbranch_execz .LBB0_1221
	s_waitcnt lgkmcnt(0)
	v_add_f32_e32 v146, v144, v145
	s_lshl_b32 s54, s75, 2
	v_lshlrev_b64 v[144:145], 6, v[160:161]
	s_ashr_i32 s55, s54, 31
	v_lshl_add_u64 v[144:145], s[26:27], 0, v[144:145]
	v_lshl_add_u64 v[144:145], s[54:55], 2, v[144:145]
	s_lshl_b32 s82, s56, 2
	v_lshl_add_u64 v[144:145], v[144:145], 0, s[82:83]
	global_store_dword v[144:145], v146, off

.LBB0_1223:
	v_add_u32_e32 v152, s16, v180
	v_ashrrev_i32_e32 v153, 31, v152
	s_waitcnt lgkmcnt(0)
	v_lshlrev_b64 v[144:145], 10, v[152:153]
	v_lshl_add_u64 v[154:155], v[144:145], 0, v[176:177]
	s_and_b64 vcc, exec, s[0:1]
	v_lshl_add_u64 v[156:157], v[154:155], 2, s[64:65]
	s_cbranch_vccnz .LBB0_1255
	global_load_dwordx4 v[144:147], v[156:157], off
	global_load_dwordx4 v[148:151], v[156:157], off offset:16
	s_cbranch_execnz .LBB0_1226

.LBB0_1226:
	s_waitcnt vmcnt(0) lgkmcnt(0)
	v_pk_add_f32 v[140:141], v[46:47], v[146:147]
	v_pk_add_f32 v[142:143], v[44:45], v[144:145]
	v_pk_add_f32 v[144:145], v[42:43], v[150:151]
	v_pk_add_f32 v[146:147], v[40:41], v[148:149]
	v_lshl_add_u64 v[154:155], v[154:155], 1, s[24:25]
	v_cvt_pk_bf16_f32 v148, v142, v143
	v_cvt_pk_bf16_f32 v149, v140, v141
	v_cvt_pk_bf16_f32 v150, v146, v147
	v_cvt_pk_bf16_f32 v151, v144, v145
	s_and_b64 vcc, exec, s[0:1]
	global_store_dwordx4 v[154:155], v[148:151], off
	s_cbranch_vccnz .LBB0_1256
	global_load_dwordx4 v[140:143], v[156:157], off offset:512
	global_load_dwordx4 v[144:147], v[156:157], off offset:528
	s_cbranch_execnz .LBB0_1229

.LBB0_1229:
	v_and_b32_e32 v137, 0xffff0000, v148
	v_lshlrev_b32_e32 v136, 16, v148
	v_and_b32_e32 v139, 0xffff0000, v149
	v_mul_f32_e32 v137, v137, v137
	v_lshlrev_b32_e32 v138, 16, v149
	v_fmac_f32_e32 v137, v136, v136
	v_mul_f32_e32 v136, v139, v139
	v_and_b32_e32 v149, 0xffff0000, v150
	v_fmac_f32_e32 v136, v138, v138
	v_lshlrev_b32_e32 v148, 16, v150
	v_add_f32_e32 v136, v137, v136
	v_mul_f32_e32 v137, v149, v149
	v_lshlrev_b32_e32 v150, 16, v151
	v_and_b32_e32 v151, 0xffff0000, v151
	v_fmac_f32_e32 v137, v148, v148
	v_add_f32_e32 v136, v137, v136
	v_mul_f32_e32 v137, v151, v151
	v_fmac_f32_e32 v137, v150, v150
	s_waitcnt vmcnt(0) lgkmcnt(0)
	v_pk_add_f32 v[138:139], v[12:13], v[140:141]
	v_add_f32_e32 v148, v137, v136
	v_pk_add_f32 v[136:137], v[14:15], v[142:143]
	v_cvt_pk_bf16_f32 v138, v138, v139
	v_pk_add_f32 v[142:143], v[10:11], v[146:147]
	v_pk_add_f32 v[140:141], v[8:9], v[144:145]
	v_cvt_pk_bf16_f32 v139, v136, v137
	v_and_b32_e32 v137, 0xffff0000, v138
	v_cvt_pk_bf16_f32 v140, v140, v141
	v_cvt_pk_bf16_f32 v141, v142, v143
	v_lshlrev_b32_e32 v136, 16, v138
	v_and_b32_e32 v143, 0xffff0000, v139
	v_mul_f32_e32 v137, v137, v137
	v_lshlrev_b32_e32 v142, 16, v139
	v_fmac_f32_e32 v137, v136, v136
	v_mul_f32_e32 v136, v143, v143
	v_and_b32_e32 v145, 0xffff0000, v140
	v_fmac_f32_e32 v136, v142, v142
	v_lshlrev_b32_e32 v144, 16, v140
	v_add_f32_e32 v136, v137, v136
	v_mul_f32_e32 v137, v145, v145
	v_and_b32_e32 v147, 0xffff0000, v141
	v_fmac_f32_e32 v137, v144, v144
	v_lshlrev_b32_e32 v146, 16, v141
	v_add_f32_e32 v136, v137, v136
	v_mul_f32_e32 v137, v147, v147
	v_fmac_f32_e32 v137, v146, v146
	v_add_f32_e32 v136, v137, v136
	v_add_f32_e32 v136, v148, v136
	ds_bpermute_b32 v137, v173, v136
	global_store_dwordx4 v[154:155], v[138:141], off offset:256
	s_waitcnt lgkmcnt(0)
	v_add_f32_e32 v136, v136, v137
	ds_bpermute_b32 v137, v175, v136
	s_and_saveexec_b64 s[20:21], s[40:41]
	s_cbranch_execz .LBB0_1231
	s_waitcnt lgkmcnt(0)
	v_add_f32_e32 v138, v136, v137
	s_lshl_b32 s54, s75, 2
	v_lshlrev_b64 v[136:137], 6, v[152:153]
	s_ashr_i32 s55, s54, 31
	v_lshl_add_u64 v[136:137], s[26:27], 0, v[136:137]
	v_lshl_add_u64 v[136:137], s[54:55], 2, v[136:137]
	s_lshl_b32 s82, s56, 2
	v_lshl_add_u64 v[136:137], v[136:137], 0, s[82:83]
	global_store_dword v[136:137], v138, off
.LBB0_1231:
	s_or_b64 exec, exec, s[20:21]
	v_add_u32_e32 v144, s17, v180
	v_ashrrev_i32_e32 v145, 31, v144
	s_waitcnt lgkmcnt(0)
	v_lshlrev_b64 v[136:137], 10, v[144:145]
	v_lshl_add_u64 v[146:147], v[136:137], 0, v[176:177]
	s_and_b64 vcc, exec, s[0:1]
	v_lshl_add_u64 v[148:149], v[146:147], 2, s[64:65]
	s_cbranch_vccnz .LBB0_1257
	global_load_dwordx4 v[136:139], v[148:149], off
	global_load_dwordx4 v[140:143], v[148:149], off offset:16
	s_cbranch_execnz .LBB0_1234

.LBB0_1234:
	s_waitcnt vmcnt(0) lgkmcnt(0)
	v_pk_add_f32 v[132:133], v[38:39], v[138:139]
	v_pk_add_f32 v[134:135], v[36:37], v[136:137]
	v_pk_add_f32 v[136:137], v[34:35], v[142:143]
	v_pk_add_f32 v[138:139], v[32:33], v[140:141]
	v_lshl_add_u64 v[146:147], v[146:147], 1, s[24:25]
	v_cvt_pk_bf16_f32 v140, v134, v135
	v_cvt_pk_bf16_f32 v141, v132, v133
	v_cvt_pk_bf16_f32 v142, v138, v139
	v_cvt_pk_bf16_f32 v143, v136, v137
	s_and_b64 vcc, exec, s[0:1]
	global_store_dwordx4 v[146:147], v[140:143], off
	s_cbranch_vccnz .LBB0_1258
	global_load_dwordx4 v[132:135], v[148:149], off offset:512
	global_load_dwordx4 v[136:139], v[148:149], off offset:528
	s_cbranch_execnz .LBB0_1237

.LBB0_1237:
	v_and_b32_e32 v129, 0xffff0000, v140
	v_lshlrev_b32_e32 v128, 16, v140
	v_and_b32_e32 v131, 0xffff0000, v141
	v_mul_f32_e32 v129, v129, v129
	v_lshlrev_b32_e32 v130, 16, v141
	v_fmac_f32_e32 v129, v128, v128
	v_mul_f32_e32 v128, v131, v131
	v_and_b32_e32 v141, 0xffff0000, v142
	v_fmac_f32_e32 v128, v130, v130
	v_lshlrev_b32_e32 v140, 16, v142
	v_add_f32_e32 v128, v129, v128
	v_mul_f32_e32 v129, v141, v141
	v_lshlrev_b32_e32 v142, 16, v143
	v_and_b32_e32 v143, 0xffff0000, v143
	v_fmac_f32_e32 v129, v140, v140
	v_add_f32_e32 v128, v129, v128
	v_mul_f32_e32 v129, v143, v143
	v_fmac_f32_e32 v129, v142, v142
	s_waitcnt vmcnt(0) lgkmcnt(0)
	v_pk_add_f32 v[130:131], v[4:5], v[132:133]
	v_add_f32_e32 v140, v129, v128
	v_pk_add_f32 v[128:129], v[6:7], v[134:135]
	v_cvt_pk_bf16_f32 v130, v130, v131
	v_pk_add_f32 v[134:135], v[2:3], v[138:139]
	v_pk_add_f32 v[132:133], v[0:1], v[136:137]
	v_cvt_pk_bf16_f32 v131, v128, v129
	v_and_b32_e32 v129, 0xffff0000, v130
	v_cvt_pk_bf16_f32 v132, v132, v133
	v_cvt_pk_bf16_f32 v133, v134, v135
	v_lshlrev_b32_e32 v128, 16, v130
	v_and_b32_e32 v135, 0xffff0000, v131
	v_mul_f32_e32 v129, v129, v129
	v_lshlrev_b32_e32 v134, 16, v131
	v_fmac_f32_e32 v129, v128, v128
	v_mul_f32_e32 v128, v135, v135
	v_and_b32_e32 v137, 0xffff0000, v132
	v_fmac_f32_e32 v128, v134, v134
	v_lshlrev_b32_e32 v136, 16, v132
	v_add_f32_e32 v128, v129, v128
	v_mul_f32_e32 v129, v137, v137
	v_and_b32_e32 v139, 0xffff0000, v133
	v_fmac_f32_e32 v129, v136, v136
	v_lshlrev_b32_e32 v138, 16, v133
	v_add_f32_e32 v128, v129, v128
	v_mul_f32_e32 v129, v139, v139
	v_fmac_f32_e32 v129, v138, v138
	v_add_f32_e32 v128, v129, v128
	v_add_f32_e32 v128, v140, v128
	ds_bpermute_b32 v129, v173, v128
	global_store_dwordx4 v[146:147], v[130:133], off offset:256
	s_waitcnt lgkmcnt(0)
	v_add_f32_e32 v128, v128, v129
	ds_bpermute_b32 v129, v175, v128
	s_and_saveexec_b64 s[20:21], s[40:41]
	s_cbranch_execz .LBB0_1239
	s_waitcnt lgkmcnt(0)
	v_add_f32_e32 v130, v128, v129
	s_lshl_b32 s16, s75, 2
	v_lshlrev_b64 v[128:129], 6, v[144:145]
	s_ashr_i32 s17, s16, 31
	v_lshl_add_u64 v[128:129], s[26:27], 0, v[128:129]
	v_lshl_add_u64 v[128:129], s[16:17], 2, v[128:129]
	s_lshl_b32 s82, s56, 2
	v_lshl_add_u64 v[128:129], v[128:129], 0, s[82:83]
	global_store_dword v[128:129], v130, off
